# all flat_load/flat_store converted to global_load/global_store (same addresses; no LGKM coupling), on top of v26
# speedup vs baseline: 1.0145x; 1.0044x over previous
.LBB0_15:
	s_mul_hi_i32 s0, s13, 0x10624dd3
	s_lshr_b32 s1, s0, 31
	s_ashr_i32 s0, s0, 3
	s_add_i32 s1, s0, s1
	s_lshl_b32 s0, s1, 6
	s_mulk_i32 s1, 0xf060
	s_add_i32 s6, s8, s1
	s_ashr_i32 s7, s6, 31
	v_or_b32_e32 v25, s0, v8
	v_lshl_add_u64 v[26:27], s[6:7], 2, v[2:3]
	v_or_b32_e32 v28, 8, v25
	v_or_b32_e32 v29, 16, v25
	v_or_b32_e32 v30, 24, v25
	v_or_b32_e32 v31, 32, v25
	v_or_b32_e32 v32, 40, v25
	v_or_b32_e32 v33, 48, v25
	v_or_b32_e32 v34, 56, v25
	v_mad_i64_i32 v[46:47], s[18:19], v25, s11, v[26:27]
	v_mad_i64_i32 v[62:63], s[18:19], v28, s11, v[26:27]
	v_mad_i64_i32 v[64:65], s[18:19], v29, s11, v[26:27]
	v_mad_i64_i32 v[66:67], s[18:19], v30, s11, v[26:27]
	v_mad_i64_i32 v[68:69], s[18:19], v31, s11, v[26:27]
	v_mad_i64_i32 v[70:71], s[18:19], v32, s11, v[26:27]
	v_mad_i64_i32 v[72:73], s[18:19], v33, s11, v[26:27]
	v_mad_i64_i32 v[74:75], s[18:19], v34, s11, v[26:27]
	global_load_dwordx4 v[26:29], v[46:47], off
	global_load_dwordx4 v[30:33], v[62:63], off
	global_load_dwordx4 v[34:37], v[64:65], off
	global_load_dwordx4 v[38:41], v[66:67], off
	global_load_dwordx4 v[42:45], v[68:69], off
	global_load_dwordx4 v[50:53], v[70:71], off
	global_load_dwordx4 v[54:57], v[72:73], off
	global_load_dwordx4 v[58:61], v[74:75], off
	v_add_u32_e32 v62, s6, v8
	s_ashr_i32 s1, s0, 31
	v_ashrrev_i32_e32 v63, 31, v62
	v_lshl_add_u64 v[46:47], s[0:1], 1, v[4:5]
	v_add_u32_e32 v64, 8, v62
	v_add_u32_e32 v66, 16, v62
	v_add_u32_e32 v68, 24, v62
	v_lshlrev_b64 v[62:63], 11, v[62:63]
	v_lshl_add_u64 v[62:63], v[46:47], 0, v[62:63]
	v_ashrrev_i32_e32 v65, 31, v64
	v_lshlrev_b64 v[64:65], 11, v[64:65]
	v_lshl_add_u64 v[64:65], v[46:47], 0, v[64:65]
	v_ashrrev_i32_e32 v67, 31, v66
	v_lshlrev_b64 v[66:67], 11, v[66:67]
	v_lshl_add_u64 v[66:67], v[46:47], 0, v[66:67]
	v_ashrrev_i32_e32 v69, 31, v68
	s_add_i32 s13, s13, s12
	s_add_i32 s8, s8, s9
	v_lshlrev_b64 v[68:69], 11, v[68:69]
	s_cmpk_lt_i32 s13, 0x7d0
	v_lshl_add_u64 v[46:47], v[46:47], 0, v[68:69]
	s_waitcnt vmcnt(0) lgkmcnt(0)
	ds_write2_b32 v10, v26, v27 offset1:1
	ds_write2_b32 v10, v28, v29 offset0:2 offset1:3
	ds_write2_b32 v11, v30, v31 offset1:1
	ds_write2_b32 v12, v32, v33 offset1:1
	ds_write2_b32 v13, v34, v35 offset1:1
	ds_write2_b32 v14, v36, v37 offset1:1
	ds_write2_b32 v15, v38, v39 offset1:1
	ds_write2_b32 v16, v40, v41 offset1:1
	ds_write2_b32 v17, v42, v43 offset1:1
	ds_write2_b32 v18, v44, v45 offset1:1
	ds_write2_b32 v19, v50, v51 offset1:1
	ds_write2_b32 v20, v52, v53 offset1:1
	ds_write2_b32 v21, v54, v55 offset1:1
	ds_write2_b32 v22, v56, v57 offset1:1
	ds_write2_b32 v23, v58, v59 offset1:1
	ds_write2_b32 v24, v60, v61 offset1:1
	ds_read_b32 v25, v9
	ds_read_b32 v26, v9 offset:132
	ds_read_b32 v27, v9 offset:264
	ds_read_b32 v28, v9 offset:396
	ds_read_b32 v29, v9 offset:528
	ds_read_b32 v30, v9 offset:660
	ds_read_b32 v31, v9 offset:792
	ds_read_b32 v32, v9 offset:924
	s_waitcnt lgkmcnt(6)
	v_cvt_pk_bf16_f32 v26, v25, v26
	s_waitcnt lgkmcnt(4)
	v_cvt_pk_bf16_f32 v27, v27, v28
	s_waitcnt lgkmcnt(2)
	v_cvt_pk_bf16_f32 v28, v29, v30
	s_waitcnt lgkmcnt(0)
	v_cvt_pk_bf16_f32 v29, v31, v32
	global_store_dwordx4 v[62:63], v[26:29], off
	ds_read_b32 v25, v9 offset:32
	ds_read_b32 v26, v9 offset:164
	ds_read_b32 v27, v9 offset:296
	ds_read_b32 v28, v9 offset:428
	ds_read_b32 v29, v9 offset:560
	ds_read_b32 v30, v9 offset:692
	ds_read_b32 v31, v9 offset:824
	ds_read_b32 v32, v9 offset:956
	s_waitcnt lgkmcnt(0)
	v_cvt_pk_bf16_f32 v26, v25, v26
	v_cvt_pk_bf16_f32 v27, v27, v28
	v_cvt_pk_bf16_f32 v28, v29, v30
	v_cvt_pk_bf16_f32 v29, v31, v32
	global_store_dwordx4 v[64:65], v[26:29], off
	ds_read_b32 v25, v9 offset:64
	ds_read_b32 v26, v9 offset:196
	ds_read_b32 v27, v9 offset:328
	ds_read_b32 v28, v9 offset:460
	ds_read_b32 v29, v9 offset:592
	ds_read_b32 v30, v9 offset:724
	ds_read_b32 v31, v9 offset:856
	ds_read_b32 v32, v9 offset:988
	s_waitcnt lgkmcnt(0)
	v_cvt_pk_bf16_f32 v26, v25, v26
	v_cvt_pk_bf16_f32 v27, v27, v28
	v_cvt_pk_bf16_f32 v28, v29, v30
	v_cvt_pk_bf16_f32 v29, v31, v32
	global_store_dwordx4 v[66:67], v[26:29], off
	ds_read_b32 v25, v9 offset:96
	ds_read_b32 v26, v9 offset:228
	ds_read_b32 v27, v9 offset:360
	ds_read_b32 v28, v9 offset:492
	ds_read_b32 v29, v9 offset:624
	ds_read_b32 v30, v9 offset:756
	ds_read_b32 v31, v9 offset:888
	ds_read_b32 v32, v9 offset:1020
	s_waitcnt lgkmcnt(0)
	v_cvt_pk_bf16_f32 v26, v25, v26
	v_cvt_pk_bf16_f32 v27, v27, v28
	v_cvt_pk_bf16_f32 v28, v29, v30
	v_cvt_pk_bf16_f32 v29, v31, v32
	global_store_dwordx4 v[46:47], v[26:29], off
	s_cbranch_scc1 .LBB0_15

.LBB0_18:
	s_ashr_i32 s4, s18, 31
	s_lshr_b32 s4, s4, 25
	s_add_i32 s4, s18, s4
	s_ashr_i32 s5, s4, 7
	s_lshl_b32 s4, s5, 6
	s_lshl_b32 s5, s5, 12
	s_sub_i32 s8, s11, s5
	s_ashr_i32 s9, s8, 31
	v_or_b32_e32 v25, s4, v8
	v_lshl_add_u64 v[26:27], s[8:9], 2, v[2:3]
	v_or_b32_e32 v28, 8, v25
	v_or_b32_e32 v29, 16, v25
	v_or_b32_e32 v30, 24, v25
	v_or_b32_e32 v31, 32, v25
	v_or_b32_e32 v32, 40, v25
	v_or_b32_e32 v33, 48, v25
	v_or_b32_e32 v34, 56, v25
	v_mad_i64_i32 v[46:47], s[20:21], v25, s17, v[26:27]
	v_mad_i64_i32 v[62:63], s[20:21], v28, s17, v[26:27]
	v_mad_i64_i32 v[64:65], s[20:21], v29, s17, v[26:27]
	v_mad_i64_i32 v[66:67], s[20:21], v30, s17, v[26:27]
	v_mad_i64_i32 v[68:69], s[20:21], v31, s17, v[26:27]
	v_mad_i64_i32 v[70:71], s[20:21], v32, s17, v[26:27]
	v_mad_i64_i32 v[72:73], s[20:21], v33, s17, v[26:27]
	v_mad_i64_i32 v[74:75], s[20:21], v34, s17, v[26:27]
	global_load_dwordx4 v[26:29], v[46:47], off
	global_load_dwordx4 v[30:33], v[62:63], off
	global_load_dwordx4 v[34:37], v[64:65], off
	global_load_dwordx4 v[38:41], v[66:67], off
	global_load_dwordx4 v[42:45], v[68:69], off
	global_load_dwordx4 v[50:53], v[70:71], off
	global_load_dwordx4 v[54:57], v[72:73], off
	global_load_dwordx4 v[58:61], v[74:75], off
	v_add_u32_e32 v62, s8, v8
	s_ashr_i32 s5, s4, 31
	v_ashrrev_i32_e32 v63, 31, v62
	v_lshl_add_u64 v[46:47], s[4:5], 1, v[4:5]
	v_add_u32_e32 v64, 8, v62
	v_add_u32_e32 v66, 16, v62
	v_add_u32_e32 v68, 24, v62
	v_lshlrev_b64 v[62:63], 11, v[62:63]
	v_lshl_add_u64 v[62:63], v[46:47], 0, v[62:63]
	v_ashrrev_i32_e32 v65, 31, v64
	v_lshlrev_b64 v[64:65], 11, v[64:65]
	v_lshl_add_u64 v[64:65], v[46:47], 0, v[64:65]
	v_ashrrev_i32_e32 v67, 31, v66
	v_lshlrev_b64 v[66:67], 11, v[66:67]
	v_lshl_add_u64 v[66:67], v[46:47], 0, v[66:67]
	v_ashrrev_i32_e32 v69, 31, v68
	s_add_i32 s18, s18, s12
	s_add_i32 s11, s11, s13
	v_lshlrev_b64 v[68:69], 11, v[68:69]
	s_cmpk_lt_i32 s18, 0x800
	v_lshl_add_u64 v[46:47], v[46:47], 0, v[68:69]
	s_waitcnt vmcnt(0) lgkmcnt(0)
	ds_write2_b32 v10, v26, v27 offset1:1
	ds_write2_b32 v10, v28, v29 offset0:2 offset1:3
	ds_write2_b32 v11, v30, v31 offset1:1
	ds_write2_b32 v12, v32, v33 offset1:1
	ds_write2_b32 v13, v34, v35 offset1:1
	ds_write2_b32 v14, v36, v37 offset1:1
	ds_write2_b32 v15, v38, v39 offset1:1
	ds_write2_b32 v16, v40, v41 offset1:1
	ds_write2_b32 v17, v42, v43 offset1:1
	ds_write2_b32 v18, v44, v45 offset1:1
	ds_write2_b32 v19, v50, v51 offset1:1
	ds_write2_b32 v20, v52, v53 offset1:1
	ds_write2_b32 v21, v54, v55 offset1:1
	ds_write2_b32 v22, v56, v57 offset1:1
	ds_write2_b32 v23, v58, v59 offset1:1
	ds_write2_b32 v24, v60, v61 offset1:1
	ds_read_b32 v25, v9
	ds_read_b32 v26, v9 offset:132
	ds_read_b32 v27, v9 offset:264
	ds_read_b32 v28, v9 offset:396
	ds_read_b32 v29, v9 offset:528
	ds_read_b32 v30, v9 offset:660
	ds_read_b32 v31, v9 offset:792
	ds_read_b32 v32, v9 offset:924
	s_waitcnt lgkmcnt(6)
	v_cvt_pk_bf16_f32 v26, v25, v26
	s_waitcnt lgkmcnt(4)
	v_cvt_pk_bf16_f32 v27, v27, v28
	s_waitcnt lgkmcnt(2)
	v_cvt_pk_bf16_f32 v28, v29, v30
	s_waitcnt lgkmcnt(0)
	v_cvt_pk_bf16_f32 v29, v31, v32
	global_store_dwordx4 v[62:63], v[26:29], off
	ds_read_b32 v25, v9 offset:32
	ds_read_b32 v26, v9 offset:164
	ds_read_b32 v27, v9 offset:296
	ds_read_b32 v28, v9 offset:428
	ds_read_b32 v29, v9 offset:560
	ds_read_b32 v30, v9 offset:692
	ds_read_b32 v31, v9 offset:824
	ds_read_b32 v32, v9 offset:956
	s_waitcnt lgkmcnt(0)
	v_cvt_pk_bf16_f32 v26, v25, v26
	v_cvt_pk_bf16_f32 v27, v27, v28
	v_cvt_pk_bf16_f32 v28, v29, v30
	v_cvt_pk_bf16_f32 v29, v31, v32
	global_store_dwordx4 v[64:65], v[26:29], off
	ds_read_b32 v25, v9 offset:64
	ds_read_b32 v26, v9 offset:196
	ds_read_b32 v27, v9 offset:328
	ds_read_b32 v28, v9 offset:460
	ds_read_b32 v29, v9 offset:592
	ds_read_b32 v30, v9 offset:724
	ds_read_b32 v31, v9 offset:856
	ds_read_b32 v32, v9 offset:988
	s_waitcnt lgkmcnt(0)
	v_cvt_pk_bf16_f32 v26, v25, v26
	v_cvt_pk_bf16_f32 v27, v27, v28
	v_cvt_pk_bf16_f32 v28, v29, v30
	v_cvt_pk_bf16_f32 v29, v31, v32
	global_store_dwordx4 v[66:67], v[26:29], off
	ds_read_b32 v25, v9 offset:96
	ds_read_b32 v26, v9 offset:228
	ds_read_b32 v27, v9 offset:360
	ds_read_b32 v28, v9 offset:492
	ds_read_b32 v29, v9 offset:624
	ds_read_b32 v30, v9 offset:756
	ds_read_b32 v31, v9 offset:888
	ds_read_b32 v32, v9 offset:1020
	s_waitcnt lgkmcnt(0)
	v_cvt_pk_bf16_f32 v26, v25, v26
	v_cvt_pk_bf16_f32 v27, v27, v28
	v_cvt_pk_bf16_f32 v28, v29, v30
	v_cvt_pk_bf16_f32 v29, v31, v32
	global_store_dwordx4 v[46:47], v[26:29], off
	s_cbranch_scc1 .LBB0_18

.LBB0_21:
	s_ashr_i32 s4, s11, 31
	s_lshr_b32 s4, s4, 25
	s_add_i32 s4, s11, s4
	s_ashr_i32 s5, s4, 7
	s_lshl_b32 s4, s5, 6
	s_lshl_b32 s5, s5, 12
	v_or_b32_e32 v26, s4, v8
	s_sub_i32 s6, s8, s5
	v_or_b32_e32 v28, 8, v26
	s_ashr_i32 s7, s6, 31
	v_ashrrev_i32_e32 v27, 31, v26
	v_or_b32_e32 v30, 16, v26
	v_or_b32_e32 v32, 24, v26
	v_or_b32_e32 v34, 32, v26
	v_or_b32_e32 v36, 40, v26
	v_or_b32_e32 v38, 48, v26
	v_or_b32_e32 v40, 56, v26
	v_ashrrev_i32_e32 v29, 31, v28
	v_lshl_add_u64 v[42:43], s[6:7], 2, v[2:3]
	v_lshlrev_b64 v[26:27], 14, v[26:27]
	v_ashrrev_i32_e32 v31, 31, v30
	v_ashrrev_i32_e32 v33, 31, v32
	v_ashrrev_i32_e32 v35, 31, v34
	v_ashrrev_i32_e32 v37, 31, v36
	v_ashrrev_i32_e32 v39, 31, v38
	v_ashrrev_i32_e32 v41, 31, v40
	v_lshlrev_b64 v[44:45], 14, v[28:29]
	v_lshl_add_u64 v[26:27], v[42:43], 0, v[26:27]
	v_lshlrev_b64 v[30:31], 14, v[30:31]
	v_lshlrev_b64 v[32:33], 14, v[32:33]
	v_lshlrev_b64 v[34:35], 14, v[34:35]
	v_lshlrev_b64 v[36:37], 14, v[36:37]
	v_lshlrev_b64 v[38:39], 14, v[38:39]
	v_lshlrev_b64 v[40:41], 14, v[40:41]
	v_lshl_add_u64 v[46:47], v[42:43], 0, v[44:45]
	global_load_dwordx4 v[26:29], v[26:27], off
	v_lshl_add_u64 v[62:63], v[42:43], 0, v[30:31]
	v_lshl_add_u64 v[64:65], v[42:43], 0, v[32:33]
	v_lshl_add_u64 v[66:67], v[42:43], 0, v[34:35]
	v_lshl_add_u64 v[68:69], v[42:43], 0, v[36:37]
	v_lshl_add_u64 v[70:71], v[42:43], 0, v[38:39]
	v_lshl_add_u64 v[72:73], v[42:43], 0, v[40:41]
	global_load_dwordx4 v[30:33], v[46:47], off
	global_load_dwordx4 v[34:37], v[62:63], off
	global_load_dwordx4 v[38:41], v[64:65], off
	global_load_dwordx4 v[42:45], v[66:67], off
	global_load_dwordx4 v[50:53], v[68:69], off
	global_load_dwordx4 v[54:57], v[70:71], off
	global_load_dwordx4 v[58:61], v[72:73], off
	v_add_u32_e32 v62, s6, v8
	s_ashr_i32 s5, s4, 31
	v_ashrrev_i32_e32 v63, 31, v62
	v_lshl_add_u64 v[46:47], s[4:5], 1, v[4:5]
	v_add_u32_e32 v64, 8, v62
	v_add_u32_e32 v66, 16, v62
	v_add_u32_e32 v68, 24, v62
	v_lshlrev_b64 v[62:63], 11, v[62:63]
	v_lshl_add_u64 v[62:63], v[46:47], 0, v[62:63]
	v_ashrrev_i32_e32 v65, 31, v64
	v_lshlrev_b64 v[64:65], 11, v[64:65]
	v_lshl_add_u64 v[64:65], v[46:47], 0, v[64:65]
	v_ashrrev_i32_e32 v67, 31, v66
	v_lshlrev_b64 v[66:67], 11, v[66:67]
	v_lshl_add_u64 v[66:67], v[46:47], 0, v[66:67]
	v_ashrrev_i32_e32 v69, 31, v68
	s_add_i32 s11, s11, s12
	s_add_i32 s8, s8, s9
	v_lshlrev_b64 v[68:69], 11, v[68:69]
	s_cmpk_lt_i32 s11, 0x800
	v_lshl_add_u64 v[46:47], v[46:47], 0, v[68:69]
	s_waitcnt vmcnt(0) lgkmcnt(0)
	ds_write2_b32 v10, v26, v27 offset1:1
	ds_write2_b32 v10, v28, v29 offset0:2 offset1:3
	ds_write2_b32 v11, v30, v31 offset1:1
	ds_write2_b32 v12, v32, v33 offset1:1
	ds_write2_b32 v13, v34, v35 offset1:1
	ds_write2_b32 v14, v36, v37 offset1:1
	ds_write2_b32 v15, v38, v39 offset1:1
	ds_write2_b32 v16, v40, v41 offset1:1
	ds_write2_b32 v17, v42, v43 offset1:1
	ds_write2_b32 v18, v44, v45 offset1:1
	ds_write2_b32 v19, v50, v51 offset1:1
	ds_write2_b32 v20, v52, v53 offset1:1
	ds_write2_b32 v21, v54, v55 offset1:1
	ds_write2_b32 v22, v56, v57 offset1:1
	ds_write2_b32 v23, v58, v59 offset1:1
	ds_write2_b32 v24, v60, v61 offset1:1
	ds_read_b32 v25, v9
	ds_read_b32 v26, v9 offset:132
	ds_read_b32 v27, v9 offset:264
	ds_read_b32 v28, v9 offset:396
	ds_read_b32 v29, v9 offset:528
	ds_read_b32 v30, v9 offset:660
	ds_read_b32 v31, v9 offset:792
	ds_read_b32 v32, v9 offset:924
	s_waitcnt lgkmcnt(6)
	v_cvt_pk_bf16_f32 v26, v25, v26
	s_waitcnt lgkmcnt(4)
	v_cvt_pk_bf16_f32 v27, v27, v28
	s_waitcnt lgkmcnt(2)
	v_cvt_pk_bf16_f32 v28, v29, v30
	s_waitcnt lgkmcnt(0)
	v_cvt_pk_bf16_f32 v29, v31, v32
	global_store_dwordx4 v[62:63], v[26:29], off
	ds_read_b32 v25, v9 offset:32
	ds_read_b32 v26, v9 offset:164
	ds_read_b32 v27, v9 offset:296
	ds_read_b32 v28, v9 offset:428
	ds_read_b32 v29, v9 offset:560
	ds_read_b32 v30, v9 offset:692
	ds_read_b32 v31, v9 offset:824
	ds_read_b32 v32, v9 offset:956
	s_waitcnt lgkmcnt(0)
	v_cvt_pk_bf16_f32 v26, v25, v26
	v_cvt_pk_bf16_f32 v27, v27, v28
	v_cvt_pk_bf16_f32 v28, v29, v30
	v_cvt_pk_bf16_f32 v29, v31, v32
	global_store_dwordx4 v[64:65], v[26:29], off
	ds_read_b32 v25, v9 offset:64
	ds_read_b32 v26, v9 offset:196
	ds_read_b32 v27, v9 offset:328
	ds_read_b32 v28, v9 offset:460
	ds_read_b32 v29, v9 offset:592
	ds_read_b32 v30, v9 offset:724
	ds_read_b32 v31, v9 offset:856
	ds_read_b32 v32, v9 offset:988
	s_waitcnt lgkmcnt(0)
	v_cvt_pk_bf16_f32 v26, v25, v26
	v_cvt_pk_bf16_f32 v27, v27, v28
	v_cvt_pk_bf16_f32 v28, v29, v30
	v_cvt_pk_bf16_f32 v29, v31, v32
	global_store_dwordx4 v[66:67], v[26:29], off
	ds_read_b32 v25, v9 offset:96
	ds_read_b32 v26, v9 offset:228
	ds_read_b32 v27, v9 offset:360
	ds_read_b32 v28, v9 offset:492
	ds_read_b32 v29, v9 offset:624
	ds_read_b32 v30, v9 offset:756
	ds_read_b32 v31, v9 offset:888
	ds_read_b32 v32, v9 offset:1020
	s_waitcnt lgkmcnt(0)
	v_cvt_pk_bf16_f32 v26, v25, v26
	v_cvt_pk_bf16_f32 v27, v27, v28
	v_cvt_pk_bf16_f32 v28, v29, v30
	v_cvt_pk_bf16_f32 v29, v31, v32
	global_store_dwordx4 v[46:47], v[26:29], off
	s_cbranch_scc1 .LBB0_21

.LBB0_26:
	s_ashr_i32 s0, s8, 31
	s_lshr_b32 s0, s0, 27
	s_add_i32 s0, s8, s0
	s_ashr_i32 s1, s0, 5
	s_lshl_b32 s0, s1, 6
	s_lshl_b32 s1, s1, 10
	v_or_b32_e32 v28, s0, v6
	s_sub_i32 s4, s6, s1
	v_or_b32_e32 v30, 8, v28
	s_ashr_i32 s5, s4, 31
	v_ashrrev_i32_e32 v29, 31, v28
	v_or_b32_e32 v32, 16, v28
	v_or_b32_e32 v34, 24, v28
	v_or_b32_e32 v36, 32, v28
	v_or_b32_e32 v38, 40, v28
	v_or_b32_e32 v44, 48, v28
	v_or_b32_e32 v46, 56, v28
	v_ashrrev_i32_e32 v31, 31, v30
	v_lshl_add_u64 v[52:53], s[4:5], 2, v[2:3]
	v_lshlrev_b64 v[28:29], 12, v[28:29]
	v_ashrrev_i32_e32 v33, 31, v32
	v_ashrrev_i32_e32 v35, 31, v34
	v_ashrrev_i32_e32 v37, 31, v36
	v_ashrrev_i32_e32 v39, 31, v38
	v_ashrrev_i32_e32 v45, 31, v44
	v_ashrrev_i32_e32 v47, 31, v46
	v_lshlrev_b64 v[54:55], 12, v[30:31]
	v_lshl_add_u64 v[28:29], v[52:53], 0, v[28:29]
	v_lshlrev_b64 v[32:33], 12, v[32:33]
	v_lshlrev_b64 v[34:35], 12, v[34:35]
	v_lshlrev_b64 v[36:37], 12, v[36:37]
	v_lshlrev_b64 v[38:39], 12, v[38:39]
	v_lshlrev_b64 v[44:45], 12, v[44:45]
	v_lshlrev_b64 v[46:47], 12, v[46:47]
	v_lshl_add_u64 v[68:69], v[52:53], 0, v[54:55]
	global_load_dwordx4 v[28:31], v[28:29], off
	v_lshl_add_u64 v[70:71], v[52:53], 0, v[32:33]
	v_lshl_add_u64 v[72:73], v[52:53], 0, v[34:35]
	v_lshl_add_u64 v[74:75], v[52:53], 0, v[36:37]
	v_lshl_add_u64 v[76:77], v[52:53], 0, v[38:39]
	v_lshl_add_u64 v[78:79], v[52:53], 0, v[44:45]
	v_lshl_add_u64 v[80:81], v[52:53], 0, v[46:47]
	global_load_dwordx4 v[32:35], v[68:69], off
	global_load_dwordx4 v[36:39], v[70:71], off
	global_load_dwordx4 v[44:47], v[72:73], off
	global_load_dwordx4 v[52:55], v[74:75], off
	global_load_dwordx4 v[56:59], v[76:77], off
	global_load_dwordx4 v[60:63], v[78:79], off
	global_load_dwordx4 v[64:67], v[80:81], off
	v_add_u32_e32 v70, s4, v6
	s_ashr_i32 s1, s0, 31
	v_ashrrev_i32_e32 v71, 31, v70
	v_lshl_add_u64 v[68:69], s[0:1], 1, v[4:5]
	v_add_u32_e32 v72, 8, v70
	v_add_u32_e32 v74, 16, v70
	v_add_u32_e32 v76, 24, v70
	v_lshlrev_b64 v[70:71], 13, v[70:71]
	v_lshl_add_u64 v[70:71], v[68:69], 0, v[70:71]
	v_ashrrev_i32_e32 v73, 31, v72
	v_lshlrev_b64 v[72:73], 13, v[72:73]
	v_lshl_add_u64 v[72:73], v[68:69], 0, v[72:73]
	v_ashrrev_i32_e32 v75, 31, v74
	v_lshlrev_b64 v[74:75], 13, v[74:75]
	v_lshl_add_u64 v[74:75], v[68:69], 0, v[74:75]
	v_ashrrev_i32_e32 v77, 31, v76
	s_add_i32 s8, s8, s12
	s_add_i32 s6, s6, s7
	v_lshlrev_b64 v[76:77], 13, v[76:77]
	s_cmpk_lt_i32 s8, 0x800
	v_lshl_add_u64 v[68:69], v[68:69], 0, v[76:77]
	s_waitcnt vmcnt(0) lgkmcnt(0)
	ds_write2_b32 v13, v28, v29 offset1:1
	ds_write2_b32 v13, v30, v31 offset0:2 offset1:3
	ds_write2_b32 v14, v32, v33 offset1:1
	ds_write2_b32 v15, v34, v35 offset1:1
	ds_write2_b32 v16, v36, v37 offset1:1
	ds_write2_b32 v17, v38, v39 offset1:1
	ds_write2_b32 v18, v44, v45 offset1:1
	ds_write2_b32 v19, v46, v47 offset1:1
	ds_write2_b32 v20, v52, v53 offset1:1
	ds_write2_b32 v21, v54, v55 offset1:1
	ds_write2_b32 v22, v56, v57 offset1:1
	ds_write2_b32 v23, v58, v59 offset1:1
	ds_write2_b32 v24, v60, v61 offset1:1
	ds_write2_b32 v25, v62, v63 offset1:1
	ds_write2_b32 v26, v64, v65 offset1:1
	ds_write2_b32 v27, v66, v67 offset1:1
	ds_read_b32 v28, v7
	ds_read_b32 v29, v7 offset:132
	ds_read_b32 v30, v7 offset:264
	ds_read_b32 v31, v7 offset:396
	ds_read_b32 v32, v7 offset:528
	ds_read_b32 v33, v7 offset:660
	ds_read_b32 v34, v7 offset:792
	ds_read_b32 v35, v7 offset:924
	s_waitcnt lgkmcnt(6)
	v_cvt_pk_bf16_f32 v28, v28, v29
	s_waitcnt lgkmcnt(4)
	v_cvt_pk_bf16_f32 v29, v30, v31
	s_waitcnt lgkmcnt(2)
	v_cvt_pk_bf16_f32 v30, v32, v33
	s_waitcnt lgkmcnt(0)
	v_cvt_pk_bf16_f32 v31, v34, v35
	global_store_dwordx4 v[70:71], v[28:31], off
	ds_read_b32 v28, v7 offset:32
	ds_read_b32 v29, v7 offset:164
	ds_read_b32 v30, v7 offset:296
	ds_read_b32 v31, v7 offset:428
	ds_read_b32 v32, v7 offset:560
	ds_read_b32 v33, v7 offset:692
	ds_read_b32 v34, v7 offset:824
	ds_read_b32 v35, v7 offset:956
	s_waitcnt lgkmcnt(0)
	v_cvt_pk_bf16_f32 v28, v28, v29
	v_cvt_pk_bf16_f32 v29, v30, v31
	v_cvt_pk_bf16_f32 v30, v32, v33
	v_cvt_pk_bf16_f32 v31, v34, v35
	global_store_dwordx4 v[72:73], v[28:31], off
	ds_read_b32 v28, v7 offset:64
	ds_read_b32 v29, v7 offset:196
	ds_read_b32 v30, v7 offset:328
	ds_read_b32 v31, v7 offset:460
	ds_read_b32 v32, v7 offset:592
	ds_read_b32 v33, v7 offset:724
	ds_read_b32 v34, v7 offset:856
	ds_read_b32 v35, v7 offset:988
	s_waitcnt lgkmcnt(0)
	v_cvt_pk_bf16_f32 v28, v28, v29
	v_cvt_pk_bf16_f32 v29, v30, v31
	v_cvt_pk_bf16_f32 v30, v32, v33
	v_cvt_pk_bf16_f32 v31, v34, v35
	global_store_dwordx4 v[74:75], v[28:31], off
	ds_read_b32 v28, v7 offset:96
	ds_read_b32 v29, v7 offset:228
	ds_read_b32 v30, v7 offset:360
	ds_read_b32 v31, v7 offset:492
	ds_read_b32 v32, v7 offset:624
	ds_read_b32 v33, v7 offset:756
	ds_read_b32 v34, v7 offset:888
	ds_read_b32 v35, v7 offset:1020
	s_waitcnt lgkmcnt(0)
	v_cvt_pk_bf16_f32 v28, v28, v29
	v_cvt_pk_bf16_f32 v29, v30, v31
	v_cvt_pk_bf16_f32 v30, v32, v33
	v_cvt_pk_bf16_f32 v31, v34, v35
	global_store_dwordx4 v[68:69], v[28:31], off
	s_cbranch_scc1 .LBB0_26
	v_mov_b32_e32 v38, v6

.LBB0_32:
	s_ashr_i32 s6, s17, 31
	s_lshr_b32 s6, s6, 27
	s_add_i32 s6, s17, s6
	s_ashr_i32 s6, s6, 5
	s_lshl_b32 s8, s6, 6
	s_lshl_b32 s6, s6, 10
	v_or_b32_e32 v20, s8, v38
	s_sub_i32 s6, s11, s6
	v_or_b32_e32 v22, 8, v20
	s_ashr_i32 s7, s6, 31
	v_ashrrev_i32_e32 v21, 31, v20
	v_or_b32_e32 v24, 16, v20
	v_or_b32_e32 v26, 24, v20
	v_or_b32_e32 v28, 32, v20
	v_or_b32_e32 v30, 40, v20
	v_or_b32_e32 v32, 48, v20
	v_or_b32_e32 v34, 56, v20
	v_ashrrev_i32_e32 v23, 31, v22
	v_lshl_add_u64 v[36:37], s[6:7], 2, v[6:7]
	v_lshlrev_b64 v[20:21], 12, v[20:21]
	v_ashrrev_i32_e32 v25, 31, v24
	v_ashrrev_i32_e32 v27, 31, v26
	v_ashrrev_i32_e32 v29, 31, v28
	v_ashrrev_i32_e32 v31, 31, v30
	v_ashrrev_i32_e32 v33, 31, v32
	v_ashrrev_i32_e32 v35, 31, v34
	v_lshlrev_b64 v[44:45], 12, v[22:23]
	v_lshl_add_u64 v[20:21], v[36:37], 0, v[20:21]
	v_lshlrev_b64 v[24:25], 12, v[24:25]
	v_lshlrev_b64 v[26:27], 12, v[26:27]
	v_lshlrev_b64 v[28:29], 12, v[28:29]
	v_lshlrev_b64 v[30:31], 12, v[30:31]
	v_lshlrev_b64 v[32:33], 12, v[32:33]
	v_lshlrev_b64 v[34:35], 12, v[34:35]
	v_lshl_add_u64 v[74:75], v[36:37], 0, v[44:45]
	global_load_dwordx4 v[20:23], v[20:21], off
	v_lshl_add_u64 v[76:77], v[36:37], 0, v[24:25]
	v_lshl_add_u64 v[78:79], v[36:37], 0, v[26:27]
	v_lshl_add_u64 v[80:81], v[36:37], 0, v[28:29]
	v_lshl_add_u64 v[82:83], v[36:37], 0, v[30:31]
	v_lshl_add_u64 v[84:85], v[36:37], 0, v[32:33]
	v_lshl_add_u64 v[36:37], v[36:37], 0, v[34:35]
	global_load_dwordx4 v[24:27], v[74:75], off
	global_load_dwordx4 v[28:31], v[76:77], off
	global_load_dwordx4 v[32:35], v[78:79], off
	global_load_dwordx4 v[44:47], v[80:81], off
	global_load_dwordx4 v[62:65], v[82:83], off
	global_load_dwordx4 v[66:69], v[84:85], off
	global_load_dwordx4 v[70:73], v[36:37], off
	v_add_u32_e32 v74, s6, v38
	s_ashr_i32 s9, s8, 31
	v_ashrrev_i32_e32 v75, 31, v74
	v_lshl_add_u64 v[36:37], s[8:9], 1, v[8:9]
	v_lshlrev_b64 v[74:75], 9, v[74:75]
	v_lshl_add_u64 v[74:75], v[36:37], 0, v[74:75]
	v_add_u32_e32 v76, s6, v49
	v_ashrrev_i32_e32 v77, 31, v76
	v_lshlrev_b64 v[76:77], 9, v[76:77]
	v_lshl_add_u64 v[76:77], v[36:37], 0, v[76:77]
	v_add_u32_e32 v78, s6, v50
	v_ashrrev_i32_e32 v79, 31, v78
	v_lshlrev_b64 v[78:79], 9, v[78:79]
	v_lshl_add_u64 v[78:79], v[36:37], 0, v[78:79]
	v_add_u32_e32 v80, s6, v51
	v_ashrrev_i32_e32 v81, 31, v80
	s_add_i32 s17, s17, s12
	s_add_i32 s11, s11, s13
	v_lshlrev_b64 v[80:81], 9, v[80:81]
	s_cmpk_lt_i32 s17, 0x80
	v_lshl_add_u64 v[36:37], v[36:37], 0, v[80:81]
	s_waitcnt vmcnt(0) lgkmcnt(0)
	ds_write2_b32 v56, v20, v21 offset1:1
	ds_write2_b32 v56, v22, v23 offset0:2 offset1:3
	ds_write2_b32 v57, v24, v25 offset1:1
	ds_write2_b32 v57, v26, v27 offset0:2 offset1:3
	ds_write2_b32 v58, v28, v29 offset1:1
	ds_write2_b32 v58, v30, v31 offset0:2 offset1:3
	ds_write2_b32 v59, v32, v33 offset1:1
	ds_write2_b32 v59, v34, v35 offset0:2 offset1:3
	ds_write2_b32 v10, v44, v45 offset1:1
	ds_write2_b32 v11, v46, v47 offset1:1
	ds_write2_b32 v13, v62, v63 offset1:1
	ds_write2_b32 v14, v64, v65 offset1:1
	ds_write2_b32 v15, v66, v67 offset1:1
	ds_write2_b32 v16, v68, v69 offset1:1
	ds_write2_b32 v17, v70, v71 offset1:1
	ds_write2_b32 v18, v72, v73 offset1:1
	ds_read2_b32 v[20:21], v52 offset1:33
	ds_read2_b32 v[22:23], v52 offset0:66 offset1:99
	ds_read2_b32 v[24:25], v52 offset0:132 offset1:165
	ds_read2_b32 v[26:27], v52 offset0:198 offset1:231
	s_waitcnt lgkmcnt(3)
	v_cvt_pk_bf16_f32 v20, v20, v21
	s_waitcnt lgkmcnt(2)
	v_cvt_pk_bf16_f32 v21, v22, v23
	s_waitcnt lgkmcnt(1)
	v_cvt_pk_bf16_f32 v22, v24, v25
	s_waitcnt lgkmcnt(0)
	v_cvt_pk_bf16_f32 v23, v26, v27
	global_store_dwordx4 v[74:75], v[20:23], off
	ds_read2_b32 v[20:21], v53 offset1:33
	ds_read2_b32 v[22:23], v53 offset0:66 offset1:99
	ds_read2_b32 v[24:25], v53 offset0:132 offset1:165
	ds_read2_b32 v[26:27], v53 offset0:198 offset1:231
	s_waitcnt lgkmcnt(0)
	v_cvt_pk_bf16_f32 v20, v20, v21
	v_cvt_pk_bf16_f32 v21, v22, v23
	v_cvt_pk_bf16_f32 v22, v24, v25
	v_cvt_pk_bf16_f32 v23, v26, v27
	global_store_dwordx4 v[76:77], v[20:23], off
	ds_read2_b32 v[20:21], v54 offset1:33
	ds_read2_b32 v[22:23], v54 offset0:66 offset1:99
	ds_read2_b32 v[24:25], v54 offset0:132 offset1:165
	ds_read2_b32 v[26:27], v54 offset0:198 offset1:231
	s_waitcnt lgkmcnt(0)
	v_cvt_pk_bf16_f32 v20, v20, v21
	v_cvt_pk_bf16_f32 v21, v22, v23
	v_cvt_pk_bf16_f32 v22, v24, v25
	v_cvt_pk_bf16_f32 v23, v26, v27
	global_store_dwordx4 v[78:79], v[20:23], off
	ds_read2_b32 v[20:21], v55 offset1:33
	ds_read2_b32 v[22:23], v55 offset0:66 offset1:99
	ds_read2_b32 v[24:25], v55 offset0:132 offset1:165
	ds_read2_b32 v[26:27], v55 offset0:198 offset1:231
	s_waitcnt lgkmcnt(0)
	v_cvt_pk_bf16_f32 v20, v20, v21
	v_cvt_pk_bf16_f32 v21, v22, v23
	v_cvt_pk_bf16_f32 v22, v24, v25
	v_cvt_pk_bf16_f32 v23, v26, v27
	global_store_dwordx4 v[36:37], v[20:23], off
	s_cbranch_scc1 .LBB0_32
	s_branch .LBB0_29

.LBB0_35:
	s_ashr_i32 s6, s11, 31
	s_lshr_b32 s6, s6, 27
	s_add_i32 s6, s11, s6
	s_ashr_i32 s6, s6, 5
	s_lshl_b32 s8, s6, 6
	s_lshl_b32 s6, s6, 10
	v_or_b32_e32 v16, s8, v38
	s_sub_i32 s6, s10, s6
	v_or_b32_e32 v18, 8, v16
	s_ashr_i32 s7, s6, 31
	v_ashrrev_i32_e32 v17, 31, v16
	v_or_b32_e32 v20, 16, v16
	v_or_b32_e32 v22, 24, v16
	v_or_b32_e32 v24, 32, v16
	v_or_b32_e32 v26, 40, v16
	v_or_b32_e32 v28, 48, v16
	v_or_b32_e32 v30, 56, v16
	v_ashrrev_i32_e32 v19, 31, v18
	v_lshl_add_u64 v[32:33], s[6:7], 2, v[4:5]
	v_lshlrev_b64 v[16:17], 12, v[16:17]
	v_ashrrev_i32_e32 v21, 31, v20
	v_ashrrev_i32_e32 v23, 31, v22
	v_ashrrev_i32_e32 v25, 31, v24
	v_ashrrev_i32_e32 v27, 31, v26
	v_ashrrev_i32_e32 v29, 31, v28
	v_ashrrev_i32_e32 v31, 31, v30
	v_lshlrev_b64 v[34:35], 12, v[18:19]
	v_lshl_add_u64 v[16:17], v[32:33], 0, v[16:17]
	v_lshlrev_b64 v[20:21], 12, v[20:21]
	v_lshlrev_b64 v[22:23], 12, v[22:23]
	v_lshlrev_b64 v[24:25], 12, v[24:25]
	v_lshlrev_b64 v[26:27], 12, v[26:27]
	v_lshlrev_b64 v[28:29], 12, v[28:29]
	v_lshlrev_b64 v[30:31], 12, v[30:31]
	v_lshl_add_u64 v[36:37], v[32:33], 0, v[34:35]
	global_load_dwordx4 v[16:19], v[16:17], off
	v_lshl_add_u64 v[70:71], v[32:33], 0, v[20:21]
	v_lshl_add_u64 v[72:73], v[32:33], 0, v[22:23]
	v_lshl_add_u64 v[74:75], v[32:33], 0, v[24:25]
	v_lshl_add_u64 v[76:77], v[32:33], 0, v[26:27]
	v_lshl_add_u64 v[78:79], v[32:33], 0, v[28:29]
	v_lshl_add_u64 v[80:81], v[32:33], 0, v[30:31]
	global_load_dwordx4 v[20:23], v[36:37], off
	global_load_dwordx4 v[24:27], v[70:71], off
	global_load_dwordx4 v[28:31], v[72:73], off
	global_load_dwordx4 v[32:35], v[74:75], off
	global_load_dwordx4 v[44:47], v[76:77], off
	global_load_dwordx4 v[62:65], v[78:79], off
	global_load_dwordx4 v[66:69], v[80:81], off
	v_add_u32_e32 v70, s6, v38
	s_ashr_i32 s9, s8, 31
	v_ashrrev_i32_e32 v71, 31, v70
	v_lshl_add_u64 v[36:37], s[8:9], 1, v[6:7]
	v_lshlrev_b64 v[70:71], 11, v[70:71]
	v_lshl_add_u64 v[70:71], v[36:37], 0, v[70:71]
	v_add_u32_e32 v72, s6, v49
	v_ashrrev_i32_e32 v73, 31, v72
	v_lshlrev_b64 v[72:73], 11, v[72:73]
	v_lshl_add_u64 v[72:73], v[36:37], 0, v[72:73]
	v_add_u32_e32 v74, s6, v50
	v_ashrrev_i32_e32 v75, 31, v74
	v_lshlrev_b64 v[74:75], 11, v[74:75]
	v_lshl_add_u64 v[74:75], v[36:37], 0, v[74:75]
	v_add_u32_e32 v76, s6, v51
	v_ashrrev_i32_e32 v77, 31, v76
	s_add_i32 s11, s11, s12
	s_add_i32 s10, s10, s13
	v_lshlrev_b64 v[76:77], 11, v[76:77]
	s_cmpk_lt_i32 s11, 0x200
	v_lshl_add_u64 v[36:37], v[36:37], 0, v[76:77]
	s_waitcnt vmcnt(0) lgkmcnt(0)
	ds_write2_b32 v56, v16, v17 offset1:1
	ds_write2_b32 v56, v18, v19 offset0:2 offset1:3
	ds_write2_b32 v57, v20, v21 offset1:1
	ds_write2_b32 v57, v22, v23 offset0:2 offset1:3
	ds_write2_b32 v58, v24, v25 offset1:1
	ds_write2_b32 v58, v26, v27 offset0:2 offset1:3
	ds_write2_b32 v59, v28, v29 offset1:1
	ds_write2_b32 v59, v30, v31 offset0:2 offset1:3
	ds_write2_b32 v8, v32, v33 offset1:1
	ds_write2_b32 v9, v34, v35 offset1:1
	ds_write2_b32 v10, v44, v45 offset1:1
	ds_write2_b32 v11, v46, v47 offset1:1
	ds_write2_b32 v12, v62, v63 offset1:1
	ds_write2_b32 v13, v64, v65 offset1:1
	ds_write2_b32 v14, v66, v67 offset1:1
	ds_write2_b32 v15, v68, v69 offset1:1
	ds_read2_b32 v[16:17], v52 offset1:33
	ds_read2_b32 v[18:19], v52 offset0:66 offset1:99
	ds_read2_b32 v[20:21], v52 offset0:132 offset1:165
	ds_read2_b32 v[22:23], v52 offset0:198 offset1:231
	s_waitcnt lgkmcnt(3)
	v_cvt_pk_bf16_f32 v16, v16, v17
	s_waitcnt lgkmcnt(2)
	v_cvt_pk_bf16_f32 v17, v18, v19
	s_waitcnt lgkmcnt(1)
	v_cvt_pk_bf16_f32 v18, v20, v21
	s_waitcnt lgkmcnt(0)
	v_cvt_pk_bf16_f32 v19, v22, v23
	global_store_dwordx4 v[70:71], v[16:19], off
	ds_read2_b32 v[16:17], v53 offset1:33
	ds_read2_b32 v[18:19], v53 offset0:66 offset1:99
	ds_read2_b32 v[20:21], v53 offset0:132 offset1:165
	ds_read2_b32 v[22:23], v53 offset0:198 offset1:231
	s_waitcnt lgkmcnt(0)
	v_cvt_pk_bf16_f32 v16, v16, v17
	v_cvt_pk_bf16_f32 v17, v18, v19
	v_cvt_pk_bf16_f32 v18, v20, v21
	v_cvt_pk_bf16_f32 v19, v22, v23
	global_store_dwordx4 v[72:73], v[16:19], off
	ds_read2_b32 v[16:17], v54 offset1:33
	ds_read2_b32 v[18:19], v54 offset0:66 offset1:99
	ds_read2_b32 v[20:21], v54 offset0:132 offset1:165
	ds_read2_b32 v[22:23], v54 offset0:198 offset1:231
	s_waitcnt lgkmcnt(0)
	v_cvt_pk_bf16_f32 v16, v16, v17
	v_cvt_pk_bf16_f32 v17, v18, v19
	v_cvt_pk_bf16_f32 v18, v20, v21
	v_cvt_pk_bf16_f32 v19, v22, v23
	global_store_dwordx4 v[74:75], v[16:19], off
	ds_read2_b32 v[16:17], v55 offset1:33
	ds_read2_b32 v[18:19], v55 offset0:66 offset1:99
	ds_read2_b32 v[20:21], v55 offset0:132 offset1:165
	ds_read2_b32 v[22:23], v55 offset0:198 offset1:231
	s_waitcnt lgkmcnt(0)
	v_cvt_pk_bf16_f32 v16, v16, v17
	v_cvt_pk_bf16_f32 v17, v18, v19
	v_cvt_pk_bf16_f32 v18, v20, v21
	v_cvt_pk_bf16_f32 v19, v22, v23
	global_store_dwordx4 v[36:37], v[16:19], off
	s_cbranch_scc1 .LBB0_35

.LBB0_38:
	s_ashr_i32 s4, s9, 31
	s_lshr_b32 s4, s4, 27
	s_add_i32 s4, s9, s4
	s_ashr_i32 s4, s4, 5
	s_lshl_b32 s6, s4, 6
	s_lshl_b32 s4, s4, 10
	v_or_b32_e32 v16, s6, v38
	s_sub_i32 s4, s8, s4
	v_or_b32_e32 v18, 8, v16
	s_ashr_i32 s5, s4, 31
	v_ashrrev_i32_e32 v17, 31, v16
	v_or_b32_e32 v20, 16, v16
	v_or_b32_e32 v22, 24, v16
	v_or_b32_e32 v24, 32, v16
	v_or_b32_e32 v26, 40, v16
	v_or_b32_e32 v28, 48, v16
	v_or_b32_e32 v30, 56, v16
	v_ashrrev_i32_e32 v19, 31, v18
	v_lshl_add_u64 v[32:33], s[4:5], 2, v[4:5]
	v_lshlrev_b64 v[16:17], 12, v[16:17]
	v_ashrrev_i32_e32 v21, 31, v20
	v_ashrrev_i32_e32 v23, 31, v22
	v_ashrrev_i32_e32 v25, 31, v24
	v_ashrrev_i32_e32 v27, 31, v26
	v_ashrrev_i32_e32 v29, 31, v28
	v_ashrrev_i32_e32 v31, 31, v30
	v_lshlrev_b64 v[34:35], 12, v[18:19]
	v_lshl_add_u64 v[16:17], v[32:33], 0, v[16:17]
	v_lshlrev_b64 v[20:21], 12, v[20:21]
	v_lshlrev_b64 v[22:23], 12, v[22:23]
	v_lshlrev_b64 v[24:25], 12, v[24:25]
	v_lshlrev_b64 v[26:27], 12, v[26:27]
	v_lshlrev_b64 v[28:29], 12, v[28:29]
	v_lshlrev_b64 v[30:31], 12, v[30:31]
	v_lshl_add_u64 v[36:37], v[32:33], 0, v[34:35]
	global_load_dwordx4 v[16:19], v[16:17], off
	v_lshl_add_u64 v[70:71], v[32:33], 0, v[20:21]
	v_lshl_add_u64 v[72:73], v[32:33], 0, v[22:23]
	v_lshl_add_u64 v[74:75], v[32:33], 0, v[24:25]
	v_lshl_add_u64 v[76:77], v[32:33], 0, v[26:27]
	v_lshl_add_u64 v[78:79], v[32:33], 0, v[28:29]
	v_lshl_add_u64 v[80:81], v[32:33], 0, v[30:31]
	global_load_dwordx4 v[20:23], v[36:37], off
	global_load_dwordx4 v[24:27], v[70:71], off
	global_load_dwordx4 v[28:31], v[72:73], off
	global_load_dwordx4 v[32:35], v[74:75], off
	global_load_dwordx4 v[44:47], v[76:77], off
	global_load_dwordx4 v[62:65], v[78:79], off
	global_load_dwordx4 v[66:69], v[80:81], off
	v_add_u32_e32 v70, s4, v38
	s_ashr_i32 s7, s6, 31
	v_ashrrev_i32_e32 v71, 31, v70
	v_lshl_add_u64 v[36:37], s[6:7], 1, v[6:7]
	v_lshlrev_b64 v[70:71], 11, v[70:71]
	v_lshl_add_u64 v[70:71], v[36:37], 0, v[70:71]
	v_add_u32_e32 v72, s4, v49
	v_ashrrev_i32_e32 v73, 31, v72
	v_lshlrev_b64 v[72:73], 11, v[72:73]
	v_lshl_add_u64 v[72:73], v[36:37], 0, v[72:73]
	v_add_u32_e32 v74, s4, v50
	v_ashrrev_i32_e32 v75, 31, v74
	v_lshlrev_b64 v[74:75], 11, v[74:75]
	v_lshl_add_u64 v[74:75], v[36:37], 0, v[74:75]
	v_add_u32_e32 v76, s4, v51
	v_ashrrev_i32_e32 v77, 31, v76
	s_add_i32 s9, s9, s12
	s_add_i32 s8, s8, s13
	v_lshlrev_b64 v[76:77], 11, v[76:77]
	s_cmpk_lt_i32 s9, 0x200
	v_lshl_add_u64 v[36:37], v[36:37], 0, v[76:77]
	s_waitcnt vmcnt(0) lgkmcnt(0)
	ds_write2_b32 v56, v16, v17 offset1:1
	ds_write2_b32 v56, v18, v19 offset0:2 offset1:3
	ds_write2_b32 v57, v20, v21 offset1:1
	ds_write2_b32 v57, v22, v23 offset0:2 offset1:3
	ds_write2_b32 v58, v24, v25 offset1:1
	ds_write2_b32 v58, v26, v27 offset0:2 offset1:3
	ds_write2_b32 v59, v28, v29 offset1:1
	ds_write2_b32 v59, v30, v31 offset0:2 offset1:3
	ds_write2_b32 v8, v32, v33 offset1:1
	ds_write2_b32 v9, v34, v35 offset1:1
	ds_write2_b32 v10, v44, v45 offset1:1
	ds_write2_b32 v11, v46, v47 offset1:1
	ds_write2_b32 v12, v62, v63 offset1:1
	ds_write2_b32 v13, v64, v65 offset1:1
	ds_write2_b32 v14, v66, v67 offset1:1
	ds_write2_b32 v15, v68, v69 offset1:1
	ds_read2_b32 v[16:17], v52 offset1:33
	ds_read2_b32 v[18:19], v52 offset0:66 offset1:99
	ds_read2_b32 v[20:21], v52 offset0:132 offset1:165
	ds_read2_b32 v[22:23], v52 offset0:198 offset1:231
	s_waitcnt lgkmcnt(3)
	v_cvt_pk_bf16_f32 v16, v16, v17
	s_waitcnt lgkmcnt(2)
	v_cvt_pk_bf16_f32 v17, v18, v19
	s_waitcnt lgkmcnt(1)
	v_cvt_pk_bf16_f32 v18, v20, v21
	s_waitcnt lgkmcnt(0)
	v_cvt_pk_bf16_f32 v19, v22, v23
	global_store_dwordx4 v[70:71], v[16:19], off
	ds_read2_b32 v[16:17], v53 offset1:33
	ds_read2_b32 v[18:19], v53 offset0:66 offset1:99
	ds_read2_b32 v[20:21], v53 offset0:132 offset1:165
	ds_read2_b32 v[22:23], v53 offset0:198 offset1:231
	s_waitcnt lgkmcnt(0)
	v_cvt_pk_bf16_f32 v16, v16, v17
	v_cvt_pk_bf16_f32 v17, v18, v19
	v_cvt_pk_bf16_f32 v18, v20, v21
	v_cvt_pk_bf16_f32 v19, v22, v23
	global_store_dwordx4 v[72:73], v[16:19], off
	ds_read2_b32 v[16:17], v54 offset1:33
	ds_read2_b32 v[18:19], v54 offset0:66 offset1:99
	ds_read2_b32 v[20:21], v54 offset0:132 offset1:165
	ds_read2_b32 v[22:23], v54 offset0:198 offset1:231
	s_waitcnt lgkmcnt(0)
	v_cvt_pk_bf16_f32 v16, v16, v17
	v_cvt_pk_bf16_f32 v17, v18, v19
	v_cvt_pk_bf16_f32 v18, v20, v21
	v_cvt_pk_bf16_f32 v19, v22, v23
	global_store_dwordx4 v[74:75], v[16:19], off
	ds_read2_b32 v[16:17], v55 offset1:33
	ds_read2_b32 v[18:19], v55 offset0:66 offset1:99
	ds_read2_b32 v[20:21], v55 offset0:132 offset1:165
	ds_read2_b32 v[22:23], v55 offset0:198 offset1:231
	s_waitcnt lgkmcnt(0)
	v_cvt_pk_bf16_f32 v16, v16, v17
	v_cvt_pk_bf16_f32 v17, v18, v19
	v_cvt_pk_bf16_f32 v18, v20, v21
	v_cvt_pk_bf16_f32 v19, v22, v23
	global_store_dwordx4 v[36:37], v[16:19], off
	s_cbranch_scc1 .LBB0_38

.LBB0_41:
	s_ashr_i32 s0, s7, 31
	s_lshr_b32 s0, s0, 27
	s_add_i32 s0, s7, s0
	s_ashr_i32 s0, s0, 5
	s_lshl_b32 s4, s0, 6
	s_lshl_b32 s0, s0, 10
	v_or_b32_e32 v16, s4, v38
	s_sub_i32 s0, s6, s0
	v_or_b32_e32 v18, 8, v16
	s_ashr_i32 s1, s0, 31
	v_ashrrev_i32_e32 v17, 31, v16
	v_or_b32_e32 v20, 16, v16
	v_or_b32_e32 v22, 24, v16
	v_or_b32_e32 v24, 32, v16
	v_or_b32_e32 v26, 40, v16
	v_or_b32_e32 v28, 48, v16
	v_or_b32_e32 v30, 56, v16
	v_ashrrev_i32_e32 v19, 31, v18
	v_lshl_add_u64 v[32:33], s[0:1], 2, v[4:5]
	v_lshlrev_b64 v[16:17], 12, v[16:17]
	v_ashrrev_i32_e32 v21, 31, v20
	v_ashrrev_i32_e32 v23, 31, v22
	v_ashrrev_i32_e32 v25, 31, v24
	v_ashrrev_i32_e32 v27, 31, v26
	v_ashrrev_i32_e32 v29, 31, v28
	v_ashrrev_i32_e32 v31, 31, v30
	v_lshlrev_b64 v[34:35], 12, v[18:19]
	v_lshl_add_u64 v[16:17], v[32:33], 0, v[16:17]
	v_lshlrev_b64 v[20:21], 12, v[20:21]
	v_lshlrev_b64 v[22:23], 12, v[22:23]
	v_lshlrev_b64 v[24:25], 12, v[24:25]
	v_lshlrev_b64 v[26:27], 12, v[26:27]
	v_lshlrev_b64 v[28:29], 12, v[28:29]
	v_lshlrev_b64 v[30:31], 12, v[30:31]
	v_lshl_add_u64 v[36:37], v[32:33], 0, v[34:35]
	global_load_dwordx4 v[16:19], v[16:17], off
	v_lshl_add_u64 v[70:71], v[32:33], 0, v[20:21]
	v_lshl_add_u64 v[72:73], v[32:33], 0, v[22:23]
	v_lshl_add_u64 v[74:75], v[32:33], 0, v[24:25]
	v_lshl_add_u64 v[76:77], v[32:33], 0, v[26:27]
	v_lshl_add_u64 v[78:79], v[32:33], 0, v[28:29]
	v_lshl_add_u64 v[80:81], v[32:33], 0, v[30:31]
	global_load_dwordx4 v[20:23], v[36:37], off
	global_load_dwordx4 v[24:27], v[70:71], off
	global_load_dwordx4 v[28:31], v[72:73], off
	global_load_dwordx4 v[32:35], v[74:75], off
	global_load_dwordx4 v[44:47], v[76:77], off
	global_load_dwordx4 v[62:65], v[78:79], off
	global_load_dwordx4 v[66:69], v[80:81], off
	v_add_u32_e32 v70, s0, v38
	s_ashr_i32 s5, s4, 31
	v_ashrrev_i32_e32 v71, 31, v70
	v_lshl_add_u64 v[36:37], s[4:5], 1, v[6:7]
	v_lshlrev_b64 v[70:71], 9, v[70:71]
	v_lshl_add_u64 v[70:71], v[36:37], 0, v[70:71]
	v_add_u32_e32 v72, s0, v49
	v_ashrrev_i32_e32 v73, 31, v72
	v_lshlrev_b64 v[72:73], 9, v[72:73]
	v_lshl_add_u64 v[72:73], v[36:37], 0, v[72:73]
	v_add_u32_e32 v74, s0, v50
	v_ashrrev_i32_e32 v75, 31, v74
	v_lshlrev_b64 v[74:75], 9, v[74:75]
	v_lshl_add_u64 v[74:75], v[36:37], 0, v[74:75]
	v_add_u32_e32 v76, s0, v51
	v_ashrrev_i32_e32 v77, 31, v76
	s_add_i32 s7, s7, s12
	s_add_i32 s6, s6, s13
	v_lshlrev_b64 v[76:77], 9, v[76:77]
	s_cmpk_lt_i32 s7, 0x80
	v_lshl_add_u64 v[36:37], v[36:37], 0, v[76:77]
	s_waitcnt vmcnt(0) lgkmcnt(0)
	ds_write2_b32 v56, v16, v17 offset1:1
	ds_write2_b32 v56, v18, v19 offset0:2 offset1:3
	ds_write2_b32 v57, v20, v21 offset1:1
	ds_write2_b32 v57, v22, v23 offset0:2 offset1:3
	ds_write2_b32 v58, v24, v25 offset1:1
	ds_write2_b32 v58, v26, v27 offset0:2 offset1:3
	ds_write2_b32 v59, v28, v29 offset1:1
	ds_write2_b32 v59, v30, v31 offset0:2 offset1:3
	ds_write2_b32 v8, v32, v33 offset1:1
	ds_write2_b32 v9, v34, v35 offset1:1
	ds_write2_b32 v10, v44, v45 offset1:1
	ds_write2_b32 v11, v46, v47 offset1:1
	ds_write2_b32 v12, v62, v63 offset1:1
	ds_write2_b32 v13, v64, v65 offset1:1
	ds_write2_b32 v14, v66, v67 offset1:1
	ds_write2_b32 v15, v68, v69 offset1:1
	ds_read2_b32 v[16:17], v52 offset1:33
	ds_read2_b32 v[18:19], v52 offset0:66 offset1:99
	ds_read2_b32 v[20:21], v52 offset0:132 offset1:165
	ds_read2_b32 v[22:23], v52 offset0:198 offset1:231
	s_waitcnt lgkmcnt(3)
	v_cvt_pk_bf16_f32 v16, v16, v17
	s_waitcnt lgkmcnt(2)
	v_cvt_pk_bf16_f32 v17, v18, v19
	s_waitcnt lgkmcnt(1)
	v_cvt_pk_bf16_f32 v18, v20, v21
	s_waitcnt lgkmcnt(0)
	v_cvt_pk_bf16_f32 v19, v22, v23
	global_store_dwordx4 v[70:71], v[16:19], off
	ds_read2_b32 v[16:17], v53 offset1:33
	ds_read2_b32 v[18:19], v53 offset0:66 offset1:99
	ds_read2_b32 v[20:21], v53 offset0:132 offset1:165
	ds_read2_b32 v[22:23], v53 offset0:198 offset1:231
	s_waitcnt lgkmcnt(0)
	v_cvt_pk_bf16_f32 v16, v16, v17
	v_cvt_pk_bf16_f32 v17, v18, v19
	v_cvt_pk_bf16_f32 v18, v20, v21
	v_cvt_pk_bf16_f32 v19, v22, v23
	global_store_dwordx4 v[72:73], v[16:19], off
	ds_read2_b32 v[16:17], v54 offset1:33
	ds_read2_b32 v[18:19], v54 offset0:66 offset1:99
	ds_read2_b32 v[20:21], v54 offset0:132 offset1:165
	ds_read2_b32 v[22:23], v54 offset0:198 offset1:231
	s_waitcnt lgkmcnt(0)
	v_cvt_pk_bf16_f32 v16, v16, v17
	v_cvt_pk_bf16_f32 v17, v18, v19
	v_cvt_pk_bf16_f32 v18, v20, v21
	v_cvt_pk_bf16_f32 v19, v22, v23
	global_store_dwordx4 v[74:75], v[16:19], off
	ds_read2_b32 v[16:17], v55 offset1:33
	ds_read2_b32 v[18:19], v55 offset0:66 offset1:99
	ds_read2_b32 v[20:21], v55 offset0:132 offset1:165
	ds_read2_b32 v[22:23], v55 offset0:198 offset1:231
	s_waitcnt lgkmcnt(0)
	v_cvt_pk_bf16_f32 v16, v16, v17
	v_cvt_pk_bf16_f32 v17, v18, v19
	v_cvt_pk_bf16_f32 v18, v20, v21
	v_cvt_pk_bf16_f32 v19, v22, v23
	global_store_dwordx4 v[36:37], v[16:19], off
	s_cbranch_scc1 .LBB0_41

.LBB0_44:
	ds_write2_b32 v66, v10, v11 offset1:1
	ds_write2_b32 v66, v12, v13 offset0:2 offset1:3
	ds_read2_b32 v[2:3], v52 offset1:33
	ds_read2_b32 v[4:5], v52 offset0:66 offset1:99
	ds_read2_b32 v[6:7], v52 offset0:132 offset1:165
	ds_read2_b32 v[8:9], v52 offset0:198 offset1:231
	v_lshl_add_u64 v[10:11], s[8:9], 1, v[46:47]
	s_waitcnt lgkmcnt(3)
	v_cvt_pk_bf16_f32 v2, v2, v3
	s_waitcnt lgkmcnt(2)
	v_cvt_pk_bf16_f32 v3, v4, v5
	s_waitcnt lgkmcnt(1)
	v_cvt_pk_bf16_f32 v4, v6, v7
	v_add_u32_e32 v6, s6, v38
	v_ashrrev_i32_e32 v7, 31, v6
	v_lshlrev_b64 v[6:7], 9, v[6:7]
	s_waitcnt lgkmcnt(0)
	v_cvt_pk_bf16_f32 v5, v8, v9
	v_lshl_add_u64 v[6:7], v[10:11], 0, v[6:7]
	global_store_dwordx4 v[6:7], v[2:5], off
	ds_read2_b32 v[2:3], v53 offset1:33
	ds_read2_b32 v[4:5], v53 offset0:66 offset1:99
	ds_read2_b32 v[6:7], v53 offset0:132 offset1:165
	ds_read2_b32 v[8:9], v53 offset0:198 offset1:231
	s_add_i32 s19, s19, s12
	s_waitcnt lgkmcnt(0)
	v_cvt_pk_bf16_f32 v2, v2, v3
	v_cvt_pk_bf16_f32 v3, v4, v5
	v_cvt_pk_bf16_f32 v4, v6, v7
	v_add_u32_e32 v6, s6, v49
	v_ashrrev_i32_e32 v7, 31, v6
	v_lshlrev_b64 v[6:7], 9, v[6:7]
	v_cvt_pk_bf16_f32 v5, v8, v9
	v_lshl_add_u64 v[6:7], v[10:11], 0, v[6:7]
	global_store_dwordx4 v[6:7], v[2:5], off
	ds_read2_b32 v[2:3], v54 offset1:33
	ds_read2_b32 v[4:5], v54 offset0:66 offset1:99
	ds_read2_b32 v[6:7], v54 offset0:132 offset1:165
	ds_read2_b32 v[8:9], v54 offset0:198 offset1:231
	s_add_i32 s17, s17, s13
	s_waitcnt lgkmcnt(0)
	v_cvt_pk_bf16_f32 v2, v2, v3
	v_cvt_pk_bf16_f32 v3, v4, v5
	v_cvt_pk_bf16_f32 v4, v6, v7
	v_add_u32_e32 v6, s6, v50
	v_ashrrev_i32_e32 v7, 31, v6
	v_lshlrev_b64 v[6:7], 9, v[6:7]
	v_cvt_pk_bf16_f32 v5, v8, v9
	v_lshl_add_u64 v[6:7], v[10:11], 0, v[6:7]
	global_store_dwordx4 v[6:7], v[2:5], off
	ds_read2_b32 v[2:3], v55 offset1:33
	ds_read2_b32 v[4:5], v55 offset0:66 offset1:99
	ds_read2_b32 v[6:7], v55 offset0:132 offset1:165
	ds_read2_b32 v[8:9], v55 offset0:198 offset1:231
	s_cmp_lt_i32 s19, 48
	s_waitcnt lgkmcnt(0)
	v_cvt_pk_bf16_f32 v2, v2, v3
	v_cvt_pk_bf16_f32 v3, v4, v5
	v_cvt_pk_bf16_f32 v4, v6, v7
	v_add_u32_e32 v6, s6, v51
	v_ashrrev_i32_e32 v7, 31, v6
	v_lshlrev_b64 v[6:7], 9, v[6:7]
	v_cvt_pk_bf16_f32 v5, v8, v9
	v_lshl_add_u64 v[6:7], v[10:11], 0, v[6:7]
	global_store_dwordx4 v[6:7], v[2:5], off
	s_cbranch_scc0 .LBB0_61
.LBB0_45:
	s_mul_hi_i32 s6, s19, 0x2aaaaaab
	s_lshr_b32 s7, s6, 31
	s_ashr_i32 s6, s6, 1
	s_add_i32 s6, s6, s7
	s_lshl_b32 s8, s6, 6
	s_mulk_i32 s6, 0xfe80
	s_add_i32 s6, s17, s6
	s_ashr_i32 s7, s6, 31
	v_or_b32_e32 v34, s8, v38
	v_lshl_add_u64 v[2:3], s[6:7], 2, v[44:45]
	v_mad_i64_i32 v[4:5], s[10:11], v34, s18, v[2:3]
	v_or_b32_e32 v6, 8, v34
	v_mad_i64_i32 v[6:7], s[10:11], v6, s18, v[2:3]
	global_load_dwordx4 v[26:29], v[4:5], off
	global_load_dwordx4 v[30:33], v[6:7], off
	v_or_b32_e32 v4, 16, v34
	v_mad_i64_i32 v[4:5], s[10:11], v4, s18, v[2:3]
	v_or_b32_e32 v6, 24, v34
	v_mad_i64_i32 v[6:7], s[10:11], v6, s18, v[2:3]
	global_load_dwordx4 v[18:21], v[4:5], off
	global_load_dwordx4 v[22:25], v[6:7], off
	v_or_b32_e32 v4, 32, v34
	v_mad_i64_i32 v[4:5], s[10:11], v4, s18, v[2:3]
	v_or_b32_e32 v6, 40, v34
	v_mad_i64_i32 v[6:7], s[10:11], v6, s18, v[2:3]
	global_load_dwordx4 v[10:13], v[4:5], off
	global_load_dwordx4 v[14:17], v[6:7], off
	v_or_b32_e32 v4, 48, v34
	v_mad_i64_i32 v[36:37], s[10:11], v4, s18, v[2:3]
	v_or_b32_e32 v4, 56, v34
	v_mad_i64_i32 v[70:71], s[10:11], v4, s18, v[2:3]
	global_load_dwordx4 v[6:9], v[36:37], off
	global_load_dwordx4 v[2:5], v[70:71], off
	s_and_b64 vcc, exec, s[0:1]
	s_cbranch_vccnz .LBB0_56
	v_ashrrev_i32_e32 v35, 31, v34
	v_lshl_add_u64 v[34:35], v[34:35], 2, s[4:5]
	global_load_dword v34, v[34:35], off
	v_or_b32_e32 v36, s8, v49
	v_ashrrev_i32_e32 v37, 31, v36
	v_lshl_add_u64 v[36:37], v[36:37], 2, s[4:5]
	s_waitcnt vmcnt(0) lgkmcnt(0)
	v_pk_mul_f32 v[70:71], v[28:29], v[34:35] op_sel_hi:[1,0]
	v_pk_mul_f32 v[34:35], v[26:27], v[34:35] op_sel_hi:[1,0]
	ds_write2_b32 v56, v34, v35 offset1:1
	ds_write2_b32 v56, v70, v71 offset0:2 offset1:3
	global_load_dword v34, v[36:37], off
	s_waitcnt vmcnt(0) lgkmcnt(0)
	v_pk_mul_f32 v[36:37], v[32:33], v[34:35] op_sel_hi:[1,0]
	v_pk_mul_f32 v[34:35], v[30:31], v[34:35] op_sel_hi:[1,0]
	s_cbranch_execnz .LBB0_48

.LBB0_48:
	s_and_b64 vcc, exec, s[0:1]
	ds_write2_b32 v57, v34, v35 offset1:1
	ds_write2_b32 v57, v36, v37 offset0:2 offset1:3
	s_cbranch_vccnz .LBB0_57
	s_waitcnt vmcnt(0) lgkmcnt(0)
	v_or_b32_e32 v26, s8, v50
	v_ashrrev_i32_e32 v27, 31, v26
	v_lshl_add_u64 v[26:27], v[26:27], 2, s[4:5]
	global_load_dword v26, v[26:27], off
	v_or_b32_e32 v28, s8, v51
	v_ashrrev_i32_e32 v29, 31, v28
	v_lshl_add_u64 v[28:29], v[28:29], 2, s[4:5]
	s_waitcnt vmcnt(0) lgkmcnt(0)
	v_pk_mul_f32 v[30:31], v[20:21], v[26:27] op_sel_hi:[1,0]
	v_pk_mul_f32 v[26:27], v[18:19], v[26:27] op_sel_hi:[1,0]
	ds_write2_b32 v58, v26, v27 offset1:1
	ds_write2_b32 v58, v30, v31 offset0:2 offset1:3
	global_load_dword v26, v[28:29], off
	s_waitcnt vmcnt(0) lgkmcnt(0)
	v_pk_mul_f32 v[28:29], v[24:25], v[26:27] op_sel_hi:[1,0]
	v_pk_mul_f32 v[26:27], v[22:23], v[26:27] op_sel_hi:[1,0]
	s_cbranch_execnz .LBB0_51

.LBB0_51:
	s_and_b64 vcc, exec, s[0:1]
	s_waitcnt vmcnt(0) lgkmcnt(0)
	ds_write2_b32 v59, v26, v27 offset1:1
	ds_write2_b32 v59, v28, v29 offset0:2 offset1:3
	s_cbranch_vccnz .LBB0_58
	s_ashr_i32 s9, s8, 31
	v_lshl_add_u64 v[18:19], s[8:9], 0, v[38:39]
	v_lshl_add_u64 v[18:19], v[18:19], 2, s[4:5]
	global_load_dword v20, v[18:19], off offset:128
	s_waitcnt vmcnt(0) lgkmcnt(0)
	v_pk_mul_f32 v[22:23], v[12:13], v[20:21] op_sel_hi:[1,0]
	v_pk_mul_f32 v[20:21], v[10:11], v[20:21] op_sel_hi:[1,0]
	ds_write2_b32 v67, v20, v21 offset1:1
	ds_write2_b32 v67, v22, v23 offset0:2 offset1:3
	global_load_dword v18, v[18:19], off offset:160
	s_waitcnt vmcnt(0) lgkmcnt(0)
	v_pk_mul_f32 v[20:21], v[16:17], v[18:19] op_sel_hi:[1,0]
	v_pk_mul_f32 v[18:19], v[14:15], v[18:19] op_sel_hi:[1,0]
	s_cbranch_execnz .LBB0_54

.LBB0_54:
	s_and_b64 vcc, exec, s[0:1]
	ds_write2_b32 v65, v18, v19 offset1:1
	ds_write2_b32 v65, v20, v21 offset0:2 offset1:3
	s_cbranch_vccnz .LBB0_59
	s_ashr_i32 s9, s8, 31
	v_lshl_add_u64 v[10:11], s[8:9], 0, v[38:39]
	v_lshl_add_u64 v[10:11], v[10:11], 2, s[4:5]
	global_load_dword v12, v[10:11], off offset:192
	s_waitcnt vmcnt(0) lgkmcnt(0)
	v_pk_mul_f32 v[14:15], v[8:9], v[12:13] op_sel_hi:[1,0]
	v_pk_mul_f32 v[12:13], v[6:7], v[12:13] op_sel_hi:[1,0]
	ds_write2_b32 v68, v12, v13 offset1:1
	ds_write2_b32 v68, v14, v15 offset0:2 offset1:3
	global_load_dword v10, v[10:11], off offset:224
	s_waitcnt vmcnt(0) lgkmcnt(0)
	v_pk_mul_f32 v[12:13], v[4:5], v[10:11] op_sel_hi:[1,0]
	v_pk_mul_f32 v[10:11], v[2:3], v[10:11] op_sel_hi:[1,0]
	s_cbranch_execnz .LBB0_44
	s_branch .LBB0_60

.LBB0_63:
	ds_write2_b32 v45, v10, v11 offset1:1
	ds_write2_b32 v45, v12, v13 offset0:2 offset1:3
	ds_read2_b32 v[2:3], v52 offset1:33
	ds_read2_b32 v[4:5], v52 offset0:66 offset1:99
	ds_read2_b32 v[6:7], v52 offset0:132 offset1:165
	ds_read2_b32 v[8:9], v52 offset0:198 offset1:231
	s_sub_i32 s10, 0, s19
	s_add_i32 s10, s10, s17
	s_waitcnt lgkmcnt(3)
	v_cvt_pk_bf16_f32 v2, v2, v3
	s_waitcnt lgkmcnt(2)
	v_cvt_pk_bf16_f32 v3, v4, v5
	s_waitcnt lgkmcnt(1)
	v_cvt_pk_bf16_f32 v4, v6, v7
	v_add_u32_e32 v6, s10, v38
	v_ashrrev_i32_e32 v7, 31, v6
	v_lshl_add_u64 v[10:11], s[8:9], 1, v[42:43]
	v_lshlrev_b64 v[6:7], 9, v[6:7]
	s_waitcnt lgkmcnt(0)
	v_cvt_pk_bf16_f32 v5, v8, v9
	v_lshl_add_u64 v[6:7], v[10:11], 0, v[6:7]
	global_store_dwordx4 v[6:7], v[2:5], off
	ds_read2_b32 v[2:3], v53 offset1:33
	ds_read2_b32 v[4:5], v53 offset0:66 offset1:99
	ds_read2_b32 v[6:7], v53 offset0:132 offset1:165
	ds_read2_b32 v[8:9], v53 offset0:198 offset1:231
	s_add_i32 s18, s18, s12
	s_waitcnt lgkmcnt(0)
	v_cvt_pk_bf16_f32 v2, v2, v3
	v_cvt_pk_bf16_f32 v3, v4, v5
	v_cvt_pk_bf16_f32 v4, v6, v7
	v_add_u32_e32 v6, s10, v49
	v_ashrrev_i32_e32 v7, 31, v6
	v_lshlrev_b64 v[6:7], 9, v[6:7]
	v_cvt_pk_bf16_f32 v5, v8, v9
	v_lshl_add_u64 v[6:7], v[10:11], 0, v[6:7]
	global_store_dwordx4 v[6:7], v[2:5], off
	ds_read2_b32 v[2:3], v54 offset1:33
	ds_read2_b32 v[4:5], v54 offset0:66 offset1:99
	ds_read2_b32 v[6:7], v54 offset0:132 offset1:165
	ds_read2_b32 v[8:9], v54 offset0:198 offset1:231
	s_add_i32 s17, s17, s13
	s_waitcnt lgkmcnt(0)
	v_cvt_pk_bf16_f32 v2, v2, v3
	v_cvt_pk_bf16_f32 v3, v4, v5
	v_cvt_pk_bf16_f32 v4, v6, v7
	v_add_u32_e32 v6, s10, v50
	v_ashrrev_i32_e32 v7, 31, v6
	v_lshlrev_b64 v[6:7], 9, v[6:7]
	v_cvt_pk_bf16_f32 v5, v8, v9
	v_lshl_add_u64 v[6:7], v[10:11], 0, v[6:7]
	global_store_dwordx4 v[6:7], v[2:5], off
	ds_read2_b32 v[2:3], v55 offset1:33
	ds_read2_b32 v[4:5], v55 offset0:66 offset1:99
	ds_read2_b32 v[6:7], v55 offset0:132 offset1:165
	ds_read2_b32 v[8:9], v55 offset0:198 offset1:231
	s_cmp_lt_i32 s18, 32
	s_waitcnt lgkmcnt(0)
	v_cvt_pk_bf16_f32 v2, v2, v3
	v_cvt_pk_bf16_f32 v3, v4, v5
	v_cvt_pk_bf16_f32 v4, v6, v7
	v_add_u32_e32 v6, s10, v51
	v_ashrrev_i32_e32 v7, 31, v6
	v_lshlrev_b64 v[6:7], 9, v[6:7]
	v_cvt_pk_bf16_f32 v5, v8, v9
	v_lshl_add_u64 v[6:7], v[10:11], 0, v[6:7]
	global_store_dwordx4 v[6:7], v[2:5], off
	s_cbranch_scc0 .LBB0_80
.LBB0_64:
	s_ashr_i32 s8, s18, 31
	s_lshr_b32 s8, s8, 28
	s_add_i32 s8, s18, s8
	s_ashr_i32 s9, s8, 4
	s_lshl_b32 s8, s9, 6
	s_lshl_b32 s19, s9, 9
	s_sub_i32 s10, s17, s19
	v_or_b32_e32 v34, s8, v38
	s_ashr_i32 s11, s10, 31
	v_ashrrev_i32_e32 v35, 31, v34
	v_or_b32_e32 v6, 8, v34
	v_lshl_add_u64 v[2:3], s[10:11], 2, v[40:41]
	v_lshlrev_b64 v[4:5], 11, v[34:35]
	v_ashrrev_i32_e32 v7, 31, v6
	v_lshl_add_u64 v[4:5], v[2:3], 0, v[4:5]
	v_lshlrev_b64 v[6:7], 11, v[6:7]
	v_lshl_add_u64 v[6:7], v[2:3], 0, v[6:7]
	global_load_dwordx4 v[26:29], v[4:5], off
	global_load_dwordx4 v[30:33], v[6:7], off
	v_or_b32_e32 v4, 16, v34
	v_ashrrev_i32_e32 v5, 31, v4
	v_or_b32_e32 v6, 24, v34
	v_lshlrev_b64 v[4:5], 11, v[4:5]
	v_ashrrev_i32_e32 v7, 31, v6
	v_lshl_add_u64 v[4:5], v[2:3], 0, v[4:5]
	v_lshlrev_b64 v[6:7], 11, v[6:7]
	v_lshl_add_u64 v[6:7], v[2:3], 0, v[6:7]
	global_load_dwordx4 v[18:21], v[4:5], off
	global_load_dwordx4 v[22:25], v[6:7], off
	v_or_b32_e32 v4, 32, v34
	v_ashrrev_i32_e32 v5, 31, v4
	v_or_b32_e32 v6, 40, v34
	v_lshlrev_b64 v[4:5], 11, v[4:5]
	v_ashrrev_i32_e32 v7, 31, v6
	v_lshl_add_u64 v[4:5], v[2:3], 0, v[4:5]
	v_lshlrev_b64 v[6:7], 11, v[6:7]
	v_lshl_add_u64 v[6:7], v[2:3], 0, v[6:7]
	global_load_dwordx4 v[10:13], v[4:5], off
	global_load_dwordx4 v[14:17], v[6:7], off
	v_or_b32_e32 v4, 48, v34
	v_ashrrev_i32_e32 v5, 31, v4
	v_lshlrev_b64 v[4:5], 11, v[4:5]
	v_lshl_add_u64 v[36:37], v[2:3], 0, v[4:5]
	v_or_b32_e32 v4, 56, v34
	v_ashrrev_i32_e32 v5, 31, v4
	v_lshlrev_b64 v[4:5], 11, v[4:5]
	v_lshl_add_u64 v[60:61], v[2:3], 0, v[4:5]
	global_load_dwordx4 v[6:9], v[36:37], off
	global_load_dwordx4 v[2:5], v[60:61], off
	s_and_b64 vcc, exec, s[0:1]
	s_cbranch_vccnz .LBB0_75
	v_lshl_add_u64 v[34:35], v[34:35], 2, s[4:5]
	global_load_dword v34, v[34:35], off
	v_or_b32_e32 v36, s8, v49
	v_ashrrev_i32_e32 v37, 31, v36
	v_lshl_add_u64 v[36:37], v[36:37], 2, s[4:5]
	s_waitcnt vmcnt(0) lgkmcnt(0)
	v_pk_mul_f32 v[60:61], v[28:29], v[34:35] op_sel_hi:[1,0]
	v_pk_mul_f32 v[34:35], v[26:27], v[34:35] op_sel_hi:[1,0]
	ds_write2_b32 v56, v34, v35 offset1:1
	ds_write2_b32 v56, v60, v61 offset0:2 offset1:3
	global_load_dword v34, v[36:37], off
	s_waitcnt vmcnt(0) lgkmcnt(0)
	v_pk_mul_f32 v[36:37], v[32:33], v[34:35] op_sel_hi:[1,0]
	v_pk_mul_f32 v[34:35], v[30:31], v[34:35] op_sel_hi:[1,0]
	s_cbranch_execnz .LBB0_67

.LBB0_70:
	s_and_b64 vcc, exec, s[0:1]
	s_waitcnt vmcnt(0) lgkmcnt(0)
	ds_write2_b32 v59, v26, v27 offset1:1
	ds_write2_b32 v59, v28, v29 offset0:2 offset1:3
	s_cbranch_vccnz .LBB0_77
	s_ashr_i32 s9, s8, 31
	v_lshl_add_u64 v[18:19], s[8:9], 0, v[38:39]
	v_lshl_add_u64 v[18:19], v[18:19], 2, s[4:5]
	global_load_dword v20, v[18:19], off offset:128
	s_waitcnt vmcnt(0) lgkmcnt(0)
	v_pk_mul_f32 v[22:23], v[12:13], v[20:21] op_sel_hi:[1,0]
	v_pk_mul_f32 v[20:21], v[10:11], v[20:21] op_sel_hi:[1,0]
	ds_write2_b32 v46, v20, v21 offset1:1
	ds_write2_b32 v46, v22, v23 offset0:2 offset1:3
	global_load_dword v18, v[18:19], off offset:160
	s_waitcnt vmcnt(0) lgkmcnt(0)
	v_pk_mul_f32 v[20:21], v[16:17], v[18:19] op_sel_hi:[1,0]
	v_pk_mul_f32 v[18:19], v[14:15], v[18:19] op_sel_hi:[1,0]
	s_cbranch_execnz .LBB0_73

.LBB0_73:
	s_and_b64 vcc, exec, s[0:1]
	ds_write2_b32 v44, v18, v19 offset1:1
	ds_write2_b32 v44, v20, v21 offset0:2 offset1:3
	s_cbranch_vccnz .LBB0_78
	s_ashr_i32 s9, s8, 31
	v_lshl_add_u64 v[10:11], s[8:9], 0, v[38:39]
	v_lshl_add_u64 v[10:11], v[10:11], 2, s[4:5]
	global_load_dword v12, v[10:11], off offset:192
	s_waitcnt vmcnt(0) lgkmcnt(0)
	v_pk_mul_f32 v[14:15], v[8:9], v[12:13] op_sel_hi:[1,0]
	v_pk_mul_f32 v[12:13], v[6:7], v[12:13] op_sel_hi:[1,0]
	ds_write2_b32 v47, v12, v13 offset1:1
	ds_write2_b32 v47, v14, v15 offset0:2 offset1:3
	global_load_dword v10, v[10:11], off offset:224
	s_waitcnt vmcnt(0) lgkmcnt(0)
	v_pk_mul_f32 v[12:13], v[4:5], v[10:11] op_sel_hi:[1,0]
	v_pk_mul_f32 v[10:11], v[2:3], v[10:11] op_sel_hi:[1,0]
	s_cbranch_execnz .LBB0_63
	s_branch .LBB0_79

.LBB0_83:
	v_add_u32_e32 v10, -2, v10
	v_ashrrev_i32_e32 v13, 31, v5
	v_mov_b32_e32 v12, v5
	v_ashrrev_i32_e32 v15, 31, v4
	v_mov_b32_e32 v14, v4
	v_cmp_eq_u32_e32 vcc, 0, v10
	v_add_u32_e32 v5, s17, v5
	v_add_u32_e32 v4, s5, v4
	v_lshl_add_u64 v[14:15], v[14:15], 2, s[10:11]
	v_lshl_add_u64 v[12:13], v[12:13], 2, s[10:11]
	s_or_b64 s[12:13], vcc, s[12:13]
	global_store_dword v[14:15], v9, off
	global_store_dword v[12:13], v9, off
	s_andn2_b64 exec, exec, s[12:13]
	s_cbranch_execnz .LBB0_83
	s_or_b64 exec, exec, s[12:13]
	v_mad_u64_u32 v[4:5], s[10:11], v7, s4, v[2:3]
	v_cmp_ne_u32_e32 vcc, v6, v7
	s_orn2_b64 s[10:11], vcc, exec

.LBB0_87:
	v_add_u32_e32 v4, s4, v4
	v_cmp_lt_i32_e32 vcc, s5, v4
	global_store_dword v[6:7], v5, off
	s_or_b64 s[10:11], vcc, s[10:11]
	v_lshl_add_u64 v[6:7], v[6:7], 0, s[0:1]
	s_andn2_b64 exec, exec, s[10:11]
	s_cbranch_execnz .LBB0_87

.LBB0_99:
	v_add_u32_e32 v3, s5, v8
	v_add_u32_e32 v13, s12, v9
	v_ashrrev_i32_e32 v16, 6, v8
	v_ashrrev_i32_e32 v14, 6, v9
	v_add_u32_e32 v12, -4, v12
	v_ashrrev_i32_e32 v18, 6, v13
	v_ashrrev_i32_e32 v20, 6, v3
	v_ashrrev_i32_e32 v17, 31, v16
	v_ashrrev_i32_e32 v15, 31, v14
	v_cmp_eq_u32_e32 vcc, 0, v12
	v_ashrrev_i32_e32 v21, 31, v20
	v_ashrrev_i32_e32 v19, 31, v18
	v_lshlrev_b64 v[16:17], 9, v[16:17]
	v_add_u32_e32 v9, s17, v9
	v_add_u32_e32 v8, s13, v8
	v_lshlrev_b64 v[14:15], 9, v[14:15]
	s_or_b64 s[10:11], vcc, s[10:11]
	v_lshlrev_b64 v[18:19], 9, v[18:19]
	v_lshlrev_b64 v[20:21], 9, v[20:21]
	v_lshl_add_u64 v[16:17], v[6:7], 0, v[16:17]
	v_lshl_add_u64 v[14:15], v[6:7], 0, v[14:15]
	v_lshl_add_u64 v[20:21], v[6:7], 0, v[20:21]
	v_lshl_add_u64 v[18:19], v[6:7], 0, v[18:19]
	global_store_dword v[16:17], v5, off offset:256
	global_store_dword v[14:15], v5, off offset:256
	global_store_dword v[20:21], v5, off offset:256
	global_store_dword v[18:19], v5, off offset:256
	s_andn2_b64 exec, exec, s[10:11]
	s_cbranch_execnz .LBB0_99
	s_or_b64 exec, exec, s[10:11]
	v_mad_u64_u32 v[6:7], s[10:11], v11, s4, v[2:3]
	v_cmp_ne_u32_e32 vcc, v10, v11
	s_orn2_b64 s[10:11], vcc, exec

.LBB0_103:
	v_ashrrev_i32_e32 v10, 6, v6
	v_add_u32_e32 v6, s4, v6
	v_ashrrev_i32_e32 v11, 31, v10
	v_cmp_lt_i32_e32 vcc, s5, v6
	v_lshlrev_b64 v[10:11], 9, v[10:11]
	s_or_b64 s[0:1], vcc, s[0:1]
	v_lshl_add_u64 v[10:11], v[8:9], 0, v[10:11]
	global_store_dword v[10:11], v5, off offset:256
	s_andn2_b64 exec, exec, s[0:1]
	s_cbranch_execnz .LBB0_103

.LBB0_106:
	v_ashrrev_i32_e32 v7, 31, v6
	v_lshl_add_u64 v[18:19], v[6:7], 4, s[0:1]
	global_load_dwordx4 v[10:13], v[18:19], off
	global_load_dwordx4 v[14:17], v[18:19], off offset:16
	v_add_u32_e32 v8, s4, v8
	v_cmp_lt_i32_e32 vcc, s10, v8
	v_add_u32_e32 v6, s5, v6
	s_or_b64 s[8:9], vcc, s[8:9]
	s_waitcnt vmcnt(0) lgkmcnt(0)
	v_cvt_pk_bf16_f32 v10, v10, v11
	v_cvt_pk_bf16_f32 v11, v12, v13
	v_cvt_pk_bf16_f32 v12, v14, v15
	v_cvt_pk_bf16_f32 v13, v16, v17
	global_store_dwordx4 v[4:5], v[10:13], off
	v_lshl_add_u64 v[4:5], v[4:5], 0, s[2:3]
	s_andn2_b64 exec, exec, s[8:9]
	s_cbranch_execnz .LBB0_106

.LBB0_110:
	s_or_b64 exec, exec, s[10:11]
	v_ashrrev_i32_e32 v21, 4, v20
	v_cvt_f32_i32_e32 v21, v21
	v_mul_f64 v[12:13], v[12:13], v[14:15]
	v_cvt_f32_f64_e32 v12, v[12:13]
	v_add_u32_e32 v20, s4, v20
	v_mul_f32_e32 v12, v21, v12
	v_cvt_f64_f32_e32 v[12:13], v12
	v_mul_f64 v[14:15], v[12:13], s[8:9]
	v_floor_f64_e32 v[14:15], v[14:15]
	v_fma_f64 v[12:13], v[12:13], s[8:9], -v[14:15]
	v_cvt_f32_f64_e32 v13, v[12:13]
	v_cos_f32_e32 v14, v13
	v_add_co_u32_e32 v12, vcc, 0xfff80000, v6
	v_sin_f32_e32 v15, v13
	s_nop 0
	v_addc_co_u32_e32 v13, vcc, -1, v7, vcc
	v_cmp_lt_i32_e32 vcc, s5, v20
	global_store_dword v[12:13], v14, off
	global_store_dword v[6:7], v15, off
	s_or_b64 s[6:7], vcc, s[6:7]
	v_lshl_add_u64 v[6:7], v[6:7], 0, s[2:3]
	s_andn2_b64 exec, exec, s[6:7]
	s_cbranch_execz .LBB0_120

.LBB0_122:
	s_or_b64 exec, exec, s[10:11]
	v_cmp_lt_i32_e32 vcc, s12, v6
	v_sub_u32_e32 v5, 0, v5
	s_nop 0
	v_cndmask_b32_e64 v6, 0, 16, vcc
	v_add_u32_e32 v6, v7, v6
	v_lshl_add_u32 v6, v6, 4, v4
	v_ashrrev_i32_e32 v7, 31, v6
	v_lshl_add_u64 v[6:7], v[6:7], 2, s[0:1]
	global_load_dword v6, v[6:7], off
	v_mul_i32_i24_e32 v4, 0x104, v4
	v_add3_u32 v4, v4, v3, v5
	v_add_u32_e32 v3, s4, v3
	v_ashrrev_i32_e32 v5, 31, v4
	v_cmp_lt_i32_e32 vcc, s18, v3
	v_lshl_add_u64 v[4:5], v[4:5], 2, s[6:7]
	s_or_b64 s[8:9], vcc, s[8:9]
	s_waitcnt vmcnt(0) lgkmcnt(0)
	v_mul_f32_e32 v6, 0x3fb8aa3b, v6
	global_store_dword v[4:5], v6, off
	s_andn2_b64 exec, exec, s[8:9]
	s_cbranch_execz .LBB0_125

.LBB0_127:
	s_or_b64 exec, exec, s[10:11]
	v_cmp_lt_i32_e32 vcc, 64, v8
	v_ashrrev_i32_e32 v7, 31, v6
	s_nop 0
	v_cndmask_b32_e64 v4, 0, 16, vcc
	v_add_lshl_u32 v4, v3, v4, 4
	v_lshl_add_u64 v[8:9], v[6:7], 0, v[4:5]
	v_lshl_add_u64 v[8:9], v[8:9], 2, s[0:1]
	global_load_dword v3, v[8:9], off offset:16
	s_waitcnt vmcnt(0) lgkmcnt(0)
	v_mad_u64_u32 v[6:7], s[10:11], v6, 3, v[2:3]
	v_add_u32_e32 v2, s4, v2
	v_ashrrev_i32_e32 v7, 31, v6
	v_cmp_lt_i32_e32 vcc, s20, v2
	v_lshl_add_u64 v[6:7], v[6:7], 2, s[6:7]
	v_mul_f32_e32 v3, 0x3fb8aa3b, v3
	s_or_b64 s[8:9], vcc, s[8:9]
	global_store_dword v[6:7], v3, off
	s_andn2_b64 exec, exec, s[8:9]
	s_cbranch_execz .LBB0_130

.LBB0_132:
	s_or_b64 exec, exec, s[2:3]
	global_load_dwordx4 v[156:159], v[132:133], off
	global_load_dwordx4 v[160:163], v[134:135], off
	v_pk_mul_f32 v[168:169], v[106:107], v[120:121] op_sel_hi:[1,0]
	v_lshl_add_u64 v[106:107], s[54:55], 0, v[136:137]
	v_pk_mul_f32 v[164:165], v[18:19], v[56:57] op_sel_hi:[1,0]
	v_add_co_u32_e32 v18, vcc, s59, v106
	v_pk_mul_f32 v[170:171], v[20:21], v[56:57] op_sel_hi:[1,0]
	s_nop 0
	v_addc_co_u32_e32 v19, vcc, 0, v107, vcc
	v_add_co_u32_e32 v20, vcc, s68, v106
	v_pk_mul_f32 v[166:167], v[22:23], v[84:85] op_sel_hi:[1,0]
	s_nop 0
	v_addc_co_u32_e32 v21, vcc, 0, v107, vcc
	v_add_co_u32_e32 v22, vcc, s69, v106
	v_pk_mul_f32 v[110:111], v[110:111], v[124:125] op_sel_hi:[1,0]
	v_pk_mul_f32 v[114:115], v[114:115], v[128:129] op_sel_hi:[1,0]
	v_pk_mul_f32 v[118:119], v[118:119], v[150:151] op_sel_hi:[1,0]
	v_pk_mul_f32 v[122:123], v[122:123], v[152:153] op_sel_hi:[1,0]
	v_pk_mul_f32 v[126:127], v[126:127], v[154:155] op_sel_hi:[1,0]
	v_pk_mul_f32 v[142:143], v[142:143], v[84:85] op_sel_hi:[1,0]
	v_pk_mul_f32 v[108:109], v[108:109], v[120:121] op_sel_hi:[1,0]
	v_pk_mul_f32 v[112:113], v[112:113], v[124:125] op_sel_hi:[1,0]
	v_pk_mul_f32 v[116:117], v[116:117], v[128:129] op_sel_hi:[1,0]
	v_pk_mul_f32 v[144:145], v[144:145], v[150:151] op_sel_hi:[1,0]
	v_pk_mul_f32 v[146:147], v[146:147], v[152:153] op_sel_hi:[1,0]
	v_pk_mul_f32 v[148:149], v[148:149], v[154:155] op_sel_hi:[1,0]
	v_addc_co_u32_e32 v23, vcc, 0, v107, vcc
	v_add_co_u32_e32 v106, vcc, s70, v106
	v_pk_mul_f32 v[10:11], v[10:11], v[56:57] op_sel_hi:[1,0]
	s_nop 0
	v_addc_co_u32_e32 v107, vcc, 0, v107, vcc
	v_pk_mul_f32 v[12:13], v[12:13], v[56:57] op_sel_hi:[1,0]
	v_pk_mul_f32 v[14:15], v[14:15], v[84:85] op_sel_hi:[1,0]
	v_pk_mul_f32 v[70:71], v[70:71], v[120:121] op_sel_hi:[1,0]
	v_pk_mul_f32 v[86:87], v[86:87], v[124:125] op_sel_hi:[1,0]
	v_pk_mul_f32 v[90:91], v[90:91], v[128:129] op_sel_hi:[1,0]
	v_pk_mul_f32 v[94:95], v[94:95], v[150:151] op_sel_hi:[1,0]
	v_pk_mul_f32 v[98:99], v[98:99], v[152:153] op_sel_hi:[1,0]
	v_pk_mul_f32 v[102:103], v[102:103], v[154:155] op_sel_hi:[1,0]
	v_pk_mul_f32 v[72:73], v[72:73], v[120:121] op_sel_hi:[1,0]
	v_pk_mul_f32 v[88:89], v[88:89], v[124:125] op_sel_hi:[1,0]
	v_pk_mul_f32 v[92:93], v[92:93], v[128:129] op_sel_hi:[1,0]
	v_pk_mul_f32 v[96:97], v[96:97], v[150:151] op_sel_hi:[1,0]
	v_pk_mul_f32 v[100:101], v[100:101], v[152:153] op_sel_hi:[1,0]
	v_pk_mul_f32 v[104:105], v[104:105], v[154:155] op_sel_hi:[1,0]
	v_pk_mul_f32 v[8:9], v[8:9], v[56:57] op_sel_hi:[1,0]
	v_pk_mul_f32 v[6:7], v[6:7], v[56:57] op_sel_hi:[1,0]
	v_pk_mul_f32 v[46:47], v[46:47], v[84:85] op_sel_hi:[1,0]
	v_pk_mul_f32 v[58:59], v[58:59], v[120:121] op_sel_hi:[1,0]
	v_pk_mul_f32 v[62:63], v[62:63], v[124:125] op_sel_hi:[1,0]
	v_pk_mul_f32 v[66:67], v[66:67], v[128:129] op_sel_hi:[1,0]
	v_pk_mul_f32 v[74:75], v[74:75], v[150:151] op_sel_hi:[1,0]
	v_pk_mul_f32 v[78:79], v[78:79], v[152:153] op_sel_hi:[1,0]
	v_pk_mul_f32 v[52:53], v[52:53], v[154:155] op_sel_hi:[1,0]
	s_add_i32 s56, s56, s58
	v_pk_mul_f32 v[4:5], v[4:5], v[56:57] op_sel_hi:[1,0]
	v_pk_mul_f32 v[2:3], v[2:3], v[56:57] op_sel_hi:[1,0]
	s_add_u32 s60, s60, s62
	v_pk_mul_f32 v[24:25], v[24:25], v[120:121] op_sel_hi:[1,0]
	v_pk_mul_f32 v[28:29], v[28:29], v[124:125] op_sel_hi:[1,0]
	v_pk_mul_f32 v[32:33], v[32:33], v[128:129] op_sel_hi:[1,0]
	v_pk_mul_f32 v[36:37], v[36:37], v[150:151] op_sel_hi:[1,0]
	v_pk_mul_f32 v[40:41], v[40:41], v[152:153] op_sel_hi:[1,0]
	v_pk_mul_f32 v[44:45], v[44:45], v[154:155] op_sel_hi:[1,0]
	s_addc_u32 s61, s61, s63
	v_lshl_add_u64 v[136:137], v[136:137], 0, s[64:65]
	s_cmp_lt_i32 s56, 0x8000
	v_lshl_add_u64 v[138:139], v[138:139], 0, s[66:67]
	s_waitcnt vmcnt(0) lgkmcnt(0)
	v_pk_fma_f32 v[170:171], v[170:171], v[158:159], v[162:163]
	v_pk_fma_f32 v[164:165], v[164:165], v[156:157], v[160:161]
	v_pk_fma_f32 v[142:143], v[142:143], v[158:159], v[162:163]
	v_pk_fma_f32 v[166:167], v[166:167], v[156:157], v[160:161]
	v_pk_fma_f32 v[108:109], v[108:109], v[158:159], v[162:163]
	v_pk_fma_f32 v[168:169], v[168:169], v[156:157], v[160:161]
	v_pk_fma_f32 v[112:113], v[112:113], v[158:159], v[162:163]
	v_pk_fma_f32 v[110:111], v[110:111], v[156:157], v[160:161]
	v_pk_fma_f32 v[116:117], v[116:117], v[158:159], v[162:163]
	v_pk_fma_f32 v[114:115], v[114:115], v[156:157], v[160:161]
	v_pk_fma_f32 v[144:145], v[144:145], v[158:159], v[162:163]
	v_pk_fma_f32 v[118:119], v[118:119], v[156:157], v[160:161]
	v_pk_fma_f32 v[146:147], v[146:147], v[158:159], v[162:163]
	v_pk_fma_f32 v[122:123], v[122:123], v[156:157], v[160:161]
	v_pk_fma_f32 v[148:149], v[148:149], v[158:159], v[162:163]
	v_pk_fma_f32 v[126:127], v[126:127], v[156:157], v[160:161]
	v_cvt_pk_bf16_f32 v156, v164, v165
	v_cvt_pk_bf16_f32 v157, v170, v171
	v_cvt_pk_bf16_f32 v158, v166, v167
	v_cvt_pk_bf16_f32 v159, v142, v143
	v_cvt_pk_bf16_f32 v142, v168, v169
	v_cvt_pk_bf16_f32 v143, v108, v109
	v_cvt_pk_bf16_f32 v108, v110, v111
	v_cvt_pk_bf16_f32 v109, v112, v113
	v_cvt_pk_bf16_f32 v110, v114, v115
	v_cvt_pk_bf16_f32 v111, v116, v117
	v_cvt_pk_bf16_f32 v112, v118, v119
	v_cvt_pk_bf16_f32 v113, v144, v145
	v_cvt_pk_bf16_f32 v114, v122, v123
	v_cvt_pk_bf16_f32 v115, v146, v147
	v_cvt_pk_bf16_f32 v116, v126, v127
	v_cvt_pk_bf16_f32 v117, v148, v149
	global_store_dwordx2 v[18:19], v[156:157], off
	global_store_dwordx2 v[18:19], v[158:159], off offset:2048
	global_store_dwordx2 v[20:21], v[142:143], off
	global_store_dwordx2 v[20:21], v[108:109], off offset:2048
	global_store_dwordx2 v[22:23], v[110:111], off
	global_store_dwordx2 v[22:23], v[112:113], off offset:2048
	global_store_dwordx2 v[106:107], v[114:115], off
	global_store_dwordx2 v[106:107], v[116:117], off offset:2048
	global_load_dwordx4 v[108:111], v[132:133], off offset:1024
	s_nop 0
	global_load_dwordx4 v[112:115], v[134:135], off offset:1024
	v_pk_mul_f32 v[116:117], v[140:141], v[84:85] op_sel_hi:[1,0]
	s_waitcnt vmcnt(0) lgkmcnt(0)
	v_pk_fma_f32 v[12:13], v[12:13], v[110:111], v[114:115]
	v_pk_fma_f32 v[10:11], v[10:11], v[108:109], v[112:113]
	v_pk_fma_f32 v[116:117], v[116:117], v[110:111], v[114:115]
	v_pk_fma_f32 v[14:15], v[14:15], v[108:109], v[112:113]
	v_pk_fma_f32 v[72:73], v[72:73], v[110:111], v[114:115]
	v_pk_fma_f32 v[70:71], v[70:71], v[108:109], v[112:113]
	v_pk_fma_f32 v[88:89], v[88:89], v[110:111], v[114:115]
	v_pk_fma_f32 v[86:87], v[86:87], v[108:109], v[112:113]
	v_pk_fma_f32 v[92:93], v[92:93], v[110:111], v[114:115]
	v_pk_fma_f32 v[90:91], v[90:91], v[108:109], v[112:113]
	v_pk_fma_f32 v[96:97], v[96:97], v[110:111], v[114:115]
	v_pk_fma_f32 v[94:95], v[94:95], v[108:109], v[112:113]
	v_pk_fma_f32 v[100:101], v[100:101], v[110:111], v[114:115]
	v_pk_fma_f32 v[98:99], v[98:99], v[108:109], v[112:113]
	v_pk_fma_f32 v[104:105], v[104:105], v[110:111], v[114:115]
	v_pk_fma_f32 v[102:103], v[102:103], v[108:109], v[112:113]
	v_cvt_pk_bf16_f32 v10, v10, v11
	v_cvt_pk_bf16_f32 v11, v12, v13
	v_cvt_pk_bf16_f32 v12, v14, v15
	v_cvt_pk_bf16_f32 v13, v116, v117
	v_cvt_pk_bf16_f32 v14, v70, v71
	v_cvt_pk_bf16_f32 v15, v72, v73
	v_cvt_pk_bf16_f32 v70, v86, v87
	v_cvt_pk_bf16_f32 v71, v88, v89
	v_cvt_pk_bf16_f32 v72, v90, v91
	v_cvt_pk_bf16_f32 v73, v92, v93
	v_cvt_pk_bf16_f32 v86, v94, v95
	v_cvt_pk_bf16_f32 v87, v96, v97
	v_cvt_pk_bf16_f32 v88, v98, v99
	v_cvt_pk_bf16_f32 v89, v100, v101
	v_cvt_pk_bf16_f32 v90, v102, v103
	v_cvt_pk_bf16_f32 v91, v104, v105
	global_store_dwordx2 v[18:19], v[10:11], off offset:512
	global_store_dwordx2 v[18:19], v[12:13], off offset:2560
	global_store_dwordx2 v[20:21], v[14:15], off offset:512
	global_store_dwordx2 v[20:21], v[70:71], off offset:2560
	global_store_dwordx2 v[22:23], v[72:73], off offset:512
	global_store_dwordx2 v[22:23], v[86:87], off offset:2560
	global_store_dwordx2 v[106:107], v[88:89], off offset:512
	global_store_dwordx2 v[106:107], v[90:91], off offset:2560
	global_load_dwordx4 v[10:13], v[132:133], off offset:2048
	s_nop 0
	global_load_dwordx4 v[70:73], v[134:135], off offset:2048
	v_pk_mul_f32 v[14:15], v[48:49], v[84:85] op_sel_hi:[1,0]
	v_pk_mul_f32 v[48:49], v[60:61], v[120:121] op_sel_hi:[1,0]
	v_pk_mul_f32 v[60:61], v[64:65], v[124:125] op_sel_hi:[1,0]
	v_pk_mul_f32 v[64:65], v[68:69], v[128:129] op_sel_hi:[1,0]
	v_pk_mul_f32 v[68:69], v[76:77], v[150:151] op_sel_hi:[1,0]
	v_pk_mul_f32 v[76:77], v[80:81], v[152:153] op_sel_hi:[1,0]
	v_pk_mul_f32 v[80:81], v[82:83], v[154:155] op_sel_hi:[1,0]
	s_waitcnt vmcnt(0) lgkmcnt(0)
	v_pk_fma_f32 v[8:9], v[8:9], v[12:13], v[72:73]
	v_pk_fma_f32 v[6:7], v[6:7], v[10:11], v[70:71]
	v_pk_fma_f32 v[14:15], v[14:15], v[12:13], v[72:73]
	v_pk_fma_f32 v[46:47], v[46:47], v[10:11], v[70:71]
	v_pk_fma_f32 v[48:49], v[48:49], v[12:13], v[72:73]
	v_pk_fma_f32 v[58:59], v[58:59], v[10:11], v[70:71]
	v_pk_fma_f32 v[60:61], v[60:61], v[12:13], v[72:73]
	v_pk_fma_f32 v[62:63], v[62:63], v[10:11], v[70:71]
	v_pk_fma_f32 v[64:65], v[64:65], v[12:13], v[72:73]
	v_pk_fma_f32 v[66:67], v[66:67], v[10:11], v[70:71]
	v_pk_fma_f32 v[68:69], v[68:69], v[12:13], v[72:73]
	v_pk_fma_f32 v[74:75], v[74:75], v[10:11], v[70:71]
	v_pk_fma_f32 v[76:77], v[76:77], v[12:13], v[72:73]
	v_pk_fma_f32 v[78:79], v[78:79], v[10:11], v[70:71]
	v_pk_fma_f32 v[12:13], v[52:53], v[12:13], v[72:73]
	v_pk_fma_f32 v[10:11], v[80:81], v[10:11], v[70:71]
	v_cvt_pk_bf16_f32 v6, v6, v7
	v_cvt_pk_bf16_f32 v7, v8, v9
	v_cvt_pk_bf16_f32 v8, v46, v47
	v_cvt_pk_bf16_f32 v9, v14, v15
	v_cvt_pk_bf16_f32 v14, v58, v59
	v_cvt_pk_bf16_f32 v15, v48, v49
	v_cvt_pk_bf16_f32 v46, v62, v63
	v_cvt_pk_bf16_f32 v47, v60, v61
	v_cvt_pk_bf16_f32 v48, v66, v67
	v_cvt_pk_bf16_f32 v49, v64, v65
	v_cvt_pk_bf16_f32 v52, v74, v75
	v_cvt_pk_bf16_f32 v53, v68, v69
	v_cvt_pk_bf16_f32 v58, v78, v79
	v_cvt_pk_bf16_f32 v59, v76, v77
	v_cvt_pk_bf16_f32 v10, v10, v11
	v_cvt_pk_bf16_f32 v11, v12, v13
	global_store_dwordx2 v[18:19], v[6:7], off offset:1024
	global_store_dwordx2 v[18:19], v[8:9], off offset:3072
	global_store_dwordx2 v[20:21], v[14:15], off offset:1024
	global_store_dwordx2 v[20:21], v[46:47], off offset:3072
	global_store_dwordx2 v[22:23], v[48:49], off offset:1024
	global_store_dwordx2 v[22:23], v[52:53], off offset:3072
	global_store_dwordx2 v[106:107], v[58:59], off offset:1024
	global_store_dwordx2 v[106:107], v[10:11], off offset:3072
	global_load_dwordx4 v[6:9], v[132:133], off offset:3072
	s_nop 0
	global_load_dwordx4 v[10:13], v[134:135], off offset:3072
	v_pk_mul_f32 v[14:15], v[16:17], v[84:85] op_sel_hi:[1,0]
	v_pk_mul_f32 v[16:17], v[26:27], v[84:85] op_sel_hi:[1,0]
	v_pk_mul_f32 v[26:27], v[30:31], v[120:121] op_sel_hi:[1,0]
	v_pk_mul_f32 v[30:31], v[34:35], v[124:125] op_sel_hi:[1,0]
	v_pk_mul_f32 v[34:35], v[38:39], v[128:129] op_sel_hi:[1,0]
	v_pk_mul_f32 v[38:39], v[42:43], v[150:151] op_sel_hi:[1,0]
	v_pk_mul_f32 v[42:43], v[50:51], v[152:153] op_sel_hi:[1,0]
	v_pk_mul_f32 v[46:47], v[54:55], v[154:155] op_sel_hi:[1,0]
	s_waitcnt vmcnt(0) lgkmcnt(0)
	v_pk_fma_f32 v[4:5], v[4:5], v[8:9], v[12:13]
	v_pk_fma_f32 v[2:3], v[2:3], v[6:7], v[10:11]
	v_pk_fma_f32 v[14:15], v[14:15], v[8:9], v[12:13]
	v_pk_fma_f32 v[16:17], v[16:17], v[6:7], v[10:11]
	v_pk_fma_f32 v[24:25], v[24:25], v[8:9], v[12:13]
	v_pk_fma_f32 v[26:27], v[26:27], v[6:7], v[10:11]
	v_pk_fma_f32 v[28:29], v[28:29], v[8:9], v[12:13]
	v_pk_fma_f32 v[30:31], v[30:31], v[6:7], v[10:11]
	v_pk_fma_f32 v[32:33], v[32:33], v[8:9], v[12:13]
	v_pk_fma_f32 v[34:35], v[34:35], v[6:7], v[10:11]
	v_pk_fma_f32 v[36:37], v[36:37], v[8:9], v[12:13]
	v_pk_fma_f32 v[38:39], v[38:39], v[6:7], v[10:11]
	v_pk_fma_f32 v[40:41], v[40:41], v[8:9], v[12:13]
	v_pk_fma_f32 v[42:43], v[42:43], v[6:7], v[10:11]
	v_pk_fma_f32 v[8:9], v[44:45], v[8:9], v[12:13]
	v_pk_fma_f32 v[6:7], v[46:47], v[6:7], v[10:11]
	v_cvt_pk_bf16_f32 v2, v2, v3
	v_cvt_pk_bf16_f32 v3, v4, v5
	v_cvt_pk_bf16_f32 v4, v16, v17
	v_cvt_pk_bf16_f32 v5, v14, v15
	v_cvt_pk_bf16_f32 v10, v26, v27
	v_cvt_pk_bf16_f32 v11, v24, v25
	v_cvt_pk_bf16_f32 v12, v30, v31
	v_cvt_pk_bf16_f32 v13, v28, v29
	v_cvt_pk_bf16_f32 v14, v34, v35
	v_cvt_pk_bf16_f32 v15, v32, v33
	v_cvt_pk_bf16_f32 v16, v38, v39
	v_cvt_pk_bf16_f32 v17, v36, v37
	v_cvt_pk_bf16_f32 v24, v42, v43
	v_cvt_pk_bf16_f32 v25, v40, v41
	v_cvt_pk_bf16_f32 v6, v6, v7
	v_cvt_pk_bf16_f32 v7, v8, v9
	global_store_dwordx2 v[18:19], v[2:3], off offset:1536
	global_store_dwordx2 v[18:19], v[4:5], off offset:3584
	global_store_dwordx2 v[20:21], v[10:11], off offset:1536
	global_store_dwordx2 v[20:21], v[12:13], off offset:3584
	global_store_dwordx2 v[22:23], v[14:15], off offset:1536
	global_store_dwordx2 v[22:23], v[16:17], off offset:3584
	global_store_dwordx2 v[106:107], v[24:25], off offset:1536
	global_store_dwordx2 v[106:107], v[6:7], off offset:3584
	s_cbranch_scc0 .LBB0_149
.LBB0_133:
	v_add_co_u32_e32 v2, vcc, 0xffff8400, v138
	s_nop 1
	v_addc_co_u32_e32 v3, vcc, -1, v139, vcc
	v_add_co_u32_e32 v4, vcc, 0xffff8800, v138
	s_nop 1
	v_addc_co_u32_e32 v5, vcc, -1, v139, vcc
	global_load_dwordx4 v[18:21], v[2:3], off
	global_load_dwordx4 v[10:13], v[4:5], off
	v_add_co_u32_e32 v2, vcc, 0xffff8c00, v138
	s_waitcnt vmcnt(0) lgkmcnt(0)
	v_add_f32_e32 v33, v12, v13
	v_addc_co_u32_e32 v3, vcc, -1, v139, vcc
	global_load_dwordx4 v[6:9], v[2:3], off
	v_add_co_u32_e32 v2, vcc, 0xffff9000, v138
	s_waitcnt vmcnt(0) lgkmcnt(0)
	v_add_f32_e32 v35, v8, v9
	v_addc_co_u32_e32 v3, vcc, -1, v139, vcc
	global_load_dwordx4 v[2:5], v[2:3], off
	v_add_co_u32_e32 v26, vcc, 0xffff9400, v138
	s_nop 1
	v_addc_co_u32_e32 v27, vcc, -1, v139, vcc
	v_add_co_u32_e32 v30, vcc, 0xffff9800, v138
	s_nop 1
	v_addc_co_u32_e32 v31, vcc, -1, v139, vcc
	global_load_dwordx4 v[22:25], v[26:27], off
	global_load_dwordx4 v[14:17], v[30:31], off
	v_add_f32_e32 v27, v18, v19
	v_add_f32_e32 v31, v20, v21
	v_add_f32_e32 v27, v27, v31
	v_add_f32_e32 v31, v10, v11
	v_add_f32_e32 v27, 0, v27
	v_add_f32_e32 v31, v31, v33
	v_add_f32_e32 v33, v6, v7
	v_add_f32_e32 v27, v27, v31
	v_add_f32_e32 v31, v33, v35
	v_add_f32_e32 v27, v27, v31
	v_add_co_u32_e32 v28, vcc, 0xffff9c00, v138
	s_waitcnt vmcnt(0) lgkmcnt(0)
	v_add_f32_e32 v33, v2, v3
	v_add_f32_e32 v35, v4, v5
	v_add_f32_e32 v31, v33, v35
	v_add_f32_e32 v27, v27, v31
	ds_swizzle_b32 v31, v27 offset:swizzle(SWAP,1)
	v_addc_co_u32_e32 v29, vcc, -1, v139, vcc
	v_add_co_u32_e32 v26, vcc, 0xffffa000, v138
	s_waitcnt lgkmcnt(0)
	v_add_f32_e32 v27, v27, v31
	ds_swizzle_b32 v31, v27 offset:swizzle(SWAP,2)
	s_mov_b64 s[8:9], vcc
	v_add_co_u32_e32 v32, vcc, 0xffffa400, v138
	s_mov_b64 s[6:7], vcc
	s_waitcnt lgkmcnt(0)
	v_add_f32_e32 v27, v27, v31
	ds_swizzle_b32 v31, v27 offset:swizzle(SWAP,4)
	v_add_co_u32_e32 v34, vcc, 0xffffa800, v138
	s_mov_b64 s[4:5], vcc
	v_add_co_u32_e32 v30, vcc, 0xffffac00, v138
	s_waitcnt lgkmcnt(0)
	v_add_f32_e32 v27, v27, v31
	ds_swizzle_b32 v31, v27 offset:swizzle(SWAP,8)
	s_mov_b64 s[2:3], vcc
	v_add_co_u32_e32 v62, vcc, 0xffffb000, v138
	s_mov_b64 s[28:29], vcc
	s_waitcnt lgkmcnt(0)
	v_add_f32_e32 v27, v27, v31
	ds_swizzle_b32 v31, v27 offset:swizzle(SWAP,16)
	v_add_co_u32_e32 v54, vcc, 0xffffb400, v138
	s_mov_b64 s[24:25], vcc
	v_add_co_u32_e32 v56, vcc, 0xffffb800, v138
	s_waitcnt lgkmcnt(0)
	v_add_f32_e32 v27, v27, v31
	v_mov_b32_e32 v31, v27
	s_nop 1
	v_permlane32_swap_b32_e32 v27, v31
	v_add_f32_e32 v150, v27, v31
	v_fmamk_f32 v21, v150, 0xba800000, v21
	v_fmamk_f32 v19, v150, 0xba800000, v19
	v_fmamk_f32 v20, v150, 0xba800000, v20
	v_fmac_f32_e32 v18, 0xba800000, v150
	v_mul_f32_e32 v27, v19, v19
	v_mul_f32_e32 v31, v21, v21
	v_fmamk_f32 v13, v150, 0xba800000, v13
	v_fmamk_f32 v11, v150, 0xba800000, v11
	v_fmac_f32_e32 v27, v18, v18
	v_fmac_f32_e32 v31, v20, v20
	v_fmamk_f32 v12, v150, 0xba800000, v12
	v_fmac_f32_e32 v10, 0xba800000, v150
	v_add_f32_e32 v27, v27, v31
	v_mul_f32_e32 v31, v11, v11
	v_mul_f32_e32 v33, v13, v13
	v_fmac_f32_e32 v31, v10, v10
	v_fmac_f32_e32 v33, v12, v12
	v_add_f32_e32 v31, v31, v33
	v_fmamk_f32 v9, v150, 0xba800000, v9
	v_fmamk_f32 v7, v150, 0xba800000, v7
	v_add_f32_e32 v27, v27, v31
	v_fmamk_f32 v8, v150, 0xba800000, v8
	v_fmac_f32_e32 v6, 0xba800000, v150
	v_mul_f32_e32 v31, v7, v7
	v_mul_f32_e32 v33, v9, v9
	v_fmac_f32_e32 v31, v6, v6
	v_fmac_f32_e32 v33, v8, v8
	v_add_f32_e32 v31, v31, v33
	v_fmamk_f32 v5, v150, 0xba800000, v5
	v_fmamk_f32 v3, v150, 0xba800000, v3
	v_add_f32_e32 v27, v31, v27
	v_fmamk_f32 v4, v150, 0xba800000, v4
	v_fmac_f32_e32 v2, 0xba800000, v150
	v_mul_f32_e32 v31, v3, v3
	v_mul_f32_e32 v33, v5, v5
	v_fmac_f32_e32 v31, v2, v2
	v_fmac_f32_e32 v33, v4, v4
	v_add_f32_e32 v31, v31, v33
	v_add_f32_e32 v27, v31, v27
	ds_swizzle_b32 v31, v27 offset:swizzle(SWAP,1)
	s_mov_b64 s[26:27], vcc
	v_add_co_u32_e32 v36, vcc, 0xffffbc00, v138
	s_mov_b64 s[18:19], vcc
	s_waitcnt lgkmcnt(0)
	v_add_f32_e32 v27, v27, v31
	ds_swizzle_b32 v31, v27 offset:swizzle(SWAP,2)
	v_add_co_u32_e32 v52, vcc, 0xffffc000, v138
	s_mov_b64 s[22:23], vcc
	v_add_co_u32_e32 v40, vcc, 0xffffc400, v138
	s_waitcnt lgkmcnt(0)
	v_add_f32_e32 v27, v27, v31
	ds_swizzle_b32 v31, v27 offset:swizzle(SWAP,4)
	s_mov_b64 s[16:17], vcc
	v_add_co_u32_e32 v50, vcc, 0xffffc800, v138
	s_mov_b64 s[20:21], vcc
	s_waitcnt lgkmcnt(0)
	v_add_f32_e32 v27, v27, v31
	ds_swizzle_b32 v31, v27 offset:swizzle(SWAP,8)
	v_add_co_u32_e32 v38, vcc, 0xffffcc00, v138
	s_mov_b64 s[12:13], vcc
	v_add_co_u32_e32 v44, vcc, 0xffffd000, v138
	s_mov_b64 s[14:15], vcc
	v_add_co_u32_e32 v42, vcc, 0xffffd400, v138
	s_waitcnt lgkmcnt(0)
	v_add_f32_e32 v31, v27, v31
	s_mov_b64 s[10:11], vcc
	v_add_co_u32_e32 v76, vcc, 0xffffd800, v138
	ds_swizzle_b32 v33, v31 offset:swizzle(SWAP,16)
	s_mov_b64 s[42:43], vcc
	v_add_co_u32_e32 v74, vcc, 0xffffdc00, v138
	s_mov_b64 s[36:37], vcc
	v_add_co_u32_e32 v84, vcc, 0xffffe000, v138
	s_mov_b64 s[40:41], vcc
	v_add_co_u32_e32 v80, vcc, 0xffffe400, v138
	s_mov_b64 s[34:35], vcc
	v_add_co_u32_e32 v82, vcc, 0xffffe800, v138
	global_load_dwordx4 v[46:49], v[28:29], off
	s_mov_b64 s[38:39], vcc
	v_add_co_u32_e32 v78, vcc, 0xffffec00, v138
	s_waitcnt lgkmcnt(0)
	v_add_f32_e32 v31, v31, v33
	s_mov_b64 s[30:31], vcc
	v_add_co_u32_e32 v102, vcc, 0xfffff000, v138
	v_mov_b32_e32 v33, v31
	s_mov_b64 s[48:49], vcc
	v_add_co_u32_e32 v104, vcc, 0xfffff400, v138
	v_permlane32_swap_b32_e32 v31, v33
	s_mov_b64 s[44:45], vcc
	v_add_co_u32_e32 v140, vcc, 0xfffff800, v138
	v_add_f32_e32 v31, v31, v33
	s_mov_b64 s[46:47], vcc
	v_addc_co_u32_e64 v27, vcc, -1, v139, s[8:9]
	v_fmamk_f32 v31, v31, 0x3a800000, v1
	v_add_f32_e32 v35, v22, v23
	v_add_f32_e32 v37, v24, v25
	v_mul_f32_e32 v33, 0x4f800000, v31
	v_cmp_gt_f32_e32 vcc, s57, v31
	v_add_f32_e32 v41, v14, v15
	s_nop 0
	v_cndmask_b32_e32 v31, v31, v33, vcc
	v_add_f32_e32 v33, v35, v37
	v_add_f32_e32 v37, 0, v33
	v_addc_co_u32_e64 v33, s[6:7], -1, v139, s[6:7]
	global_load_dwordx4 v[106:109], v[32:33], off
	v_sqrt_f32_e32 v39, v31
	global_load_dwordx4 v[26:29], v[26:27], off
	v_addc_co_u32_e64 v35, s[4:5], -1, v139, s[4:5]
	v_add_u32_e32 v32, -1, v39
	v_fma_f32 v33, -v32, v39, v31
	v_cmp_ge_f32_e64 s[6:7], 0, v33
	v_add_u32_e32 v33, 1, v39
	global_load_dwordx4 v[70:73], v[34:35], off
	v_cndmask_b32_e64 v32, v39, v32, s[6:7]
	v_fma_f32 v39, -v33, v39, v31
	v_cmp_lt_f32_e64 s[4:5], 0, v39
	s_nop 1
	v_cndmask_b32_e64 v32, v32, v33, s[4:5]
	v_mul_f32_e32 v33, 0x37800000, v32
	v_cndmask_b32_e32 v32, v32, v33, vcc
	v_cmp_class_f32_e32 vcc, v31, v131
	s_nop 1
	v_cndmask_b32_e32 v151, v32, v31, vcc
	v_div_scale_f32 v32, s[4:5], v151, v151, 1.0
	v_rcp_f32_e32 v34, v32
	v_add_f32_e32 v31, v16, v17
	v_add_f32_e32 v31, v41, v31
	v_add_f32_e32 v39, v37, v31
	v_fma_f32 v31, -v32, v34, 1.0
	v_fmac_f32_e32 v34, v31, v34
	v_addc_co_u32_e64 v31, vcc, -1, v139, s[2:3]
	global_load_dwordx4 v[58:61], v[30:31], off
	v_div_scale_f32 v30, s[4:5], 1.0, v151, 1.0
	v_mul_f32_e32 v35, v30, v34
	v_fma_f32 v31, -v32, v35, v30
	v_fmac_f32_e32 v35, v31, v34
	v_addc_co_u32_e64 v63, vcc, -1, v139, s[28:29]
	v_fma_f32 v37, -v32, v35, v30
	global_load_dwordx4 v[30:33], v[62:63], off
	v_add_co_u32_e32 v142, vcc, 0xfffffc00, v138
	s_mov_b64 s[2:3], vcc
	v_addc_co_u32_e64 v55, vcc, -1, v139, s[24:25]
	v_addc_co_u32_e64 v57, vcc, -1, v139, s[26:27]
	global_load_dwordx4 v[110:113], v[54:55], off
	global_load_dwordx4 v[86:89], v[56:57], off
	s_mov_b64 vcc, s[4:5]
	s_nop 0
	v_div_fmas_f32 v152, v37, v34, v35
	s_waitcnt vmcnt(0)
	v_add_f32_e32 v34, v46, v47
	v_add_f32_e32 v35, v48, v49
	v_addc_co_u32_e64 v37, vcc, -1, v139, s[18:19]
	global_load_dwordx4 v[62:65], v[36:37], off
	v_add_f32_e32 v41, v34, v35
	v_addc_co_u32_e64 v53, vcc, -1, v139, s[22:23]
	v_add_f32_e32 v43, v39, v41
	v_addc_co_u32_e64 v39, vcc, -1, v139, s[12:13]
	global_load_dwordx4 v[66:69], v[38:39], off
	global_load_dwordx4 v[34:37], v[52:53], off
	v_addc_co_u32_e64 v41, vcc, -1, v139, s[16:17]
	global_load_dwordx4 v[114:117], v[40:41], off
	v_addc_co_u32_e64 v51, vcc, -1, v139, s[20:21]
	global_load_dwordx4 v[90:93], v[50:51], off
	v_addc_co_u32_e64 v45, vcc, -1, v139, s[14:15]
	v_addc_co_u32_e64 v77, vcc, -1, v139, s[42:43]
	global_load_dwordx4 v[94:97], v[76:77], off
	v_addc_co_u32_e64 v75, vcc, -1, v139, s[36:37]
	v_addc_co_u32_e64 v81, vcc, -1, v139, s[34:35]
	v_addc_co_u32_e64 v83, vcc, -1, v139, s[38:39]
	s_waitcnt lgkmcnt(0)
	v_add_f32_e32 v40, v26, v27
	v_add_f32_e32 v41, v28, v29
	v_add_f32_e32 v50, v40, v41
	global_load_dwordx4 v[38:41], v[44:45], off
	v_add_f32_e32 v144, v43, v50
	v_addc_co_u32_e64 v43, vcc, -1, v139, s[10:11]
	global_load_dwordx4 v[118:121], v[42:43], off
	v_addc_co_u32_e64 v79, vcc, -1, v139, s[30:31]
	global_load_dwordx4 v[122:125], v[80:81], off
	global_load_dwordx4 v[98:101], v[82:83], off
	v_add_f32_e32 v42, v106, v107
	global_load_dwordx4 v[78:81], v[78:79], off
	v_add_f32_e32 v43, v108, v109
	global_load_dwordx4 v[74:77], v[74:75], off
	v_addc_co_u32_e64 v85, vcc, -1, v139, s[40:41]
	v_add_f32_e32 v50, v42, v43
	global_load_dwordx4 v[42:45], v[84:85], off
	v_add_f32_e32 v51, v70, v71
	v_add_f32_e32 v52, v72, v73
	v_addc_co_u32_e64 v103, vcc, -1, v139, s[48:49]
	v_add_f32_e32 v54, v51, v52
	v_add_f32_e32 v55, 0, v50
	global_load_dwordx4 v[50:53], v[102:103], off
	v_addc_co_u32_e64 v105, vcc, -1, v139, s[44:45]
	global_load_dwordx4 v[126:129], v[104:105], off
	v_addc_co_u32_e64 v141, vcc, -1, v139, s[46:47]
	v_addc_co_u32_e64 v143, vcc, -1, v139, s[2:3]
	global_load_dwordx4 v[82:85], v[142:143], off
	global_load_dwordx4 v[102:105], v[140:141], off
	v_add_f32_e32 v54, v55, v54
	v_add_f32_e32 v55, v58, v59
	v_add_f32_e32 v56, v60, v61
	v_add_f32_e32 v55, v55, v56
	v_add_f32_e32 v54, v54, v55
	v_add_f32_e32 v55, v30, v31
	v_add_f32_e32 v56, v32, v33
	v_add_f32_e32 v55, v55, v56
	v_add_f32_e32 v140, v54, v55
	s_add_u32 s5, s54, s60
	v_add_f32_e32 v54, v110, v111
	v_add_f32_e32 v55, v112, v113
	v_add_f32_e32 v141, v54, v55
	global_load_dwordx4 v[54:57], v[138:139], off
	v_add_f32_e32 v142, v86, v87
	v_add_f32_e32 v143, v88, v89
	v_add_f32_e32 v142, v142, v143
	v_add_f32_e32 v141, 0, v141
	v_add_f32_e32 v141, v141, v142
	s_waitcnt vmcnt(0)
	v_add_f32_e32 v142, v62, v63
	v_add_f32_e32 v143, v64, v65
	v_add_f32_e32 v142, v142, v143
	v_add_f32_e32 v141, v141, v142
	s_addc_u32 s4, s55, s61
	v_add_f32_e32 v142, v34, v35
	v_add_f32_e32 v143, v36, v37
	v_add_f32_e32 v142, v142, v143
	v_add_f32_e32 v141, v141, v142
	v_add_f32_e32 v142, v114, v115
	v_add_f32_e32 v143, v116, v117
	v_add_f32_e32 v142, v142, v143
	v_add_f32_e32 v143, v90, v91
	v_add_f32_e32 v145, v92, v93
	v_add_f32_e32 v143, v143, v145
	v_add_f32_e32 v142, 0, v142
	v_add_f32_e32 v142, v142, v143
	v_add_f32_e32 v143, v66, v67
	v_add_f32_e32 v145, v68, v69
	v_add_f32_e32 v143, v143, v145
	v_add_f32_e32 v142, v142, v143
	v_add_f32_e32 v146, v96, v97
	s_waitcnt lgkmcnt(0)
	v_add_f32_e32 v143, v38, v39
	v_add_f32_e32 v145, v40, v41
	v_add_f32_e32 v143, v143, v145
	v_add_f32_e32 v142, v142, v143
	v_add_f32_e32 v143, v118, v119
	v_add_f32_e32 v145, v120, v121
	v_add_f32_e32 v143, v143, v145
	v_add_f32_e32 v145, v94, v95
	v_add_f32_e32 v145, v145, v146
	v_add_f32_e32 v143, 0, v143
	v_add_f32_e32 v143, v143, v145
	v_add_f32_e32 v147, v100, v101
	v_add_f32_e32 v145, v74, v75
	v_add_f32_e32 v146, v76, v77
	v_add_f32_e32 v145, v145, v146
	v_add_f32_e32 v143, v143, v145
	v_add_f32_e32 v145, v42, v43
	v_add_f32_e32 v146, v44, v45
	v_add_f32_e32 v145, v145, v146
	v_add_f32_e32 v143, v143, v145
	v_add_f32_e32 v145, v122, v123
	v_add_f32_e32 v146, v124, v125
	v_add_f32_e32 v145, v145, v146
	v_add_f32_e32 v146, v98, v99
	v_add_f32_e32 v146, v146, v147
	v_add_f32_e32 v145, 0, v145
	v_add_f32_e32 v145, v145, v146
	v_add_f32_e32 v146, v78, v79
	v_add_f32_e32 v147, v80, v81
	v_add_f32_e32 v146, v146, v147
	ds_swizzle_b32 v147, v144 offset:swizzle(SWAP,1)
	v_add_f32_e32 v145, v145, v146
	v_add_f32_e32 v146, v50, v51
	v_add_f32_e32 v148, v52, v53
	v_add_f32_e32 v146, v146, v148
	s_waitcnt lgkmcnt(0)
	v_add_f32_e32 v144, v144, v147
	ds_swizzle_b32 v147, v144 offset:swizzle(SWAP,2)
	v_add_f32_e32 v145, v145, v146
	v_add_f32_e32 v146, v126, v127
	v_add_f32_e32 v148, v128, v129
	v_add_f32_e32 v146, v146, v148
	s_waitcnt lgkmcnt(0)
	v_add_f32_e32 v144, v144, v147
	ds_swizzle_b32 v147, v144 offset:swizzle(SWAP,4)
	v_add_f32_e32 v148, v102, v103
	v_add_f32_e32 v149, v104, v105
	v_add_f32_e32 v148, v148, v149
	v_add_f32_e32 v146, 0, v146
	s_waitcnt lgkmcnt(0)
	v_add_f32_e32 v144, v144, v147
	ds_swizzle_b32 v147, v144 offset:swizzle(SWAP,8)
	v_add_f32_e32 v146, v146, v148
	v_add_f32_e32 v148, v82, v83
	v_add_f32_e32 v149, v84, v85
	v_add_f32_e32 v148, v148, v149
	s_waitcnt lgkmcnt(0)
	v_add_f32_e32 v144, v144, v147
	ds_swizzle_b32 v147, v144 offset:swizzle(SWAP,16)
	ds_swizzle_b32 v149, v140 offset:swizzle(SWAP,1)
	v_add_f32_e32 v146, v146, v148
	v_add_f32_e32 v148, v54, v55
	v_add_f32_e32 v153, v56, v57
	v_add_f32_e32 v148, v148, v153
	s_waitcnt lgkmcnt(1)
	v_add_f32_e32 v144, v144, v147
	s_waitcnt lgkmcnt(0)
	v_add_f32_e32 v140, v140, v149
	ds_swizzle_b32 v149, v141 offset:swizzle(SWAP,1)
	v_add_f32_e32 v146, v146, v148
	v_mov_b32_e32 v148, v144
	s_nop 1
	v_permlane32_swap_b32_e32 v144, v148
	ds_swizzle_b32 v147, v140 offset:swizzle(SWAP,2)
	v_add_f32_e32 v159, v144, v148
	ds_swizzle_b32 v144, v142 offset:swizzle(SWAP,1)
	s_waitcnt lgkmcnt(2)
	v_add_f32_e32 v141, v141, v149
	ds_swizzle_b32 v149, v141 offset:swizzle(SWAP,2)
	s_waitcnt lgkmcnt(2)
	v_add_f32_e32 v140, v140, v147
	ds_swizzle_b32 v147, v140 offset:swizzle(SWAP,4)
	s_waitcnt lgkmcnt(2)
	v_add_f32_e32 v142, v142, v144
	ds_swizzle_b32 v144, v142 offset:swizzle(SWAP,2)
	s_waitcnt lgkmcnt(2)
	v_add_f32_e32 v141, v141, v149
	ds_swizzle_b32 v148, v141 offset:swizzle(SWAP,4)
	s_waitcnt lgkmcnt(2)
	v_add_f32_e32 v140, v140, v147
	ds_swizzle_b32 v147, v140 offset:swizzle(SWAP,8)
	s_waitcnt lgkmcnt(2)
	v_add_f32_e32 v142, v142, v144
	ds_swizzle_b32 v144, v142 offset:swizzle(SWAP,4)
	s_waitcnt lgkmcnt(2)
	v_add_f32_e32 v141, v141, v148
	ds_swizzle_b32 v148, v141 offset:swizzle(SWAP,8)
	s_waitcnt lgkmcnt(2)
	v_add_f32_e32 v140, v140, v147
	ds_swizzle_b32 v147, v140 offset:swizzle(SWAP,16)
	s_waitcnt lgkmcnt(2)
	v_add_f32_e32 v142, v142, v144
	ds_swizzle_b32 v144, v142 offset:swizzle(SWAP,8)
	s_waitcnt lgkmcnt(2)
	v_add_f32_e32 v141, v141, v148
	ds_swizzle_b32 v148, v141 offset:swizzle(SWAP,16)
	s_waitcnt lgkmcnt(2)
	v_add_f32_e32 v140, v140, v147
	v_mov_b32_e32 v147, v140
	s_waitcnt lgkmcnt(1)
	v_add_f32_e32 v142, v142, v144
	ds_swizzle_b32 v144, v142 offset:swizzle(SWAP,16)
	v_permlane32_swap_b32_e32 v140, v147
	v_add_f32_e32 v158, v140, v147
	s_waitcnt lgkmcnt(1)
	v_add_f32_e32 v140, v141, v148
	ds_swizzle_b32 v147, v143 offset:swizzle(SWAP,1)
	v_mov_b32_e32 v141, v140
	s_nop 1
	v_permlane32_swap_b32_e32 v140, v141
	v_add_f32_e32 v157, v140, v141
	s_waitcnt lgkmcnt(1)
	v_add_f32_e32 v140, v142, v144
	ds_swizzle_b32 v144, v145 offset:swizzle(SWAP,1)
	s_waitcnt lgkmcnt(1)
	v_add_f32_e32 v141, v143, v147
	ds_swizzle_b32 v142, v141 offset:swizzle(SWAP,2)
	v_mov_b32_e32 v143, v140
	s_nop 1
	v_permlane32_swap_b32_e32 v140, v143
	s_waitcnt lgkmcnt(1)
	v_add_f32_e32 v144, v145, v144
	v_add_f32_e32 v156, v140, v143
	ds_swizzle_b32 v140, v146 offset:swizzle(SWAP,1)
	ds_swizzle_b32 v145, v144 offset:swizzle(SWAP,2)
	s_waitcnt lgkmcnt(2)
	v_add_f32_e32 v141, v141, v142
	ds_swizzle_b32 v142, v141 offset:swizzle(SWAP,4)
	v_fmamk_f32 v23, v159, 0xba800000, v23
	s_waitcnt lgkmcnt(2)
	v_add_f32_e32 v140, v146, v140
	s_waitcnt lgkmcnt(1)
	v_add_f32_e32 v143, v144, v145
	ds_swizzle_b32 v145, v140 offset:swizzle(SWAP,2)
	s_waitcnt lgkmcnt(1)
	v_add_f32_e32 v141, v141, v142
	ds_swizzle_b32 v142, v141 offset:swizzle(SWAP,8)
	ds_swizzle_b32 v144, v143 offset:swizzle(SWAP,4)
	v_fmamk_f32 v15, v159, 0xba800000, v15
	s_waitcnt lgkmcnt(2)
	v_add_f32_e32 v140, v140, v145
	ds_swizzle_b32 v145, v140 offset:swizzle(SWAP,4)
	s_waitcnt lgkmcnt(2)
	v_add_f32_e32 v141, v141, v142
	s_waitcnt lgkmcnt(1)
	v_add_f32_e32 v143, v143, v144
	ds_swizzle_b32 v142, v141 offset:swizzle(SWAP,16)
	ds_swizzle_b32 v144, v143 offset:swizzle(SWAP,8)
	s_waitcnt lgkmcnt(2)
	v_add_f32_e32 v140, v140, v145
	ds_swizzle_b32 v145, v140 offset:swizzle(SWAP,8)
	v_fmac_f32_e32 v22, 0xba800000, v159
	s_waitcnt lgkmcnt(2)
	v_add_f32_e32 v141, v141, v142
	s_waitcnt lgkmcnt(1)
	v_add_f32_e32 v143, v143, v144
	v_mov_b32_e32 v142, v141
	ds_swizzle_b32 v144, v143 offset:swizzle(SWAP,16)
	s_nop 0
	v_permlane32_swap_b32_e32 v141, v142
	s_waitcnt lgkmcnt(1)
	v_add_f32_e32 v140, v140, v145
	v_add_f32_e32 v155, v141, v142
	ds_swizzle_b32 v142, v140 offset:swizzle(SWAP,16)
	s_waitcnt lgkmcnt(1)
	v_add_f32_e32 v141, v143, v144
	v_mov_b32_e32 v143, v141
	s_nop 1
	v_permlane32_swap_b32_e32 v141, v143
	s_waitcnt lgkmcnt(0)
	v_add_f32_e32 v140, v140, v142
	v_add_f32_e32 v154, v141, v143
	v_mov_b32_e32 v141, v140
	s_nop 1
	v_permlane32_swap_b32_e32 v140, v141
	v_add_f32_e32 v153, v140, v141
	v_fmamk_f32 v143, v159, 0xba800000, v25
	v_fmamk_f32 v141, v159, 0xba800000, v17
	v_fmamk_f32 v142, v159, 0xba800000, v24
	v_mul_f32_e32 v24, v23, v23
	v_mul_f32_e32 v25, v143, v143
	v_fmamk_f32 v140, v159, 0xba800000, v16
	v_fmac_f32_e32 v14, 0xba800000, v159
	v_mul_f32_e32 v16, v15, v15
	v_mul_f32_e32 v17, v141, v141
	v_fmac_f32_e32 v24, v22, v22
	v_fmac_f32_e32 v25, v142, v142
	v_fmac_f32_e32 v16, v14, v14
	v_fmac_f32_e32 v17, v140, v140
	v_add_f32_e32 v24, v24, v25
	v_add_f32_e32 v16, v16, v17
	v_fmamk_f32 v49, v159, 0xba800000, v49
	v_fmamk_f32 v47, v159, 0xba800000, v47
	v_add_f32_e32 v16, v24, v16
	v_fmamk_f32 v48, v159, 0xba800000, v48
	v_fmac_f32_e32 v46, 0xba800000, v159
	v_mul_f32_e32 v17, v47, v47
	v_mul_f32_e32 v24, v49, v49
	v_fmac_f32_e32 v17, v46, v46
	v_fmac_f32_e32 v24, v48, v48
	v_add_f32_e32 v17, v17, v24
	v_add_f32_e32 v24, v17, v16
	v_fmamk_f32 v17, v159, 0xba800000, v29
	v_fmamk_f32 v27, v159, 0xba800000, v27
	v_fmamk_f32 v16, v159, 0xba800000, v28
	v_fmac_f32_e32 v26, 0xba800000, v159
	v_mul_f32_e32 v25, v27, v27
	v_mul_f32_e32 v28, v17, v17
	v_fmac_f32_e32 v25, v26, v26
	v_fmac_f32_e32 v28, v16, v16
	v_add_f32_e32 v25, v25, v28
	v_fmamk_f32 v109, v158, 0xba800000, v109
	v_fmamk_f32 v107, v158, 0xba800000, v107
	v_add_f32_e32 v160, v25, v24
	v_fmamk_f32 v108, v158, 0xba800000, v108
	v_fmac_f32_e32 v106, 0xba800000, v158
	v_mul_f32_e32 v24, v107, v107
	v_mul_f32_e32 v25, v109, v109
	v_fmac_f32_e32 v24, v106, v106
	v_fmac_f32_e32 v25, v108, v108
	v_fmamk_f32 v73, v158, 0xba800000, v73
	v_fmamk_f32 v71, v158, 0xba800000, v71
	v_add_f32_e32 v24, v24, v25
	v_fmamk_f32 v72, v158, 0xba800000, v72
	v_fmac_f32_e32 v70, 0xba800000, v158
	v_mul_f32_e32 v25, v71, v71
	v_mul_f32_e32 v28, v73, v73
	v_fmac_f32_e32 v25, v70, v70
	v_fmac_f32_e32 v28, v72, v72
	v_add_f32_e32 v25, v25, v28
	v_fmamk_f32 v61, v158, 0xba800000, v61
	v_fmamk_f32 v59, v158, 0xba800000, v59
	v_add_f32_e32 v24, v24, v25
	v_fmamk_f32 v60, v158, 0xba800000, v60
	v_fmac_f32_e32 v58, 0xba800000, v158
	v_mul_f32_e32 v25, v59, v59
	v_mul_f32_e32 v28, v61, v61
	v_fmac_f32_e32 v25, v58, v58
	v_fmac_f32_e32 v28, v60, v60
	v_add_f32_e32 v25, v25, v28
	v_add_f32_e32 v28, v25, v24
	v_fmamk_f32 v25, v158, 0xba800000, v33
	v_fmamk_f32 v31, v158, 0xba800000, v31
	v_fmamk_f32 v24, v158, 0xba800000, v32
	v_fmac_f32_e32 v30, 0xba800000, v158
	v_mul_f32_e32 v29, v31, v31
	v_mul_f32_e32 v32, v25, v25
	v_fmac_f32_e32 v29, v30, v30
	v_fmac_f32_e32 v32, v24, v24
	v_add_f32_e32 v29, v29, v32
	v_fmamk_f32 v113, v157, 0xba800000, v113
	v_fmamk_f32 v111, v157, 0xba800000, v111
	v_add_f32_e32 v161, v29, v28
	v_fmamk_f32 v112, v157, 0xba800000, v112
	v_fmac_f32_e32 v110, 0xba800000, v157
	v_mul_f32_e32 v28, v111, v111
	v_mul_f32_e32 v29, v113, v113
	v_fmac_f32_e32 v28, v110, v110
	v_fmac_f32_e32 v29, v112, v112
	v_fmamk_f32 v89, v157, 0xba800000, v89
	v_fmamk_f32 v87, v157, 0xba800000, v87
	v_add_f32_e32 v28, v28, v29
	v_fmamk_f32 v88, v157, 0xba800000, v88
	v_fmac_f32_e32 v86, 0xba800000, v157
	v_mul_f32_e32 v29, v87, v87
	v_mul_f32_e32 v32, v89, v89
	v_fmac_f32_e32 v29, v86, v86
	v_fmac_f32_e32 v32, v88, v88
	v_add_f32_e32 v29, v29, v32
	v_fmamk_f32 v65, v157, 0xba800000, v65
	v_fmamk_f32 v63, v157, 0xba800000, v63
	v_add_f32_e32 v28, v28, v29
	v_fmamk_f32 v64, v157, 0xba800000, v64
	v_fmac_f32_e32 v62, 0xba800000, v157
	v_mul_f32_e32 v29, v63, v63
	v_mul_f32_e32 v32, v65, v65
	v_fmac_f32_e32 v29, v62, v62
	v_fmac_f32_e32 v32, v64, v64
	v_add_f32_e32 v29, v29, v32
	v_add_f32_e32 v32, v29, v28
	v_fmamk_f32 v29, v157, 0xba800000, v37
	v_fmamk_f32 v35, v157, 0xba800000, v35
	v_fmamk_f32 v28, v157, 0xba800000, v36
	v_fmac_f32_e32 v34, 0xba800000, v157
	v_mul_f32_e32 v33, v35, v35
	v_mul_f32_e32 v36, v29, v29
	v_fmac_f32_e32 v33, v34, v34
	v_fmac_f32_e32 v36, v28, v28
	v_add_f32_e32 v33, v33, v36
	v_fmamk_f32 v117, v156, 0xba800000, v117
	v_fmamk_f32 v115, v156, 0xba800000, v115
	v_add_f32_e32 v162, v33, v32
	v_fmamk_f32 v116, v156, 0xba800000, v116
	v_fmac_f32_e32 v114, 0xba800000, v156
	v_mul_f32_e32 v32, v115, v115
	v_mul_f32_e32 v33, v117, v117
	v_fmac_f32_e32 v32, v114, v114
	v_fmac_f32_e32 v33, v116, v116
	v_fmamk_f32 v93, v156, 0xba800000, v93
	v_fmamk_f32 v91, v156, 0xba800000, v91
	v_add_f32_e32 v32, v32, v33
	v_fmamk_f32 v92, v156, 0xba800000, v92
	v_fmac_f32_e32 v90, 0xba800000, v156
	v_mul_f32_e32 v33, v91, v91
	v_mul_f32_e32 v36, v93, v93
	v_fmac_f32_e32 v33, v90, v90
	v_fmac_f32_e32 v36, v92, v92
	v_add_f32_e32 v33, v33, v36
	v_fmamk_f32 v69, v156, 0xba800000, v69
	v_fmamk_f32 v67, v156, 0xba800000, v67
	v_add_f32_e32 v32, v32, v33
	v_fmamk_f32 v68, v156, 0xba800000, v68
	v_fmac_f32_e32 v66, 0xba800000, v156
	v_mul_f32_e32 v33, v67, v67
	v_mul_f32_e32 v36, v69, v69
	v_fmac_f32_e32 v33, v66, v66
	v_fmac_f32_e32 v36, v68, v68
	v_add_f32_e32 v33, v33, v36
	v_add_f32_e32 v36, v33, v32
	v_fmamk_f32 v33, v156, 0xba800000, v41
	v_fmamk_f32 v39, v156, 0xba800000, v39
	v_fmamk_f32 v32, v156, 0xba800000, v40
	v_fmac_f32_e32 v38, 0xba800000, v156
	v_mul_f32_e32 v37, v39, v39
	v_mul_f32_e32 v40, v33, v33
	v_fmac_f32_e32 v37, v38, v38
	v_fmac_f32_e32 v40, v32, v32
	v_add_f32_e32 v37, v37, v40
	v_fmamk_f32 v145, v155, 0xba800000, v121
	v_fmamk_f32 v119, v155, 0xba800000, v119
	v_add_f32_e32 v163, v37, v36
	v_fmamk_f32 v144, v155, 0xba800000, v120
	v_fmac_f32_e32 v118, 0xba800000, v155
	v_mul_f32_e32 v36, v119, v119
	v_mul_f32_e32 v37, v145, v145
	v_fmac_f32_e32 v36, v118, v118
	v_fmac_f32_e32 v37, v144, v144
	v_fmamk_f32 v97, v155, 0xba800000, v97
	v_fmamk_f32 v95, v155, 0xba800000, v95
	v_add_f32_e32 v36, v36, v37
	v_fmamk_f32 v96, v155, 0xba800000, v96
	v_fmac_f32_e32 v94, 0xba800000, v155
	v_mul_f32_e32 v37, v95, v95
	v_mul_f32_e32 v40, v97, v97
	v_fmac_f32_e32 v37, v94, v94
	v_fmac_f32_e32 v40, v96, v96
	v_add_f32_e32 v37, v37, v40
	v_fmamk_f32 v77, v155, 0xba800000, v77
	v_fmamk_f32 v75, v155, 0xba800000, v75
	v_add_f32_e32 v36, v36, v37
	v_fmamk_f32 v76, v155, 0xba800000, v76
	v_fmac_f32_e32 v74, 0xba800000, v155
	v_mul_f32_e32 v37, v75, v75
	v_mul_f32_e32 v40, v77, v77
	v_fmac_f32_e32 v37, v74, v74
	v_fmac_f32_e32 v40, v76, v76
	v_add_f32_e32 v37, v37, v40
	v_add_f32_e32 v40, v37, v36
	v_fmamk_f32 v37, v155, 0xba800000, v45
	v_fmamk_f32 v43, v155, 0xba800000, v43
	v_fmamk_f32 v36, v155, 0xba800000, v44
	v_fmac_f32_e32 v42, 0xba800000, v155
	v_mul_f32_e32 v41, v43, v43
	v_mul_f32_e32 v44, v37, v37
	v_fmac_f32_e32 v41, v42, v42
	v_fmac_f32_e32 v44, v36, v36
	v_add_f32_e32 v41, v41, v44
	v_fmamk_f32 v147, v154, 0xba800000, v125
	v_fmamk_f32 v123, v154, 0xba800000, v123
	v_add_f32_e32 v121, v41, v40
	v_fmamk_f32 v146, v154, 0xba800000, v124
	v_fmac_f32_e32 v122, 0xba800000, v154
	v_mul_f32_e32 v40, v123, v123
	v_mul_f32_e32 v41, v147, v147
	v_fmac_f32_e32 v40, v122, v122
	v_fmac_f32_e32 v41, v146, v146
	v_fmamk_f32 v101, v154, 0xba800000, v101
	v_fmamk_f32 v99, v154, 0xba800000, v99
	v_add_f32_e32 v40, v40, v41
	v_fmamk_f32 v100, v154, 0xba800000, v100
	v_fmac_f32_e32 v98, 0xba800000, v154
	v_mul_f32_e32 v41, v99, v99
	v_mul_f32_e32 v44, v101, v101
	v_fmac_f32_e32 v41, v98, v98
	v_fmac_f32_e32 v44, v100, v100
	v_add_f32_e32 v41, v41, v44
	v_fmamk_f32 v81, v154, 0xba800000, v81
	v_fmamk_f32 v79, v154, 0xba800000, v79
	v_add_f32_e32 v40, v40, v41
	v_fmamk_f32 v80, v154, 0xba800000, v80
	v_fmac_f32_e32 v78, 0xba800000, v154
	v_mul_f32_e32 v41, v79, v79
	v_mul_f32_e32 v44, v81, v81
	v_fmac_f32_e32 v41, v78, v78
	v_fmac_f32_e32 v44, v80, v80
	v_add_f32_e32 v41, v41, v44
	v_add_f32_e32 v44, v41, v40
	v_fmamk_f32 v41, v154, 0xba800000, v53
	v_fmamk_f32 v51, v154, 0xba800000, v51
	v_fmamk_f32 v40, v154, 0xba800000, v52
	v_fmac_f32_e32 v50, 0xba800000, v154
	v_mul_f32_e32 v45, v51, v51
	v_mul_f32_e32 v52, v41, v41
	v_fmac_f32_e32 v45, v50, v50
	v_fmac_f32_e32 v52, v40, v40
	v_add_f32_e32 v45, v45, v52
	v_fmamk_f32 v149, v153, 0xba800000, v129
	v_fmamk_f32 v127, v153, 0xba800000, v127
	v_add_f32_e32 v124, v45, v44
	v_fmamk_f32 v148, v153, 0xba800000, v128
	v_fmac_f32_e32 v126, 0xba800000, v153
	v_mul_f32_e32 v44, v127, v127
	v_mul_f32_e32 v45, v149, v149
	v_fmac_f32_e32 v44, v126, v126
	v_fmac_f32_e32 v45, v148, v148
	v_fmamk_f32 v105, v153, 0xba800000, v105
	v_fmamk_f32 v103, v153, 0xba800000, v103
	v_add_f32_e32 v44, v44, v45
	v_fmamk_f32 v104, v153, 0xba800000, v104
	v_fmac_f32_e32 v102, 0xba800000, v153
	v_mul_f32_e32 v45, v103, v103
	v_mul_f32_e32 v52, v105, v105
	v_fmac_f32_e32 v45, v102, v102
	v_fmac_f32_e32 v52, v104, v104
	v_fmamk_f32 v53, v153, 0xba800000, v85
	ds_swizzle_b32 v85, v160 offset:swizzle(SWAP,1)
	v_add_f32_e32 v45, v45, v52
	v_fmamk_f32 v83, v153, 0xba800000, v83
	v_add_f32_e32 v44, v44, v45
	v_fmamk_f32 v52, v153, 0xba800000, v84
	v_fmac_f32_e32 v82, 0xba800000, v153
	v_mul_f32_e32 v45, v83, v83
	v_mul_f32_e32 v84, v53, v53
	v_fmac_f32_e32 v45, v82, v82
	v_fmac_f32_e32 v84, v52, v52
	v_add_f32_e32 v45, v45, v84
	v_add_f32_e32 v84, v45, v44
	v_fmamk_f32 v44, v153, 0xba800000, v56
	s_waitcnt lgkmcnt(0)
	v_add_f32_e32 v56, v160, v85
	v_fmamk_f32 v45, v153, 0xba800000, v57
	ds_swizzle_b32 v57, v56 offset:swizzle(SWAP,2)
	ds_swizzle_b32 v120, v161 offset:swizzle(SWAP,1)
	v_fmamk_f32 v55, v153, 0xba800000, v55
	v_fmac_f32_e32 v54, 0xba800000, v153
	v_mul_f32_e32 v85, v55, v55
	s_waitcnt lgkmcnt(1)
	v_add_f32_e32 v56, v56, v57
	ds_swizzle_b32 v57, v56 offset:swizzle(SWAP,4)
	s_waitcnt lgkmcnt(1)
	v_add_f32_e32 v120, v161, v120
	ds_swizzle_b32 v128, v120 offset:swizzle(SWAP,2)
	v_mul_f32_e32 v125, v45, v45
	v_fmac_f32_e32 v85, v54, v54
	s_waitcnt lgkmcnt(1)
	v_add_f32_e32 v56, v56, v57
	ds_swizzle_b32 v57, v56 offset:swizzle(SWAP,8)
	v_fmac_f32_e32 v125, v44, v44
	s_waitcnt lgkmcnt(1)
	v_add_f32_e32 v120, v120, v128
	v_add_f32_e32 v85, v85, v125
	ds_swizzle_b32 v125, v120 offset:swizzle(SWAP,4)
	s_waitcnt lgkmcnt(1)
	v_add_f32_e32 v56, v56, v57
	ds_swizzle_b32 v57, v163 offset:swizzle(SWAP,1)
	ds_swizzle_b32 v128, v162 offset:swizzle(SWAP,1)
	v_add_f32_e32 v85, v85, v84
	s_waitcnt lgkmcnt(2)
	v_add_f32_e32 v84, v120, v125
	ds_swizzle_b32 v160, v56 offset:swizzle(SWAP,16)
	s_waitcnt lgkmcnt(2)
	v_add_f32_e32 v57, v163, v57
	ds_swizzle_b32 v129, v57 offset:swizzle(SWAP,2)
	s_waitcnt lgkmcnt(2)
	v_add_f32_e32 v120, v162, v128
	ds_swizzle_b32 v125, v120 offset:swizzle(SWAP,2)
	ds_swizzle_b32 v128, v84 offset:swizzle(SWAP,8)
	s_waitcnt lgkmcnt(2)
	v_add_f32_e32 v57, v57, v129
	ds_swizzle_b32 v129, v57 offset:swizzle(SWAP,4)
	s_waitcnt lgkmcnt(2)
	v_add_f32_e32 v120, v120, v125
	s_waitcnt lgkmcnt(1)
	v_add_f32_e32 v128, v84, v128
	v_add_f32_e32 v84, v56, v160
	ds_swizzle_b32 v125, v120 offset:swizzle(SWAP,4)
	s_waitcnt lgkmcnt(1)
	v_add_f32_e32 v56, v57, v129
	ds_swizzle_b32 v161, v128 offset:swizzle(SWAP,16)
	ds_swizzle_b32 v57, v56 offset:swizzle(SWAP,8)
	ds_swizzle_b32 v129, v121 offset:swizzle(SWAP,1)
	s_waitcnt lgkmcnt(3)
	v_add_f32_e32 v125, v120, v125
	ds_swizzle_b32 v162, v125 offset:swizzle(SWAP,8)
	s_waitcnt lgkmcnt(3)
	v_add_f32_e32 v120, v128, v161
	s_waitcnt lgkmcnt(2)
	v_add_f32_e32 v56, v56, v57
	ds_swizzle_b32 v57, v124 offset:swizzle(SWAP,1)
	ds_swizzle_b32 v161, v85 offset:swizzle(SWAP,1)
	s_waitcnt lgkmcnt(3)
	v_add_f32_e32 v121, v121, v129
	ds_swizzle_b32 v129, v121 offset:swizzle(SWAP,2)
	s_waitcnt lgkmcnt(3)
	v_add_f32_e32 v125, v125, v162
	s_waitcnt lgkmcnt(2)
	v_add_f32_e32 v57, v124, v57
	s_waitcnt lgkmcnt(1)
	v_add_f32_e32 v85, v85, v161
	ds_swizzle_b32 v124, v57 offset:swizzle(SWAP,2)
	ds_swizzle_b32 v161, v85 offset:swizzle(SWAP,2)
	s_waitcnt lgkmcnt(2)
	v_add_f32_e32 v121, v121, v129
	ds_swizzle_b32 v129, v121 offset:swizzle(SWAP,4)
	ds_swizzle_b32 v128, v125 offset:swizzle(SWAP,16)
	s_waitcnt lgkmcnt(3)
	v_add_f32_e32 v57, v57, v124
	s_waitcnt lgkmcnt(2)
	v_add_f32_e32 v85, v85, v161
	ds_swizzle_b32 v124, v57 offset:swizzle(SWAP,4)
	ds_swizzle_b32 v161, v85 offset:swizzle(SWAP,4)
	s_waitcnt lgkmcnt(3)
	v_add_f32_e32 v121, v121, v129
	ds_swizzle_b32 v129, v121 offset:swizzle(SWAP,8)
	ds_swizzle_b32 v160, v56 offset:swizzle(SWAP,16)
	s_waitcnt lgkmcnt(3)
	v_add_f32_e32 v57, v57, v124
	s_waitcnt lgkmcnt(2)
	v_add_f32_e32 v85, v85, v161
	ds_swizzle_b32 v124, v57 offset:swizzle(SWAP,8)
	ds_swizzle_b32 v161, v85 offset:swizzle(SWAP,8)
	s_waitcnt lgkmcnt(3)
	v_add_f32_e32 v121, v121, v129
	ds_swizzle_b32 v129, v121 offset:swizzle(SWAP,16)
	v_mov_b32_e32 v164, v84
	s_waitcnt lgkmcnt(2)
	v_add_f32_e32 v57, v57, v124
	s_waitcnt lgkmcnt(1)
	v_add_f32_e32 v85, v85, v161
	ds_swizzle_b32 v162, v57 offset:swizzle(SWAP,16)
	ds_swizzle_b32 v161, v85 offset:swizzle(SWAP,16)
	v_add_f32_e32 v124, v125, v128
	v_add_f32_e32 v128, v56, v160
	s_waitcnt lgkmcnt(2)
	v_add_f32_e32 v129, v121, v129
	s_waitcnt lgkmcnt(1)
	v_add_f32_e32 v121, v57, v162
	s_waitcnt lgkmcnt(0)
	v_add_f32_e32 v57, v85, v161
	v_mov_b32_e32 v163, v120
	v_mov_b32_e32 v162, v124
	v_mov_b32_e32 v161, v128
	v_mov_b32_e32 v160, v129
	v_mov_b32_e32 v125, v121
	v_mov_b32_e32 v85, v57
	v_permlane32_swap_b32_e32 v84, v164
	v_permlane32_swap_b32_e32 v120, v163
	v_permlane32_swap_b32_e32 v124, v162
	v_permlane32_swap_b32_e32 v128, v161
	v_permlane32_swap_b32_e32 v129, v160
	v_permlane32_swap_b32_e32 v121, v125
	v_permlane32_swap_b32_e32 v57, v85
	v_div_fixup_f32 v56, v152, v151, 1.0
	s_and_saveexec_b64 s[2:3], s[0:1]
	s_cbranch_execz .LBB0_135
	v_mov_b32_e32 v151, s5
	v_add_co_u32_e32 v166, vcc, 0x1fa00000, v151
	v_mov_b32_e32 v151, s4
	v_mul_f32_e32 v150, 0x3a800000, v150
	v_addc_co_u32_e32 v167, vcc, 0, v151, vcc
	v_mov_b32_e32 v151, v56
	global_store_dwordx2 v[166:167], v[150:151], off
.LBB0_135:
	s_or_b64 exec, exec, s[2:3]
	v_add_f32_e32 v84, v84, v164
	v_fmamk_f32 v84, v84, 0x3a800000, v1
	v_mul_f32_e32 v150, 0x4f800000, v84
	v_cmp_gt_f32_e32 vcc, s57, v84
	s_nop 1
	v_cndmask_b32_e32 v84, v84, v150, vcc
	v_sqrt_f32_e32 v150, v84
	s_nop 0
	v_add_u32_e32 v151, -1, v150
	v_fma_f32 v164, -v151, v150, v84
	v_add_u32_e32 v152, 1, v150
	v_cmp_ge_f32_e64 s[2:3], 0, v164
	s_nop 1
	v_cndmask_b32_e64 v151, v150, v151, s[2:3]
	v_fma_f32 v150, -v152, v150, v84
	v_cmp_lt_f32_e64 s[2:3], 0, v150
	s_nop 1
	v_cndmask_b32_e64 v150, v151, v152, s[2:3]
	v_mul_f32_e32 v151, 0x37800000, v150
	v_cndmask_b32_e32 v150, v150, v151, vcc
	v_cmp_class_f32_e32 vcc, v84, v131
	s_nop 1
	v_cndmask_b32_e32 v84, v150, v84, vcc
	v_div_scale_f32 v150, s[2:3], v84, v84, 1.0
	v_rcp_f32_e32 v151, v150
	s_nop 0
	v_fma_f32 v152, -v150, v151, 1.0
	v_fmac_f32_e32 v151, v152, v151
	v_div_scale_f32 v152, vcc, 1.0, v84, 1.0
	v_mul_f32_e32 v164, v152, v151
	v_fma_f32 v165, -v150, v164, v152
	v_fmac_f32_e32 v164, v165, v151
	v_fma_f32 v150, -v150, v164, v152
	v_div_fmas_f32 v150, v150, v151, v164
	v_div_fixup_f32 v84, v150, v84, 1.0
	s_and_saveexec_b64 s[2:3], s[0:1]
	s_cbranch_execz .LBB0_137
	v_mov_b32_e32 v151, s5
	v_add_co_u32_e32 v164, vcc, 0x1fa00000, v151
	v_mov_b32_e32 v151, s4
	v_mul_f32_e32 v150, 0x3a800000, v159
	v_addc_co_u32_e32 v165, vcc, 0, v151, vcc
	v_mov_b32_e32 v151, v84
	global_store_dwordx2 v[164:165], v[150:151], off offset:8
.LBB0_137:
	s_or_b64 exec, exec, s[2:3]
	v_add_f32_e32 v120, v120, v163
	v_fmamk_f32 v120, v120, 0x3a800000, v1
	v_mul_f32_e32 v150, 0x4f800000, v120
	v_cmp_gt_f32_e32 vcc, s57, v120
	s_nop 1
	v_cndmask_b32_e32 v120, v120, v150, vcc
	v_sqrt_f32_e32 v150, v120
	s_nop 0
	v_add_u32_e32 v151, -1, v150
	v_fma_f32 v159, -v151, v150, v120
	v_add_u32_e32 v152, 1, v150
	v_cmp_ge_f32_e64 s[2:3], 0, v159
	s_nop 1
	v_cndmask_b32_e64 v151, v150, v151, s[2:3]
	v_fma_f32 v150, -v152, v150, v120
	v_cmp_lt_f32_e64 s[2:3], 0, v150
	s_nop 1
	v_cndmask_b32_e64 v150, v151, v152, s[2:3]
	v_mul_f32_e32 v151, 0x37800000, v150
	v_cndmask_b32_e32 v150, v150, v151, vcc
	v_cmp_class_f32_e32 vcc, v120, v131
	s_nop 1
	v_cndmask_b32_e32 v120, v150, v120, vcc
	v_div_scale_f32 v150, s[2:3], v120, v120, 1.0
	v_rcp_f32_e32 v151, v150
	s_nop 0
	v_fma_f32 v152, -v150, v151, 1.0
	v_fmac_f32_e32 v151, v152, v151
	v_div_scale_f32 v152, vcc, 1.0, v120, 1.0
	v_mul_f32_e32 v159, v152, v151
	v_fma_f32 v163, -v150, v159, v152
	v_fmac_f32_e32 v159, v163, v151
	v_fma_f32 v150, -v150, v159, v152
	v_div_fmas_f32 v150, v150, v151, v159
	v_div_fixup_f32 v120, v150, v120, 1.0
	s_and_saveexec_b64 s[2:3], s[0:1]
	s_cbranch_execz .LBB0_139
	v_mov_b32_e32 v151, s5
	v_mul_f32_e32 v150, 0x3a800000, v158
	v_add_co_u32_e32 v158, vcc, 0x1fa00000, v151
	v_mov_b32_e32 v151, s4
	s_nop 0
	v_addc_co_u32_e32 v159, vcc, 0, v151, vcc
	v_mov_b32_e32 v151, v120
	global_store_dwordx2 v[158:159], v[150:151], off offset:16
.LBB0_139:
	s_or_b64 exec, exec, s[2:3]
	v_add_f32_e32 v124, v124, v162
	v_fmamk_f32 v124, v124, 0x3a800000, v1
	v_mul_f32_e32 v150, 0x4f800000, v124
	v_cmp_gt_f32_e32 vcc, s57, v124
	s_nop 1
	v_cndmask_b32_e32 v124, v124, v150, vcc
	v_sqrt_f32_e32 v150, v124
	s_nop 0
	v_add_u32_e32 v151, -1, v150
	v_fma_f32 v158, -v151, v150, v124
	v_add_u32_e32 v152, 1, v150
	v_cmp_ge_f32_e64 s[2:3], 0, v158
	s_nop 1
	v_cndmask_b32_e64 v151, v150, v151, s[2:3]
	v_fma_f32 v150, -v152, v150, v124
	v_cmp_lt_f32_e64 s[2:3], 0, v150
	s_nop 1
	v_cndmask_b32_e64 v150, v151, v152, s[2:3]
	v_mul_f32_e32 v151, 0x37800000, v150
	v_cndmask_b32_e32 v150, v150, v151, vcc
	v_cmp_class_f32_e32 vcc, v124, v131
	s_nop 1
	v_cndmask_b32_e32 v124, v150, v124, vcc
	v_div_scale_f32 v150, s[2:3], v124, v124, 1.0
	v_rcp_f32_e32 v151, v150
	s_nop 0
	v_fma_f32 v152, -v150, v151, 1.0
	v_fmac_f32_e32 v151, v152, v151
	v_div_scale_f32 v152, vcc, 1.0, v124, 1.0
	v_mul_f32_e32 v158, v152, v151
	v_fma_f32 v159, -v150, v158, v152
	v_fmac_f32_e32 v158, v159, v151
	v_fma_f32 v150, -v150, v158, v152
	v_div_fmas_f32 v150, v150, v151, v158
	v_div_fixup_f32 v124, v150, v124, 1.0
	s_and_saveexec_b64 s[2:3], s[0:1]
	s_cbranch_execz .LBB0_141
	v_mov_b32_e32 v151, s5
	v_add_co_u32_e32 v158, vcc, 0x1fa00000, v151
	v_mov_b32_e32 v151, s4
	v_mul_f32_e32 v150, 0x3a800000, v157
	v_addc_co_u32_e32 v159, vcc, 0, v151, vcc
	v_mov_b32_e32 v151, v124
	global_store_dwordx2 v[158:159], v[150:151], off offset:24
.LBB0_141:
	s_or_b64 exec, exec, s[2:3]
	v_add_f32_e32 v128, v128, v161
	v_fmamk_f32 v128, v128, 0x3a800000, v1
	v_mul_f32_e32 v150, 0x4f800000, v128
	v_cmp_gt_f32_e32 vcc, s57, v128
	s_nop 1
	v_cndmask_b32_e32 v128, v128, v150, vcc
	v_sqrt_f32_e32 v150, v128
	s_nop 0
	v_add_u32_e32 v151, -1, v150
	v_fma_f32 v157, -v151, v150, v128
	v_add_u32_e32 v152, 1, v150
	v_cmp_ge_f32_e64 s[2:3], 0, v157
	s_nop 1
	v_cndmask_b32_e64 v151, v150, v151, s[2:3]
	v_fma_f32 v150, -v152, v150, v128
	v_cmp_lt_f32_e64 s[2:3], 0, v150
	s_nop 1
	v_cndmask_b32_e64 v150, v151, v152, s[2:3]
	v_mul_f32_e32 v151, 0x37800000, v150
	v_cndmask_b32_e32 v150, v150, v151, vcc
	v_cmp_class_f32_e32 vcc, v128, v131
	s_nop 1
	v_cndmask_b32_e32 v128, v150, v128, vcc
	v_div_scale_f32 v150, s[2:3], v128, v128, 1.0
	v_rcp_f32_e32 v151, v150
	s_nop 0
	v_fma_f32 v152, -v150, v151, 1.0
	v_fmac_f32_e32 v151, v152, v151
	v_div_scale_f32 v152, vcc, 1.0, v128, 1.0
	v_mul_f32_e32 v157, v152, v151
	v_fma_f32 v158, -v150, v157, v152
	v_fmac_f32_e32 v157, v158, v151
	v_fma_f32 v150, -v150, v157, v152
	v_div_fmas_f32 v150, v150, v151, v157
	v_div_fixup_f32 v128, v150, v128, 1.0
	s_and_saveexec_b64 s[2:3], s[0:1]
	s_cbranch_execz .LBB0_143
	v_mov_b32_e32 v151, s5
	v_mul_f32_e32 v150, 0x3a800000, v156
	v_add_co_u32_e32 v156, vcc, 0x1fa00000, v151
	v_mov_b32_e32 v151, s4
	s_nop 0
	v_addc_co_u32_e32 v157, vcc, 0, v151, vcc
	v_mov_b32_e32 v151, v128
	global_store_dwordx2 v[156:157], v[150:151], off offset:32
.LBB0_143:
	s_or_b64 exec, exec, s[2:3]
	v_add_f32_e32 v129, v129, v160
	v_fmamk_f32 v129, v129, 0x3a800000, v1
	v_mul_f32_e32 v150, 0x4f800000, v129
	v_cmp_gt_f32_e32 vcc, s57, v129
	s_nop 1
	v_cndmask_b32_e32 v129, v129, v150, vcc
	v_sqrt_f32_e32 v150, v129
	s_nop 0
	v_add_u32_e32 v151, -1, v150
	v_fma_f32 v156, -v151, v150, v129
	v_add_u32_e32 v152, 1, v150
	v_cmp_ge_f32_e64 s[2:3], 0, v156
	s_nop 1
	v_cndmask_b32_e64 v151, v150, v151, s[2:3]
	v_fma_f32 v150, -v152, v150, v129
	v_cmp_lt_f32_e64 s[2:3], 0, v150
	s_nop 1
	v_cndmask_b32_e64 v150, v151, v152, s[2:3]
	v_mul_f32_e32 v151, 0x37800000, v150
	v_cndmask_b32_e32 v150, v150, v151, vcc
	v_cmp_class_f32_e32 vcc, v129, v131
	s_nop 1
	v_cndmask_b32_e32 v129, v150, v129, vcc
	v_div_scale_f32 v150, s[2:3], v129, v129, 1.0
	v_rcp_f32_e32 v151, v150
	s_nop 0
	v_fma_f32 v152, -v150, v151, 1.0
	v_fmac_f32_e32 v151, v152, v151
	v_div_scale_f32 v152, vcc, 1.0, v129, 1.0
	v_mul_f32_e32 v156, v152, v151
	v_fma_f32 v157, -v150, v156, v152
	v_fmac_f32_e32 v156, v157, v151
	v_fma_f32 v150, -v150, v156, v152
	v_div_fmas_f32 v150, v150, v151, v156
	v_div_fixup_f32 v150, v150, v129, 1.0
	s_and_saveexec_b64 s[2:3], s[0:1]
	s_cbranch_execz .LBB0_145
	v_mov_b32_e32 v129, s5
	v_add_co_u32_e32 v158, vcc, 0x1fa00000, v129
	v_mov_b32_e32 v129, s4
	v_mul_f32_e32 v156, 0x3a800000, v155
	v_addc_co_u32_e32 v159, vcc, 0, v129, vcc
	v_mov_b32_e32 v157, v150
	global_store_dwordx2 v[158:159], v[156:157], off offset:40
.LBB0_145:
	s_or_b64 exec, exec, s[2:3]
	v_add_f32_e32 v121, v121, v125
	v_fmamk_f32 v121, v121, 0x3a800000, v1
	v_mul_f32_e32 v125, 0x4f800000, v121
	v_cmp_gt_f32_e32 vcc, s57, v121
	s_nop 1
	v_cndmask_b32_e32 v121, v121, v125, vcc
	v_sqrt_f32_e32 v125, v121
	s_nop 0
	v_add_u32_e32 v129, -1, v125
	v_fma_f32 v152, -v129, v125, v121
	v_add_u32_e32 v151, 1, v125
	v_cmp_ge_f32_e64 s[2:3], 0, v152
	s_nop 1
	v_cndmask_b32_e64 v129, v125, v129, s[2:3]
	v_fma_f32 v125, -v151, v125, v121
	v_cmp_lt_f32_e64 s[2:3], 0, v125
	s_nop 1
	v_cndmask_b32_e64 v125, v129, v151, s[2:3]
	v_mul_f32_e32 v129, 0x37800000, v125
	v_cndmask_b32_e32 v125, v125, v129, vcc
	v_cmp_class_f32_e32 vcc, v121, v131
	s_nop 1
	v_cndmask_b32_e32 v121, v125, v121, vcc
	v_div_scale_f32 v125, s[2:3], v121, v121, 1.0
	v_rcp_f32_e32 v129, v125
	s_nop 0
	v_fma_f32 v151, -v125, v129, 1.0
	v_fmac_f32_e32 v129, v151, v129
	v_div_scale_f32 v151, vcc, 1.0, v121, 1.0
	v_mul_f32_e32 v152, v151, v129
	v_fma_f32 v155, -v125, v152, v151
	v_fmac_f32_e32 v152, v155, v129
	v_fma_f32 v125, -v125, v152, v151
	v_div_fmas_f32 v125, v125, v129, v152
	v_div_fixup_f32 v152, v125, v121, 1.0
	s_and_saveexec_b64 s[2:3], s[0:1]
	s_cbranch_execz .LBB0_147
	v_mov_b32_e32 v121, s5
	v_add_co_u32_e32 v156, vcc, 0x1fa00000, v121
	v_mov_b32_e32 v121, s4
	v_mul_f32_e32 v154, 0x3a800000, v154
	v_addc_co_u32_e32 v157, vcc, 0, v121, vcc
	v_mov_b32_e32 v155, v152
	global_store_dwordx2 v[156:157], v[154:155], off offset:48
.LBB0_147:
	s_or_b64 exec, exec, s[2:3]
	v_add_f32_e32 v57, v57, v85
	v_fmamk_f32 v57, v57, 0x3a800000, v1
	v_mul_f32_e32 v85, 0x4f800000, v57
	v_cmp_gt_f32_e32 vcc, s57, v57
	s_nop 1
	v_cndmask_b32_e32 v57, v57, v85, vcc
	v_sqrt_f32_e32 v85, v57
	s_nop 0
	v_add_u32_e32 v121, -1, v85
	v_fma_f32 v129, -v121, v85, v57
	v_add_u32_e32 v125, 1, v85
	v_cmp_ge_f32_e64 s[2:3], 0, v129
	s_nop 1
	v_cndmask_b32_e64 v121, v85, v121, s[2:3]
	v_fma_f32 v85, -v125, v85, v57
	v_cmp_lt_f32_e64 s[2:3], 0, v85
	s_nop 1
	v_cndmask_b32_e64 v85, v121, v125, s[2:3]
	v_mul_f32_e32 v121, 0x37800000, v85
	v_cndmask_b32_e32 v85, v85, v121, vcc
	v_cmp_class_f32_e32 vcc, v57, v131
	s_nop 1
	v_cndmask_b32_e32 v57, v85, v57, vcc
	v_div_scale_f32 v85, s[2:3], v57, v57, 1.0
	v_rcp_f32_e32 v121, v85
	s_nop 0
	v_fma_f32 v125, -v85, v121, 1.0
	v_fmac_f32_e32 v121, v125, v121
	v_div_scale_f32 v125, vcc, 1.0, v57, 1.0
	v_mul_f32_e32 v129, v125, v121
	v_fma_f32 v151, -v85, v129, v125
	v_fmac_f32_e32 v129, v151, v121
	v_fma_f32 v85, -v85, v129, v125
	v_div_fmas_f32 v85, v85, v121, v129
	v_div_fixup_f32 v154, v85, v57, 1.0
	s_and_saveexec_b64 s[2:3], s[0:1]
	s_cbranch_execz .LBB0_132
	v_mov_b32_e32 v57, s5
	v_add_co_u32_e32 v158, vcc, 0x1fa00000, v57
	v_mov_b32_e32 v57, s4
	v_mul_f32_e32 v156, 0x3a800000, v153
	v_addc_co_u32_e32 v159, vcc, 0, v57, vcc
	v_mov_b32_e32 v157, v154
	global_store_dwordx2 v[158:159], v[156:157], off offset:56
	s_branch .LBB0_132

.LBB0_191:
	s_lshl_b32 s3, s20, 8
	v_mbcnt_lo_u32_b32 v138, -1, 0
	v_mbcnt_hi_u32_b32 v138, -1, v138
	s_add_i32 s3, s3, s41
	v_and_or_b32 v140, v138, 15, s3
	s_lshl_b32 s2, s2, 8
	v_ashrrev_i32_e32 v138, 1, v138
	v_and_b32_e32 v138, -8, v138
	s_or_b32 s2, s2, s42
	v_ashrrev_i32_e32 v141, 31, v140
	v_add_u32_e32 v138, s2, v138
	v_lshlrev_b64 v[142:143], 13, v[140:141]
	v_lshl_add_u64 v[142:143], s[8:9], 0, v[142:143]
	v_cmp_gt_i32_e32 vcc, s65, v138
	v_ashrrev_i32_e32 v139, 31, v138
	s_and_saveexec_b64 s[2:3], vcc
	s_cbranch_execz .LBB0_193
	v_cvt_pk_bf16_f32 v124, v124, v125
	v_cvt_pk_bf16_f32 v125, v126, v127
	v_cvt_pk_bf16_f32 v126, v120, v121
	v_cvt_pk_bf16_f32 v127, v122, v123
	v_lshl_add_u64 v[120:121], v[138:139], 1, v[142:143]
	global_store_dwordx4 v[120:121], v[124:127], off
.LBB0_193:
	s_or_b64 exec, exec, s[2:3]
	v_add_u32_e32 v120, 0x80, v138
	v_cmp_gt_i32_e64 s[2:3], s65, v120
	s_and_saveexec_b64 s[20:21], s[2:3]
	s_cbranch_execz .LBB0_195
	v_cvt_pk_bf16_f32 v116, v116, v117
	v_cvt_pk_bf16_f32 v117, v118, v119
	v_cvt_pk_bf16_f32 v118, v108, v109
	v_cvt_pk_bf16_f32 v119, v110, v111
	v_lshl_add_u64 v[108:109], v[138:139], 1, v[142:143]
	global_store_dwordx4 v[108:109], v[116:119], off offset:256
.LBB0_195:
	s_or_b64 exec, exec, s[20:21]
	v_or_b32_e32 v108, 16, v140
	v_ashrrev_i32_e32 v109, 31, v108
	v_lshlrev_b64 v[108:109], 13, v[108:109]
	v_lshl_add_u64 v[108:109], s[8:9], 0, v[108:109]
	s_and_saveexec_b64 s[20:21], vcc
	s_cbranch_execz .LBB0_197
	v_cvt_pk_bf16_f32 v110, v112, v113
	v_cvt_pk_bf16_f32 v111, v114, v115
	v_cvt_pk_bf16_f32 v112, v104, v105
	v_cvt_pk_bf16_f32 v113, v106, v107
	v_lshl_add_u64 v[104:105], v[138:139], 1, v[108:109]
	global_store_dwordx4 v[104:105], v[110:113], off
.LBB0_197:
	s_or_b64 exec, exec, s[20:21]
	s_and_saveexec_b64 s[20:21], s[2:3]
	s_cbranch_execz .LBB0_199
	v_cvt_pk_bf16_f32 v100, v100, v101
	v_cvt_pk_bf16_f32 v101, v102, v103
	v_cvt_pk_bf16_f32 v102, v92, v93
	v_cvt_pk_bf16_f32 v103, v94, v95
	v_lshl_add_u64 v[92:93], v[138:139], 1, v[108:109]
	global_store_dwordx4 v[92:93], v[100:103], off offset:256
.LBB0_199:
	s_or_b64 exec, exec, s[20:21]
	v_or_b32_e32 v92, 32, v140
	v_ashrrev_i32_e32 v93, 31, v92
	v_lshlrev_b64 v[92:93], 13, v[92:93]
	v_lshl_add_u64 v[92:93], s[8:9], 0, v[92:93]
	s_and_saveexec_b64 s[20:21], vcc
	s_cbranch_execz .LBB0_201
	v_cvt_pk_bf16_f32 v94, v96, v97
	v_cvt_pk_bf16_f32 v95, v98, v99
	v_cvt_pk_bf16_f32 v96, v88, v89
	v_cvt_pk_bf16_f32 v97, v90, v91
	v_lshl_add_u64 v[88:89], v[138:139], 1, v[92:93]
	global_store_dwordx4 v[88:89], v[94:97], off
.LBB0_201:
	s_or_b64 exec, exec, s[20:21]
	s_and_saveexec_b64 s[20:21], s[2:3]
	s_cbranch_execz .LBB0_203
	v_cvt_pk_bf16_f32 v84, v84, v85
	v_cvt_pk_bf16_f32 v85, v86, v87
	v_cvt_pk_bf16_f32 v86, v76, v77
	v_cvt_pk_bf16_f32 v87, v78, v79
	v_lshl_add_u64 v[76:77], v[138:139], 1, v[92:93]
	global_store_dwordx4 v[76:77], v[84:87], off offset:256
.LBB0_203:
	s_or_b64 exec, exec, s[20:21]
	v_or_b32_e32 v76, 48, v140
	v_ashrrev_i32_e32 v77, 31, v76
	v_lshlrev_b64 v[76:77], 13, v[76:77]
	v_lshl_add_u64 v[76:77], s[8:9], 0, v[76:77]
	s_and_saveexec_b64 s[20:21], vcc
	s_cbranch_execz .LBB0_205
	v_cvt_pk_bf16_f32 v78, v80, v81
	v_cvt_pk_bf16_f32 v79, v82, v83
	v_cvt_pk_bf16_f32 v80, v72, v73
	v_cvt_pk_bf16_f32 v81, v74, v75
	v_lshl_add_u64 v[72:73], v[138:139], 1, v[76:77]
	global_store_dwordx4 v[72:73], v[78:81], off
.LBB0_205:
	s_or_b64 exec, exec, s[20:21]
	s_and_saveexec_b64 s[20:21], s[2:3]
	s_cbranch_execz .LBB0_207
	v_cvt_pk_bf16_f32 v68, v68, v69
	v_cvt_pk_bf16_f32 v69, v70, v71
	v_cvt_pk_bf16_f32 v70, v64, v65
	v_cvt_pk_bf16_f32 v71, v66, v67
	v_lshl_add_u64 v[64:65], v[138:139], 1, v[76:77]
	global_store_dwordx4 v[64:65], v[68:71], off offset:256
.LBB0_207:
	s_or_b64 exec, exec, s[20:21]
	v_add_u32_e32 v64, 0x80, v140
	v_ashrrev_i32_e32 v65, 31, v64
	v_lshlrev_b64 v[64:65], 13, v[64:65]
	v_lshl_add_u64 v[64:65], s[8:9], 0, v[64:65]
	s_and_saveexec_b64 s[20:21], vcc
	s_cbranch_execz .LBB0_209
	v_cvt_pk_bf16_f32 v60, v60, v61
	v_cvt_pk_bf16_f32 v61, v62, v63
	v_cvt_pk_bf16_f32 v62, v56, v57
	v_cvt_pk_bf16_f32 v63, v58, v59
	v_lshl_add_u64 v[56:57], v[138:139], 1, v[64:65]
	global_store_dwordx4 v[56:57], v[60:63], off
.LBB0_209:
	s_or_b64 exec, exec, s[20:21]
	s_and_saveexec_b64 s[20:21], s[2:3]
	s_cbranch_execz .LBB0_211
	v_cvt_pk_bf16_f32 v52, v52, v53
	v_cvt_pk_bf16_f32 v53, v54, v55
	v_cvt_pk_bf16_f32 v54, v44, v45
	v_cvt_pk_bf16_f32 v55, v46, v47
	v_lshl_add_u64 v[44:45], v[138:139], 1, v[64:65]
	global_store_dwordx4 v[44:45], v[52:55], off offset:256
.LBB0_211:
	s_or_b64 exec, exec, s[20:21]
	v_add_u32_e32 v44, 0x90, v140
	v_ashrrev_i32_e32 v45, 31, v44
	v_lshlrev_b64 v[44:45], 13, v[44:45]
	v_lshl_add_u64 v[44:45], s[8:9], 0, v[44:45]
	s_and_saveexec_b64 s[20:21], vcc
	s_cbranch_execz .LBB0_213
	v_cvt_pk_bf16_f32 v46, v48, v49
	v_cvt_pk_bf16_f32 v47, v50, v51
	v_cvt_pk_bf16_f32 v48, v40, v41
	v_cvt_pk_bf16_f32 v49, v42, v43
	v_lshl_add_u64 v[40:41], v[138:139], 1, v[44:45]
	global_store_dwordx4 v[40:41], v[46:49], off
.LBB0_213:
	s_or_b64 exec, exec, s[20:21]
	s_and_saveexec_b64 s[20:21], s[2:3]
	s_cbranch_execz .LBB0_215
	v_cvt_pk_bf16_f32 v36, v36, v37
	v_cvt_pk_bf16_f32 v37, v38, v39
	v_cvt_pk_bf16_f32 v38, v28, v29
	v_cvt_pk_bf16_f32 v39, v30, v31
	v_lshl_add_u64 v[28:29], v[138:139], 1, v[44:45]
	global_store_dwordx4 v[28:29], v[36:39], off offset:256
.LBB0_215:
	s_or_b64 exec, exec, s[20:21]
	v_add_u32_e32 v28, 0xa0, v140
	v_ashrrev_i32_e32 v29, 31, v28
	v_lshlrev_b64 v[28:29], 13, v[28:29]
	v_lshl_add_u64 v[28:29], s[8:9], 0, v[28:29]
	s_and_saveexec_b64 s[20:21], vcc
	s_cbranch_execz .LBB0_217
	v_cvt_pk_bf16_f32 v30, v32, v33
	v_cvt_pk_bf16_f32 v31, v34, v35
	v_cvt_pk_bf16_f32 v32, v24, v25
	v_cvt_pk_bf16_f32 v33, v26, v27
	v_lshl_add_u64 v[24:25], v[138:139], 1, v[28:29]
	global_store_dwordx4 v[24:25], v[30:33], off
.LBB0_217:
	s_or_b64 exec, exec, s[20:21]
	s_and_saveexec_b64 s[20:21], s[2:3]
	s_cbranch_execz .LBB0_219
	v_cvt_pk_bf16_f32 v20, v20, v21
	v_cvt_pk_bf16_f32 v21, v22, v23
	v_cvt_pk_bf16_f32 v22, v12, v13
	v_cvt_pk_bf16_f32 v23, v14, v15
	v_lshl_add_u64 v[12:13], v[138:139], 1, v[28:29]
	global_store_dwordx4 v[12:13], v[20:23], off offset:256
.LBB0_219:
	s_or_b64 exec, exec, s[20:21]
	v_add_u32_e32 v12, 0xb0, v140
	v_ashrrev_i32_e32 v13, 31, v12
	v_lshlrev_b64 v[12:13], 13, v[12:13]
	v_lshl_add_u64 v[12:13], s[8:9], 0, v[12:13]
	s_and_saveexec_b64 s[20:21], vcc
	s_cbranch_execz .LBB0_221
	v_cvt_pk_bf16_f32 v14, v16, v17
	v_cvt_pk_bf16_f32 v15, v18, v19
	v_cvt_pk_bf16_f32 v16, v8, v9
	v_cvt_pk_bf16_f32 v17, v10, v11
	v_lshl_add_u64 v[8:9], v[138:139], 1, v[12:13]
	global_store_dwordx4 v[8:9], v[14:17], off
.LBB0_221:
	s_or_b64 exec, exec, s[20:21]
	s_and_saveexec_b64 s[20:21], s[2:3]
	s_cbranch_execz .LBB0_223
	v_cvt_pk_bf16_f32 v4, v4, v5
	v_cvt_pk_bf16_f32 v5, v6, v7
	v_cvt_pk_bf16_f32 v6, v0, v1
	v_cvt_pk_bf16_f32 v7, v2, v3
	v_lshl_add_u64 v[0:1], v[138:139], 1, v[12:13]
	global_store_dwordx4 v[0:1], v[4:7], off offset:256

.LBB0_235:
	v_mov_b64_e32 v[12:13], s[36:37]
	global_load_dword v1, v[12:13], off offset:1024 sc1
	s_waitcnt lgkmcnt(0)
	global_load_dword v0, v[12:13], off offset:1280 sc1
	global_load_dword v2, v[12:13], off offset:1536 sc1
	s_or_b64 s[16:17], s[16:17], exec
	s_or_b64 s[14:15], s[14:15], exec
	s_waitcnt vmcnt(0) lgkmcnt(0)
	v_add_u32_e32 v3, v0, v1
	v_add_u32_e32 v4, v3, v2
	global_load_dword v3, v[12:13], off offset:1792 sc1
	s_waitcnt vmcnt(0) lgkmcnt(0)
	v_add_u32_e32 v5, v4, v3
	global_load_dword v4, v[12:13], off offset:2048 sc1
	s_waitcnt vmcnt(0) lgkmcnt(0)
	v_add_u32_e32 v6, v5, v4
	global_load_dword v5, v[12:13], off offset:2304 sc1
	s_waitcnt vmcnt(0) lgkmcnt(0)
	v_add_u32_e32 v7, v6, v5
	global_load_dword v6, v[12:13], off offset:2560 sc1
	s_waitcnt vmcnt(0) lgkmcnt(0)
	v_add_u32_e32 v8, v7, v6
	global_load_dword v7, v[12:13], off offset:2816 sc1
	s_waitcnt vmcnt(0) lgkmcnt(0)
	v_add_u32_e32 v9, v8, v7
	global_load_dword v8, v[12:13], off offset:3072 sc1
	s_waitcnt vmcnt(0) lgkmcnt(0)
	v_add_u32_e32 v10, v9, v8
	global_load_dword v9, v[12:13], off offset:3328 sc1
	s_waitcnt vmcnt(0) lgkmcnt(0)
	v_add_u32_e32 v11, v10, v9
	global_load_dword v10, v[12:13], off offset:3584 sc1
	s_waitcnt vmcnt(0) lgkmcnt(0)
	v_add_u32_e32 v14, v11, v10
	global_load_dword v11, v[12:13], off offset:3840 sc1
	v_mov_b64_e32 v[12:13], s[2:3]
	global_load_dword v12, v[12:13], off sc1
	s_waitcnt vmcnt(0) lgkmcnt(0)
	v_add_u32_e32 v14, v14, v11
	v_add_u32_e32 v16, v14, v12
	v_mov_b64_e32 v[14:15], s[4:5]
	global_load_dword v13, v[14:15], off sc1
	v_mov_b64_e32 v[14:15], s[6:7]
	global_load_dword v14, v[14:15], off sc1
	s_waitcnt vmcnt(0) lgkmcnt(0)
	v_add_u32_e32 v16, v16, v13
	v_add_u32_e32 v18, v16, v14
	v_mov_b64_e32 v[16:17], s[8:9]
	global_load_dword v15, v[16:17], off sc1
	s_waitcnt vmcnt(0) lgkmcnt(0)
	v_add_u32_e32 v16, v18, v15
	v_cmp_ne_u32_e32 vcc, s74, v16
	s_and_saveexec_b64 s[18:19], vcc
	s_cbranch_execz .LBB0_234
	s_and_b32 s22, s28, 0xff
	s_mov_b64 s[20:21], -1
	s_cmp_eq_u32 s22, 0
	s_mov_b64 s[24:25], -1
	s_mov_b64 s[22:23], -1
	s_sleep 1
	s_cbranch_scc1 .LBB0_238
	s_and_saveexec_b64 s[26:27], s[24:25]
	s_cbranch_execz .LBB0_233
	s_branch .LBB0_241
.LBB0_238:
	v_mov_b64_e32 v[16:17], s[36:37]
	global_load_dword v16, v[16:17], off offset:512 sc1
	s_mov_b64 s[24:25], 0
	s_waitcnt vmcnt(0) lgkmcnt(0)
	v_cmp_eq_u32_e32 vcc, 0, v16
	s_and_saveexec_b64 s[26:27], vcc
	s_cmp_lt_u32 s28, 0x100001
	s_cselect_b64 s[24:25], -1, 0
	s_xor_b64 s[22:23], exec, -1
	s_and_b64 s[24:25], s[24:25], exec
	s_or_b64 exec, exec, s[26:27]
	s_and_saveexec_b64 s[26:27], s[24:25]
	s_cbranch_execz .LBB0_233

.LBB0_245:
	s_lshl_b32 s2, s39, 8
	s_add_u32 s23, s36, s2
	s_addc_u32 s22, s37, 0
	v_mov_b32_e32 v1, s23
	v_add_co_u32_e32 v4, vcc, 0x1000, v1
	v_mov_b32_e32 v1, s22
	s_nop 0
	v_addc_co_u32_e32 v5, vcc, 0, v1, vcc
	v_mov_b32_e32 v1, 1
	flat_atomic_add v3, v[4:5], v1 offset:1024 sc0
	v_cvt_f32_u32_e32 v1, v2
	v_sub_u32_e32 v4, 0, v2
	v_rcp_iflag_f32_e32 v1, v1
	s_nop 0
	v_mul_f32_e32 v1, 0x4f7ffffe, v1
	v_cvt_u32_f32_e32 v1, v1
	v_mul_lo_u32 v4, v4, v1
	v_mul_hi_u32 v4, v1, v4
	v_add_u32_e32 v1, v1, v4
	s_waitcnt vmcnt(0) lgkmcnt(0)
	v_mul_hi_u32 v1, v3, v1
	v_mul_lo_u32 v4, v1, v2
	v_sub_u32_e32 v4, v3, v4
	v_cmp_ge_u32_e32 vcc, v4, v2
	v_add_u32_e32 v5, 1, v1
	s_nop 0
	v_cndmask_b32_e32 v1, v1, v5, vcc
	v_sub_u32_e32 v5, v4, v2
	v_cndmask_b32_e32 v4, v4, v5, vcc
	v_cmp_ge_u32_e32 vcc, v4, v2
	v_add_u32_e32 v4, 1, v1
	s_nop 0
	v_cndmask_b32_e32 v1, v1, v4, vcc
	v_add_u32_e32 v4, 1, v3
	v_mad_u64_u32 v[2:3], s[2:3], v2, v1, v[2:3]
	v_cmp_ne_u32_e32 vcc, v4, v2
	s_and_saveexec_b64 s[2:3], vcc
	s_xor_b64 s[2:3], exec, s[2:3]
	s_cbranch_execz .LBB0_258
	v_mov_b32_e32 v0, s23
	v_add_co_u32_e32 v2, vcc, 0x2000, v0
	v_mov_b32_e32 v0, s22
	s_nop 0
	v_addc_co_u32_e32 v3, vcc, 0, v0, vcc
	global_load_dword v0, v[2:3], off offset:1024 sc1
	s_add_u32 s6, s23, 0x2400
	s_addc_u32 s7, s22, 0
	s_waitcnt vmcnt(0) lgkmcnt(0)
	v_cmp_eq_u32_e32 vcc, v0, v1
	s_and_saveexec_b64 s[4:5], vcc
	s_cbranch_execz .LBB0_257
	s_mov_b32 s24, 1
	s_mov_b64 s[8:9], 0
	s_branch .LBB0_249

.LBB0_249:
	s_and_b32 s16, s24, 0xff
	s_mov_b64 s[14:15], -1
	s_cmp_lg_u32 s16, 0
	s_mov_b64 s[16:17], -1
	s_sleep 1
	s_cbranch_scc1 .LBB0_253
	v_mov_b64_e32 v[2:3], s[36:37]
	global_load_dword v0, v[2:3], off offset:512 sc1
	s_mov_b64 s[16:17], 0
	s_mov_b64 s[18:19], -1
	s_waitcnt vmcnt(0) lgkmcnt(0)
	v_cmp_eq_u32_e32 vcc, 0, v0
	s_and_saveexec_b64 s[20:21], vcc
	s_cmp_lt_u32 s24, 0x100001
	s_cselect_b64 s[16:17], -1, 0
	s_xor_b64 s[18:19], exec, -1
	s_and_b64 s[16:17], s[16:17], exec
	s_or_b64 exec, exec, s[20:21]
.LBB0_253:
	s_andn2_b64 s[12:13], s[12:13], exec
	s_and_b64 s[18:19], s[18:19], exec
	s_or_b64 s[12:13], s[12:13], s[18:19]
	s_and_saveexec_b64 s[18:19], s[16:17]
	s_cbranch_execz .LBB0_248
	v_mov_b64_e32 v[2:3], s[6:7]
	global_load_dword v0, v[2:3], off sc1
	s_add_i32 s24, s24, 1
	s_or_b64 s[12:13], s[12:13], exec
	s_waitcnt vmcnt(0) lgkmcnt(0)
	v_cmp_ne_u32_e32 vcc, v0, v1
	s_orn2_b64 s[14:15], vcc, exec
	s_branch .LBB0_248

.LBB0_258:
	s_andn2_saveexec_b64 s[2:3], s[2:3]
	s_cbranch_execz .LBB0_274
	v_mov_b32_e32 v1, s36
	v_add_co_u32_e32 v2, vcc, 0x3000, v1
	v_mov_b32_e32 v1, s37
	buffer_wbl2 sc1
	s_waitcnt vmcnt(0)
	v_addc_co_u32_e32 v3, vcc, 0, v1, vcc
	v_mov_b32_e32 v1, 1
	flat_atomic_add v1, v[2:3], v1 offset:1024 sc0
	v_cvt_f32_u32_e32 v2, v0
	v_sub_u32_e32 v3, 0, v0
	s_mov_b64 s[6:7], -1
	v_rcp_iflag_f32_e32 v2, v2
	s_nop 0
	v_mul_f32_e32 v2, 0x4f7ffffe, v2
	v_cvt_u32_f32_e32 v2, v2
	v_mul_lo_u32 v3, v3, v2
	v_mul_hi_u32 v3, v2, v3
	v_add_u32_e32 v2, v2, v3
	s_waitcnt vmcnt(0) lgkmcnt(0)
	v_mul_hi_u32 v2, v1, v2
	v_mul_lo_u32 v3, v2, v0
	v_sub_u32_e32 v3, v1, v3
	v_cmp_ge_u32_e32 vcc, v3, v0
	v_add_u32_e32 v4, 1, v2
	s_nop 0
	v_cndmask_b32_e32 v2, v2, v4, vcc
	v_sub_u32_e32 v4, v3, v0
	v_cndmask_b32_e32 v3, v3, v4, vcc
	v_cmp_ge_u32_e32 vcc, v3, v0
	v_add_u32_e32 v3, 1, v2
	s_nop 0
	v_cndmask_b32_e32 v2, v2, v3, vcc
	v_add_u32_e32 v3, 1, v1
	v_mad_u64_u32 v[0:1], s[2:3], v0, v2, v[0:1]
	s_add_u32 s2, s36, 0x3500
	s_addc_u32 s3, s37, 0
	v_cmp_ne_u32_e32 vcc, v3, v0
	v_mov_b64_e32 v[0:1], s[2:3]
	s_and_saveexec_b64 s[4:5], vcc
	s_cbranch_execz .LBB0_271
	v_mov_b64_e32 v[0:1], s[2:3]
	global_load_dword v0, v[0:1], off sc1
	s_mov_b64 s[10:11], 0
	s_waitcnt vmcnt(0) lgkmcnt(0)
	v_cmp_eq_u32_e32 vcc, v0, v2
	s_and_saveexec_b64 s[8:9], vcc
	s_cbranch_execz .LBB0_270
	s_add_u32 s6, s36, 0x200
	s_addc_u32 s7, s37, 0
	s_mov_b32 s24, 1
	s_branch .LBB0_263

.LBB0_265:
	v_mov_b64_e32 v[0:1], s[6:7]
	global_load_dword v0, v[0:1], off sc1
	s_mov_b64 s[18:19], 0
	s_mov_b64 s[16:17], -1
	s_waitcnt vmcnt(0) lgkmcnt(0)
	v_cmp_eq_u32_e32 vcc, 0, v0
	s_and_saveexec_b64 s[20:21], vcc
	s_cmp_lt_u32 s24, 0x100001
	s_cselect_b64 s[18:19], -1, 0
	s_xor_b64 s[16:17], exec, -1
	s_and_b64 s[18:19], s[18:19], exec
	s_or_b64 exec, exec, s[20:21]
	s_and_saveexec_b64 s[20:21], s[18:19]
	s_cbranch_execz .LBB0_262
.LBB0_268:
	v_mov_b64_e32 v[0:1], s[2:3]
	global_load_dword v0, v[0:1], off sc1
	s_add_i32 s24, s24, 1
	s_or_b64 s[16:17], s[16:17], exec
	s_waitcnt vmcnt(0) lgkmcnt(0)
	v_cmp_ne_u32_e32 vcc, v0, v2
	s_orn2_b64 s[14:15], vcc, exec
	s_branch .LBB0_262

.LBB0_288:
	v_add_u32_e32 v14, s21, v19
	v_ashrrev_i32_e32 v15, 31, v14
	s_waitcnt lgkmcnt(0)
	v_lshlrev_b64 v[0:1], 13, v[14:15]
	v_lshl_add_u64 v[16:17], s[8:9], 0, v[0:1]
	v_lshl_add_u64 v[30:31], v[16:17], 0, v[232:233]
	global_load_dwordx4 v[0:3], v[30:31], off
	s_waitcnt vmcnt(0) lgkmcnt(0)
	v_lshlrev_b32_e32 v25, 16, v0
	v_and_b32_e32 v0, 0xffff0000, v0
	v_mul_f32_e32 v13, v0, v0
	v_lshlrev_b32_e32 v27, 16, v1
	v_and_b32_e32 v26, 0xffff0000, v1
	v_lshlrev_b32_e32 v24, 16, v2
	v_and_b32_e32 v23, 0xffff0000, v2
	v_lshlrev_b32_e32 v22, 16, v3
	v_and_b32_e32 v21, 0xffff0000, v3
	global_load_dwordx4 v[0:3], v[30:31], off offset:16
	v_fmac_f32_e32 v13, v25, v25
	v_fmac_f32_e32 v13, v27, v27
	v_fmac_f32_e32 v13, v26, v26
	v_fmac_f32_e32 v13, v24, v24
	v_fmac_f32_e32 v13, v23, v23
	v_fmac_f32_e32 v13, v22, v22
	v_fmac_f32_e32 v13, v21, v21
	s_waitcnt vmcnt(0) lgkmcnt(0)
	v_lshlrev_b32_e32 v11, 16, v0
	v_and_b32_e32 v0, 0xffff0000, v0
	v_mul_f32_e32 v28, v0, v0
	v_fmac_f32_e32 v28, v11, v11
	v_lshlrev_b32_e32 v0, 16, v1
	v_fmac_f32_e32 v28, v0, v0
	v_and_b32_e32 v0, 0xffff0000, v1
	v_fmac_f32_e32 v28, v0, v0
	v_lshlrev_b32_e32 v0, 16, v2
	v_fmac_f32_e32 v28, v0, v0
	v_and_b32_e32 v0, 0xffff0000, v2
	v_fmac_f32_e32 v28, v0, v0
	v_lshlrev_b32_e32 v0, 16, v3
	v_fmac_f32_e32 v28, v0, v0
	v_and_b32_e32 v0, 0xffff0000, v3
	v_fmac_f32_e32 v28, v0, v0
	global_load_dwordx4 v[0:3], v[30:31], off offset:32
	s_waitcnt vmcnt(0) lgkmcnt(0)
	v_lshlrev_b32_e32 v11, 16, v0
	v_and_b32_e32 v0, 0xffff0000, v0
	v_mul_f32_e32 v29, v0, v0
	v_fmac_f32_e32 v29, v11, v11
	v_lshlrev_b32_e32 v0, 16, v1
	v_fmac_f32_e32 v29, v0, v0
	v_and_b32_e32 v0, 0xffff0000, v1
	v_fmac_f32_e32 v29, v0, v0
	v_lshlrev_b32_e32 v0, 16, v2
	v_fmac_f32_e32 v29, v0, v0
	v_and_b32_e32 v0, 0xffff0000, v2
	v_fmac_f32_e32 v29, v0, v0
	v_lshlrev_b32_e32 v0, 16, v3
	v_fmac_f32_e32 v29, v0, v0
	v_and_b32_e32 v0, 0xffff0000, v3
	v_fmac_f32_e32 v29, v0, v0
	global_load_dwordx4 v[0:3], v[30:31], off offset:48
	s_waitcnt vmcnt(0) lgkmcnt(0)
	v_lshlrev_b32_e32 v11, 16, v0
	v_and_b32_e32 v0, 0xffff0000, v0
	v_mul_f32_e32 v30, v0, v0
	v_fmac_f32_e32 v30, v11, v11
	v_lshlrev_b32_e32 v0, 16, v1
	v_fmac_f32_e32 v30, v0, v0
	v_and_b32_e32 v0, 0xffff0000, v1
	v_fmac_f32_e32 v30, v0, v0
	v_lshlrev_b32_e32 v0, 16, v2
	v_fmac_f32_e32 v30, v0, v0
	v_and_b32_e32 v0, 0xffff0000, v2
	v_fmac_f32_e32 v30, v0, v0
	v_lshlrev_b32_e32 v0, 16, v3
	v_mov_b32_e32 v11, v233
	v_fmac_f32_e32 v30, v0, v0
	v_and_b32_e32 v0, 0xffff0000, v3
	v_lshl_add_u64 v[32:33], v[16:17], 0, v[10:11]
	v_fmac_f32_e32 v30, v0, v0
	global_load_dwordx4 v[0:3], v[32:33], off offset:512
	s_waitcnt vmcnt(0) lgkmcnt(0)
	v_lshlrev_b32_e32 v11, 16, v0
	v_and_b32_e32 v0, 0xffff0000, v0
	v_mul_f32_e32 v31, v0, v0
	v_fmac_f32_e32 v31, v11, v11
	v_lshlrev_b32_e32 v0, 16, v1
	v_fmac_f32_e32 v31, v0, v0
	v_and_b32_e32 v0, 0xffff0000, v1
	v_fmac_f32_e32 v31, v0, v0
	v_lshlrev_b32_e32 v0, 16, v2
	v_fmac_f32_e32 v31, v0, v0
	v_and_b32_e32 v0, 0xffff0000, v2
	v_fmac_f32_e32 v31, v0, v0
	v_lshlrev_b32_e32 v0, 16, v3
	v_fmac_f32_e32 v31, v0, v0
	v_and_b32_e32 v0, 0xffff0000, v3
	v_fmac_f32_e32 v31, v0, v0
	global_load_dwordx4 v[0:3], v[32:33], off offset:528
	s_waitcnt vmcnt(0) lgkmcnt(0)
	v_lshlrev_b32_e32 v11, 16, v0
	v_and_b32_e32 v0, 0xffff0000, v0
	v_mul_f32_e32 v0, v0, v0
	v_fmac_f32_e32 v0, v11, v11
	v_lshlrev_b32_e32 v11, 16, v1
	v_fmac_f32_e32 v0, v11, v11
	v_and_b32_e32 v1, 0xffff0000, v1
	v_fmac_f32_e32 v0, v1, v1
	v_lshlrev_b32_e32 v1, 16, v2
	v_fmac_f32_e32 v0, v1, v1
	v_and_b32_e32 v1, 0xffff0000, v2
	v_fmac_f32_e32 v0, v1, v1
	v_lshlrev_b32_e32 v1, 16, v3
	v_fmac_f32_e32 v0, v1, v1
	v_and_b32_e32 v1, 0xffff0000, v3
	v_fmac_f32_e32 v0, v1, v1
	v_add_f32_e32 v1, v13, v28
	v_add_f32_e32 v1, v1, v29
	v_add_f32_e32 v1, v1, v30
	ds_swizzle_b32 v2, v1 offset:swizzle(SWAP,1)
	v_add_f32_e32 v0, v31, v0
	s_waitcnt lgkmcnt(0)
	v_add_f32_e32 v1, v1, v2
	ds_swizzle_b32 v2, v0 offset:swizzle(SWAP,1)
	s_waitcnt lgkmcnt(0)
	v_add_f32_e32 v2, v0, v2
	ds_swizzle_b32 v0, v1 offset:swizzle(SWAP,2)
	s_waitcnt lgkmcnt(0)
	v_add_f32_e32 v0, v1, v0
	ds_swizzle_b32 v1, v2 offset:swizzle(SWAP,2)
	s_waitcnt lgkmcnt(0)
	v_add_f32_e32 v2, v2, v1
	ds_swizzle_b32 v1, v0 offset:swizzle(SWAP,4)
	ds_swizzle_b32 v3, v2 offset:swizzle(SWAP,4)
	s_and_saveexec_b64 s[14:15], s[2:3]
	s_cbranch_execz .LBB0_290
	s_waitcnt lgkmcnt(1)
	v_add_f32_e32 v0, v0, v1
	v_fmamk_f32 v0, v0, 0x3b800000, v249
	v_cmp_gt_f32_e32 vcc, s84, v0
	v_mul_f32_e32 v1, 0x4f800000, v0
	s_waitcnt lgkmcnt(0)
	v_add_f32_e32 v2, v2, v3
	v_cndmask_b32_e32 v0, v0, v1, vcc
	v_sqrt_f32_e32 v1, v0
	v_fmamk_f32 v2, v2, 0x3c000000, v249
	v_add_u32_e32 v3, -1, v1
	v_fma_f32 v11, -v3, v1, v0
	v_cmp_ge_f32_e64 s[6:7], 0, v11
	v_add_u32_e32 v11, 1, v1
	s_nop 0
	v_cndmask_b32_e64 v3, v1, v3, s[6:7]
	v_fma_f32 v1, -v11, v1, v0
	v_cmp_lt_f32_e64 s[6:7], 0, v1
	s_nop 1
	v_cndmask_b32_e64 v1, v3, v11, s[6:7]
	v_mul_f32_e32 v3, 0x37800000, v1
	v_cndmask_b32_e32 v1, v1, v3, vcc
	v_cmp_class_f32_e32 vcc, v0, v248
	v_mul_f32_e32 v3, 0x4f800000, v2
	s_nop 0
	v_cndmask_b32_e32 v11, v1, v0, vcc
	v_cmp_gt_f32_e32 vcc, s84, v2
	v_lshl_add_u64 v[0:1], v[14:15], 3, s[10:11]
	s_nop 0
	v_cndmask_b32_e32 v2, v2, v3, vcc
	v_sqrt_f32_e32 v3, v2
	s_nop 0
	v_add_u32_e32 v13, -1, v3
	v_fma_f32 v21, -v13, v3, v2
	v_cmp_ge_f32_e64 s[6:7], 0, v21
	v_add_u32_e32 v21, 1, v3
	s_nop 0
	v_cndmask_b32_e64 v13, v3, v13, s[6:7]
	v_fma_f32 v3, -v21, v3, v2
	v_cmp_lt_f32_e64 s[6:7], 0, v3
	s_nop 1
	v_cndmask_b32_e64 v3, v13, v21, s[6:7]
	v_mul_f32_e32 v13, 0x37800000, v3
	v_cndmask_b32_e32 v3, v3, v13, vcc
	v_cmp_class_f32_e32 vcc, v2, v248
	s_nop 1
	v_cndmask_b32_e32 v2, v3, v2, vcc
	v_div_scale_f32 v3, s[6:7], v2, v2, 1.0
	v_rcp_f32_e32 v13, v3
	s_nop 0
	v_fma_f32 v21, -v3, v13, 1.0
	v_fmac_f32_e32 v13, v21, v13
	v_div_scale_f32 v21, vcc, 1.0, v2, 1.0
	v_mul_f32_e32 v22, v21, v13
	v_fma_f32 v23, -v3, v22, v21
	v_fmac_f32_e32 v22, v23, v13
	v_fma_f32 v3, -v3, v22, v21
	v_div_fmas_f32 v3, v3, v13, v22
	v_div_fixup_f32 v3, v3, v2, 1.0
	v_div_scale_f32 v2, s[6:7], v11, v11, 1.0
	v_rcp_f32_e32 v13, v2
	s_nop 0
	v_fma_f32 v21, -v2, v13, 1.0
	v_fmac_f32_e32 v13, v21, v13
	v_div_scale_f32 v21, vcc, 1.0, v11, 1.0
	v_mul_f32_e32 v22, v21, v13
	v_fma_f32 v23, -v2, v22, v21
	v_fmac_f32_e32 v22, v23, v13
	v_fma_f32 v2, -v2, v22, v21
	v_div_fmas_f32 v2, v2, v13, v22
	v_div_fixup_f32 v2, v2, v11, 1.0
	global_store_dwordx2 v[0:1], v[2:3], off
.LBB0_290:
	s_or_b64 exec, exec, s[14:15]
	s_and_saveexec_b64 s[6:7], s[12:13]
	s_cbranch_execz .LBB0_287
	v_mov_b32_e32 v13, v233
	s_waitcnt lgkmcnt(0)
	v_lshl_add_u64 v[0:1], v[16:17], 0, v[12:13]
	global_load_dwordx2 v[16:17], v[0:1], off offset:768
	global_load_dwordx2 v[26:27], v[0:1], off offset:800
	v_and_b32_e32 v0, 0x1fff0, v20
	v_lshlrev_b32_e32 v22, 2, v0
	v_mov_b32_e32 v23, v233
	v_lshl_add_u64 v[0:1], v[4:5], 0, v[22:23]
	v_lshl_add_u64 v[22:23], v[6:7], 0, v[22:23]
	global_load_dwordx4 v[0:3], v[0:1], off
	s_waitcnt vmcnt(0) lgkmcnt(0)
	v_lshlrev_b32_e32 v28, 16, v16
	global_load_dwordx4 v[22:25], v[22:23], off
	v_lshlrev_b32_e32 v30, 16, v26
	v_and_b32_e32 v31, 0xffff0000, v26
	v_and_b32_e32 v29, 0xffff0000, v16
	v_lshlrev_b32_e32 v26, 16, v27
	v_and_b32_e32 v27, 0xffff0000, v27
	s_waitcnt vmcnt(0) lgkmcnt(0)
	v_pk_mul_f32 v[32:33], v[22:23], v[30:31]
	s_nop 0
	v_pk_fma_f32 v[32:33], v[0:1], v[28:29], v[32:33] neg_lo:[0,0,1] neg_hi:[0,0,1]
	v_pk_mul_f32 v[0:1], v[0:1], v[30:31]
	v_cvt_pk_bf16_f32 v16, v32, v33
	v_pk_fma_f32 v[0:1], v[22:23], v[28:29], v[0:1]
	v_lshlrev_b32_e32 v22, 16, v17
	v_and_b32_e32 v23, 0xffff0000, v17
	v_pk_mul_f32 v[28:29], v[24:25], v[26:27]
	v_cvt_pk_bf16_f32 v0, v0, v1
	v_pk_fma_f32 v[28:29], v[2:3], v[22:23], v[28:29] neg_lo:[0,0,1] neg_hi:[0,0,1]
	v_pk_mul_f32 v[2:3], v[2:3], v[26:27]
	v_cvt_pk_bf16_f32 v17, v28, v29
	v_pk_fma_f32 v[2:3], v[24:25], v[22:23], v[2:3]
	s_nop 0
	v_cvt_pk_bf16_f32 v1, v2, v3
	v_lshlrev_b64 v[2:3], 6, v[14:15]
	v_lshl_add_u64 v[2:3], v[8:9], 0, v[2:3]
	global_store_dwordx2 v[2:3], v[16:17], off
	global_store_dwordx2 v[2:3], v[0:1], off offset:32
	s_branch .LBB0_287

.LBB0_314:
	s_lshl_b32 s5, s22, 8
	s_add_i32 s5, s5, s55
	v_mbcnt_lo_u32_b32 v156, -1, 0
	v_mbcnt_hi_u32_b32 v156, -1, v156
	s_lshl_b32 s4, s4, 8
	v_and_or_b32 v150, v156, 15, s5
	v_ashrrev_i32_e32 v151, 31, v150
	v_or_b32_e32 v148, 16, v150
	v_lshl_add_u64 v[134:135], v[150:151], 3, s[10:11]
	v_ashrrev_i32_e32 v149, 31, v148
	v_or_b32_e32 v146, 32, v150
	global_load_dword v157, v[134:135], off
	v_lshl_add_u64 v[134:135], v[148:149], 3, s[10:11]
	v_ashrrev_i32_e32 v147, 31, v146
	v_or_b32_e32 v144, 48, v150
	global_load_dword v149, v[134:135], off
	v_lshl_add_u64 v[134:135], v[146:147], 3, s[10:11]
	v_ashrrev_i32_e32 v145, 31, v144
	v_add_u32_e32 v142, 0x80, v150
	global_load_dword v147, v[134:135], off
	v_lshl_add_u64 v[134:135], v[144:145], 3, s[10:11]
	v_ashrrev_i32_e32 v143, 31, v142
	v_add_u32_e32 v140, 0x90, v150
	global_load_dword v145, v[134:135], off
	v_lshl_add_u64 v[134:135], v[142:143], 3, s[10:11]
	v_ashrrev_i32_e32 v141, 31, v140
	v_add_u32_e32 v138, 0xa0, v150
	global_load_dword v143, v[134:135], off
	v_lshl_add_u64 v[134:135], v[140:141], 3, s[10:11]
	v_ashrrev_i32_e32 v139, 31, v138
	v_add_u32_e32 v136, 0xb0, v150
	global_load_dword v141, v[134:135], off
	v_lshl_add_u64 v[134:135], v[138:139], 3, s[10:11]
	v_ashrrev_i32_e32 v137, 31, v136
	global_load_dword v139, v[134:135], off
	v_lshl_add_u64 v[134:135], v[136:137], 3, s[10:11]
	global_load_dword v137, v[134:135], off
	v_ashrrev_i32_e32 v134, 1, v156
	v_mov_b64_e32 v[152:153], s[8:9]
	s_or_b32 s4, s4, s56
	v_and_b32_e32 v134, -8, v134
	v_add_u32_e32 v134, s4, v134
	v_mad_i64_i32 v[150:151], s[4:5], v150, s85, v[152:153]
	v_cmp_gt_i32_e32 vcc, s79, v134
	v_ashrrev_i32_e32 v135, 31, v134
	s_waitcnt vmcnt(0) lgkmcnt(0)
	v_mul_f32_e32 v152, 0x3e16c740, v157
	v_mov_b32_e32 v153, v152
	s_and_saveexec_b64 s[4:5], vcc
	s_cbranch_execz .LBB0_316
	v_mov_b32_e32 v156, v152
	v_mov_b32_e32 v157, v152
	v_pk_mul_f32 v[126:127], v[126:127], v[156:157]
	v_pk_mul_f32 v[124:125], v[124:125], v[152:153]
	v_pk_mul_f32 v[156:157], v[122:123], v[156:157]
	v_pk_mul_f32 v[122:123], v[120:121], v[152:153]
	v_cvt_pk_bf16_f32 v120, v124, v125
	v_cvt_pk_bf16_f32 v121, v126, v127
	v_cvt_pk_bf16_f32 v122, v122, v123
	v_cvt_pk_bf16_f32 v123, v156, v157
	v_lshl_add_u64 v[124:125], v[134:135], 1, v[150:151]
	global_store_dwordx4 v[124:125], v[120:123], off
.LBB0_316:
	s_or_b64 exec, exec, s[4:5]
	s_nop 0
	v_add_u32_e32 v120, 0x80, v134
	v_cmp_gt_i32_e64 s[4:5], s79, v120
	s_and_saveexec_b64 s[22:23], s[4:5]
	s_cbranch_execz .LBB0_318
	v_mov_b32_e32 v120, v152
	v_mov_b32_e32 v121, v152
	v_pk_mul_f32 v[118:119], v[118:119], v[120:121]
	v_pk_mul_f32 v[116:117], v[116:117], v[152:153]
	v_pk_mul_f32 v[120:121], v[114:115], v[120:121]
	v_pk_mul_f32 v[114:115], v[112:113], v[152:153]
	v_cvt_pk_bf16_f32 v112, v116, v117
	v_cvt_pk_bf16_f32 v113, v118, v119
	v_cvt_pk_bf16_f32 v114, v114, v115
	v_cvt_pk_bf16_f32 v115, v120, v121
	v_lshl_add_u64 v[116:117], v[134:135], 1, v[150:151]
	global_store_dwordx4 v[116:117], v[112:115], off offset:256
.LBB0_318:
	s_or_b64 exec, exec, s[22:23]
	s_nop 0
	v_mul_f32_e32 v114, 0x3e16c740, v149
	v_mov_b64_e32 v[112:113], s[8:9]
	v_mad_i64_i32 v[112:113], s[22:23], v148, s85, v[112:113]
	v_mov_b32_e32 v115, v114
	s_and_saveexec_b64 s[22:23], vcc
	s_mov_b32 s66, 0xc2800000
	s_cbranch_execz .LBB0_320
	v_mov_b32_e32 v116, v114
	v_mov_b32_e32 v117, v114
	v_pk_mul_f32 v[110:111], v[110:111], v[116:117]
	v_pk_mul_f32 v[108:109], v[108:109], v[114:115]
	v_pk_mul_f32 v[116:117], v[106:107], v[116:117]
	v_pk_mul_f32 v[106:107], v[104:105], v[114:115]
	v_cvt_pk_bf16_f32 v104, v108, v109
	v_cvt_pk_bf16_f32 v105, v110, v111
	v_cvt_pk_bf16_f32 v106, v106, v107
	v_cvt_pk_bf16_f32 v107, v116, v117
	v_lshl_add_u64 v[108:109], v[134:135], 1, v[112:113]
	global_store_dwordx4 v[108:109], v[104:107], off
.LBB0_320:
	s_or_b64 exec, exec, s[22:23]
	s_and_saveexec_b64 s[22:23], s[4:5]
	s_cbranch_execz .LBB0_322
	v_mov_b32_e32 v104, v114
	v_mov_b32_e32 v105, v114
	v_pk_mul_f32 v[102:103], v[102:103], v[104:105]
	v_pk_mul_f32 v[100:101], v[100:101], v[114:115]
	v_pk_mul_f32 v[104:105], v[98:99], v[104:105]
	v_pk_mul_f32 v[98:99], v[96:97], v[114:115]
	v_cvt_pk_bf16_f32 v96, v100, v101
	v_cvt_pk_bf16_f32 v97, v102, v103
	v_cvt_pk_bf16_f32 v98, v98, v99
	v_cvt_pk_bf16_f32 v99, v104, v105
	v_lshl_add_u64 v[100:101], v[134:135], 1, v[112:113]
	global_store_dwordx4 v[100:101], v[96:99], off offset:256
.LBB0_322:
	s_or_b64 exec, exec, s[22:23]
	s_nop 0
	v_mul_f32_e32 v98, 0x3e16c740, v147
	v_mov_b64_e32 v[96:97], s[8:9]
	v_mad_i64_i32 v[96:97], s[22:23], v146, s85, v[96:97]
	v_mov_b32_e32 v99, v98
	s_and_saveexec_b64 s[22:23], vcc
	s_cbranch_execz .LBB0_324
	v_mov_b32_e32 v100, v98
	v_mov_b32_e32 v101, v98
	v_pk_mul_f32 v[94:95], v[94:95], v[100:101]
	v_pk_mul_f32 v[92:93], v[92:93], v[98:99]
	v_pk_mul_f32 v[100:101], v[90:91], v[100:101]
	v_pk_mul_f32 v[90:91], v[88:89], v[98:99]
	v_cvt_pk_bf16_f32 v88, v92, v93
	v_cvt_pk_bf16_f32 v89, v94, v95
	v_cvt_pk_bf16_f32 v90, v90, v91
	v_cvt_pk_bf16_f32 v91, v100, v101
	v_lshl_add_u64 v[92:93], v[134:135], 1, v[96:97]
	global_store_dwordx4 v[92:93], v[88:91], off
.LBB0_324:
	s_or_b64 exec, exec, s[22:23]
	s_and_saveexec_b64 s[22:23], s[4:5]
	s_cbranch_execz .LBB0_326
	v_mov_b32_e32 v88, v98
	v_mov_b32_e32 v89, v98
	v_pk_mul_f32 v[86:87], v[86:87], v[88:89]
	v_pk_mul_f32 v[84:85], v[84:85], v[98:99]
	v_pk_mul_f32 v[88:89], v[82:83], v[88:89]
	v_pk_mul_f32 v[82:83], v[80:81], v[98:99]
	v_cvt_pk_bf16_f32 v80, v84, v85
	v_cvt_pk_bf16_f32 v81, v86, v87
	v_cvt_pk_bf16_f32 v82, v82, v83
	v_cvt_pk_bf16_f32 v83, v88, v89
	v_lshl_add_u64 v[84:85], v[134:135], 1, v[96:97]
	global_store_dwordx4 v[84:85], v[80:83], off offset:256
.LBB0_326:
	s_or_b64 exec, exec, s[22:23]
	s_nop 0
	v_mul_f32_e32 v82, 0x3e16c740, v145
	v_mov_b64_e32 v[80:81], s[8:9]
	v_mad_i64_i32 v[80:81], s[22:23], v144, s85, v[80:81]
	v_mov_b32_e32 v83, v82
	s_and_saveexec_b64 s[22:23], vcc
	s_cbranch_execz .LBB0_328
	v_mov_b32_e32 v84, v82
	v_mov_b32_e32 v85, v82
	v_pk_mul_f32 v[78:79], v[78:79], v[84:85]
	v_pk_mul_f32 v[76:77], v[76:77], v[82:83]
	v_pk_mul_f32 v[84:85], v[74:75], v[84:85]
	v_pk_mul_f32 v[74:75], v[72:73], v[82:83]
	v_cvt_pk_bf16_f32 v72, v76, v77
	v_cvt_pk_bf16_f32 v73, v78, v79
	v_cvt_pk_bf16_f32 v74, v74, v75
	v_cvt_pk_bf16_f32 v75, v84, v85
	v_lshl_add_u64 v[76:77], v[134:135], 1, v[80:81]
	global_store_dwordx4 v[76:77], v[72:75], off
.LBB0_328:
	s_or_b64 exec, exec, s[22:23]
	s_and_saveexec_b64 s[22:23], s[4:5]
	s_cbranch_execz .LBB0_330
	v_mov_b32_e32 v72, v82
	v_mov_b32_e32 v73, v82
	v_pk_mul_f32 v[70:71], v[70:71], v[72:73]
	v_pk_mul_f32 v[68:69], v[68:69], v[82:83]
	v_pk_mul_f32 v[72:73], v[66:67], v[72:73]
	v_pk_mul_f32 v[66:67], v[64:65], v[82:83]
	v_cvt_pk_bf16_f32 v64, v68, v69
	v_cvt_pk_bf16_f32 v65, v70, v71
	v_cvt_pk_bf16_f32 v66, v66, v67
	v_cvt_pk_bf16_f32 v67, v72, v73
	v_lshl_add_u64 v[68:69], v[134:135], 1, v[80:81]
	global_store_dwordx4 v[68:69], v[64:67], off offset:256
.LBB0_330:
	s_or_b64 exec, exec, s[22:23]
	s_nop 0
	v_mul_f32_e32 v66, 0x3e16c740, v143
	v_mov_b64_e32 v[64:65], s[8:9]
	v_mad_i64_i32 v[64:65], s[22:23], v142, s85, v[64:65]
	v_mov_b32_e32 v67, v66
	s_and_saveexec_b64 s[22:23], vcc
	s_cbranch_execz .LBB0_332
	v_mov_b32_e32 v68, v66
	v_mov_b32_e32 v69, v66
	v_pk_mul_f32 v[62:63], v[62:63], v[68:69]
	v_pk_mul_f32 v[60:61], v[60:61], v[66:67]
	v_pk_mul_f32 v[68:69], v[58:59], v[68:69]
	v_pk_mul_f32 v[58:59], v[56:57], v[66:67]
	v_cvt_pk_bf16_f32 v56, v60, v61
	v_cvt_pk_bf16_f32 v57, v62, v63
	v_cvt_pk_bf16_f32 v58, v58, v59
	v_cvt_pk_bf16_f32 v59, v68, v69
	v_lshl_add_u64 v[60:61], v[134:135], 1, v[64:65]
	global_store_dwordx4 v[60:61], v[56:59], off
.LBB0_332:
	s_or_b64 exec, exec, s[22:23]
	s_and_saveexec_b64 s[22:23], s[4:5]
	s_cbranch_execz .LBB0_334
	v_mov_b32_e32 v56, v66
	v_mov_b32_e32 v57, v66
	v_pk_mul_f32 v[54:55], v[54:55], v[56:57]
	v_pk_mul_f32 v[52:53], v[52:53], v[66:67]
	v_pk_mul_f32 v[56:57], v[50:51], v[56:57]
	v_pk_mul_f32 v[50:51], v[48:49], v[66:67]
	v_cvt_pk_bf16_f32 v48, v52, v53
	v_cvt_pk_bf16_f32 v49, v54, v55
	v_cvt_pk_bf16_f32 v50, v50, v51
	v_cvt_pk_bf16_f32 v51, v56, v57
	v_lshl_add_u64 v[52:53], v[134:135], 1, v[64:65]
	global_store_dwordx4 v[52:53], v[48:51], off offset:256
.LBB0_334:
	s_or_b64 exec, exec, s[22:23]
	s_nop 0
	v_mul_f32_e32 v50, 0x3e16c740, v141
	v_mov_b64_e32 v[48:49], s[8:9]
	v_mad_i64_i32 v[48:49], s[22:23], v140, s85, v[48:49]
	v_mov_b32_e32 v51, v50
	s_and_saveexec_b64 s[22:23], vcc
	s_cbranch_execz .LBB0_336
	v_mov_b32_e32 v52, v50
	v_mov_b32_e32 v53, v50
	v_pk_mul_f32 v[46:47], v[46:47], v[52:53]
	v_pk_mul_f32 v[44:45], v[44:45], v[50:51]
	v_pk_mul_f32 v[52:53], v[42:43], v[52:53]
	v_pk_mul_f32 v[42:43], v[40:41], v[50:51]
	v_cvt_pk_bf16_f32 v40, v44, v45
	v_cvt_pk_bf16_f32 v41, v46, v47
	v_cvt_pk_bf16_f32 v42, v42, v43
	v_cvt_pk_bf16_f32 v43, v52, v53
	v_lshl_add_u64 v[44:45], v[134:135], 1, v[48:49]
	global_store_dwordx4 v[44:45], v[40:43], off
.LBB0_336:
	s_or_b64 exec, exec, s[22:23]
	s_and_saveexec_b64 s[22:23], s[4:5]
	s_cbranch_execz .LBB0_338
	v_mov_b32_e32 v40, v50
	v_mov_b32_e32 v41, v50
	v_pk_mul_f32 v[38:39], v[38:39], v[40:41]
	v_pk_mul_f32 v[36:37], v[36:37], v[50:51]
	v_pk_mul_f32 v[40:41], v[34:35], v[40:41]
	v_pk_mul_f32 v[34:35], v[32:33], v[50:51]
	v_cvt_pk_bf16_f32 v32, v36, v37
	v_cvt_pk_bf16_f32 v33, v38, v39
	v_cvt_pk_bf16_f32 v34, v34, v35
	v_cvt_pk_bf16_f32 v35, v40, v41
	v_lshl_add_u64 v[36:37], v[134:135], 1, v[48:49]
	global_store_dwordx4 v[36:37], v[32:35], off offset:256
.LBB0_338:
	s_or_b64 exec, exec, s[22:23]
	s_nop 0
	v_mul_f32_e32 v34, 0x3e16c740, v139
	v_mov_b64_e32 v[32:33], s[8:9]
	v_mad_i64_i32 v[32:33], s[22:23], v138, s85, v[32:33]
	v_mov_b32_e32 v35, v34
	s_and_saveexec_b64 s[22:23], vcc
	s_cbranch_execz .LBB0_340
	v_mov_b32_e32 v36, v34
	v_mov_b32_e32 v37, v34
	v_pk_mul_f32 v[30:31], v[30:31], v[36:37]
	v_pk_mul_f32 v[28:29], v[28:29], v[34:35]
	v_pk_mul_f32 v[36:37], v[26:27], v[36:37]
	v_pk_mul_f32 v[26:27], v[24:25], v[34:35]
	v_cvt_pk_bf16_f32 v24, v28, v29
	v_cvt_pk_bf16_f32 v25, v30, v31
	v_cvt_pk_bf16_f32 v26, v26, v27
	v_cvt_pk_bf16_f32 v27, v36, v37
	v_lshl_add_u64 v[28:29], v[134:135], 1, v[32:33]
	global_store_dwordx4 v[28:29], v[24:27], off
.LBB0_340:
	s_or_b64 exec, exec, s[22:23]
	s_and_saveexec_b64 s[22:23], s[4:5]
	s_cbranch_execz .LBB0_342
	v_mov_b32_e32 v24, v34
	v_mov_b32_e32 v25, v34
	v_pk_mul_f32 v[22:23], v[22:23], v[24:25]
	v_pk_mul_f32 v[20:21], v[20:21], v[34:35]
	v_pk_mul_f32 v[24:25], v[18:19], v[24:25]
	v_pk_mul_f32 v[18:19], v[16:17], v[34:35]
	v_cvt_pk_bf16_f32 v16, v20, v21
	v_cvt_pk_bf16_f32 v17, v22, v23
	v_cvt_pk_bf16_f32 v18, v18, v19
	v_cvt_pk_bf16_f32 v19, v24, v25
	v_lshl_add_u64 v[20:21], v[134:135], 1, v[32:33]
	global_store_dwordx4 v[20:21], v[16:19], off offset:256
.LBB0_342:
	s_or_b64 exec, exec, s[22:23]
	s_nop 0
	v_mul_f32_e32 v18, 0x3e16c740, v137
	v_mov_b64_e32 v[16:17], s[8:9]
	v_mad_i64_i32 v[16:17], s[22:23], v136, s85, v[16:17]
	v_mov_b32_e32 v19, v18
	s_and_saveexec_b64 s[22:23], vcc
	s_cbranch_execz .LBB0_344
	v_mov_b32_e32 v20, v18
	v_mov_b32_e32 v21, v18
	v_pk_mul_f32 v[14:15], v[14:15], v[20:21]
	v_pk_mul_f32 v[12:13], v[12:13], v[18:19]
	v_pk_mul_f32 v[20:21], v[10:11], v[20:21]
	v_pk_mul_f32 v[10:11], v[8:9], v[18:19]
	v_cvt_pk_bf16_f32 v8, v12, v13
	v_cvt_pk_bf16_f32 v9, v14, v15
	v_cvt_pk_bf16_f32 v10, v10, v11
	v_cvt_pk_bf16_f32 v11, v20, v21
	v_lshl_add_u64 v[12:13], v[134:135], 1, v[16:17]
	global_store_dwordx4 v[12:13], v[8:11], off
.LBB0_344:
	s_or_b64 exec, exec, s[22:23]
	s_and_saveexec_b64 s[22:23], s[4:5]
	s_cbranch_execz .LBB0_346
	v_mov_b32_e32 v8, v18
	v_mov_b32_e32 v9, v18
	v_pk_mul_f32 v[6:7], v[6:7], v[8:9]
	v_pk_mul_f32 v[4:5], v[4:5], v[18:19]
	v_pk_mul_f32 v[8:9], v[2:3], v[8:9]
	v_pk_mul_f32 v[2:3], v[0:1], v[18:19]
	v_cvt_pk_bf16_f32 v0, v4, v5
	v_cvt_pk_bf16_f32 v1, v6, v7
	v_cvt_pk_bf16_f32 v2, v2, v3
	v_cvt_pk_bf16_f32 v3, v8, v9
	v_lshl_add_u64 v[4:5], v[134:135], 1, v[16:17]
	global_store_dwordx4 v[4:5], v[0:3], off offset:256

.LBB0_372:
	s_lshl_b32 s5, s22, 8
	s_add_i32 s5, s5, s55
	v_mbcnt_lo_u32_b32 v136, -1, 0
	v_mbcnt_hi_u32_b32 v136, -1, v136
	s_lshl_b32 s4, s4, 8
	v_and_or_b32 v166, v136, 15, s5
	v_ashrrev_i32_e32 v167, 31, v166
	v_or_b32_e32 v162, 16, v166
	v_lshl_add_u64 v[134:135], v[166:167], 3, s[10:11]
	v_ashrrev_i32_e32 v163, 31, v162
	v_or_b32_e32 v158, 32, v166
	global_load_dword v164, v[134:135], off
	v_lshl_add_u64 v[134:135], v[162:163], 3, s[10:11]
	v_ashrrev_i32_e32 v159, 31, v158
	v_or_b32_e32 v154, 48, v166
	global_load_dword v160, v[134:135], off
	v_lshl_add_u64 v[134:135], v[158:159], 3, s[10:11]
	v_ashrrev_i32_e32 v155, 31, v154
	v_add_u32_e32 v150, 0x80, v166
	global_load_dword v156, v[134:135], off
	v_lshl_add_u64 v[134:135], v[154:155], 3, s[10:11]
	v_ashrrev_i32_e32 v151, 31, v150
	v_add_u32_e32 v146, 0x90, v166
	global_load_dword v152, v[134:135], off
	v_lshl_add_u64 v[134:135], v[150:151], 3, s[10:11]
	v_ashrrev_i32_e32 v147, 31, v146
	v_add_u32_e32 v142, 0xa0, v166
	global_load_dword v148, v[134:135], off
	v_lshl_add_u64 v[134:135], v[146:147], 3, s[10:11]
	v_ashrrev_i32_e32 v143, 31, v142
	v_add_u32_e32 v138, 0xb0, v166
	global_load_dword v144, v[134:135], off
	v_lshl_add_u64 v[134:135], v[142:143], 3, s[10:11]
	v_ashrrev_i32_e32 v139, 31, v138
	global_load_dword v140, v[134:135], off
	v_lshl_add_u64 v[134:135], v[138:139], 3, s[10:11]
	global_load_dword v134, v[134:135], off
	v_ashrrev_i32_e32 v135, 1, v136
	v_and_b32_e32 v135, -8, v135
	s_or_b32 s4, s4, s56
	v_add_u32_e32 v136, s4, v135
	v_lshlrev_b64 v[166:167], 10, v[166:167]
	v_lshl_add_u64 v[166:167], s[8:9], 0, v[166:167]
	v_cmp_gt_i32_e32 vcc, s80, v136
	v_ashrrev_i32_e32 v137, 31, v136
	s_waitcnt vmcnt(0) lgkmcnt(0)
	v_mov_b32_e32 v165, v164
	s_and_saveexec_b64 s[4:5], vcc
	s_cbranch_execz .LBB0_374
	v_mov_b32_e32 v170, v164
	v_mov_b32_e32 v171, v164
	v_pk_mul_f32 v[126:127], v[126:127], v[170:171]
	v_pk_mul_f32 v[124:125], v[124:125], v[164:165]
	v_pk_mul_f32 v[170:171], v[122:123], v[170:171]
	v_pk_mul_f32 v[122:123], v[120:121], v[164:165]
	v_cvt_pk_bf16_f32 v120, v124, v125
	v_cvt_pk_bf16_f32 v121, v126, v127
	v_cvt_pk_bf16_f32 v122, v122, v123
	v_cvt_pk_bf16_f32 v123, v170, v171
	v_lshl_add_u64 v[124:125], v[136:137], 1, v[166:167]
	global_store_dwordx4 v[124:125], v[120:123], off
.LBB0_374:
	s_or_b64 exec, exec, s[4:5]
	s_nop 0
	v_add_u32_e32 v120, 0x80, v136
	v_cmp_gt_i32_e64 s[4:5], s80, v120
	s_and_saveexec_b64 s[22:23], s[4:5]
	s_cbranch_execz .LBB0_376
	v_mov_b32_e32 v120, v164
	v_mov_b32_e32 v121, v164
	v_pk_mul_f32 v[118:119], v[118:119], v[120:121]
	v_pk_mul_f32 v[116:117], v[116:117], v[164:165]
	v_pk_mul_f32 v[120:121], v[114:115], v[120:121]
	v_pk_mul_f32 v[114:115], v[112:113], v[164:165]
	v_cvt_pk_bf16_f32 v112, v116, v117
	v_cvt_pk_bf16_f32 v113, v118, v119
	v_cvt_pk_bf16_f32 v114, v114, v115
	v_cvt_pk_bf16_f32 v115, v120, v121
	v_lshl_add_u64 v[116:117], v[136:137], 1, v[166:167]
	global_store_dwordx4 v[116:117], v[112:115], off offset:256
.LBB0_376:
	s_or_b64 exec, exec, s[22:23]
	s_nop 0
	v_lshlrev_b64 v[112:113], 10, v[162:163]
	v_lshl_add_u64 v[112:113], s[8:9], 0, v[112:113]
	v_mov_b32_e32 v161, v160
	s_and_saveexec_b64 s[22:23], vcc
	s_mov_b32 s66, 0xc2800000
	s_cbranch_execz .LBB0_378
	v_mov_b32_e32 v114, v160
	v_mov_b32_e32 v115, v160
	v_pk_mul_f32 v[110:111], v[110:111], v[114:115]
	v_pk_mul_f32 v[108:109], v[108:109], v[160:161]
	v_pk_mul_f32 v[114:115], v[106:107], v[114:115]
	v_pk_mul_f32 v[106:107], v[104:105], v[160:161]
	v_cvt_pk_bf16_f32 v104, v108, v109
	v_cvt_pk_bf16_f32 v105, v110, v111
	v_cvt_pk_bf16_f32 v106, v106, v107
	v_cvt_pk_bf16_f32 v107, v114, v115
	v_lshl_add_u64 v[108:109], v[136:137], 1, v[112:113]
	global_store_dwordx4 v[108:109], v[104:107], off
.LBB0_378:
	s_or_b64 exec, exec, s[22:23]
	s_and_saveexec_b64 s[22:23], s[4:5]
	s_cbranch_execz .LBB0_380
	v_mov_b32_e32 v104, v160
	v_mov_b32_e32 v105, v160
	v_pk_mul_f32 v[102:103], v[102:103], v[104:105]
	v_pk_mul_f32 v[100:101], v[100:101], v[160:161]
	v_pk_mul_f32 v[104:105], v[98:99], v[104:105]
	v_pk_mul_f32 v[98:99], v[96:97], v[160:161]
	v_cvt_pk_bf16_f32 v96, v100, v101
	v_cvt_pk_bf16_f32 v97, v102, v103
	v_cvt_pk_bf16_f32 v98, v98, v99
	v_cvt_pk_bf16_f32 v99, v104, v105
	v_lshl_add_u64 v[100:101], v[136:137], 1, v[112:113]
	global_store_dwordx4 v[100:101], v[96:99], off offset:256
.LBB0_380:
	s_or_b64 exec, exec, s[22:23]
	s_nop 0
	v_lshlrev_b64 v[96:97], 10, v[158:159]
	v_lshl_add_u64 v[96:97], s[8:9], 0, v[96:97]
	v_mov_b32_e32 v157, v156
	s_and_saveexec_b64 s[22:23], vcc
	s_cbranch_execz .LBB0_382
	v_mov_b32_e32 v98, v156
	v_mov_b32_e32 v99, v156
	v_pk_mul_f32 v[94:95], v[94:95], v[98:99]
	v_pk_mul_f32 v[92:93], v[92:93], v[156:157]
	v_pk_mul_f32 v[98:99], v[90:91], v[98:99]
	v_pk_mul_f32 v[90:91], v[88:89], v[156:157]
	v_cvt_pk_bf16_f32 v88, v92, v93
	v_cvt_pk_bf16_f32 v89, v94, v95
	v_cvt_pk_bf16_f32 v90, v90, v91
	v_cvt_pk_bf16_f32 v91, v98, v99
	v_lshl_add_u64 v[92:93], v[136:137], 1, v[96:97]
	global_store_dwordx4 v[92:93], v[88:91], off
.LBB0_382:
	s_or_b64 exec, exec, s[22:23]
	s_and_saveexec_b64 s[22:23], s[4:5]
	s_cbranch_execz .LBB0_384
	v_mov_b32_e32 v88, v156
	v_mov_b32_e32 v89, v156
	v_pk_mul_f32 v[86:87], v[86:87], v[88:89]
	v_pk_mul_f32 v[84:85], v[84:85], v[156:157]
	v_pk_mul_f32 v[88:89], v[82:83], v[88:89]
	v_pk_mul_f32 v[82:83], v[80:81], v[156:157]
	v_cvt_pk_bf16_f32 v80, v84, v85
	v_cvt_pk_bf16_f32 v81, v86, v87
	v_cvt_pk_bf16_f32 v82, v82, v83
	v_cvt_pk_bf16_f32 v83, v88, v89
	v_lshl_add_u64 v[84:85], v[136:137], 1, v[96:97]
	global_store_dwordx4 v[84:85], v[80:83], off offset:256
.LBB0_384:
	s_or_b64 exec, exec, s[22:23]
	s_nop 0
	v_lshlrev_b64 v[80:81], 10, v[154:155]
	v_lshl_add_u64 v[80:81], s[8:9], 0, v[80:81]
	v_mov_b32_e32 v153, v152
	s_and_saveexec_b64 s[22:23], vcc
	s_cbranch_execz .LBB0_386
	v_mov_b32_e32 v82, v152
	v_mov_b32_e32 v83, v152
	v_pk_mul_f32 v[78:79], v[78:79], v[82:83]
	v_pk_mul_f32 v[76:77], v[76:77], v[152:153]
	v_pk_mul_f32 v[82:83], v[74:75], v[82:83]
	v_pk_mul_f32 v[74:75], v[72:73], v[152:153]
	v_cvt_pk_bf16_f32 v72, v76, v77
	v_cvt_pk_bf16_f32 v73, v78, v79
	v_cvt_pk_bf16_f32 v74, v74, v75
	v_cvt_pk_bf16_f32 v75, v82, v83
	v_lshl_add_u64 v[76:77], v[136:137], 1, v[80:81]
	global_store_dwordx4 v[76:77], v[72:75], off
.LBB0_386:
	s_or_b64 exec, exec, s[22:23]
	s_and_saveexec_b64 s[22:23], s[4:5]
	s_cbranch_execz .LBB0_388
	v_mov_b32_e32 v72, v152
	v_mov_b32_e32 v73, v152
	v_pk_mul_f32 v[70:71], v[70:71], v[72:73]
	v_pk_mul_f32 v[68:69], v[68:69], v[152:153]
	v_pk_mul_f32 v[72:73], v[66:67], v[72:73]
	v_pk_mul_f32 v[66:67], v[64:65], v[152:153]
	v_cvt_pk_bf16_f32 v64, v68, v69
	v_cvt_pk_bf16_f32 v65, v70, v71
	v_cvt_pk_bf16_f32 v66, v66, v67
	v_cvt_pk_bf16_f32 v67, v72, v73
	v_lshl_add_u64 v[68:69], v[136:137], 1, v[80:81]
	global_store_dwordx4 v[68:69], v[64:67], off offset:256
.LBB0_388:
	s_or_b64 exec, exec, s[22:23]
	s_nop 0
	v_lshlrev_b64 v[64:65], 10, v[150:151]
	v_lshl_add_u64 v[64:65], s[8:9], 0, v[64:65]
	v_mov_b32_e32 v149, v148
	s_and_saveexec_b64 s[22:23], vcc
	s_cbranch_execz .LBB0_390
	v_mov_b32_e32 v66, v148
	v_mov_b32_e32 v67, v148
	v_pk_mul_f32 v[62:63], v[62:63], v[66:67]
	v_pk_mul_f32 v[60:61], v[60:61], v[148:149]
	v_pk_mul_f32 v[66:67], v[58:59], v[66:67]
	v_pk_mul_f32 v[58:59], v[56:57], v[148:149]
	v_cvt_pk_bf16_f32 v56, v60, v61
	v_cvt_pk_bf16_f32 v57, v62, v63
	v_cvt_pk_bf16_f32 v58, v58, v59
	v_cvt_pk_bf16_f32 v59, v66, v67
	v_lshl_add_u64 v[60:61], v[136:137], 1, v[64:65]
	global_store_dwordx4 v[60:61], v[56:59], off
.LBB0_390:
	s_or_b64 exec, exec, s[22:23]
	s_and_saveexec_b64 s[22:23], s[4:5]
	s_cbranch_execz .LBB0_392
	v_mov_b32_e32 v56, v148
	v_mov_b32_e32 v57, v148
	v_pk_mul_f32 v[54:55], v[54:55], v[56:57]
	v_pk_mul_f32 v[52:53], v[52:53], v[148:149]
	v_pk_mul_f32 v[56:57], v[50:51], v[56:57]
	v_pk_mul_f32 v[50:51], v[48:49], v[148:149]
	v_cvt_pk_bf16_f32 v48, v52, v53
	v_cvt_pk_bf16_f32 v49, v54, v55
	v_cvt_pk_bf16_f32 v50, v50, v51
	v_cvt_pk_bf16_f32 v51, v56, v57
	v_lshl_add_u64 v[52:53], v[136:137], 1, v[64:65]
	global_store_dwordx4 v[52:53], v[48:51], off offset:256
.LBB0_392:
	s_or_b64 exec, exec, s[22:23]
	s_nop 0
	v_lshlrev_b64 v[48:49], 10, v[146:147]
	v_lshl_add_u64 v[48:49], s[8:9], 0, v[48:49]
	v_mov_b32_e32 v145, v144
	s_and_saveexec_b64 s[22:23], vcc
	s_cbranch_execz .LBB0_394
	v_mov_b32_e32 v50, v144
	v_mov_b32_e32 v51, v144
	v_pk_mul_f32 v[46:47], v[46:47], v[50:51]
	v_pk_mul_f32 v[44:45], v[44:45], v[144:145]
	v_pk_mul_f32 v[50:51], v[42:43], v[50:51]
	v_pk_mul_f32 v[42:43], v[40:41], v[144:145]
	v_cvt_pk_bf16_f32 v40, v44, v45
	v_cvt_pk_bf16_f32 v41, v46, v47
	v_cvt_pk_bf16_f32 v42, v42, v43
	v_cvt_pk_bf16_f32 v43, v50, v51
	v_lshl_add_u64 v[44:45], v[136:137], 1, v[48:49]
	global_store_dwordx4 v[44:45], v[40:43], off
.LBB0_394:
	s_or_b64 exec, exec, s[22:23]
	s_and_saveexec_b64 s[22:23], s[4:5]
	s_cbranch_execz .LBB0_396
	v_mov_b32_e32 v40, v144
	v_mov_b32_e32 v41, v144
	v_pk_mul_f32 v[38:39], v[38:39], v[40:41]
	v_pk_mul_f32 v[36:37], v[36:37], v[144:145]
	v_pk_mul_f32 v[40:41], v[34:35], v[40:41]
	v_pk_mul_f32 v[34:35], v[32:33], v[144:145]
	v_cvt_pk_bf16_f32 v32, v36, v37
	v_cvt_pk_bf16_f32 v33, v38, v39
	v_cvt_pk_bf16_f32 v34, v34, v35
	v_cvt_pk_bf16_f32 v35, v40, v41
	v_lshl_add_u64 v[36:37], v[136:137], 1, v[48:49]
	global_store_dwordx4 v[36:37], v[32:35], off offset:256
.LBB0_396:
	s_or_b64 exec, exec, s[22:23]
	s_nop 0
	v_lshlrev_b64 v[32:33], 10, v[142:143]
	v_lshl_add_u64 v[32:33], s[8:9], 0, v[32:33]
	v_mov_b32_e32 v141, v140
	s_and_saveexec_b64 s[22:23], vcc
	s_cbranch_execz .LBB0_398
	v_mov_b32_e32 v34, v140
	v_mov_b32_e32 v35, v140
	v_pk_mul_f32 v[30:31], v[30:31], v[34:35]
	v_pk_mul_f32 v[28:29], v[28:29], v[140:141]
	v_pk_mul_f32 v[34:35], v[26:27], v[34:35]
	v_pk_mul_f32 v[26:27], v[24:25], v[140:141]
	v_cvt_pk_bf16_f32 v24, v28, v29
	v_cvt_pk_bf16_f32 v25, v30, v31
	v_cvt_pk_bf16_f32 v26, v26, v27
	v_cvt_pk_bf16_f32 v27, v34, v35
	v_lshl_add_u64 v[28:29], v[136:137], 1, v[32:33]
	global_store_dwordx4 v[28:29], v[24:27], off
.LBB0_398:
	s_or_b64 exec, exec, s[22:23]
	s_and_saveexec_b64 s[22:23], s[4:5]
	s_cbranch_execz .LBB0_400
	v_mov_b32_e32 v24, v140
	v_mov_b32_e32 v25, v140
	v_pk_mul_f32 v[22:23], v[22:23], v[24:25]
	v_pk_mul_f32 v[20:21], v[20:21], v[140:141]
	v_pk_mul_f32 v[24:25], v[18:19], v[24:25]
	v_pk_mul_f32 v[18:19], v[16:17], v[140:141]
	v_cvt_pk_bf16_f32 v16, v20, v21
	v_cvt_pk_bf16_f32 v17, v22, v23
	v_cvt_pk_bf16_f32 v18, v18, v19
	v_cvt_pk_bf16_f32 v19, v24, v25
	v_lshl_add_u64 v[20:21], v[136:137], 1, v[32:33]
	global_store_dwordx4 v[20:21], v[16:19], off offset:256
.LBB0_400:
	s_or_b64 exec, exec, s[22:23]
	s_nop 0
	v_lshlrev_b64 v[16:17], 10, v[138:139]
	v_lshl_add_u64 v[16:17], s[8:9], 0, v[16:17]
	v_mov_b32_e32 v135, v134
	s_and_saveexec_b64 s[22:23], vcc
	s_cbranch_execz .LBB0_402
	v_mov_b32_e32 v18, v134
	v_mov_b32_e32 v19, v134
	v_pk_mul_f32 v[14:15], v[14:15], v[18:19]
	v_pk_mul_f32 v[12:13], v[12:13], v[134:135]
	v_pk_mul_f32 v[18:19], v[10:11], v[18:19]
	v_pk_mul_f32 v[10:11], v[8:9], v[134:135]
	v_cvt_pk_bf16_f32 v8, v12, v13
	v_cvt_pk_bf16_f32 v9, v14, v15
	v_cvt_pk_bf16_f32 v10, v10, v11
	v_cvt_pk_bf16_f32 v11, v18, v19
	v_lshl_add_u64 v[12:13], v[136:137], 1, v[16:17]
	global_store_dwordx4 v[12:13], v[8:11], off
.LBB0_402:
	s_or_b64 exec, exec, s[22:23]
	s_and_saveexec_b64 s[22:23], s[4:5]
	s_cbranch_execz .LBB0_404
	v_mov_b32_e32 v8, v134
	v_mov_b32_e32 v9, v134
	v_pk_mul_f32 v[6:7], v[6:7], v[8:9]
	v_pk_mul_f32 v[4:5], v[4:5], v[134:135]
	v_pk_mul_f32 v[8:9], v[2:3], v[8:9]
	v_pk_mul_f32 v[2:3], v[0:1], v[134:135]
	v_cvt_pk_bf16_f32 v0, v4, v5
	v_cvt_pk_bf16_f32 v1, v6, v7
	v_cvt_pk_bf16_f32 v2, v2, v3
	v_cvt_pk_bf16_f32 v3, v8, v9
	v_lshl_add_u64 v[4:5], v[136:137], 1, v[16:17]
	global_store_dwordx4 v[4:5], v[0:3], off offset:256

.LBB0_416:
	v_mov_b64_e32 v[12:13], s[36:37]
	global_load_dword v1, v[12:13], off offset:1024 sc1
	s_waitcnt lgkmcnt(0)
	global_load_dword v0, v[12:13], off offset:1280 sc1
	global_load_dword v2, v[12:13], off offset:1536 sc1
	s_or_b64 s[16:17], s[16:17], exec
	s_or_b64 s[14:15], s[14:15], exec
	s_waitcnt vmcnt(0) lgkmcnt(0)
	v_add_u32_e32 v3, v0, v1
	v_add_u32_e32 v4, v3, v2
	global_load_dword v3, v[12:13], off offset:1792 sc1
	s_waitcnt vmcnt(0) lgkmcnt(0)
	v_add_u32_e32 v5, v4, v3
	global_load_dword v4, v[12:13], off offset:2048 sc1
	s_waitcnt vmcnt(0) lgkmcnt(0)
	v_add_u32_e32 v6, v5, v4
	global_load_dword v5, v[12:13], off offset:2304 sc1
	s_waitcnt vmcnt(0) lgkmcnt(0)
	v_add_u32_e32 v7, v6, v5
	global_load_dword v6, v[12:13], off offset:2560 sc1
	s_waitcnt vmcnt(0) lgkmcnt(0)
	v_add_u32_e32 v8, v7, v6
	global_load_dword v7, v[12:13], off offset:2816 sc1
	s_waitcnt vmcnt(0) lgkmcnt(0)
	v_add_u32_e32 v9, v8, v7
	global_load_dword v8, v[12:13], off offset:3072 sc1
	s_waitcnt vmcnt(0) lgkmcnt(0)
	v_add_u32_e32 v10, v9, v8
	global_load_dword v9, v[12:13], off offset:3328 sc1
	s_waitcnt vmcnt(0) lgkmcnt(0)
	v_add_u32_e32 v11, v10, v9
	global_load_dword v10, v[12:13], off offset:3584 sc1
	s_waitcnt vmcnt(0) lgkmcnt(0)
	v_add_u32_e32 v14, v11, v10
	global_load_dword v11, v[12:13], off offset:3840 sc1
	v_mov_b64_e32 v[12:13], s[2:3]
	global_load_dword v12, v[12:13], off sc1
	s_waitcnt vmcnt(0) lgkmcnt(0)
	v_add_u32_e32 v14, v14, v11
	v_add_u32_e32 v16, v14, v12
	v_mov_b64_e32 v[14:15], s[4:5]
	global_load_dword v13, v[14:15], off sc1
	v_mov_b64_e32 v[14:15], s[6:7]
	global_load_dword v14, v[14:15], off sc1
	s_waitcnt vmcnt(0) lgkmcnt(0)
	v_add_u32_e32 v16, v16, v13
	v_add_u32_e32 v18, v16, v14
	v_mov_b64_e32 v[16:17], s[8:9]
	global_load_dword v15, v[16:17], off sc1
	s_waitcnt vmcnt(0) lgkmcnt(0)
	v_add_u32_e32 v16, v18, v15
	v_cmp_ne_u32_e32 vcc, s29, v16
	s_and_saveexec_b64 s[18:19], vcc
	s_cbranch_execz .LBB0_415
	s_and_b32 s22, s28, 0xff
	s_mov_b64 s[20:21], -1
	s_cmp_eq_u32 s22, 0
	s_mov_b64 s[24:25], -1
	s_mov_b64 s[22:23], -1
	s_sleep 1
	s_cbranch_scc1 .LBB0_419
	s_and_saveexec_b64 s[26:27], s[24:25]
	s_cbranch_execz .LBB0_414
	s_branch .LBB0_422

.LBB0_459:
	s_or_b64 exec, exec, s[8:9]
	v_lshl_add_u32 v76, v235, 2, s10
	ds_read_b128 v[66:69], v76
	ds_read_b128 v[70:73], v76 offset:32
	s_lshl_b32 s2, s45, 7
	v_or_b32_e32 v74, s44, v235
	s_add_u32 s2, s0, s2
	v_ashrrev_i32_e32 v75, 31, v74
	s_addc_u32 s3, s1, 0
	v_lshlrev_b32_e32 v232, 1, v253
	v_lshl_add_u64 v[74:75], s[6:7], 0, v[74:75]
	v_lshl_add_u64 v[64:65], s[2:3], 0, v[232:233]
	v_lshlrev_b64 v[74:75], 11, v[74:75]
	s_waitcnt lgkmcnt(1)
	v_mul_f32_e32 v48, v48, v66
	v_cvt_pk_bf16_f32 v48, v48, s0
	v_mul_f32_e32 v32, v32, v66
	v_lshl_add_u64 v[74:75], v[64:65], 0, v[74:75]
	v_or_b32_e32 v66, 1, v235
	v_cvt_pk_bf16_f32 v32, v32, s0
	global_store_short v[74:75], v48, off
	global_store_short v[74:75], v32, off offset:64
	v_or_b32_e32 v74, s44, v66
	v_ashrrev_i32_e32 v75, 31, v74
	v_lshl_add_u64 v[74:75], s[6:7], 0, v[74:75]
	v_mul_f32_e32 v32, v49, v67
	v_lshlrev_b64 v[74:75], 11, v[74:75]
	v_cvt_pk_bf16_f32 v48, v32, s0
	v_mul_f32_e32 v32, v33, v67
	v_cvt_pk_bf16_f32 v49, v32, s0
	v_lshl_add_u64 v[32:33], v[64:65], 0, v[74:75]
	v_or_b32_e32 v67, 2, v235
	global_store_short v[32:33], v48, off
	global_store_short v[32:33], v49, off offset:64
	v_or_b32_e32 v32, s44, v67
	v_ashrrev_i32_e32 v33, 31, v32
	v_lshl_add_u64 v[32:33], s[6:7], 0, v[32:33]
	v_lshlrev_b64 v[32:33], 11, v[32:33]
	v_mul_f32_e32 v48, v50, v68
	v_cvt_pk_bf16_f32 v48, v48, s0
	v_mul_f32_e32 v34, v34, v68
	v_lshl_add_u64 v[32:33], v[64:65], 0, v[32:33]
	v_or_b32_e32 v50, 3, v235
	v_cvt_pk_bf16_f32 v34, v34, s0
	global_store_short v[32:33], v48, off
	global_store_short v[32:33], v34, off offset:64
	v_or_b32_e32 v32, s44, v50
	v_ashrrev_i32_e32 v33, 31, v32
	v_lshl_add_u64 v[32:33], s[6:7], 0, v[32:33]
	v_lshlrev_b64 v[32:33], 11, v[32:33]
	v_mul_f32_e32 v34, v51, v69
	v_cvt_pk_bf16_f32 v34, v34, s0
	v_mul_f32_e32 v35, v35, v69
	v_lshl_add_u64 v[32:33], v[64:65], 0, v[32:33]
	v_or_b32_e32 v51, 8, v235
	v_cvt_pk_bf16_f32 v35, v35, s0
	global_store_short v[32:33], v34, off
	global_store_short v[32:33], v35, off offset:64
	v_or_b32_e32 v32, s44, v51
	v_ashrrev_i32_e32 v33, 31, v32
	v_lshl_add_u64 v[32:33], s[6:7], 0, v[32:33]
	v_lshlrev_b64 v[32:33], 11, v[32:33]
	s_waitcnt lgkmcnt(0)
	v_mul_f32_e32 v34, v52, v70
	v_cvt_pk_bf16_f32 v34, v34, s0
	v_mul_f32_e32 v35, v36, v70
	v_lshl_add_u64 v[32:33], v[64:65], 0, v[32:33]
	v_or_b32_e32 v52, 9, v235
	v_cvt_pk_bf16_f32 v35, v35, s0
	global_store_short v[32:33], v34, off
	global_store_short v[32:33], v35, off offset:64
	v_or_b32_e32 v32, s44, v52
	v_ashrrev_i32_e32 v33, 31, v32
	v_lshl_add_u64 v[32:33], s[6:7], 0, v[32:33]
	v_lshlrev_b64 v[32:33], 11, v[32:33]
	v_mul_f32_e32 v34, v53, v71
	v_cvt_pk_bf16_f32 v34, v34, s0
	v_mul_f32_e32 v35, v37, v71
	v_lshl_add_u64 v[32:33], v[64:65], 0, v[32:33]
	v_or_b32_e32 v53, 10, v235
	v_cvt_pk_bf16_f32 v35, v35, s0
	global_store_short v[32:33], v34, off
	global_store_short v[32:33], v35, off offset:64
	v_or_b32_e32 v32, s44, v53
	v_ashrrev_i32_e32 v33, 31, v32
	v_lshl_add_u64 v[32:33], s[6:7], 0, v[32:33]
	v_lshlrev_b64 v[32:33], 11, v[32:33]
	v_mul_f32_e32 v34, v54, v72
	v_cvt_pk_bf16_f32 v34, v34, s0
	v_mul_f32_e32 v35, v38, v72
	v_lshl_add_u64 v[32:33], v[64:65], 0, v[32:33]
	v_or_b32_e32 v54, 11, v235
	v_cvt_pk_bf16_f32 v35, v35, s0
	global_store_short v[32:33], v34, off
	global_store_short v[32:33], v35, off offset:64
	v_or_b32_e32 v32, s44, v54
	v_ashrrev_i32_e32 v33, 31, v32
	v_lshl_add_u64 v[32:33], s[6:7], 0, v[32:33]
	v_lshlrev_b64 v[32:33], 11, v[32:33]
	v_mul_f32_e32 v34, v55, v73
	v_cvt_pk_bf16_f32 v34, v34, s0
	v_mul_f32_e32 v35, v39, v73
	v_lshl_add_u64 v[32:33], v[64:65], 0, v[32:33]
	v_cvt_pk_bf16_f32 v35, v35, s0
	global_store_short v[32:33], v34, off
	global_store_short v[32:33], v35, off offset:64
	v_or_b32_e32 v55, 16, v235
	ds_read_b128 v[32:35], v76 offset:64
	ds_read_b128 v[36:39], v76 offset:96
	v_or_b32_e32 v48, s44, v55
	v_ashrrev_i32_e32 v49, 31, v48
	v_lshl_add_u64 v[48:49], s[6:7], 0, v[48:49]
	v_lshlrev_b64 v[48:49], 11, v[48:49]
	s_waitcnt lgkmcnt(0)
	v_mul_f32_e32 v56, v56, v32
	v_cvt_pk_bf16_f32 v56, v56, s0
	v_mul_f32_e32 v32, v40, v32
	v_lshl_add_u64 v[48:49], v[64:65], 0, v[48:49]
	v_cvt_pk_bf16_f32 v32, v32, s0
	global_store_short v[48:49], v56, off
	global_store_short v[48:49], v32, off offset:64
	v_or_b32_e32 v56, 17, v235
	v_or_b32_e32 v48, s44, v56
	v_ashrrev_i32_e32 v49, 31, v48
	v_lshl_add_u64 v[48:49], s[6:7], 0, v[48:49]
	v_mul_f32_e32 v32, v57, v33
	v_lshlrev_b64 v[48:49], 11, v[48:49]
	v_cvt_pk_bf16_f32 v40, v32, s0
	v_mul_f32_e32 v32, v41, v33
	v_cvt_pk_bf16_f32 v41, v32, s0
	v_lshl_add_u64 v[32:33], v[64:65], 0, v[48:49]
	v_or_b32_e32 v48, 18, v235
	global_store_short v[32:33], v40, off
	global_store_short v[32:33], v41, off offset:64
	v_or_b32_e32 v32, s44, v48
	v_ashrrev_i32_e32 v33, 31, v32
	v_lshl_add_u64 v[32:33], s[6:7], 0, v[32:33]
	v_lshlrev_b64 v[32:33], 11, v[32:33]
	v_mul_f32_e32 v40, v58, v34
	v_cvt_pk_bf16_f32 v40, v40, s0
	v_mul_f32_e32 v34, v42, v34
	v_lshl_add_u64 v[32:33], v[64:65], 0, v[32:33]
	v_or_b32_e32 v42, 19, v235
	v_cvt_pk_bf16_f32 v34, v34, s0
	global_store_short v[32:33], v40, off
	global_store_short v[32:33], v34, off offset:64
	v_or_b32_e32 v32, s44, v42
	v_ashrrev_i32_e32 v33, 31, v32
	v_lshl_add_u64 v[32:33], s[6:7], 0, v[32:33]
	v_lshlrev_b64 v[32:33], 11, v[32:33]
	v_mul_f32_e32 v34, v59, v35
	v_cvt_pk_bf16_f32 v34, v34, s0
	v_mul_f32_e32 v35, v43, v35
	v_lshl_add_u64 v[32:33], v[64:65], 0, v[32:33]
	v_or_b32_e32 v43, 24, v235
	v_cvt_pk_bf16_f32 v35, v35, s0
	global_store_short v[32:33], v34, off
	global_store_short v[32:33], v35, off offset:64
	v_or_b32_e32 v32, s44, v43
	v_ashrrev_i32_e32 v33, 31, v32
	v_lshl_add_u64 v[32:33], s[6:7], 0, v[32:33]
	v_lshlrev_b64 v[32:33], 11, v[32:33]
	v_mul_f32_e32 v34, v60, v36
	v_cvt_pk_bf16_f32 v34, v34, s0
	v_mul_f32_e32 v35, v44, v36
	v_lshl_add_u64 v[32:33], v[64:65], 0, v[32:33]
	v_or_b32_e32 v44, 25, v235
	v_cvt_pk_bf16_f32 v35, v35, s0
	global_store_short v[32:33], v34, off
	global_store_short v[32:33], v35, off offset:64
	v_or_b32_e32 v32, s44, v44
	v_ashrrev_i32_e32 v33, 31, v32
	v_lshl_add_u64 v[32:33], s[6:7], 0, v[32:33]
	v_lshlrev_b64 v[32:33], 11, v[32:33]
	v_mul_f32_e32 v34, v61, v37
	v_cvt_pk_bf16_f32 v34, v34, s0
	v_mul_f32_e32 v35, v45, v37
	v_lshl_add_u64 v[32:33], v[64:65], 0, v[32:33]
	v_or_b32_e32 v45, 26, v235
	v_cvt_pk_bf16_f32 v35, v35, s0
	global_store_short v[32:33], v34, off
	global_store_short v[32:33], v35, off offset:64
	v_or_b32_e32 v32, s44, v45
	v_ashrrev_i32_e32 v33, 31, v32
	v_lshl_add_u64 v[32:33], s[6:7], 0, v[32:33]
	v_lshlrev_b64 v[32:33], 11, v[32:33]
	v_mul_f32_e32 v34, v62, v38
	v_cvt_pk_bf16_f32 v34, v34, s0
	v_mul_f32_e32 v35, v46, v38
	v_lshl_add_u64 v[32:33], v[64:65], 0, v[32:33]
	v_or_b32_e32 v46, 27, v235
	v_cvt_pk_bf16_f32 v35, v35, s0
	global_store_short v[32:33], v34, off
	global_store_short v[32:33], v35, off offset:64
	v_or_b32_e32 v32, s44, v46
	v_ashrrev_i32_e32 v33, 31, v32
	v_lshl_add_u64 v[32:33], s[6:7], 0, v[32:33]
	v_lshlrev_b64 v[32:33], 11, v[32:33]
	v_mul_f32_e32 v34, v63, v39
	v_cvt_pk_bf16_f32 v34, v34, s0
	v_mul_f32_e32 v35, v47, v39
	v_lshl_add_u64 v[32:33], v[64:65], 0, v[32:33]
	v_cvt_pk_bf16_f32 v35, v35, s0
	global_store_short v[32:33], v34, off
	global_store_short v[32:33], v35, off offset:64
	ds_read_b128 v[32:35], v76 offset:128
	s_or_b32 s2, s44, 32
	v_or_b32_e32 v36, s2, v235
	v_ashrrev_i32_e32 v37, 31, v36
	v_lshl_add_u64 v[36:37], s[6:7], 0, v[36:37]
	v_lshlrev_b64 v[40:41], 11, v[36:37]
	ds_read_b128 v[36:39], v76 offset:160
	s_waitcnt lgkmcnt(0)
	v_mul_f32_e32 v16, v16, v32
	v_cvt_pk_bf16_f32 v16, v16, s0
	v_mul_f32_e32 v0, v0, v32
	v_lshl_add_u64 v[40:41], v[64:65], 0, v[40:41]
	v_cvt_pk_bf16_f32 v0, v0, s0
	global_store_short v[40:41], v16, off
	global_store_short v[40:41], v0, off offset:64
	v_or_b32_e32 v40, s2, v66
	v_ashrrev_i32_e32 v41, 31, v40
	v_lshl_add_u64 v[40:41], s[6:7], 0, v[40:41]
	v_mul_f32_e32 v0, v17, v33
	v_lshlrev_b64 v[40:41], 11, v[40:41]
	v_cvt_pk_bf16_f32 v16, v0, s0
	v_mul_f32_e32 v0, v1, v33
	v_cvt_pk_bf16_f32 v17, v0, s0
	v_lshl_add_u64 v[0:1], v[64:65], 0, v[40:41]
	global_store_short v[0:1], v16, off
	global_store_short v[0:1], v17, off offset:64
	v_or_b32_e32 v0, s2, v67
	v_ashrrev_i32_e32 v1, 31, v0
	v_lshl_add_u64 v[0:1], s[6:7], 0, v[0:1]
	v_lshlrev_b64 v[0:1], 11, v[0:1]
	v_mul_f32_e32 v16, v18, v34
	v_cvt_pk_bf16_f32 v16, v16, s0
	v_mul_f32_e32 v2, v2, v34
	v_lshl_add_u64 v[0:1], v[64:65], 0, v[0:1]
	v_cvt_pk_bf16_f32 v2, v2, s0
	global_store_short v[0:1], v16, off
	global_store_short v[0:1], v2, off offset:64
	v_or_b32_e32 v0, s2, v50
	v_ashrrev_i32_e32 v1, 31, v0
	v_lshl_add_u64 v[0:1], s[6:7], 0, v[0:1]
	v_lshlrev_b64 v[0:1], 11, v[0:1]
	v_mul_f32_e32 v2, v19, v35
	v_cvt_pk_bf16_f32 v2, v2, s0
	v_mul_f32_e32 v3, v3, v35
	v_lshl_add_u64 v[0:1], v[64:65], 0, v[0:1]
	v_cvt_pk_bf16_f32 v3, v3, s0
	global_store_short v[0:1], v2, off
	global_store_short v[0:1], v3, off offset:64
	v_or_b32_e32 v0, s2, v51
	v_ashrrev_i32_e32 v1, 31, v0
	v_lshl_add_u64 v[0:1], s[6:7], 0, v[0:1]
	v_lshlrev_b64 v[0:1], 11, v[0:1]
	v_mul_f32_e32 v2, v20, v36
	v_cvt_pk_bf16_f32 v2, v2, s0
	v_mul_f32_e32 v3, v4, v36
	v_lshl_add_u64 v[0:1], v[64:65], 0, v[0:1]
	v_cvt_pk_bf16_f32 v3, v3, s0
	global_store_short v[0:1], v2, off
	global_store_short v[0:1], v3, off offset:64
	v_or_b32_e32 v0, s2, v52
	v_ashrrev_i32_e32 v1, 31, v0
	v_lshl_add_u64 v[0:1], s[6:7], 0, v[0:1]
	v_lshlrev_b64 v[0:1], 11, v[0:1]
	v_mul_f32_e32 v2, v21, v37
	v_cvt_pk_bf16_f32 v2, v2, s0
	v_mul_f32_e32 v3, v5, v37
	v_lshl_add_u64 v[0:1], v[64:65], 0, v[0:1]
	v_cvt_pk_bf16_f32 v3, v3, s0
	global_store_short v[0:1], v2, off
	global_store_short v[0:1], v3, off offset:64
	v_or_b32_e32 v0, s2, v53
	v_ashrrev_i32_e32 v1, 31, v0
	v_lshl_add_u64 v[0:1], s[6:7], 0, v[0:1]
	v_lshlrev_b64 v[0:1], 11, v[0:1]
	v_mul_f32_e32 v2, v22, v38
	v_cvt_pk_bf16_f32 v2, v2, s0
	v_mul_f32_e32 v3, v6, v38
	v_lshl_add_u64 v[0:1], v[64:65], 0, v[0:1]
	v_cvt_pk_bf16_f32 v3, v3, s0
	global_store_short v[0:1], v2, off
	global_store_short v[0:1], v3, off offset:64
	v_or_b32_e32 v0, s2, v54
	v_ashrrev_i32_e32 v1, 31, v0
	v_lshl_add_u64 v[0:1], s[6:7], 0, v[0:1]
	v_lshlrev_b64 v[0:1], 11, v[0:1]
	v_mul_f32_e32 v2, v23, v39
	v_cvt_pk_bf16_f32 v2, v2, s0
	v_mul_f32_e32 v3, v7, v39
	v_lshl_add_u64 v[0:1], v[64:65], 0, v[0:1]
	v_cvt_pk_bf16_f32 v3, v3, s0
	global_store_short v[0:1], v2, off
	global_store_short v[0:1], v3, off offset:64
	ds_read_b128 v[0:3], v76 offset:192
	v_or_b32_e32 v4, s2, v55
	v_ashrrev_i32_e32 v5, 31, v4
	v_lshl_add_u64 v[4:5], s[6:7], 0, v[4:5]
	v_lshlrev_b64 v[16:17], 11, v[4:5]
	ds_read_b128 v[4:7], v76 offset:224
	s_waitcnt lgkmcnt(0)
	v_mul_f32_e32 v18, v24, v0
	v_cvt_pk_bf16_f32 v18, v18, s0
	v_mul_f32_e32 v0, v8, v0
	v_lshl_add_u64 v[16:17], v[64:65], 0, v[16:17]
	v_cvt_pk_bf16_f32 v0, v0, s0
	global_store_short v[16:17], v18, off
	global_store_short v[16:17], v0, off offset:64
	v_or_b32_e32 v16, s2, v56
	v_ashrrev_i32_e32 v17, 31, v16
	v_lshl_add_u64 v[16:17], s[6:7], 0, v[16:17]
	v_mul_f32_e32 v0, v25, v1
	v_lshlrev_b64 v[16:17], 11, v[16:17]
	v_cvt_pk_bf16_f32 v8, v0, s0
	v_mul_f32_e32 v0, v9, v1
	v_cvt_pk_bf16_f32 v9, v0, s0
	v_lshl_add_u64 v[0:1], v[64:65], 0, v[16:17]
	global_store_short v[0:1], v8, off
	global_store_short v[0:1], v9, off offset:64
	v_or_b32_e32 v0, s2, v48
	v_ashrrev_i32_e32 v1, 31, v0
	v_lshl_add_u64 v[0:1], s[6:7], 0, v[0:1]
	v_lshlrev_b64 v[0:1], 11, v[0:1]
	v_mul_f32_e32 v8, v26, v2
	v_cvt_pk_bf16_f32 v8, v8, s0
	v_mul_f32_e32 v2, v10, v2
	v_lshl_add_u64 v[0:1], v[64:65], 0, v[0:1]
	v_cvt_pk_bf16_f32 v2, v2, s0
	global_store_short v[0:1], v8, off
	global_store_short v[0:1], v2, off offset:64
	v_or_b32_e32 v0, s2, v42
	v_ashrrev_i32_e32 v1, 31, v0
	v_lshl_add_u64 v[0:1], s[6:7], 0, v[0:1]
	v_lshlrev_b64 v[0:1], 11, v[0:1]
	v_mul_f32_e32 v2, v27, v3
	v_cvt_pk_bf16_f32 v2, v2, s0
	v_mul_f32_e32 v3, v11, v3
	v_lshl_add_u64 v[0:1], v[64:65], 0, v[0:1]
	v_cvt_pk_bf16_f32 v3, v3, s0
	global_store_short v[0:1], v2, off
	global_store_short v[0:1], v3, off offset:64
	v_or_b32_e32 v0, s2, v43
	v_ashrrev_i32_e32 v1, 31, v0
	v_lshl_add_u64 v[0:1], s[6:7], 0, v[0:1]
	v_lshlrev_b64 v[0:1], 11, v[0:1]
	v_mul_f32_e32 v2, v28, v4
	v_cvt_pk_bf16_f32 v2, v2, s0
	v_mul_f32_e32 v3, v12, v4
	v_lshl_add_u64 v[0:1], v[64:65], 0, v[0:1]
	v_cvt_pk_bf16_f32 v3, v3, s0
	global_store_short v[0:1], v2, off
	global_store_short v[0:1], v3, off offset:64
	v_or_b32_e32 v0, s2, v44
	v_ashrrev_i32_e32 v1, 31, v0
	v_lshl_add_u64 v[0:1], s[6:7], 0, v[0:1]
	v_lshlrev_b64 v[0:1], 11, v[0:1]
	v_mul_f32_e32 v2, v29, v5
	v_cvt_pk_bf16_f32 v2, v2, s0
	v_mul_f32_e32 v3, v13, v5
	v_lshl_add_u64 v[0:1], v[64:65], 0, v[0:1]
	v_cvt_pk_bf16_f32 v3, v3, s0
	global_store_short v[0:1], v2, off
	global_store_short v[0:1], v3, off offset:64
	v_or_b32_e32 v0, s2, v45
	v_ashrrev_i32_e32 v1, 31, v0
	v_lshl_add_u64 v[0:1], s[6:7], 0, v[0:1]
	v_lshlrev_b64 v[0:1], 11, v[0:1]
	v_mul_f32_e32 v2, v30, v6
	v_cvt_pk_bf16_f32 v2, v2, s0
	v_mul_f32_e32 v3, v14, v6
	v_lshl_add_u64 v[0:1], v[64:65], 0, v[0:1]
	v_cvt_pk_bf16_f32 v3, v3, s0
	global_store_short v[0:1], v2, off
	global_store_short v[0:1], v3, off offset:64
	v_or_b32_e32 v0, s2, v46
	v_ashrrev_i32_e32 v1, 31, v0
	v_lshl_add_u64 v[0:1], s[6:7], 0, v[0:1]
	v_lshlrev_b64 v[0:1], 11, v[0:1]
	v_mul_f32_e32 v2, v31, v7
	s_add_i32 s43, s43, s64
	v_cvt_pk_bf16_f32 v2, v2, s0
	v_mul_f32_e32 v3, v15, v7
	v_lshl_add_u64 v[0:1], v[64:65], 0, v[0:1]
	s_cmp_gt_i32 s43, 31
	v_cvt_pk_bf16_f32 v3, v3, s0
	global_store_short v[0:1], v2, off
	global_store_short v[0:1], v3, off offset:64
	s_waitcnt lgkmcnt(0)
	s_barrier
	s_cbranch_scc1 .LBB0_494
.LBB0_460:
	s_add_i32 s2, s43, s42
	v_mbcnt_lo_u32_b32 v0, -1, 0
	v_mbcnt_hi_u32_b32 v0, -1, v0
	s_bfe_u32 s45, s2, 0x20004
	s_waitcnt vmcnt(0)
	v_add_u32_e32 v48, s88, v0
	s_ashr_i32 s12, s2, 6
	v_readfirstlane_b32 s8, v48
	s_lshl_b32 s2, s43, 9
	s_and_b32 s46, s8, 0xffffffc0
	s_and_b32 s2, s2, 0x1e00
	s_ashr_i32 s13, s12, 31
	v_and_b32_e32 v253, 31, v48
	s_lshl_b64 s[6:7], s[12:13], 13
	s_add_i32 s44, s46, s2
	s_mul_i32 s2, s45, 0xc0
	v_bfe_u32 v49, v48, 5, 1
	v_or_b32_e32 v0, s44, v253
	s_add_u32 s2, s36, s2
	s_addc_u32 s3, s37, 0
	v_lshlrev_b32_e32 v232, 4, v49
	v_ashrrev_i32_e32 v1, 31, v0
	v_lshl_add_u64 v[2:3], s[2:3], 0, v[232:233]
	v_lshl_add_u64 v[6:7], s[6:7], 0, v[0:1]
	v_and_b32_e32 v4, 32, v48
	v_mov_b32_e32 v5, v233
	v_mad_u64_u32 v[8:9], s[2:3], v6, s85, v[2:3]
	v_lshlrev_b32_e32 v6, 4, v0
	v_lshl_add_u64 v[4:5], s[4:5], 0, v[4:5]
	v_mad_i32_i24 v9, v7, s85, v9
	v_ashrrev_i32_e32 v7, 31, v6
	v_lshl_add_u64 v[6:7], v[6:7], 2, v[4:5]
	global_load_dwordx4 v[184:187], v[8:9], off
	global_load_dwordx4 v[188:191], v[8:9], off offset:32
	global_load_dwordx4 v[192:195], v[8:9], off offset:64
	global_load_dwordx4 v[196:199], v[8:9], off offset:96
	global_load_dwordx4 v[20:23], v[8:9], off offset:128
	global_load_dwordx4 v[16:19], v[8:9], off offset:160
	global_load_dwordx4 v[24:27], v[6:7], off
	global_load_dwordx4 v[36:39], v[6:7], off offset:16
	v_add_co_u32_e32 v6, vcc, s59, v6
	v_or_b32_e32 v0, 32, v0
	s_nop 0
	v_addc_co_u32_e32 v7, vcc, 0, v7, vcc
	v_ashrrev_i32_e32 v1, 31, v0
	global_load_dwordx4 v[28:31], v[6:7], off
	global_load_dwordx4 v[44:47], v[6:7], off offset:16
	v_lshl_add_u64 v[6:7], s[6:7], 0, v[0:1]
	v_mad_u64_u32 v[2:3], s[2:3], v6, s85, v[2:3]
	v_mad_i32_i24 v3, v7, s85, v3
	v_lshlrev_b32_e32 v0, 4, v0
	global_load_dwordx4 v[200:203], v[2:3], off
	global_load_dwordx4 v[204:207], v[2:3], off offset:32
	global_load_dwordx4 v[208:211], v[2:3], off offset:64
	global_load_dwordx4 v[212:215], v[2:3], off offset:96
	global_load_dwordx4 v[12:15], v[2:3], off offset:128
	global_load_dwordx4 v[8:11], v[2:3], off offset:160
	v_ashrrev_i32_e32 v1, 31, v0
	v_lshl_add_u64 v[4:5], v[0:1], 2, v[4:5]
	global_load_dwordx4 v[32:35], v[4:5], off
	global_load_dwordx4 v[0:3], v[4:5], off offset:16
	v_add_co_u32_e32 v4, vcc, s59, v4
	s_ashr_i32 s50, s8, 6
	s_nop 0
	v_addc_co_u32_e32 v5, vcc, 0, v5, vcc
	global_load_dwordx4 v[40:43], v[4:5], off
	s_nop 0
	global_load_dwordx4 v[4:7], v[4:5], off offset:16
	s_mul_hi_i32 s2, s50, 0x2aaaaaab
	s_lshr_b32 s3, s2, 31
	s_add_i32 s8, s2, s3
	s_mul_i32 s2, s8, 6
	s_sub_i32 s52, s50, s2
	s_lshl_b32 s47, s52, 10
	s_mul_i32 s2, s8, 0x1800
	s_add_i32 s47, s47, s2
	s_add_i32 s16, s47, 0
	s_cmp_gt_i32 s52, 3
	s_cselect_b64 s[2:3], -1, 0
	s_lshl_b32 s14, s8, 5
	s_ashr_i32 s15, s14, 31
	s_add_u32 s8, s6, s14
	v_mov_b32_e32 v247, 0x1c000
	v_mov_b64_e32 v[250:251], 0xff
	v_lshl_or_b32 v252, v253, 6, v232
	s_addc_u32 s9, s7, s15
	s_mov_b64 s[10:11], -1
	s_and_b64 vcc, exec, s[2:3]
	s_cbranch_vccz .LBB0_462
	s_lshl_b64 s[10:11], s[8:9], 6
	s_add_u32 s10, s40, s10
	s_addc_u32 s11, s41, s11
	s_lshl_b32 s17, s52, 5
	s_add_u32 s10, s10, s17
	s_addc_u32 s11, s11, 0
	s_add_u32 s10, s10, 0xffffff80
	s_addc_u32 s11, s11, -1
	s_mov_b32 s17, m0
	s_mov_b32 m0, s16
	s_nop 0
	global_load_lds_dwordx4 v252, s[10:11]
	s_mov_b32 m0, s17
	s_mov_b64 s[10:11], 0

.LBB0_496:
	s_or_b64 exec, exec, s[4:5]
	v_or_b32_e32 v40, s24, v121
	v_add_u32_e32 v44, s22, v232
	ds_read_b128 v[32:35], v44
	ds_read_b128 v[36:39], v44 offset:32
	v_ashrrev_i32_e32 v41, 31, v40
	v_lshl_add_u64 v[42:43], s[8:9], 0, v[40:41]
	v_lshlrev_b64 v[42:43], 11, v[42:43]
	v_lshl_add_u64 v[42:43], s[0:1], 0, v[42:43]
	s_lshl_b32 s40, s23, 1
	v_lshl_add_u64 v[42:43], v[42:43], 0, s[40:41]
	s_waitcnt lgkmcnt(0)
	v_mul_f32_e32 v0, v0, v32
	v_lshlrev_b32_e32 v232, 1, v120
	v_cvt_pk_bf16_f32 v0, v0, s0
	v_mul_f32_e32 v16, v16, v32
	v_lshl_add_u64 v[42:43], v[42:43], 0, v[232:233]
	v_cvt_pk_bf16_f32 v16, v16, s0
	global_store_short v[42:43], v0, off offset:512
	global_store_short v[42:43], v16, off offset:576
	v_or_b32_e32 v42, 1, v40
	v_ashrrev_i32_e32 v43, 31, v42
	v_lshl_add_u64 v[42:43], s[8:9], 0, v[42:43]
	v_lshlrev_b64 v[42:43], 11, v[42:43]
	v_lshl_add_u64 v[42:43], s[0:1], 0, v[42:43]
	v_mul_f32_e32 v0, v1, v33
	v_lshl_add_u64 v[42:43], v[42:43], 0, s[40:41]
	v_cvt_pk_bf16_f32 v16, v0, s0
	v_mul_f32_e32 v0, v17, v33
	v_cvt_pk_bf16_f32 v17, v0, s0
	v_lshl_add_u64 v[0:1], v[42:43], 0, v[232:233]
	global_store_short v[0:1], v16, off offset:512
	global_store_short v[0:1], v17, off offset:576
	v_or_b32_e32 v0, 2, v40
	v_ashrrev_i32_e32 v1, 31, v0
	v_lshl_add_u64 v[0:1], s[8:9], 0, v[0:1]
	v_lshlrev_b64 v[0:1], 11, v[0:1]
	v_lshl_add_u64 v[0:1], s[0:1], 0, v[0:1]
	v_lshl_add_u64 v[0:1], v[0:1], 0, s[40:41]
	v_mul_f32_e32 v2, v2, v34
	v_cvt_pk_bf16_f32 v2, v2, s0
	v_mul_f32_e32 v16, v18, v34
	v_lshl_add_u64 v[0:1], v[0:1], 0, v[232:233]
	v_cvt_pk_bf16_f32 v16, v16, s0
	global_store_short v[0:1], v2, off offset:512
	global_store_short v[0:1], v16, off offset:576
	v_or_b32_e32 v0, 3, v40
	v_ashrrev_i32_e32 v1, 31, v0
	v_lshl_add_u64 v[0:1], s[8:9], 0, v[0:1]
	v_lshlrev_b64 v[0:1], 11, v[0:1]
	v_lshl_add_u64 v[0:1], s[0:1], 0, v[0:1]
	v_lshl_add_u64 v[0:1], v[0:1], 0, s[40:41]
	v_mul_f32_e32 v2, v3, v35
	v_cvt_pk_bf16_f32 v2, v2, s0
	v_mul_f32_e32 v3, v19, v35
	v_lshl_add_u64 v[0:1], v[0:1], 0, v[232:233]
	v_cvt_pk_bf16_f32 v3, v3, s0
	global_store_short v[0:1], v2, off offset:512
	global_store_short v[0:1], v3, off offset:576
	v_or_b32_e32 v0, 8, v40
	v_ashrrev_i32_e32 v1, 31, v0
	v_lshl_add_u64 v[0:1], s[8:9], 0, v[0:1]
	v_lshlrev_b64 v[0:1], 11, v[0:1]
	v_lshl_add_u64 v[0:1], s[0:1], 0, v[0:1]
	v_lshl_add_u64 v[0:1], v[0:1], 0, s[40:41]
	v_mul_f32_e32 v2, v4, v36
	v_cvt_pk_bf16_f32 v2, v2, s0
	v_mul_f32_e32 v3, v20, v36
	v_lshl_add_u64 v[0:1], v[0:1], 0, v[232:233]
	v_cvt_pk_bf16_f32 v3, v3, s0
	global_store_short v[0:1], v2, off offset:512
	global_store_short v[0:1], v3, off offset:576
	v_or_b32_e32 v0, 9, v40
	v_ashrrev_i32_e32 v1, 31, v0
	v_lshl_add_u64 v[0:1], s[8:9], 0, v[0:1]
	v_lshlrev_b64 v[0:1], 11, v[0:1]
	v_lshl_add_u64 v[0:1], s[0:1], 0, v[0:1]
	v_lshl_add_u64 v[0:1], v[0:1], 0, s[40:41]
	v_mul_f32_e32 v2, v5, v37
	v_cvt_pk_bf16_f32 v2, v2, s0
	v_mul_f32_e32 v3, v21, v37
	v_lshl_add_u64 v[0:1], v[0:1], 0, v[232:233]
	v_cvt_pk_bf16_f32 v3, v3, s0
	global_store_short v[0:1], v2, off offset:512
	global_store_short v[0:1], v3, off offset:576
	v_or_b32_e32 v0, 10, v40
	v_ashrrev_i32_e32 v1, 31, v0
	v_lshl_add_u64 v[0:1], s[8:9], 0, v[0:1]
	v_lshlrev_b64 v[0:1], 11, v[0:1]
	v_lshl_add_u64 v[0:1], s[0:1], 0, v[0:1]
	v_lshl_add_u64 v[0:1], v[0:1], 0, s[40:41]
	v_mul_f32_e32 v2, v6, v38
	v_cvt_pk_bf16_f32 v2, v2, s0
	v_mul_f32_e32 v3, v22, v38
	v_lshl_add_u64 v[0:1], v[0:1], 0, v[232:233]
	v_cvt_pk_bf16_f32 v3, v3, s0
	global_store_short v[0:1], v2, off offset:512
	global_store_short v[0:1], v3, off offset:576
	v_or_b32_e32 v0, 11, v40
	v_ashrrev_i32_e32 v1, 31, v0
	v_lshl_add_u64 v[0:1], s[8:9], 0, v[0:1]
	v_lshlrev_b64 v[0:1], 11, v[0:1]
	v_lshl_add_u64 v[0:1], s[0:1], 0, v[0:1]
	v_lshl_add_u64 v[0:1], v[0:1], 0, s[40:41]
	v_mul_f32_e32 v2, v7, v39
	v_cvt_pk_bf16_f32 v2, v2, s0
	v_mul_f32_e32 v3, v23, v39
	v_lshl_add_u64 v[0:1], v[0:1], 0, v[232:233]
	v_cvt_pk_bf16_f32 v3, v3, s0
	global_store_short v[0:1], v2, off offset:512
	global_store_short v[0:1], v3, off offset:576
	v_or_b32_e32 v16, 16, v40
	ds_read_b128 v[0:3], v44 offset:64
	ds_read_b128 v[4:7], v44 offset:96
	v_ashrrev_i32_e32 v17, 31, v16
	v_lshl_add_u64 v[16:17], s[8:9], 0, v[16:17]
	v_lshlrev_b64 v[16:17], 11, v[16:17]
	v_lshl_add_u64 v[16:17], s[0:1], 0, v[16:17]
	v_lshl_add_u64 v[16:17], v[16:17], 0, s[40:41]
	s_waitcnt lgkmcnt(0)
	v_mul_f32_e32 v8, v8, v0
	v_cvt_pk_bf16_f32 v8, v8, s0
	v_mul_f32_e32 v0, v24, v0
	v_lshl_add_u64 v[16:17], v[16:17], 0, v[232:233]
	v_cvt_pk_bf16_f32 v0, v0, s0
	global_store_short v[16:17], v8, off offset:512
	global_store_short v[16:17], v0, off offset:576
	v_or_b32_e32 v16, 17, v40
	v_ashrrev_i32_e32 v17, 31, v16
	v_lshl_add_u64 v[16:17], s[8:9], 0, v[16:17]
	v_lshlrev_b64 v[16:17], 11, v[16:17]
	v_lshl_add_u64 v[16:17], s[0:1], 0, v[16:17]
	v_mul_f32_e32 v0, v9, v1
	v_lshl_add_u64 v[16:17], v[16:17], 0, s[40:41]
	v_cvt_pk_bf16_f32 v8, v0, s0
	v_mul_f32_e32 v0, v25, v1
	v_cvt_pk_bf16_f32 v9, v0, s0
	v_lshl_add_u64 v[0:1], v[16:17], 0, v[232:233]
	global_store_short v[0:1], v8, off offset:512
	global_store_short v[0:1], v9, off offset:576
	v_or_b32_e32 v0, 18, v40
	v_ashrrev_i32_e32 v1, 31, v0
	v_lshl_add_u64 v[0:1], s[8:9], 0, v[0:1]
	v_lshlrev_b64 v[0:1], 11, v[0:1]
	v_lshl_add_u64 v[0:1], s[0:1], 0, v[0:1]
	v_lshl_add_u64 v[0:1], v[0:1], 0, s[40:41]
	v_mul_f32_e32 v8, v10, v2
	v_cvt_pk_bf16_f32 v8, v8, s0
	v_mul_f32_e32 v2, v26, v2
	v_lshl_add_u64 v[0:1], v[0:1], 0, v[232:233]
	v_cvt_pk_bf16_f32 v2, v2, s0
	global_store_short v[0:1], v8, off offset:512
	global_store_short v[0:1], v2, off offset:576
	v_or_b32_e32 v0, 19, v40
	v_ashrrev_i32_e32 v1, 31, v0
	v_lshl_add_u64 v[0:1], s[8:9], 0, v[0:1]
	v_lshlrev_b64 v[0:1], 11, v[0:1]
	v_lshl_add_u64 v[0:1], s[0:1], 0, v[0:1]
	v_lshl_add_u64 v[0:1], v[0:1], 0, s[40:41]
	v_mul_f32_e32 v2, v11, v3
	v_cvt_pk_bf16_f32 v2, v2, s0
	v_mul_f32_e32 v3, v27, v3
	v_lshl_add_u64 v[0:1], v[0:1], 0, v[232:233]
	v_cvt_pk_bf16_f32 v3, v3, s0
	global_store_short v[0:1], v2, off offset:512
	global_store_short v[0:1], v3, off offset:576
	v_or_b32_e32 v0, 24, v40
	v_ashrrev_i32_e32 v1, 31, v0
	v_lshl_add_u64 v[0:1], s[8:9], 0, v[0:1]
	v_lshlrev_b64 v[0:1], 11, v[0:1]
	v_lshl_add_u64 v[0:1], s[0:1], 0, v[0:1]
	v_lshl_add_u64 v[0:1], v[0:1], 0, s[40:41]
	v_mul_f32_e32 v2, v12, v4
	v_cvt_pk_bf16_f32 v2, v2, s0
	v_mul_f32_e32 v3, v28, v4
	v_lshl_add_u64 v[0:1], v[0:1], 0, v[232:233]
	v_cvt_pk_bf16_f32 v3, v3, s0
	global_store_short v[0:1], v2, off offset:512
	global_store_short v[0:1], v3, off offset:576
	v_or_b32_e32 v0, 25, v40
	v_ashrrev_i32_e32 v1, 31, v0
	v_lshl_add_u64 v[0:1], s[8:9], 0, v[0:1]
	v_lshlrev_b64 v[0:1], 11, v[0:1]
	v_lshl_add_u64 v[0:1], s[0:1], 0, v[0:1]
	v_lshl_add_u64 v[0:1], v[0:1], 0, s[40:41]
	v_mul_f32_e32 v2, v13, v5
	v_cvt_pk_bf16_f32 v2, v2, s0
	v_mul_f32_e32 v3, v29, v5
	v_lshl_add_u64 v[0:1], v[0:1], 0, v[232:233]
	v_cvt_pk_bf16_f32 v3, v3, s0
	global_store_short v[0:1], v2, off offset:512
	global_store_short v[0:1], v3, off offset:576
	v_or_b32_e32 v0, 26, v40
	v_ashrrev_i32_e32 v1, 31, v0
	v_lshl_add_u64 v[0:1], s[8:9], 0, v[0:1]
	v_lshlrev_b64 v[0:1], 11, v[0:1]
	v_lshl_add_u64 v[0:1], s[0:1], 0, v[0:1]
	v_lshl_add_u64 v[0:1], v[0:1], 0, s[40:41]
	v_mul_f32_e32 v2, v14, v6
	v_cvt_pk_bf16_f32 v2, v2, s0
	v_mul_f32_e32 v3, v30, v6
	v_lshl_add_u64 v[0:1], v[0:1], 0, v[232:233]
	v_cvt_pk_bf16_f32 v3, v3, s0
	global_store_short v[0:1], v2, off offset:512
	global_store_short v[0:1], v3, off offset:576
	v_or_b32_e32 v0, 27, v40
	v_ashrrev_i32_e32 v1, 31, v0
	v_lshl_add_u64 v[0:1], s[8:9], 0, v[0:1]
	v_lshlrev_b64 v[0:1], 11, v[0:1]
	v_lshl_add_u64 v[0:1], s[0:1], 0, v[0:1]
	v_lshl_add_u64 v[0:1], v[0:1], 0, s[40:41]
	v_mul_f32_e32 v2, v15, v7
	s_add_i32 s21, s21, s64
	s_add_i32 s20, s20, s64
	s_add_i32 s18, s18, s19
	v_cvt_pk_bf16_f32 v2, v2, s0
	v_mul_f32_e32 v3, v31, v7
	v_lshl_add_u64 v[0:1], v[0:1], 0, v[232:233]
	s_cmp_gt_i32 s21, 63
	v_cvt_pk_bf16_f32 v3, v3, s0
	global_store_short v[0:1], v2, off offset:512
	global_store_short v[0:1], v3, off offset:576
	s_waitcnt lgkmcnt(0)
	s_barrier
	s_cbranch_scc1 .LBB0_598

.LBB0_499:
	global_load_dword v5, v[0:1], off
	v_add_u32_e32 v3, 0x200, v3
	s_movk_i32 s8, 0xff00
	v_cmp_lt_i32_e32 vcc, s8, v3
	v_lshl_add_u64 v[0:1], v[0:1], 0, s[82:83]
	s_or_b64 s[4:5], vcc, s[4:5]
	s_waitcnt vmcnt(0) lgkmcnt(0)
	ds_write_b32 v4, v5
	v_add_u32_e32 v4, 0x800, v4
	s_andn2_b64 exec, exec, s[4:5]
	s_cbranch_execnz .LBB0_499
.LBB0_500:
	s_or_b64 exec, exec, s[2:3]
	s_and_b32 s2, s10, 0x3fffffc0
	s_add_i32 s4, s21, s56
	s_lshl_b32 s2, s2, 2
	s_add_i32 s22, s2, 0
	s_ashr_i32 s2, s4, 7
	s_lshl_b32 s3, s21, 8
	s_ashr_i32 s10, s10, 1
	s_bfe_u32 s5, s4, 0x20005
	s_and_b32 s11, s3, 0x1f00
	s_ashr_i32 s3, s2, 31
	s_and_b32 s12, s10, 0xffffffe0
	s_and_b32 s25, s18, 0x1f00
	s_add_i32 s22, s22, 0x1c800
	s_lshl_b64 s[8:9], s[2:3], 13
	s_add_i32 s24, s12, s11
	s_lshl_b32 s23, s5, 6
	s_lshl_b32 s40, s5, 7
	s_lshl_b32 s2, s5, 2
	v_and_b32_e32 v120, 31, v2
	s_add_u32 s2, s16, s2
	v_or_b32_e32 v0, s24, v120
	s_addc_u32 s3, s17, 0
	v_ashrrev_i32_e32 v1, 31, v0
	v_mov_b64_e32 v[4:5], s[2:3]
	s_add_i32 s2, s11, 0xffffff80
	v_ashrrev_i32_e32 v10, 3, v2
	v_lshl_add_u64 v[0:1], s[8:9], 0, v[0:1]
	global_load_dword v3, v[4:5], off
	v_add_u32_e32 v4, s2, v10
	v_mov_b32_e32 v14, 0x1fff
	v_lshlrev_b64 v[0:1], 13, v[0:1]
	v_med3_i32 v4, v4, 0, v14
	v_lshl_add_u64 v[0:1], s[74:75], 0, v[0:1]
	v_or_b32_e32 v4, s8, v4
	v_mov_b32_e32 v5, s9
	s_and_b32 s2, s4, 64
	v_lshl_add_u64 v[0:1], v[0:1], 0, s[40:41]
	v_lshlrev_b64 v[6:7], 13, v[4:5]
	s_lshl_b32 s40, s2, 1
	v_lshlrev_b32_e32 v4, 4, v2
	s_sub_i32 s2, s11, 64
	v_lshl_add_u64 v[6:7], s[74:75], 0, v[6:7]
	v_and_b32_e32 v8, 0x70, v4
	v_add_u32_e32 v4, s2, v10
	v_lshl_add_u64 v[6:7], v[6:7], 0, s[40:41]
	v_mov_b32_e32 v9, v233
	v_med3_i32 v4, v4, 0, v14
	v_lshl_add_u64 v[6:7], v[6:7], 0, v[8:9]
	v_or_b32_e32 v4, s8, v4
	s_waitcnt vmcnt(0)
	global_load_dwordx4 v[64:67], v[6:7], off offset:1344
	global_load_dwordx4 v[68:71], v[6:7], off offset:1600
	v_lshlrev_b64 v[6:7], 13, v[4:5]
	v_lshl_add_u64 v[6:7], s[74:75], 0, v[6:7]
	v_add_u32_e32 v12, s11, v10
	v_lshl_add_u64 v[6:7], v[6:7], 0, s[40:41]
	v_med3_i32 v4, v12, 0, v14
	v_lshl_add_u64 v[6:7], v[6:7], 0, v[8:9]
	v_or_b32_e32 v4, s8, v4
	global_load_dwordx4 v[72:75], v[6:7], off offset:1344
	global_load_dwordx4 v[76:79], v[6:7], off offset:1600
	v_lshlrev_b64 v[6:7], 13, v[4:5]
	v_lshl_add_u64 v[6:7], s[74:75], 0, v[6:7]
	v_add_u32_e32 v4, 64, v12
	v_lshl_add_u64 v[6:7], v[6:7], 0, s[40:41]
	v_med3_i32 v4, v4, 0, v14
	v_lshl_add_u64 v[6:7], v[6:7], 0, v[8:9]
	v_or_b32_e32 v4, s8, v4
	global_load_dwordx4 v[80:83], v[6:7], off offset:1344
	global_load_dwordx4 v[84:87], v[6:7], off offset:1600
	v_lshlrev_b64 v[6:7], 13, v[4:5]
	v_lshl_add_u64 v[6:7], s[74:75], 0, v[6:7]
	v_bfe_u32 v4, v2, 5, 1
	v_lshl_add_u64 v[6:7], v[6:7], 0, s[40:41]
	v_lshlrev_b32_e32 v232, 4, v4
	v_lshl_add_u64 v[6:7], v[6:7], 0, v[8:9]
	v_lshl_add_u64 v[0:1], v[0:1], 0, v[232:233]
	global_load_dwordx4 v[88:91], v[6:7], off offset:1344
	global_load_dwordx4 v[92:95], v[6:7], off offset:1600
	global_load_dwordx4 v[96:99], v[0:1], off offset:832
	global_load_dwordx4 v[100:103], v[0:1], off offset:864
	global_load_dwordx4 v[104:107], v[0:1], off offset:896
	global_load_dwordx4 v[108:111], v[0:1], off offset:928
	v_lshrrev_b32_e32 v0, 2, v2
	v_lshlrev_b32_e32 v121, 2, v4
	v_and_or_b32 v13, v0, 3, v121
	v_add_u32_e32 v0, 0x80, v12
	v_med3_i32 v0, v0, 0, v14
	v_cmp_eq_u32_e64 s[2:3], 0, v4
	v_or_b32_e32 v4, s8, v0
	s_movk_i32 s11, 0x90
	v_lshlrev_b64 v[0:1], 13, v[4:5]
	v_add_u32_e32 v4, 0xc0, v12
	v_mul_lo_u32 v6, v10, s11
	v_med3_i32 v4, v4, 0, v14
	v_add_u32_e32 v6, 0, v6
	v_or_b32_e32 v4, s8, v4
	v_add_u32_e32 v123, v6, v8
	v_lshlrev_b64 v[6:7], 13, v[4:5]
	v_add_u32_e32 v4, 0x100, v12
	v_med3_i32 v4, v4, 0, v14
	v_lshl_add_u64 v[0:1], s[74:75], 0, v[0:1]
	v_or_b32_e32 v4, s8, v4
	v_lshl_add_u64 v[0:1], v[0:1], 0, s[40:41]
	v_lshlrev_b64 v[10:11], 13, v[4:5]
	v_add_u32_e32 v4, 0x140, v12
	v_lshl_add_u64 v[112:113], v[0:1], 0, v[8:9]
	v_lshl_add_u64 v[0:1], s[74:75], 0, v[6:7]
	v_med3_i32 v4, v4, 0, v14
	v_lshl_add_u64 v[0:1], v[0:1], 0, s[40:41]
	v_or_b32_e32 v4, s8, v4
	v_lshl_add_u64 v[114:115], v[0:1], 0, v[8:9]
	v_lshl_add_u64 v[0:1], s[74:75], 0, v[10:11]
	v_lshlrev_b64 v[4:5], 13, v[4:5]
	v_lshl_add_u64 v[0:1], v[0:1], 0, s[40:41]
	v_lshl_add_u64 v[116:117], v[0:1], 0, v[8:9]
	v_lshl_add_u64 v[0:1], s[74:75], 0, v[4:5]
	s_waitcnt vmcnt(0) lgkmcnt(0)
	v_mul_f32_e32 v136, 0x3fb8aa3b, v3
	v_lshlrev_b32_e32 v3, 2, v120
	v_lshl_add_u64 v[0:1], v[0:1], 0, s[40:41]
	s_lshl_b32 s5, s10, 2
	v_lshl_add_u64 v[118:119], v[0:1], 0, v[8:9]
	v_sub_u32_e32 v0, v232, v3
	s_and_b32 s5, s5, 0xffffff80
	v_subrev_u32_e32 v125, s5, v0
	v_sub_u32_e32 v0, v121, v120
	v_subrev_u32_e32 v126, s12, v0
	v_lshlrev_b32_e32 v0, 1, v2
	v_and_b32_e32 v1, 3, v2
	v_mul_u32_u24_e32 v12, 0x90, v13
	v_and_b32_e32 v0, 32, v0
	v_lshlrev_b32_e32 v1, 3, v1
	v_mov_b32_e32 v14, v233
	v_mov_b32_e32 v15, v233
	s_max_i32 s26, s24, 0x80
	s_min_i32 s27, s24, 0x1f60
	v_add_u32_e32 v122, s22, v3
	v_add3_u32 v128, v12, v0, v1
	v_mov_b32_e32 v0, v233
	v_mov_b32_e32 v1, v233
	v_mov_b32_e32 v2, v233
	v_mov_b32_e32 v3, v233
	v_mov_b32_e32 v4, v233
	v_mov_b32_e32 v5, v233
	v_mov_b32_e32 v6, v233
	v_mov_b32_e32 v7, v233
	v_mov_b32_e32 v8, v233
	v_mov_b32_e32 v10, v233
	v_mov_b32_e32 v11, v233
	v_mov_b32_e32 v12, v233
	v_mov_b32_e32 v13, v233
	v_mov_b64_e32 v[30:31], v[14:15]
	s_mov_b32 s4, 0
	v_cndmask_b32_e64 v124, 0, 1.0, s[2:3]
	s_addk_i32 s26, 0xff80
	s_addk_i32 s27, 0x9f
	s_sub_i32 s28, 0, s12
	v_or_b32_e32 v127, s25, v121
	v_mad_u32_u24 v129, v120, s11, v232
	s_mov_b64 s[10:11], -1
	v_mov_b64_e32 v[28:29], v[12:13]
	v_mov_b64_e32 v[26:27], v[10:11]
	v_mov_b64_e32 v[24:25], v[8:9]
	v_mov_b64_e32 v[22:23], v[6:7]
	v_mov_b64_e32 v[20:21], v[4:5]
	v_mov_b64_e32 v[18:19], v[2:3]
	v_mov_b64_e32 v[16:17], v[0:1]
	ds_write_b128 v123, v[64:67]
	ds_write_b128 v123, v[68:71] offset:36864
	ds_write_b128 v123, v[72:75] offset:9216
	ds_write_b128 v123, v[76:79] offset:46080
	ds_write_b128 v123, v[80:83] offset:18432
	ds_write_b128 v123, v[84:87] offset:55296
	ds_write_b128 v123, v[88:91] offset:27648
	ds_write_b128 v123, v[92:95] offset:64512
	s_waitcnt lgkmcnt(0)
	s_barrier
	s_branch .LBB0_502

.LBB0_502:
	s_xor_b64 s[12:13], s[10:11], -1
	s_and_b64 vcc, exec, s[12:13]
	s_cbranch_vccnz .LBB0_504
	s_waitcnt vmcnt(0)
	global_load_dwordx4 v[64:67], v[112:113], off offset:1344
	global_load_dwordx4 v[68:71], v[112:113], off offset:1600
	global_load_dwordx4 v[72:75], v[114:115], off offset:1344
	global_load_dwordx4 v[76:79], v[114:115], off offset:1600
	global_load_dwordx4 v[80:83], v[116:117], off offset:1344
	global_load_dwordx4 v[84:87], v[116:117], off offset:1600
	global_load_dwordx4 v[88:91], v[118:119], off offset:1344
	global_load_dwordx4 v[92:95], v[118:119], off offset:1600

.LBB0_599:
	s_or_b64 exec, exec, s[4:5]
	v_readlane_b32 s2, v255, 11
	s_lshl_b32 s2, s2, 6
	v_or_b32_e32 v42, s86, v124
	v_or_b32_e32 v40, s2, v42
	v_lshl_add_u32 v43, v124, 2, s88
	ds_read_b128 v[32:35], v43
	ds_read_b128 v[36:39], v43 offset:32
	v_ashrrev_i32_e32 v41, 31, v40
	v_lshl_add_u64 v[40:41], s[78:79], 0, v[40:41]
	v_lshlrev_b64 v[40:41], 11, v[40:41]
	v_readlane_b32 s4, v254, 32
	v_readlane_b32 s3, v255, 10
	v_lshl_add_u64 v[40:41], s[0:1], 0, v[40:41]
	v_readlane_b32 s5, v254, 33
	s_lshl_b32 s4, s3, 1
	s_waitcnt lgkmcnt(0)
	v_mul_f32_e32 v0, v0, v32
	v_lshl_add_u64 v[40:41], v[40:41], 0, s[4:5]
	v_lshlrev_b32_e32 v232, 1, v125
	v_cvt_pk_bf16_f32 v0, v0, s0
	v_mul_f32_e32 v16, v16, v32
	v_lshl_add_u64 v[40:41], v[40:41], 0, v[232:233]
	v_or_b32_e32 v32, 1, v124
	s_or_b32 s3, s2, s86
	v_cvt_pk_bf16_f32 v16, v16, s0
	global_store_short v[40:41], v0, off offset:1024
	global_store_short v[40:41], v16, off offset:1088
	v_or_b32_e32 v40, s3, v32
	v_ashrrev_i32_e32 v41, 31, v40
	v_lshl_add_u64 v[40:41], s[78:79], 0, v[40:41]
	v_lshlrev_b64 v[40:41], 11, v[40:41]
	v_lshl_add_u64 v[40:41], s[0:1], 0, v[40:41]
	v_mul_f32_e32 v0, v1, v33
	v_lshl_add_u64 v[40:41], v[40:41], 0, s[4:5]
	v_cvt_pk_bf16_f32 v16, v0, s0
	v_mul_f32_e32 v0, v17, v33
	v_cvt_pk_bf16_f32 v17, v0, s0
	v_lshl_add_u64 v[0:1], v[40:41], 0, v[232:233]
	v_or_b32_e32 v33, 2, v124
	global_store_short v[0:1], v16, off offset:1024
	global_store_short v[0:1], v17, off offset:1088
	v_or_b32_e32 v0, s3, v33
	v_ashrrev_i32_e32 v1, 31, v0
	v_lshl_add_u64 v[0:1], s[78:79], 0, v[0:1]
	v_lshlrev_b64 v[0:1], 11, v[0:1]
	v_lshl_add_u64 v[0:1], s[0:1], 0, v[0:1]
	v_lshl_add_u64 v[0:1], v[0:1], 0, s[4:5]
	v_mul_f32_e32 v2, v2, v34
	v_cvt_pk_bf16_f32 v2, v2, s0
	v_mul_f32_e32 v16, v18, v34
	v_lshl_add_u64 v[0:1], v[0:1], 0, v[232:233]
	v_or_b32_e32 v18, 3, v124
	v_cvt_pk_bf16_f32 v16, v16, s0
	global_store_short v[0:1], v2, off offset:1024
	global_store_short v[0:1], v16, off offset:1088
	v_or_b32_e32 v0, s3, v18
	v_ashrrev_i32_e32 v1, 31, v0
	v_lshl_add_u64 v[0:1], s[78:79], 0, v[0:1]
	v_lshlrev_b64 v[0:1], 11, v[0:1]
	v_lshl_add_u64 v[0:1], s[0:1], 0, v[0:1]
	v_lshl_add_u64 v[0:1], v[0:1], 0, s[4:5]
	v_mul_f32_e32 v2, v3, v35
	v_cvt_pk_bf16_f32 v2, v2, s0
	v_mul_f32_e32 v3, v19, v35
	v_lshl_add_u64 v[0:1], v[0:1], 0, v[232:233]
	v_or_b32_e32 v19, 8, v124
	v_cvt_pk_bf16_f32 v3, v3, s0
	global_store_short v[0:1], v2, off offset:1024
	global_store_short v[0:1], v3, off offset:1088
	v_or_b32_e32 v0, s3, v19
	v_ashrrev_i32_e32 v1, 31, v0
	v_lshl_add_u64 v[0:1], s[78:79], 0, v[0:1]
	v_lshlrev_b64 v[0:1], 11, v[0:1]
	v_lshl_add_u64 v[0:1], s[0:1], 0, v[0:1]
	v_lshl_add_u64 v[0:1], v[0:1], 0, s[4:5]
	v_mul_f32_e32 v2, v4, v36
	v_cvt_pk_bf16_f32 v2, v2, s0
	v_mul_f32_e32 v3, v20, v36
	v_lshl_add_u64 v[0:1], v[0:1], 0, v[232:233]
	v_or_b32_e32 v20, 9, v124
	v_cvt_pk_bf16_f32 v3, v3, s0
	global_store_short v[0:1], v2, off offset:1024
	global_store_short v[0:1], v3, off offset:1088
	v_or_b32_e32 v0, s3, v20
	v_ashrrev_i32_e32 v1, 31, v0
	v_lshl_add_u64 v[0:1], s[78:79], 0, v[0:1]
	v_lshlrev_b64 v[0:1], 11, v[0:1]
	v_lshl_add_u64 v[0:1], s[0:1], 0, v[0:1]
	v_lshl_add_u64 v[0:1], v[0:1], 0, s[4:5]
	v_mul_f32_e32 v2, v5, v37
	v_cvt_pk_bf16_f32 v2, v2, s0
	v_mul_f32_e32 v3, v21, v37
	v_lshl_add_u64 v[0:1], v[0:1], 0, v[232:233]
	v_or_b32_e32 v21, 10, v124
	v_cvt_pk_bf16_f32 v3, v3, s0
	global_store_short v[0:1], v2, off offset:1024
	global_store_short v[0:1], v3, off offset:1088
	v_or_b32_e32 v0, s3, v21
	v_ashrrev_i32_e32 v1, 31, v0
	v_lshl_add_u64 v[0:1], s[78:79], 0, v[0:1]
	v_lshlrev_b64 v[0:1], 11, v[0:1]
	v_lshl_add_u64 v[0:1], s[0:1], 0, v[0:1]
	v_lshl_add_u64 v[0:1], v[0:1], 0, s[4:5]
	v_mul_f32_e32 v2, v6, v38
	v_cvt_pk_bf16_f32 v2, v2, s0
	v_mul_f32_e32 v3, v22, v38
	v_lshl_add_u64 v[0:1], v[0:1], 0, v[232:233]
	v_or_b32_e32 v22, 11, v124
	v_cvt_pk_bf16_f32 v3, v3, s0
	global_store_short v[0:1], v2, off offset:1024
	global_store_short v[0:1], v3, off offset:1088
	v_or_b32_e32 v0, s3, v22
	v_ashrrev_i32_e32 v1, 31, v0
	v_lshl_add_u64 v[0:1], s[78:79], 0, v[0:1]
	v_lshlrev_b64 v[0:1], 11, v[0:1]
	v_lshl_add_u64 v[0:1], s[0:1], 0, v[0:1]
	v_lshl_add_u64 v[0:1], v[0:1], 0, s[4:5]
	v_mul_f32_e32 v2, v7, v39
	v_cvt_pk_bf16_f32 v2, v2, s0
	v_mul_f32_e32 v3, v23, v39
	v_lshl_add_u64 v[0:1], v[0:1], 0, v[232:233]
	v_cvt_pk_bf16_f32 v3, v3, s0
	global_store_short v[0:1], v2, off offset:1024
	global_store_short v[0:1], v3, off offset:1088
	s_or_b32 s2, s2, 64
	v_or_b32_e32 v4, s2, v42
	ds_read_b128 v[0:3], v43 offset:64
	v_ashrrev_i32_e32 v5, 31, v4
	v_lshl_add_u64 v[4:5], s[78:79], 0, v[4:5]
	v_lshlrev_b64 v[4:5], 11, v[4:5]
	v_lshl_add_u64 v[4:5], s[0:1], 0, v[4:5]
	v_lshl_add_u64 v[16:17], v[4:5], 0, s[4:5]
	ds_read_b128 v[4:7], v43 offset:96
	s_waitcnt lgkmcnt(0)
	v_mul_f32_e32 v8, v8, v0
	v_mul_f32_e32 v0, v24, v0
	v_cvt_pk_bf16_f32 v8, v8, s0
	v_cvt_pk_bf16_f32 v0, v0, s0
	v_lshl_add_u64 v[16:17], v[16:17], 0, v[232:233]
	global_store_short v[16:17], v8, off offset:1024
	global_store_short v[16:17], v0, off offset:1088
	v_and_or_b32 v0, v32, 5, s86
	v_or_b32_e32 v16, s2, v0
	v_ashrrev_i32_e32 v17, 31, v16
	v_lshl_add_u64 v[16:17], s[78:79], 0, v[16:17]
	v_lshlrev_b64 v[16:17], 11, v[16:17]
	v_lshl_add_u64 v[16:17], s[0:1], 0, v[16:17]
	v_mul_f32_e32 v0, v9, v1
	v_lshl_add_u64 v[16:17], v[16:17], 0, s[4:5]
	v_cvt_pk_bf16_f32 v8, v0, s0
	v_mul_f32_e32 v0, v25, v1
	v_cvt_pk_bf16_f32 v9, v0, s0
	v_lshl_add_u64 v[0:1], v[16:17], 0, v[232:233]
	global_store_short v[0:1], v8, off offset:1024
	global_store_short v[0:1], v9, off offset:1088
	v_and_or_b32 v0, v33, 6, s86
	v_or_b32_e32 v0, s2, v0
	v_ashrrev_i32_e32 v1, 31, v0
	v_lshl_add_u64 v[0:1], s[78:79], 0, v[0:1]
	v_lshlrev_b64 v[0:1], 11, v[0:1]
	v_lshl_add_u64 v[0:1], s[0:1], 0, v[0:1]
	v_lshl_add_u64 v[0:1], v[0:1], 0, s[4:5]
	v_mul_f32_e32 v8, v10, v2
	v_cvt_pk_bf16_f32 v8, v8, s0
	v_mul_f32_e32 v2, v26, v2
	v_lshl_add_u64 v[0:1], v[0:1], 0, v[232:233]
	v_cvt_pk_bf16_f32 v2, v2, s0
	global_store_short v[0:1], v8, off offset:1024
	global_store_short v[0:1], v2, off offset:1088
	v_or_b32_e32 v0, s86, v18
	v_or_b32_e32 v0, s2, v0
	v_ashrrev_i32_e32 v1, 31, v0
	v_lshl_add_u64 v[0:1], s[78:79], 0, v[0:1]
	v_lshlrev_b64 v[0:1], 11, v[0:1]
	v_lshl_add_u64 v[0:1], s[0:1], 0, v[0:1]
	v_lshl_add_u64 v[0:1], v[0:1], 0, s[4:5]
	v_mul_f32_e32 v2, v11, v3
	v_cvt_pk_bf16_f32 v2, v2, s0
	v_mul_f32_e32 v3, v27, v3
	v_lshl_add_u64 v[0:1], v[0:1], 0, v[232:233]
	v_cvt_pk_bf16_f32 v3, v3, s0
	global_store_short v[0:1], v2, off offset:1024
	global_store_short v[0:1], v3, off offset:1088
	v_and_or_b32 v0, v19, 12, s86
	v_or_b32_e32 v0, s2, v0
	v_ashrrev_i32_e32 v1, 31, v0
	v_lshl_add_u64 v[0:1], s[78:79], 0, v[0:1]
	v_lshlrev_b64 v[0:1], 11, v[0:1]
	v_lshl_add_u64 v[0:1], s[0:1], 0, v[0:1]
	v_lshl_add_u64 v[0:1], v[0:1], 0, s[4:5]
	v_mul_f32_e32 v2, v12, v4
	v_cvt_pk_bf16_f32 v2, v2, s0
	v_mul_f32_e32 v3, v28, v4
	v_lshl_add_u64 v[0:1], v[0:1], 0, v[232:233]
	v_cvt_pk_bf16_f32 v3, v3, s0
	global_store_short v[0:1], v2, off offset:1024
	global_store_short v[0:1], v3, off offset:1088
	v_and_or_b32 v0, v20, 13, s86
	v_or_b32_e32 v0, s2, v0
	v_ashrrev_i32_e32 v1, 31, v0
	v_lshl_add_u64 v[0:1], s[78:79], 0, v[0:1]
	v_readlane_b32 s9, v254, 37
	v_lshlrev_b64 v[0:1], 11, v[0:1]
	v_readlane_b32 s8, v254, 36
	v_readlane_b32 s10, v254, 38
	v_readlane_b32 s11, v254, 39
	v_readlane_b32 s12, v254, 40
	v_readlane_b32 s13, v254, 41
	v_readlane_b32 s14, v254, 42
	v_readlane_b32 s15, v254, 43
	v_readlane_b32 s16, v254, 44
	v_readlane_b32 s17, v254, 45
	v_readlane_b32 s18, v254, 46
	v_readlane_b32 s19, v254, 47
	v_lshl_add_u64 v[0:1], s[0:1], 0, v[0:1]
	s_mov_b32 s9, s5
	v_readlane_b32 s6, v254, 34
	v_readlane_b32 s7, v254, 35
	v_lshl_add_u64 v[0:1], v[0:1], 0, s[4:5]
	v_mul_f32_e32 v2, v13, v5
	v_writelane_b32 v254, s8, 32
	v_cvt_pk_bf16_f32 v2, v2, s0
	v_mul_f32_e32 v3, v29, v5
	v_lshl_add_u64 v[0:1], v[0:1], 0, v[232:233]
	v_writelane_b32 v254, s9, 33
	v_cvt_pk_bf16_f32 v3, v3, s0
	global_store_short v[0:1], v2, off offset:1024
	global_store_short v[0:1], v3, off offset:1088
	v_and_or_b32 v0, v21, 14, s86
	v_writelane_b32 v254, s10, 34
	v_or_b32_e32 v0, s2, v0
	v_writelane_b32 v254, s11, 35
	v_ashrrev_i32_e32 v1, 31, v0
	v_writelane_b32 v254, s12, 36
	v_lshl_add_u64 v[0:1], s[78:79], 0, v[0:1]
	v_writelane_b32 v254, s13, 37
	v_lshlrev_b64 v[0:1], 11, v[0:1]
	v_writelane_b32 v254, s14, 38
	v_lshl_add_u64 v[0:1], s[0:1], 0, v[0:1]
	v_writelane_b32 v254, s15, 39
	v_lshl_add_u64 v[0:1], v[0:1], 0, s[4:5]
	v_mul_f32_e32 v2, v14, v6
	v_writelane_b32 v254, s16, 40
	v_cvt_pk_bf16_f32 v2, v2, s0
	v_mul_f32_e32 v3, v30, v6
	v_lshl_add_u64 v[0:1], v[0:1], 0, v[232:233]
	v_writelane_b32 v254, s17, 41
	v_cvt_pk_bf16_f32 v3, v3, s0
	global_store_short v[0:1], v2, off offset:1024
	global_store_short v[0:1], v3, off offset:1088
	v_or_b32_e32 v0, s86, v22
	v_writelane_b32 v254, s18, 42
	v_or_b32_e32 v0, s2, v0
	v_writelane_b32 v254, s19, 43
	v_ashrrev_i32_e32 v1, 31, v0
	v_writelane_b32 v254, s20, 44
	v_readlane_b32 s64, v255, 7
	v_readlane_b32 s2, v255, 3
	v_lshl_add_u64 v[0:1], s[78:79], 0, v[0:1]
	v_writelane_b32 v254, s21, 45
	s_add_i32 s2, s2, s64
	v_lshlrev_b64 v[0:1], 11, v[0:1]
	v_writelane_b32 v254, s22, 46
	v_writelane_b32 v255, s2, 3
	v_lshl_add_u64 v[0:1], s[0:1], 0, v[0:1]
	v_writelane_b32 v254, s23, 47
	v_readlane_b32 s8, v255, 9
	v_readlane_b32 s2, v255, 6
	v_lshl_add_u64 v[0:1], v[0:1], 0, s[4:5]
	v_mul_f32_e32 v2, v15, v7
	s_add_i32 s77, s77, s64
	s_add_i32 s8, s8, s2
	v_readlane_b32 s86, v254, 50
	v_cvt_pk_bf16_f32 v2, v2, s0
	v_mul_f32_e32 v3, v31, v7
	v_lshl_add_u64 v[0:1], v[0:1], 0, v[232:233]
	s_cmp_gt_i32 s77, 63
	v_readlane_b32 s87, v254, 51
	v_readlane_b32 s88, v254, 52
	s_movk_i32 s76, 0xfc00
	s_movk_i32 s78, 0x400
	s_mov_b32 s84, 0xf800000
	s_movk_i32 s85, 0x300
	s_movk_i32 s79, 0x180
	s_movk_i32 s80, 0x200
	v_readlane_b32 s89, v254, 54
	s_movk_i32 s46, 0xe800
	s_mov_b32 s66, 0xc2800000
	v_readlane_b32 s56, v255, 8
	v_cvt_pk_bf16_f32 v3, v3, s0
	global_store_short v[0:1], v2, off offset:1024
	global_store_short v[0:1], v3, off offset:1088
	s_waitcnt lgkmcnt(0)
	s_barrier
	s_cbranch_scc1 .LBB0_692

.LBB0_602:
	global_load_dword v5, v[0:1], off
	v_add_u32_e32 v3, 0x200, v3
	s_movk_i32 s7, 0xffd0
	v_cmp_lt_i32_e32 vcc, s7, v3
	v_lshl_add_u64 v[0:1], v[0:1], 0, s[82:83]
	s_or_b64 s[4:5], vcc, s[4:5]
	s_waitcnt vmcnt(0) lgkmcnt(0)
	v_mul_f32_e32 v5, 0x3fb8aa3b, v5
	ds_write_b32 v4, v5
	v_add_u32_e32 v4, 0x800, v4
	s_andn2_b64 exec, exec, s[4:5]
	s_cbranch_execnz .LBB0_602
.LBB0_603:
	s_or_b64 exec, exec, s[2:3]
	s_add_i32 s2, s77, s56
	s_bfe_u32 s4, s2, 0x20005
	s_ashr_i32 s2, s2, 7
	s_ashr_i32 s3, s2, 31
	s_lshl_b64 s[78:79], s[2:3], 13
	s_lshl_b32 s2, s77, 2
	s_and_b32 s2, s2, 0x7c
	v_sub_u32_e64 v0, s2, 4 clamp
	v_ashrrev_i32_e32 v3, 3, v2
	v_lshl_add_u32 v14, v0, 6, v3
	v_min_i32_e32 v0, 0x1fff, v14
	v_ashrrev_i32_e32 v1, 31, v0
	v_lshl_add_u64 v[0:1], s[78:79], 0, v[0:1]
	v_readlane_b32 s40, v254, 32
	v_lshlrev_b64 v[0:1], 13, v[0:1]
	v_readlane_b32 s41, v254, 33
	s_lshl_b32 s40, s4, 7
	v_lshl_add_u64 v[0:1], s[74:75], 0, v[0:1]
	v_lshl_add_u64 v[4:5], v[0:1], 0, s[40:41]
	v_lshlrev_b32_e32 v0, 4, v2
	v_and_b32_e32 v0, 0x70, v0
	v_mov_b32_e32 v1, v233
	v_lshl_add_u64 v[4:5], v[4:5], 0, v[0:1]
	s_waitcnt vmcnt(0)
	global_load_dwordx4 v[48:51], v[4:5], off offset:2368
	global_load_dwordx4 v[52:55], v[4:5], off offset:2880
	v_min_i32_e32 v4, 0x1fbf, v14
	v_add_u32_e32 v4, 64, v4
	v_ashrrev_i32_e32 v5, 31, v4
	v_lshl_add_u64 v[4:5], s[78:79], 0, v[4:5]
	v_lshlrev_b64 v[4:5], 13, v[4:5]
	v_lshl_add_u64 v[4:5], s[74:75], 0, v[4:5]
	v_lshl_add_u64 v[4:5], v[4:5], 0, s[40:41]
	v_lshl_add_u64 v[4:5], v[4:5], 0, v[0:1]
	global_load_dwordx4 v[56:59], v[4:5], off offset:2368
	global_load_dwordx4 v[60:63], v[4:5], off offset:2880
	v_min_i32_e32 v4, 0x1f7f, v14
	v_add_u32_e32 v4, 0x80, v4
	v_ashrrev_i32_e32 v5, 31, v4
	v_lshl_add_u64 v[4:5], s[78:79], 0, v[4:5]
	v_lshlrev_b64 v[4:5], 13, v[4:5]
	v_lshl_add_u64 v[4:5], s[74:75], 0, v[4:5]
	v_lshl_add_u64 v[4:5], v[4:5], 0, s[40:41]
	v_lshl_add_u64 v[4:5], v[4:5], 0, v[0:1]
	s_waitcnt vmcnt(0)
	global_load_dwordx4 v[64:67], v[4:5], off offset:2368
	global_load_dwordx4 v[68:71], v[4:5], off offset:2880
	v_min_i32_e32 v4, 0x1f3f, v14
	v_add_u32_e32 v4, 0xc0, v4
	v_ashrrev_i32_e32 v5, 31, v4
	v_lshl_add_u64 v[4:5], s[78:79], 0, v[4:5]
	v_lshlrev_b64 v[4:5], 13, v[4:5]
	v_lshl_add_u64 v[4:5], s[74:75], 0, v[4:5]
	v_lshl_add_u64 v[4:5], v[4:5], 0, s[40:41]
	v_lshl_add_u64 v[4:5], v[4:5], 0, v[0:1]
	global_load_dwordx4 v[72:75], v[4:5], off offset:2368
	global_load_dwordx4 v[76:79], v[4:5], off offset:2880
	v_min_i32_e32 v4, 0x1eff, v14
	v_add_u32_e32 v4, 0x100, v4
	v_ashrrev_i32_e32 v5, 31, v4
	v_lshl_add_u64 v[4:5], s[78:79], 0, v[4:5]
	v_lshlrev_b64 v[4:5], 13, v[4:5]
	v_lshl_add_u64 v[4:5], s[74:75], 0, v[4:5]
	v_lshl_add_u64 v[4:5], v[4:5], 0, s[40:41]
	v_lshl_add_u64 v[4:5], v[4:5], 0, v[0:1]
	s_bfe_u32 s3, s8, 0x50002
	global_load_dwordx4 v[80:83], v[4:5], off offset:2368
	global_load_dwordx4 v[84:87], v[4:5], off offset:2880
	v_min_i32_e32 v4, 0x1ebf, v14
	s_lshl_b32 s63, s3, 8
	s_lshl_b32 s3, s3, 2
	v_add_u32_e32 v4, 0x140, v4
	s_min_u32 s3, s3, 4
	v_ashrrev_i32_e32 v5, 31, v4
	s_lshl_b32 s62, s3, 6
	s_and_b32 s3, s6, 0x3fffffc0
	v_lshl_add_u64 v[4:5], s[78:79], 0, v[4:5]
	s_lshl_b32 s3, s3, 2
	v_lshlrev_b64 v[4:5], 13, v[4:5]
	s_add_i32 s88, s3, 0
	s_ashr_i32 s3, s6, 7
	v_lshl_add_u64 v[4:5], s[74:75], 0, v[4:5]
	s_and_b32 s3, s3, -2
	v_lshl_add_u64 v[4:5], v[4:5], 0, s[40:41]
	s_add_i32 s3, s3, s2
	s_lshr_b32 s2, s6, 2
	v_lshl_add_u64 v[4:5], v[4:5], 0, v[0:1]
	s_and_b32 s86, s2, 48
	global_load_dwordx4 v[88:91], v[4:5], off offset:2368
	global_load_dwordx4 v[92:95], v[4:5], off offset:2880
	v_sub_u32_e64 v4, s86, 8 clamp
	v_and_b32_e32 v7, 15, v2
	v_readfirstlane_b32 s2, v4
	v_bfe_u32 v4, v2, 4, 1
	v_or_b32_e32 v126, s3, v4
	v_lshlrev_b32_e32 v4, 6, v126
	v_or3_b32 v4, v4, v7, s86
	v_ashrrev_i32_e32 v5, 31, v4
	v_lshl_add_u64 v[4:5], s[78:79], 0, v[4:5]
	v_lshlrev_b64 v[4:5], 13, v[4:5]
	v_bfe_u32 v6, v2, 5, 1
	v_lshl_add_u64 v[4:5], s[74:75], 0, v[4:5]
	v_lshl_add_u64 v[4:5], v[4:5], 0, s[40:41]
	v_lshlrev_b32_e32 v232, 4, v6
	v_lshl_add_u64 v[4:5], v[4:5], 0, v[232:233]
	global_load_dwordx4 v[96:99], v[4:5], off offset:1856
	global_load_dwordx4 v[100:103], v[4:5], off offset:1888
	global_load_dwordx4 v[104:107], v[4:5], off offset:1920
	global_load_dwordx4 v[108:111], v[4:5], off offset:1952
	s_min_u32 s64, s2, 32
	v_lshlrev_b32_e32 v124, 2, v6
	v_or_b32_e32 v16, s86, v7
	v_or_b32_e32 v17, s64, v124
	v_sub_u32_e32 v18, v17, v16
	v_sub_u32_e64 v5, v16, 8 clamp
	v_max_i32_e32 v18, -15, v18
	v_min_u32_e32 v32, 48, v5
	v_add_u32_e32 v18, 15, v18
	v_add_u32_e32 v33, 16, v32
	v_min_u32_e32 v135, 30, v18
	v_or_b32_e32 v18, 1, v17
	v_writelane_b32 v255, s8, 9
	v_cmp_ge_u32_e64 s[8:9], v18, v32
	v_cmp_lt_u32_e64 s[10:11], v18, v33
	v_sub_u32_e32 v18, v18, v16
	v_max_i32_e32 v18, -15, v18
	v_add_u32_e32 v18, 15, v18
	v_min_u32_e32 v136, 30, v18
	v_or_b32_e32 v18, 2, v17
	v_cmp_ge_u32_e64 s[12:13], v18, v32
	v_cmp_lt_u32_e64 s[14:15], v18, v33
	v_sub_u32_e32 v18, v18, v16
	v_max_i32_e32 v18, -15, v18
	v_add_u32_e32 v18, 15, v18
	v_min_u32_e32 v137, 30, v18
	v_or_b32_e32 v18, 3, v17
	v_cmp_ge_u32_e64 s[16:17], v18, v32
	v_cmp_lt_u32_e64 s[18:19], v18, v33
	v_sub_u32_e32 v18, v18, v16
	v_max_i32_e32 v18, -15, v18
	v_add_u32_e32 v18, 15, v18
	v_min_u32_e32 v138, 30, v18
	v_add_u32_e32 v18, 8, v17
	v_cmp_ge_u32_e64 s[20:21], v18, v32
	v_cmp_lt_u32_e64 s[22:23], v18, v33
	v_sub_u32_e32 v18, v18, v16
	v_max_i32_e32 v18, -15, v18
	v_add_u32_e32 v18, 15, v18
	v_min_u32_e32 v139, 30, v18
	v_add_u32_e32 v18, 9, v17
	v_cmp_ge_u32_e64 s[24:25], v18, v32
	v_cmp_lt_u32_e64 s[26:27], v18, v33
	v_sub_u32_e32 v18, v18, v16
	v_max_i32_e32 v18, -15, v18
	v_add_u32_e32 v18, 15, v18
	v_min_u32_e32 v140, 30, v18
	v_add_u32_e32 v18, 10, v17
	v_cmp_ge_u32_e64 s[28:29], v18, v32
	v_cmp_lt_u32_e64 s[30:31], v18, v33
	v_sub_u32_e32 v18, v18, v16
	v_max_i32_e32 v18, -15, v18
	v_add_u32_e32 v18, 15, v18
	v_min_u32_e32 v141, 30, v18
	v_add_u32_e32 v18, 11, v17
	v_cmp_ge_u32_e64 s[34:35], v18, v32
	v_cmp_lt_u32_e64 s[36:37], v18, v33
	v_sub_u32_e32 v18, v18, v16
	v_max_i32_e32 v18, -15, v18
	s_movk_i32 s65, 0x90
	v_add_u32_e32 v18, 15, v18
	s_lshl_b32 s2, s4, 6
	v_mul_lo_u32 v3, v3, s65
	v_min_u32_e32 v142, 30, v18
	v_add_u32_e32 v18, 16, v17
	v_writelane_b32 v255, s2, 10
	v_add_u32_e32 v7, 0, v3
	s_add_i32 s2, 0, 0x12000
	v_cmp_ge_u32_e64 s[38:39], v18, v32
	v_sub_u32_e32 v18, v18, v16
	v_add_u32_e32 v127, v7, v0
	v_add_u32_e32 v7, s2, v3
	v_max_i32_e32 v18, -15, v18
	v_add_u32_e32 v128, v7, v0
	v_add_u32_e32 v7, s89, v3
	v_readlane_b32 s2, v254, 10
	v_add_u32_e32 v18, 15, v18
	v_readlane_b32 s42, v254, 34
	v_readlane_b32 s43, v254, 35
	v_readlane_b32 s44, v254, 36
	v_readlane_b32 s45, v254, 37
	v_add_u32_e32 v129, v7, v0
	v_add_u32_e32 v7, s2, v3
	v_readlane_b32 s2, v254, 11
	v_min_u32_e32 v143, 30, v18
	v_add_u32_e32 v18, 17, v17
	v_max_i32_e32 v4, 4, v126
	v_add_u32_e32 v3, s2, v3
	s_max_i32 s2, s3, 4
	v_cmp_ge_u32_e64 s[42:43], v18, v32
	v_cmp_lt_u32_e64 s[44:45], v18, v33
	v_sub_u32_e32 v18, v18, v16
	v_add_u32_e32 v4, -4, v4
	s_add_i32 s2, s2, -4
	v_max_i32_e32 v18, -15, v18
	v_min_u32_e32 v133, 0x78, v4
	s_min_u32 s89, s2, 0x78
	s_max_i32 s2, s3, 3
	v_min_i32_e32 v4, 0x1e7f, v14
	v_add_u32_e32 v18, 15, v18
	v_readlane_b32 s46, v254, 38
	v_readlane_b32 s47, v254, 39
	v_readlane_b32 s48, v254, 40
	v_readlane_b32 s49, v254, 41
	s_add_i32 s2, s2, -3
	v_add_u32_e32 v4, 0x180, v4
	v_min_u32_e32 v144, 30, v18
	v_add_u32_e32 v18, 18, v17
	v_writelane_b32 v255, s3, 11
	s_min_u32 s72, s2, 0x78
	v_cmp_eq_u32_e64 s[2:3], 0, v6
	v_ashrrev_i32_e32 v5, 31, v4
	v_min_i32_e32 v6, 0x1e3f, v14
	v_cmp_ge_u32_e64 s[46:47], v18, v32
	v_cmp_lt_u32_e64 s[48:49], v18, v33
	v_sub_u32_e32 v18, v18, v16
	v_lshl_add_u64 v[4:5], s[78:79], 0, v[4:5]
	v_add_u32_e32 v6, 0x1c0, v6
	v_max_i32_e32 v18, -15, v18
	v_add_u32_e32 v131, v7, v0
	v_lshlrev_b64 v[4:5], 13, v[4:5]
	v_ashrrev_i32_e32 v7, 31, v6
	v_min_i32_e32 v8, 0x1dff, v14
	s_mov_b64 s[68:69], s[40:41]
	v_add_u32_e32 v18, 15, v18
	v_readlane_b32 s50, v254, 42
	v_readlane_b32 s51, v254, 43
	v_readlane_b32 s52, v254, 44
	v_readlane_b32 s53, v254, 45
	v_and_b32_e32 v125, 31, v2
	s_add_i32 s88, s88, 0x1c800
	v_lshl_add_u64 v[6:7], s[78:79], 0, v[6:7]
	v_add_u32_e32 v8, 0x200, v8
	v_min_u32_e32 v145, 30, v18
	v_add_u32_e32 v18, 19, v17
	v_lshl_add_u64 v[4:5], s[74:75], 0, v[4:5]
	s_mov_b32 s81, s69
	v_readlane_b32 s54, v254, 46
	v_readlane_b32 s55, v254, 47
	v_lshl_add_u32 v130, v125, 2, s88
	v_lshlrev_b64 v[6:7], 13, v[6:7]
	v_ashrrev_i32_e32 v9, 31, v8
	v_min_i32_e32 v10, 0x1dbf, v14
	v_cmp_ge_u32_e64 s[50:51], v18, v32
	v_cmp_lt_u32_e64 s[52:53], v18, v33
	v_sub_u32_e32 v18, v18, v16
	v_lshl_add_u64 v[4:5], v[4:5], 0, s[68:69]
	v_writelane_b32 v254, s80, 32
	v_lshl_add_u64 v[8:9], s[78:79], 0, v[8:9]
	v_add_u32_e32 v10, 0x240, v10
	v_max_i32_e32 v18, -15, v18
	v_lshl_add_u64 v[112:113], v[4:5], 0, v[0:1]
	v_lshl_add_u64 v[4:5], s[74:75], 0, v[6:7]
	v_writelane_b32 v254, s81, 33
	v_lshlrev_b64 v[8:9], 13, v[8:9]
	v_ashrrev_i32_e32 v11, 31, v10
	v_min_i32_e32 v12, 0x1d7f, v14
	v_add_u32_e32 v18, 15, v18
	v_lshl_add_u64 v[4:5], v[4:5], 0, s[68:69]
	v_writelane_b32 v254, s82, 34
	v_lshl_add_u64 v[10:11], s[78:79], 0, v[10:11]
	v_add_u32_e32 v12, 0x280, v12
	v_min_u32_e32 v146, 30, v18
	v_add_u32_e32 v18, 24, v17
	v_lshl_add_u64 v[114:115], v[4:5], 0, v[0:1]
	v_lshl_add_u64 v[4:5], s[74:75], 0, v[8:9]
	v_writelane_b32 v254, s83, 35
	v_lshlrev_b64 v[10:11], 13, v[10:11]
	v_ashrrev_i32_e32 v13, 31, v12
	v_min_i32_e32 v14, 0x1d3f, v14
	v_cmp_ge_u32_e64 s[54:55], v18, v32
	v_cmp_lt_u32_e64 s[56:57], v18, v33
	v_sub_u32_e32 v18, v18, v16
	v_lshl_add_u64 v[4:5], v[4:5], 0, s[68:69]
	v_writelane_b32 v254, s84, 36
	v_add_u32_e32 v132, v3, v0
	v_lshrrev_b32_e32 v3, 2, v2
	v_lshl_add_u64 v[12:13], s[78:79], 0, v[12:13]
	v_add_u32_e32 v14, 0x2c0, v14
	v_max_i32_e32 v18, -15, v18
	v_lshl_add_u64 v[116:117], v[4:5], 0, v[0:1]
	v_lshl_add_u64 v[4:5], s[74:75], 0, v[10:11]
	v_writelane_b32 v254, s85, 37
	v_and_or_b32 v3, v3, 3, v124
	v_lshlrev_b64 v[12:13], 13, v[12:13]
	v_ashrrev_i32_e32 v15, 31, v14
	v_add_u32_e32 v18, 15, v18
	v_lshlrev_b32_e32 v19, 1, v2
	v_lshl_add_u64 v[4:5], v[4:5], 0, s[68:69]
	v_writelane_b32 v254, s86, 38
	v_lshl_add_u64 v[14:15], s[78:79], 0, v[14:15]
	v_min_u32_e32 v147, 30, v18
	v_add_u32_e32 v18, 25, v17
	v_mul_u32_u24_e32 v3, 0x90, v3
	s_mul_i32 s60, s64, 0x90
	v_and_b32_e32 v19, 32, v19
	v_lshl_add_u64 v[118:119], v[4:5], 0, v[0:1]
	v_lshl_add_u64 v[4:5], s[74:75], 0, v[12:13]
	v_writelane_b32 v254, s87, 39
	v_lshlrev_b64 v[14:15], 13, v[14:15]
	v_cmp_ge_u32_e64 s[58:59], v18, v32
	v_add3_u32 v3, v3, s60, v19
	v_mov_b32_e32 v19, s60
	v_cmp_lt_u32_e64 s[60:61], v18, v33
	v_sub_u32_e32 v18, v18, v16
	v_lshl_add_u64 v[4:5], v[4:5], 0, s[68:69]
	v_writelane_b32 v254, s88, 40
	v_max_i32_e32 v18, -15, v18
	v_lshl_add_u64 v[120:121], v[4:5], 0, v[0:1]
	v_lshl_add_u64 v[4:5], s[74:75], 0, v[14:15]
	v_writelane_b32 v254, s89, 41
	v_add_u32_e32 v18, 15, v18
	v_add_u32_e32 v34, 26, v17
	v_add_u32_e32 v35, 27, v17
	v_writelane_b32 v254, s90, 42
	v_lshl_add_u64 v[4:5], v[4:5], 0, s[68:69]
	v_min_u32_e32 v148, 30, v18
	v_sub_u32_e32 v18, v34, v16
	v_sub_u32_e32 v16, v35, v16
	v_writelane_b32 v254, s91, 43
	v_lshl_add_u64 v[122:123], v[4:5], 0, v[0:1]
	v_and_b32_e32 v0, 3, v2
	v_max_i32_e32 v18, -15, v18
	v_max_i32_e32 v16, -15, v16
	v_writelane_b32 v254, s92, 44
	v_lshlrev_b32_e32 v0, 3, v0
	v_add_u32_e32 v18, 15, v18
	v_add_u32_e32 v16, 15, v16
	v_writelane_b32 v254, s93, 45
	v_add3_u32 v151, v3, v0, 0
	v_mad_u32_u24 v0, v125, s65, v19
	v_mov_b32_e32 v14, v233
	v_mov_b32_e32 v15, v233
	v_cmp_ge_u32_e64 s[4:5], v17, v32
	v_cmp_lt_u32_e64 s[6:7], v17, v33
	v_cmp_lt_u32_e64 s[40:41], v17, v32
	s_or_b32 s63, s64, s63
	v_min_u32_e32 v149, 30, v18
	v_min_u32_e32 v150, 30, v16
	v_writelane_b32 v254, s94, 46
	v_add3_u32 v152, v0, v232, 0
	v_mov_b32_e32 v0, v233
	v_mov_b32_e32 v2, v233
	v_mov_b32_e32 v3, v233
	v_mov_b32_e32 v4, v233
	v_mov_b32_e32 v5, v233
	v_mov_b32_e32 v6, v233
	v_mov_b32_e32 v7, v233
	v_mov_b32_e32 v8, v233
	v_mov_b32_e32 v9, v233
	v_mov_b32_e32 v10, v233
	v_mov_b32_e32 v11, v233
	v_mov_b32_e32 v12, v233
	v_mov_b32_e32 v13, v233
	v_mov_b64_e32 v[30:31], v[14:15]
	s_add_i32 s72, s72, 8
	v_add_u32_e32 v134, 8, v133
	s_mov_b32 s70, 0
	s_sub_i32 s73, s63, s62
	v_cmp_ge_u32_e64 s[62:63], v34, v32
	v_writelane_b32 v254, s95, 47
	v_mov_b32_e32 v153, 0
	v_mov_b32_e32 v154, 0xf149f2ca
	v_mov_b64_e32 v[28:29], v[12:13]
	v_mov_b64_e32 v[26:27], v[10:11]
	v_mov_b64_e32 v[24:25], v[8:9]
	v_mov_b64_e32 v[22:23], v[6:7]
	v_mov_b64_e32 v[20:21], v[4:5]
	v_mov_b64_e32 v[18:19], v[2:3]
	v_mov_b64_e32 v[16:17], v[0:1]
	v_cmp_lt_u32_e64 s[64:65], v34, v33
	v_cmp_ge_u32_e64 s[66:67], v35, v32
	v_cmp_lt_u32_e64 s[68:69], v35, v33
	s_mov_b64 s[80:81], -1
	s_waitcnt lgkmcnt(0)
	ds_write_b128 v127, v[48:51]
	ds_write_b128 v127, v[52:55] offset:55296
	ds_write_b128 v127, v[56:59] offset:9216
	ds_write_b128 v127, v[60:63] offset:64512
	s_waitcnt vmcnt(0)
	ds_write_b128 v127, v[64:67] offset:18432
	ds_write_b128 v128, v[68:71]
	ds_write_b128 v127, v[72:75] offset:27648
	ds_write_b128 v129, v[76:79]
	ds_write_b128 v127, v[80:83] offset:36864
	ds_write_b128 v131, v[84:87]
	ds_write_b128 v127, v[88:91] offset:46080
	ds_write_b128 v132, v[92:95]
	s_waitcnt lgkmcnt(0)
	s_barrier
	s_branch .LBB0_605

.LBB0_605:
	s_xor_b64 s[82:83], s[80:81], -1
	s_and_b64 vcc, exec, s[82:83]
	s_cbranch_vccnz .LBB0_607
	s_waitcnt vmcnt(0)
	global_load_dwordx4 v[48:51], v[112:113], off offset:2368
	global_load_dwordx4 v[52:55], v[112:113], off offset:2880
	global_load_dwordx4 v[56:59], v[114:115], off offset:2368
	global_load_dwordx4 v[60:63], v[114:115], off offset:2880
	global_load_dwordx4 v[64:67], v[116:117], off offset:2368
	global_load_dwordx4 v[68:71], v[116:117], off offset:2880
	global_load_dwordx4 v[72:75], v[118:119], off offset:2368
	global_load_dwordx4 v[76:79], v[118:119], off offset:2880
	global_load_dwordx4 v[80:83], v[120:121], off offset:2368
	global_load_dwordx4 v[84:87], v[120:121], off offset:2880
	global_load_dwordx4 v[88:91], v[122:123], off offset:2368
	global_load_dwordx4 v[92:95], v[122:123], off offset:2880

.LBB0_695:
	s_or_b64 exec, exec, s[10:11]
	v_or_b32_e32 v32, s22, v83
	v_ashrrev_i32_e32 v33, 31, v32
	v_add_u32_e32 v44, s17, v232
	v_lshlrev_b64 v[42:43], s16, v[32:33]
	ds_read_b128 v[34:37], v44
	ds_read_b128 v[38:41], v44 offset:32
	v_lshl_add_u64 v[42:43], v[42:43], 0, s[6:7]
	v_lshlrev_b64 v[42:43], 13, v[42:43]
	v_lshl_add_u64 v[42:43], s[74:75], 0, v[42:43]
	v_lshl_add_u64 v[42:43], v[42:43], 0, s[8:9]
	s_lshl_b32 s40, s23, 1
	v_lshl_add_u64 v[42:43], v[42:43], 0, s[40:41]
	s_waitcnt lgkmcnt(0)
	v_mul_f32_e32 v0, v0, v34
	v_lshlrev_b32_e32 v232, 1, v82
	v_cvt_pk_bf16_f32 v0, v0, s0
	v_mul_f32_e32 v16, v16, v34
	v_lshl_add_u64 v[42:43], v[42:43], 0, v[232:233]
	v_cvt_pk_bf16_f32 v16, v16, s0
	global_store_short v[42:43], v0, off offset:3392
	global_store_short v[42:43], v16, off offset:3456
	v_or_b32_e32 v42, 1, v32
	v_ashrrev_i32_e32 v43, 31, v42
	v_lshlrev_b64 v[42:43], s16, v[42:43]
	v_lshl_add_u64 v[42:43], v[42:43], 0, s[6:7]
	v_lshlrev_b64 v[42:43], 13, v[42:43]
	v_lshl_add_u64 v[42:43], s[74:75], 0, v[42:43]
	v_lshl_add_u64 v[42:43], v[42:43], 0, s[8:9]
	v_mul_f32_e32 v0, v1, v35
	v_lshl_add_u64 v[42:43], v[42:43], 0, s[40:41]
	v_cvt_pk_bf16_f32 v16, v0, s0
	v_mul_f32_e32 v0, v17, v35
	v_cvt_pk_bf16_f32 v17, v0, s0
	v_lshl_add_u64 v[0:1], v[42:43], 0, v[232:233]
	global_store_short v[0:1], v16, off offset:3392
	global_store_short v[0:1], v17, off offset:3456
	v_or_b32_e32 v0, 2, v32
	v_ashrrev_i32_e32 v1, 31, v0
	v_lshlrev_b64 v[0:1], s16, v[0:1]
	v_lshl_add_u64 v[0:1], v[0:1], 0, s[6:7]
	v_lshlrev_b64 v[0:1], 13, v[0:1]
	v_lshl_add_u64 v[0:1], s[74:75], 0, v[0:1]
	v_lshl_add_u64 v[0:1], v[0:1], 0, s[8:9]
	v_lshl_add_u64 v[0:1], v[0:1], 0, s[40:41]
	v_mul_f32_e32 v2, v2, v36
	v_cvt_pk_bf16_f32 v2, v2, s0
	v_mul_f32_e32 v16, v18, v36
	v_lshl_add_u64 v[0:1], v[0:1], 0, v[232:233]
	v_cvt_pk_bf16_f32 v16, v16, s0
	global_store_short v[0:1], v2, off offset:3392
	global_store_short v[0:1], v16, off offset:3456
	v_or_b32_e32 v0, 3, v32
	v_ashrrev_i32_e32 v1, 31, v0
	v_lshlrev_b64 v[0:1], s16, v[0:1]
	v_lshl_add_u64 v[0:1], v[0:1], 0, s[6:7]
	v_lshlrev_b64 v[0:1], 13, v[0:1]
	v_lshl_add_u64 v[0:1], s[74:75], 0, v[0:1]
	v_lshl_add_u64 v[0:1], v[0:1], 0, s[8:9]
	v_lshl_add_u64 v[0:1], v[0:1], 0, s[40:41]
	v_mul_f32_e32 v2, v3, v37
	v_cvt_pk_bf16_f32 v2, v2, s0
	v_mul_f32_e32 v3, v19, v37
	v_lshl_add_u64 v[0:1], v[0:1], 0, v[232:233]
	v_cvt_pk_bf16_f32 v3, v3, s0
	global_store_short v[0:1], v2, off offset:3392
	global_store_short v[0:1], v3, off offset:3456
	v_or_b32_e32 v0, 8, v32
	v_ashrrev_i32_e32 v1, 31, v0
	v_lshlrev_b64 v[0:1], s16, v[0:1]
	v_lshl_add_u64 v[0:1], v[0:1], 0, s[6:7]
	v_lshlrev_b64 v[0:1], 13, v[0:1]
	v_lshl_add_u64 v[0:1], s[74:75], 0, v[0:1]
	v_lshl_add_u64 v[0:1], v[0:1], 0, s[8:9]
	v_lshl_add_u64 v[0:1], v[0:1], 0, s[40:41]
	v_mul_f32_e32 v2, v4, v38
	v_cvt_pk_bf16_f32 v2, v2, s0
	v_mul_f32_e32 v3, v20, v38
	v_lshl_add_u64 v[0:1], v[0:1], 0, v[232:233]
	v_cvt_pk_bf16_f32 v3, v3, s0
	global_store_short v[0:1], v2, off offset:3392
	global_store_short v[0:1], v3, off offset:3456
	v_or_b32_e32 v0, 9, v32
	v_ashrrev_i32_e32 v1, 31, v0
	v_lshlrev_b64 v[0:1], s16, v[0:1]
	v_lshl_add_u64 v[0:1], v[0:1], 0, s[6:7]
	v_lshlrev_b64 v[0:1], 13, v[0:1]
	v_lshl_add_u64 v[0:1], s[74:75], 0, v[0:1]
	v_lshl_add_u64 v[0:1], v[0:1], 0, s[8:9]
	v_lshl_add_u64 v[0:1], v[0:1], 0, s[40:41]
	v_mul_f32_e32 v2, v5, v39
	v_cvt_pk_bf16_f32 v2, v2, s0
	v_mul_f32_e32 v3, v21, v39
	v_lshl_add_u64 v[0:1], v[0:1], 0, v[232:233]
	v_cvt_pk_bf16_f32 v3, v3, s0
	global_store_short v[0:1], v2, off offset:3392
	global_store_short v[0:1], v3, off offset:3456
	v_or_b32_e32 v0, 10, v32
	v_ashrrev_i32_e32 v1, 31, v0
	v_lshlrev_b64 v[0:1], s16, v[0:1]
	v_lshl_add_u64 v[0:1], v[0:1], 0, s[6:7]
	v_lshlrev_b64 v[0:1], 13, v[0:1]
	v_lshl_add_u64 v[0:1], s[74:75], 0, v[0:1]
	v_lshl_add_u64 v[0:1], v[0:1], 0, s[8:9]
	v_lshl_add_u64 v[0:1], v[0:1], 0, s[40:41]
	v_mul_f32_e32 v2, v6, v40
	v_cvt_pk_bf16_f32 v2, v2, s0
	v_mul_f32_e32 v3, v22, v40
	v_lshl_add_u64 v[0:1], v[0:1], 0, v[232:233]
	v_cvt_pk_bf16_f32 v3, v3, s0
	global_store_short v[0:1], v2, off offset:3392
	global_store_short v[0:1], v3, off offset:3456
	v_or_b32_e32 v0, 11, v32
	v_ashrrev_i32_e32 v1, 31, v0
	v_lshlrev_b64 v[0:1], s16, v[0:1]
	v_lshl_add_u64 v[0:1], v[0:1], 0, s[6:7]
	v_lshlrev_b64 v[0:1], 13, v[0:1]
	v_lshl_add_u64 v[0:1], s[74:75], 0, v[0:1]
	v_lshl_add_u64 v[0:1], v[0:1], 0, s[8:9]
	v_lshl_add_u64 v[0:1], v[0:1], 0, s[40:41]
	v_mul_f32_e32 v2, v7, v41
	v_cvt_pk_bf16_f32 v2, v2, s0
	v_mul_f32_e32 v3, v23, v41
	v_lshl_add_u64 v[0:1], v[0:1], 0, v[232:233]
	v_or_b32_e32 v4, 16, v32
	v_cvt_pk_bf16_f32 v3, v3, s0
	global_store_short v[0:1], v2, off offset:3392
	global_store_short v[0:1], v3, off offset:3456
	v_ashrrev_i32_e32 v5, 31, v4
	ds_read_b128 v[0:3], v44 offset:64
	v_lshlrev_b64 v[4:5], s16, v[4:5]
	v_lshl_add_u64 v[4:5], v[4:5], 0, s[6:7]
	v_lshlrev_b64 v[4:5], 13, v[4:5]
	v_lshl_add_u64 v[4:5], s[74:75], 0, v[4:5]
	v_lshl_add_u64 v[4:5], v[4:5], 0, s[8:9]
	v_lshl_add_u64 v[16:17], v[4:5], 0, s[40:41]
	ds_read_b128 v[4:7], v44 offset:96
	s_waitcnt lgkmcnt(0)
	v_mul_f32_e32 v8, v8, v0
	v_cvt_pk_bf16_f32 v8, v8, s0
	v_mul_f32_e32 v0, v24, v0
	v_lshl_add_u64 v[16:17], v[16:17], 0, v[232:233]
	v_cvt_pk_bf16_f32 v0, v0, s0
	global_store_short v[16:17], v8, off offset:3392
	global_store_short v[16:17], v0, off offset:3456
	v_or_b32_e32 v16, 17, v32
	v_ashrrev_i32_e32 v17, 31, v16
	v_lshlrev_b64 v[16:17], s16, v[16:17]
	v_lshl_add_u64 v[16:17], v[16:17], 0, s[6:7]
	v_lshlrev_b64 v[16:17], 13, v[16:17]
	v_lshl_add_u64 v[16:17], s[74:75], 0, v[16:17]
	v_lshl_add_u64 v[16:17], v[16:17], 0, s[8:9]
	v_mul_f32_e32 v0, v9, v1
	v_lshl_add_u64 v[16:17], v[16:17], 0, s[40:41]
	v_cvt_pk_bf16_f32 v8, v0, s0
	v_mul_f32_e32 v0, v25, v1
	v_cvt_pk_bf16_f32 v9, v0, s0
	v_lshl_add_u64 v[0:1], v[16:17], 0, v[232:233]
	global_store_short v[0:1], v8, off offset:3392
	global_store_short v[0:1], v9, off offset:3456
	v_or_b32_e32 v0, 18, v32
	v_ashrrev_i32_e32 v1, 31, v0
	v_lshlrev_b64 v[0:1], s16, v[0:1]
	v_lshl_add_u64 v[0:1], v[0:1], 0, s[6:7]
	v_lshlrev_b64 v[0:1], 13, v[0:1]
	v_lshl_add_u64 v[0:1], s[74:75], 0, v[0:1]
	v_lshl_add_u64 v[0:1], v[0:1], 0, s[8:9]
	v_lshl_add_u64 v[0:1], v[0:1], 0, s[40:41]
	v_mul_f32_e32 v8, v10, v2
	v_cvt_pk_bf16_f32 v8, v8, s0
	v_mul_f32_e32 v2, v26, v2
	v_lshl_add_u64 v[0:1], v[0:1], 0, v[232:233]
	v_cvt_pk_bf16_f32 v2, v2, s0
	global_store_short v[0:1], v8, off offset:3392
	global_store_short v[0:1], v2, off offset:3456
	v_or_b32_e32 v0, 19, v32
	v_ashrrev_i32_e32 v1, 31, v0
	v_lshlrev_b64 v[0:1], s16, v[0:1]
	v_lshl_add_u64 v[0:1], v[0:1], 0, s[6:7]
	v_lshlrev_b64 v[0:1], 13, v[0:1]
	v_lshl_add_u64 v[0:1], s[74:75], 0, v[0:1]
	v_lshl_add_u64 v[0:1], v[0:1], 0, s[8:9]
	v_lshl_add_u64 v[0:1], v[0:1], 0, s[40:41]
	v_mul_f32_e32 v2, v11, v3
	v_cvt_pk_bf16_f32 v2, v2, s0
	v_mul_f32_e32 v3, v27, v3
	v_lshl_add_u64 v[0:1], v[0:1], 0, v[232:233]
	v_cvt_pk_bf16_f32 v3, v3, s0
	global_store_short v[0:1], v2, off offset:3392
	global_store_short v[0:1], v3, off offset:3456
	v_or_b32_e32 v0, 24, v32
	v_ashrrev_i32_e32 v1, 31, v0
	v_lshlrev_b64 v[0:1], s16, v[0:1]
	v_lshl_add_u64 v[0:1], v[0:1], 0, s[6:7]
	v_lshlrev_b64 v[0:1], 13, v[0:1]
	v_lshl_add_u64 v[0:1], s[74:75], 0, v[0:1]
	v_lshl_add_u64 v[0:1], v[0:1], 0, s[8:9]
	v_lshl_add_u64 v[0:1], v[0:1], 0, s[40:41]
	v_mul_f32_e32 v2, v12, v4
	v_cvt_pk_bf16_f32 v2, v2, s0
	v_mul_f32_e32 v3, v28, v4
	v_lshl_add_u64 v[0:1], v[0:1], 0, v[232:233]
	v_cvt_pk_bf16_f32 v3, v3, s0
	global_store_short v[0:1], v2, off offset:3392
	global_store_short v[0:1], v3, off offset:3456
	v_or_b32_e32 v0, 25, v32
	v_ashrrev_i32_e32 v1, 31, v0
	v_lshlrev_b64 v[0:1], s16, v[0:1]
	v_lshl_add_u64 v[0:1], v[0:1], 0, s[6:7]
	v_lshlrev_b64 v[0:1], 13, v[0:1]
	v_lshl_add_u64 v[0:1], s[74:75], 0, v[0:1]
	v_lshl_add_u64 v[0:1], v[0:1], 0, s[8:9]
	v_lshl_add_u64 v[0:1], v[0:1], 0, s[40:41]
	v_mul_f32_e32 v2, v13, v5
	v_cvt_pk_bf16_f32 v2, v2, s0
	v_mul_f32_e32 v3, v29, v5
	v_lshl_add_u64 v[0:1], v[0:1], 0, v[232:233]
	v_cvt_pk_bf16_f32 v3, v3, s0
	global_store_short v[0:1], v2, off offset:3392
	global_store_short v[0:1], v3, off offset:3456
	v_or_b32_e32 v0, 26, v32
	v_ashrrev_i32_e32 v1, 31, v0
	v_lshlrev_b64 v[0:1], s16, v[0:1]
	v_lshl_add_u64 v[0:1], v[0:1], 0, s[6:7]
	v_lshlrev_b64 v[0:1], 13, v[0:1]
	v_lshl_add_u64 v[0:1], s[74:75], 0, v[0:1]
	v_lshl_add_u64 v[0:1], v[0:1], 0, s[8:9]
	v_lshl_add_u64 v[0:1], v[0:1], 0, s[40:41]
	v_mul_f32_e32 v2, v14, v6
	v_cvt_pk_bf16_f32 v2, v2, s0
	v_mul_f32_e32 v3, v30, v6
	v_lshl_add_u64 v[0:1], v[0:1], 0, v[232:233]
	v_cvt_pk_bf16_f32 v3, v3, s0
	global_store_short v[0:1], v2, off offset:3392
	global_store_short v[0:1], v3, off offset:3456
	v_or_b32_e32 v0, 27, v32
	v_ashrrev_i32_e32 v1, 31, v0
	v_lshlrev_b64 v[0:1], s16, v[0:1]
	v_lshl_add_u64 v[0:1], v[0:1], 0, s[6:7]
	v_lshlrev_b64 v[0:1], 13, v[0:1]
	v_lshl_add_u64 v[0:1], s[74:75], 0, v[0:1]
	v_lshl_add_u64 v[0:1], v[0:1], 0, s[8:9]
	s_mov_b32 s9, s41
	v_writelane_b32 v254, s8, 32
	v_lshl_add_u64 v[0:1], v[0:1], 0, s[40:41]
	v_mul_f32_e32 v2, v15, v7
	v_writelane_b32 v254, s9, 33
	v_writelane_b32 v254, s10, 34
	v_writelane_b32 v254, s11, 35
	v_writelane_b32 v254, s12, 36
	v_writelane_b32 v254, s13, 37
	v_writelane_b32 v254, s14, 38
	v_writelane_b32 v254, s15, 39
	v_writelane_b32 v254, s16, 40
	v_writelane_b32 v254, s17, 41
	v_writelane_b32 v254, s18, 42
	v_writelane_b32 v254, s19, 43
	v_writelane_b32 v254, s20, 44
	v_writelane_b32 v254, s21, 45
	v_writelane_b32 v254, s22, 46
	v_writelane_b32 v254, s23, 47
	s_add_i32 s38, s38, s64
	s_add_i32 s15, s15, s64
	v_cvt_pk_bf16_f32 v2, v2, s0
	v_mul_f32_e32 v3, v31, v7
	v_lshl_add_u64 v[0:1], v[0:1], 0, v[232:233]
	s_cmpk_lt_i32 s38, 0xc0
	v_cvt_pk_bf16_f32 v3, v3, s0
	global_store_short v[0:1], v2, off offset:3392
	global_store_short v[0:1], v3, off offset:3456
	s_waitcnt lgkmcnt(0)
	s_barrier
	s_cbranch_scc0 .LBB0_791

.LBB0_699:
	s_and_b32 s2, s10, 0x3fffffc0
	s_lshl_b32 s2, s2, 2
	s_add_i32 s17, s2, 0
	s_mul_hi_i32 s2, s8, 0x2aaaaaab
	s_lshr_b32 s6, s2, 31
	s_ashr_i32 s2, s2, 6
	s_add_i32 s17, s17, 0x1c800
	s_and_b32 s3, s38, 31
	s_bfe_u32 s19, s8, 0x20005
	s_add_i32 s2, s2, s6
	s_cmp_eq_u32 s18, 1
	s_cselect_b32 s6, 2, 4
	s_cmp_lg_u32 s18, 0
	s_cselect_b32 s16, s6, 0
	s_lshr_b32 s6, 32, s16
	s_sub_i32 s7, 5, s16
	s_add_i32 s6, s6, -1
	s_lshr_b32 s8, s3, s7
	s_and_b32 s3, s6, s3
	s_lshl_b32 s21, s3, 8
	s_ashr_i32 s3, s2, 31
	s_lshl_b64 s[6:7], s[2:3], 13
	s_lshl_b32 s2, s18, 8
	s_ashr_i32 s3, s2, 31
	s_or_b32 s6, s6, s8
	s_lshl_b64 s[8:9], s[2:3], 1
	s_sub_i32 s2, s21, 64
	v_ashrrev_i32_e32 v1, 3, v0
	s_lshr_b32 s20, 0x2000, s16
	v_add_u32_e32 v2, s2, v1
	v_max_i32_e32 v2, 0, v2
	s_add_i32 s2, s20, -1
	v_min_u32_e32 v2, s2, v2
	v_mov_b32_e32 v3, v233
	v_add_u32_e32 v42, s21, v1
	v_lshlrev_b64 v[2:3], s16, v[2:3]
	v_max_i32_e32 v10, 0, v42
	v_lshl_add_u64 v[2:3], v[2:3], 0, s[6:7]
	v_min_u32_e32 v10, s2, v10
	v_mov_b32_e32 v11, v233
	v_add_u32_e32 v18, 64, v42
	v_readlane_b32 s48, v254, 32
	v_lshlrev_b64 v[2:3], 13, v[2:3]
	v_lshlrev_b64 v[10:11], s16, v[10:11]
	v_max_i32_e32 v18, 0, v18
	v_readlane_b32 s49, v254, 33
	v_lshl_add_u64 v[2:3], s[74:75], 0, v[2:3]
	v_lshl_add_u64 v[10:11], v[10:11], 0, s[6:7]
	v_min_u32_e32 v18, s2, v18
	v_mov_b32_e32 v19, v233
	v_add_u32_e32 v26, 0x80, v42
	s_mov_b32 s13, s49
	s_lshl_b32 s12, s19, 7
	v_lshl_add_u64 v[2:3], v[2:3], 0, s[8:9]
	v_lshlrev_b32_e32 v4, 4, v0
	v_lshlrev_b64 v[10:11], 13, v[10:11]
	v_lshlrev_b64 v[18:19], s16, v[18:19]
	v_max_i32_e32 v26, 0, v26
	v_lshl_add_u64 v[2:3], v[2:3], 0, s[12:13]
	s_waitcnt vmcnt(0)
	v_cmp_gt_i32_e64 s[30:31], s37, v0
	s_and_saveexec_b64 s[34:35], s[30:31]
	s_bfe_u32 s28, s15, 0x20005
	s_mulk_i32 s28, 0x84
	s_mul_i32 s29, s18, 0x210
	s_add_i32 s29, s29, s28
	v_add_u32_e32 v200, s29, v0
	v_ashrrev_i32_e32 v201, 31, v200
	v_lshl_add_u64 v[200:201], v[200:201], 2, s[4:5]
	global_load_dword v202, v[200:201], off
	s_or_b64 exec, exec, s[34:35]
	v_and_b32_e32 v50, 0x70, v4
	v_mov_b32_e32 v51, v233
	v_lshl_add_u64 v[10:11], s[74:75], 0, v[10:11]
	v_lshl_add_u64 v[18:19], v[18:19], 0, s[6:7]
	v_min_u32_e32 v26, s2, v26
	v_mov_b32_e32 v27, v233
	v_add_u32_e32 v34, 0xc0, v42
	v_lshl_add_u64 v[2:3], v[2:3], 0, v[50:51]
	v_lshl_add_u64 v[10:11], v[10:11], 0, s[8:9]
	v_lshlrev_b64 v[18:19], 13, v[18:19]
	v_lshlrev_b64 v[26:27], s16, v[26:27]
	v_max_i32_e32 v34, 0, v34
	v_add_co_u32_e32 v6, vcc, s36, v2
	v_lshl_add_u64 v[10:11], v[10:11], 0, s[12:13]
	v_lshl_add_u64 v[18:19], s[74:75], 0, v[18:19]
	v_lshl_add_u64 v[26:27], v[26:27], 0, s[6:7]
	v_min_u32_e32 v34, s2, v34
	v_mov_b32_e32 v35, v233
	v_add_u32_e32 v42, 0x100, v42
	v_addc_co_u32_e32 v7, vcc, 0, v3, vcc
	v_lshl_add_u64 v[10:11], v[10:11], 0, v[50:51]
	v_lshl_add_u64 v[18:19], v[18:19], 0, s[8:9]
	v_lshlrev_b64 v[26:27], 13, v[26:27]
	v_lshlrev_b64 v[34:35], s16, v[34:35]
	v_max_i32_e32 v42, 0, v42
	v_add_co_u32_e32 v14, vcc, s36, v10
	v_lshl_add_u64 v[18:19], v[18:19], 0, s[12:13]
	v_lshl_add_u64 v[26:27], s[74:75], 0, v[26:27]
	v_lshl_add_u64 v[34:35], v[34:35], 0, s[6:7]
	v_min_u32_e32 v42, s2, v42
	v_mov_b32_e32 v43, v233
	v_addc_co_u32_e32 v15, vcc, 0, v11, vcc
	v_lshl_add_u64 v[18:19], v[18:19], 0, v[50:51]
	v_lshl_add_u64 v[26:27], v[26:27], 0, s[8:9]
	v_lshlrev_b64 v[34:35], 13, v[34:35]
	v_lshlrev_b64 v[42:43], s16, v[42:43]
	v_add_co_u32_e32 v22, vcc, s36, v18
	v_lshl_add_u64 v[26:27], v[26:27], 0, s[12:13]
	v_lshl_add_u64 v[34:35], s[74:75], 0, v[34:35]
	v_lshl_add_u64 v[42:43], v[42:43], 0, s[6:7]
	s_ashr_i32 s10, s10, 1
	v_addc_co_u32_e32 v23, vcc, 0, v19, vcc
	v_lshl_add_u64 v[26:27], v[26:27], 0, v[50:51]
	v_lshl_add_u64 v[34:35], v[34:35], 0, s[8:9]
	v_lshlrev_b64 v[42:43], 13, v[42:43]
	s_and_b32 s11, s10, 0xffffffe0
	v_add_co_u32_e32 v30, vcc, s36, v26
	v_lshl_add_u64 v[34:35], v[34:35], 0, s[12:13]
	v_lshl_add_u64 v[42:43], s[74:75], 0, v[42:43]
	v_and_b32_e32 v82, 31, v0
	s_add_i32 s22, s11, s21
	v_addc_co_u32_e32 v31, vcc, 0, v27, vcc
	v_lshl_add_u64 v[34:35], v[34:35], 0, v[50:51]
	v_lshl_add_u64 v[42:43], v[42:43], 0, s[8:9]
	v_or_b32_e32 v52, s22, v82
	global_load_dwordx4 v[2:5], v[6:7], off offset:832
	s_nop 0
	global_load_dwordx4 v[6:9], v[6:7], off offset:2368
	s_nop 0
	global_load_dwordx4 v[10:13], v[14:15], off offset:832
	s_nop 0
	global_load_dwordx4 v[14:17], v[14:15], off offset:2368
	v_add_co_u32_e32 v38, vcc, s36, v34
	v_lshl_add_u64 v[42:43], v[42:43], 0, s[12:13]
	v_ashrrev_i32_e32 v53, 31, v52
	global_load_dwordx4 v[18:21], v[22:23], off offset:832
	s_nop 0
	global_load_dwordx4 v[22:25], v[22:23], off offset:2368
	v_addc_co_u32_e32 v39, vcc, 0, v35, vcc
	v_lshl_add_u64 v[42:43], v[42:43], 0, v[50:51]
	v_lshlrev_b64 v[52:53], s16, v[52:53]
	global_load_dwordx4 v[26:29], v[30:31], off offset:832
	s_nop 0
	global_load_dwordx4 v[30:33], v[30:31], off offset:2368
	v_add_co_u32_e32 v46, vcc, s36, v42
	v_lshl_add_u64 v[80:81], v[52:53], 0, s[6:7]
	global_load_dwordx4 v[34:37], v[38:39], off offset:832
	s_nop 0
	global_load_dwordx4 v[38:41], v[38:39], off offset:2368
	v_addc_co_u32_e32 v47, vcc, 0, v43, vcc
	v_lshlrev_b64 v[52:53], 13, v[80:81]
	global_load_dwordx4 v[42:45], v[46:47], off offset:832
	s_nop 0
	global_load_dwordx4 v[46:49], v[46:47], off offset:2368
	v_lshl_add_u64 v[52:53], s[74:75], 0, v[52:53]
	v_bfe_u32 v51, v0, 5, 1
	v_lshl_add_u64 v[52:53], v[52:53], 0, s[8:9]
	v_lshl_add_u64 v[52:53], v[52:53], 0, s[12:13]
	v_lshlrev_b32_e32 v232, 4, v51
	v_lshl_add_u64 v[52:53], v[52:53], 0, v[232:233]
	global_load_dwordx4 v[64:67], v[52:53], off offset:3392
	global_load_dwordx4 v[68:71], v[52:53], off offset:3424
	global_load_dwordx4 v[72:75], v[52:53], off offset:3456
	global_load_dwordx4 v[76:79], v[52:53], off offset:3488
	s_movk_i32 s12, 0x90
	v_mul_lo_u32 v1, v1, s12
	v_add3_u32 v52, 0, v1, v50
	s_add_i32 s3, 0, 0x12000
	s_waitcnt vmcnt(0) lgkmcnt(0)
	s_and_saveexec_b64 s[34:35], s[30:31]
	v_lshl_add_u32 v203, v0, 2, v251
	ds_write_b32 v203, v202
	s_or_b64 exec, exec, s[34:35]
	ds_write_b128 v52, v[2:5]
	ds_write_b128 v52, v[6:9] offset:55296
	ds_write_b128 v52, v[10:13] offset:9216
	ds_write_b128 v52, v[14:17] offset:64512
	ds_write_b128 v52, v[18:21] offset:18432
	v_add3_u32 v2, s3, v1, v50
	ds_write_b128 v2, v[22:25]
	ds_write_b128 v52, v[26:29] offset:27648
	v_add3_u32 v2, s89, v1, v50
	v_readlane_b32 s3, v254, 10
	ds_write_b128 v2, v[30:33]
	ds_write_b128 v52, v[34:37] offset:36864
	v_add3_u32 v2, s3, v1, v50
	ds_write_b128 v2, v[38:41]
	ds_write_b128 v52, v[42:45] offset:46080
	v_readlane_b32 s3, v254, 11
	v_lshlrev_b32_e32 v2, 2, v82
	s_lshl_b32 s10, s10, 2
	v_add3_u32 v1, s3, v1, v50
	v_lshlrev_b32_e32 v83, 2, v51
	v_add_u32_e32 v84, s17, v2
	v_sub_u32_e32 v2, v232, v2
	s_and_b32 s10, s10, 0xffffff80
	ds_write_b128 v1, v[46:49]
	v_lshrrev_b32_e32 v1, 2, v0
	v_subrev_u32_e32 v86, s10, v2
	v_sub_u32_e32 v2, v83, v82
	v_and_or_b32 v1, v1, 3, v83
	v_subrev_u32_e32 v87, s11, v2
	v_lshlrev_b32_e32 v2, 1, v0
	v_and_b32_e32 v0, 3, v0
	s_max_i32 s3, s22, 64
	v_mul_u32_u24_e32 v1, 0x90, v1
	v_and_b32_e32 v2, 32, v2
	v_lshlrev_b32_e32 v0, 3, v0
	v_mov_b32_e32 v14, v233
	v_mov_b32_e32 v15, v233
	s_sub_i32 s25, s3, 64
	s_add_i32 s3, s22, 0x5f
	v_add3_u32 v90, v1, v2, v0
	v_mov_b32_e32 v0, v233
	v_mov_b32_e32 v1, v233
	v_mov_b32_e32 v2, v233
	v_mov_b32_e32 v3, v233
	v_mov_b32_e32 v4, v233
	v_mov_b32_e32 v5, v233
	v_mov_b32_e32 v6, v233
	v_mov_b32_e32 v7, v233
	v_mov_b32_e32 v8, v233
	v_mov_b32_e32 v9, v233
	v_mov_b32_e32 v10, v233
	v_mov_b32_e32 v11, v233
	v_mov_b32_e32 v12, v233
	v_mov_b32_e32 v13, v233
	v_mov_b64_e32 v[30:31], v[14:15]
	s_mov_b32 s41, s49
	s_mov_b32 s24, 0
	s_lshl_b32 s23, s19, 6
	s_min_i32 s26, s3, s2
	v_cmp_eq_u32_e64 s[2:3], 0, v51
	s_sub_i32 s27, 0, s11
	v_lshl_add_u32 v88, v87, 2, v251
	v_or_b32_e32 v89, s21, v83
	v_mad_u32_u24 v91, v82, s12, v232
	v_mov_b32_e32 v85, 0
	v_mov_b32_e32 v92, 0xf149f2ca
	v_mov_b64_e32 v[28:29], v[12:13]
	v_mov_b64_e32 v[26:27], v[10:11]
	v_mov_b64_e32 v[24:25], v[8:9]
	v_mov_b64_e32 v[22:23], v[6:7]
	v_mov_b64_e32 v[20:21], v[4:5]
	v_mov_b64_e32 v[18:19], v[2:3]
	v_mov_b64_e32 v[16:17], v[0:1]
	v_readlane_b32 s50, v254, 34
	v_readlane_b32 s51, v254, 35
	v_readlane_b32 s52, v254, 36
	v_readlane_b32 s53, v254, 37
	v_readlane_b32 s54, v254, 38
	v_readlane_b32 s55, v254, 39
	v_readlane_b32 s56, v254, 40
	v_readlane_b32 s57, v254, 41
	v_readlane_b32 s58, v254, 42
	v_readlane_b32 s59, v254, 43
	v_readlane_b32 s60, v254, 44
	v_readlane_b32 s61, v254, 45
	v_readlane_b32 s62, v254, 46
	v_readlane_b32 s63, v254, 47
	s_waitcnt lgkmcnt(0)
	s_barrier
	s_branch .LBB0_702

.LBB0_789:
	v_mov_b32_e32 v32, v85
	s_nop 1
	v_permlane32_swap_b32_e32 v85, v32
	s_barrier
	s_and_saveexec_b64 s[10:11], s[2:3]
	s_cbranch_execz .LBB0_695
	v_mad_u64_u32 v[34:35], s[2:3], v80, 48, s[0:1]
	v_mov_b32_e32 v36, v35
	v_mad_u64_u32 v[36:37], s[2:3], v81, 48, v[36:37]
	s_lshl_b32 s2, s18, 2
	v_mov_b32_e32 v35, v36
	s_ashr_i32 s3, s2, 31
	v_add_f32_e32 v32, v85, v32
	v_lshl_add_u64 v[34:35], s[2:3], 2, v[34:35]
	v_div_scale_f32 v33, s[2:3], v32, v32, 1.0
	v_rcp_f32_e32 v36, v33
	s_mov_b32 s13, s41
	s_lshl_b32 s12, s19, 2
	v_lshl_add_u64 v[34:35], v[34:35], 0, s[12:13]
	v_fma_f32 v37, -v33, v36, 1.0
	v_fmac_f32_e32 v36, v37, v36
	v_div_scale_f32 v37, vcc, 1.0, v32, 1.0
	v_mul_f32_e32 v38, v37, v36
	v_fma_f32 v39, -v33, v38, v37
	v_fmac_f32_e32 v38, v39, v36
	v_fma_f32 v33, -v33, v38, v37
	v_div_fmas_f32 v33, v33, v36, v38
	v_div_fixup_f32 v33, v33, v32, 1.0
	v_log_f32_e32 v32, v32
	ds_write_b32 v84, v33
	v_add_f32_e32 v32, v92, v32
	global_store_dword v[34:35], v32, off
	s_branch .LBB0_695

.LBB0_842:
	v_ashrrev_i32_e32 v0, 5, v5
	v_bfe_u32 v7, v5, 3, 2
	v_mad_i64_i32 v[2:3], s[12:13], v0, 48, s[6:7]
	v_lshlrev_b32_e32 v232, 2, v7
	v_lshl_add_u64 v[2:3], v[2:3], 0, v[232:233]
	global_load_dword v4, v[2:3], off
	global_load_dword v8, v[2:3], off offset:16
	s_nop 0
	global_load_dword v2, v[2:3], off offset:32
	v_ashrrev_i32_e32 v1, 31, v0
	v_lshlrev_b32_e32 v232, 7, v7
	v_mov_b32_e32 v25, v233
	s_waitcnt vmcnt(0) lgkmcnt(0)
	v_max3_f32 v3, v4, v8, v2
	v_sub_f32_e32 v4, v4, v3
	v_exp_f32_e32 v21, v4
	v_sub_f32_e32 v4, v8, v3
	v_exp_f32_e32 v20, v4
	v_sub_f32_e32 v2, v2, v3
	v_exp_f32_e32 v2, v2
	v_add_f32_e32 v3, v21, v20
	v_add_f32_e32 v3, v2, v3
	v_div_scale_f32 v4, s[12:13], v3, v3, 1.0
	v_rcp_f32_e32 v8, v4
	s_mov_b64 s[12:13], 0x7a00d40
	v_fma_f32 v9, -v4, v8, 1.0
	v_fmac_f32_e32 v8, v9, v8
	v_div_scale_f32 v9, vcc, 1.0, v3, 1.0
	v_mul_f32_e32 v10, v9, v8
	v_fma_f32 v11, -v4, v10, v9
	v_fmac_f32_e32 v10, v11, v8
	v_fma_f32 v4, -v4, v10, v9
	v_div_fmas_f32 v4, v4, v8, v10
	v_div_fixup_f32 v22, v4, v3, 1.0
	v_mul_f32_e32 v4, v2, v22
	v_lshlrev_b64 v[2:3], 13, v[0:1]
	v_lshl_add_u64 v[2:3], s[0:1], 0, v[2:3]
	v_and_b32_e32 v1, 56, v6
	v_lshl_add_u64 v[8:9], v[2:3], 0, v[232:233]
	v_lshlrev_b32_e32 v24, 1, v1
	v_lshl_add_u64 v[8:9], v[8:9], 0, v[24:25]
	v_lshl_add_u64 v[16:17], v[8:9], 0, s[12:13]
	s_mov_b32 s12, 0x7a00000
	v_add_co_u32_e32 v8, vcc, s12, v8
	v_pk_mul_f32 v[20:21], v[20:21], v[22:23] op_sel_hi:[1,0]
	s_nop 0
	v_addc_co_u32_e32 v9, vcc, 0, v9, vcc
	global_load_dwordx4 v[8:11], v[8:9], off offset:3392
	s_nop 0
	global_load_dwordx4 v[12:15], v[16:17], off offset:512
	s_nop 0
	global_load_dwordx4 v[16:19], v[16:17], off offset:1024
	v_mad_i64_i32 v[0:1], s[12:13], v0, s46, v[2:3]
	v_lshl_add_u64 v[0:1], v[0:1], 0, v[232:233]
	v_lshl_add_u64 v[0:1], v[0:1], 0, v[24:25]
	v_add_co_u32_e32 v0, vcc, 0x17a00000, v0
	v_add_u32_e32 v6, s11, v6
	s_nop 0
	v_addc_co_u32_e32 v1, vcc, 0, v1, vcc
	s_waitcnt vmcnt(0) lgkmcnt(0)
	v_lshlrev_b32_e32 v26, 16, v8
	v_and_b32_e32 v27, 0xffff0000, v12
	v_lshlrev_b32_e32 v22, 16, v12
	v_and_b32_e32 v23, 0xffff0000, v8
	v_pk_mul_f32 v[26:27], v[20:21], v[26:27] op_sel:[1,0] op_sel_hi:[0,1]
	v_lshlrev_b32_e32 v28, 16, v16
	v_and_b32_e32 v29, 0xffff0000, v16
	v_pk_fma_f32 v[22:23], v[20:21], v[22:23], v[26:27]
	v_lshlrev_b32_e32 v12, 16, v9
	v_pk_fma_f32 v[22:23], v[4:5], v[28:29], v[22:23] op_sel_hi:[0,1,1]
	v_cvt_pk_bf16_f32 v8, v22, v23
	v_lshlrev_b32_e32 v22, 16, v13
	v_and_b32_e32 v13, 0xffff0000, v13
	v_and_b32_e32 v23, 0xffff0000, v9
	v_pk_mul_f32 v[12:13], v[20:21], v[12:13] op_sel:[1,0] op_sel_hi:[0,1]
	v_lshlrev_b32_e32 v16, 16, v17
	v_and_b32_e32 v17, 0xffff0000, v17
	v_pk_fma_f32 v[12:13], v[20:21], v[22:23], v[12:13]
	v_lshlrev_b32_e32 v22, 16, v18
	v_pk_fma_f32 v[12:13], v[4:5], v[16:17], v[12:13] op_sel_hi:[0,1,1]
	v_lshlrev_b32_e32 v16, 16, v10
	v_and_b32_e32 v17, 0xffff0000, v14
	v_cvt_pk_bf16_f32 v9, v12, v13
	v_lshlrev_b32_e32 v12, 16, v14
	v_and_b32_e32 v13, 0xffff0000, v10
	v_pk_mul_f32 v[16:17], v[20:21], v[16:17] op_sel:[1,0] op_sel_hi:[0,1]
	v_and_b32_e32 v23, 0xffff0000, v18
	v_pk_fma_f32 v[12:13], v[20:21], v[12:13], v[16:17]
	v_lshlrev_b32_e32 v14, 16, v11
	v_pk_fma_f32 v[12:13], v[4:5], v[22:23], v[12:13] op_sel_hi:[0,1,1]
	v_cvt_pk_bf16_f32 v10, v12, v13
	v_lshlrev_b32_e32 v12, 16, v15
	v_and_b32_e32 v15, 0xffff0000, v15
	v_and_b32_e32 v13, 0xffff0000, v11
	v_pk_mul_f32 v[14:15], v[20:21], v[14:15] op_sel:[1,0] op_sel_hi:[0,1]
	v_pk_fma_f32 v[12:13], v[20:21], v[12:13], v[14:15]
	v_lshlrev_b32_e32 v14, 16, v19
	v_and_b32_e32 v15, 0xffff0000, v19
	v_pk_fma_f32 v[12:13], v[4:5], v[14:15], v[12:13] op_sel_hi:[0,1,1]
	v_add_u32_e32 v5, s10, v5
	v_cmp_lt_i32_e32 vcc, s14, v5
	v_cvt_pk_bf16_f32 v11, v12, v13
	s_or_b64 s[8:9], vcc, s[8:9]
	global_store_dwordx4 v[0:1], v[8:11], off offset:1536
	s_andn2_b64 exec, exec, s[8:9]
	s_cbranch_execnz .LBB0_842

.LBB0_915:
	s_lshl_b32 s5, s20, 8
	v_mbcnt_lo_u32_b32 v138, -1, 0
	v_mbcnt_hi_u32_b32 v138, -1, v138
	s_add_i32 s5, s5, s41
	v_and_or_b32 v140, v138, 15, s5
	s_lshl_b32 s4, s4, 8
	v_ashrrev_i32_e32 v138, 1, v138
	v_and_b32_e32 v138, -8, v138
	s_or_b32 s4, s4, s42
	v_ashrrev_i32_e32 v141, 31, v140
	v_add_u32_e32 v138, s4, v138
	v_lshlrev_b64 v[142:143], 13, v[140:141]
	v_lshl_add_u64 v[142:143], s[8:9], 0, v[142:143]
	v_cmp_gt_i32_e32 vcc, s65, v138
	v_ashrrev_i32_e32 v139, 31, v138
	s_and_saveexec_b64 s[4:5], vcc
	s_cbranch_execz .LBB0_917
	v_mul_f32_e32 v120, 0xbfb8aa3b, v120
	v_exp_f32_e32 v120, v120
	v_mul_f32_e32 v125, 0xbfb8aa3b, v125
	v_exp_f32_e32 v125, v125
	v_mul_f32_e32 v121, 0xbfb8aa3b, v121
	v_add_f32_e32 v120, 1.0, v120
	v_exp_f32_e32 v121, v121
	v_rcp_f32_e32 v141, v120
	v_add_f32_e32 v120, 1.0, v125
	v_mul_f32_e32 v125, 0xbfb8aa3b, v126
	v_exp_f32_e32 v125, v125
	v_add_f32_e32 v121, 1.0, v121
	v_mul_f32_e32 v122, 0xbfb8aa3b, v122
	v_mul_f32_e32 v124, 0xbfb8aa3b, v124
	v_exp_f32_e32 v122, v122
	v_rcp_f32_e32 v126, v121
	v_add_f32_e32 v121, 1.0, v125
	v_mul_f32_e32 v125, 0xbfb8aa3b, v127
	v_mul_f32_e32 v123, 0xbfb8aa3b, v123
	v_exp_f32_e32 v124, v124
	v_exp_f32_e32 v125, v125
	v_exp_f32_e32 v123, v123
	v_add_f32_e32 v122, 1.0, v122
	v_add_f32_e32 v124, 1.0, v124
	v_rcp_f32_e32 v127, v122
	v_add_f32_e32 v122, 1.0, v125
	v_add_f32_e32 v123, 1.0, v123
	v_rcp_f32_e32 v124, v124
	v_rcp_f32_e32 v120, v120
	v_rcp_f32_e32 v121, v121
	v_rcp_f32_e32 v122, v122
	v_rcp_f32_e32 v123, v123
	v_cvt_pk_bf16_f32 v120, v124, v120
	v_lshl_add_u64 v[124:125], v[138:139], 1, v[142:143]
	v_cvt_pk_bf16_f32 v121, v121, v122
	v_cvt_pk_bf16_f32 v122, v141, v126
	v_cvt_pk_bf16_f32 v123, v127, v123
	global_store_dwordx4 v[124:125], v[120:123], off
.LBB0_917:
	s_or_b64 exec, exec, s[4:5]
	s_nop 0
	v_add_u32_e32 v120, 0x80, v138
	v_cmp_gt_i32_e64 s[4:5], s65, v120
	s_and_saveexec_b64 s[20:21], s[4:5]
	s_cbranch_execz .LBB0_919
	v_mul_f32_e32 v112, 0xbfb8aa3b, v112
	v_exp_f32_e32 v112, v112
	v_mul_f32_e32 v117, 0xbfb8aa3b, v117
	v_exp_f32_e32 v117, v117
	v_mul_f32_e32 v113, 0xbfb8aa3b, v113
	v_add_f32_e32 v112, 1.0, v112
	v_exp_f32_e32 v113, v113
	v_rcp_f32_e32 v120, v112
	v_add_f32_e32 v112, 1.0, v117
	v_mul_f32_e32 v117, 0xbfb8aa3b, v118
	v_exp_f32_e32 v117, v117
	v_add_f32_e32 v113, 1.0, v113
	v_mul_f32_e32 v114, 0xbfb8aa3b, v114
	v_mul_f32_e32 v116, 0xbfb8aa3b, v116
	v_exp_f32_e32 v114, v114
	v_rcp_f32_e32 v118, v113
	v_add_f32_e32 v113, 1.0, v117
	v_mul_f32_e32 v117, 0xbfb8aa3b, v119
	v_mul_f32_e32 v115, 0xbfb8aa3b, v115
	v_exp_f32_e32 v116, v116
	v_exp_f32_e32 v117, v117
	v_exp_f32_e32 v115, v115
	v_add_f32_e32 v114, 1.0, v114
	v_add_f32_e32 v116, 1.0, v116
	v_rcp_f32_e32 v119, v114
	v_add_f32_e32 v114, 1.0, v117
	v_add_f32_e32 v115, 1.0, v115
	v_rcp_f32_e32 v116, v116
	v_rcp_f32_e32 v112, v112
	v_rcp_f32_e32 v113, v113
	v_rcp_f32_e32 v114, v114
	v_rcp_f32_e32 v115, v115
	v_cvt_pk_bf16_f32 v112, v116, v112
	v_lshl_add_u64 v[116:117], v[138:139], 1, v[142:143]
	v_cvt_pk_bf16_f32 v113, v113, v114
	v_cvt_pk_bf16_f32 v114, v120, v118
	v_cvt_pk_bf16_f32 v115, v119, v115
	global_store_dwordx4 v[116:117], v[112:115], off offset:256
.LBB0_919:
	s_or_b64 exec, exec, s[20:21]
	s_nop 0
	v_or_b32_e32 v112, 16, v140
	v_ashrrev_i32_e32 v113, 31, v112
	v_lshlrev_b64 v[112:113], 13, v[112:113]
	v_lshl_add_u64 v[112:113], s[8:9], 0, v[112:113]
	s_and_saveexec_b64 s[20:21], vcc
	s_cbranch_execz .LBB0_921
	v_mul_f32_e32 v104, 0xbfb8aa3b, v104
	v_exp_f32_e32 v104, v104
	v_mul_f32_e32 v109, 0xbfb8aa3b, v109
	v_exp_f32_e32 v109, v109
	v_mul_f32_e32 v105, 0xbfb8aa3b, v105
	v_add_f32_e32 v104, 1.0, v104
	v_exp_f32_e32 v105, v105
	v_rcp_f32_e32 v114, v104
	v_add_f32_e32 v104, 1.0, v109
	v_mul_f32_e32 v109, 0xbfb8aa3b, v110
	v_exp_f32_e32 v109, v109
	v_add_f32_e32 v105, 1.0, v105
	v_mul_f32_e32 v106, 0xbfb8aa3b, v106
	v_mul_f32_e32 v108, 0xbfb8aa3b, v108
	v_exp_f32_e32 v106, v106
	v_rcp_f32_e32 v110, v105
	v_add_f32_e32 v105, 1.0, v109
	v_mul_f32_e32 v109, 0xbfb8aa3b, v111
	v_mul_f32_e32 v107, 0xbfb8aa3b, v107
	v_exp_f32_e32 v108, v108
	v_exp_f32_e32 v109, v109
	v_exp_f32_e32 v107, v107
	v_add_f32_e32 v106, 1.0, v106
	v_add_f32_e32 v108, 1.0, v108
	v_rcp_f32_e32 v111, v106
	v_add_f32_e32 v106, 1.0, v109
	v_add_f32_e32 v107, 1.0, v107
	v_rcp_f32_e32 v108, v108
	v_rcp_f32_e32 v104, v104
	v_rcp_f32_e32 v105, v105
	v_rcp_f32_e32 v106, v106
	v_rcp_f32_e32 v107, v107
	v_cvt_pk_bf16_f32 v104, v108, v104
	v_lshl_add_u64 v[108:109], v[138:139], 1, v[112:113]
	v_cvt_pk_bf16_f32 v105, v105, v106
	v_cvt_pk_bf16_f32 v106, v114, v110
	v_cvt_pk_bf16_f32 v107, v111, v107
	global_store_dwordx4 v[108:109], v[104:107], off
.LBB0_921:
	s_or_b64 exec, exec, s[20:21]
	s_and_saveexec_b64 s[20:21], s[4:5]
	s_cbranch_execz .LBB0_923
	v_mul_f32_e32 v96, 0xbfb8aa3b, v96
	v_exp_f32_e32 v96, v96
	v_mul_f32_e32 v101, 0xbfb8aa3b, v101
	v_exp_f32_e32 v101, v101
	v_mul_f32_e32 v97, 0xbfb8aa3b, v97
	v_add_f32_e32 v96, 1.0, v96
	v_exp_f32_e32 v97, v97
	v_rcp_f32_e32 v104, v96
	v_add_f32_e32 v96, 1.0, v101
	v_mul_f32_e32 v101, 0xbfb8aa3b, v102
	v_exp_f32_e32 v101, v101
	v_add_f32_e32 v97, 1.0, v97
	v_mul_f32_e32 v98, 0xbfb8aa3b, v98
	v_mul_f32_e32 v100, 0xbfb8aa3b, v100
	v_exp_f32_e32 v98, v98
	v_rcp_f32_e32 v102, v97
	v_add_f32_e32 v97, 1.0, v101
	v_mul_f32_e32 v101, 0xbfb8aa3b, v103
	v_mul_f32_e32 v99, 0xbfb8aa3b, v99
	v_exp_f32_e32 v100, v100
	v_exp_f32_e32 v101, v101
	v_exp_f32_e32 v99, v99
	v_add_f32_e32 v98, 1.0, v98
	v_add_f32_e32 v100, 1.0, v100
	v_rcp_f32_e32 v103, v98
	v_add_f32_e32 v98, 1.0, v101
	v_add_f32_e32 v99, 1.0, v99
	v_rcp_f32_e32 v100, v100
	v_rcp_f32_e32 v96, v96
	v_rcp_f32_e32 v97, v97
	v_rcp_f32_e32 v98, v98
	v_rcp_f32_e32 v99, v99
	v_cvt_pk_bf16_f32 v96, v100, v96
	v_lshl_add_u64 v[100:101], v[138:139], 1, v[112:113]
	v_cvt_pk_bf16_f32 v97, v97, v98
	v_cvt_pk_bf16_f32 v98, v104, v102
	v_cvt_pk_bf16_f32 v99, v103, v99
	global_store_dwordx4 v[100:101], v[96:99], off offset:256
.LBB0_923:
	s_or_b64 exec, exec, s[20:21]
	s_nop 0
	v_or_b32_e32 v96, 32, v140
	v_ashrrev_i32_e32 v97, 31, v96
	v_lshlrev_b64 v[96:97], 13, v[96:97]
	v_lshl_add_u64 v[96:97], s[8:9], 0, v[96:97]
	s_and_saveexec_b64 s[20:21], vcc
	s_cbranch_execz .LBB0_925
	v_mul_f32_e32 v88, 0xbfb8aa3b, v88
	v_exp_f32_e32 v88, v88
	v_mul_f32_e32 v93, 0xbfb8aa3b, v93
	v_exp_f32_e32 v93, v93
	v_mul_f32_e32 v89, 0xbfb8aa3b, v89
	v_add_f32_e32 v88, 1.0, v88
	v_exp_f32_e32 v89, v89
	v_rcp_f32_e32 v98, v88
	v_add_f32_e32 v88, 1.0, v93
	v_mul_f32_e32 v93, 0xbfb8aa3b, v94
	v_exp_f32_e32 v93, v93
	v_add_f32_e32 v89, 1.0, v89
	v_mul_f32_e32 v90, 0xbfb8aa3b, v90
	v_mul_f32_e32 v92, 0xbfb8aa3b, v92
	v_exp_f32_e32 v90, v90
	v_rcp_f32_e32 v94, v89
	v_add_f32_e32 v89, 1.0, v93
	v_mul_f32_e32 v93, 0xbfb8aa3b, v95
	v_mul_f32_e32 v91, 0xbfb8aa3b, v91
	v_exp_f32_e32 v92, v92
	v_exp_f32_e32 v93, v93
	v_exp_f32_e32 v91, v91
	v_add_f32_e32 v90, 1.0, v90
	v_add_f32_e32 v92, 1.0, v92
	v_rcp_f32_e32 v95, v90
	v_add_f32_e32 v90, 1.0, v93
	v_add_f32_e32 v91, 1.0, v91
	v_rcp_f32_e32 v92, v92
	v_rcp_f32_e32 v88, v88
	v_rcp_f32_e32 v89, v89
	v_rcp_f32_e32 v90, v90
	v_rcp_f32_e32 v91, v91
	v_cvt_pk_bf16_f32 v88, v92, v88
	v_lshl_add_u64 v[92:93], v[138:139], 1, v[96:97]
	v_cvt_pk_bf16_f32 v89, v89, v90
	v_cvt_pk_bf16_f32 v90, v98, v94
	v_cvt_pk_bf16_f32 v91, v95, v91
	global_store_dwordx4 v[92:93], v[88:91], off
.LBB0_925:
	s_or_b64 exec, exec, s[20:21]
	s_and_saveexec_b64 s[20:21], s[4:5]
	s_cbranch_execz .LBB0_927
	v_mul_f32_e32 v80, 0xbfb8aa3b, v80
	v_exp_f32_e32 v80, v80
	v_mul_f32_e32 v85, 0xbfb8aa3b, v85
	v_exp_f32_e32 v85, v85
	v_mul_f32_e32 v81, 0xbfb8aa3b, v81
	v_add_f32_e32 v80, 1.0, v80
	v_exp_f32_e32 v81, v81
	v_rcp_f32_e32 v88, v80
	v_add_f32_e32 v80, 1.0, v85
	v_mul_f32_e32 v85, 0xbfb8aa3b, v86
	v_exp_f32_e32 v85, v85
	v_add_f32_e32 v81, 1.0, v81
	v_mul_f32_e32 v82, 0xbfb8aa3b, v82
	v_mul_f32_e32 v84, 0xbfb8aa3b, v84
	v_exp_f32_e32 v82, v82
	v_rcp_f32_e32 v86, v81
	v_add_f32_e32 v81, 1.0, v85
	v_mul_f32_e32 v85, 0xbfb8aa3b, v87
	v_mul_f32_e32 v83, 0xbfb8aa3b, v83
	v_exp_f32_e32 v84, v84
	v_exp_f32_e32 v85, v85
	v_exp_f32_e32 v83, v83
	v_add_f32_e32 v82, 1.0, v82
	v_add_f32_e32 v84, 1.0, v84
	v_rcp_f32_e32 v87, v82
	v_add_f32_e32 v82, 1.0, v85
	v_add_f32_e32 v83, 1.0, v83
	v_rcp_f32_e32 v84, v84
	v_rcp_f32_e32 v80, v80
	v_rcp_f32_e32 v81, v81
	v_rcp_f32_e32 v82, v82
	v_rcp_f32_e32 v83, v83
	v_cvt_pk_bf16_f32 v80, v84, v80
	v_lshl_add_u64 v[84:85], v[138:139], 1, v[96:97]
	v_cvt_pk_bf16_f32 v81, v81, v82
	v_cvt_pk_bf16_f32 v82, v88, v86
	v_cvt_pk_bf16_f32 v83, v87, v83
	global_store_dwordx4 v[84:85], v[80:83], off offset:256
.LBB0_927:
	s_or_b64 exec, exec, s[20:21]
	s_nop 0
	v_or_b32_e32 v80, 48, v140
	v_ashrrev_i32_e32 v81, 31, v80
	v_lshlrev_b64 v[80:81], 13, v[80:81]
	v_lshl_add_u64 v[80:81], s[8:9], 0, v[80:81]
	s_and_saveexec_b64 s[20:21], vcc
	s_cbranch_execz .LBB0_929
	v_mul_f32_e32 v72, 0xbfb8aa3b, v72
	v_exp_f32_e32 v72, v72
	v_mul_f32_e32 v77, 0xbfb8aa3b, v77
	v_exp_f32_e32 v77, v77
	v_mul_f32_e32 v73, 0xbfb8aa3b, v73
	v_add_f32_e32 v72, 1.0, v72
	v_exp_f32_e32 v73, v73
	v_rcp_f32_e32 v82, v72
	v_add_f32_e32 v72, 1.0, v77
	v_mul_f32_e32 v77, 0xbfb8aa3b, v78
	v_exp_f32_e32 v77, v77
	v_add_f32_e32 v73, 1.0, v73
	v_mul_f32_e32 v74, 0xbfb8aa3b, v74
	v_mul_f32_e32 v76, 0xbfb8aa3b, v76
	v_exp_f32_e32 v74, v74
	v_rcp_f32_e32 v78, v73
	v_add_f32_e32 v73, 1.0, v77
	v_mul_f32_e32 v77, 0xbfb8aa3b, v79
	v_mul_f32_e32 v75, 0xbfb8aa3b, v75
	v_exp_f32_e32 v76, v76
	v_exp_f32_e32 v77, v77
	v_exp_f32_e32 v75, v75
	v_add_f32_e32 v74, 1.0, v74
	v_add_f32_e32 v76, 1.0, v76
	v_rcp_f32_e32 v79, v74
	v_add_f32_e32 v74, 1.0, v77
	v_add_f32_e32 v75, 1.0, v75
	v_rcp_f32_e32 v76, v76
	v_rcp_f32_e32 v72, v72
	v_rcp_f32_e32 v73, v73
	v_rcp_f32_e32 v74, v74
	v_rcp_f32_e32 v75, v75
	v_cvt_pk_bf16_f32 v72, v76, v72
	v_lshl_add_u64 v[76:77], v[138:139], 1, v[80:81]
	v_cvt_pk_bf16_f32 v73, v73, v74
	v_cvt_pk_bf16_f32 v74, v82, v78
	v_cvt_pk_bf16_f32 v75, v79, v75
	global_store_dwordx4 v[76:77], v[72:75], off
.LBB0_929:
	s_or_b64 exec, exec, s[20:21]
	s_and_saveexec_b64 s[20:21], s[4:5]
	s_cbranch_execz .LBB0_931
	v_mul_f32_e32 v64, 0xbfb8aa3b, v64
	v_exp_f32_e32 v64, v64
	v_mul_f32_e32 v69, 0xbfb8aa3b, v69
	v_exp_f32_e32 v69, v69
	v_mul_f32_e32 v65, 0xbfb8aa3b, v65
	v_add_f32_e32 v64, 1.0, v64
	v_exp_f32_e32 v65, v65
	v_rcp_f32_e32 v72, v64
	v_add_f32_e32 v64, 1.0, v69
	v_mul_f32_e32 v69, 0xbfb8aa3b, v70
	v_exp_f32_e32 v69, v69
	v_add_f32_e32 v65, 1.0, v65
	v_mul_f32_e32 v66, 0xbfb8aa3b, v66
	v_mul_f32_e32 v68, 0xbfb8aa3b, v68
	v_exp_f32_e32 v66, v66
	v_rcp_f32_e32 v70, v65
	v_add_f32_e32 v65, 1.0, v69
	v_mul_f32_e32 v69, 0xbfb8aa3b, v71
	v_mul_f32_e32 v67, 0xbfb8aa3b, v67
	v_exp_f32_e32 v68, v68
	v_exp_f32_e32 v69, v69
	v_exp_f32_e32 v67, v67
	v_add_f32_e32 v66, 1.0, v66
	v_add_f32_e32 v68, 1.0, v68
	v_rcp_f32_e32 v71, v66
	v_add_f32_e32 v66, 1.0, v69
	v_add_f32_e32 v67, 1.0, v67
	v_rcp_f32_e32 v68, v68
	v_rcp_f32_e32 v64, v64
	v_rcp_f32_e32 v65, v65
	v_rcp_f32_e32 v66, v66
	v_rcp_f32_e32 v67, v67
	v_cvt_pk_bf16_f32 v64, v68, v64
	v_lshl_add_u64 v[68:69], v[138:139], 1, v[80:81]
	v_cvt_pk_bf16_f32 v65, v65, v66
	v_cvt_pk_bf16_f32 v66, v72, v70
	v_cvt_pk_bf16_f32 v67, v71, v67
	global_store_dwordx4 v[68:69], v[64:67], off offset:256
.LBB0_931:
	s_or_b64 exec, exec, s[20:21]
	s_nop 0
	v_add_u32_e32 v64, 0x80, v140
	v_ashrrev_i32_e32 v65, 31, v64
	v_lshlrev_b64 v[64:65], 13, v[64:65]
	v_lshl_add_u64 v[64:65], s[8:9], 0, v[64:65]
	s_and_saveexec_b64 s[20:21], vcc
	s_cbranch_execz .LBB0_933
	v_mul_f32_e32 v56, 0xbfb8aa3b, v56
	v_exp_f32_e32 v56, v56
	v_mul_f32_e32 v61, 0xbfb8aa3b, v61
	v_exp_f32_e32 v61, v61
	v_mul_f32_e32 v57, 0xbfb8aa3b, v57
	v_add_f32_e32 v56, 1.0, v56
	v_exp_f32_e32 v57, v57
	v_rcp_f32_e32 v66, v56
	v_add_f32_e32 v56, 1.0, v61
	v_mul_f32_e32 v61, 0xbfb8aa3b, v62
	v_exp_f32_e32 v61, v61
	v_add_f32_e32 v57, 1.0, v57
	v_mul_f32_e32 v58, 0xbfb8aa3b, v58
	v_mul_f32_e32 v60, 0xbfb8aa3b, v60
	v_exp_f32_e32 v58, v58
	v_rcp_f32_e32 v62, v57
	v_add_f32_e32 v57, 1.0, v61
	v_mul_f32_e32 v61, 0xbfb8aa3b, v63
	v_mul_f32_e32 v59, 0xbfb8aa3b, v59
	v_exp_f32_e32 v60, v60
	v_exp_f32_e32 v61, v61
	v_exp_f32_e32 v59, v59
	v_add_f32_e32 v58, 1.0, v58
	v_add_f32_e32 v60, 1.0, v60
	v_rcp_f32_e32 v63, v58
	v_add_f32_e32 v58, 1.0, v61
	v_add_f32_e32 v59, 1.0, v59
	v_rcp_f32_e32 v60, v60
	v_rcp_f32_e32 v56, v56
	v_rcp_f32_e32 v57, v57
	v_rcp_f32_e32 v58, v58
	v_rcp_f32_e32 v59, v59
	v_cvt_pk_bf16_f32 v56, v60, v56
	v_lshl_add_u64 v[60:61], v[138:139], 1, v[64:65]
	v_cvt_pk_bf16_f32 v57, v57, v58
	v_cvt_pk_bf16_f32 v58, v66, v62
	v_cvt_pk_bf16_f32 v59, v63, v59
	global_store_dwordx4 v[60:61], v[56:59], off
.LBB0_933:
	s_or_b64 exec, exec, s[20:21]
	s_and_saveexec_b64 s[20:21], s[4:5]
	s_cbranch_execz .LBB0_935
	v_mul_f32_e32 v48, 0xbfb8aa3b, v48
	v_exp_f32_e32 v48, v48
	v_mul_f32_e32 v53, 0xbfb8aa3b, v53
	v_exp_f32_e32 v53, v53
	v_mul_f32_e32 v49, 0xbfb8aa3b, v49
	v_add_f32_e32 v48, 1.0, v48
	v_exp_f32_e32 v49, v49
	v_rcp_f32_e32 v56, v48
	v_add_f32_e32 v48, 1.0, v53
	v_mul_f32_e32 v53, 0xbfb8aa3b, v54
	v_exp_f32_e32 v53, v53
	v_add_f32_e32 v49, 1.0, v49
	v_mul_f32_e32 v50, 0xbfb8aa3b, v50
	v_mul_f32_e32 v52, 0xbfb8aa3b, v52
	v_exp_f32_e32 v50, v50
	v_rcp_f32_e32 v54, v49
	v_add_f32_e32 v49, 1.0, v53
	v_mul_f32_e32 v53, 0xbfb8aa3b, v55
	v_mul_f32_e32 v51, 0xbfb8aa3b, v51
	v_exp_f32_e32 v52, v52
	v_exp_f32_e32 v53, v53
	v_exp_f32_e32 v51, v51
	v_add_f32_e32 v50, 1.0, v50
	v_add_f32_e32 v52, 1.0, v52
	v_rcp_f32_e32 v55, v50
	v_add_f32_e32 v50, 1.0, v53
	v_add_f32_e32 v51, 1.0, v51
	v_rcp_f32_e32 v52, v52
	v_rcp_f32_e32 v48, v48
	v_rcp_f32_e32 v49, v49
	v_rcp_f32_e32 v50, v50
	v_rcp_f32_e32 v51, v51
	v_cvt_pk_bf16_f32 v48, v52, v48
	v_lshl_add_u64 v[52:53], v[138:139], 1, v[64:65]
	v_cvt_pk_bf16_f32 v49, v49, v50
	v_cvt_pk_bf16_f32 v50, v56, v54
	v_cvt_pk_bf16_f32 v51, v55, v51
	global_store_dwordx4 v[52:53], v[48:51], off offset:256
.LBB0_935:
	s_or_b64 exec, exec, s[20:21]
	s_nop 0
	v_add_u32_e32 v48, 0x90, v140
	v_ashrrev_i32_e32 v49, 31, v48
	v_lshlrev_b64 v[48:49], 13, v[48:49]
	v_lshl_add_u64 v[48:49], s[8:9], 0, v[48:49]
	s_and_saveexec_b64 s[20:21], vcc
	s_cbranch_execz .LBB0_937
	v_mul_f32_e32 v40, 0xbfb8aa3b, v40
	v_exp_f32_e32 v40, v40
	v_mul_f32_e32 v45, 0xbfb8aa3b, v45
	v_exp_f32_e32 v45, v45
	v_mul_f32_e32 v41, 0xbfb8aa3b, v41
	v_add_f32_e32 v40, 1.0, v40
	v_exp_f32_e32 v41, v41
	v_rcp_f32_e32 v50, v40
	v_add_f32_e32 v40, 1.0, v45
	v_mul_f32_e32 v45, 0xbfb8aa3b, v46
	v_exp_f32_e32 v45, v45
	v_add_f32_e32 v41, 1.0, v41
	v_mul_f32_e32 v42, 0xbfb8aa3b, v42
	v_mul_f32_e32 v44, 0xbfb8aa3b, v44
	v_exp_f32_e32 v42, v42
	v_rcp_f32_e32 v46, v41
	v_add_f32_e32 v41, 1.0, v45
	v_mul_f32_e32 v45, 0xbfb8aa3b, v47
	v_mul_f32_e32 v43, 0xbfb8aa3b, v43
	v_exp_f32_e32 v44, v44
	v_exp_f32_e32 v45, v45
	v_exp_f32_e32 v43, v43
	v_add_f32_e32 v42, 1.0, v42
	v_add_f32_e32 v44, 1.0, v44
	v_rcp_f32_e32 v47, v42
	v_add_f32_e32 v42, 1.0, v45
	v_add_f32_e32 v43, 1.0, v43
	v_rcp_f32_e32 v44, v44
	v_rcp_f32_e32 v40, v40
	v_rcp_f32_e32 v41, v41
	v_rcp_f32_e32 v42, v42
	v_rcp_f32_e32 v43, v43
	v_cvt_pk_bf16_f32 v40, v44, v40
	v_lshl_add_u64 v[44:45], v[138:139], 1, v[48:49]
	v_cvt_pk_bf16_f32 v41, v41, v42
	v_cvt_pk_bf16_f32 v42, v50, v46
	v_cvt_pk_bf16_f32 v43, v47, v43
	global_store_dwordx4 v[44:45], v[40:43], off
.LBB0_937:
	s_or_b64 exec, exec, s[20:21]
	s_and_saveexec_b64 s[20:21], s[4:5]
	s_cbranch_execz .LBB0_939
	v_mul_f32_e32 v32, 0xbfb8aa3b, v32
	v_exp_f32_e32 v32, v32
	v_mul_f32_e32 v37, 0xbfb8aa3b, v37
	v_exp_f32_e32 v37, v37
	v_mul_f32_e32 v33, 0xbfb8aa3b, v33
	v_add_f32_e32 v32, 1.0, v32
	v_exp_f32_e32 v33, v33
	v_rcp_f32_e32 v40, v32
	v_add_f32_e32 v32, 1.0, v37
	v_mul_f32_e32 v37, 0xbfb8aa3b, v38
	v_exp_f32_e32 v37, v37
	v_add_f32_e32 v33, 1.0, v33
	v_mul_f32_e32 v34, 0xbfb8aa3b, v34
	v_mul_f32_e32 v36, 0xbfb8aa3b, v36
	v_exp_f32_e32 v34, v34
	v_rcp_f32_e32 v38, v33
	v_add_f32_e32 v33, 1.0, v37
	v_mul_f32_e32 v37, 0xbfb8aa3b, v39
	v_mul_f32_e32 v35, 0xbfb8aa3b, v35
	v_exp_f32_e32 v36, v36
	v_exp_f32_e32 v37, v37
	v_exp_f32_e32 v35, v35
	v_add_f32_e32 v34, 1.0, v34
	v_add_f32_e32 v36, 1.0, v36
	v_rcp_f32_e32 v39, v34
	v_add_f32_e32 v34, 1.0, v37
	v_add_f32_e32 v35, 1.0, v35
	v_rcp_f32_e32 v36, v36
	v_rcp_f32_e32 v32, v32
	v_rcp_f32_e32 v33, v33
	v_rcp_f32_e32 v34, v34
	v_rcp_f32_e32 v35, v35
	v_cvt_pk_bf16_f32 v32, v36, v32
	v_lshl_add_u64 v[36:37], v[138:139], 1, v[48:49]
	v_cvt_pk_bf16_f32 v33, v33, v34
	v_cvt_pk_bf16_f32 v34, v40, v38
	v_cvt_pk_bf16_f32 v35, v39, v35
	global_store_dwordx4 v[36:37], v[32:35], off offset:256
.LBB0_939:
	s_or_b64 exec, exec, s[20:21]
	s_nop 0
	v_add_u32_e32 v32, 0xa0, v140
	v_ashrrev_i32_e32 v33, 31, v32
	v_lshlrev_b64 v[32:33], 13, v[32:33]
	v_lshl_add_u64 v[32:33], s[8:9], 0, v[32:33]
	s_and_saveexec_b64 s[20:21], vcc
	s_cbranch_execz .LBB0_941
	v_mul_f32_e32 v24, 0xbfb8aa3b, v24
	v_exp_f32_e32 v24, v24
	v_mul_f32_e32 v29, 0xbfb8aa3b, v29
	v_exp_f32_e32 v29, v29
	v_mul_f32_e32 v25, 0xbfb8aa3b, v25
	v_add_f32_e32 v24, 1.0, v24
	v_exp_f32_e32 v25, v25
	v_rcp_f32_e32 v34, v24
	v_add_f32_e32 v24, 1.0, v29
	v_mul_f32_e32 v29, 0xbfb8aa3b, v30
	v_exp_f32_e32 v29, v29
	v_add_f32_e32 v25, 1.0, v25
	v_mul_f32_e32 v26, 0xbfb8aa3b, v26
	v_mul_f32_e32 v28, 0xbfb8aa3b, v28
	v_exp_f32_e32 v26, v26
	v_rcp_f32_e32 v30, v25
	v_add_f32_e32 v25, 1.0, v29
	v_mul_f32_e32 v29, 0xbfb8aa3b, v31
	v_mul_f32_e32 v27, 0xbfb8aa3b, v27
	v_exp_f32_e32 v28, v28
	v_exp_f32_e32 v29, v29
	v_exp_f32_e32 v27, v27
	v_add_f32_e32 v26, 1.0, v26
	v_add_f32_e32 v28, 1.0, v28
	v_rcp_f32_e32 v31, v26
	v_add_f32_e32 v26, 1.0, v29
	v_add_f32_e32 v27, 1.0, v27
	v_rcp_f32_e32 v28, v28
	v_rcp_f32_e32 v24, v24
	v_rcp_f32_e32 v25, v25
	v_rcp_f32_e32 v26, v26
	v_rcp_f32_e32 v27, v27
	v_cvt_pk_bf16_f32 v24, v28, v24
	v_lshl_add_u64 v[28:29], v[138:139], 1, v[32:33]
	v_cvt_pk_bf16_f32 v25, v25, v26
	v_cvt_pk_bf16_f32 v26, v34, v30
	v_cvt_pk_bf16_f32 v27, v31, v27
	global_store_dwordx4 v[28:29], v[24:27], off
.LBB0_941:
	s_or_b64 exec, exec, s[20:21]
	s_and_saveexec_b64 s[20:21], s[4:5]
	s_cbranch_execz .LBB0_943
	v_mul_f32_e32 v16, 0xbfb8aa3b, v16
	v_exp_f32_e32 v16, v16
	v_mul_f32_e32 v21, 0xbfb8aa3b, v21
	v_exp_f32_e32 v21, v21
	v_mul_f32_e32 v17, 0xbfb8aa3b, v17
	v_add_f32_e32 v16, 1.0, v16
	v_exp_f32_e32 v17, v17
	v_rcp_f32_e32 v24, v16
	v_add_f32_e32 v16, 1.0, v21
	v_mul_f32_e32 v21, 0xbfb8aa3b, v22
	v_exp_f32_e32 v21, v21
	v_add_f32_e32 v17, 1.0, v17
	v_mul_f32_e32 v18, 0xbfb8aa3b, v18
	v_mul_f32_e32 v20, 0xbfb8aa3b, v20
	v_exp_f32_e32 v18, v18
	v_rcp_f32_e32 v22, v17
	v_add_f32_e32 v17, 1.0, v21
	v_mul_f32_e32 v21, 0xbfb8aa3b, v23
	v_mul_f32_e32 v19, 0xbfb8aa3b, v19
	v_exp_f32_e32 v20, v20
	v_exp_f32_e32 v21, v21
	v_exp_f32_e32 v19, v19
	v_add_f32_e32 v18, 1.0, v18
	v_add_f32_e32 v20, 1.0, v20
	v_rcp_f32_e32 v23, v18
	v_add_f32_e32 v18, 1.0, v21
	v_add_f32_e32 v19, 1.0, v19
	v_rcp_f32_e32 v20, v20
	v_rcp_f32_e32 v16, v16
	v_rcp_f32_e32 v17, v17
	v_rcp_f32_e32 v18, v18
	v_rcp_f32_e32 v19, v19
	v_cvt_pk_bf16_f32 v16, v20, v16
	v_lshl_add_u64 v[20:21], v[138:139], 1, v[32:33]
	v_cvt_pk_bf16_f32 v17, v17, v18
	v_cvt_pk_bf16_f32 v18, v24, v22
	v_cvt_pk_bf16_f32 v19, v23, v19
	global_store_dwordx4 v[20:21], v[16:19], off offset:256
.LBB0_943:
	s_or_b64 exec, exec, s[20:21]
	s_nop 0
	v_add_u32_e32 v16, 0xb0, v140
	v_ashrrev_i32_e32 v17, 31, v16
	v_lshlrev_b64 v[16:17], 13, v[16:17]
	v_lshl_add_u64 v[16:17], s[8:9], 0, v[16:17]
	s_and_saveexec_b64 s[20:21], vcc
	s_cbranch_execz .LBB0_945
	v_mul_f32_e32 v8, 0xbfb8aa3b, v8
	v_exp_f32_e32 v8, v8
	v_mul_f32_e32 v13, 0xbfb8aa3b, v13
	v_exp_f32_e32 v13, v13
	v_mul_f32_e32 v9, 0xbfb8aa3b, v9
	v_add_f32_e32 v8, 1.0, v8
	v_exp_f32_e32 v9, v9
	v_rcp_f32_e32 v18, v8
	v_add_f32_e32 v8, 1.0, v13
	v_mul_f32_e32 v13, 0xbfb8aa3b, v14
	v_exp_f32_e32 v13, v13
	v_add_f32_e32 v9, 1.0, v9
	v_mul_f32_e32 v10, 0xbfb8aa3b, v10
	v_mul_f32_e32 v12, 0xbfb8aa3b, v12
	v_exp_f32_e32 v10, v10
	v_rcp_f32_e32 v14, v9
	v_add_f32_e32 v9, 1.0, v13
	v_mul_f32_e32 v13, 0xbfb8aa3b, v15
	v_mul_f32_e32 v11, 0xbfb8aa3b, v11
	v_exp_f32_e32 v12, v12
	v_exp_f32_e32 v13, v13
	v_exp_f32_e32 v11, v11
	v_add_f32_e32 v10, 1.0, v10
	v_add_f32_e32 v12, 1.0, v12
	v_rcp_f32_e32 v15, v10
	v_add_f32_e32 v10, 1.0, v13
	v_add_f32_e32 v11, 1.0, v11
	v_rcp_f32_e32 v12, v12
	v_rcp_f32_e32 v8, v8
	v_rcp_f32_e32 v9, v9
	v_rcp_f32_e32 v10, v10
	v_rcp_f32_e32 v11, v11
	v_cvt_pk_bf16_f32 v8, v12, v8
	v_lshl_add_u64 v[12:13], v[138:139], 1, v[16:17]
	v_cvt_pk_bf16_f32 v9, v9, v10
	v_cvt_pk_bf16_f32 v10, v18, v14
	v_cvt_pk_bf16_f32 v11, v15, v11
	global_store_dwordx4 v[12:13], v[8:11], off
.LBB0_945:
	s_or_b64 exec, exec, s[20:21]
	s_and_saveexec_b64 s[20:21], s[4:5]
	s_cbranch_execz .LBB0_947
	v_mul_f32_e32 v0, 0xbfb8aa3b, v0
	v_exp_f32_e32 v0, v0
	v_mul_f32_e32 v5, 0xbfb8aa3b, v5
	v_exp_f32_e32 v5, v5
	v_mul_f32_e32 v1, 0xbfb8aa3b, v1
	v_add_f32_e32 v0, 1.0, v0
	v_exp_f32_e32 v1, v1
	v_rcp_f32_e32 v8, v0
	v_add_f32_e32 v0, 1.0, v5
	v_mul_f32_e32 v5, 0xbfb8aa3b, v6
	v_exp_f32_e32 v5, v5
	v_add_f32_e32 v1, 1.0, v1
	v_mul_f32_e32 v2, 0xbfb8aa3b, v2
	v_mul_f32_e32 v4, 0xbfb8aa3b, v4
	v_exp_f32_e32 v2, v2
	v_rcp_f32_e32 v6, v1
	v_add_f32_e32 v1, 1.0, v5
	v_mul_f32_e32 v5, 0xbfb8aa3b, v7
	v_mul_f32_e32 v3, 0xbfb8aa3b, v3
	v_exp_f32_e32 v4, v4
	v_exp_f32_e32 v5, v5
	v_exp_f32_e32 v3, v3
	v_add_f32_e32 v2, 1.0, v2
	v_add_f32_e32 v4, 1.0, v4
	v_rcp_f32_e32 v7, v2
	v_add_f32_e32 v2, 1.0, v5
	v_add_f32_e32 v3, 1.0, v3
	v_rcp_f32_e32 v4, v4
	v_rcp_f32_e32 v0, v0
	v_rcp_f32_e32 v1, v1
	v_rcp_f32_e32 v2, v2
	v_rcp_f32_e32 v3, v3
	v_cvt_pk_bf16_f32 v0, v4, v0
	v_lshl_add_u64 v[4:5], v[138:139], 1, v[16:17]
	v_cvt_pk_bf16_f32 v1, v1, v2
	v_cvt_pk_bf16_f32 v2, v8, v6
	v_cvt_pk_bf16_f32 v3, v7, v3
	global_store_dwordx4 v[4:5], v[0:3], off offset:256

.LBB0_1020:
	s_lshl_b32 s13, s20, 8
	s_lshl_b32 s20, s5, 10
	v_mbcnt_lo_u32_b32 v16, -1, 0
	v_mbcnt_hi_u32_b32 v16, -1, v16
	s_lshl_b32 s4, s4, 8
	v_and_or_b32 v176, v16, 15, s45
	s_ashr_i32 s21, s20, 31
	v_ashrrev_i32_e32 v16, 1, v16
	v_add_u32_e32 v168, s13, v176
	s_or_b32 s4, s4, s46
	s_lshl_b64 s[20:21], s[20:21], 1
	v_and_b32_e32 v16, -8, v16
	s_add_u32 s20, s43, s20
	v_ashrrev_i32_e32 v169, 31, v168
	v_add_u32_e32 v166, s4, v16
	s_addc_u32 s21, s44, s21
	v_lshlrev_b64 v[16:17], 13, v[168:169]
	v_lshl_add_u64 v[16:17], s[20:21], 0, v[16:17]
	v_ashrrev_i32_e32 v167, 31, v166
	v_lshl_add_u64 v[16:17], v[166:167], 1, v[16:17]
	global_load_dwordx4 v[156:159], v[16:17], off
	v_lshlrev_b64 v[18:19], 11, v[168:169]
	s_cmp_lg_u32 s5, 0
	v_lshl_add_u64 v[18:19], s[8:9], 0, v[18:19]
	s_cselect_b64 s[22:23], -1, 0
	s_cmp_eq_u32 s5, 0
	v_lshl_add_u64 v[172:173], v[166:167], 1, v[18:19]
	s_cbranch_scc1 .LBB0_1022
	global_load_dwordx4 v[44:47], v[172:173], off
.LBB0_1022:
	global_load_dwordx4 v[152:155], v[16:17], off offset:256
	v_cndmask_b32_e64 v16, 0, 1, s[22:23]
	v_cmp_ne_u32_e64 s[4:5], 1, v16
	s_andn2_b64 vcc, exec, s[22:23]
	v_mov_b64_e32 v[230:231], v[250:251]
	v_mov_b32_e32 v243, v249
	v_mov_b32_e32 v251, v248
	s_cbranch_vccnz .LBB0_1024
	global_load_dwordx4 v[32:35], v[172:173], off offset:256
.LBB0_1024:
	v_or_b32_e32 v18, 16, v168
	v_ashrrev_i32_e32 v19, 31, v18
	v_lshlrev_b64 v[16:17], 13, v[18:19]
	v_lshl_add_u64 v[16:17], s[20:21], 0, v[16:17]
	v_lshl_add_u64 v[16:17], v[166:167], 1, v[16:17]
	global_load_dwordx4 v[148:151], v[16:17], off
	v_lshlrev_b64 v[18:19], 11, v[18:19]
	v_lshl_add_u64 v[18:19], s[8:9], 0, v[18:19]
	s_and_b64 vcc, exec, s[4:5]
	v_lshl_add_u64 v[170:171], v[166:167], 1, v[18:19]
	v_mov_b32_e32 v249, 0x358637bd
	s_cbranch_vccnz .LBB0_1026
	global_load_dwordx4 v[24:27], v[170:171], off
.LBB0_1026:
	global_load_dwordx4 v[136:139], v[16:17], off offset:256
	s_and_b64 vcc, exec, s[4:5]
	v_mov_b32_e32 v248, 0x260
	s_cbranch_vccnz .LBB0_1028
	global_load_dwordx4 v[16:19], v[170:171], off offset:256

.LBB0_1030:
	v_cvt_pk_bf16_f32 v144, v144, v145
	v_cvt_pk_bf16_f32 v145, v146, v147
	v_cvt_pk_bf16_f32 v146, v140, v141
	v_lshlrev_b32_e32 v140, 16, v152
	v_and_b32_e32 v141, 0xffff0000, v152
	v_pk_mul_f32 v[132:133], v[132:133], v[140:141]
	v_lshlrev_b32_e32 v140, 16, v153
	v_and_b32_e32 v141, 0xffff0000, v153
	v_pk_mul_f32 v[134:135], v[134:135], v[140:141]
	v_lshlrev_b32_e32 v140, 16, v154
	v_and_b32_e32 v141, 0xffff0000, v154
	v_pk_mul_f32 v[128:129], v[128:129], v[140:141]
	v_lshlrev_b32_e32 v140, 16, v155
	v_and_b32_e32 v141, 0xffff0000, v155
	v_cvt_pk_bf16_f32 v147, v142, v143
	s_and_b64 vcc, exec, s[4:5]
	v_pk_mul_f32 v[130:131], v[130:131], v[140:141]
	global_store_dwordx4 v[172:173], v[144:147], off
	s_cbranch_vccnz .LBB0_1032
	v_lshlrev_b32_e32 v140, 16, v32
	v_and_b32_e32 v141, 0xffff0000, v32
	v_pk_add_f32 v[132:133], v[132:133], v[140:141]
	v_lshlrev_b32_e32 v140, 16, v33
	v_and_b32_e32 v141, 0xffff0000, v33
	v_pk_add_f32 v[134:135], v[134:135], v[140:141]
	v_lshlrev_b32_e32 v140, 16, v34
	v_and_b32_e32 v141, 0xffff0000, v34
	v_pk_add_f32 v[128:129], v[128:129], v[140:141]
	v_lshlrev_b32_e32 v140, 16, v35
	v_and_b32_e32 v141, 0xffff0000, v35
	v_pk_add_f32 v[130:131], v[130:131], v[140:141]
.LBB0_1032:
	v_cvt_pk_bf16_f32 v132, v132, v133
	v_cvt_pk_bf16_f32 v133, v134, v135
	v_cvt_pk_bf16_f32 v134, v128, v129
	v_lshlrev_b32_e32 v128, 16, v148
	v_and_b32_e32 v129, 0xffff0000, v148
	v_pk_mul_f32 v[124:125], v[124:125], v[128:129]
	v_lshlrev_b32_e32 v128, 16, v149
	v_and_b32_e32 v129, 0xffff0000, v149
	v_pk_mul_f32 v[126:127], v[126:127], v[128:129]
	v_lshlrev_b32_e32 v128, 16, v150
	v_and_b32_e32 v129, 0xffff0000, v150
	v_pk_mul_f32 v[120:121], v[120:121], v[128:129]
	v_lshlrev_b32_e32 v128, 16, v151
	v_and_b32_e32 v129, 0xffff0000, v151
	v_cvt_pk_bf16_f32 v135, v130, v131
	s_and_b64 vcc, exec, s[4:5]
	v_pk_mul_f32 v[122:123], v[122:123], v[128:129]
	global_store_dwordx4 v[172:173], v[132:135], off offset:256
	s_cbranch_vccnz .LBB0_1034
	v_lshlrev_b32_e32 v128, 16, v24
	v_and_b32_e32 v129, 0xffff0000, v24
	v_pk_add_f32 v[124:125], v[124:125], v[128:129]
	v_lshlrev_b32_e32 v128, 16, v25
	v_and_b32_e32 v129, 0xffff0000, v25
	v_pk_add_f32 v[126:127], v[126:127], v[128:129]
	v_lshlrev_b32_e32 v128, 16, v26
	v_and_b32_e32 v129, 0xffff0000, v26
	v_pk_add_f32 v[120:121], v[120:121], v[128:129]
	v_lshlrev_b32_e32 v128, 16, v27
	v_and_b32_e32 v129, 0xffff0000, v27
	v_pk_add_f32 v[122:123], v[122:123], v[128:129]
.LBB0_1034:
	v_cvt_pk_bf16_f32 v124, v124, v125
	v_cvt_pk_bf16_f32 v125, v126, v127
	v_cvt_pk_bf16_f32 v126, v120, v121
	v_lshlrev_b32_e32 v120, 16, v136
	v_and_b32_e32 v121, 0xffff0000, v136
	v_pk_mul_f32 v[116:117], v[116:117], v[120:121]
	v_lshlrev_b32_e32 v120, 16, v137
	v_and_b32_e32 v121, 0xffff0000, v137
	v_pk_mul_f32 v[118:119], v[118:119], v[120:121]
	v_lshlrev_b32_e32 v120, 16, v138
	v_and_b32_e32 v121, 0xffff0000, v138
	v_pk_mul_f32 v[112:113], v[112:113], v[120:121]
	v_lshlrev_b32_e32 v120, 16, v139
	v_and_b32_e32 v121, 0xffff0000, v139
	v_cvt_pk_bf16_f32 v127, v122, v123
	s_and_b64 vcc, exec, s[4:5]
	v_pk_mul_f32 v[114:115], v[114:115], v[120:121]
	global_store_dwordx4 v[170:171], v[124:127], off
	s_cbranch_vccnz .LBB0_1036
	v_lshlrev_b32_e32 v120, 16, v16
	v_and_b32_e32 v121, 0xffff0000, v16
	v_pk_add_f32 v[116:117], v[116:117], v[120:121]
	v_lshlrev_b32_e32 v120, 16, v17
	v_and_b32_e32 v121, 0xffff0000, v17
	v_pk_add_f32 v[118:119], v[118:119], v[120:121]
	v_lshlrev_b32_e32 v120, 16, v18
	v_and_b32_e32 v121, 0xffff0000, v18
	v_pk_add_f32 v[112:113], v[112:113], v[120:121]
	v_lshlrev_b32_e32 v120, 16, v19
	v_and_b32_e32 v121, 0xffff0000, v19
	v_pk_add_f32 v[114:115], v[114:115], v[120:121]
.LBB0_1036:
	v_cvt_pk_bf16_f32 v116, v116, v117
	v_cvt_pk_bf16_f32 v117, v118, v119
	v_cvt_pk_bf16_f32 v118, v112, v113
	v_add3_u32 v112, s13, v176, 32
	v_ashrrev_i32_e32 v113, 31, v112
	v_cvt_pk_bf16_f32 v119, v114, v115
	v_lshlrev_b64 v[114:115], 13, v[112:113]
	global_store_dwordx4 v[170:171], v[116:119], off offset:256
	v_lshl_add_u64 v[114:115], s[20:21], 0, v[114:115]
	v_lshl_add_u64 v[114:115], v[166:167], 1, v[114:115]
	global_load_dwordx4 v[124:127], v[114:115], off
	v_lshlrev_b64 v[116:117], 11, v[112:113]
	v_lshl_add_u64 v[116:117], s[8:9], 0, v[116:117]
	s_and_b64 vcc, exec, s[4:5]
	v_lshl_add_u64 v[128:129], v[166:167], 1, v[116:117]
	s_cbranch_vccnz .LBB0_1038
	global_load_dwordx4 v[44:47], v[128:129], off
.LBB0_1038:
	global_load_dwordx4 v[120:123], v[114:115], off offset:256
	s_and_b64 vcc, exec, s[4:5]
	s_cbranch_vccnz .LBB0_1040
	global_load_dwordx4 v[32:35], v[128:129], off offset:256
.LBB0_1040:
	v_or_b32_e32 v114, 16, v112
	v_ashrrev_i32_e32 v115, 31, v114
	v_lshlrev_b64 v[112:113], 13, v[114:115]
	v_lshl_add_u64 v[112:113], s[20:21], 0, v[112:113]
	v_lshl_add_u64 v[112:113], v[166:167], 1, v[112:113]
	global_load_dwordx4 v[116:119], v[112:113], off
	v_lshlrev_b64 v[114:115], 11, v[114:115]
	v_lshl_add_u64 v[114:115], s[8:9], 0, v[114:115]
	s_and_b64 vcc, exec, s[4:5]
	v_lshl_add_u64 v[130:131], v[166:167], 1, v[114:115]
	s_cbranch_vccnz .LBB0_1042
	global_load_dwordx4 v[24:27], v[130:131], off
.LBB0_1042:
	s_nop 0
	global_load_dwordx4 v[112:115], v[112:113], off offset:256
	s_and_b64 vcc, exec, s[4:5]
	s_cbranch_vccnz .LBB0_1044
	global_load_dwordx4 v[16:19], v[130:131], off offset:256

.LBB0_1046:
	v_cvt_pk_bf16_f32 v108, v108, v109
	v_cvt_pk_bf16_f32 v109, v110, v111
	v_cvt_pk_bf16_f32 v110, v104, v105
	v_lshlrev_b32_e32 v104, 16, v120
	v_and_b32_e32 v105, 0xffff0000, v120
	v_pk_mul_f32 v[100:101], v[100:101], v[104:105]
	v_lshlrev_b32_e32 v104, 16, v121
	v_and_b32_e32 v105, 0xffff0000, v121
	v_pk_mul_f32 v[102:103], v[102:103], v[104:105]
	v_lshlrev_b32_e32 v104, 16, v122
	v_and_b32_e32 v105, 0xffff0000, v122
	v_pk_mul_f32 v[96:97], v[96:97], v[104:105]
	v_lshlrev_b32_e32 v104, 16, v123
	v_and_b32_e32 v105, 0xffff0000, v123
	v_cvt_pk_bf16_f32 v111, v106, v107
	s_and_b64 vcc, exec, s[4:5]
	v_pk_mul_f32 v[98:99], v[98:99], v[104:105]
	global_store_dwordx4 v[128:129], v[108:111], off
	s_cbranch_vccnz .LBB0_1048
	v_lshlrev_b32_e32 v104, 16, v32
	v_and_b32_e32 v105, 0xffff0000, v32
	v_pk_add_f32 v[100:101], v[100:101], v[104:105]
	v_lshlrev_b32_e32 v104, 16, v33
	v_and_b32_e32 v105, 0xffff0000, v33
	v_pk_add_f32 v[102:103], v[102:103], v[104:105]
	v_lshlrev_b32_e32 v104, 16, v34
	v_and_b32_e32 v105, 0xffff0000, v34
	v_pk_add_f32 v[96:97], v[96:97], v[104:105]
	v_lshlrev_b32_e32 v104, 16, v35
	v_and_b32_e32 v105, 0xffff0000, v35
	v_pk_add_f32 v[98:99], v[98:99], v[104:105]
.LBB0_1048:
	v_cvt_pk_bf16_f32 v100, v100, v101
	v_cvt_pk_bf16_f32 v101, v102, v103
	v_cvt_pk_bf16_f32 v102, v96, v97
	v_lshlrev_b32_e32 v96, 16, v116
	v_and_b32_e32 v97, 0xffff0000, v116
	v_pk_mul_f32 v[92:93], v[92:93], v[96:97]
	v_lshlrev_b32_e32 v96, 16, v117
	v_and_b32_e32 v97, 0xffff0000, v117
	v_pk_mul_f32 v[94:95], v[94:95], v[96:97]
	v_lshlrev_b32_e32 v96, 16, v118
	v_and_b32_e32 v97, 0xffff0000, v118
	v_pk_mul_f32 v[88:89], v[88:89], v[96:97]
	v_lshlrev_b32_e32 v96, 16, v119
	v_and_b32_e32 v97, 0xffff0000, v119
	v_cvt_pk_bf16_f32 v103, v98, v99
	s_and_b64 vcc, exec, s[4:5]
	v_pk_mul_f32 v[90:91], v[90:91], v[96:97]
	global_store_dwordx4 v[128:129], v[100:103], off offset:256
	s_cbranch_vccnz .LBB0_1050
	v_lshlrev_b32_e32 v96, 16, v24
	v_and_b32_e32 v97, 0xffff0000, v24
	v_pk_add_f32 v[92:93], v[92:93], v[96:97]
	v_lshlrev_b32_e32 v96, 16, v25
	v_and_b32_e32 v97, 0xffff0000, v25
	v_pk_add_f32 v[94:95], v[94:95], v[96:97]
	v_lshlrev_b32_e32 v96, 16, v26
	v_and_b32_e32 v97, 0xffff0000, v26
	v_pk_add_f32 v[88:89], v[88:89], v[96:97]
	v_lshlrev_b32_e32 v96, 16, v27
	v_and_b32_e32 v97, 0xffff0000, v27
	v_pk_add_f32 v[90:91], v[90:91], v[96:97]
.LBB0_1050:
	v_or_b32_e32 v96, 48, v168
	v_cvt_pk_bf16_f32 v92, v92, v93
	v_cvt_pk_bf16_f32 v93, v94, v95
	v_cvt_pk_bf16_f32 v95, v90, v91
	v_lshlrev_b32_e32 v90, 16, v112
	v_and_b32_e32 v91, 0xffff0000, v112
	v_ashrrev_i32_e32 v97, 31, v96
	v_pk_mul_f32 v[84:85], v[84:85], v[90:91]
	v_lshlrev_b32_e32 v90, 16, v113
	v_and_b32_e32 v91, 0xffff0000, v113
	v_cvt_pk_bf16_f32 v94, v88, v89
	v_lshlrev_b64 v[88:89], 11, v[96:97]
	v_pk_mul_f32 v[86:87], v[86:87], v[90:91]
	v_lshlrev_b32_e32 v90, 16, v114
	v_and_b32_e32 v91, 0xffff0000, v114
	v_lshl_add_u64 v[88:89], s[8:9], 0, v[88:89]
	v_pk_mul_f32 v[80:81], v[80:81], v[90:91]
	v_lshlrev_b32_e32 v90, 16, v115
	v_and_b32_e32 v91, 0xffff0000, v115
	v_lshl_add_u64 v[88:89], v[166:167], 1, v[88:89]
	s_and_b64 vcc, exec, s[4:5]
	v_pk_mul_f32 v[82:83], v[82:83], v[90:91]
	global_store_dwordx4 v[88:89], v[92:95], off
	s_cbranch_vccnz .LBB0_1052
	v_lshlrev_b32_e32 v90, 16, v16
	v_and_b32_e32 v91, 0xffff0000, v16
	v_pk_add_f32 v[84:85], v[84:85], v[90:91]
	v_lshlrev_b32_e32 v90, 16, v17
	v_and_b32_e32 v91, 0xffff0000, v17
	v_pk_add_f32 v[86:87], v[86:87], v[90:91]
	v_lshlrev_b32_e32 v90, 16, v18
	v_and_b32_e32 v91, 0xffff0000, v18
	v_pk_add_f32 v[80:81], v[80:81], v[90:91]
	v_lshlrev_b32_e32 v90, 16, v19
	v_and_b32_e32 v91, 0xffff0000, v19
	v_pk_add_f32 v[82:83], v[82:83], v[90:91]
.LBB0_1052:
	v_cvt_pk_bf16_f32 v84, v84, v85
	v_cvt_pk_bf16_f32 v85, v86, v87
	v_cvt_pk_bf16_f32 v86, v80, v81
	v_add_u32_e32 v80, 0x80, v168
	v_ashrrev_i32_e32 v81, 31, v80
	v_cvt_pk_bf16_f32 v87, v82, v83
	v_lshlrev_b64 v[82:83], 13, v[80:81]
	global_store_dwordx4 v[88:89], v[84:87], off offset:256
	v_lshl_add_u64 v[82:83], s[20:21], 0, v[82:83]
	v_lshl_add_u64 v[82:83], v[166:167], 1, v[82:83]
	global_load_dwordx4 v[92:95], v[82:83], off
	v_lshlrev_b64 v[84:85], 11, v[80:81]
	v_lshl_add_u64 v[84:85], s[8:9], 0, v[84:85]
	s_and_b64 vcc, exec, s[4:5]
	v_lshl_add_u64 v[96:97], v[166:167], 1, v[84:85]
	s_cbranch_vccnz .LBB0_1054
	global_load_dwordx4 v[44:47], v[96:97], off
.LBB0_1054:
	global_load_dwordx4 v[88:91], v[82:83], off offset:256
	s_and_b64 vcc, exec, s[4:5]
	s_cbranch_vccnz .LBB0_1056
	global_load_dwordx4 v[32:35], v[96:97], off offset:256
.LBB0_1056:
	v_or_b32_e32 v82, 16, v80
	v_ashrrev_i32_e32 v83, 31, v82
	v_lshlrev_b64 v[80:81], 13, v[82:83]
	v_lshl_add_u64 v[80:81], s[20:21], 0, v[80:81]
	v_lshl_add_u64 v[80:81], v[166:167], 1, v[80:81]
	global_load_dwordx4 v[84:87], v[80:81], off
	v_lshlrev_b64 v[82:83], 11, v[82:83]
	v_lshl_add_u64 v[82:83], s[8:9], 0, v[82:83]
	s_and_b64 vcc, exec, s[4:5]
	v_lshl_add_u64 v[98:99], v[166:167], 1, v[82:83]
	s_cbranch_vccnz .LBB0_1058
	global_load_dwordx4 v[24:27], v[98:99], off
.LBB0_1058:
	s_nop 0
	global_load_dwordx4 v[80:83], v[80:81], off offset:256
	s_and_b64 vcc, exec, s[4:5]
	s_cbranch_vccnz .LBB0_1060
	global_load_dwordx4 v[16:19], v[98:99], off offset:256

.LBB0_1062:
	v_cvt_pk_bf16_f32 v76, v76, v77
	v_cvt_pk_bf16_f32 v77, v78, v79
	v_cvt_pk_bf16_f32 v78, v72, v73
	v_lshlrev_b32_e32 v72, 16, v88
	v_and_b32_e32 v73, 0xffff0000, v88
	v_pk_mul_f32 v[68:69], v[68:69], v[72:73]
	v_lshlrev_b32_e32 v72, 16, v89
	v_and_b32_e32 v73, 0xffff0000, v89
	v_pk_mul_f32 v[70:71], v[70:71], v[72:73]
	v_lshlrev_b32_e32 v72, 16, v90
	v_and_b32_e32 v73, 0xffff0000, v90
	v_pk_mul_f32 v[64:65], v[64:65], v[72:73]
	v_lshlrev_b32_e32 v72, 16, v91
	v_and_b32_e32 v73, 0xffff0000, v91
	v_cvt_pk_bf16_f32 v79, v74, v75
	s_and_b64 vcc, exec, s[4:5]
	v_pk_mul_f32 v[66:67], v[66:67], v[72:73]
	global_store_dwordx4 v[96:97], v[76:79], off
	s_cbranch_vccnz .LBB0_1064
	v_lshlrev_b32_e32 v72, 16, v32
	v_and_b32_e32 v73, 0xffff0000, v32
	v_pk_add_f32 v[68:69], v[68:69], v[72:73]
	v_lshlrev_b32_e32 v72, 16, v33
	v_and_b32_e32 v73, 0xffff0000, v33
	v_pk_add_f32 v[70:71], v[70:71], v[72:73]
	v_lshlrev_b32_e32 v72, 16, v34
	v_and_b32_e32 v73, 0xffff0000, v34
	v_pk_add_f32 v[64:65], v[64:65], v[72:73]
	v_lshlrev_b32_e32 v72, 16, v35
	v_and_b32_e32 v73, 0xffff0000, v35
	v_pk_add_f32 v[66:67], v[66:67], v[72:73]
.LBB0_1064:
	v_cvt_pk_bf16_f32 v68, v68, v69
	v_cvt_pk_bf16_f32 v69, v70, v71
	v_cvt_pk_bf16_f32 v70, v64, v65
	v_lshlrev_b32_e32 v64, 16, v84
	v_and_b32_e32 v65, 0xffff0000, v84
	v_pk_mul_f32 v[60:61], v[60:61], v[64:65]
	v_lshlrev_b32_e32 v64, 16, v85
	v_and_b32_e32 v65, 0xffff0000, v85
	v_pk_mul_f32 v[62:63], v[62:63], v[64:65]
	v_lshlrev_b32_e32 v64, 16, v86
	v_and_b32_e32 v65, 0xffff0000, v86
	v_pk_mul_f32 v[56:57], v[56:57], v[64:65]
	v_lshlrev_b32_e32 v64, 16, v87
	v_and_b32_e32 v65, 0xffff0000, v87
	v_cvt_pk_bf16_f32 v71, v66, v67
	s_and_b64 vcc, exec, s[4:5]
	v_pk_mul_f32 v[58:59], v[58:59], v[64:65]
	global_store_dwordx4 v[96:97], v[68:71], off offset:256
	s_cbranch_vccnz .LBB0_1066
	v_lshlrev_b32_e32 v64, 16, v24
	v_and_b32_e32 v65, 0xffff0000, v24
	v_pk_add_f32 v[60:61], v[60:61], v[64:65]
	v_lshlrev_b32_e32 v64, 16, v25
	v_and_b32_e32 v65, 0xffff0000, v25
	v_pk_add_f32 v[62:63], v[62:63], v[64:65]
	v_lshlrev_b32_e32 v64, 16, v26
	v_and_b32_e32 v65, 0xffff0000, v26
	v_pk_add_f32 v[56:57], v[56:57], v[64:65]
	v_lshlrev_b32_e32 v64, 16, v27
	v_and_b32_e32 v65, 0xffff0000, v27
	v_pk_add_f32 v[58:59], v[58:59], v[64:65]
.LBB0_1066:
	v_add_u32_e32 v64, 0x90, v168
	v_cvt_pk_bf16_f32 v60, v60, v61
	v_cvt_pk_bf16_f32 v61, v62, v63
	v_cvt_pk_bf16_f32 v63, v58, v59
	v_lshlrev_b32_e32 v58, 16, v80
	v_and_b32_e32 v59, 0xffff0000, v80
	v_ashrrev_i32_e32 v65, 31, v64
	v_pk_mul_f32 v[52:53], v[52:53], v[58:59]
	v_lshlrev_b32_e32 v58, 16, v81
	v_and_b32_e32 v59, 0xffff0000, v81
	v_cvt_pk_bf16_f32 v62, v56, v57
	v_lshlrev_b64 v[56:57], 11, v[64:65]
	v_pk_mul_f32 v[54:55], v[54:55], v[58:59]
	v_lshlrev_b32_e32 v58, 16, v82
	v_and_b32_e32 v59, 0xffff0000, v82
	v_lshl_add_u64 v[56:57], s[8:9], 0, v[56:57]
	v_pk_mul_f32 v[48:49], v[48:49], v[58:59]
	v_lshlrev_b32_e32 v58, 16, v83
	v_and_b32_e32 v59, 0xffff0000, v83
	v_lshl_add_u64 v[56:57], v[166:167], 1, v[56:57]
	s_and_b64 vcc, exec, s[4:5]
	v_pk_mul_f32 v[50:51], v[50:51], v[58:59]
	global_store_dwordx4 v[56:57], v[60:63], off
	s_cbranch_vccnz .LBB0_1068
	v_lshlrev_b32_e32 v58, 16, v16
	v_and_b32_e32 v59, 0xffff0000, v16
	v_pk_add_f32 v[52:53], v[52:53], v[58:59]
	v_lshlrev_b32_e32 v58, 16, v17
	v_and_b32_e32 v59, 0xffff0000, v17
	v_pk_add_f32 v[54:55], v[54:55], v[58:59]
	v_lshlrev_b32_e32 v58, 16, v18
	v_and_b32_e32 v59, 0xffff0000, v18
	v_pk_add_f32 v[48:49], v[48:49], v[58:59]
	v_lshlrev_b32_e32 v58, 16, v19
	v_and_b32_e32 v59, 0xffff0000, v19
	v_pk_add_f32 v[50:51], v[50:51], v[58:59]
.LBB0_1068:
	v_cvt_pk_bf16_f32 v52, v52, v53
	v_cvt_pk_bf16_f32 v53, v54, v55
	v_cvt_pk_bf16_f32 v54, v48, v49
	v_add_u32_e32 v48, 0xa0, v168
	v_ashrrev_i32_e32 v49, 31, v48
	v_cvt_pk_bf16_f32 v55, v50, v51
	v_lshlrev_b64 v[50:51], 13, v[48:49]
	global_store_dwordx4 v[56:57], v[52:55], off offset:256
	v_lshl_add_u64 v[50:51], s[20:21], 0, v[50:51]
	v_lshl_add_u64 v[50:51], v[166:167], 1, v[50:51]
	global_load_dwordx4 v[60:63], v[50:51], off
	v_lshlrev_b64 v[52:53], 11, v[48:49]
	v_lshl_add_u64 v[52:53], s[8:9], 0, v[52:53]
	s_and_b64 vcc, exec, s[4:5]
	v_lshl_add_u64 v[64:65], v[166:167], 1, v[52:53]
	s_cbranch_vccnz .LBB0_1070
	global_load_dwordx4 v[44:47], v[64:65], off
.LBB0_1070:
	global_load_dwordx4 v[56:59], v[50:51], off offset:256
	s_and_b64 vcc, exec, s[4:5]
	s_cbranch_vccnz .LBB0_1072
	global_load_dwordx4 v[32:35], v[64:65], off offset:256
.LBB0_1072:
	v_or_b32_e32 v50, 16, v48
	v_ashrrev_i32_e32 v51, 31, v50
	v_lshlrev_b64 v[48:49], 13, v[50:51]
	v_lshl_add_u64 v[48:49], s[20:21], 0, v[48:49]
	v_lshl_add_u64 v[48:49], v[166:167], 1, v[48:49]
	global_load_dwordx4 v[52:55], v[48:49], off
	v_lshlrev_b64 v[50:51], 11, v[50:51]
	v_lshl_add_u64 v[50:51], s[8:9], 0, v[50:51]
	s_and_b64 vcc, exec, s[4:5]
	v_lshl_add_u64 v[66:67], v[166:167], 1, v[50:51]
	s_cbranch_vccnz .LBB0_1074
	global_load_dwordx4 v[24:27], v[66:67], off
.LBB0_1074:
	s_nop 0
	global_load_dwordx4 v[48:51], v[48:49], off offset:256
	s_and_b64 vcc, exec, s[4:5]
	s_cbranch_vccnz .LBB0_1076
	global_load_dwordx4 v[16:19], v[66:67], off offset:256

.LBB0_1078:
	v_cvt_pk_bf16_f32 v40, v40, v41
	v_cvt_pk_bf16_f32 v41, v42, v43
	v_cvt_pk_bf16_f32 v42, v36, v37
	v_lshlrev_b32_e32 v36, 16, v56
	v_and_b32_e32 v37, 0xffff0000, v56
	v_pk_mul_f32 v[28:29], v[28:29], v[36:37]
	v_lshlrev_b32_e32 v36, 16, v57
	v_and_b32_e32 v37, 0xffff0000, v57
	v_pk_mul_f32 v[30:31], v[30:31], v[36:37]
	v_lshlrev_b32_e32 v36, 16, v58
	v_and_b32_e32 v37, 0xffff0000, v58
	v_pk_mul_f32 v[20:21], v[20:21], v[36:37]
	v_lshlrev_b32_e32 v36, 16, v59
	v_and_b32_e32 v37, 0xffff0000, v59
	v_cvt_pk_bf16_f32 v43, v38, v39
	s_and_b64 vcc, exec, s[4:5]
	v_pk_mul_f32 v[22:23], v[22:23], v[36:37]
	global_store_dwordx4 v[64:65], v[40:43], off
	s_cbranch_vccnz .LBB0_1080
	v_lshlrev_b32_e32 v36, 16, v32
	v_and_b32_e32 v37, 0xffff0000, v32
	v_lshlrev_b32_e32 v32, 16, v33
	v_and_b32_e32 v33, 0xffff0000, v33
	v_pk_add_f32 v[30:31], v[30:31], v[32:33]
	v_lshlrev_b32_e32 v32, 16, v34
	v_and_b32_e32 v33, 0xffff0000, v34
	v_pk_add_f32 v[20:21], v[20:21], v[32:33]
	v_lshlrev_b32_e32 v32, 16, v35
	v_and_b32_e32 v33, 0xffff0000, v35
	v_pk_add_f32 v[28:29], v[28:29], v[36:37]
	v_pk_add_f32 v[22:23], v[22:23], v[32:33]
.LBB0_1080:
	v_cvt_pk_bf16_f32 v28, v28, v29
	v_cvt_pk_bf16_f32 v29, v30, v31
	v_cvt_pk_bf16_f32 v30, v20, v21
	v_lshlrev_b32_e32 v20, 16, v52
	v_and_b32_e32 v21, 0xffff0000, v52
	v_pk_mul_f32 v[12:13], v[12:13], v[20:21]
	v_lshlrev_b32_e32 v20, 16, v53
	v_and_b32_e32 v21, 0xffff0000, v53
	v_pk_mul_f32 v[14:15], v[14:15], v[20:21]
	v_lshlrev_b32_e32 v20, 16, v54
	v_and_b32_e32 v21, 0xffff0000, v54
	v_pk_mul_f32 v[8:9], v[8:9], v[20:21]
	v_lshlrev_b32_e32 v20, 16, v55
	v_and_b32_e32 v21, 0xffff0000, v55
	v_cvt_pk_bf16_f32 v31, v22, v23
	s_and_b64 vcc, exec, s[4:5]
	v_pk_mul_f32 v[10:11], v[10:11], v[20:21]
	global_store_dwordx4 v[64:65], v[28:31], off offset:256
	s_cbranch_vccnz .LBB0_1082
	v_lshlrev_b32_e32 v20, 16, v24
	v_and_b32_e32 v21, 0xffff0000, v24
	v_pk_add_f32 v[12:13], v[12:13], v[20:21]
	v_lshlrev_b32_e32 v20, 16, v25
	v_and_b32_e32 v21, 0xffff0000, v25
	v_pk_add_f32 v[14:15], v[14:15], v[20:21]
	v_lshlrev_b32_e32 v20, 16, v26
	v_and_b32_e32 v21, 0xffff0000, v26
	v_pk_add_f32 v[8:9], v[8:9], v[20:21]
	v_lshlrev_b32_e32 v20, 16, v27
	v_and_b32_e32 v21, 0xffff0000, v27
	v_pk_add_f32 v[10:11], v[10:11], v[20:21]
.LBB0_1082:
	v_add_u32_e32 v20, 0xb0, v168
	v_cvt_pk_bf16_f32 v12, v12, v13
	v_cvt_pk_bf16_f32 v13, v14, v15
	v_cvt_pk_bf16_f32 v15, v10, v11
	v_lshlrev_b32_e32 v10, 16, v48
	v_and_b32_e32 v11, 0xffff0000, v48
	v_ashrrev_i32_e32 v21, 31, v20
	v_pk_mul_f32 v[4:5], v[4:5], v[10:11]
	v_lshlrev_b32_e32 v10, 16, v49
	v_and_b32_e32 v11, 0xffff0000, v49
	v_cvt_pk_bf16_f32 v14, v8, v9
	v_lshlrev_b64 v[8:9], 11, v[20:21]
	v_pk_mul_f32 v[6:7], v[6:7], v[10:11]
	v_lshlrev_b32_e32 v10, 16, v50
	v_and_b32_e32 v11, 0xffff0000, v50
	v_lshl_add_u64 v[8:9], s[8:9], 0, v[8:9]
	v_pk_mul_f32 v[0:1], v[0:1], v[10:11]
	v_lshlrev_b32_e32 v10, 16, v51
	v_and_b32_e32 v11, 0xffff0000, v51
	v_lshl_add_u64 v[8:9], v[166:167], 1, v[8:9]
	s_and_b64 vcc, exec, s[4:5]
	v_pk_mul_f32 v[2:3], v[2:3], v[10:11]
	global_store_dwordx4 v[8:9], v[12:15], off
	s_cbranch_vccnz .LBB0_1084
	v_lshlrev_b32_e32 v10, 16, v16
	v_and_b32_e32 v11, 0xffff0000, v16
	v_pk_add_f32 v[4:5], v[4:5], v[10:11]
	v_lshlrev_b32_e32 v10, 16, v17
	v_and_b32_e32 v11, 0xffff0000, v17
	v_pk_add_f32 v[6:7], v[6:7], v[10:11]
	v_lshlrev_b32_e32 v10, 16, v18
	v_and_b32_e32 v11, 0xffff0000, v18
	v_pk_add_f32 v[0:1], v[0:1], v[10:11]
	v_lshlrev_b32_e32 v10, 16, v19
	v_and_b32_e32 v11, 0xffff0000, v19
	v_pk_add_f32 v[2:3], v[2:3], v[10:11]
.LBB0_1084:
	v_cvt_pk_bf16_f32 v4, v4, v5
	v_cvt_pk_bf16_f32 v5, v6, v7
	v_cvt_pk_bf16_f32 v6, v0, v1
	v_cvt_pk_bf16_f32 v7, v2, v3
	global_store_dwordx4 v[8:9], v[4:7], off offset:256
	s_andn2_b64 vcc, exec, s[2:3]
	s_mov_b64 s[2:3], -1
	s_cbranch_vccnz .LBB0_1011
	s_andn2_b64 vcc, exec, s[6:7]
	s_cbranch_vccnz .LBB0_1010
	s_barrier
	s_branch .LBB0_1010

.LBB0_1167:
	v_mbcnt_lo_u32_b32 v130, -1, 0
	v_mbcnt_hi_u32_b32 v130, -1, v130
	s_lshl_b32 s21, s55, 8
	v_ashrrev_i32_e32 v128, 1, v130
	v_and_b32_e32 v128, -8, v128
	s_or_b32 s21, s21, s50
	v_add_u32_e32 v128, s21, v128
	s_lshl_b32 s21, s28, 8
	v_ashrrev_i32_e32 v129, 31, v128
	s_add_i32 s21, s21, s49
	v_lshlrev_b64 v[154:155], 2, v[128:129]
	v_and_or_b32 v172, v130, 15, s21
	v_lshl_add_u64 v[128:129], s[10:11], 0, v[154:155]
	v_ashrrev_i32_e32 v173, 31, v172
	global_load_dwordx4 v[156:159], v[128:129], off
	global_load_dwordx4 v[160:163], v[128:129], off offset:16
	global_load_dwordx4 v[176:179], v[128:129], off offset:512
	global_load_dwordx4 v[180:183], v[128:129], off offset:528
	v_lshl_add_u64 v[128:129], v[172:173], 3, s[16:17]
	v_lshlrev_b64 v[164:165], 12, v[172:173]
	global_load_dwordx2 v[216:217], v[128:129], off
	v_lshl_add_u64 v[128:129], s[8:9], 0, v[164:165]
	v_lshl_add_u64 v[128:129], v[128:129], 0, v[154:155]
	global_load_dwordx4 v[184:187], v[128:129], off
	global_load_dwordx4 v[188:191], v[128:129], off offset:16
	global_load_dwordx4 v[192:195], v[128:129], off offset:512
	global_load_dwordx4 v[196:199], v[128:129], off offset:528
	v_or_b32_e32 v130, 16, v172
	v_lshl_add_u64 v[128:129], s[12:13], 0, v[154:155]
	v_ashrrev_i32_e32 v131, 31, v130
	global_load_dwordx4 v[140:143], v[128:129], off
	global_load_dwordx4 v[136:139], v[128:129], off offset:16
	global_load_dwordx4 v[132:135], v[128:129], off offset:512
	v_lshl_add_u64 v[166:167], v[130:131], 3, s[16:17]
	v_lshlrev_b64 v[218:219], 12, v[130:131]
	global_load_dwordx4 v[128:131], v[128:129], off offset:528
	s_nop 0
	global_load_dwordx2 v[220:221], v[166:167], off
	v_lshl_add_u64 v[166:167], s[8:9], 0, v[218:219]
	v_lshl_add_u64 v[166:167], v[166:167], 0, v[154:155]
	global_load_dwordx4 v[200:203], v[166:167], off
	global_load_dwordx4 v[204:207], v[166:167], off offset:16
	global_load_dwordx4 v[208:211], v[166:167], off offset:512
	global_load_dwordx4 v[212:215], v[166:167], off offset:528
	v_lshl_add_u64 v[164:165], s[6:7], 0, v[164:165]
	s_mov_b32 s28, 0x3fb504f3
	v_lshl_add_u64 v[222:223], v[164:165], 0, v[154:155]
	s_andn2_b64 vcc, exec, s[4:5]
	s_mov_b64 s[4:5], -1
	s_waitcnt vmcnt(0) lgkmcnt(0)
	v_pk_mul_f32 v[168:169], v[158:159], s[28:29] op_sel_hi:[1,0]
	v_pk_mul_f32 v[164:165], v[162:163], s[28:29] op_sel_hi:[1,0]
	v_pk_mul_f32 v[166:167], v[160:161], s[28:29] op_sel_hi:[1,0]
	v_pk_mul_f32 v[160:161], v[178:179], s[28:29] op_sel_hi:[1,0]
	v_pk_mul_f32 v[162:163], v[176:177], s[28:29] op_sel_hi:[1,0]
	v_pk_mul_f32 v[170:171], v[156:157], s[28:29] op_sel_hi:[1,0]
	v_sub_f32_e32 v177, v187, v216
	v_sub_f32_e32 v176, v186, v216
	v_sub_f32_e32 v179, v185, v216
	v_sub_f32_e32 v178, v184, v216
	v_pk_mul_f32 v[156:157], v[182:183], s[28:29] op_sel_hi:[1,0]
	v_pk_mul_f32 v[158:159], v[180:181], s[28:29] op_sel_hi:[1,0]
	v_sub_f32_e32 v181, v191, v216
	v_sub_f32_e32 v180, v190, v216
	v_sub_f32_e32 v183, v189, v216
	v_sub_f32_e32 v182, v188, v216
	v_sub_f32_e32 v185, v195, v216
	v_sub_f32_e32 v184, v194, v216
	v_sub_f32_e32 v187, v193, v216
	v_sub_f32_e32 v186, v192, v216
	v_sub_f32_e32 v189, v199, v216
	v_sub_f32_e32 v188, v198, v216
	v_sub_f32_e32 v191, v197, v216
	v_sub_f32_e32 v190, v196, v216
	v_pk_mul_f32 v[178:179], v[216:217], v[178:179] op_sel:[1,0]
	v_pk_mul_f32 v[176:177], v[216:217], v[176:177] op_sel:[1,0]
	v_pk_mul_f32 v[182:183], v[216:217], v[182:183] op_sel:[1,0]
	v_pk_mul_f32 v[180:181], v[216:217], v[180:181] op_sel:[1,0]
	v_pk_mul_f32 v[186:187], v[216:217], v[186:187] op_sel:[1,0]
	v_pk_mul_f32 v[184:185], v[216:217], v[184:185] op_sel:[1,0]
	v_pk_mul_f32 v[190:191], v[216:217], v[190:191] op_sel:[1,0]
	v_pk_mul_f32 v[188:189], v[216:217], v[188:189] op_sel:[1,0]
	v_pk_fma_f32 v[126:127], v[168:169], v[176:177], v[126:127]
	v_pk_fma_f32 v[124:125], v[170:171], v[178:179], v[124:125]
	v_pk_fma_f32 v[122:123], v[164:165], v[180:181], v[122:123]
	v_pk_fma_f32 v[120:121], v[166:167], v[182:183], v[120:121]
	v_pk_fma_f32 v[176:177], v[160:161], v[184:185], v[118:119]
	v_pk_fma_f32 v[178:179], v[162:163], v[186:187], v[116:117]
	v_pk_fma_f32 v[180:181], v[156:157], v[188:189], v[114:115]
	v_pk_fma_f32 v[182:183], v[158:159], v[190:191], v[112:113]
	v_pk_fma_f32 v[114:115], v[142:143], s[28:29], v[126:127] op_sel_hi:[1,0,1]
	v_pk_fma_f32 v[112:113], v[140:141], s[28:29], v[124:125] op_sel_hi:[1,0,1]
	v_pk_fma_f32 v[118:119], v[138:139], s[28:29], v[122:123] op_sel_hi:[1,0,1]
	v_pk_fma_f32 v[116:117], v[136:137], s[28:29], v[120:121] op_sel_hi:[1,0,1]
	v_pk_fma_f32 v[122:123], v[134:135], s[28:29], v[176:177] op_sel_hi:[1,0,1]
	v_pk_fma_f32 v[120:121], v[132:133], s[28:29], v[178:179] op_sel_hi:[1,0,1]
	global_store_dwordx4 v[222:223], v[112:115], off
	global_store_dwordx4 v[222:223], v[116:119], off offset:16
	s_nop 0
	v_pk_fma_f32 v[112:113], v[128:129], s[28:29], v[182:183] op_sel_hi:[1,0,1]
	v_pk_fma_f32 v[114:115], v[130:131], s[28:29], v[180:181] op_sel_hi:[1,0,1]
	global_store_dwordx4 v[222:223], v[120:123], off offset:512
	global_store_dwordx4 v[222:223], v[112:115], off offset:528
	s_nop 1
	v_sub_f32_e32 v113, v203, v220
	v_sub_f32_e32 v112, v202, v220
	v_sub_f32_e32 v115, v201, v220
	v_sub_f32_e32 v114, v200, v220
	v_pk_mul_f32 v[112:113], v[220:221], v[112:113] op_sel:[1,0]
	v_pk_mul_f32 v[114:115], v[220:221], v[114:115] op_sel:[1,0]
	v_pk_fma_f32 v[110:111], v[168:169], v[112:113], v[110:111]
	v_sub_f32_e32 v113, v207, v220
	v_sub_f32_e32 v112, v206, v220
	v_pk_fma_f32 v[108:109], v[170:171], v[114:115], v[108:109]
	v_sub_f32_e32 v115, v205, v220
	v_sub_f32_e32 v114, v204, v220
	v_pk_mul_f32 v[112:113], v[220:221], v[112:113] op_sel:[1,0]
	v_pk_mul_f32 v[114:115], v[220:221], v[114:115] op_sel:[1,0]
	v_pk_fma_f32 v[106:107], v[164:165], v[112:113], v[106:107]
	v_lshl_add_u64 v[112:113], s[6:7], 0, v[218:219]
	v_pk_fma_f32 v[110:111], v[142:143], s[28:29], v[110:111] op_sel_hi:[1,0,1]
	v_pk_fma_f32 v[108:109], v[140:141], s[28:29], v[108:109] op_sel_hi:[1,0,1]
	v_pk_fma_f32 v[104:105], v[166:167], v[114:115], v[104:105]
	v_pk_fma_f32 v[106:107], v[138:139], s[28:29], v[106:107] op_sel_hi:[1,0,1]
	v_lshl_add_u64 v[112:113], v[112:113], 0, v[154:155]
	v_pk_fma_f32 v[104:105], v[136:137], s[28:29], v[104:105] op_sel_hi:[1,0,1]
	global_store_dwordx4 v[112:113], v[108:111], off
	global_store_dwordx4 v[112:113], v[104:107], off offset:16
	s_nop 1
	v_sub_f32_e32 v107, v209, v220
	v_sub_f32_e32 v106, v208, v220
	v_sub_f32_e32 v105, v211, v220
	v_sub_f32_e32 v104, v210, v220
	v_pk_mul_f32 v[106:107], v[220:221], v[106:107] op_sel:[1,0]
	v_pk_mul_f32 v[104:105], v[220:221], v[104:105] op_sel:[1,0]
	v_pk_fma_f32 v[100:101], v[162:163], v[106:107], v[100:101]
	v_sub_f32_e32 v107, v213, v220
	v_sub_f32_e32 v106, v212, v220
	v_pk_fma_f32 v[102:103], v[160:161], v[104:105], v[102:103]
	v_sub_f32_e32 v105, v215, v220
	v_sub_f32_e32 v104, v214, v220
	v_pk_mul_f32 v[106:107], v[220:221], v[106:107] op_sel:[1,0]
	v_pk_mul_f32 v[104:105], v[220:221], v[104:105] op_sel:[1,0]
	v_pk_fma_f32 v[96:97], v[158:159], v[106:107], v[96:97]
	v_pk_fma_f32 v[102:103], v[134:135], s[28:29], v[102:103] op_sel_hi:[1,0,1]
	v_pk_fma_f32 v[100:101], v[132:133], s[28:29], v[100:101] op_sel_hi:[1,0,1]
	v_pk_fma_f32 v[98:99], v[156:157], v[104:105], v[98:99]
	v_pk_fma_f32 v[96:97], v[128:129], s[28:29], v[96:97] op_sel_hi:[1,0,1]
	v_pk_fma_f32 v[98:99], v[130:131], s[28:29], v[98:99] op_sel_hi:[1,0,1]
	global_store_dwordx4 v[112:113], v[100:103], off offset:512
	global_store_dwordx4 v[112:113], v[96:99], off offset:528
	v_or_b32_e32 v112, 48, v172
	v_ashrrev_i32_e32 v113, 31, v112
	v_or_b32_e32 v96, 32, v172
	v_ashrrev_i32_e32 v97, 31, v96
	v_lshl_add_u64 v[98:99], v[96:97], 3, s[16:17]
	global_load_dwordx2 v[176:177], v[98:99], off
	v_lshlrev_b64 v[178:179], 12, v[96:97]
	v_lshl_add_u64 v[96:97], s[8:9], 0, v[178:179]
	v_lshl_add_u64 v[108:109], v[96:97], 0, v[154:155]
	global_load_dwordx4 v[96:99], v[108:109], off
	global_load_dwordx4 v[100:103], v[108:109], off offset:16
	global_load_dwordx4 v[104:107], v[108:109], off offset:512
	s_nop 0
	global_load_dwordx4 v[108:111], v[108:109], off offset:528
	v_lshl_add_u64 v[114:115], v[112:113], 3, s[16:17]
	global_load_dwordx2 v[180:181], v[114:115], off
	v_lshlrev_b64 v[182:183], 12, v[112:113]
	v_lshl_add_u64 v[112:113], s[8:9], 0, v[182:183]
	v_lshl_add_u64 v[124:125], v[112:113], 0, v[154:155]
	global_load_dwordx4 v[112:115], v[124:125], off
	global_load_dwordx4 v[116:119], v[124:125], off offset:16
	global_load_dwordx4 v[120:123], v[124:125], off offset:512
	s_nop 0
	global_load_dwordx4 v[124:127], v[124:125], off offset:528
	s_waitcnt vmcnt(0) lgkmcnt(0)
	v_sub_f32_e32 v99, v99, v176
	v_sub_f32_e32 v98, v98, v176
	v_sub_f32_e32 v97, v97, v176
	v_sub_f32_e32 v96, v96, v176
	v_sub_f32_e32 v103, v103, v176
	v_sub_f32_e32 v102, v102, v176
	v_sub_f32_e32 v101, v101, v176
	v_pk_mul_f32 v[96:97], v[176:177], v[96:97] op_sel:[1,0]
	v_pk_mul_f32 v[98:99], v[176:177], v[98:99] op_sel:[1,0]
	v_sub_f32_e32 v100, v100, v176
	v_pk_fma_f32 v[94:95], v[168:169], v[98:99], v[94:95]
	v_pk_fma_f32 v[92:93], v[170:171], v[96:97], v[92:93]
	v_pk_mul_f32 v[96:97], v[176:177], v[100:101] op_sel:[1,0]
	v_pk_mul_f32 v[98:99], v[176:177], v[102:103] op_sel:[1,0]
	v_pk_fma_f32 v[88:89], v[166:167], v[96:97], v[88:89]
	v_pk_fma_f32 v[90:91], v[164:165], v[98:99], v[90:91]
	v_lshl_add_u64 v[96:97], s[6:7], 0, v[178:179]
	v_pk_fma_f32 v[94:95], v[142:143], s[28:29], v[94:95] op_sel_hi:[1,0,1]
	v_pk_fma_f32 v[92:93], v[140:141], s[28:29], v[92:93] op_sel_hi:[1,0,1]
	v_pk_fma_f32 v[90:91], v[138:139], s[28:29], v[90:91] op_sel_hi:[1,0,1]
	v_pk_fma_f32 v[88:89], v[136:137], s[28:29], v[88:89] op_sel_hi:[1,0,1]
	v_lshl_add_u64 v[96:97], v[96:97], 0, v[154:155]
	global_store_dwordx4 v[96:97], v[92:95], off
	global_store_dwordx4 v[96:97], v[88:91], off offset:16
	s_nop 1
	v_sub_f32_e32 v89, v107, v176
	v_sub_f32_e32 v88, v106, v176
	v_sub_f32_e32 v91, v105, v176
	v_sub_f32_e32 v90, v104, v176
	v_pk_mul_f32 v[90:91], v[176:177], v[90:91] op_sel:[1,0]
	v_pk_mul_f32 v[88:89], v[176:177], v[88:89] op_sel:[1,0]
	v_pk_fma_f32 v[84:85], v[162:163], v[90:91], v[84:85]
	v_pk_fma_f32 v[86:87], v[160:161], v[88:89], v[86:87]
	v_sub_f32_e32 v89, v111, v176
	v_sub_f32_e32 v88, v110, v176
	v_sub_f32_e32 v91, v109, v176
	v_sub_f32_e32 v90, v108, v176
	v_pk_mul_f32 v[90:91], v[176:177], v[90:91] op_sel:[1,0]
	v_pk_mul_f32 v[88:89], v[176:177], v[88:89] op_sel:[1,0]
	v_pk_fma_f32 v[76:77], v[158:159], v[90:91], v[76:77]
	v_pk_fma_f32 v[78:79], v[156:157], v[88:89], v[78:79]
	v_pk_fma_f32 v[86:87], v[134:135], s[28:29], v[86:87] op_sel_hi:[1,0,1]
	v_pk_fma_f32 v[84:85], v[132:133], s[28:29], v[84:85] op_sel_hi:[1,0,1]
	v_pk_fma_f32 v[78:79], v[130:131], s[28:29], v[78:79] op_sel_hi:[1,0,1]
	v_pk_fma_f32 v[76:77], v[128:129], s[28:29], v[76:77] op_sel_hi:[1,0,1]
	global_store_dwordx4 v[96:97], v[84:87], off offset:512
	global_store_dwordx4 v[96:97], v[76:79], off offset:528
	s_nop 1
	v_sub_f32_e32 v77, v115, v180
	v_sub_f32_e32 v76, v114, v180
	v_sub_f32_e32 v79, v113, v180
	v_sub_f32_e32 v78, v112, v180
	v_pk_mul_f32 v[78:79], v[180:181], v[78:79] op_sel:[1,0]
	v_pk_mul_f32 v[76:77], v[180:181], v[76:77] op_sel:[1,0]
	v_pk_fma_f32 v[80:81], v[170:171], v[78:79], v[80:81]
	v_pk_fma_f32 v[76:77], v[168:169], v[76:77], v[82:83]
	v_sub_f32_e32 v83, v117, v180
	v_pk_fma_f32 v[78:79], v[142:143], s[28:29], v[76:77] op_sel_hi:[1,0,1]
	v_pk_fma_f32 v[76:77], v[140:141], s[28:29], v[80:81] op_sel_hi:[1,0,1]
	v_sub_f32_e32 v81, v119, v180
	v_sub_f32_e32 v80, v118, v180
	v_sub_f32_e32 v82, v116, v180
	v_pk_mul_f32 v[80:81], v[180:181], v[80:81] op_sel:[1,0]
	v_pk_mul_f32 v[82:83], v[180:181], v[82:83] op_sel:[1,0]
	v_pk_fma_f32 v[74:75], v[164:165], v[80:81], v[74:75]
	v_lshl_add_u64 v[80:81], s[6:7], 0, v[182:183]
	v_pk_fma_f32 v[72:73], v[166:167], v[82:83], v[72:73]
	v_pk_fma_f32 v[74:75], v[138:139], s[28:29], v[74:75] op_sel_hi:[1,0,1]
	v_lshl_add_u64 v[80:81], v[80:81], 0, v[154:155]
	v_pk_fma_f32 v[72:73], v[136:137], s[28:29], v[72:73] op_sel_hi:[1,0,1]
	global_store_dwordx4 v[80:81], v[76:79], off
	global_store_dwordx4 v[80:81], v[72:75], off offset:16
	s_nop 1
	v_sub_f32_e32 v75, v121, v180
	v_sub_f32_e32 v74, v120, v180
	v_sub_f32_e32 v73, v123, v180
	v_sub_f32_e32 v72, v122, v180
	v_pk_mul_f32 v[74:75], v[180:181], v[74:75] op_sel:[1,0]
	v_pk_mul_f32 v[72:73], v[180:181], v[72:73] op_sel:[1,0]
	v_pk_fma_f32 v[68:69], v[162:163], v[74:75], v[68:69]
	v_sub_f32_e32 v75, v125, v180
	v_sub_f32_e32 v74, v124, v180
	v_pk_fma_f32 v[70:71], v[160:161], v[72:73], v[70:71]
	v_sub_f32_e32 v73, v127, v180
	v_sub_f32_e32 v72, v126, v180
	v_pk_mul_f32 v[74:75], v[180:181], v[74:75] op_sel:[1,0]
	v_pk_mul_f32 v[72:73], v[180:181], v[72:73] op_sel:[1,0]
	v_pk_fma_f32 v[64:65], v[158:159], v[74:75], v[64:65]
	v_pk_fma_f32 v[70:71], v[134:135], s[28:29], v[70:71] op_sel_hi:[1,0,1]
	v_pk_fma_f32 v[68:69], v[132:133], s[28:29], v[68:69] op_sel_hi:[1,0,1]
	v_pk_fma_f32 v[66:67], v[156:157], v[72:73], v[66:67]
	v_pk_fma_f32 v[64:65], v[128:129], s[28:29], v[64:65] op_sel_hi:[1,0,1]
	v_pk_fma_f32 v[66:67], v[130:131], s[28:29], v[66:67] op_sel_hi:[1,0,1]
	global_store_dwordx4 v[80:81], v[68:71], off offset:512
	global_store_dwordx4 v[80:81], v[64:67], off offset:528
	v_add_u32_e32 v80, 0x90, v172
	v_ashrrev_i32_e32 v81, 31, v80
	v_add_u32_e32 v64, 0x80, v172
	v_ashrrev_i32_e32 v65, 31, v64
	v_lshl_add_u64 v[66:67], v[64:65], 3, s[16:17]
	global_load_dwordx2 v[96:97], v[66:67], off
	v_lshlrev_b64 v[98:99], 12, v[64:65]
	v_lshl_add_u64 v[64:65], s[8:9], 0, v[98:99]
	v_lshl_add_u64 v[76:77], v[64:65], 0, v[154:155]
	global_load_dwordx4 v[64:67], v[76:77], off
	global_load_dwordx4 v[68:71], v[76:77], off offset:16
	global_load_dwordx4 v[72:75], v[76:77], off offset:512
	s_nop 0
	global_load_dwordx4 v[76:79], v[76:77], off offset:528
	v_lshl_add_u64 v[82:83], v[80:81], 3, s[16:17]
	global_load_dwordx2 v[100:101], v[82:83], off
	v_lshlrev_b64 v[102:103], 12, v[80:81]
	v_lshl_add_u64 v[80:81], s[8:9], 0, v[102:103]
	v_lshl_add_u64 v[92:93], v[80:81], 0, v[154:155]
	global_load_dwordx4 v[80:83], v[92:93], off
	global_load_dwordx4 v[84:87], v[92:93], off offset:16
	global_load_dwordx4 v[88:91], v[92:93], off offset:512
	s_nop 0
	global_load_dwordx4 v[92:95], v[92:93], off offset:528
	s_waitcnt vmcnt(0) lgkmcnt(0)
	v_sub_f32_e32 v67, v67, v96
	v_sub_f32_e32 v66, v66, v96
	v_sub_f32_e32 v65, v65, v96
	v_sub_f32_e32 v64, v64, v96
	v_pk_mul_f32 v[64:65], v[96:97], v[64:65] op_sel:[1,0]
	v_pk_mul_f32 v[66:67], v[96:97], v[66:67] op_sel:[1,0]
	v_pk_fma_f32 v[60:61], v[170:171], v[64:65], v[60:61]
	v_pk_fma_f32 v[62:63], v[168:169], v[66:67], v[62:63]
	v_sub_f32_e32 v65, v71, v96
	v_sub_f32_e32 v64, v70, v96
	v_sub_f32_e32 v67, v69, v96
	v_sub_f32_e32 v66, v68, v96
	v_pk_mul_f32 v[66:67], v[96:97], v[66:67] op_sel:[1,0]
	v_pk_mul_f32 v[64:65], v[96:97], v[64:65] op_sel:[1,0]
	v_pk_fma_f32 v[56:57], v[166:167], v[66:67], v[56:57]
	v_pk_fma_f32 v[58:59], v[164:165], v[64:65], v[58:59]
	v_lshl_add_u64 v[64:65], s[6:7], 0, v[98:99]
	v_pk_fma_f32 v[62:63], v[142:143], s[28:29], v[62:63] op_sel_hi:[1,0,1]
	v_pk_fma_f32 v[60:61], v[140:141], s[28:29], v[60:61] op_sel_hi:[1,0,1]
	v_pk_fma_f32 v[58:59], v[138:139], s[28:29], v[58:59] op_sel_hi:[1,0,1]
	v_pk_fma_f32 v[56:57], v[136:137], s[28:29], v[56:57] op_sel_hi:[1,0,1]
	v_lshl_add_u64 v[64:65], v[64:65], 0, v[154:155]
	global_store_dwordx4 v[64:65], v[60:63], off
	global_store_dwordx4 v[64:65], v[56:59], off offset:16
	s_nop 1
	v_sub_f32_e32 v57, v75, v96
	v_sub_f32_e32 v56, v74, v96
	v_sub_f32_e32 v59, v73, v96
	v_sub_f32_e32 v58, v72, v96
	v_pk_mul_f32 v[58:59], v[96:97], v[58:59] op_sel:[1,0]
	v_pk_mul_f32 v[56:57], v[96:97], v[56:57] op_sel:[1,0]
	v_pk_fma_f32 v[52:53], v[162:163], v[58:59], v[52:53]
	v_pk_fma_f32 v[54:55], v[160:161], v[56:57], v[54:55]
	v_sub_f32_e32 v57, v79, v96
	v_sub_f32_e32 v56, v78, v96
	v_sub_f32_e32 v59, v77, v96
	v_sub_f32_e32 v58, v76, v96
	v_pk_mul_f32 v[58:59], v[96:97], v[58:59] op_sel:[1,0]
	v_pk_mul_f32 v[56:57], v[96:97], v[56:57] op_sel:[1,0]
	v_pk_fma_f32 v[44:45], v[158:159], v[58:59], v[44:45]
	v_pk_fma_f32 v[46:47], v[156:157], v[56:57], v[46:47]
	v_pk_fma_f32 v[54:55], v[134:135], s[28:29], v[54:55] op_sel_hi:[1,0,1]
	v_pk_fma_f32 v[52:53], v[132:133], s[28:29], v[52:53] op_sel_hi:[1,0,1]
	v_pk_fma_f32 v[46:47], v[130:131], s[28:29], v[46:47] op_sel_hi:[1,0,1]
	v_pk_fma_f32 v[44:45], v[128:129], s[28:29], v[44:45] op_sel_hi:[1,0,1]
	global_store_dwordx4 v[64:65], v[52:55], off offset:512
	global_store_dwordx4 v[64:65], v[44:47], off offset:528
	s_nop 1
	v_sub_f32_e32 v45, v83, v100
	v_sub_f32_e32 v44, v82, v100
	v_sub_f32_e32 v47, v81, v100
	v_sub_f32_e32 v46, v80, v100
	v_pk_mul_f32 v[46:47], v[100:101], v[46:47] op_sel:[1,0]
	v_pk_mul_f32 v[44:45], v[100:101], v[44:45] op_sel:[1,0]
	v_pk_fma_f32 v[48:49], v[170:171], v[46:47], v[48:49]
	v_pk_fma_f32 v[44:45], v[168:169], v[44:45], v[50:51]
	v_sub_f32_e32 v51, v85, v100
	v_pk_fma_f32 v[46:47], v[142:143], s[28:29], v[44:45] op_sel_hi:[1,0,1]
	v_pk_fma_f32 v[44:45], v[140:141], s[28:29], v[48:49] op_sel_hi:[1,0,1]
	v_sub_f32_e32 v49, v87, v100
	v_sub_f32_e32 v48, v86, v100
	v_sub_f32_e32 v50, v84, v100
	v_pk_mul_f32 v[48:49], v[100:101], v[48:49] op_sel:[1,0]
	v_pk_mul_f32 v[50:51], v[100:101], v[50:51] op_sel:[1,0]
	v_pk_fma_f32 v[42:43], v[164:165], v[48:49], v[42:43]
	v_lshl_add_u64 v[48:49], s[6:7], 0, v[102:103]
	v_pk_fma_f32 v[40:41], v[166:167], v[50:51], v[40:41]
	v_pk_fma_f32 v[42:43], v[138:139], s[28:29], v[42:43] op_sel_hi:[1,0,1]
	v_lshl_add_u64 v[48:49], v[48:49], 0, v[154:155]
	v_pk_fma_f32 v[40:41], v[136:137], s[28:29], v[40:41] op_sel_hi:[1,0,1]
	global_store_dwordx4 v[48:49], v[44:47], off
	global_store_dwordx4 v[48:49], v[40:43], off offset:16
	s_nop 1
	v_sub_f32_e32 v43, v89, v100
	v_sub_f32_e32 v42, v88, v100
	v_sub_f32_e32 v41, v91, v100
	v_sub_f32_e32 v40, v90, v100
	v_pk_mul_f32 v[42:43], v[100:101], v[42:43] op_sel:[1,0]
	v_pk_mul_f32 v[40:41], v[100:101], v[40:41] op_sel:[1,0]
	v_pk_fma_f32 v[36:37], v[162:163], v[42:43], v[36:37]
	v_sub_f32_e32 v43, v93, v100
	v_sub_f32_e32 v42, v92, v100
	v_pk_fma_f32 v[38:39], v[160:161], v[40:41], v[38:39]
	v_sub_f32_e32 v41, v95, v100
	v_sub_f32_e32 v40, v94, v100
	v_pk_mul_f32 v[42:43], v[100:101], v[42:43] op_sel:[1,0]
	v_pk_mul_f32 v[40:41], v[100:101], v[40:41] op_sel:[1,0]
	v_pk_fma_f32 v[32:33], v[158:159], v[42:43], v[32:33]
	v_pk_fma_f32 v[38:39], v[134:135], s[28:29], v[38:39] op_sel_hi:[1,0,1]
	v_pk_fma_f32 v[36:37], v[132:133], s[28:29], v[36:37] op_sel_hi:[1,0,1]
	v_pk_fma_f32 v[34:35], v[156:157], v[40:41], v[34:35]
	v_pk_fma_f32 v[32:33], v[128:129], s[28:29], v[32:33] op_sel_hi:[1,0,1]
	v_pk_fma_f32 v[34:35], v[130:131], s[28:29], v[34:35] op_sel_hi:[1,0,1]
	global_store_dwordx4 v[48:49], v[36:39], off offset:512
	global_store_dwordx4 v[48:49], v[32:35], off offset:528
	v_add_u32_e32 v48, 0xb0, v172
	v_ashrrev_i32_e32 v49, 31, v48
	v_add_u32_e32 v32, 0xa0, v172
	v_ashrrev_i32_e32 v33, 31, v32
	v_lshl_add_u64 v[34:35], v[32:33], 3, s[16:17]
	global_load_dwordx2 v[64:65], v[34:35], off
	v_lshlrev_b64 v[66:67], 12, v[32:33]
	v_lshl_add_u64 v[32:33], s[8:9], 0, v[66:67]
	v_lshl_add_u64 v[44:45], v[32:33], 0, v[154:155]
	global_load_dwordx4 v[32:35], v[44:45], off
	global_load_dwordx4 v[36:39], v[44:45], off offset:16
	global_load_dwordx4 v[40:43], v[44:45], off offset:512
	s_nop 0
	global_load_dwordx4 v[44:47], v[44:45], off offset:528
	v_lshl_add_u64 v[50:51], v[48:49], 3, s[16:17]
	global_load_dwordx2 v[68:69], v[50:51], off
	v_lshlrev_b64 v[70:71], 12, v[48:49]
	v_lshl_add_u64 v[48:49], s[8:9], 0, v[70:71]
	v_lshl_add_u64 v[60:61], v[48:49], 0, v[154:155]
	global_load_dwordx4 v[48:51], v[60:61], off
	global_load_dwordx4 v[52:55], v[60:61], off offset:16
	global_load_dwordx4 v[56:59], v[60:61], off offset:512
	s_nop 0
	global_load_dwordx4 v[60:63], v[60:61], off offset:528
	s_waitcnt vmcnt(0) lgkmcnt(0)
	v_sub_f32_e32 v35, v35, v64
	v_sub_f32_e32 v34, v34, v64
	v_sub_f32_e32 v33, v33, v64
	v_sub_f32_e32 v32, v32, v64
	v_pk_mul_f32 v[32:33], v[64:65], v[32:33] op_sel:[1,0]
	v_pk_mul_f32 v[34:35], v[64:65], v[34:35] op_sel:[1,0]
	v_pk_fma_f32 v[28:29], v[170:171], v[32:33], v[28:29]
	v_pk_fma_f32 v[30:31], v[168:169], v[34:35], v[30:31]
	v_sub_f32_e32 v33, v39, v64
	v_sub_f32_e32 v32, v38, v64
	v_sub_f32_e32 v35, v37, v64
	v_sub_f32_e32 v34, v36, v64
	v_pk_mul_f32 v[34:35], v[64:65], v[34:35] op_sel:[1,0]
	v_pk_mul_f32 v[32:33], v[64:65], v[32:33] op_sel:[1,0]
	v_pk_fma_f32 v[24:25], v[166:167], v[34:35], v[24:25]
	v_pk_fma_f32 v[26:27], v[164:165], v[32:33], v[26:27]
	v_lshl_add_u64 v[32:33], s[6:7], 0, v[66:67]
	v_pk_fma_f32 v[30:31], v[142:143], s[28:29], v[30:31] op_sel_hi:[1,0,1]
	v_pk_fma_f32 v[28:29], v[140:141], s[28:29], v[28:29] op_sel_hi:[1,0,1]
	v_pk_fma_f32 v[26:27], v[138:139], s[28:29], v[26:27] op_sel_hi:[1,0,1]
	v_pk_fma_f32 v[24:25], v[136:137], s[28:29], v[24:25] op_sel_hi:[1,0,1]
	v_lshl_add_u64 v[32:33], v[32:33], 0, v[154:155]
	global_store_dwordx4 v[32:33], v[28:31], off
	global_store_dwordx4 v[32:33], v[24:27], off offset:16
	s_nop 1
	v_sub_f32_e32 v25, v43, v64
	v_sub_f32_e32 v24, v42, v64
	v_sub_f32_e32 v27, v41, v64
	v_sub_f32_e32 v26, v40, v64
	v_pk_mul_f32 v[26:27], v[64:65], v[26:27] op_sel:[1,0]
	v_pk_mul_f32 v[24:25], v[64:65], v[24:25] op_sel:[1,0]
	v_pk_fma_f32 v[20:21], v[162:163], v[26:27], v[20:21]
	v_pk_fma_f32 v[22:23], v[160:161], v[24:25], v[22:23]
	v_sub_f32_e32 v25, v47, v64
	v_sub_f32_e32 v24, v46, v64
	v_sub_f32_e32 v27, v45, v64
	v_sub_f32_e32 v26, v44, v64
	v_pk_mul_f32 v[26:27], v[64:65], v[26:27] op_sel:[1,0]
	v_pk_mul_f32 v[24:25], v[64:65], v[24:25] op_sel:[1,0]
	v_pk_fma_f32 v[12:13], v[158:159], v[26:27], v[12:13]
	v_pk_fma_f32 v[14:15], v[156:157], v[24:25], v[14:15]
	v_pk_fma_f32 v[22:23], v[134:135], s[28:29], v[22:23] op_sel_hi:[1,0,1]
	v_pk_fma_f32 v[20:21], v[132:133], s[28:29], v[20:21] op_sel_hi:[1,0,1]
	v_pk_fma_f32 v[14:15], v[130:131], s[28:29], v[14:15] op_sel_hi:[1,0,1]
	v_pk_fma_f32 v[12:13], v[128:129], s[28:29], v[12:13] op_sel_hi:[1,0,1]
	global_store_dwordx4 v[32:33], v[20:23], off offset:512
	global_store_dwordx4 v[32:33], v[12:15], off offset:528
	s_nop 1
	v_sub_f32_e32 v13, v51, v68
	v_sub_f32_e32 v12, v50, v68
	v_sub_f32_e32 v15, v49, v68
	v_sub_f32_e32 v14, v48, v68
	v_pk_mul_f32 v[14:15], v[68:69], v[14:15] op_sel:[1,0]
	v_pk_mul_f32 v[12:13], v[68:69], v[12:13] op_sel:[1,0]
	v_pk_fma_f32 v[16:17], v[170:171], v[14:15], v[16:17]
	v_pk_fma_f32 v[12:13], v[168:169], v[12:13], v[18:19]
	v_sub_f32_e32 v19, v53, v68
	v_pk_fma_f32 v[14:15], v[142:143], s[28:29], v[12:13] op_sel_hi:[1,0,1]
	v_pk_fma_f32 v[12:13], v[140:141], s[28:29], v[16:17] op_sel_hi:[1,0,1]
	v_sub_f32_e32 v17, v55, v68
	v_sub_f32_e32 v16, v54, v68
	v_sub_f32_e32 v18, v52, v68
	v_pk_mul_f32 v[18:19], v[68:69], v[18:19] op_sel:[1,0]
	v_pk_mul_f32 v[16:17], v[68:69], v[16:17] op_sel:[1,0]
	v_pk_fma_f32 v[8:9], v[166:167], v[18:19], v[8:9]
	v_pk_fma_f32 v[10:11], v[164:165], v[16:17], v[10:11]
	v_lshl_add_u64 v[16:17], s[6:7], 0, v[70:71]
	v_pk_fma_f32 v[10:11], v[138:139], s[28:29], v[10:11] op_sel_hi:[1,0,1]
	v_pk_fma_f32 v[8:9], v[136:137], s[28:29], v[8:9] op_sel_hi:[1,0,1]
	v_lshl_add_u64 v[16:17], v[16:17], 0, v[154:155]
	global_store_dwordx4 v[16:17], v[12:15], off
	global_store_dwordx4 v[16:17], v[8:11], off offset:16
	s_nop 1
	v_sub_f32_e32 v9, v59, v68
	v_sub_f32_e32 v8, v58, v68
	v_sub_f32_e32 v11, v57, v68
	v_sub_f32_e32 v10, v56, v68
	v_pk_mul_f32 v[10:11], v[68:69], v[10:11] op_sel:[1,0]
	v_pk_mul_f32 v[8:9], v[68:69], v[8:9] op_sel:[1,0]
	v_pk_fma_f32 v[4:5], v[162:163], v[10:11], v[4:5]
	v_pk_fma_f32 v[6:7], v[160:161], v[8:9], v[6:7]
	v_sub_f32_e32 v9, v63, v68
	v_sub_f32_e32 v8, v62, v68
	v_sub_f32_e32 v11, v61, v68
	v_sub_f32_e32 v10, v60, v68
	v_pk_mul_f32 v[10:11], v[68:69], v[10:11] op_sel:[1,0]
	v_pk_mul_f32 v[8:9], v[68:69], v[8:9] op_sel:[1,0]
	v_pk_fma_f32 v[6:7], v[134:135], s[28:29], v[6:7] op_sel_hi:[1,0,1]
	v_pk_fma_f32 v[4:5], v[132:133], s[28:29], v[4:5] op_sel_hi:[1,0,1]
	v_pk_fma_f32 v[2:3], v[156:157], v[8:9], v[2:3]
	v_pk_fma_f32 v[0:1], v[158:159], v[10:11], v[0:1]
	v_pk_fma_f32 v[2:3], v[130:131], s[28:29], v[2:3] op_sel_hi:[1,0,1]
	v_pk_fma_f32 v[0:1], v[128:129], s[28:29], v[0:1] op_sel_hi:[1,0,1]
	global_store_dwordx4 v[16:17], v[4:7], off offset:512
	global_store_dwordx4 v[16:17], v[0:3], off offset:528
	s_cbranch_vccnz .LBB0_1156
	s_andn2_b64 vcc, exec, s[14:15]
	s_cbranch_vccnz .LBB0_1155
	s_barrier
	s_branch .LBB0_1155

.LBB0_1179:
	v_mov_b64_e32 v[12:13], s[38:39]
	global_load_dword v1, v[12:13], off offset:1024 sc1
	s_waitcnt lgkmcnt(0)
	global_load_dword v0, v[12:13], off offset:1280 sc1
	global_load_dword v2, v[12:13], off offset:1536 sc1
	s_or_b64 s[18:19], s[18:19], exec
	s_or_b64 s[16:17], s[16:17], exec
	s_waitcnt vmcnt(0) lgkmcnt(0)
	v_add_u32_e32 v3, v0, v1
	v_add_u32_e32 v4, v3, v2
	global_load_dword v3, v[12:13], off offset:1792 sc1
	s_waitcnt vmcnt(0) lgkmcnt(0)
	v_add_u32_e32 v5, v4, v3
	global_load_dword v4, v[12:13], off offset:2048 sc1
	s_waitcnt vmcnt(0) lgkmcnt(0)
	v_add_u32_e32 v6, v5, v4
	global_load_dword v5, v[12:13], off offset:2304 sc1
	s_waitcnt vmcnt(0) lgkmcnt(0)
	v_add_u32_e32 v7, v6, v5
	global_load_dword v6, v[12:13], off offset:2560 sc1
	s_waitcnt vmcnt(0) lgkmcnt(0)
	v_add_u32_e32 v8, v7, v6
	global_load_dword v7, v[12:13], off offset:2816 sc1
	s_waitcnt vmcnt(0) lgkmcnt(0)
	v_add_u32_e32 v9, v8, v7
	global_load_dword v8, v[12:13], off offset:3072 sc1
	s_waitcnt vmcnt(0) lgkmcnt(0)
	v_add_u32_e32 v10, v9, v8
	global_load_dword v9, v[12:13], off offset:3328 sc1
	s_waitcnt vmcnt(0) lgkmcnt(0)
	v_add_u32_e32 v11, v10, v9
	global_load_dword v10, v[12:13], off offset:3584 sc1
	s_waitcnt vmcnt(0) lgkmcnt(0)
	v_add_u32_e32 v14, v11, v10
	global_load_dword v11, v[12:13], off offset:3840 sc1
	v_mov_b64_e32 v[12:13], s[4:5]
	global_load_dword v12, v[12:13], off sc1
	s_waitcnt vmcnt(0) lgkmcnt(0)
	v_add_u32_e32 v14, v14, v11
	v_add_u32_e32 v16, v14, v12
	v_mov_b64_e32 v[14:15], s[6:7]
	global_load_dword v13, v[14:15], off sc1
	v_mov_b64_e32 v[14:15], s[8:9]
	global_load_dword v14, v[14:15], off sc1
	s_waitcnt vmcnt(0) lgkmcnt(0)
	v_add_u32_e32 v16, v16, v13
	v_add_u32_e32 v18, v16, v14
	v_mov_b64_e32 v[16:17], s[10:11]
	global_load_dword v15, v[16:17], off sc1
	s_waitcnt vmcnt(0) lgkmcnt(0)
	v_add_u32_e32 v16, v18, v15
	v_cmp_ne_u32_e32 vcc, s74, v16
	s_and_saveexec_b64 s[20:21], vcc
	s_cbranch_execz .LBB0_1178
	s_and_b32 s24, s30, 0xff
	s_mov_b64 s[22:23], -1
	s_cmp_eq_u32 s24, 0
	s_mov_b64 s[26:27], -1
	s_mov_b64 s[24:25], -1
	s_sleep 1
	s_cbranch_scc1 .LBB0_1182
	s_and_saveexec_b64 s[28:29], s[26:27]
	s_cbranch_execz .LBB0_1177
	s_branch .LBB0_1185
.LBB0_1182:
	v_mov_b64_e32 v[16:17], s[38:39]
	global_load_dword v16, v[16:17], off offset:512 sc1
	s_mov_b64 s[26:27], 0
	s_waitcnt vmcnt(0) lgkmcnt(0)
	v_cmp_eq_u32_e32 vcc, 0, v16
	s_and_saveexec_b64 s[28:29], vcc
	s_cmp_lt_u32 s30, 0x100001
	s_cselect_b64 s[26:27], -1, 0
	s_xor_b64 s[24:25], exec, -1
	s_and_b64 s[26:27], s[26:27], exec
	s_or_b64 exec, exec, s[28:29]
	s_and_saveexec_b64 s[28:29], s[26:27]
	s_cbranch_execz .LBB0_1177

.LBB0_1189:
	s_lshl_b32 s4, s41, 8
	s_add_u32 s25, s38, s4
	s_addc_u32 s24, s39, 0
	v_mov_b32_e32 v1, s25
	v_add_co_u32_e32 v4, vcc, 0x1000, v1
	v_mov_b32_e32 v1, s24
	s_nop 0
	v_addc_co_u32_e32 v5, vcc, 0, v1, vcc
	v_mov_b32_e32 v1, 1
	flat_atomic_add v3, v[4:5], v1 offset:1024 sc0
	v_cvt_f32_u32_e32 v1, v2
	v_sub_u32_e32 v4, 0, v2
	v_rcp_iflag_f32_e32 v1, v1
	s_nop 0
	v_mul_f32_e32 v1, 0x4f7ffffe, v1
	v_cvt_u32_f32_e32 v1, v1
	v_mul_lo_u32 v4, v4, v1
	v_mul_hi_u32 v4, v1, v4
	v_add_u32_e32 v1, v1, v4
	s_waitcnt vmcnt(0) lgkmcnt(0)
	v_mul_hi_u32 v1, v3, v1
	v_mul_lo_u32 v4, v1, v2
	v_sub_u32_e32 v4, v3, v4
	v_cmp_ge_u32_e32 vcc, v4, v2
	v_add_u32_e32 v5, 1, v1
	s_nop 0
	v_cndmask_b32_e32 v1, v1, v5, vcc
	v_sub_u32_e32 v5, v4, v2
	v_cndmask_b32_e32 v4, v4, v5, vcc
	v_cmp_ge_u32_e32 vcc, v4, v2
	v_add_u32_e32 v4, 1, v1
	s_nop 0
	v_cndmask_b32_e32 v1, v1, v4, vcc
	v_add_u32_e32 v4, 1, v3
	v_mad_u64_u32 v[2:3], s[4:5], v2, v1, v[2:3]
	v_cmp_ne_u32_e32 vcc, v4, v2
	s_and_saveexec_b64 s[4:5], vcc
	s_xor_b64 s[4:5], exec, s[4:5]
	s_cbranch_execz .LBB0_1202
	v_mov_b32_e32 v0, s25
	v_add_co_u32_e32 v2, vcc, 0x2000, v0
	v_mov_b32_e32 v0, s24
	s_nop 0
	v_addc_co_u32_e32 v3, vcc, 0, v0, vcc
	global_load_dword v0, v[2:3], off offset:1024 sc1
	s_add_u32 s8, s25, 0x2400
	s_addc_u32 s9, s24, 0
	s_waitcnt vmcnt(0) lgkmcnt(0)
	v_cmp_eq_u32_e32 vcc, v0, v1
	s_and_saveexec_b64 s[6:7], vcc
	s_cbranch_execz .LBB0_1201
	s_mov_b32 s26, 1
	s_mov_b64 s[10:11], 0
	s_branch .LBB0_1193

.LBB0_1193:
	s_and_b32 s18, s26, 0xff
	s_mov_b64 s[16:17], -1
	s_cmp_lg_u32 s18, 0
	s_mov_b64 s[18:19], -1
	s_sleep 1
	s_cbranch_scc1 .LBB0_1197
	v_mov_b64_e32 v[2:3], s[38:39]
	global_load_dword v0, v[2:3], off offset:512 sc1
	s_mov_b64 s[18:19], 0
	s_mov_b64 s[20:21], -1
	s_waitcnt vmcnt(0) lgkmcnt(0)
	v_cmp_eq_u32_e32 vcc, 0, v0
	s_and_saveexec_b64 s[22:23], vcc
	s_cmp_lt_u32 s26, 0x100001
	s_cselect_b64 s[18:19], -1, 0
	s_xor_b64 s[20:21], exec, -1
	s_and_b64 s[18:19], s[18:19], exec
	s_or_b64 exec, exec, s[22:23]
.LBB0_1197:
	s_andn2_b64 s[14:15], s[14:15], exec
	s_and_b64 s[20:21], s[20:21], exec
	s_or_b64 s[14:15], s[14:15], s[20:21]
	s_and_saveexec_b64 s[20:21], s[18:19]
	s_cbranch_execz .LBB0_1192
	v_mov_b64_e32 v[2:3], s[8:9]
	global_load_dword v0, v[2:3], off sc1
	s_add_i32 s26, s26, 1
	s_or_b64 s[14:15], s[14:15], exec
	s_waitcnt vmcnt(0) lgkmcnt(0)
	v_cmp_ne_u32_e32 vcc, v0, v1
	s_orn2_b64 s[16:17], vcc, exec
	s_branch .LBB0_1192

.LBB0_1202:
	s_andn2_saveexec_b64 s[4:5], s[4:5]
	s_cbranch_execz .LBB0_1218
	v_mov_b32_e32 v1, s38
	v_add_co_u32_e32 v2, vcc, 0x3000, v1
	v_mov_b32_e32 v1, s39
	buffer_wbl2 sc1
	s_waitcnt vmcnt(0)
	v_addc_co_u32_e32 v3, vcc, 0, v1, vcc
	v_mov_b32_e32 v1, 1
	flat_atomic_add v1, v[2:3], v1 offset:1024 sc0
	v_cvt_f32_u32_e32 v2, v0
	v_sub_u32_e32 v3, 0, v0
	s_mov_b64 s[8:9], -1
	v_rcp_iflag_f32_e32 v2, v2
	s_nop 0
	v_mul_f32_e32 v2, 0x4f7ffffe, v2
	v_cvt_u32_f32_e32 v2, v2
	v_mul_lo_u32 v3, v3, v2
	v_mul_hi_u32 v3, v2, v3
	v_add_u32_e32 v2, v2, v3
	s_waitcnt vmcnt(0) lgkmcnt(0)
	v_mul_hi_u32 v2, v1, v2
	v_mul_lo_u32 v3, v2, v0
	v_sub_u32_e32 v3, v1, v3
	v_cmp_ge_u32_e32 vcc, v3, v0
	v_add_u32_e32 v4, 1, v2
	s_nop 0
	v_cndmask_b32_e32 v2, v2, v4, vcc
	v_sub_u32_e32 v4, v3, v0
	v_cndmask_b32_e32 v3, v3, v4, vcc
	v_cmp_ge_u32_e32 vcc, v3, v0
	v_add_u32_e32 v3, 1, v2
	s_nop 0
	v_cndmask_b32_e32 v2, v2, v3, vcc
	v_add_u32_e32 v3, 1, v1
	v_mad_u64_u32 v[0:1], s[4:5], v0, v2, v[0:1]
	s_add_u32 s4, s38, 0x3500
	s_addc_u32 s5, s39, 0
	v_cmp_ne_u32_e32 vcc, v3, v0
	v_mov_b64_e32 v[0:1], s[4:5]
	s_and_saveexec_b64 s[6:7], vcc
	s_cbranch_execz .LBB0_1215
	v_mov_b64_e32 v[0:1], s[4:5]
	global_load_dword v0, v[0:1], off sc1
	s_mov_b64 s[12:13], 0
	s_waitcnt vmcnt(0) lgkmcnt(0)
	v_cmp_eq_u32_e32 vcc, v0, v2
	s_and_saveexec_b64 s[10:11], vcc
	s_cbranch_execz .LBB0_1214
	s_add_u32 s8, s38, 0x200
	s_addc_u32 s9, s39, 0
	s_mov_b32 s26, 1
	s_branch .LBB0_1207

.LBB0_1209:
	v_mov_b64_e32 v[0:1], s[8:9]
	global_load_dword v0, v[0:1], off sc1
	s_mov_b64 s[20:21], 0
	s_mov_b64 s[18:19], -1
	s_waitcnt vmcnt(0) lgkmcnt(0)
	v_cmp_eq_u32_e32 vcc, 0, v0
	s_and_saveexec_b64 s[22:23], vcc
	s_cmp_lt_u32 s26, 0x100001
	s_cselect_b64 s[20:21], -1, 0
	s_xor_b64 s[18:19], exec, -1
	s_and_b64 s[20:21], s[20:21], exec
	s_or_b64 exec, exec, s[22:23]
	s_and_saveexec_b64 s[22:23], s[20:21]
	s_cbranch_execz .LBB0_1206
.LBB0_1212:
	v_mov_b64_e32 v[0:1], s[4:5]
	global_load_dword v0, v[0:1], off sc1
	s_add_i32 s26, s26, 1
	s_or_b64 s[18:19], s[18:19], exec
	s_waitcnt vmcnt(0) lgkmcnt(0)
	v_cmp_ne_u32_e32 vcc, v0, v2
	s_orn2_b64 s[16:17], vcc, exec
	s_branch .LBB0_1206

.LBB0_1222:
	s_or_b64 exec, exec, s[6:7]
	global_load_dwordx4 v[126:129], v[134:135], off
	global_load_dwordx4 v[130:133], v[136:137], off
	v_pk_mul_f32 v[94:95], v[150:151], v[74:75] op_sel_hi:[1,0]
	v_pk_mul_f32 v[104:105], v[104:105], v[74:75] op_sel_hi:[1,0]
	v_lshl_add_u64 v[62:63], s[8:9], 0, v[138:139]
	s_mov_b32 s6, 0x3a00000
	v_pk_mul_f32 v[96:97], v[96:97], v[78:79] op_sel_hi:[1,0]
	v_pk_mul_f32 v[64:65], v[64:65], v[74:75] op_sel_hi:[1,0]
	v_pk_mul_f32 v[34:35], v[34:35], v[74:75] op_sel_hi:[1,0]
	v_pk_mul_f32 v[32:33], v[32:33], v[74:75] op_sel_hi:[1,0]
	v_pk_mul_f32 v[2:3], v[2:3], v[74:75] op_sel_hi:[1,0]
	v_pk_mul_f32 v[0:1], v[0:1], v[74:75] op_sel_hi:[1,0]
	s_add_i32 s10, s10, s12
	s_add_u32 s14, s14, s16
	s_addc_u32 s15, s15, s17
	v_lshl_add_u64 v[138:139], v[138:139], 0, s[18:19]
	v_lshl_add_u64 v[140:141], v[140:141], 0, s[20:21]
	s_cmp_lt_i32 s10, 0x8000
	s_waitcnt vmcnt(0) lgkmcnt(0)
	v_pk_fma_f32 v[94:95], v[94:95], v[128:129], v[132:133]
	v_pk_fma_f32 v[104:105], v[104:105], v[126:127], v[130:131]
	v_cvt_pk_bf16_f32 v151, v94, v95
	v_pk_mul_f32 v[94:95], v[98:99], v[78:79] op_sel_hi:[1,0]
	v_cvt_pk_bf16_f32 v150, v104, v105
	v_add_co_u32_e32 v104, vcc, s6, v62
	v_pk_fma_f32 v[94:95], v[94:95], v[128:129], v[132:133]
	v_pk_fma_f32 v[96:97], v[96:97], v[126:127], v[130:131]
	v_addc_co_u32_e32 v105, vcc, 0, v63, vcc
	v_cvt_pk_bf16_f32 v96, v96, v97
	v_cvt_pk_bf16_f32 v97, v94, v95
	global_store_dwordx2 v[104:105], v[96:97], off offset:2048
	v_pk_mul_f32 v[94:95], v[152:153], v[82:83] op_sel_hi:[1,0]
	v_pk_mul_f32 v[96:97], v[108:109], v[82:83] op_sel_hi:[1,0]
	s_mov_b32 s6, 0x3a01000
	v_pk_fma_f32 v[94:95], v[94:95], v[128:129], v[132:133]
	v_pk_fma_f32 v[96:97], v[96:97], v[126:127], v[130:131]
	v_add_co_u32_e32 v108, vcc, s6, v62
	v_cvt_pk_bf16_f32 v96, v96, v97
	v_cvt_pk_bf16_f32 v97, v94, v95
	v_addc_co_u32_e32 v109, vcc, 0, v63, vcc
	global_store_dwordx2 v[108:109], v[96:97], off
	v_pk_mul_f32 v[94:95], v[154:155], v[86:87] op_sel_hi:[1,0]
	v_pk_mul_f32 v[96:97], v[100:101], v[86:87] op_sel_hi:[1,0]
	v_pk_fma_f32 v[94:95], v[94:95], v[128:129], v[132:133]
	v_pk_fma_f32 v[96:97], v[96:97], v[126:127], v[130:131]
	s_mov_b32 s6, 0x3a02000
	v_cvt_pk_bf16_f32 v96, v96, v97
	v_cvt_pk_bf16_f32 v97, v94, v95
	global_store_dwordx2 v[108:109], v[96:97], off offset:2048
	v_pk_mul_f32 v[94:95], v[156:157], v[90:91] op_sel_hi:[1,0]
	v_pk_mul_f32 v[96:97], v[116:117], v[90:91] op_sel_hi:[1,0]
	v_pk_fma_f32 v[94:95], v[94:95], v[128:129], v[132:133]
	v_pk_fma_f32 v[96:97], v[96:97], v[126:127], v[130:131]
	v_add_co_u32_e32 v116, vcc, s6, v62
	v_cvt_pk_bf16_f32 v96, v96, v97
	v_cvt_pk_bf16_f32 v97, v94, v95
	v_addc_co_u32_e32 v117, vcc, 0, v63, vcc
	global_store_dwordx2 v[116:117], v[96:97], off
	v_pk_mul_f32 v[94:95], v[158:159], v[102:103] op_sel_hi:[1,0]
	v_pk_mul_f32 v[96:97], v[112:113], v[102:103] op_sel_hi:[1,0]
	v_pk_fma_f32 v[94:95], v[94:95], v[128:129], v[132:133]
	v_pk_fma_f32 v[96:97], v[96:97], v[126:127], v[130:131]
	s_mov_b32 s6, 0x3a03000
	v_cvt_pk_bf16_f32 v96, v96, v97
	v_cvt_pk_bf16_f32 v97, v94, v95
	global_store_dwordx2 v[116:117], v[96:97], off offset:2048
	v_pk_mul_f32 v[94:95], v[160:161], v[114:115] op_sel_hi:[1,0]
	v_pk_mul_f32 v[96:97], v[124:125], v[114:115] op_sel_hi:[1,0]
	v_pk_fma_f32 v[94:95], v[94:95], v[128:129], v[132:133]
	v_pk_fma_f32 v[96:97], v[96:97], v[126:127], v[130:131]
	v_add_co_u32_e32 v112, vcc, s6, v62
	v_cvt_pk_bf16_f32 v96, v96, v97
	v_cvt_pk_bf16_f32 v97, v94, v95
	v_addc_co_u32_e32 v113, vcc, 0, v63, vcc
	v_pk_mul_f32 v[62:63], v[162:163], v[118:119] op_sel_hi:[1,0]
	v_pk_mul_f32 v[94:95], v[120:121], v[118:119] op_sel_hi:[1,0]
	v_pk_fma_f32 v[62:63], v[62:63], v[128:129], v[132:133]
	v_pk_fma_f32 v[94:95], v[94:95], v[126:127], v[130:131]
	global_store_dwordx2 v[104:105], v[150:151], off
	v_cvt_pk_bf16_f32 v94, v94, v95
	v_cvt_pk_bf16_f32 v95, v62, v63
	global_store_dwordx2 v[112:113], v[96:97], off
	global_store_dwordx2 v[112:113], v[94:95], off offset:2048
	global_load_dwordx4 v[94:97], v[134:135], off offset:1024
	s_nop 0
	global_load_dwordx4 v[98:101], v[136:137], off offset:1024
	v_pk_mul_f32 v[62:63], v[66:67], v[74:75] op_sel_hi:[1,0]
	s_waitcnt vmcnt(0) lgkmcnt(0)
	v_pk_fma_f32 v[64:65], v[64:65], v[94:95], v[98:99]
	v_pk_fma_f32 v[62:63], v[62:63], v[96:97], v[100:101]
	v_cvt_pk_bf16_f32 v64, v64, v65
	v_cvt_pk_bf16_f32 v65, v62, v63
	global_store_dwordx2 v[104:105], v[64:65], off offset:512
	v_pk_mul_f32 v[62:63], v[106:107], v[78:79] op_sel_hi:[1,0]
	v_pk_mul_f32 v[64:65], v[68:69], v[78:79] op_sel_hi:[1,0]
	v_pk_fma_f32 v[62:63], v[62:63], v[96:97], v[100:101]
	v_pk_fma_f32 v[64:65], v[64:65], v[94:95], v[98:99]
	s_nop 0
	v_cvt_pk_bf16_f32 v64, v64, v65
	v_cvt_pk_bf16_f32 v65, v62, v63
	global_store_dwordx2 v[104:105], v[64:65], off offset:2560
	v_pk_mul_f32 v[62:63], v[110:111], v[82:83] op_sel_hi:[1,0]
	v_pk_mul_f32 v[64:65], v[72:73], v[82:83] op_sel_hi:[1,0]
	v_pk_fma_f32 v[62:63], v[62:63], v[96:97], v[100:101]
	v_pk_fma_f32 v[64:65], v[64:65], v[94:95], v[98:99]
	s_nop 0
	v_cvt_pk_bf16_f32 v64, v64, v65
	v_cvt_pk_bf16_f32 v65, v62, v63
	global_store_dwordx2 v[108:109], v[64:65], off offset:512
	v_pk_mul_f32 v[62:63], v[142:143], v[86:87] op_sel_hi:[1,0]
	v_pk_mul_f32 v[64:65], v[76:77], v[86:87] op_sel_hi:[1,0]
	v_pk_fma_f32 v[62:63], v[62:63], v[96:97], v[100:101]
	v_pk_fma_f32 v[64:65], v[64:65], v[94:95], v[98:99]
	s_nop 0
	v_cvt_pk_bf16_f32 v64, v64, v65
	v_cvt_pk_bf16_f32 v65, v62, v63
	global_store_dwordx2 v[108:109], v[64:65], off offset:2560
	v_pk_mul_f32 v[62:63], v[144:145], v[90:91] op_sel_hi:[1,0]
	v_pk_mul_f32 v[64:65], v[80:81], v[90:91] op_sel_hi:[1,0]
	v_pk_fma_f32 v[62:63], v[62:63], v[96:97], v[100:101]
	v_pk_fma_f32 v[64:65], v[64:65], v[94:95], v[98:99]
	s_nop 0
	v_cvt_pk_bf16_f32 v64, v64, v65
	v_cvt_pk_bf16_f32 v65, v62, v63
	global_store_dwordx2 v[116:117], v[64:65], off offset:512
	v_pk_mul_f32 v[62:63], v[146:147], v[102:103] op_sel_hi:[1,0]
	v_pk_mul_f32 v[64:65], v[84:85], v[102:103] op_sel_hi:[1,0]
	v_pk_fma_f32 v[62:63], v[62:63], v[96:97], v[100:101]
	v_pk_fma_f32 v[64:65], v[64:65], v[94:95], v[98:99]
	s_nop 0
	v_cvt_pk_bf16_f32 v64, v64, v65
	v_cvt_pk_bf16_f32 v65, v62, v63
	global_store_dwordx2 v[116:117], v[64:65], off offset:2560
	v_pk_mul_f32 v[62:63], v[148:149], v[114:115] op_sel_hi:[1,0]
	v_pk_mul_f32 v[64:65], v[88:89], v[114:115] op_sel_hi:[1,0]
	v_pk_fma_f32 v[62:63], v[62:63], v[96:97], v[100:101]
	v_pk_fma_f32 v[64:65], v[64:65], v[94:95], v[98:99]
	s_nop 0
	v_cvt_pk_bf16_f32 v64, v64, v65
	v_cvt_pk_bf16_f32 v65, v62, v63
	global_store_dwordx2 v[112:113], v[64:65], off offset:512
	v_pk_mul_f32 v[62:63], v[122:123], v[118:119] op_sel_hi:[1,0]
	v_pk_mul_f32 v[64:65], v[92:93], v[118:119] op_sel_hi:[1,0]
	v_pk_fma_f32 v[62:63], v[62:63], v[96:97], v[100:101]
	v_pk_fma_f32 v[64:65], v[64:65], v[94:95], v[98:99]
	s_nop 0
	v_cvt_pk_bf16_f32 v64, v64, v65
	v_cvt_pk_bf16_f32 v65, v62, v63
	global_store_dwordx2 v[112:113], v[64:65], off offset:2560
	global_load_dwordx4 v[62:65], v[134:135], off offset:2048
	s_nop 0
	global_load_dwordx4 v[66:69], v[136:137], off offset:2048
	s_waitcnt vmcnt(0) lgkmcnt(0)
	v_pk_fma_f32 v[34:35], v[34:35], v[64:65], v[68:69]
	v_pk_fma_f32 v[32:33], v[32:33], v[62:63], v[66:67]
	s_nop 0
	v_cvt_pk_bf16_f32 v32, v32, v33
	v_cvt_pk_bf16_f32 v33, v34, v35
	global_store_dwordx2 v[104:105], v[32:33], off offset:1024
	v_pk_mul_f32 v[32:33], v[38:39], v[78:79] op_sel_hi:[1,0]
	v_pk_mul_f32 v[34:35], v[36:37], v[78:79] op_sel_hi:[1,0]
	v_pk_fma_f32 v[32:33], v[32:33], v[64:65], v[68:69]
	v_pk_fma_f32 v[34:35], v[34:35], v[62:63], v[66:67]
	s_nop 0
	v_cvt_pk_bf16_f32 v34, v34, v35
	v_cvt_pk_bf16_f32 v35, v32, v33
	global_store_dwordx2 v[104:105], v[34:35], off offset:3072
	v_pk_mul_f32 v[32:33], v[42:43], v[82:83] op_sel_hi:[1,0]
	v_pk_mul_f32 v[34:35], v[40:41], v[82:83] op_sel_hi:[1,0]
	v_pk_fma_f32 v[32:33], v[32:33], v[64:65], v[68:69]
	v_pk_fma_f32 v[34:35], v[34:35], v[62:63], v[66:67]
	s_nop 0
	v_cvt_pk_bf16_f32 v34, v34, v35
	v_cvt_pk_bf16_f32 v35, v32, v33
	global_store_dwordx2 v[108:109], v[34:35], off offset:1024
	v_pk_mul_f32 v[32:33], v[46:47], v[86:87] op_sel_hi:[1,0]
	v_pk_mul_f32 v[34:35], v[44:45], v[86:87] op_sel_hi:[1,0]
	v_pk_fma_f32 v[32:33], v[32:33], v[64:65], v[68:69]
	v_pk_fma_f32 v[34:35], v[34:35], v[62:63], v[66:67]
	s_nop 0
	v_cvt_pk_bf16_f32 v34, v34, v35
	v_cvt_pk_bf16_f32 v35, v32, v33
	global_store_dwordx2 v[108:109], v[34:35], off offset:3072
	v_pk_mul_f32 v[32:33], v[50:51], v[90:91] op_sel_hi:[1,0]
	v_pk_mul_f32 v[34:35], v[48:49], v[90:91] op_sel_hi:[1,0]
	v_pk_fma_f32 v[32:33], v[32:33], v[64:65], v[68:69]
	v_pk_fma_f32 v[34:35], v[34:35], v[62:63], v[66:67]
	s_nop 0
	v_cvt_pk_bf16_f32 v34, v34, v35
	v_cvt_pk_bf16_f32 v35, v32, v33
	global_store_dwordx2 v[116:117], v[34:35], off offset:1024
	v_pk_mul_f32 v[32:33], v[54:55], v[102:103] op_sel_hi:[1,0]
	v_pk_mul_f32 v[34:35], v[52:53], v[102:103] op_sel_hi:[1,0]
	v_pk_fma_f32 v[32:33], v[32:33], v[64:65], v[68:69]
	v_pk_fma_f32 v[34:35], v[34:35], v[62:63], v[66:67]
	s_nop 0
	v_cvt_pk_bf16_f32 v34, v34, v35
	v_cvt_pk_bf16_f32 v35, v32, v33
	global_store_dwordx2 v[116:117], v[34:35], off offset:3072
	v_pk_mul_f32 v[32:33], v[58:59], v[114:115] op_sel_hi:[1,0]
	v_pk_mul_f32 v[34:35], v[56:57], v[114:115] op_sel_hi:[1,0]
	v_pk_fma_f32 v[32:33], v[32:33], v[64:65], v[68:69]
	v_pk_fma_f32 v[34:35], v[34:35], v[62:63], v[66:67]
	s_nop 0
	v_cvt_pk_bf16_f32 v34, v34, v35
	v_cvt_pk_bf16_f32 v35, v32, v33
	global_store_dwordx2 v[112:113], v[34:35], off offset:1024
	v_pk_mul_f32 v[32:33], v[70:71], v[118:119] op_sel_hi:[1,0]
	v_pk_mul_f32 v[34:35], v[60:61], v[118:119] op_sel_hi:[1,0]
	v_pk_fma_f32 v[32:33], v[32:33], v[64:65], v[68:69]
	v_pk_fma_f32 v[34:35], v[34:35], v[62:63], v[66:67]
	s_nop 0
	v_cvt_pk_bf16_f32 v34, v34, v35
	v_cvt_pk_bf16_f32 v35, v32, v33
	global_store_dwordx2 v[112:113], v[34:35], off offset:3072
	global_load_dwordx4 v[32:35], v[134:135], off offset:3072
	s_nop 0
	global_load_dwordx4 v[36:39], v[136:137], off offset:3072
	s_waitcnt vmcnt(0) lgkmcnt(0)
	v_pk_fma_f32 v[2:3], v[2:3], v[34:35], v[38:39]
	v_pk_fma_f32 v[0:1], v[0:1], v[32:33], v[36:37]
	s_nop 0
	v_cvt_pk_bf16_f32 v0, v0, v1
	v_cvt_pk_bf16_f32 v1, v2, v3
	global_store_dwordx2 v[104:105], v[0:1], off offset:1536
	v_pk_mul_f32 v[0:1], v[6:7], v[78:79] op_sel_hi:[1,0]
	v_pk_mul_f32 v[2:3], v[4:5], v[78:79] op_sel_hi:[1,0]
	v_pk_fma_f32 v[0:1], v[0:1], v[34:35], v[38:39]
	v_pk_fma_f32 v[2:3], v[2:3], v[32:33], v[36:37]
	s_nop 0
	v_cvt_pk_bf16_f32 v2, v2, v3
	v_cvt_pk_bf16_f32 v3, v0, v1
	global_store_dwordx2 v[104:105], v[2:3], off offset:3584
	v_pk_mul_f32 v[0:1], v[10:11], v[82:83] op_sel_hi:[1,0]
	v_pk_mul_f32 v[2:3], v[8:9], v[82:83] op_sel_hi:[1,0]
	v_pk_fma_f32 v[0:1], v[0:1], v[34:35], v[38:39]
	v_pk_fma_f32 v[2:3], v[2:3], v[32:33], v[36:37]
	s_nop 0
	v_cvt_pk_bf16_f32 v2, v2, v3
	v_cvt_pk_bf16_f32 v3, v0, v1
	global_store_dwordx2 v[108:109], v[2:3], off offset:1536
	v_pk_mul_f32 v[0:1], v[14:15], v[86:87] op_sel_hi:[1,0]
	v_pk_mul_f32 v[2:3], v[12:13], v[86:87] op_sel_hi:[1,0]
	v_pk_fma_f32 v[0:1], v[0:1], v[34:35], v[38:39]
	v_pk_fma_f32 v[2:3], v[2:3], v[32:33], v[36:37]
	s_nop 0
	v_cvt_pk_bf16_f32 v2, v2, v3
	v_cvt_pk_bf16_f32 v3, v0, v1
	global_store_dwordx2 v[108:109], v[2:3], off offset:3584
	v_pk_mul_f32 v[0:1], v[18:19], v[90:91] op_sel_hi:[1,0]
	v_pk_mul_f32 v[2:3], v[16:17], v[90:91] op_sel_hi:[1,0]
	v_pk_fma_f32 v[0:1], v[0:1], v[34:35], v[38:39]
	v_pk_fma_f32 v[2:3], v[2:3], v[32:33], v[36:37]
	s_nop 0
	v_cvt_pk_bf16_f32 v2, v2, v3
	v_cvt_pk_bf16_f32 v3, v0, v1
	global_store_dwordx2 v[116:117], v[2:3], off offset:1536
	v_pk_mul_f32 v[0:1], v[22:23], v[102:103] op_sel_hi:[1,0]
	v_pk_mul_f32 v[2:3], v[20:21], v[102:103] op_sel_hi:[1,0]
	v_pk_fma_f32 v[0:1], v[0:1], v[34:35], v[38:39]
	v_pk_fma_f32 v[2:3], v[2:3], v[32:33], v[36:37]
	s_nop 0
	v_cvt_pk_bf16_f32 v2, v2, v3
	v_cvt_pk_bf16_f32 v3, v0, v1
	global_store_dwordx2 v[116:117], v[2:3], off offset:3584
	v_pk_mul_f32 v[0:1], v[26:27], v[114:115] op_sel_hi:[1,0]
	v_pk_mul_f32 v[2:3], v[24:25], v[114:115] op_sel_hi:[1,0]
	v_pk_fma_f32 v[0:1], v[0:1], v[34:35], v[38:39]
	v_pk_fma_f32 v[2:3], v[2:3], v[32:33], v[36:37]
	s_nop 0
	v_cvt_pk_bf16_f32 v2, v2, v3
	v_cvt_pk_bf16_f32 v3, v0, v1
	global_store_dwordx2 v[112:113], v[2:3], off offset:1536
	v_pk_mul_f32 v[0:1], v[30:31], v[118:119] op_sel_hi:[1,0]
	v_pk_mul_f32 v[2:3], v[28:29], v[118:119] op_sel_hi:[1,0]
	v_pk_fma_f32 v[0:1], v[0:1], v[34:35], v[38:39]
	v_pk_fma_f32 v[2:3], v[2:3], v[32:33], v[36:37]
	s_nop 0
	v_cvt_pk_bf16_f32 v2, v2, v3
	v_cvt_pk_bf16_f32 v3, v0, v1
	global_store_dwordx2 v[112:113], v[2:3], off offset:3584
	s_cbranch_scc0 .LBB0_1239
.LBB0_1223:
	v_add_co_u32_e32 v0, vcc, 0xffff8400, v140
	s_add_u32 s13, s8, s14
	s_nop 0
	v_addc_co_u32_e32 v1, vcc, -1, v141, vcc
	v_add_co_u32_e32 v2, vcc, 0xffff8800, v140
	s_addc_u32 s11, s9, s15
	s_nop 0
	v_addc_co_u32_e32 v3, vcc, -1, v141, vcc
	global_load_dwordx4 v[104:107], v[0:1], off
	s_waitcnt vmcnt(0)
	global_load_dwordx4 v[64:67], v[2:3], off
	v_add_co_u32_e32 v0, vcc, 0xffff8c00, v140
	s_waitcnt lgkmcnt(0)
	v_add_f32_e32 v128, v104, v105
	v_addc_co_u32_e32 v1, vcc, -1, v141, vcc
	v_add_co_u32_e32 v2, vcc, 0xffff9000, v140
	v_add_f32_e32 v129, v106, v107
	s_nop 0
	v_addc_co_u32_e32 v3, vcc, -1, v141, vcc
	v_add_co_u32_e32 v4, vcc, 0xffff9400, v140
	global_load_dwordx4 v[32:35], v[0:1], off
	s_nop 0
	global_load_dwordx4 v[0:3], v[2:3], off
	v_addc_co_u32_e32 v5, vcc, -1, v141, vcc
	v_add_co_u32_e32 v6, vcc, 0xffff9800, v140
	v_add_f32_e32 v128, v128, v129
	s_nop 0
	v_addc_co_u32_e32 v7, vcc, -1, v141, vcc
	global_load_dwordx4 v[96:99], v[4:5], off
	global_load_dwordx4 v[68:71], v[6:7], off
	v_add_co_u32_e32 v4, vcc, 0xffff9c00, v140
	s_waitcnt vmcnt(0)
	v_add_f32_e32 v129, v64, v65
	v_addc_co_u32_e32 v5, vcc, -1, v141, vcc
	v_add_co_u32_e32 v6, vcc, 0xffffa000, v140
	v_add_f32_e32 v130, v66, v67
	s_nop 0
	v_addc_co_u32_e32 v7, vcc, -1, v141, vcc
	v_add_co_u32_e32 v8, vcc, 0xffffa400, v140
	global_load_dwordx4 v[36:39], v[4:5], off
	s_nop 0
	global_load_dwordx4 v[4:7], v[6:7], off
	v_addc_co_u32_e32 v9, vcc, -1, v141, vcc
	v_add_co_u32_e32 v10, vcc, 0xffffa800, v140
	v_add_f32_e32 v128, 0, v128
	s_nop 0
	v_addc_co_u32_e32 v11, vcc, -1, v141, vcc
	global_load_dwordx4 v[108:111], v[8:9], off
	global_load_dwordx4 v[72:75], v[10:11], off
	v_add_co_u32_e32 v8, vcc, 0xffffac00, v140
	v_add_f32_e32 v129, v129, v130
	s_nop 0
	v_addc_co_u32_e32 v9, vcc, -1, v141, vcc
	v_add_co_u32_e32 v10, vcc, 0xffffb000, v140
	v_add_f32_e32 v128, v128, v129
	s_nop 0
	v_addc_co_u32_e32 v11, vcc, -1, v141, vcc
	v_add_co_u32_e32 v12, vcc, 0xffffb400, v140
	global_load_dwordx4 v[40:43], v[8:9], off
	s_nop 0
	global_load_dwordx4 v[8:11], v[10:11], off
	v_addc_co_u32_e32 v13, vcc, -1, v141, vcc
	v_add_co_u32_e32 v14, vcc, 0xffffb800, v140
	s_waitcnt lgkmcnt(0)
	v_add_f32_e32 v129, v32, v33
	v_addc_co_u32_e32 v15, vcc, -1, v141, vcc
	global_load_dwordx4 v[100:103], v[12:13], off
	global_load_dwordx4 v[76:79], v[14:15], off
	v_add_co_u32_e32 v12, vcc, 0xffffbc00, v140
	v_add_f32_e32 v130, v34, v35
	s_nop 0
	v_addc_co_u32_e32 v13, vcc, -1, v141, vcc
	v_add_co_u32_e32 v14, vcc, 0xffffc000, v140
	v_add_f32_e32 v129, v129, v130
	s_nop 0
	v_addc_co_u32_e32 v15, vcc, -1, v141, vcc
	v_add_co_u32_e32 v16, vcc, 0xffffc400, v140
	global_load_dwordx4 v[44:47], v[12:13], off
	s_nop 0
	global_load_dwordx4 v[12:15], v[14:15], off
	v_addc_co_u32_e32 v17, vcc, -1, v141, vcc
	v_add_co_u32_e32 v18, vcc, 0xffffc800, v140
	v_add_f32_e32 v128, v128, v129
	s_nop 0
	v_addc_co_u32_e32 v19, vcc, -1, v141, vcc
	global_load_dwordx4 v[116:119], v[16:17], off
	global_load_dwordx4 v[80:83], v[18:19], off
	v_add_co_u32_e32 v16, vcc, 0xffffcc00, v140
	v_add_f32_e32 v129, v0, v1
	s_nop 0
	v_addc_co_u32_e32 v17, vcc, -1, v141, vcc
	v_add_co_u32_e32 v18, vcc, 0xffffd000, v140
	v_add_f32_e32 v130, v2, v3
	s_nop 0
	v_addc_co_u32_e32 v19, vcc, -1, v141, vcc
	v_add_co_u32_e32 v20, vcc, 0xffffd400, v140
	global_load_dwordx4 v[48:51], v[16:17], off
	s_nop 0
	global_load_dwordx4 v[16:19], v[18:19], off
	v_addc_co_u32_e32 v21, vcc, -1, v141, vcc
	v_add_co_u32_e32 v22, vcc, 0xffffd800, v140
	v_add_f32_e32 v129, v129, v130
	s_nop 0
	v_addc_co_u32_e32 v23, vcc, -1, v141, vcc
	global_load_dwordx4 v[112:115], v[20:21], off
	global_load_dwordx4 v[84:87], v[22:23], off
	v_add_co_u32_e32 v20, vcc, 0xffffdc00, v140
	v_add_f32_e32 v128, v128, v129
	s_nop 0
	v_addc_co_u32_e32 v21, vcc, -1, v141, vcc
	v_add_co_u32_e32 v22, vcc, 0xffffe000, v140
	v_add_f32_e32 v129, v96, v97
	s_nop 0
	v_addc_co_u32_e32 v23, vcc, -1, v141, vcc
	v_add_co_u32_e32 v24, vcc, 0xffffe400, v140
	global_load_dwordx4 v[52:55], v[20:21], off
	s_nop 0
	global_load_dwordx4 v[20:23], v[22:23], off
	v_addc_co_u32_e32 v25, vcc, -1, v141, vcc
	v_add_co_u32_e32 v26, vcc, s46, v140
	v_add_f32_e32 v130, v98, v99
	s_nop 0
	v_addc_co_u32_e32 v27, vcc, -1, v141, vcc
	global_load_dwordx4 v[124:127], v[24:25], off
	global_load_dwordx4 v[88:91], v[26:27], off
	v_add_co_u32_e32 v24, vcc, 0xffffec00, v140
	v_add_f32_e32 v129, v129, v130
	s_nop 0
	v_addc_co_u32_e32 v25, vcc, -1, v141, vcc
	v_add_co_u32_e32 v26, vcc, 0xfffff000, v140
	v_add_f32_e32 v130, v68, v69
	s_nop 0
	v_addc_co_u32_e32 v27, vcc, -1, v141, vcc
	global_load_dwordx4 v[56:59], v[24:25], off
	s_nop 0
	global_load_dwordx4 v[24:27], v[26:27], off
	v_add_co_u32_e32 v28, vcc, 0xfffff400, v140
	v_add_f32_e32 v131, v70, v71
	s_nop 0
	v_addc_co_u32_e32 v29, vcc, -1, v141, vcc
	v_add_co_u32_e32 v30, vcc, 0xfffff800, v140
	v_add_f32_e32 v129, 0, v129
	s_nop 0
	v_addc_co_u32_e32 v31, vcc, -1, v141, vcc
	global_load_dwordx4 v[120:123], v[28:29], off
	global_load_dwordx4 v[92:95], v[30:31], off
	v_add_co_u32_e32 v28, vcc, s76, v140
	v_add_f32_e32 v130, v130, v131
	s_nop 0
	v_addc_co_u32_e32 v29, vcc, -1, v141, vcc
	global_load_dwordx4 v[60:63], v[28:29], off
	s_nop 0
	global_load_dwordx4 v[28:31], v[140:141], off
	v_add_f32_e32 v129, v129, v130
	s_waitcnt vmcnt(0)
	v_add_f32_e32 v130, v36, v37
	v_add_f32_e32 v131, v38, v39
	v_add_f32_e32 v130, v130, v131
	v_add_f32_e32 v129, v129, v130
	v_add_f32_e32 v130, v4, v5
	v_add_f32_e32 v131, v6, v7
	v_add_f32_e32 v130, v130, v131
	v_add_f32_e32 v129, v129, v130
	v_add_f32_e32 v130, v108, v109
	v_add_f32_e32 v131, v110, v111
	v_add_f32_e32 v130, v130, v131
	v_add_f32_e32 v131, v72, v73
	v_add_f32_e32 v132, v74, v75
	v_add_f32_e32 v130, 0, v130
	v_add_f32_e32 v131, v131, v132
	v_add_f32_e32 v130, v130, v131
	v_add_f32_e32 v131, v40, v41
	v_add_f32_e32 v132, v42, v43
	v_add_f32_e32 v131, v131, v132
	v_add_f32_e32 v130, v130, v131
	v_add_f32_e32 v131, v8, v9
	v_add_f32_e32 v132, v10, v11
	v_add_f32_e32 v131, v131, v132
	v_add_f32_e32 v130, v130, v131
	s_waitcnt lgkmcnt(0)
	v_add_f32_e32 v131, v100, v101
	v_add_f32_e32 v132, v102, v103
	v_add_f32_e32 v131, v131, v132
	v_add_f32_e32 v132, v76, v77
	v_add_f32_e32 v133, v78, v79
	v_add_f32_e32 v131, 0, v131
	v_add_f32_e32 v132, v132, v133
	v_add_f32_e32 v131, v131, v132
	v_add_f32_e32 v132, v44, v45
	v_add_f32_e32 v133, v46, v47
	v_add_f32_e32 v132, v132, v133
	v_add_f32_e32 v131, v131, v132
	v_add_f32_e32 v132, v12, v13
	v_add_f32_e32 v133, v14, v15
	v_add_f32_e32 v132, v132, v133
	v_add_f32_e32 v131, v131, v132
	v_add_f32_e32 v132, v116, v117
	v_add_f32_e32 v133, v118, v119
	v_add_f32_e32 v132, v132, v133
	v_add_f32_e32 v133, v80, v81
	v_add_f32_e32 v142, v82, v83
	v_add_f32_e32 v132, 0, v132
	v_add_f32_e32 v133, v133, v142
	v_add_f32_e32 v132, v132, v133
	v_add_f32_e32 v133, v48, v49
	v_add_f32_e32 v142, v50, v51
	v_add_f32_e32 v133, v133, v142
	v_add_f32_e32 v132, v132, v133
	v_add_f32_e32 v133, v16, v17
	v_add_f32_e32 v142, v18, v19
	v_add_f32_e32 v133, v133, v142
	v_add_f32_e32 v132, v132, v133
	v_add_f32_e32 v133, v112, v113
	v_add_f32_e32 v142, v114, v115
	v_add_f32_e32 v133, v133, v142
	v_add_f32_e32 v142, v84, v85
	v_add_f32_e32 v143, v86, v87
	v_add_f32_e32 v133, 0, v133
	v_add_f32_e32 v142, v142, v143
	v_add_f32_e32 v133, v133, v142
	v_add_f32_e32 v142, v52, v53
	v_add_f32_e32 v143, v54, v55
	v_add_f32_e32 v142, v142, v143
	v_add_f32_e32 v133, v133, v142
	v_add_f32_e32 v142, v20, v21
	v_add_f32_e32 v143, v22, v23
	v_add_f32_e32 v142, v142, v143
	v_add_f32_e32 v142, v133, v142
	v_add_f32_e32 v133, v124, v125
	v_add_f32_e32 v143, v126, v127
	v_add_f32_e32 v133, v133, v143
	v_add_f32_e32 v143, v88, v89
	v_add_f32_e32 v144, v90, v91
	v_add_f32_e32 v133, 0, v133
	v_add_f32_e32 v143, v143, v144
	v_add_f32_e32 v133, v133, v143
	v_add_f32_e32 v143, v56, v57
	v_add_f32_e32 v144, v58, v59
	v_add_f32_e32 v143, v143, v144
	v_add_f32_e32 v133, v133, v143
	v_add_f32_e32 v143, v24, v25
	v_add_f32_e32 v144, v26, v27
	v_add_f32_e32 v143, v143, v144
	v_add_f32_e32 v143, v133, v143
	v_add_f32_e32 v133, v120, v121
	v_add_f32_e32 v144, v122, v123
	v_add_f32_e32 v133, v133, v144
	ds_swizzle_b32 v144, v128 offset:swizzle(SWAP,1)
	v_add_f32_e32 v145, v92, v93
	v_add_f32_e32 v146, v94, v95
	v_add_f32_e32 v133, 0, v133
	v_add_f32_e32 v145, v145, v146
	s_waitcnt lgkmcnt(0)
	v_add_f32_e32 v128, v128, v144
	v_add_f32_e32 v133, v133, v145
	ds_swizzle_b32 v145, v129 offset:swizzle(SWAP,1)
	ds_swizzle_b32 v144, v128 offset:swizzle(SWAP,2)
	v_add_f32_e32 v146, v60, v61
	v_add_f32_e32 v147, v62, v63
	v_add_f32_e32 v146, v146, v147
	s_waitcnt lgkmcnt(1)
	v_add_f32_e32 v129, v129, v145
	s_waitcnt lgkmcnt(0)
	v_add_f32_e32 v128, v128, v144
	ds_swizzle_b32 v145, v129 offset:swizzle(SWAP,2)
	ds_swizzle_b32 v144, v128 offset:swizzle(SWAP,4)
	v_add_f32_e32 v133, v133, v146
	v_add_f32_e32 v146, v28, v29
	v_add_f32_e32 v147, v30, v31
	s_waitcnt lgkmcnt(1)
	v_add_f32_e32 v129, v129, v145
	s_waitcnt lgkmcnt(0)
	v_add_f32_e32 v128, v128, v144
	ds_swizzle_b32 v145, v129 offset:swizzle(SWAP,4)
	ds_swizzle_b32 v144, v128 offset:swizzle(SWAP,8)
	v_add_f32_e32 v146, v146, v147
	v_add_f32_e32 v146, v133, v146
	s_waitcnt lgkmcnt(1)
	v_add_f32_e32 v129, v129, v145
	s_waitcnt lgkmcnt(0)
	v_add_f32_e32 v128, v128, v144
	ds_swizzle_b32 v145, v129 offset:swizzle(SWAP,8)
	ds_swizzle_b32 v144, v128 offset:swizzle(SWAP,16)
	s_waitcnt lgkmcnt(1)
	v_add_f32_e32 v129, v129, v145
	s_waitcnt lgkmcnt(0)
	v_add_f32_e32 v128, v128, v144
	ds_swizzle_b32 v144, v129 offset:swizzle(SWAP,16)
	ds_swizzle_b32 v145, v130 offset:swizzle(SWAP,1)
	v_mov_b32_e32 v133, v128
	s_nop 1
	v_permlane32_swap_b32_e32 v128, v133
	v_add_f32_e32 v165, v128, v133
	s_waitcnt lgkmcnt(1)
	v_add_f32_e32 v128, v129, v144
	ds_swizzle_b32 v144, v131 offset:swizzle(SWAP,1)
	s_waitcnt lgkmcnt(1)
	v_add_f32_e32 v129, v130, v145
	ds_swizzle_b32 v130, v129 offset:swizzle(SWAP,2)
	v_mov_b32_e32 v133, v128
	s_nop 1
	v_permlane32_swap_b32_e32 v128, v133
	s_waitcnt lgkmcnt(1)
	v_add_f32_e32 v131, v131, v144
	ds_swizzle_b32 v144, v131 offset:swizzle(SWAP,2)
	v_add_f32_e32 v164, v128, v133
	ds_swizzle_b32 v128, v132 offset:swizzle(SWAP,1)
	s_waitcnt lgkmcnt(2)
	v_add_f32_e32 v129, v129, v130
	ds_swizzle_b32 v130, v129 offset:swizzle(SWAP,4)
	s_waitcnt lgkmcnt(2)
	v_add_f32_e32 v131, v131, v144
	ds_swizzle_b32 v133, v131 offset:swizzle(SWAP,4)
	s_waitcnt lgkmcnt(2)
	v_add_f32_e32 v128, v132, v128
	ds_swizzle_b32 v132, v128 offset:swizzle(SWAP,2)
	s_waitcnt lgkmcnt(2)
	v_add_f32_e32 v129, v129, v130
	ds_swizzle_b32 v130, v129 offset:swizzle(SWAP,8)
	s_waitcnt lgkmcnt(2)
	v_add_f32_e32 v131, v131, v133
	ds_swizzle_b32 v133, v131 offset:swizzle(SWAP,8)
	s_waitcnt lgkmcnt(2)
	v_add_f32_e32 v128, v128, v132
	ds_swizzle_b32 v132, v128 offset:swizzle(SWAP,4)
	s_waitcnt lgkmcnt(2)
	v_add_f32_e32 v129, v129, v130
	ds_swizzle_b32 v130, v129 offset:swizzle(SWAP,16)
	s_waitcnt lgkmcnt(2)
	v_add_f32_e32 v131, v131, v133
	ds_swizzle_b32 v144, v131 offset:swizzle(SWAP,16)
	s_waitcnt lgkmcnt(2)
	v_add_f32_e32 v128, v128, v132
	ds_swizzle_b32 v132, v128 offset:swizzle(SWAP,8)
	s_waitcnt lgkmcnt(2)
	v_add_f32_e32 v129, v129, v130
	v_mov_b32_e32 v130, v129
	s_nop 1
	v_permlane32_swap_b32_e32 v129, v130
	v_add_f32_e32 v133, v129, v130
	s_waitcnt lgkmcnt(1)
	v_add_f32_e32 v129, v131, v144
	ds_swizzle_b32 v144, v142 offset:swizzle(SWAP,1)
	s_waitcnt lgkmcnt(1)
	v_add_f32_e32 v128, v128, v132
	ds_swizzle_b32 v131, v128 offset:swizzle(SWAP,16)
	v_mov_b32_e32 v130, v129
	s_nop 1
	v_permlane32_swap_b32_e32 v129, v130
	v_add_f32_e32 v132, v129, v130
	s_waitcnt lgkmcnt(1)
	v_add_f32_e32 v129, v142, v144
	ds_swizzle_b32 v142, v143 offset:swizzle(SWAP,1)
	s_waitcnt lgkmcnt(1)
	v_add_f32_e32 v128, v128, v131
	ds_swizzle_b32 v130, v129 offset:swizzle(SWAP,2)
	v_mov_b32_e32 v131, v128
	s_nop 1
	v_permlane32_swap_b32_e32 v128, v131
	s_waitcnt lgkmcnt(1)
	v_add_f32_e32 v142, v143, v142
	v_add_f32_e32 v131, v128, v131
	ds_swizzle_b32 v128, v146 offset:swizzle(SWAP,1)
	ds_swizzle_b32 v143, v142 offset:swizzle(SWAP,2)
	s_waitcnt lgkmcnt(2)
	v_add_f32_e32 v129, v129, v130
	ds_swizzle_b32 v130, v129 offset:swizzle(SWAP,4)
	v_fmamk_f32 v151, v165, 0xba800000, v107
	s_waitcnt lgkmcnt(2)
	v_add_f32_e32 v128, v146, v128
	s_waitcnt lgkmcnt(1)
	v_add_f32_e32 v142, v142, v143
	ds_swizzle_b32 v144, v128 offset:swizzle(SWAP,2)
	ds_swizzle_b32 v143, v142 offset:swizzle(SWAP,4)
	s_waitcnt lgkmcnt(2)
	v_add_f32_e32 v129, v129, v130
	ds_swizzle_b32 v130, v129 offset:swizzle(SWAP,8)
	v_fmamk_f32 v105, v165, 0xba800000, v105
	s_waitcnt lgkmcnt(2)
	v_add_f32_e32 v128, v128, v144
	s_waitcnt lgkmcnt(1)
	v_add_f32_e32 v142, v142, v143
	ds_swizzle_b32 v144, v128 offset:swizzle(SWAP,4)
	ds_swizzle_b32 v143, v142 offset:swizzle(SWAP,8)
	s_waitcnt lgkmcnt(2)
	v_add_f32_e32 v129, v129, v130
	ds_swizzle_b32 v130, v129 offset:swizzle(SWAP,16)
	v_fmamk_f32 v150, v165, 0xba800000, v106
	s_waitcnt lgkmcnt(2)
	v_add_f32_e32 v128, v128, v144
	s_waitcnt lgkmcnt(1)
	v_add_f32_e32 v142, v142, v143
	ds_swizzle_b32 v144, v128 offset:swizzle(SWAP,8)
	ds_swizzle_b32 v143, v142 offset:swizzle(SWAP,16)
	s_waitcnt lgkmcnt(2)
	v_add_f32_e32 v129, v129, v130
	v_mov_b32_e32 v130, v129
	s_nop 1
	v_permlane32_swap_b32_e32 v129, v130
	s_waitcnt lgkmcnt(1)
	v_add_f32_e32 v128, v128, v144
	v_add_f32_e32 v130, v129, v130
	s_waitcnt lgkmcnt(0)
	v_add_f32_e32 v129, v142, v143
	ds_swizzle_b32 v142, v128 offset:swizzle(SWAP,16)
	v_fmac_f32_e32 v104, 0xba800000, v165
	v_mul_f32_e32 v106, v105, v105
	v_mul_f32_e32 v107, v151, v151
	v_fmac_f32_e32 v106, v104, v104
	s_waitcnt lgkmcnt(0)
	v_add_f32_e32 v128, v128, v142
	v_mov_b32_e32 v142, v128
	s_nop 1
	v_permlane32_swap_b32_e32 v128, v142
	v_fmac_f32_e32 v107, v150, v150
	v_fmamk_f32 v67, v165, 0xba800000, v67
	v_fmamk_f32 v65, v165, 0xba800000, v65
	v_add_f32_e32 v128, v128, v142
	v_add_f32_e32 v106, v106, v107
	v_fmamk_f32 v66, v165, 0xba800000, v66
	v_fmac_f32_e32 v64, 0xba800000, v165
	v_mul_f32_e32 v107, v65, v65
	v_mul_f32_e32 v142, v67, v67
	v_fmac_f32_e32 v107, v64, v64
	v_fmac_f32_e32 v142, v66, v66
	v_add_f32_e32 v107, v107, v142
	v_fmamk_f32 v35, v165, 0xba800000, v35
	v_fmamk_f32 v33, v165, 0xba800000, v33
	v_add_f32_e32 v106, v106, v107
	v_fmamk_f32 v34, v165, 0xba800000, v34
	v_fmac_f32_e32 v32, 0xba800000, v165
	v_mul_f32_e32 v107, v33, v33
	v_mul_f32_e32 v142, v35, v35
	v_fmac_f32_e32 v107, v32, v32
	v_fmac_f32_e32 v142, v34, v34
	v_add_f32_e32 v107, v107, v142
	v_fmamk_f32 v3, v165, 0xba800000, v3
	v_fmamk_f32 v1, v165, 0xba800000, v1
	v_add_f32_e32 v106, v107, v106
	v_fmamk_f32 v2, v165, 0xba800000, v2
	v_fmac_f32_e32 v0, 0xba800000, v165
	v_mul_f32_e32 v107, v1, v1
	v_mul_f32_e32 v142, v3, v3
	v_fmac_f32_e32 v107, v0, v0
	v_fmac_f32_e32 v142, v2, v2
	v_add_f32_e32 v107, v107, v142
	v_fmamk_f32 v99, v164, 0xba800000, v99
	v_fmamk_f32 v97, v164, 0xba800000, v97
	v_add_f32_e32 v166, v107, v106
	v_fmamk_f32 v98, v164, 0xba800000, v98
	v_fmac_f32_e32 v96, 0xba800000, v164
	v_mul_f32_e32 v106, v97, v97
	v_mul_f32_e32 v107, v99, v99
	v_fmac_f32_e32 v106, v96, v96
	v_fmac_f32_e32 v107, v98, v98
	v_add_f32_e32 v142, v106, v107
	v_fmamk_f32 v107, v164, 0xba800000, v71
	v_fmamk_f32 v69, v164, 0xba800000, v69
	v_fmamk_f32 v106, v164, 0xba800000, v70
	v_fmac_f32_e32 v68, 0xba800000, v164
	v_mul_f32_e32 v70, v69, v69
	v_mul_f32_e32 v71, v107, v107
	v_fmac_f32_e32 v70, v68, v68
	v_fmac_f32_e32 v71, v106, v106
	v_add_f32_e32 v70, v70, v71
	v_fmamk_f32 v39, v164, 0xba800000, v39
	v_fmamk_f32 v37, v164, 0xba800000, v37
	v_add_f32_e32 v70, v142, v70
	v_fmamk_f32 v38, v164, 0xba800000, v38
	v_fmac_f32_e32 v36, 0xba800000, v164
	v_mul_f32_e32 v71, v37, v37
	v_mul_f32_e32 v142, v39, v39
	v_fmac_f32_e32 v71, v36, v36
	v_fmac_f32_e32 v142, v38, v38
	v_add_f32_e32 v71, v71, v142
	v_fmamk_f32 v7, v164, 0xba800000, v7
	v_fmamk_f32 v5, v164, 0xba800000, v5
	v_add_f32_e32 v70, v71, v70
	v_fmamk_f32 v6, v164, 0xba800000, v6
	v_fmac_f32_e32 v4, 0xba800000, v164
	v_mul_f32_e32 v71, v5, v5
	v_mul_f32_e32 v142, v7, v7
	v_fmac_f32_e32 v71, v4, v4
	v_fmac_f32_e32 v142, v6, v6
	v_add_f32_e32 v71, v71, v142
	v_fmamk_f32 v153, v133, 0xba800000, v111
	v_fmamk_f32 v109, v133, 0xba800000, v109
	v_add_f32_e32 v167, v71, v70
	v_fmamk_f32 v152, v133, 0xba800000, v110
	v_fmac_f32_e32 v108, 0xba800000, v133
	v_mul_f32_e32 v70, v109, v109
	v_mul_f32_e32 v71, v153, v153
	v_fmac_f32_e32 v70, v108, v108
	v_fmac_f32_e32 v71, v152, v152
	v_fmamk_f32 v111, v133, 0xba800000, v75
	v_fmamk_f32 v73, v133, 0xba800000, v73
	v_add_f32_e32 v70, v70, v71
	v_fmamk_f32 v110, v133, 0xba800000, v74
	v_fmac_f32_e32 v72, 0xba800000, v133
	v_mul_f32_e32 v71, v73, v73
	v_mul_f32_e32 v74, v111, v111
	v_fmac_f32_e32 v71, v72, v72
	v_fmac_f32_e32 v74, v110, v110
	v_add_f32_e32 v71, v71, v74
	v_fmamk_f32 v43, v133, 0xba800000, v43
	v_fmamk_f32 v41, v133, 0xba800000, v41
	v_add_f32_e32 v70, v70, v71
	v_fmamk_f32 v42, v133, 0xba800000, v42
	v_fmac_f32_e32 v40, 0xba800000, v133
	v_mul_f32_e32 v71, v41, v41
	v_mul_f32_e32 v74, v43, v43
	v_fmac_f32_e32 v71, v40, v40
	v_fmac_f32_e32 v74, v42, v42
	v_add_f32_e32 v71, v71, v74
	v_fmamk_f32 v11, v133, 0xba800000, v11
	v_fmamk_f32 v9, v133, 0xba800000, v9
	v_add_f32_e32 v70, v71, v70
	v_fmamk_f32 v10, v133, 0xba800000, v10
	v_fmac_f32_e32 v8, 0xba800000, v133
	v_mul_f32_e32 v71, v9, v9
	v_mul_f32_e32 v74, v11, v11
	v_fmac_f32_e32 v71, v8, v8
	v_fmac_f32_e32 v74, v10, v10
	v_mov_b32_e32 v143, v129
	v_add_f32_e32 v71, v71, v74
	v_fmamk_f32 v155, v132, 0xba800000, v103
	v_fmamk_f32 v101, v132, 0xba800000, v101
	v_permlane32_swap_b32_e32 v129, v143
	v_add_f32_e32 v74, v71, v70
	v_fmamk_f32 v154, v132, 0xba800000, v102
	v_fmac_f32_e32 v100, 0xba800000, v132
	v_mul_f32_e32 v70, v101, v101
	v_mul_f32_e32 v71, v155, v155
	v_add_f32_e32 v129, v129, v143
	v_fmac_f32_e32 v70, v100, v100
	v_fmac_f32_e32 v71, v154, v154
	v_fmamk_f32 v143, v132, 0xba800000, v79
	v_fmamk_f32 v77, v132, 0xba800000, v77
	v_add_f32_e32 v70, v70, v71
	v_fmamk_f32 v142, v132, 0xba800000, v78
	v_fmac_f32_e32 v76, 0xba800000, v132
	v_mul_f32_e32 v71, v77, v77
	v_mul_f32_e32 v75, v143, v143
	v_fmac_f32_e32 v71, v76, v76
	v_fmac_f32_e32 v75, v142, v142
	v_add_f32_e32 v71, v71, v75
	v_fmamk_f32 v47, v132, 0xba800000, v47
	v_fmamk_f32 v45, v132, 0xba800000, v45
	v_add_f32_e32 v70, v70, v71
	v_fmamk_f32 v46, v132, 0xba800000, v46
	v_fmac_f32_e32 v44, 0xba800000, v132
	v_mul_f32_e32 v71, v45, v45
	v_mul_f32_e32 v75, v47, v47
	v_fmac_f32_e32 v71, v44, v44
	v_fmac_f32_e32 v75, v46, v46
	v_add_f32_e32 v71, v71, v75
	v_fmamk_f32 v15, v132, 0xba800000, v15
	v_fmamk_f32 v13, v132, 0xba800000, v13
	v_add_f32_e32 v70, v71, v70
	v_fmamk_f32 v14, v132, 0xba800000, v14
	v_fmac_f32_e32 v12, 0xba800000, v132
	v_mul_f32_e32 v71, v13, v13
	v_mul_f32_e32 v75, v15, v15
	v_fmac_f32_e32 v71, v12, v12
	v_fmac_f32_e32 v75, v14, v14
	v_add_f32_e32 v71, v71, v75
	v_fmamk_f32 v157, v131, 0xba800000, v119
	v_fmamk_f32 v117, v131, 0xba800000, v117
	v_add_f32_e32 v75, v71, v70
	v_fmamk_f32 v156, v131, 0xba800000, v118
	v_fmac_f32_e32 v116, 0xba800000, v131
	v_mul_f32_e32 v70, v117, v117
	v_mul_f32_e32 v71, v157, v157
	v_fmac_f32_e32 v70, v116, v116
	v_fmac_f32_e32 v71, v156, v156
	v_fmamk_f32 v145, v131, 0xba800000, v83
	v_fmamk_f32 v81, v131, 0xba800000, v81
	v_add_f32_e32 v70, v70, v71
	v_fmamk_f32 v144, v131, 0xba800000, v82
	v_fmac_f32_e32 v80, 0xba800000, v131
	v_mul_f32_e32 v71, v81, v81
	v_mul_f32_e32 v78, v145, v145
	v_fmac_f32_e32 v71, v80, v80
	v_fmac_f32_e32 v78, v144, v144
	v_add_f32_e32 v71, v71, v78
	v_fmamk_f32 v51, v131, 0xba800000, v51
	v_fmamk_f32 v49, v131, 0xba800000, v49
	v_add_f32_e32 v70, v70, v71
	v_fmamk_f32 v50, v131, 0xba800000, v50
	v_fmac_f32_e32 v48, 0xba800000, v131
	v_mul_f32_e32 v71, v49, v49
	v_mul_f32_e32 v78, v51, v51
	v_fmac_f32_e32 v71, v48, v48
	v_fmac_f32_e32 v78, v50, v50
	v_add_f32_e32 v71, v71, v78
	v_fmamk_f32 v19, v131, 0xba800000, v19
	v_fmamk_f32 v17, v131, 0xba800000, v17
	v_add_f32_e32 v70, v71, v70
	v_fmamk_f32 v18, v131, 0xba800000, v18
	v_fmac_f32_e32 v16, 0xba800000, v131
	v_mul_f32_e32 v71, v17, v17
	v_mul_f32_e32 v78, v19, v19
	v_fmac_f32_e32 v71, v16, v16
	v_fmac_f32_e32 v78, v18, v18
	v_add_f32_e32 v71, v71, v78
	v_fmamk_f32 v159, v130, 0xba800000, v115
	v_fmamk_f32 v113, v130, 0xba800000, v113
	v_add_f32_e32 v79, v71, v70
	v_fmamk_f32 v158, v130, 0xba800000, v114
	v_fmac_f32_e32 v112, 0xba800000, v130
	v_mul_f32_e32 v70, v113, v113
	v_mul_f32_e32 v71, v159, v159
	v_fmac_f32_e32 v70, v112, v112
	v_fmac_f32_e32 v71, v158, v158
	v_fmamk_f32 v147, v130, 0xba800000, v87
	v_fmamk_f32 v85, v130, 0xba800000, v85
	v_add_f32_e32 v70, v70, v71
	v_fmamk_f32 v146, v130, 0xba800000, v86
	v_fmac_f32_e32 v84, 0xba800000, v130
	v_mul_f32_e32 v71, v85, v85
	v_mul_f32_e32 v78, v147, v147
	v_fmac_f32_e32 v71, v84, v84
	v_fmac_f32_e32 v78, v146, v146
	v_add_f32_e32 v71, v71, v78
	v_fmamk_f32 v55, v130, 0xba800000, v55
	v_fmamk_f32 v53, v130, 0xba800000, v53
	v_add_f32_e32 v70, v70, v71
	v_fmamk_f32 v54, v130, 0xba800000, v54
	v_fmac_f32_e32 v52, 0xba800000, v130
	v_mul_f32_e32 v71, v53, v53
	v_mul_f32_e32 v78, v55, v55
	v_fmac_f32_e32 v71, v52, v52
	v_fmac_f32_e32 v78, v54, v54
	v_add_f32_e32 v71, v71, v78
	v_fmamk_f32 v23, v130, 0xba800000, v23
	v_fmamk_f32 v21, v130, 0xba800000, v21
	v_add_f32_e32 v70, v71, v70
	v_fmamk_f32 v22, v130, 0xba800000, v22
	v_fmac_f32_e32 v20, 0xba800000, v130
	v_mul_f32_e32 v71, v21, v21
	v_mul_f32_e32 v78, v23, v23
	v_fmac_f32_e32 v71, v20, v20
	v_fmac_f32_e32 v78, v22, v22
	v_add_f32_e32 v71, v71, v78
	v_fmamk_f32 v161, v129, 0xba800000, v127
	v_fmamk_f32 v125, v129, 0xba800000, v125
	v_add_f32_e32 v83, v71, v70
	v_fmamk_f32 v160, v129, 0xba800000, v126
	v_fmac_f32_e32 v124, 0xba800000, v129
	v_mul_f32_e32 v70, v125, v125
	v_mul_f32_e32 v71, v161, v161
	v_fmac_f32_e32 v70, v124, v124
	v_fmac_f32_e32 v71, v160, v160
	v_fmamk_f32 v149, v129, 0xba800000, v91
	v_fmamk_f32 v89, v129, 0xba800000, v89
	v_add_f32_e32 v70, v70, v71
	v_fmamk_f32 v148, v129, 0xba800000, v90
	v_fmac_f32_e32 v88, 0xba800000, v129
	v_mul_f32_e32 v71, v89, v89
	v_mul_f32_e32 v78, v149, v149
	v_fmac_f32_e32 v71, v88, v88
	v_fmac_f32_e32 v78, v148, v148
	v_add_f32_e32 v71, v71, v78
	v_fmamk_f32 v59, v129, 0xba800000, v59
	v_fmamk_f32 v57, v129, 0xba800000, v57
	v_add_f32_e32 v70, v70, v71
	v_fmamk_f32 v58, v129, 0xba800000, v58
	v_fmac_f32_e32 v56, 0xba800000, v129
	v_mul_f32_e32 v71, v57, v57
	v_mul_f32_e32 v78, v59, v59
	v_fmac_f32_e32 v71, v56, v56
	v_fmac_f32_e32 v78, v58, v58
	v_add_f32_e32 v71, v71, v78
	v_fmamk_f32 v27, v129, 0xba800000, v27
	v_fmamk_f32 v25, v129, 0xba800000, v25
	v_add_f32_e32 v70, v71, v70
	v_fmamk_f32 v26, v129, 0xba800000, v26
	v_fmac_f32_e32 v24, 0xba800000, v129
	v_mul_f32_e32 v71, v25, v25
	v_mul_f32_e32 v78, v27, v27
	v_fmac_f32_e32 v71, v24, v24
	v_fmac_f32_e32 v78, v26, v26
	v_add_f32_e32 v71, v71, v78
	v_fmamk_f32 v163, v128, 0xba800000, v123
	v_fmamk_f32 v121, v128, 0xba800000, v121
	v_add_f32_e32 v87, v71, v70
	v_fmamk_f32 v162, v128, 0xba800000, v122
	v_fmac_f32_e32 v120, 0xba800000, v128
	v_mul_f32_e32 v70, v121, v121
	v_mul_f32_e32 v71, v163, v163
	v_fmac_f32_e32 v70, v120, v120
	v_fmac_f32_e32 v71, v162, v162
	v_fmamk_f32 v123, v128, 0xba800000, v95
	v_fmamk_f32 v93, v128, 0xba800000, v93
	v_add_f32_e32 v70, v70, v71
	v_fmamk_f32 v122, v128, 0xba800000, v94
	v_fmac_f32_e32 v92, 0xba800000, v128
	v_mul_f32_e32 v71, v93, v93
	v_mul_f32_e32 v78, v123, v123
	v_fmac_f32_e32 v71, v92, v92
	v_fmac_f32_e32 v78, v122, v122
	v_add_f32_e32 v71, v71, v78
	v_add_f32_e32 v78, v70, v71
	v_fmamk_f32 v70, v128, 0xba800000, v62
	ds_swizzle_b32 v62, v166 offset:swizzle(SWAP,1)
	v_fmamk_f32 v71, v128, 0xba800000, v63
	v_fmamk_f32 v61, v128, 0xba800000, v61
	v_fmac_f32_e32 v60, 0xba800000, v128
	v_mul_f32_e32 v63, v61, v61
	s_waitcnt lgkmcnt(0)
	v_add_f32_e32 v62, v166, v62
	ds_swizzle_b32 v86, v62 offset:swizzle(SWAP,2)
	v_mul_f32_e32 v82, v71, v71
	v_fmac_f32_e32 v63, v60, v60
	v_fmac_f32_e32 v82, v70, v70
	v_add_f32_e32 v63, v63, v82
	s_waitcnt lgkmcnt(0)
	v_add_f32_e32 v62, v62, v86
	v_add_f32_e32 v63, v63, v78
	ds_swizzle_b32 v78, v62 offset:swizzle(SWAP,4)
	ds_swizzle_b32 v82, v167 offset:swizzle(SWAP,1)
	v_fmamk_f32 v31, v128, 0xba800000, v31
	v_fmamk_f32 v29, v128, 0xba800000, v29
	v_fmamk_f32 v30, v128, 0xba800000, v30
	s_waitcnt lgkmcnt(1)
	v_add_f32_e32 v62, v62, v78
	s_waitcnt lgkmcnt(0)
	v_add_f32_e32 v82, v167, v82
	ds_swizzle_b32 v78, v62 offset:swizzle(SWAP,8)
	ds_swizzle_b32 v90, v82 offset:swizzle(SWAP,2)
	v_fmac_f32_e32 v28, 0xba800000, v128
	v_mul_f32_e32 v86, v29, v29
	v_mul_f32_e32 v91, v31, v31
	s_waitcnt lgkmcnt(1)
	v_add_f32_e32 v62, v62, v78
	s_waitcnt lgkmcnt(0)
	v_add_f32_e32 v82, v82, v90
	ds_swizzle_b32 v78, v62 offset:swizzle(SWAP,16)
	ds_swizzle_b32 v90, v82 offset:swizzle(SWAP,4)
	v_fmac_f32_e32 v86, v28, v28
	v_fmac_f32_e32 v91, v30, v30
	v_add_f32_e32 v86, v86, v91
	s_waitcnt lgkmcnt(1)
	v_add_f32_e32 v62, v62, v78
	s_waitcnt lgkmcnt(0)
	v_add_f32_e32 v78, v82, v90
	ds_swizzle_b32 v90, v74 offset:swizzle(SWAP,1)
	ds_swizzle_b32 v82, v78 offset:swizzle(SWAP,8)
	v_add_f32_e32 v63, v86, v63
	v_mov_b32_e32 v86, v62
	s_nop 1
	v_permlane32_swap_b32_e32 v62, v86
	s_waitcnt lgkmcnt(1)
	v_add_f32_e32 v74, v74, v90
	s_waitcnt lgkmcnt(0)
	v_add_f32_e32 v78, v78, v82
	ds_swizzle_b32 v90, v74 offset:swizzle(SWAP,2)
	v_add_f32_e32 v62, v62, v86
	ds_swizzle_b32 v86, v75 offset:swizzle(SWAP,1)
	ds_swizzle_b32 v82, v78 offset:swizzle(SWAP,16)
	ds_swizzle_b32 v91, v83 offset:swizzle(SWAP,1)
	s_waitcnt lgkmcnt(3)
	v_add_f32_e32 v74, v74, v90
	ds_swizzle_b32 v90, v79 offset:swizzle(SWAP,1)
	s_waitcnt lgkmcnt(3)
	v_add_f32_e32 v75, v75, v86
	s_waitcnt lgkmcnt(2)
	v_add_f32_e32 v78, v78, v82
	ds_swizzle_b32 v82, v74 offset:swizzle(SWAP,4)
	ds_swizzle_b32 v86, v75 offset:swizzle(SWAP,2)
	s_waitcnt lgkmcnt(2)
	v_add_f32_e32 v79, v79, v90
	ds_swizzle_b32 v90, v79 offset:swizzle(SWAP,2)
	ds_swizzle_b32 v103, v87 offset:swizzle(SWAP,1)
	s_waitcnt lgkmcnt(3)
	v_add_f32_e32 v74, v74, v82
	s_waitcnt lgkmcnt(2)
	v_add_f32_e32 v75, v75, v86
	ds_swizzle_b32 v82, v74 offset:swizzle(SWAP,8)
	ds_swizzle_b32 v86, v75 offset:swizzle(SWAP,4)
	s_waitcnt lgkmcnt(3)
	v_add_f32_e32 v79, v79, v90
	ds_swizzle_b32 v90, v79 offset:swizzle(SWAP,4)
	v_fmamk_f32 v62, v62, 0x3a800000, v243
	s_waitcnt lgkmcnt(2)
	v_add_f32_e32 v74, v74, v82
	s_waitcnt lgkmcnt(1)
	v_add_f32_e32 v75, v75, v86
	ds_swizzle_b32 v82, v74 offset:swizzle(SWAP,16)
	ds_swizzle_b32 v86, v75 offset:swizzle(SWAP,8)
	s_waitcnt lgkmcnt(2)
	v_add_f32_e32 v79, v79, v90
	ds_swizzle_b32 v90, v79 offset:swizzle(SWAP,8)
	v_cmp_gt_f32_e32 vcc, s84, v62
	s_waitcnt lgkmcnt(2)
	v_add_f32_e32 v82, v74, v82
	s_waitcnt lgkmcnt(1)
	v_add_f32_e32 v74, v75, v86
	ds_swizzle_b32 v75, v74 offset:swizzle(SWAP,16)
	v_mov_b32_e32 v102, v78
	v_mov_b32_e32 v95, v82
	s_nop 0
	v_permlane32_swap_b32_e32 v78, v102
	s_waitcnt lgkmcnt(0)
	v_add_f32_e32 v86, v74, v75
	v_add_f32_e32 v74, v79, v90
	v_add_f32_e32 v79, v83, v91
	ds_swizzle_b32 v75, v74 offset:swizzle(SWAP,16)
	ds_swizzle_b32 v83, v79 offset:swizzle(SWAP,2)
	v_mov_b32_e32 v94, v86
	v_permlane32_swap_b32_e32 v82, v95
	s_waitcnt lgkmcnt(1)
	v_add_f32_e32 v90, v74, v75
	s_waitcnt lgkmcnt(0)
	v_add_f32_e32 v74, v79, v83
	v_add_f32_e32 v79, v87, v103
	ds_swizzle_b32 v87, v63 offset:swizzle(SWAP,1)
	ds_swizzle_b32 v75, v74 offset:swizzle(SWAP,4)
	ds_swizzle_b32 v83, v79 offset:swizzle(SWAP,2)
	v_mov_b32_e32 v91, v90
	v_permlane32_swap_b32_e32 v86, v94
	s_waitcnt lgkmcnt(2)
	v_add_f32_e32 v63, v63, v87
	s_waitcnt lgkmcnt(1)
	v_add_f32_e32 v74, v74, v75
	s_waitcnt lgkmcnt(0)
	v_add_f32_e32 v79, v79, v83
	ds_swizzle_b32 v87, v63 offset:swizzle(SWAP,2)
	ds_swizzle_b32 v75, v74 offset:swizzle(SWAP,8)
	ds_swizzle_b32 v83, v79 offset:swizzle(SWAP,4)
	v_permlane32_swap_b32_e32 v90, v91
	s_waitcnt lgkmcnt(2)
	v_add_f32_e32 v63, v63, v87
	s_waitcnt lgkmcnt(1)
	v_add_f32_e32 v74, v74, v75
	s_waitcnt lgkmcnt(0)
	v_add_f32_e32 v79, v79, v83
	ds_swizzle_b32 v114, v63 offset:swizzle(SWAP,4)
	ds_swizzle_b32 v75, v74 offset:swizzle(SWAP,16)
	ds_swizzle_b32 v103, v79 offset:swizzle(SWAP,8)
	s_waitcnt lgkmcnt(2)
	v_add_f32_e32 v63, v63, v114
	s_waitcnt lgkmcnt(1)
	v_add_f32_e32 v83, v74, v75
	s_waitcnt lgkmcnt(0)
	v_add_f32_e32 v74, v79, v103
	ds_swizzle_b32 v103, v63 offset:swizzle(SWAP,8)
	ds_swizzle_b32 v75, v74 offset:swizzle(SWAP,16)
	v_mov_b32_e32 v87, v83
	s_nop 1
	v_permlane32_swap_b32_e32 v83, v87
	s_waitcnt lgkmcnt(1)
	v_add_f32_e32 v63, v63, v103
	v_mul_f32_e32 v103, 0x4f800000, v62
	s_waitcnt lgkmcnt(0)
	v_add_f32_e32 v75, v74, v75
	ds_swizzle_b32 v74, v63 offset:swizzle(SWAP,16)
	v_cndmask_b32_e32 v103, v62, v103, vcc
	v_sqrt_f32_e32 v114, v103
	v_mov_b32_e32 v79, v75
	s_nop 1
	v_permlane32_swap_b32_e32 v75, v79
	s_waitcnt lgkmcnt(0)
	v_add_f32_e32 v62, v63, v74
	v_add_u32_e32 v63, -1, v114
	v_fma_f32 v74, -v63, v114, v103
	v_cmp_ge_f32_e64 s[6:7], 0, v74
	v_add_u32_e32 v74, 1, v114
	s_nop 0
	v_cndmask_b32_e64 v63, v114, v63, s[6:7]
	v_fma_f32 v114, -v74, v114, v103
	v_cmp_lt_f32_e64 s[6:7], 0, v114
	s_nop 1
	v_cndmask_b32_e64 v63, v63, v74, s[6:7]
	v_mul_f32_e32 v74, 0x37800000, v63
	v_cndmask_b32_e32 v63, v63, v74, vcc
	v_cmp_class_f32_e32 vcc, v103, v248
	s_nop 1
	v_cndmask_b32_e32 v74, v63, v103, vcc
	v_div_scale_f32 v103, s[6:7], v74, v74, 1.0
	v_rcp_f32_e32 v114, v103
	v_mov_b32_e32 v63, v62
	s_nop 1
	v_permlane32_swap_b32_e32 v62, v63
	v_fma_f32 v115, -v103, v114, 1.0
	v_fmac_f32_e32 v114, v115, v114
	v_div_scale_f32 v115, vcc, 1.0, v74, 1.0
	v_mul_f32_e32 v118, v115, v114
	v_fma_f32 v119, -v103, v118, v115
	v_fmac_f32_e32 v118, v119, v114
	v_fma_f32 v103, -v103, v118, v115
	v_div_fmas_f32 v103, v103, v114, v118
	v_div_fixup_f32 v74, v103, v74, 1.0
	s_and_saveexec_b64 s[6:7], s[4:5]
	s_cbranch_execz .LBB0_1225
	v_mov_b32_e32 v103, s13
	v_add_co_u32_e32 v118, vcc, 0x1fa00000, v103
	v_mov_b32_e32 v103, s11
	v_mul_f32_e32 v114, 0x3a800000, v165
	v_addc_co_u32_e32 v119, vcc, 0, v103, vcc
	v_mov_b32_e32 v115, v74
	global_store_dwordx2 v[118:119], v[114:115], off
.LBB0_1225:
	s_or_b64 exec, exec, s[6:7]
	v_add_f32_e32 v78, v78, v102
	v_fmamk_f32 v78, v78, 0x3a800000, v243
	v_mul_f32_e32 v102, 0x4f800000, v78
	v_cmp_gt_f32_e32 vcc, s84, v78
	s_nop 1
	v_cndmask_b32_e32 v78, v78, v102, vcc
	v_sqrt_f32_e32 v102, v78
	s_nop 0
	v_add_u32_e32 v103, -1, v102
	v_fma_f32 v115, -v103, v102, v78
	v_add_u32_e32 v114, 1, v102
	v_cmp_ge_f32_e64 s[6:7], 0, v115
	s_nop 1
	v_cndmask_b32_e64 v103, v102, v103, s[6:7]
	v_fma_f32 v102, -v114, v102, v78
	v_cmp_lt_f32_e64 s[6:7], 0, v102
	s_nop 1
	v_cndmask_b32_e64 v102, v103, v114, s[6:7]
	v_mul_f32_e32 v103, 0x37800000, v102
	v_cndmask_b32_e32 v102, v102, v103, vcc
	v_cmp_class_f32_e32 vcc, v78, v248
	s_nop 1
	v_cndmask_b32_e32 v78, v102, v78, vcc
	v_div_scale_f32 v102, s[6:7], v78, v78, 1.0
	v_rcp_f32_e32 v103, v102
	s_nop 0
	v_fma_f32 v114, -v102, v103, 1.0
	v_fmac_f32_e32 v103, v114, v103
	v_div_scale_f32 v114, vcc, 1.0, v78, 1.0
	v_mul_f32_e32 v115, v114, v103
	v_fma_f32 v118, -v102, v115, v114
	v_fmac_f32_e32 v115, v118, v103
	v_fma_f32 v102, -v102, v115, v114
	v_div_fmas_f32 v102, v102, v103, v115
	v_div_fixup_f32 v78, v102, v78, 1.0
	s_and_saveexec_b64 s[6:7], s[4:5]
	s_cbranch_execz .LBB0_1227
	v_mov_b32_e32 v103, s13
	v_add_co_u32_e32 v114, vcc, 0x1fa00000, v103
	v_mov_b32_e32 v103, s11
	v_mul_f32_e32 v102, 0x3a800000, v164
	v_addc_co_u32_e32 v115, vcc, 0, v103, vcc
	v_mov_b32_e32 v103, v78
	global_store_dwordx2 v[114:115], v[102:103], off offset:8
.LBB0_1227:
	s_or_b64 exec, exec, s[6:7]
	v_add_f32_e32 v82, v82, v95
	v_fmamk_f32 v82, v82, 0x3a800000, v243
	v_mul_f32_e32 v95, 0x4f800000, v82
	v_cmp_gt_f32_e32 vcc, s84, v82
	s_nop 1
	v_cndmask_b32_e32 v82, v82, v95, vcc
	v_sqrt_f32_e32 v95, v82
	s_nop 0
	v_add_u32_e32 v102, -1, v95
	v_fma_f32 v114, -v102, v95, v82
	v_add_u32_e32 v103, 1, v95
	v_cmp_ge_f32_e64 s[6:7], 0, v114
	s_nop 1
	v_cndmask_b32_e64 v102, v95, v102, s[6:7]
	v_fma_f32 v95, -v103, v95, v82
	v_cmp_lt_f32_e64 s[6:7], 0, v95
	s_nop 1
	v_cndmask_b32_e64 v95, v102, v103, s[6:7]
	v_mul_f32_e32 v102, 0x37800000, v95
	v_cndmask_b32_e32 v95, v95, v102, vcc
	v_cmp_class_f32_e32 vcc, v82, v248
	s_nop 1
	v_cndmask_b32_e32 v82, v95, v82, vcc
	v_div_scale_f32 v95, s[6:7], v82, v82, 1.0
	v_rcp_f32_e32 v102, v95
	s_nop 0
	v_fma_f32 v103, -v95, v102, 1.0
	v_fmac_f32_e32 v102, v103, v102
	v_div_scale_f32 v103, vcc, 1.0, v82, 1.0
	v_mul_f32_e32 v114, v103, v102
	v_fma_f32 v115, -v95, v114, v103
	v_fmac_f32_e32 v114, v115, v102
	v_fma_f32 v95, -v95, v114, v103
	v_div_fmas_f32 v95, v95, v102, v114
	v_div_fixup_f32 v82, v95, v82, 1.0
	s_and_saveexec_b64 s[6:7], s[4:5]
	s_cbranch_execz .LBB0_1229
	v_mov_b32_e32 v95, s13
	v_add_co_u32_e32 v114, vcc, 0x1fa00000, v95
	v_mov_b32_e32 v95, s11
	v_mul_f32_e32 v102, 0x3a800000, v133
	v_addc_co_u32_e32 v115, vcc, 0, v95, vcc
	v_mov_b32_e32 v103, v82
	global_store_dwordx2 v[114:115], v[102:103], off offset:16
.LBB0_1229:
	s_or_b64 exec, exec, s[6:7]
	v_add_f32_e32 v86, v86, v94
	v_fmamk_f32 v86, v86, 0x3a800000, v243
	v_mul_f32_e32 v94, 0x4f800000, v86
	v_cmp_gt_f32_e32 vcc, s84, v86
	s_nop 1
	v_cndmask_b32_e32 v86, v86, v94, vcc
	v_sqrt_f32_e32 v94, v86
	s_nop 0
	v_add_u32_e32 v95, -1, v94
	v_fma_f32 v103, -v95, v94, v86
	v_add_u32_e32 v102, 1, v94
	v_cmp_ge_f32_e64 s[6:7], 0, v103
	s_nop 1
	v_cndmask_b32_e64 v95, v94, v95, s[6:7]
	v_fma_f32 v94, -v102, v94, v86
	v_cmp_lt_f32_e64 s[6:7], 0, v94
	s_nop 1
	v_cndmask_b32_e64 v94, v95, v102, s[6:7]
	v_mul_f32_e32 v95, 0x37800000, v94
	v_cndmask_b32_e32 v94, v94, v95, vcc
	v_cmp_class_f32_e32 vcc, v86, v248
	s_nop 1
	v_cndmask_b32_e32 v86, v94, v86, vcc
	v_div_scale_f32 v94, s[6:7], v86, v86, 1.0
	v_rcp_f32_e32 v95, v94
	s_nop 0
	v_fma_f32 v102, -v94, v95, 1.0
	v_fmac_f32_e32 v95, v102, v95
	v_div_scale_f32 v102, vcc, 1.0, v86, 1.0
	v_mul_f32_e32 v103, v102, v95
	v_fma_f32 v114, -v94, v103, v102
	v_fmac_f32_e32 v103, v114, v95
	v_fma_f32 v94, -v94, v103, v102
	v_div_fmas_f32 v94, v94, v95, v103
	v_div_fixup_f32 v86, v94, v86, 1.0
	s_and_saveexec_b64 s[6:7], s[4:5]
	s_cbranch_execz .LBB0_1231
	v_mov_b32_e32 v95, s13
	v_add_co_u32_e32 v102, vcc, 0x1fa00000, v95
	v_mov_b32_e32 v95, s11
	v_mul_f32_e32 v94, 0x3a800000, v132
	v_addc_co_u32_e32 v103, vcc, 0, v95, vcc
	v_mov_b32_e32 v95, v86
	global_store_dwordx2 v[102:103], v[94:95], off offset:24
.LBB0_1231:
	s_or_b64 exec, exec, s[6:7]
	v_add_f32_e32 v90, v90, v91
	v_fmamk_f32 v90, v90, 0x3a800000, v243
	v_mul_f32_e32 v91, 0x4f800000, v90
	v_cmp_gt_f32_e32 vcc, s84, v90
	s_nop 1
	v_cndmask_b32_e32 v90, v90, v91, vcc
	v_sqrt_f32_e32 v91, v90
	s_nop 0
	v_add_u32_e32 v94, -1, v91
	v_fma_f32 v102, -v94, v91, v90
	v_add_u32_e32 v95, 1, v91
	v_cmp_ge_f32_e64 s[6:7], 0, v102
	s_nop 1
	v_cndmask_b32_e64 v94, v91, v94, s[6:7]
	v_fma_f32 v91, -v95, v91, v90
	v_cmp_lt_f32_e64 s[6:7], 0, v91
	s_nop 1
	v_cndmask_b32_e64 v91, v94, v95, s[6:7]
	v_mul_f32_e32 v94, 0x37800000, v91
	v_cndmask_b32_e32 v91, v91, v94, vcc
	v_cmp_class_f32_e32 vcc, v90, v248
	s_nop 1
	v_cndmask_b32_e32 v90, v91, v90, vcc
	v_div_scale_f32 v91, s[6:7], v90, v90, 1.0
	v_rcp_f32_e32 v94, v91
	s_nop 0
	v_fma_f32 v95, -v91, v94, 1.0
	v_fmac_f32_e32 v94, v95, v94
	v_div_scale_f32 v95, vcc, 1.0, v90, 1.0
	v_mul_f32_e32 v102, v95, v94
	v_fma_f32 v103, -v91, v102, v95
	v_fmac_f32_e32 v102, v103, v94
	v_fma_f32 v91, -v91, v102, v95
	v_div_fmas_f32 v91, v91, v94, v102
	v_div_fixup_f32 v90, v91, v90, 1.0
	s_and_saveexec_b64 s[6:7], s[4:5]
	s_cbranch_execz .LBB0_1233
	v_mov_b32_e32 v91, s13
	v_add_co_u32_e32 v102, vcc, 0x1fa00000, v91
	v_mov_b32_e32 v91, s11
	v_mul_f32_e32 v94, 0x3a800000, v131
	v_addc_co_u32_e32 v103, vcc, 0, v91, vcc
	v_mov_b32_e32 v95, v90
	global_store_dwordx2 v[102:103], v[94:95], off offset:32
.LBB0_1233:
	s_or_b64 exec, exec, s[6:7]
	v_add_f32_e32 v83, v83, v87
	v_fmamk_f32 v83, v83, 0x3a800000, v243
	v_mul_f32_e32 v87, 0x4f800000, v83
	v_cmp_gt_f32_e32 vcc, s84, v83
	s_nop 1
	v_cndmask_b32_e32 v83, v83, v87, vcc
	v_sqrt_f32_e32 v87, v83
	s_nop 0
	v_add_u32_e32 v91, -1, v87
	v_fma_f32 v95, -v91, v87, v83
	v_add_u32_e32 v94, 1, v87
	v_cmp_ge_f32_e64 s[6:7], 0, v95
	s_nop 1
	v_cndmask_b32_e64 v91, v87, v91, s[6:7]
	v_fma_f32 v87, -v94, v87, v83
	v_cmp_lt_f32_e64 s[6:7], 0, v87
	s_nop 1
	v_cndmask_b32_e64 v87, v91, v94, s[6:7]
	v_mul_f32_e32 v91, 0x37800000, v87
	v_cndmask_b32_e32 v87, v87, v91, vcc
	v_cmp_class_f32_e32 vcc, v83, v248
	s_nop 1
	v_cndmask_b32_e32 v83, v87, v83, vcc
	v_div_scale_f32 v87, s[6:7], v83, v83, 1.0
	v_rcp_f32_e32 v91, v87
	s_nop 0
	v_fma_f32 v94, -v87, v91, 1.0
	v_fmac_f32_e32 v91, v94, v91
	v_div_scale_f32 v94, vcc, 1.0, v83, 1.0
	v_mul_f32_e32 v95, v94, v91
	v_fma_f32 v102, -v87, v95, v94
	v_fmac_f32_e32 v95, v102, v91
	v_fma_f32 v87, -v87, v95, v94
	v_div_fmas_f32 v87, v87, v91, v95
	v_div_fixup_f32 v102, v87, v83, 1.0
	s_and_saveexec_b64 s[6:7], s[4:5]
	s_cbranch_execz .LBB0_1235
	v_mov_b32_e32 v83, s13
	v_add_co_u32_e32 v114, vcc, 0x1fa00000, v83
	v_mov_b32_e32 v83, s11
	v_mul_f32_e32 v94, 0x3a800000, v130
	v_addc_co_u32_e32 v115, vcc, 0, v83, vcc
	v_mov_b32_e32 v95, v102
	global_store_dwordx2 v[114:115], v[94:95], off offset:40
.LBB0_1235:
	s_or_b64 exec, exec, s[6:7]
	v_add_f32_e32 v75, v75, v79
	v_fmamk_f32 v75, v75, 0x3a800000, v243
	v_mul_f32_e32 v79, 0x4f800000, v75
	v_cmp_gt_f32_e32 vcc, s84, v75
	s_nop 1
	v_cndmask_b32_e32 v75, v75, v79, vcc
	v_sqrt_f32_e32 v79, v75
	s_nop 0
	v_add_u32_e32 v83, -1, v79
	v_fma_f32 v91, -v83, v79, v75
	v_add_u32_e32 v87, 1, v79
	v_cmp_ge_f32_e64 s[6:7], 0, v91
	s_nop 1
	v_cndmask_b32_e64 v83, v79, v83, s[6:7]
	v_fma_f32 v79, -v87, v79, v75
	v_cmp_lt_f32_e64 s[6:7], 0, v79
	s_nop 1
	v_cndmask_b32_e64 v79, v83, v87, s[6:7]
	v_mul_f32_e32 v83, 0x37800000, v79
	v_cndmask_b32_e32 v79, v79, v83, vcc
	v_cmp_class_f32_e32 vcc, v75, v248
	s_nop 1
	v_cndmask_b32_e32 v75, v79, v75, vcc
	v_div_scale_f32 v79, s[6:7], v75, v75, 1.0
	v_rcp_f32_e32 v83, v79
	s_nop 0
	v_fma_f32 v87, -v79, v83, 1.0
	v_fmac_f32_e32 v83, v87, v83
	v_div_scale_f32 v87, vcc, 1.0, v75, 1.0
	v_mul_f32_e32 v91, v87, v83
	v_fma_f32 v94, -v79, v91, v87
	v_fmac_f32_e32 v91, v94, v83
	v_fma_f32 v79, -v79, v91, v87
	v_div_fmas_f32 v79, v79, v83, v91
	v_div_fixup_f32 v114, v79, v75, 1.0
	s_and_saveexec_b64 s[6:7], s[4:5]
	s_cbranch_execz .LBB0_1237
	v_mov_b32_e32 v75, s13
	v_add_co_u32_e32 v118, vcc, 0x1fa00000, v75
	v_mov_b32_e32 v75, s11
	v_mul_f32_e32 v94, 0x3a800000, v129
	v_addc_co_u32_e32 v119, vcc, 0, v75, vcc
	v_mov_b32_e32 v95, v114
	global_store_dwordx2 v[118:119], v[94:95], off offset:48
.LBB0_1237:
	s_or_b64 exec, exec, s[6:7]
	v_add_f32_e32 v62, v62, v63
	v_fmamk_f32 v62, v62, 0x3a800000, v243
	v_mul_f32_e32 v63, 0x4f800000, v62
	v_cmp_gt_f32_e32 vcc, s84, v62
	s_nop 1
	v_cndmask_b32_e32 v62, v62, v63, vcc
	v_sqrt_f32_e32 v63, v62
	s_nop 0
	v_add_u32_e32 v75, -1, v63
	v_fma_f32 v83, -v75, v63, v62
	v_add_u32_e32 v79, 1, v63
	v_cmp_ge_f32_e64 s[6:7], 0, v83
	s_nop 1
	v_cndmask_b32_e64 v75, v63, v75, s[6:7]
	v_fma_f32 v63, -v79, v63, v62
	v_cmp_lt_f32_e64 s[6:7], 0, v63
	s_nop 1
	v_cndmask_b32_e64 v63, v75, v79, s[6:7]
	v_mul_f32_e32 v75, 0x37800000, v63
	v_cndmask_b32_e32 v63, v63, v75, vcc
	v_cmp_class_f32_e32 vcc, v62, v248
	s_nop 1
	v_cndmask_b32_e32 v62, v63, v62, vcc
	v_div_scale_f32 v63, s[6:7], v62, v62, 1.0
	v_rcp_f32_e32 v75, v63
	s_nop 0
	v_fma_f32 v79, -v63, v75, 1.0
	v_fmac_f32_e32 v75, v79, v75
	v_div_scale_f32 v79, vcc, 1.0, v62, 1.0
	v_mul_f32_e32 v83, v79, v75
	v_fma_f32 v87, -v63, v83, v79
	v_fmac_f32_e32 v83, v87, v75
	v_fma_f32 v63, -v63, v83, v79
	v_div_fmas_f32 v63, v63, v75, v83
	v_div_fixup_f32 v118, v63, v62, 1.0
	s_and_saveexec_b64 s[6:7], s[4:5]
	s_cbranch_execz .LBB0_1222
	v_mov_b32_e32 v63, s13
	v_add_co_u32_e32 v94, vcc, 0x1fa00000, v63
	v_mov_b32_e32 v63, s11
	v_mul_f32_e32 v62, 0x3a800000, v128
	v_addc_co_u32_e32 v95, vcc, 0, v63, vcc
	v_mov_b32_e32 v63, v118
	global_store_dwordx2 v[94:95], v[62:63], off offset:56
	s_branch .LBB0_1222

.LBB0_1310:
	s_lshl_b32 s7, s22, 8
	v_mbcnt_lo_u32_b32 v138, -1, 0
	v_mbcnt_hi_u32_b32 v138, -1, v138
	s_add_i32 s7, s7, s43
	v_and_or_b32 v140, v138, 15, s7
	s_lshl_b32 s6, s6, 8
	v_ashrrev_i32_e32 v138, 1, v138
	v_and_b32_e32 v138, -8, v138
	s_or_b32 s6, s6, s44
	v_ashrrev_i32_e32 v141, 31, v140
	v_add_u32_e32 v138, s6, v138
	v_lshlrev_b64 v[142:143], 13, v[140:141]
	v_lshl_add_u64 v[142:143], s[10:11], 0, v[142:143]
	v_cmp_gt_i32_e32 vcc, s65, v138
	v_ashrrev_i32_e32 v139, 31, v138
	s_and_saveexec_b64 s[6:7], vcc
	s_cbranch_execz .LBB0_1312
	v_max_f32_e32 v120, v120, v120
	v_max_f32_e32 v121, v121, v121
	v_max_f32_e32 v120, 0, v120
	v_max_f32_e32 v121, 0, v121
	v_pk_mul_f32 v[146:147], v[120:121], v[120:121]
	v_max_f32_e32 v121, v122, v122
	v_max_f32_e32 v124, v124, v124
	v_max_f32_e32 v125, v125, v125
	v_max_f32_e32 v120, v126, v126
	v_max_f32_e32 v122, 0, v121
	v_max_f32_e32 v121, v127, v127
	v_max_f32_e32 v123, v123, v123
	v_max_f32_e32 v124, 0, v124
	v_max_f32_e32 v125, 0, v125
	v_max_f32_e32 v120, 0, v120
	v_max_f32_e32 v121, 0, v121
	v_max_f32_e32 v123, 0, v123
	v_pk_mul_f32 v[124:125], v[124:125], v[124:125]
	v_pk_mul_f32 v[126:127], v[120:121], v[120:121]
	v_pk_mul_f32 v[148:149], v[122:123], v[122:123]
	v_cvt_pk_bf16_f32 v120, v124, v125
	v_cvt_pk_bf16_f32 v121, v126, v127
	v_cvt_pk_bf16_f32 v122, v146, v147
	v_cvt_pk_bf16_f32 v123, v148, v149
	v_lshl_add_u64 v[124:125], v[138:139], 1, v[142:143]
	global_store_dwordx4 v[124:125], v[120:123], off
.LBB0_1312:
	s_or_b64 exec, exec, s[6:7]
	s_nop 0
	v_add_u32_e32 v120, 0x80, v138
	v_cmp_gt_i32_e64 s[6:7], s65, v120
	s_and_saveexec_b64 s[22:23], s[6:7]
	s_cbranch_execz .LBB0_1314
	v_max_f32_e32 v112, v112, v112
	v_max_f32_e32 v113, v113, v113
	v_max_f32_e32 v112, 0, v112
	v_max_f32_e32 v113, 0, v113
	v_pk_mul_f32 v[120:121], v[112:113], v[112:113]
	v_max_f32_e32 v113, v114, v114
	v_max_f32_e32 v116, v116, v116
	v_max_f32_e32 v117, v117, v117
	v_max_f32_e32 v112, v118, v118
	v_max_f32_e32 v114, 0, v113
	v_max_f32_e32 v113, v119, v119
	v_max_f32_e32 v115, v115, v115
	v_max_f32_e32 v116, 0, v116
	v_max_f32_e32 v117, 0, v117
	v_max_f32_e32 v112, 0, v112
	v_max_f32_e32 v113, 0, v113
	v_max_f32_e32 v115, 0, v115
	v_pk_mul_f32 v[116:117], v[116:117], v[116:117]
	v_pk_mul_f32 v[118:119], v[112:113], v[112:113]
	v_pk_mul_f32 v[122:123], v[114:115], v[114:115]
	v_cvt_pk_bf16_f32 v112, v116, v117
	v_cvt_pk_bf16_f32 v113, v118, v119
	v_cvt_pk_bf16_f32 v114, v120, v121
	v_cvt_pk_bf16_f32 v115, v122, v123
	v_lshl_add_u64 v[116:117], v[138:139], 1, v[142:143]
	global_store_dwordx4 v[116:117], v[112:115], off offset:256
.LBB0_1314:
	s_or_b64 exec, exec, s[22:23]
	s_nop 0
	v_or_b32_e32 v112, 16, v140
	v_ashrrev_i32_e32 v113, 31, v112
	v_lshlrev_b64 v[112:113], 13, v[112:113]
	v_lshl_add_u64 v[112:113], s[10:11], 0, v[112:113]
	s_and_saveexec_b64 s[22:23], vcc
	s_cbranch_execz .LBB0_1316
	v_max_f32_e32 v104, v104, v104
	v_max_f32_e32 v105, v105, v105
	v_max_f32_e32 v104, 0, v104
	v_max_f32_e32 v105, 0, v105
	v_pk_mul_f32 v[114:115], v[104:105], v[104:105]
	v_max_f32_e32 v105, v106, v106
	v_max_f32_e32 v108, v108, v108
	v_max_f32_e32 v109, v109, v109
	v_max_f32_e32 v104, v110, v110
	v_max_f32_e32 v106, 0, v105
	v_max_f32_e32 v105, v111, v111
	v_max_f32_e32 v107, v107, v107
	v_max_f32_e32 v108, 0, v108
	v_max_f32_e32 v109, 0, v109
	v_max_f32_e32 v104, 0, v104
	v_max_f32_e32 v105, 0, v105
	v_max_f32_e32 v107, 0, v107
	v_pk_mul_f32 v[108:109], v[108:109], v[108:109]
	v_pk_mul_f32 v[110:111], v[104:105], v[104:105]
	v_pk_mul_f32 v[116:117], v[106:107], v[106:107]
	v_cvt_pk_bf16_f32 v104, v108, v109
	v_cvt_pk_bf16_f32 v105, v110, v111
	v_cvt_pk_bf16_f32 v106, v114, v115
	v_cvt_pk_bf16_f32 v107, v116, v117
	v_lshl_add_u64 v[108:109], v[138:139], 1, v[112:113]
	global_store_dwordx4 v[108:109], v[104:107], off
.LBB0_1316:
	s_or_b64 exec, exec, s[22:23]
	s_and_saveexec_b64 s[22:23], s[6:7]
	s_cbranch_execz .LBB0_1318
	v_max_f32_e32 v96, v96, v96
	v_max_f32_e32 v97, v97, v97
	v_max_f32_e32 v96, 0, v96
	v_max_f32_e32 v97, 0, v97
	v_pk_mul_f32 v[104:105], v[96:97], v[96:97]
	v_max_f32_e32 v97, v98, v98
	v_max_f32_e32 v100, v100, v100
	v_max_f32_e32 v101, v101, v101
	v_max_f32_e32 v96, v102, v102
	v_max_f32_e32 v98, 0, v97
	v_max_f32_e32 v97, v103, v103
	v_max_f32_e32 v99, v99, v99
	v_max_f32_e32 v100, 0, v100
	v_max_f32_e32 v101, 0, v101
	v_max_f32_e32 v96, 0, v96
	v_max_f32_e32 v97, 0, v97
	v_max_f32_e32 v99, 0, v99
	v_pk_mul_f32 v[100:101], v[100:101], v[100:101]
	v_pk_mul_f32 v[102:103], v[96:97], v[96:97]
	v_pk_mul_f32 v[106:107], v[98:99], v[98:99]
	v_cvt_pk_bf16_f32 v96, v100, v101
	v_cvt_pk_bf16_f32 v97, v102, v103
	v_cvt_pk_bf16_f32 v98, v104, v105
	v_cvt_pk_bf16_f32 v99, v106, v107
	v_lshl_add_u64 v[100:101], v[138:139], 1, v[112:113]
	global_store_dwordx4 v[100:101], v[96:99], off offset:256
.LBB0_1318:
	s_or_b64 exec, exec, s[22:23]
	s_nop 0
	v_or_b32_e32 v96, 32, v140
	v_ashrrev_i32_e32 v97, 31, v96
	v_lshlrev_b64 v[96:97], 13, v[96:97]
	v_lshl_add_u64 v[96:97], s[10:11], 0, v[96:97]
	s_and_saveexec_b64 s[22:23], vcc
	s_cbranch_execz .LBB0_1320
	v_max_f32_e32 v88, v88, v88
	v_max_f32_e32 v89, v89, v89
	v_max_f32_e32 v88, 0, v88
	v_max_f32_e32 v89, 0, v89
	v_pk_mul_f32 v[98:99], v[88:89], v[88:89]
	v_max_f32_e32 v89, v90, v90
	v_max_f32_e32 v92, v92, v92
	v_max_f32_e32 v93, v93, v93
	v_max_f32_e32 v88, v94, v94
	v_max_f32_e32 v90, 0, v89
	v_max_f32_e32 v89, v95, v95
	v_max_f32_e32 v91, v91, v91
	v_max_f32_e32 v92, 0, v92
	v_max_f32_e32 v93, 0, v93
	v_max_f32_e32 v88, 0, v88
	v_max_f32_e32 v89, 0, v89
	v_max_f32_e32 v91, 0, v91
	v_pk_mul_f32 v[92:93], v[92:93], v[92:93]
	v_pk_mul_f32 v[94:95], v[88:89], v[88:89]
	v_pk_mul_f32 v[100:101], v[90:91], v[90:91]
	v_cvt_pk_bf16_f32 v88, v92, v93
	v_cvt_pk_bf16_f32 v89, v94, v95
	v_cvt_pk_bf16_f32 v90, v98, v99
	v_cvt_pk_bf16_f32 v91, v100, v101
	v_lshl_add_u64 v[92:93], v[138:139], 1, v[96:97]
	global_store_dwordx4 v[92:93], v[88:91], off
.LBB0_1320:
	s_or_b64 exec, exec, s[22:23]
	s_and_saveexec_b64 s[22:23], s[6:7]
	s_cbranch_execz .LBB0_1322
	v_max_f32_e32 v80, v80, v80
	v_max_f32_e32 v81, v81, v81
	v_max_f32_e32 v80, 0, v80
	v_max_f32_e32 v81, 0, v81
	v_pk_mul_f32 v[88:89], v[80:81], v[80:81]
	v_max_f32_e32 v81, v82, v82
	v_max_f32_e32 v84, v84, v84
	v_max_f32_e32 v85, v85, v85
	v_max_f32_e32 v80, v86, v86
	v_max_f32_e32 v82, 0, v81
	v_max_f32_e32 v81, v87, v87
	v_max_f32_e32 v83, v83, v83
	v_max_f32_e32 v84, 0, v84
	v_max_f32_e32 v85, 0, v85
	v_max_f32_e32 v80, 0, v80
	v_max_f32_e32 v81, 0, v81
	v_max_f32_e32 v83, 0, v83
	v_pk_mul_f32 v[84:85], v[84:85], v[84:85]
	v_pk_mul_f32 v[86:87], v[80:81], v[80:81]
	v_pk_mul_f32 v[90:91], v[82:83], v[82:83]
	v_cvt_pk_bf16_f32 v80, v84, v85
	v_cvt_pk_bf16_f32 v81, v86, v87
	v_cvt_pk_bf16_f32 v82, v88, v89
	v_cvt_pk_bf16_f32 v83, v90, v91
	v_lshl_add_u64 v[84:85], v[138:139], 1, v[96:97]
	global_store_dwordx4 v[84:85], v[80:83], off offset:256
.LBB0_1322:
	s_or_b64 exec, exec, s[22:23]
	s_nop 0
	v_or_b32_e32 v80, 48, v140
	v_ashrrev_i32_e32 v81, 31, v80
	v_lshlrev_b64 v[80:81], 13, v[80:81]
	v_lshl_add_u64 v[80:81], s[10:11], 0, v[80:81]
	s_and_saveexec_b64 s[22:23], vcc
	s_cbranch_execz .LBB0_1324
	v_max_f32_e32 v72, v72, v72
	v_max_f32_e32 v73, v73, v73
	v_max_f32_e32 v72, 0, v72
	v_max_f32_e32 v73, 0, v73
	v_pk_mul_f32 v[82:83], v[72:73], v[72:73]
	v_max_f32_e32 v73, v74, v74
	v_max_f32_e32 v76, v76, v76
	v_max_f32_e32 v77, v77, v77
	v_max_f32_e32 v72, v78, v78
	v_max_f32_e32 v74, 0, v73
	v_max_f32_e32 v73, v79, v79
	v_max_f32_e32 v75, v75, v75
	v_max_f32_e32 v76, 0, v76
	v_max_f32_e32 v77, 0, v77
	v_max_f32_e32 v72, 0, v72
	v_max_f32_e32 v73, 0, v73
	v_max_f32_e32 v75, 0, v75
	v_pk_mul_f32 v[76:77], v[76:77], v[76:77]
	v_pk_mul_f32 v[78:79], v[72:73], v[72:73]
	v_pk_mul_f32 v[84:85], v[74:75], v[74:75]
	v_cvt_pk_bf16_f32 v72, v76, v77
	v_cvt_pk_bf16_f32 v73, v78, v79
	v_cvt_pk_bf16_f32 v74, v82, v83
	v_cvt_pk_bf16_f32 v75, v84, v85
	v_lshl_add_u64 v[76:77], v[138:139], 1, v[80:81]
	global_store_dwordx4 v[76:77], v[72:75], off
.LBB0_1324:
	s_or_b64 exec, exec, s[22:23]
	s_and_saveexec_b64 s[22:23], s[6:7]
	s_cbranch_execz .LBB0_1326
	v_max_f32_e32 v64, v64, v64
	v_max_f32_e32 v65, v65, v65
	v_max_f32_e32 v64, 0, v64
	v_max_f32_e32 v65, 0, v65
	v_pk_mul_f32 v[72:73], v[64:65], v[64:65]
	v_max_f32_e32 v65, v66, v66
	v_max_f32_e32 v68, v68, v68
	v_max_f32_e32 v69, v69, v69
	v_max_f32_e32 v64, v70, v70
	v_max_f32_e32 v66, 0, v65
	v_max_f32_e32 v65, v71, v71
	v_max_f32_e32 v67, v67, v67
	v_max_f32_e32 v68, 0, v68
	v_max_f32_e32 v69, 0, v69
	v_max_f32_e32 v64, 0, v64
	v_max_f32_e32 v65, 0, v65
	v_max_f32_e32 v67, 0, v67
	v_pk_mul_f32 v[68:69], v[68:69], v[68:69]
	v_pk_mul_f32 v[70:71], v[64:65], v[64:65]
	v_pk_mul_f32 v[74:75], v[66:67], v[66:67]
	v_cvt_pk_bf16_f32 v64, v68, v69
	v_cvt_pk_bf16_f32 v65, v70, v71
	v_cvt_pk_bf16_f32 v66, v72, v73
	v_cvt_pk_bf16_f32 v67, v74, v75
	v_lshl_add_u64 v[68:69], v[138:139], 1, v[80:81]
	global_store_dwordx4 v[68:69], v[64:67], off offset:256
.LBB0_1326:
	s_or_b64 exec, exec, s[22:23]
	s_nop 0
	v_add_u32_e32 v64, 0x80, v140
	v_ashrrev_i32_e32 v65, 31, v64
	v_lshlrev_b64 v[64:65], 13, v[64:65]
	v_lshl_add_u64 v[64:65], s[10:11], 0, v[64:65]
	s_and_saveexec_b64 s[22:23], vcc
	s_cbranch_execz .LBB0_1328
	v_max_f32_e32 v56, v56, v56
	v_max_f32_e32 v57, v57, v57
	v_max_f32_e32 v56, 0, v56
	v_max_f32_e32 v57, 0, v57
	v_pk_mul_f32 v[66:67], v[56:57], v[56:57]
	v_max_f32_e32 v57, v58, v58
	v_max_f32_e32 v60, v60, v60
	v_max_f32_e32 v61, v61, v61
	v_max_f32_e32 v56, v62, v62
	v_max_f32_e32 v58, 0, v57
	v_max_f32_e32 v57, v63, v63
	v_max_f32_e32 v59, v59, v59
	v_max_f32_e32 v60, 0, v60
	v_max_f32_e32 v61, 0, v61
	v_max_f32_e32 v56, 0, v56
	v_max_f32_e32 v57, 0, v57
	v_max_f32_e32 v59, 0, v59
	v_pk_mul_f32 v[60:61], v[60:61], v[60:61]
	v_pk_mul_f32 v[62:63], v[56:57], v[56:57]
	v_pk_mul_f32 v[68:69], v[58:59], v[58:59]
	v_cvt_pk_bf16_f32 v56, v60, v61
	v_cvt_pk_bf16_f32 v57, v62, v63
	v_cvt_pk_bf16_f32 v58, v66, v67
	v_cvt_pk_bf16_f32 v59, v68, v69
	v_lshl_add_u64 v[60:61], v[138:139], 1, v[64:65]
	global_store_dwordx4 v[60:61], v[56:59], off
.LBB0_1328:
	s_or_b64 exec, exec, s[22:23]
	s_and_saveexec_b64 s[22:23], s[6:7]
	s_cbranch_execz .LBB0_1330
	v_max_f32_e32 v48, v48, v48
	v_max_f32_e32 v49, v49, v49
	v_max_f32_e32 v48, 0, v48
	v_max_f32_e32 v49, 0, v49
	v_pk_mul_f32 v[56:57], v[48:49], v[48:49]
	v_max_f32_e32 v49, v50, v50
	v_max_f32_e32 v52, v52, v52
	v_max_f32_e32 v53, v53, v53
	v_max_f32_e32 v48, v54, v54
	v_max_f32_e32 v50, 0, v49
	v_max_f32_e32 v49, v55, v55
	v_max_f32_e32 v51, v51, v51
	v_max_f32_e32 v52, 0, v52
	v_max_f32_e32 v53, 0, v53
	v_max_f32_e32 v48, 0, v48
	v_max_f32_e32 v49, 0, v49
	v_max_f32_e32 v51, 0, v51
	v_pk_mul_f32 v[52:53], v[52:53], v[52:53]
	v_pk_mul_f32 v[54:55], v[48:49], v[48:49]
	v_pk_mul_f32 v[58:59], v[50:51], v[50:51]
	v_cvt_pk_bf16_f32 v48, v52, v53
	v_cvt_pk_bf16_f32 v49, v54, v55
	v_cvt_pk_bf16_f32 v50, v56, v57
	v_cvt_pk_bf16_f32 v51, v58, v59
	v_lshl_add_u64 v[52:53], v[138:139], 1, v[64:65]
	global_store_dwordx4 v[52:53], v[48:51], off offset:256
.LBB0_1330:
	s_or_b64 exec, exec, s[22:23]
	s_nop 0
	v_add_u32_e32 v48, 0x90, v140
	v_ashrrev_i32_e32 v49, 31, v48
	v_lshlrev_b64 v[48:49], 13, v[48:49]
	v_lshl_add_u64 v[48:49], s[10:11], 0, v[48:49]
	s_and_saveexec_b64 s[22:23], vcc
	s_cbranch_execz .LBB0_1332
	v_max_f32_e32 v40, v40, v40
	v_max_f32_e32 v41, v41, v41
	v_max_f32_e32 v40, 0, v40
	v_max_f32_e32 v41, 0, v41
	v_pk_mul_f32 v[50:51], v[40:41], v[40:41]
	v_max_f32_e32 v41, v42, v42
	v_max_f32_e32 v44, v44, v44
	v_max_f32_e32 v45, v45, v45
	v_max_f32_e32 v40, v46, v46
	v_max_f32_e32 v42, 0, v41
	v_max_f32_e32 v41, v47, v47
	v_max_f32_e32 v43, v43, v43
	v_max_f32_e32 v44, 0, v44
	v_max_f32_e32 v45, 0, v45
	v_max_f32_e32 v40, 0, v40
	v_max_f32_e32 v41, 0, v41
	v_max_f32_e32 v43, 0, v43
	v_pk_mul_f32 v[44:45], v[44:45], v[44:45]
	v_pk_mul_f32 v[46:47], v[40:41], v[40:41]
	v_pk_mul_f32 v[52:53], v[42:43], v[42:43]
	v_cvt_pk_bf16_f32 v40, v44, v45
	v_cvt_pk_bf16_f32 v41, v46, v47
	v_cvt_pk_bf16_f32 v42, v50, v51
	v_cvt_pk_bf16_f32 v43, v52, v53
	v_lshl_add_u64 v[44:45], v[138:139], 1, v[48:49]
	global_store_dwordx4 v[44:45], v[40:43], off
.LBB0_1332:
	s_or_b64 exec, exec, s[22:23]
	s_and_saveexec_b64 s[22:23], s[6:7]
	s_cbranch_execz .LBB0_1334
	v_max_f32_e32 v32, v32, v32
	v_max_f32_e32 v33, v33, v33
	v_max_f32_e32 v32, 0, v32
	v_max_f32_e32 v33, 0, v33
	v_pk_mul_f32 v[40:41], v[32:33], v[32:33]
	v_max_f32_e32 v33, v34, v34
	v_max_f32_e32 v36, v36, v36
	v_max_f32_e32 v37, v37, v37
	v_max_f32_e32 v32, v38, v38
	v_max_f32_e32 v34, 0, v33
	v_max_f32_e32 v33, v39, v39
	v_max_f32_e32 v35, v35, v35
	v_max_f32_e32 v36, 0, v36
	v_max_f32_e32 v37, 0, v37
	v_max_f32_e32 v32, 0, v32
	v_max_f32_e32 v33, 0, v33
	v_max_f32_e32 v35, 0, v35
	v_pk_mul_f32 v[36:37], v[36:37], v[36:37]
	v_pk_mul_f32 v[38:39], v[32:33], v[32:33]
	v_pk_mul_f32 v[42:43], v[34:35], v[34:35]
	v_cvt_pk_bf16_f32 v32, v36, v37
	v_cvt_pk_bf16_f32 v33, v38, v39
	v_cvt_pk_bf16_f32 v34, v40, v41
	v_cvt_pk_bf16_f32 v35, v42, v43
	v_lshl_add_u64 v[36:37], v[138:139], 1, v[48:49]
	global_store_dwordx4 v[36:37], v[32:35], off offset:256
.LBB0_1334:
	s_or_b64 exec, exec, s[22:23]
	s_nop 0
	v_add_u32_e32 v32, 0xa0, v140
	v_ashrrev_i32_e32 v33, 31, v32
	v_lshlrev_b64 v[32:33], 13, v[32:33]
	v_lshl_add_u64 v[32:33], s[10:11], 0, v[32:33]
	s_and_saveexec_b64 s[22:23], vcc
	s_cbranch_execz .LBB0_1336
	v_max_f32_e32 v24, v24, v24
	v_max_f32_e32 v25, v25, v25
	v_max_f32_e32 v24, 0, v24
	v_max_f32_e32 v25, 0, v25
	v_pk_mul_f32 v[34:35], v[24:25], v[24:25]
	v_max_f32_e32 v25, v26, v26
	v_max_f32_e32 v28, v28, v28
	v_max_f32_e32 v29, v29, v29
	v_max_f32_e32 v24, v30, v30
	v_max_f32_e32 v26, 0, v25
	v_max_f32_e32 v25, v31, v31
	v_max_f32_e32 v27, v27, v27
	v_max_f32_e32 v28, 0, v28
	v_max_f32_e32 v29, 0, v29
	v_max_f32_e32 v24, 0, v24
	v_max_f32_e32 v25, 0, v25
	v_max_f32_e32 v27, 0, v27
	v_pk_mul_f32 v[28:29], v[28:29], v[28:29]
	v_pk_mul_f32 v[30:31], v[24:25], v[24:25]
	v_pk_mul_f32 v[36:37], v[26:27], v[26:27]
	v_cvt_pk_bf16_f32 v24, v28, v29
	v_cvt_pk_bf16_f32 v25, v30, v31
	v_cvt_pk_bf16_f32 v26, v34, v35
	v_cvt_pk_bf16_f32 v27, v36, v37
	v_lshl_add_u64 v[28:29], v[138:139], 1, v[32:33]
	global_store_dwordx4 v[28:29], v[24:27], off
.LBB0_1336:
	s_or_b64 exec, exec, s[22:23]
	s_and_saveexec_b64 s[22:23], s[6:7]
	s_cbranch_execz .LBB0_1338
	v_max_f32_e32 v16, v16, v16
	v_max_f32_e32 v17, v17, v17
	v_max_f32_e32 v16, 0, v16
	v_max_f32_e32 v17, 0, v17
	v_pk_mul_f32 v[24:25], v[16:17], v[16:17]
	v_max_f32_e32 v17, v18, v18
	v_max_f32_e32 v20, v20, v20
	v_max_f32_e32 v21, v21, v21
	v_max_f32_e32 v16, v22, v22
	v_max_f32_e32 v18, 0, v17
	v_max_f32_e32 v17, v23, v23
	v_max_f32_e32 v19, v19, v19
	v_max_f32_e32 v20, 0, v20
	v_max_f32_e32 v21, 0, v21
	v_max_f32_e32 v16, 0, v16
	v_max_f32_e32 v17, 0, v17
	v_max_f32_e32 v19, 0, v19
	v_pk_mul_f32 v[20:21], v[20:21], v[20:21]
	v_pk_mul_f32 v[22:23], v[16:17], v[16:17]
	v_pk_mul_f32 v[26:27], v[18:19], v[18:19]
	v_cvt_pk_bf16_f32 v16, v20, v21
	v_cvt_pk_bf16_f32 v17, v22, v23
	v_cvt_pk_bf16_f32 v18, v24, v25
	v_cvt_pk_bf16_f32 v19, v26, v27
	v_lshl_add_u64 v[20:21], v[138:139], 1, v[32:33]
	global_store_dwordx4 v[20:21], v[16:19], off offset:256
.LBB0_1338:
	s_or_b64 exec, exec, s[22:23]
	s_nop 0
	v_add_u32_e32 v16, 0xb0, v140
	v_ashrrev_i32_e32 v17, 31, v16
	v_lshlrev_b64 v[16:17], 13, v[16:17]
	v_lshl_add_u64 v[16:17], s[10:11], 0, v[16:17]
	s_and_saveexec_b64 s[22:23], vcc
	s_cbranch_execz .LBB0_1340
	v_max_f32_e32 v8, v8, v8
	v_max_f32_e32 v9, v9, v9
	v_max_f32_e32 v8, 0, v8
	v_max_f32_e32 v9, 0, v9
	v_pk_mul_f32 v[18:19], v[8:9], v[8:9]
	v_max_f32_e32 v9, v10, v10
	v_max_f32_e32 v12, v12, v12
	v_max_f32_e32 v13, v13, v13
	v_max_f32_e32 v8, v14, v14
	v_max_f32_e32 v10, 0, v9
	v_max_f32_e32 v9, v15, v15
	v_max_f32_e32 v11, v11, v11
	v_max_f32_e32 v12, 0, v12
	v_max_f32_e32 v13, 0, v13
	v_max_f32_e32 v8, 0, v8
	v_max_f32_e32 v9, 0, v9
	v_max_f32_e32 v11, 0, v11
	v_pk_mul_f32 v[12:13], v[12:13], v[12:13]
	v_pk_mul_f32 v[14:15], v[8:9], v[8:9]
	v_pk_mul_f32 v[20:21], v[10:11], v[10:11]
	v_cvt_pk_bf16_f32 v8, v12, v13
	v_cvt_pk_bf16_f32 v9, v14, v15
	v_cvt_pk_bf16_f32 v10, v18, v19
	v_cvt_pk_bf16_f32 v11, v20, v21
	v_lshl_add_u64 v[12:13], v[138:139], 1, v[16:17]
	global_store_dwordx4 v[12:13], v[8:11], off
.LBB0_1340:
	s_or_b64 exec, exec, s[22:23]
	s_and_saveexec_b64 s[22:23], s[6:7]
	s_cbranch_execz .LBB0_1342
	v_max_f32_e32 v0, v0, v0
	v_max_f32_e32 v1, v1, v1
	v_max_f32_e32 v0, 0, v0
	v_max_f32_e32 v1, 0, v1
	v_pk_mul_f32 v[8:9], v[0:1], v[0:1]
	v_max_f32_e32 v1, v2, v2
	v_max_f32_e32 v4, v4, v4
	v_max_f32_e32 v5, v5, v5
	v_max_f32_e32 v0, v6, v6
	v_max_f32_e32 v2, 0, v1
	v_max_f32_e32 v1, v7, v7
	v_max_f32_e32 v3, v3, v3
	v_max_f32_e32 v4, 0, v4
	v_max_f32_e32 v5, 0, v5
	v_max_f32_e32 v0, 0, v0
	v_max_f32_e32 v1, 0, v1
	v_max_f32_e32 v3, 0, v3
	v_pk_mul_f32 v[4:5], v[4:5], v[4:5]
	v_pk_mul_f32 v[6:7], v[0:1], v[0:1]
	v_pk_mul_f32 v[10:11], v[2:3], v[2:3]
	v_cvt_pk_bf16_f32 v0, v4, v5
	v_cvt_pk_bf16_f32 v1, v6, v7
	v_cvt_pk_bf16_f32 v2, v8, v9
	v_cvt_pk_bf16_f32 v3, v10, v11
	v_lshl_add_u64 v[4:5], v[138:139], 1, v[16:17]
	global_store_dwordx4 v[4:5], v[0:3], off offset:256

.LBB0_1368:
	s_lshl_b32 s7, s22, 8
	v_mbcnt_lo_u32_b32 v138, -1, 0
	v_mbcnt_hi_u32_b32 v138, -1, v138
	s_add_i32 s7, s7, s43
	v_and_or_b32 v140, v138, 15, s7
	s_lshl_b32 s6, s6, 8
	v_ashrrev_i32_e32 v138, 1, v138
	v_and_b32_e32 v138, -8, v138
	s_or_b32 s6, s6, s44
	v_ashrrev_i32_e32 v141, 31, v140
	v_add_u32_e32 v138, s6, v138
	v_lshlrev_b64 v[142:143], 11, v[140:141]
	v_lshl_add_u64 v[142:143], s[10:11], 0, v[142:143]
	v_cmp_gt_i32_e32 vcc, s78, v138
	v_ashrrev_i32_e32 v139, 31, v138
	s_and_saveexec_b64 s[6:7], vcc
	s_cbranch_execz .LBB0_1370
	v_mul_f32_e32 v120, 0xbfb8aa3b, v120
	v_exp_f32_e32 v120, v120
	v_mul_f32_e32 v125, 0xbfb8aa3b, v125
	v_exp_f32_e32 v125, v125
	v_mul_f32_e32 v121, 0xbfb8aa3b, v121
	v_add_f32_e32 v120, 1.0, v120
	v_exp_f32_e32 v121, v121
	v_rcp_f32_e32 v141, v120
	v_add_f32_e32 v120, 1.0, v125
	v_mul_f32_e32 v125, 0xbfb8aa3b, v126
	v_exp_f32_e32 v125, v125
	v_add_f32_e32 v121, 1.0, v121
	v_mul_f32_e32 v122, 0xbfb8aa3b, v122
	v_mul_f32_e32 v124, 0xbfb8aa3b, v124
	v_exp_f32_e32 v122, v122
	v_rcp_f32_e32 v126, v121
	v_add_f32_e32 v121, 1.0, v125
	v_mul_f32_e32 v125, 0xbfb8aa3b, v127
	v_mul_f32_e32 v123, 0xbfb8aa3b, v123
	v_exp_f32_e32 v124, v124
	v_exp_f32_e32 v125, v125
	v_exp_f32_e32 v123, v123
	v_add_f32_e32 v122, 1.0, v122
	v_add_f32_e32 v124, 1.0, v124
	v_rcp_f32_e32 v127, v122
	v_add_f32_e32 v122, 1.0, v125
	v_add_f32_e32 v123, 1.0, v123
	v_rcp_f32_e32 v124, v124
	v_rcp_f32_e32 v120, v120
	v_rcp_f32_e32 v121, v121
	v_rcp_f32_e32 v122, v122
	v_rcp_f32_e32 v123, v123
	v_cvt_pk_bf16_f32 v120, v124, v120
	v_lshl_add_u64 v[124:125], v[138:139], 1, v[142:143]
	v_cvt_pk_bf16_f32 v121, v121, v122
	v_cvt_pk_bf16_f32 v122, v141, v126
	v_cvt_pk_bf16_f32 v123, v127, v123
	global_store_dwordx4 v[124:125], v[120:123], off
.LBB0_1370:
	s_or_b64 exec, exec, s[6:7]
	s_nop 0
	v_add_u32_e32 v120, 0x80, v138
	v_cmp_gt_i32_e64 s[6:7], s78, v120
	s_and_saveexec_b64 s[22:23], s[6:7]
	s_cbranch_execz .LBB0_1372
	v_mul_f32_e32 v112, 0xbfb8aa3b, v112
	v_exp_f32_e32 v112, v112
	v_mul_f32_e32 v117, 0xbfb8aa3b, v117
	v_exp_f32_e32 v117, v117
	v_mul_f32_e32 v113, 0xbfb8aa3b, v113
	v_add_f32_e32 v112, 1.0, v112
	v_exp_f32_e32 v113, v113
	v_rcp_f32_e32 v120, v112
	v_add_f32_e32 v112, 1.0, v117
	v_mul_f32_e32 v117, 0xbfb8aa3b, v118
	v_exp_f32_e32 v117, v117
	v_add_f32_e32 v113, 1.0, v113
	v_mul_f32_e32 v114, 0xbfb8aa3b, v114
	v_mul_f32_e32 v116, 0xbfb8aa3b, v116
	v_exp_f32_e32 v114, v114
	v_rcp_f32_e32 v118, v113
	v_add_f32_e32 v113, 1.0, v117
	v_mul_f32_e32 v117, 0xbfb8aa3b, v119
	v_mul_f32_e32 v115, 0xbfb8aa3b, v115
	v_exp_f32_e32 v116, v116
	v_exp_f32_e32 v117, v117
	v_exp_f32_e32 v115, v115
	v_add_f32_e32 v114, 1.0, v114
	v_add_f32_e32 v116, 1.0, v116
	v_rcp_f32_e32 v119, v114
	v_add_f32_e32 v114, 1.0, v117
	v_add_f32_e32 v115, 1.0, v115
	v_rcp_f32_e32 v116, v116
	v_rcp_f32_e32 v112, v112
	v_rcp_f32_e32 v113, v113
	v_rcp_f32_e32 v114, v114
	v_rcp_f32_e32 v115, v115
	v_cvt_pk_bf16_f32 v112, v116, v112
	v_lshl_add_u64 v[116:117], v[138:139], 1, v[142:143]
	v_cvt_pk_bf16_f32 v113, v113, v114
	v_cvt_pk_bf16_f32 v114, v120, v118
	v_cvt_pk_bf16_f32 v115, v119, v115
	global_store_dwordx4 v[116:117], v[112:115], off offset:256
.LBB0_1372:
	s_or_b64 exec, exec, s[22:23]
	s_nop 0
	v_or_b32_e32 v112, 16, v140
	v_ashrrev_i32_e32 v113, 31, v112
	v_lshlrev_b64 v[112:113], 11, v[112:113]
	v_lshl_add_u64 v[112:113], s[10:11], 0, v[112:113]
	s_and_saveexec_b64 s[22:23], vcc
	s_cbranch_execz .LBB0_1374
	v_mul_f32_e32 v104, 0xbfb8aa3b, v104
	v_exp_f32_e32 v104, v104
	v_mul_f32_e32 v109, 0xbfb8aa3b, v109
	v_exp_f32_e32 v109, v109
	v_mul_f32_e32 v105, 0xbfb8aa3b, v105
	v_add_f32_e32 v104, 1.0, v104
	v_exp_f32_e32 v105, v105
	v_rcp_f32_e32 v114, v104
	v_add_f32_e32 v104, 1.0, v109
	v_mul_f32_e32 v109, 0xbfb8aa3b, v110
	v_exp_f32_e32 v109, v109
	v_add_f32_e32 v105, 1.0, v105
	v_mul_f32_e32 v106, 0xbfb8aa3b, v106
	v_mul_f32_e32 v108, 0xbfb8aa3b, v108
	v_exp_f32_e32 v106, v106
	v_rcp_f32_e32 v110, v105
	v_add_f32_e32 v105, 1.0, v109
	v_mul_f32_e32 v109, 0xbfb8aa3b, v111
	v_mul_f32_e32 v107, 0xbfb8aa3b, v107
	v_exp_f32_e32 v108, v108
	v_exp_f32_e32 v109, v109
	v_exp_f32_e32 v107, v107
	v_add_f32_e32 v106, 1.0, v106
	v_add_f32_e32 v108, 1.0, v108
	v_rcp_f32_e32 v111, v106
	v_add_f32_e32 v106, 1.0, v109
	v_add_f32_e32 v107, 1.0, v107
	v_rcp_f32_e32 v108, v108
	v_rcp_f32_e32 v104, v104
	v_rcp_f32_e32 v105, v105
	v_rcp_f32_e32 v106, v106
	v_rcp_f32_e32 v107, v107
	v_cvt_pk_bf16_f32 v104, v108, v104
	v_lshl_add_u64 v[108:109], v[138:139], 1, v[112:113]
	v_cvt_pk_bf16_f32 v105, v105, v106
	v_cvt_pk_bf16_f32 v106, v114, v110
	v_cvt_pk_bf16_f32 v107, v111, v107
	global_store_dwordx4 v[108:109], v[104:107], off
.LBB0_1374:
	s_or_b64 exec, exec, s[22:23]
	s_and_saveexec_b64 s[22:23], s[6:7]
	s_cbranch_execz .LBB0_1376
	v_mul_f32_e32 v96, 0xbfb8aa3b, v96
	v_exp_f32_e32 v96, v96
	v_mul_f32_e32 v101, 0xbfb8aa3b, v101
	v_exp_f32_e32 v101, v101
	v_mul_f32_e32 v97, 0xbfb8aa3b, v97
	v_add_f32_e32 v96, 1.0, v96
	v_exp_f32_e32 v97, v97
	v_rcp_f32_e32 v104, v96
	v_add_f32_e32 v96, 1.0, v101
	v_mul_f32_e32 v101, 0xbfb8aa3b, v102
	v_exp_f32_e32 v101, v101
	v_add_f32_e32 v97, 1.0, v97
	v_mul_f32_e32 v98, 0xbfb8aa3b, v98
	v_mul_f32_e32 v100, 0xbfb8aa3b, v100
	v_exp_f32_e32 v98, v98
	v_rcp_f32_e32 v102, v97
	v_add_f32_e32 v97, 1.0, v101
	v_mul_f32_e32 v101, 0xbfb8aa3b, v103
	v_mul_f32_e32 v99, 0xbfb8aa3b, v99
	v_exp_f32_e32 v100, v100
	v_exp_f32_e32 v101, v101
	v_exp_f32_e32 v99, v99
	v_add_f32_e32 v98, 1.0, v98
	v_add_f32_e32 v100, 1.0, v100
	v_rcp_f32_e32 v103, v98
	v_add_f32_e32 v98, 1.0, v101
	v_add_f32_e32 v99, 1.0, v99
	v_rcp_f32_e32 v100, v100
	v_rcp_f32_e32 v96, v96
	v_rcp_f32_e32 v97, v97
	v_rcp_f32_e32 v98, v98
	v_rcp_f32_e32 v99, v99
	v_cvt_pk_bf16_f32 v96, v100, v96
	v_lshl_add_u64 v[100:101], v[138:139], 1, v[112:113]
	v_cvt_pk_bf16_f32 v97, v97, v98
	v_cvt_pk_bf16_f32 v98, v104, v102
	v_cvt_pk_bf16_f32 v99, v103, v99
	global_store_dwordx4 v[100:101], v[96:99], off offset:256
.LBB0_1376:
	s_or_b64 exec, exec, s[22:23]
	s_nop 0
	v_or_b32_e32 v96, 32, v140
	v_ashrrev_i32_e32 v97, 31, v96
	v_lshlrev_b64 v[96:97], 11, v[96:97]
	v_lshl_add_u64 v[96:97], s[10:11], 0, v[96:97]
	s_and_saveexec_b64 s[22:23], vcc
	s_cbranch_execz .LBB0_1378
	v_mul_f32_e32 v88, 0xbfb8aa3b, v88
	v_exp_f32_e32 v88, v88
	v_mul_f32_e32 v93, 0xbfb8aa3b, v93
	v_exp_f32_e32 v93, v93
	v_mul_f32_e32 v89, 0xbfb8aa3b, v89
	v_add_f32_e32 v88, 1.0, v88
	v_exp_f32_e32 v89, v89
	v_rcp_f32_e32 v98, v88
	v_add_f32_e32 v88, 1.0, v93
	v_mul_f32_e32 v93, 0xbfb8aa3b, v94
	v_exp_f32_e32 v93, v93
	v_add_f32_e32 v89, 1.0, v89
	v_mul_f32_e32 v90, 0xbfb8aa3b, v90
	v_mul_f32_e32 v92, 0xbfb8aa3b, v92
	v_exp_f32_e32 v90, v90
	v_rcp_f32_e32 v94, v89
	v_add_f32_e32 v89, 1.0, v93
	v_mul_f32_e32 v93, 0xbfb8aa3b, v95
	v_mul_f32_e32 v91, 0xbfb8aa3b, v91
	v_exp_f32_e32 v92, v92
	v_exp_f32_e32 v93, v93
	v_exp_f32_e32 v91, v91
	v_add_f32_e32 v90, 1.0, v90
	v_add_f32_e32 v92, 1.0, v92
	v_rcp_f32_e32 v95, v90
	v_add_f32_e32 v90, 1.0, v93
	v_add_f32_e32 v91, 1.0, v91
	v_rcp_f32_e32 v92, v92
	v_rcp_f32_e32 v88, v88
	v_rcp_f32_e32 v89, v89
	v_rcp_f32_e32 v90, v90
	v_rcp_f32_e32 v91, v91
	v_cvt_pk_bf16_f32 v88, v92, v88
	v_lshl_add_u64 v[92:93], v[138:139], 1, v[96:97]
	v_cvt_pk_bf16_f32 v89, v89, v90
	v_cvt_pk_bf16_f32 v90, v98, v94
	v_cvt_pk_bf16_f32 v91, v95, v91
	global_store_dwordx4 v[92:93], v[88:91], off
.LBB0_1378:
	s_or_b64 exec, exec, s[22:23]
	s_and_saveexec_b64 s[22:23], s[6:7]
	s_cbranch_execz .LBB0_1380
	v_mul_f32_e32 v80, 0xbfb8aa3b, v80
	v_exp_f32_e32 v80, v80
	v_mul_f32_e32 v85, 0xbfb8aa3b, v85
	v_exp_f32_e32 v85, v85
	v_mul_f32_e32 v81, 0xbfb8aa3b, v81
	v_add_f32_e32 v80, 1.0, v80
	v_exp_f32_e32 v81, v81
	v_rcp_f32_e32 v88, v80
	v_add_f32_e32 v80, 1.0, v85
	v_mul_f32_e32 v85, 0xbfb8aa3b, v86
	v_exp_f32_e32 v85, v85
	v_add_f32_e32 v81, 1.0, v81
	v_mul_f32_e32 v82, 0xbfb8aa3b, v82
	v_mul_f32_e32 v84, 0xbfb8aa3b, v84
	v_exp_f32_e32 v82, v82
	v_rcp_f32_e32 v86, v81
	v_add_f32_e32 v81, 1.0, v85
	v_mul_f32_e32 v85, 0xbfb8aa3b, v87
	v_mul_f32_e32 v83, 0xbfb8aa3b, v83
	v_exp_f32_e32 v84, v84
	v_exp_f32_e32 v85, v85
	v_exp_f32_e32 v83, v83
	v_add_f32_e32 v82, 1.0, v82
	v_add_f32_e32 v84, 1.0, v84
	v_rcp_f32_e32 v87, v82
	v_add_f32_e32 v82, 1.0, v85
	v_add_f32_e32 v83, 1.0, v83
	v_rcp_f32_e32 v84, v84
	v_rcp_f32_e32 v80, v80
	v_rcp_f32_e32 v81, v81
	v_rcp_f32_e32 v82, v82
	v_rcp_f32_e32 v83, v83
	v_cvt_pk_bf16_f32 v80, v84, v80
	v_lshl_add_u64 v[84:85], v[138:139], 1, v[96:97]
	v_cvt_pk_bf16_f32 v81, v81, v82
	v_cvt_pk_bf16_f32 v82, v88, v86
	v_cvt_pk_bf16_f32 v83, v87, v83
	global_store_dwordx4 v[84:85], v[80:83], off offset:256
.LBB0_1380:
	s_or_b64 exec, exec, s[22:23]
	s_nop 0
	v_or_b32_e32 v80, 48, v140
	v_ashrrev_i32_e32 v81, 31, v80
	v_lshlrev_b64 v[80:81], 11, v[80:81]
	v_lshl_add_u64 v[80:81], s[10:11], 0, v[80:81]
	s_and_saveexec_b64 s[22:23], vcc
	s_cbranch_execz .LBB0_1382
	v_mul_f32_e32 v72, 0xbfb8aa3b, v72
	v_exp_f32_e32 v72, v72
	v_mul_f32_e32 v77, 0xbfb8aa3b, v77
	v_exp_f32_e32 v77, v77
	v_mul_f32_e32 v73, 0xbfb8aa3b, v73
	v_add_f32_e32 v72, 1.0, v72
	v_exp_f32_e32 v73, v73
	v_rcp_f32_e32 v82, v72
	v_add_f32_e32 v72, 1.0, v77
	v_mul_f32_e32 v77, 0xbfb8aa3b, v78
	v_exp_f32_e32 v77, v77
	v_add_f32_e32 v73, 1.0, v73
	v_mul_f32_e32 v74, 0xbfb8aa3b, v74
	v_mul_f32_e32 v76, 0xbfb8aa3b, v76
	v_exp_f32_e32 v74, v74
	v_rcp_f32_e32 v78, v73
	v_add_f32_e32 v73, 1.0, v77
	v_mul_f32_e32 v77, 0xbfb8aa3b, v79
	v_mul_f32_e32 v75, 0xbfb8aa3b, v75
	v_exp_f32_e32 v76, v76
	v_exp_f32_e32 v77, v77
	v_exp_f32_e32 v75, v75
	v_add_f32_e32 v74, 1.0, v74
	v_add_f32_e32 v76, 1.0, v76
	v_rcp_f32_e32 v79, v74
	v_add_f32_e32 v74, 1.0, v77
	v_add_f32_e32 v75, 1.0, v75
	v_rcp_f32_e32 v76, v76
	v_rcp_f32_e32 v72, v72
	v_rcp_f32_e32 v73, v73
	v_rcp_f32_e32 v74, v74
	v_rcp_f32_e32 v75, v75
	v_cvt_pk_bf16_f32 v72, v76, v72
	v_lshl_add_u64 v[76:77], v[138:139], 1, v[80:81]
	v_cvt_pk_bf16_f32 v73, v73, v74
	v_cvt_pk_bf16_f32 v74, v82, v78
	v_cvt_pk_bf16_f32 v75, v79, v75
	global_store_dwordx4 v[76:77], v[72:75], off
.LBB0_1382:
	s_or_b64 exec, exec, s[22:23]
	s_and_saveexec_b64 s[22:23], s[6:7]
	s_cbranch_execz .LBB0_1384
	v_mul_f32_e32 v64, 0xbfb8aa3b, v64
	v_exp_f32_e32 v64, v64
	v_mul_f32_e32 v69, 0xbfb8aa3b, v69
	v_exp_f32_e32 v69, v69
	v_mul_f32_e32 v65, 0xbfb8aa3b, v65
	v_add_f32_e32 v64, 1.0, v64
	v_exp_f32_e32 v65, v65
	v_rcp_f32_e32 v72, v64
	v_add_f32_e32 v64, 1.0, v69
	v_mul_f32_e32 v69, 0xbfb8aa3b, v70
	v_exp_f32_e32 v69, v69
	v_add_f32_e32 v65, 1.0, v65
	v_mul_f32_e32 v66, 0xbfb8aa3b, v66
	v_mul_f32_e32 v68, 0xbfb8aa3b, v68
	v_exp_f32_e32 v66, v66
	v_rcp_f32_e32 v70, v65
	v_add_f32_e32 v65, 1.0, v69
	v_mul_f32_e32 v69, 0xbfb8aa3b, v71
	v_mul_f32_e32 v67, 0xbfb8aa3b, v67
	v_exp_f32_e32 v68, v68
	v_exp_f32_e32 v69, v69
	v_exp_f32_e32 v67, v67
	v_add_f32_e32 v66, 1.0, v66
	v_add_f32_e32 v68, 1.0, v68
	v_rcp_f32_e32 v71, v66
	v_add_f32_e32 v66, 1.0, v69
	v_add_f32_e32 v67, 1.0, v67
	v_rcp_f32_e32 v68, v68
	v_rcp_f32_e32 v64, v64
	v_rcp_f32_e32 v65, v65
	v_rcp_f32_e32 v66, v66
	v_rcp_f32_e32 v67, v67
	v_cvt_pk_bf16_f32 v64, v68, v64
	v_lshl_add_u64 v[68:69], v[138:139], 1, v[80:81]
	v_cvt_pk_bf16_f32 v65, v65, v66
	v_cvt_pk_bf16_f32 v66, v72, v70
	v_cvt_pk_bf16_f32 v67, v71, v67
	global_store_dwordx4 v[68:69], v[64:67], off offset:256
.LBB0_1384:
	s_or_b64 exec, exec, s[22:23]
	s_nop 0
	v_add_u32_e32 v64, 0x80, v140
	v_ashrrev_i32_e32 v65, 31, v64
	v_lshlrev_b64 v[64:65], 11, v[64:65]
	v_lshl_add_u64 v[64:65], s[10:11], 0, v[64:65]
	s_and_saveexec_b64 s[22:23], vcc
	s_cbranch_execz .LBB0_1386
	v_mul_f32_e32 v56, 0xbfb8aa3b, v56
	v_exp_f32_e32 v56, v56
	v_mul_f32_e32 v61, 0xbfb8aa3b, v61
	v_exp_f32_e32 v61, v61
	v_mul_f32_e32 v57, 0xbfb8aa3b, v57
	v_add_f32_e32 v56, 1.0, v56
	v_exp_f32_e32 v57, v57
	v_rcp_f32_e32 v66, v56
	v_add_f32_e32 v56, 1.0, v61
	v_mul_f32_e32 v61, 0xbfb8aa3b, v62
	v_exp_f32_e32 v61, v61
	v_add_f32_e32 v57, 1.0, v57
	v_mul_f32_e32 v58, 0xbfb8aa3b, v58
	v_mul_f32_e32 v60, 0xbfb8aa3b, v60
	v_exp_f32_e32 v58, v58
	v_rcp_f32_e32 v62, v57
	v_add_f32_e32 v57, 1.0, v61
	v_mul_f32_e32 v61, 0xbfb8aa3b, v63
	v_mul_f32_e32 v59, 0xbfb8aa3b, v59
	v_exp_f32_e32 v60, v60
	v_exp_f32_e32 v61, v61
	v_exp_f32_e32 v59, v59
	v_add_f32_e32 v58, 1.0, v58
	v_add_f32_e32 v60, 1.0, v60
	v_rcp_f32_e32 v63, v58
	v_add_f32_e32 v58, 1.0, v61
	v_add_f32_e32 v59, 1.0, v59
	v_rcp_f32_e32 v60, v60
	v_rcp_f32_e32 v56, v56
	v_rcp_f32_e32 v57, v57
	v_rcp_f32_e32 v58, v58
	v_rcp_f32_e32 v59, v59
	v_cvt_pk_bf16_f32 v56, v60, v56
	v_lshl_add_u64 v[60:61], v[138:139], 1, v[64:65]
	v_cvt_pk_bf16_f32 v57, v57, v58
	v_cvt_pk_bf16_f32 v58, v66, v62
	v_cvt_pk_bf16_f32 v59, v63, v59
	global_store_dwordx4 v[60:61], v[56:59], off
.LBB0_1386:
	s_or_b64 exec, exec, s[22:23]
	s_and_saveexec_b64 s[22:23], s[6:7]
	s_cbranch_execz .LBB0_1388
	v_mul_f32_e32 v48, 0xbfb8aa3b, v48
	v_exp_f32_e32 v48, v48
	v_mul_f32_e32 v53, 0xbfb8aa3b, v53
	v_exp_f32_e32 v53, v53
	v_mul_f32_e32 v49, 0xbfb8aa3b, v49
	v_add_f32_e32 v48, 1.0, v48
	v_exp_f32_e32 v49, v49
	v_rcp_f32_e32 v56, v48
	v_add_f32_e32 v48, 1.0, v53
	v_mul_f32_e32 v53, 0xbfb8aa3b, v54
	v_exp_f32_e32 v53, v53
	v_add_f32_e32 v49, 1.0, v49
	v_mul_f32_e32 v50, 0xbfb8aa3b, v50
	v_mul_f32_e32 v52, 0xbfb8aa3b, v52
	v_exp_f32_e32 v50, v50
	v_rcp_f32_e32 v54, v49
	v_add_f32_e32 v49, 1.0, v53
	v_mul_f32_e32 v53, 0xbfb8aa3b, v55
	v_mul_f32_e32 v51, 0xbfb8aa3b, v51
	v_exp_f32_e32 v52, v52
	v_exp_f32_e32 v53, v53
	v_exp_f32_e32 v51, v51
	v_add_f32_e32 v50, 1.0, v50
	v_add_f32_e32 v52, 1.0, v52
	v_rcp_f32_e32 v55, v50
	v_add_f32_e32 v50, 1.0, v53
	v_add_f32_e32 v51, 1.0, v51
	v_rcp_f32_e32 v52, v52
	v_rcp_f32_e32 v48, v48
	v_rcp_f32_e32 v49, v49
	v_rcp_f32_e32 v50, v50
	v_rcp_f32_e32 v51, v51
	v_cvt_pk_bf16_f32 v48, v52, v48
	v_lshl_add_u64 v[52:53], v[138:139], 1, v[64:65]
	v_cvt_pk_bf16_f32 v49, v49, v50
	v_cvt_pk_bf16_f32 v50, v56, v54
	v_cvt_pk_bf16_f32 v51, v55, v51
	global_store_dwordx4 v[52:53], v[48:51], off offset:256
.LBB0_1388:
	s_or_b64 exec, exec, s[22:23]
	s_nop 0
	v_add_u32_e32 v48, 0x90, v140
	v_ashrrev_i32_e32 v49, 31, v48
	v_lshlrev_b64 v[48:49], 11, v[48:49]
	v_lshl_add_u64 v[48:49], s[10:11], 0, v[48:49]
	s_and_saveexec_b64 s[22:23], vcc
	s_cbranch_execz .LBB0_1390
	v_mul_f32_e32 v40, 0xbfb8aa3b, v40
	v_exp_f32_e32 v40, v40
	v_mul_f32_e32 v45, 0xbfb8aa3b, v45
	v_exp_f32_e32 v45, v45
	v_mul_f32_e32 v41, 0xbfb8aa3b, v41
	v_add_f32_e32 v40, 1.0, v40
	v_exp_f32_e32 v41, v41
	v_rcp_f32_e32 v50, v40
	v_add_f32_e32 v40, 1.0, v45
	v_mul_f32_e32 v45, 0xbfb8aa3b, v46
	v_exp_f32_e32 v45, v45
	v_add_f32_e32 v41, 1.0, v41
	v_mul_f32_e32 v42, 0xbfb8aa3b, v42
	v_mul_f32_e32 v44, 0xbfb8aa3b, v44
	v_exp_f32_e32 v42, v42
	v_rcp_f32_e32 v46, v41
	v_add_f32_e32 v41, 1.0, v45
	v_mul_f32_e32 v45, 0xbfb8aa3b, v47
	v_mul_f32_e32 v43, 0xbfb8aa3b, v43
	v_exp_f32_e32 v44, v44
	v_exp_f32_e32 v45, v45
	v_exp_f32_e32 v43, v43
	v_add_f32_e32 v42, 1.0, v42
	v_add_f32_e32 v44, 1.0, v44
	v_rcp_f32_e32 v47, v42
	v_add_f32_e32 v42, 1.0, v45
	v_add_f32_e32 v43, 1.0, v43
	v_rcp_f32_e32 v44, v44
	v_rcp_f32_e32 v40, v40
	v_rcp_f32_e32 v41, v41
	v_rcp_f32_e32 v42, v42
	v_rcp_f32_e32 v43, v43
	v_cvt_pk_bf16_f32 v40, v44, v40
	v_lshl_add_u64 v[44:45], v[138:139], 1, v[48:49]
	v_cvt_pk_bf16_f32 v41, v41, v42
	v_cvt_pk_bf16_f32 v42, v50, v46
	v_cvt_pk_bf16_f32 v43, v47, v43
	global_store_dwordx4 v[44:45], v[40:43], off
.LBB0_1390:
	s_or_b64 exec, exec, s[22:23]
	s_and_saveexec_b64 s[22:23], s[6:7]
	s_cbranch_execz .LBB0_1392
	v_mul_f32_e32 v32, 0xbfb8aa3b, v32
	v_exp_f32_e32 v32, v32
	v_mul_f32_e32 v37, 0xbfb8aa3b, v37
	v_exp_f32_e32 v37, v37
	v_mul_f32_e32 v33, 0xbfb8aa3b, v33
	v_add_f32_e32 v32, 1.0, v32
	v_exp_f32_e32 v33, v33
	v_rcp_f32_e32 v40, v32
	v_add_f32_e32 v32, 1.0, v37
	v_mul_f32_e32 v37, 0xbfb8aa3b, v38
	v_exp_f32_e32 v37, v37
	v_add_f32_e32 v33, 1.0, v33
	v_mul_f32_e32 v34, 0xbfb8aa3b, v34
	v_mul_f32_e32 v36, 0xbfb8aa3b, v36
	v_exp_f32_e32 v34, v34
	v_rcp_f32_e32 v38, v33
	v_add_f32_e32 v33, 1.0, v37
	v_mul_f32_e32 v37, 0xbfb8aa3b, v39
	v_mul_f32_e32 v35, 0xbfb8aa3b, v35
	v_exp_f32_e32 v36, v36
	v_exp_f32_e32 v37, v37
	v_exp_f32_e32 v35, v35
	v_add_f32_e32 v34, 1.0, v34
	v_add_f32_e32 v36, 1.0, v36
	v_rcp_f32_e32 v39, v34
	v_add_f32_e32 v34, 1.0, v37
	v_add_f32_e32 v35, 1.0, v35
	v_rcp_f32_e32 v36, v36
	v_rcp_f32_e32 v32, v32
	v_rcp_f32_e32 v33, v33
	v_rcp_f32_e32 v34, v34
	v_rcp_f32_e32 v35, v35
	v_cvt_pk_bf16_f32 v32, v36, v32
	v_lshl_add_u64 v[36:37], v[138:139], 1, v[48:49]
	v_cvt_pk_bf16_f32 v33, v33, v34
	v_cvt_pk_bf16_f32 v34, v40, v38
	v_cvt_pk_bf16_f32 v35, v39, v35
	global_store_dwordx4 v[36:37], v[32:35], off offset:256
.LBB0_1392:
	s_or_b64 exec, exec, s[22:23]
	s_nop 0
	v_add_u32_e32 v32, 0xa0, v140
	v_ashrrev_i32_e32 v33, 31, v32
	v_lshlrev_b64 v[32:33], 11, v[32:33]
	v_lshl_add_u64 v[32:33], s[10:11], 0, v[32:33]
	s_and_saveexec_b64 s[22:23], vcc
	s_cbranch_execz .LBB0_1394
	v_mul_f32_e32 v24, 0xbfb8aa3b, v24
	v_exp_f32_e32 v24, v24
	v_mul_f32_e32 v29, 0xbfb8aa3b, v29
	v_exp_f32_e32 v29, v29
	v_mul_f32_e32 v25, 0xbfb8aa3b, v25
	v_add_f32_e32 v24, 1.0, v24
	v_exp_f32_e32 v25, v25
	v_rcp_f32_e32 v34, v24
	v_add_f32_e32 v24, 1.0, v29
	v_mul_f32_e32 v29, 0xbfb8aa3b, v30
	v_exp_f32_e32 v29, v29
	v_add_f32_e32 v25, 1.0, v25
	v_mul_f32_e32 v26, 0xbfb8aa3b, v26
	v_mul_f32_e32 v28, 0xbfb8aa3b, v28
	v_exp_f32_e32 v26, v26
	v_rcp_f32_e32 v30, v25
	v_add_f32_e32 v25, 1.0, v29
	v_mul_f32_e32 v29, 0xbfb8aa3b, v31
	v_mul_f32_e32 v27, 0xbfb8aa3b, v27
	v_exp_f32_e32 v28, v28
	v_exp_f32_e32 v29, v29
	v_exp_f32_e32 v27, v27
	v_add_f32_e32 v26, 1.0, v26
	v_add_f32_e32 v28, 1.0, v28
	v_rcp_f32_e32 v31, v26
	v_add_f32_e32 v26, 1.0, v29
	v_add_f32_e32 v27, 1.0, v27
	v_rcp_f32_e32 v28, v28
	v_rcp_f32_e32 v24, v24
	v_rcp_f32_e32 v25, v25
	v_rcp_f32_e32 v26, v26
	v_rcp_f32_e32 v27, v27
	v_cvt_pk_bf16_f32 v24, v28, v24
	v_lshl_add_u64 v[28:29], v[138:139], 1, v[32:33]
	v_cvt_pk_bf16_f32 v25, v25, v26
	v_cvt_pk_bf16_f32 v26, v34, v30
	v_cvt_pk_bf16_f32 v27, v31, v27
	global_store_dwordx4 v[28:29], v[24:27], off
.LBB0_1394:
	s_or_b64 exec, exec, s[22:23]
	s_and_saveexec_b64 s[22:23], s[6:7]
	s_cbranch_execz .LBB0_1396
	v_mul_f32_e32 v16, 0xbfb8aa3b, v16
	v_exp_f32_e32 v16, v16
	v_mul_f32_e32 v21, 0xbfb8aa3b, v21
	v_exp_f32_e32 v21, v21
	v_mul_f32_e32 v17, 0xbfb8aa3b, v17
	v_add_f32_e32 v16, 1.0, v16
	v_exp_f32_e32 v17, v17
	v_rcp_f32_e32 v24, v16
	v_add_f32_e32 v16, 1.0, v21
	v_mul_f32_e32 v21, 0xbfb8aa3b, v22
	v_exp_f32_e32 v21, v21
	v_add_f32_e32 v17, 1.0, v17
	v_mul_f32_e32 v18, 0xbfb8aa3b, v18
	v_mul_f32_e32 v20, 0xbfb8aa3b, v20
	v_exp_f32_e32 v18, v18
	v_rcp_f32_e32 v22, v17
	v_add_f32_e32 v17, 1.0, v21
	v_mul_f32_e32 v21, 0xbfb8aa3b, v23
	v_mul_f32_e32 v19, 0xbfb8aa3b, v19
	v_exp_f32_e32 v20, v20
	v_exp_f32_e32 v21, v21
	v_exp_f32_e32 v19, v19
	v_add_f32_e32 v18, 1.0, v18
	v_add_f32_e32 v20, 1.0, v20
	v_rcp_f32_e32 v23, v18
	v_add_f32_e32 v18, 1.0, v21
	v_add_f32_e32 v19, 1.0, v19
	v_rcp_f32_e32 v20, v20
	v_rcp_f32_e32 v16, v16
	v_rcp_f32_e32 v17, v17
	v_rcp_f32_e32 v18, v18
	v_rcp_f32_e32 v19, v19
	v_cvt_pk_bf16_f32 v16, v20, v16
	v_lshl_add_u64 v[20:21], v[138:139], 1, v[32:33]
	v_cvt_pk_bf16_f32 v17, v17, v18
	v_cvt_pk_bf16_f32 v18, v24, v22
	v_cvt_pk_bf16_f32 v19, v23, v19
	global_store_dwordx4 v[20:21], v[16:19], off offset:256
.LBB0_1396:
	s_or_b64 exec, exec, s[22:23]
	s_nop 0
	v_add_u32_e32 v16, 0xb0, v140
	v_ashrrev_i32_e32 v17, 31, v16
	v_lshlrev_b64 v[16:17], 11, v[16:17]
	v_lshl_add_u64 v[16:17], s[10:11], 0, v[16:17]
	s_and_saveexec_b64 s[22:23], vcc
	s_cbranch_execz .LBB0_1398
	v_mul_f32_e32 v8, 0xbfb8aa3b, v8
	v_exp_f32_e32 v8, v8
	v_mul_f32_e32 v13, 0xbfb8aa3b, v13
	v_exp_f32_e32 v13, v13
	v_mul_f32_e32 v9, 0xbfb8aa3b, v9
	v_add_f32_e32 v8, 1.0, v8
	v_exp_f32_e32 v9, v9
	v_rcp_f32_e32 v18, v8
	v_add_f32_e32 v8, 1.0, v13
	v_mul_f32_e32 v13, 0xbfb8aa3b, v14
	v_exp_f32_e32 v13, v13
	v_add_f32_e32 v9, 1.0, v9
	v_mul_f32_e32 v10, 0xbfb8aa3b, v10
	v_mul_f32_e32 v12, 0xbfb8aa3b, v12
	v_exp_f32_e32 v10, v10
	v_rcp_f32_e32 v14, v9
	v_add_f32_e32 v9, 1.0, v13
	v_mul_f32_e32 v13, 0xbfb8aa3b, v15
	v_mul_f32_e32 v11, 0xbfb8aa3b, v11
	v_exp_f32_e32 v12, v12
	v_exp_f32_e32 v13, v13
	v_exp_f32_e32 v11, v11
	v_add_f32_e32 v10, 1.0, v10
	v_add_f32_e32 v12, 1.0, v12
	v_rcp_f32_e32 v15, v10
	v_add_f32_e32 v10, 1.0, v13
	v_add_f32_e32 v11, 1.0, v11
	v_rcp_f32_e32 v12, v12
	v_rcp_f32_e32 v8, v8
	v_rcp_f32_e32 v9, v9
	v_rcp_f32_e32 v10, v10
	v_rcp_f32_e32 v11, v11
	v_cvt_pk_bf16_f32 v8, v12, v8
	v_lshl_add_u64 v[12:13], v[138:139], 1, v[16:17]
	v_cvt_pk_bf16_f32 v9, v9, v10
	v_cvt_pk_bf16_f32 v10, v18, v14
	v_cvt_pk_bf16_f32 v11, v15, v11
	global_store_dwordx4 v[12:13], v[8:11], off
.LBB0_1398:
	s_or_b64 exec, exec, s[22:23]
	s_and_saveexec_b64 s[22:23], s[6:7]
	s_cbranch_execz .LBB0_1400
	v_mul_f32_e32 v0, 0xbfb8aa3b, v0
	v_exp_f32_e32 v0, v0
	v_mul_f32_e32 v5, 0xbfb8aa3b, v5
	v_exp_f32_e32 v5, v5
	v_mul_f32_e32 v1, 0xbfb8aa3b, v1
	v_add_f32_e32 v0, 1.0, v0
	v_exp_f32_e32 v1, v1
	v_rcp_f32_e32 v8, v0
	v_add_f32_e32 v0, 1.0, v5
	v_mul_f32_e32 v5, 0xbfb8aa3b, v6
	v_exp_f32_e32 v5, v5
	v_add_f32_e32 v1, 1.0, v1
	v_mul_f32_e32 v2, 0xbfb8aa3b, v2
	v_mul_f32_e32 v4, 0xbfb8aa3b, v4
	v_exp_f32_e32 v2, v2
	v_rcp_f32_e32 v6, v1
	v_add_f32_e32 v1, 1.0, v5
	v_mul_f32_e32 v5, 0xbfb8aa3b, v7
	v_mul_f32_e32 v3, 0xbfb8aa3b, v3
	v_exp_f32_e32 v4, v4
	v_exp_f32_e32 v5, v5
	v_exp_f32_e32 v3, v3
	v_add_f32_e32 v2, 1.0, v2
	v_add_f32_e32 v4, 1.0, v4
	v_rcp_f32_e32 v7, v2
	v_add_f32_e32 v2, 1.0, v5
	v_add_f32_e32 v3, 1.0, v3
	v_rcp_f32_e32 v4, v4
	v_rcp_f32_e32 v0, v0
	v_rcp_f32_e32 v1, v1
	v_rcp_f32_e32 v2, v2
	v_rcp_f32_e32 v3, v3
	v_cvt_pk_bf16_f32 v0, v4, v0
	v_lshl_add_u64 v[4:5], v[138:139], 1, v[16:17]
	v_cvt_pk_bf16_f32 v1, v1, v2
	v_cvt_pk_bf16_f32 v2, v8, v6
	v_cvt_pk_bf16_f32 v3, v7, v3
	global_store_dwordx4 v[4:5], v[0:3], off offset:256

.LBB0_1422:
	s_lshl_b32 s15, s22, 8
	v_mbcnt_lo_u32_b32 v104, -1, 0
	v_mbcnt_hi_u32_b32 v104, -1, v104
	s_add_i32 s15, s15, s44
	v_and_or_b32 v154, v104, 15, s15
	s_lshl_b32 s15, s23, 8
	v_ashrrev_i32_e32 v104, 1, v104
	v_and_b32_e32 v104, -8, v104
	s_or_b32 s15, s15, s45
	v_add_u32_e32 v104, s15, v104
	v_ashrrev_i32_e32 v155, 31, v154
	v_ashrrev_i32_e32 v105, 31, v104
	v_lshlrev_b64 v[106:107], 11, v[154:155]
	v_lshl_add_u64 v[106:107], s[8:9], 0, v[106:107]
	v_lshlrev_b64 v[156:157], 1, v[104:105]
	v_lshl_add_u64 v[178:179], v[106:107], 0, v[156:157]
	global_load_dwordx4 v[166:169], v[178:179], off
	global_load_dwordx4 v[170:173], v[178:179], off offset:256
	v_or_b32_e32 v104, 16, v154
	v_ashrrev_i32_e32 v105, 31, v104
	v_lshlrev_b64 v[104:105], 11, v[104:105]
	v_lshl_add_u64 v[104:105], s[8:9], 0, v[104:105]
	v_lshl_add_u64 v[162:163], v[104:105], 0, v[156:157]
	global_load_dwordx4 v[174:177], v[162:163], off
	global_load_dwordx4 v[124:127], v[162:163], off offset:256
	v_or_b32_e32 v104, 32, v154
	v_ashrrev_i32_e32 v105, 31, v104
	v_lshlrev_b64 v[104:105], 11, v[104:105]
	v_lshl_add_u64 v[104:105], s[8:9], 0, v[104:105]
	v_lshl_add_u64 v[160:161], v[104:105], 0, v[156:157]
	global_load_dwordx4 v[116:119], v[160:161], off
	global_load_dwordx4 v[112:115], v[160:161], off offset:256
	v_or_b32_e32 v104, 48, v154
	v_ashrrev_i32_e32 v105, 31, v104
	v_lshlrev_b64 v[104:105], 11, v[104:105]
	v_lshl_add_u64 v[104:105], s[8:9], 0, v[104:105]
	v_lshl_add_u64 v[158:159], v[104:105], 0, v[156:157]
	global_load_dwordx4 v[108:111], v[158:159], off
	global_load_dwordx4 v[104:107], v[158:159], off offset:256
	s_mov_b64 s[22:23], -1
	s_andn2_b64 vcc, exec, s[4:5]
	v_mov_b32_e32 v243, v250
	v_mov_b64_e32 v[230:231], v[246:247]
	s_waitcnt vmcnt(0) lgkmcnt(0)
	v_lshlrev_b32_e32 v180, 16, v166
	v_and_b32_e32 v181, 0xffff0000, v166
	v_lshlrev_b32_e32 v166, 16, v167
	v_and_b32_e32 v167, 0xffff0000, v167
	v_pk_mul_f32 v[146:147], v[146:147], v[166:167]
	v_lshlrev_b32_e32 v166, 16, v168
	v_and_b32_e32 v167, 0xffff0000, v168
	v_pk_mul_f32 v[166:167], v[140:141], v[166:167]
	v_lshlrev_b32_e32 v140, 16, v169
	v_and_b32_e32 v141, 0xffff0000, v169
	v_pk_mul_f32 v[144:145], v[144:145], v[180:181]
	v_pk_mul_f32 v[168:169], v[142:143], v[140:141]
	v_cvt_pk_bf16_f32 v140, v144, v145
	v_cvt_pk_bf16_f32 v141, v146, v147
	v_cvt_pk_bf16_f32 v142, v166, v167
	v_cvt_pk_bf16_f32 v143, v168, v169
	global_store_dwordx4 v[178:179], v[140:143], off
	s_nop 1
	v_lshlrev_b32_e32 v140, 16, v170
	v_and_b32_e32 v141, 0xffff0000, v170
	v_pk_mul_f32 v[136:137], v[136:137], v[140:141]
	v_lshlrev_b32_e32 v140, 16, v171
	v_and_b32_e32 v141, 0xffff0000, v171
	v_pk_mul_f32 v[138:139], v[138:139], v[140:141]
	v_lshlrev_b32_e32 v140, 16, v172
	v_and_b32_e32 v141, 0xffff0000, v172
	v_pk_mul_f32 v[140:141], v[132:133], v[140:141]
	v_lshlrev_b32_e32 v132, 16, v173
	v_and_b32_e32 v133, 0xffff0000, v173
	v_pk_mul_f32 v[142:143], v[134:135], v[132:133]
	v_cvt_pk_bf16_f32 v132, v136, v137
	v_cvt_pk_bf16_f32 v133, v138, v139
	v_cvt_pk_bf16_f32 v134, v140, v141
	v_cvt_pk_bf16_f32 v135, v142, v143
	global_store_dwordx4 v[178:179], v[132:135], off offset:256
	s_nop 1
	v_lshlrev_b32_e32 v132, 16, v174
	v_and_b32_e32 v133, 0xffff0000, v174
	v_pk_mul_f32 v[128:129], v[128:129], v[132:133]
	v_lshlrev_b32_e32 v132, 16, v175
	v_and_b32_e32 v133, 0xffff0000, v175
	v_pk_mul_f32 v[130:131], v[130:131], v[132:133]
	v_lshlrev_b32_e32 v132, 16, v176
	v_and_b32_e32 v133, 0xffff0000, v176
	v_pk_mul_f32 v[132:133], v[120:121], v[132:133]
	v_lshlrev_b32_e32 v120, 16, v177
	v_and_b32_e32 v121, 0xffff0000, v177
	v_pk_mul_f32 v[134:135], v[122:123], v[120:121]
	v_cvt_pk_bf16_f32 v120, v128, v129
	v_cvt_pk_bf16_f32 v121, v130, v131
	v_cvt_pk_bf16_f32 v122, v132, v133
	v_cvt_pk_bf16_f32 v123, v134, v135
	global_store_dwordx4 v[162:163], v[120:123], off
	s_nop 1
	v_lshlrev_b32_e32 v120, 16, v124
	v_and_b32_e32 v121, 0xffff0000, v124
	v_pk_mul_f32 v[100:101], v[100:101], v[120:121]
	v_lshlrev_b32_e32 v120, 16, v125
	v_and_b32_e32 v121, 0xffff0000, v125
	v_pk_mul_f32 v[102:103], v[102:103], v[120:121]
	v_lshlrev_b32_e32 v120, 16, v126
	v_and_b32_e32 v121, 0xffff0000, v126
	v_pk_mul_f32 v[120:121], v[96:97], v[120:121]
	v_lshlrev_b32_e32 v96, 16, v127
	v_and_b32_e32 v97, 0xffff0000, v127
	v_pk_mul_f32 v[122:123], v[98:99], v[96:97]
	v_cvt_pk_bf16_f32 v96, v100, v101
	v_cvt_pk_bf16_f32 v97, v102, v103
	v_cvt_pk_bf16_f32 v98, v120, v121
	v_cvt_pk_bf16_f32 v99, v122, v123
	global_store_dwordx4 v[162:163], v[96:99], off offset:256
	s_nop 1
	v_lshlrev_b32_e32 v96, 16, v116
	v_and_b32_e32 v97, 0xffff0000, v116
	v_pk_mul_f32 v[92:93], v[92:93], v[96:97]
	v_lshlrev_b32_e32 v96, 16, v117
	v_and_b32_e32 v97, 0xffff0000, v117
	v_pk_mul_f32 v[94:95], v[94:95], v[96:97]
	v_lshlrev_b32_e32 v96, 16, v118
	v_and_b32_e32 v97, 0xffff0000, v118
	v_pk_mul_f32 v[96:97], v[88:89], v[96:97]
	v_lshlrev_b32_e32 v88, 16, v119
	v_and_b32_e32 v89, 0xffff0000, v119
	v_pk_mul_f32 v[98:99], v[90:91], v[88:89]
	v_cvt_pk_bf16_f32 v88, v92, v93
	v_cvt_pk_bf16_f32 v89, v94, v95
	v_cvt_pk_bf16_f32 v90, v96, v97
	v_cvt_pk_bf16_f32 v91, v98, v99
	global_store_dwordx4 v[160:161], v[88:91], off
	s_nop 1
	v_lshlrev_b32_e32 v88, 16, v112
	v_and_b32_e32 v89, 0xffff0000, v112
	v_pk_mul_f32 v[84:85], v[84:85], v[88:89]
	v_lshlrev_b32_e32 v88, 16, v113
	v_and_b32_e32 v89, 0xffff0000, v113
	v_pk_mul_f32 v[86:87], v[86:87], v[88:89]
	v_lshlrev_b32_e32 v88, 16, v114
	v_and_b32_e32 v89, 0xffff0000, v114
	v_pk_mul_f32 v[88:89], v[80:81], v[88:89]
	v_lshlrev_b32_e32 v80, 16, v115
	v_and_b32_e32 v81, 0xffff0000, v115
	v_pk_mul_f32 v[90:91], v[82:83], v[80:81]
	v_cvt_pk_bf16_f32 v80, v84, v85
	v_cvt_pk_bf16_f32 v81, v86, v87
	v_cvt_pk_bf16_f32 v82, v88, v89
	v_cvt_pk_bf16_f32 v83, v90, v91
	global_store_dwordx4 v[160:161], v[80:83], off offset:256
	s_nop 1
	v_lshlrev_b32_e32 v80, 16, v108
	v_and_b32_e32 v81, 0xffff0000, v108
	v_pk_mul_f32 v[76:77], v[76:77], v[80:81]
	v_lshlrev_b32_e32 v80, 16, v109
	v_and_b32_e32 v81, 0xffff0000, v109
	v_pk_mul_f32 v[78:79], v[78:79], v[80:81]
	v_lshlrev_b32_e32 v80, 16, v110
	v_and_b32_e32 v81, 0xffff0000, v110
	v_pk_mul_f32 v[80:81], v[72:73], v[80:81]
	v_lshlrev_b32_e32 v72, 16, v111
	v_and_b32_e32 v73, 0xffff0000, v111
	v_pk_mul_f32 v[82:83], v[74:75], v[72:73]
	v_cvt_pk_bf16_f32 v72, v76, v77
	v_cvt_pk_bf16_f32 v73, v78, v79
	v_cvt_pk_bf16_f32 v74, v80, v81
	v_cvt_pk_bf16_f32 v75, v82, v83
	global_store_dwordx4 v[158:159], v[72:75], off
	s_nop 1
	v_lshlrev_b32_e32 v72, 16, v104
	v_and_b32_e32 v73, 0xffff0000, v104
	v_pk_mul_f32 v[68:69], v[68:69], v[72:73]
	v_lshlrev_b32_e32 v72, 16, v105
	v_and_b32_e32 v73, 0xffff0000, v105
	v_pk_mul_f32 v[70:71], v[70:71], v[72:73]
	v_lshlrev_b32_e32 v72, 16, v106
	v_and_b32_e32 v73, 0xffff0000, v106
	v_pk_mul_f32 v[72:73], v[64:65], v[72:73]
	v_lshlrev_b32_e32 v64, 16, v107
	v_and_b32_e32 v65, 0xffff0000, v107
	v_pk_mul_f32 v[74:75], v[66:67], v[64:65]
	v_cvt_pk_bf16_f32 v64, v68, v69
	v_cvt_pk_bf16_f32 v65, v70, v71
	v_cvt_pk_bf16_f32 v66, v72, v73
	v_cvt_pk_bf16_f32 v67, v74, v75
	global_store_dwordx4 v[158:159], v[64:67], off offset:256
	s_nop 1
	v_add_u32_e32 v64, 0x80, v154
	v_ashrrev_i32_e32 v65, 31, v64
	v_lshlrev_b64 v[64:65], 11, v[64:65]
	v_lshl_add_u64 v[64:65], s[8:9], 0, v[64:65]
	v_lshl_add_u64 v[98:99], v[64:65], 0, v[156:157]
	global_load_dwordx4 v[66:69], v[98:99], off
	global_load_dwordx4 v[70:73], v[98:99], off offset:256
	v_add_u32_e32 v64, 0x90, v154
	v_ashrrev_i32_e32 v65, 31, v64
	v_lshlrev_b64 v[64:65], 11, v[64:65]
	v_lshl_add_u64 v[64:65], s[8:9], 0, v[64:65]
	v_lshl_add_u64 v[100:101], v[64:65], 0, v[156:157]
	global_load_dwordx4 v[74:77], v[100:101], off
	global_load_dwordx4 v[78:81], v[100:101], off offset:256
	v_add_u32_e32 v64, 0xa0, v154
	v_ashrrev_i32_e32 v65, 31, v64
	v_lshlrev_b64 v[64:65], 11, v[64:65]
	v_lshl_add_u64 v[64:65], s[8:9], 0, v[64:65]
	v_lshl_add_u64 v[102:103], v[64:65], 0, v[156:157]
	global_load_dwordx4 v[82:85], v[102:103], off
	global_load_dwordx4 v[86:89], v[102:103], off offset:256
	v_add_u32_e32 v64, 0xb0, v154
	v_ashrrev_i32_e32 v65, 31, v64
	v_lshlrev_b64 v[64:65], 11, v[64:65]
	v_lshl_add_u64 v[64:65], s[8:9], 0, v[64:65]
	v_lshl_add_u64 v[64:65], v[64:65], 0, v[156:157]
	global_load_dwordx4 v[90:93], v[64:65], off
	global_load_dwordx4 v[94:97], v[64:65], off offset:256
	s_waitcnt vmcnt(0) lgkmcnt(0)
	v_lshlrev_b32_e32 v104, 16, v66
	v_and_b32_e32 v105, 0xffff0000, v66
	v_lshlrev_b32_e32 v66, 16, v67
	v_and_b32_e32 v67, 0xffff0000, v67
	v_pk_mul_f32 v[62:63], v[62:63], v[66:67]
	v_lshlrev_b32_e32 v66, 16, v68
	v_and_b32_e32 v67, 0xffff0000, v68
	v_pk_mul_f32 v[66:67], v[56:57], v[66:67]
	v_lshlrev_b32_e32 v56, 16, v69
	v_and_b32_e32 v57, 0xffff0000, v69
	v_pk_mul_f32 v[60:61], v[60:61], v[104:105]
	v_pk_mul_f32 v[68:69], v[58:59], v[56:57]
	v_cvt_pk_bf16_f32 v56, v60, v61
	v_cvt_pk_bf16_f32 v57, v62, v63
	v_cvt_pk_bf16_f32 v58, v66, v67
	v_cvt_pk_bf16_f32 v59, v68, v69
	global_store_dwordx4 v[98:99], v[56:59], off
	s_nop 1
	v_lshlrev_b32_e32 v56, 16, v70
	v_and_b32_e32 v57, 0xffff0000, v70
	v_pk_mul_f32 v[52:53], v[52:53], v[56:57]
	v_lshlrev_b32_e32 v56, 16, v71
	v_and_b32_e32 v57, 0xffff0000, v71
	v_pk_mul_f32 v[54:55], v[54:55], v[56:57]
	v_lshlrev_b32_e32 v56, 16, v72
	v_and_b32_e32 v57, 0xffff0000, v72
	v_pk_mul_f32 v[56:57], v[48:49], v[56:57]
	v_lshlrev_b32_e32 v48, 16, v73
	v_and_b32_e32 v49, 0xffff0000, v73
	v_pk_mul_f32 v[58:59], v[50:51], v[48:49]
	v_cvt_pk_bf16_f32 v48, v52, v53
	v_cvt_pk_bf16_f32 v49, v54, v55
	v_cvt_pk_bf16_f32 v50, v56, v57
	v_cvt_pk_bf16_f32 v51, v58, v59
	global_store_dwordx4 v[98:99], v[48:51], off offset:256
	s_nop 1
	v_lshlrev_b32_e32 v48, 16, v74
	v_and_b32_e32 v49, 0xffff0000, v74
	v_pk_mul_f32 v[44:45], v[44:45], v[48:49]
	v_lshlrev_b32_e32 v48, 16, v75
	v_and_b32_e32 v49, 0xffff0000, v75
	v_pk_mul_f32 v[46:47], v[46:47], v[48:49]
	v_lshlrev_b32_e32 v48, 16, v76
	v_and_b32_e32 v49, 0xffff0000, v76
	v_pk_mul_f32 v[48:49], v[40:41], v[48:49]
	v_lshlrev_b32_e32 v40, 16, v77
	v_and_b32_e32 v41, 0xffff0000, v77
	v_pk_mul_f32 v[50:51], v[42:43], v[40:41]
	v_cvt_pk_bf16_f32 v40, v44, v45
	v_cvt_pk_bf16_f32 v41, v46, v47
	v_cvt_pk_bf16_f32 v42, v48, v49
	v_cvt_pk_bf16_f32 v43, v50, v51
	global_store_dwordx4 v[100:101], v[40:43], off
	s_nop 1
	v_lshlrev_b32_e32 v40, 16, v78
	v_and_b32_e32 v41, 0xffff0000, v78
	v_pk_mul_f32 v[36:37], v[36:37], v[40:41]
	v_lshlrev_b32_e32 v40, 16, v79
	v_and_b32_e32 v41, 0xffff0000, v79
	v_pk_mul_f32 v[38:39], v[38:39], v[40:41]
	v_lshlrev_b32_e32 v40, 16, v80
	v_and_b32_e32 v41, 0xffff0000, v80
	v_pk_mul_f32 v[40:41], v[32:33], v[40:41]
	v_lshlrev_b32_e32 v32, 16, v81
	v_and_b32_e32 v33, 0xffff0000, v81
	v_pk_mul_f32 v[42:43], v[34:35], v[32:33]
	v_cvt_pk_bf16_f32 v32, v36, v37
	v_cvt_pk_bf16_f32 v33, v38, v39
	v_cvt_pk_bf16_f32 v34, v40, v41
	v_cvt_pk_bf16_f32 v35, v42, v43
	global_store_dwordx4 v[100:101], v[32:35], off offset:256
	s_nop 1
	v_lshlrev_b32_e32 v32, 16, v82
	v_and_b32_e32 v33, 0xffff0000, v82
	v_pk_mul_f32 v[28:29], v[28:29], v[32:33]
	v_lshlrev_b32_e32 v32, 16, v83
	v_and_b32_e32 v33, 0xffff0000, v83
	v_pk_mul_f32 v[30:31], v[30:31], v[32:33]
	v_lshlrev_b32_e32 v32, 16, v84
	v_and_b32_e32 v33, 0xffff0000, v84
	v_pk_mul_f32 v[32:33], v[24:25], v[32:33]
	v_lshlrev_b32_e32 v24, 16, v85
	v_and_b32_e32 v25, 0xffff0000, v85
	v_pk_mul_f32 v[34:35], v[26:27], v[24:25]
	v_cvt_pk_bf16_f32 v24, v28, v29
	v_cvt_pk_bf16_f32 v25, v30, v31
	v_cvt_pk_bf16_f32 v26, v32, v33
	v_cvt_pk_bf16_f32 v27, v34, v35
	global_store_dwordx4 v[102:103], v[24:27], off
	s_nop 1
	v_lshlrev_b32_e32 v24, 16, v86
	v_and_b32_e32 v25, 0xffff0000, v86
	v_pk_mul_f32 v[20:21], v[20:21], v[24:25]
	v_lshlrev_b32_e32 v24, 16, v87
	v_and_b32_e32 v25, 0xffff0000, v87
	v_pk_mul_f32 v[22:23], v[22:23], v[24:25]
	v_lshlrev_b32_e32 v24, 16, v88
	v_and_b32_e32 v25, 0xffff0000, v88
	v_pk_mul_f32 v[24:25], v[16:17], v[24:25]
	v_lshlrev_b32_e32 v16, 16, v89
	v_and_b32_e32 v17, 0xffff0000, v89
	v_pk_mul_f32 v[26:27], v[18:19], v[16:17]
	v_cvt_pk_bf16_f32 v16, v20, v21
	v_cvt_pk_bf16_f32 v17, v22, v23
	v_cvt_pk_bf16_f32 v18, v24, v25
	v_cvt_pk_bf16_f32 v19, v26, v27
	global_store_dwordx4 v[102:103], v[16:19], off offset:256
	s_nop 1
	v_lshlrev_b32_e32 v16, 16, v90
	v_and_b32_e32 v17, 0xffff0000, v90
	v_pk_mul_f32 v[12:13], v[12:13], v[16:17]
	v_lshlrev_b32_e32 v16, 16, v91
	v_and_b32_e32 v17, 0xffff0000, v91
	v_pk_mul_f32 v[14:15], v[14:15], v[16:17]
	v_lshlrev_b32_e32 v16, 16, v92
	v_and_b32_e32 v17, 0xffff0000, v92
	v_pk_mul_f32 v[16:17], v[8:9], v[16:17]
	v_lshlrev_b32_e32 v8, 16, v93
	v_and_b32_e32 v9, 0xffff0000, v93
	v_pk_mul_f32 v[18:19], v[10:11], v[8:9]
	v_cvt_pk_bf16_f32 v8, v12, v13
	v_cvt_pk_bf16_f32 v9, v14, v15
	v_cvt_pk_bf16_f32 v10, v16, v17
	v_cvt_pk_bf16_f32 v11, v18, v19
	global_store_dwordx4 v[64:65], v[8:11], off
	s_nop 1
	v_lshlrev_b32_e32 v8, 16, v94
	v_and_b32_e32 v9, 0xffff0000, v94
	v_pk_mul_f32 v[4:5], v[4:5], v[8:9]
	v_lshlrev_b32_e32 v8, 16, v95
	v_and_b32_e32 v9, 0xffff0000, v95
	v_pk_mul_f32 v[6:7], v[6:7], v[8:9]
	v_lshlrev_b32_e32 v8, 16, v96
	v_and_b32_e32 v9, 0xffff0000, v96
	v_pk_mul_f32 v[8:9], v[0:1], v[8:9]
	v_lshlrev_b32_e32 v0, 16, v97
	v_and_b32_e32 v1, 0xffff0000, v97
	v_pk_mul_f32 v[10:11], v[2:3], v[0:1]
	v_cvt_pk_bf16_f32 v0, v4, v5
	v_cvt_pk_bf16_f32 v1, v6, v7
	v_cvt_pk_bf16_f32 v2, v8, v9
	v_cvt_pk_bf16_f32 v3, v10, v11
	global_store_dwordx4 v[64:65], v[0:3], off offset:256
	s_cbranch_vccnz .LBB0_1413
	s_andn2_b64 vcc, exec, s[6:7]
	s_cbranch_vccnz .LBB0_1412
	s_barrier
	s_branch .LBB0_1412

.LBB0_1495:
	v_mbcnt_lo_u32_b32 v148, -1, 0
	v_mbcnt_hi_u32_b32 v148, -1, v148
	s_lshl_b32 s21, s29, 8
	v_ashrrev_i32_e32 v88, 1, v148
	v_and_b32_e32 v88, -8, v88
	s_or_b32 s21, s21, s51
	v_add_u32_e32 v144, s21, v88
	v_ashrrev_i32_e32 v145, 31, v144
	v_lshlrev_b64 v[206:207], 2, v[144:145]
	v_lshl_add_u64 v[92:93], s[14:15], 0, v[206:207]
	global_load_dwordx4 v[88:91], v[92:93], off
	s_mov_b32 s30, 0x3fb504f3
	v_lshl_add_u64 v[146:147], s[16:17], 0, v[206:207]
	s_lshl_b32 s21, s28, 8
	s_add_i32 s21, s21, s50
	v_and_or_b32 v208, v148, 15, s21
	v_ashrrev_i32_e32 v209, 31, v208
	v_lshlrev_b64 v[148:149], 11, v[208:209]
	v_lshl_add_u64 v[148:149], s[10:11], 0, v[148:149]
	v_lshlrev_b64 v[210:211], 1, v[144:145]
	v_lshl_add_u64 v[144:145], v[148:149], 0, v[210:211]
	s_mov_b64 s[28:29], -1
	s_andn2_b64 vcc, exec, s[4:5]
	s_waitcnt vmcnt(0) lgkmcnt(0)
	v_pk_mul_f32 v[202:203], v[90:91], s[30:31] op_sel_hi:[1,0]
	v_pk_mul_f32 v[204:205], v[88:89], s[30:31] op_sel_hi:[1,0]
	global_load_dwordx4 v[88:91], v[92:93], off offset:16
	s_waitcnt vmcnt(0) lgkmcnt(0)
	v_pk_mul_f32 v[198:199], v[90:91], s[30:31] op_sel_hi:[1,0]
	v_pk_mul_f32 v[200:201], v[88:89], s[30:31] op_sel_hi:[1,0]
	global_load_dwordx4 v[100:103], v[146:147], off
	global_load_dwordx4 v[96:99], v[146:147], off offset:16
	global_load_dwordx4 v[88:91], v[92:93], off offset:512
	s_waitcnt vmcnt(0) lgkmcnt(0)
	v_pk_mul_f32 v[194:195], v[90:91], s[30:31] op_sel_hi:[1,0]
	v_pk_mul_f32 v[196:197], v[88:89], s[30:31] op_sel_hi:[1,0]
	global_load_dwordx4 v[88:91], v[92:93], off offset:528
	s_waitcnt vmcnt(0) lgkmcnt(0)
	v_pk_mul_f32 v[190:191], v[90:91], s[30:31] op_sel_hi:[1,0]
	v_pk_mul_f32 v[192:193], v[88:89], s[30:31] op_sel_hi:[1,0]
	global_load_dwordx4 v[92:95], v[146:147], off offset:512
	global_load_dwordx4 v[88:91], v[146:147], off offset:528
	v_lshl_add_u64 v[146:147], v[208:209], 3, s[12:13]
	global_load_dwordx2 v[218:219], v[146:147], off
	v_lshlrev_b64 v[146:147], 12, v[208:209]
	v_lshl_add_u64 v[146:147], s[6:7], 0, v[146:147]
	v_lshl_add_u64 v[216:217], v[146:147], 0, v[206:207]
	global_load_dwordx4 v[222:225], v[216:217], off
	global_load_dwordx4 v[226:229], v[216:217], off offset:16
	global_load_dwordx4 v[234:237], v[144:145], off
	global_load_dwordx4 v[176:179], v[216:217], off offset:512
	global_load_dwordx4 v[172:175], v[216:217], off offset:528
	global_load_dwordx4 v[164:167], v[144:145], off offset:256
	v_or_b32_e32 v144, 16, v208
	v_ashrrev_i32_e32 v145, 31, v144
	v_lshl_add_u64 v[146:147], v[144:145], 3, s[12:13]
	global_load_dwordx2 v[214:215], v[146:147], off
	v_lshlrev_b64 v[146:147], 12, v[144:145]
	v_lshl_add_u64 v[146:147], s[6:7], 0, v[146:147]
	v_lshl_add_u64 v[212:213], v[146:147], 0, v[206:207]
	global_load_dwordx4 v[168:171], v[212:213], off
	global_load_dwordx4 v[160:163], v[212:213], off offset:16
	v_lshlrev_b64 v[144:145], 11, v[144:145]
	v_lshl_add_u64 v[144:145], s[10:11], 0, v[144:145]
	v_lshl_add_u64 v[144:145], v[144:145], 0, v[210:211]
	global_load_dwordx4 v[156:159], v[144:145], off
	global_load_dwordx4 v[152:155], v[212:213], off offset:512
	global_load_dwordx4 v[148:151], v[212:213], off offset:528
	s_nop 0
	global_load_dwordx4 v[144:147], v[144:145], off offset:256
	s_waitcnt vmcnt(0) lgkmcnt(0)
	v_sub_f32_e32 v225, v225, v218
	v_sub_f32_e32 v224, v224, v218
	v_sub_f32_e32 v223, v223, v218
	v_sub_f32_e32 v222, v222, v218
	v_pk_mul_f32 v[222:223], v[218:219], v[222:223] op_sel:[1,0]
	v_pk_mul_f32 v[224:225], v[218:219], v[224:225] op_sel:[1,0]
	v_pk_fma_f32 v[140:141], v[204:205], v[222:223], v[140:141]
	v_pk_fma_f32 v[142:143], v[202:203], v[224:225], v[142:143]
	v_sub_f32_e32 v223, v229, v218
	v_sub_f32_e32 v222, v228, v218
	v_sub_f32_e32 v225, v227, v218
	v_sub_f32_e32 v224, v226, v218
	v_pk_mul_f32 v[224:225], v[218:219], v[224:225] op_sel:[1,0]
	v_pk_mul_f32 v[222:223], v[218:219], v[222:223] op_sel:[1,0]
	v_pk_fma_f32 v[136:137], v[200:201], v[224:225], v[136:137]
	v_pk_fma_f32 v[138:139], v[198:199], v[222:223], v[138:139]
	v_pk_fma_f32 v[142:143], v[102:103], s[30:31], v[142:143] op_sel_hi:[1,0,1]
	v_pk_fma_f32 v[140:141], v[100:101], s[30:31], v[140:141] op_sel_hi:[1,0,1]
	v_pk_fma_f32 v[222:223], v[98:99], s[30:31], v[138:139] op_sel_hi:[1,0,1]
	v_pk_fma_f32 v[224:225], v[96:97], s[30:31], v[136:137] op_sel_hi:[1,0,1]
	v_lshlrev_b32_e32 v136, 16, v234
	v_and_b32_e32 v137, 0xffff0000, v234
	v_lshlrev_b32_e32 v138, 16, v235
	v_and_b32_e32 v139, 0xffff0000, v235
	v_pk_add_f32 v[136:137], v[140:141], v[136:137]
	v_pk_add_f32 v[138:139], v[142:143], v[138:139]
	v_lshlrev_b32_e32 v140, 16, v236
	v_and_b32_e32 v141, 0xffff0000, v236
	v_lshlrev_b32_e32 v142, 16, v237
	v_and_b32_e32 v143, 0xffff0000, v237
	v_pk_add_f32 v[140:141], v[224:225], v[140:141]
	v_pk_add_f32 v[142:143], v[222:223], v[142:143]
	global_store_dwordx4 v[216:217], v[136:139], off
	global_store_dwordx4 v[216:217], v[140:143], off offset:16
	s_nop 0
	v_sub_f32_e32 v137, v179, v218
	v_sub_f32_e32 v136, v178, v218
	v_sub_f32_e32 v139, v177, v218
	v_sub_f32_e32 v138, v176, v218
	v_pk_mul_f32 v[138:139], v[218:219], v[138:139] op_sel:[1,0]
	v_pk_mul_f32 v[136:137], v[218:219], v[136:137] op_sel:[1,0]
	v_pk_fma_f32 v[132:133], v[196:197], v[138:139], v[132:133]
	v_pk_fma_f32 v[134:135], v[194:195], v[136:137], v[134:135]
	v_sub_f32_e32 v137, v175, v218
	v_sub_f32_e32 v136, v174, v218
	v_sub_f32_e32 v139, v173, v218
	v_sub_f32_e32 v138, v172, v218
	v_pk_mul_f32 v[138:139], v[218:219], v[138:139] op_sel:[1,0]
	v_pk_mul_f32 v[136:137], v[218:219], v[136:137] op_sel:[1,0]
	v_pk_fma_f32 v[128:129], v[192:193], v[138:139], v[128:129]
	v_pk_fma_f32 v[130:131], v[190:191], v[136:137], v[130:131]
	v_pk_fma_f32 v[134:135], v[94:95], s[30:31], v[134:135] op_sel_hi:[1,0,1]
	v_pk_fma_f32 v[132:133], v[92:93], s[30:31], v[132:133] op_sel_hi:[1,0,1]
	v_pk_fma_f32 v[136:137], v[90:91], s[30:31], v[130:131] op_sel_hi:[1,0,1]
	v_pk_fma_f32 v[138:139], v[88:89], s[30:31], v[128:129] op_sel_hi:[1,0,1]
	v_lshlrev_b32_e32 v128, 16, v164
	v_and_b32_e32 v129, 0xffff0000, v164
	v_lshlrev_b32_e32 v130, 16, v165
	v_and_b32_e32 v131, 0xffff0000, v165
	v_pk_add_f32 v[128:129], v[132:133], v[128:129]
	v_pk_add_f32 v[130:131], v[134:135], v[130:131]
	v_lshlrev_b32_e32 v132, 16, v166
	v_and_b32_e32 v133, 0xffff0000, v166
	v_lshlrev_b32_e32 v134, 16, v167
	v_and_b32_e32 v135, 0xffff0000, v167
	v_pk_add_f32 v[132:133], v[138:139], v[132:133]
	v_pk_add_f32 v[134:135], v[136:137], v[134:135]
	global_store_dwordx4 v[216:217], v[128:131], off offset:512
	global_store_dwordx4 v[216:217], v[132:135], off offset:528
	s_nop 0
	v_sub_f32_e32 v129, v171, v214
	v_sub_f32_e32 v128, v170, v214
	v_sub_f32_e32 v131, v169, v214
	v_sub_f32_e32 v130, v168, v214
	v_pk_mul_f32 v[130:131], v[214:215], v[130:131] op_sel:[1,0]
	v_pk_mul_f32 v[128:129], v[214:215], v[128:129] op_sel:[1,0]
	v_pk_fma_f32 v[124:125], v[204:205], v[130:131], v[124:125]
	v_pk_fma_f32 v[126:127], v[202:203], v[128:129], v[126:127]
	v_sub_f32_e32 v129, v163, v214
	v_sub_f32_e32 v128, v162, v214
	v_sub_f32_e32 v131, v161, v214
	v_sub_f32_e32 v130, v160, v214
	v_pk_mul_f32 v[130:131], v[214:215], v[130:131] op_sel:[1,0]
	v_pk_mul_f32 v[128:129], v[214:215], v[128:129] op_sel:[1,0]
	v_pk_fma_f32 v[120:121], v[200:201], v[130:131], v[120:121]
	v_pk_fma_f32 v[122:123], v[198:199], v[128:129], v[122:123]
	v_pk_fma_f32 v[126:127], v[102:103], s[30:31], v[126:127] op_sel_hi:[1,0,1]
	v_pk_fma_f32 v[124:125], v[100:101], s[30:31], v[124:125] op_sel_hi:[1,0,1]
	v_pk_fma_f32 v[128:129], v[98:99], s[30:31], v[122:123] op_sel_hi:[1,0,1]
	v_pk_fma_f32 v[130:131], v[96:97], s[30:31], v[120:121] op_sel_hi:[1,0,1]
	v_lshlrev_b32_e32 v120, 16, v156
	v_and_b32_e32 v121, 0xffff0000, v156
	v_lshlrev_b32_e32 v122, 16, v157
	v_and_b32_e32 v123, 0xffff0000, v157
	v_pk_add_f32 v[120:121], v[124:125], v[120:121]
	v_pk_add_f32 v[122:123], v[126:127], v[122:123]
	v_lshlrev_b32_e32 v124, 16, v158
	v_and_b32_e32 v125, 0xffff0000, v158
	v_lshlrev_b32_e32 v126, 16, v159
	v_and_b32_e32 v127, 0xffff0000, v159
	v_pk_add_f32 v[124:125], v[130:131], v[124:125]
	v_pk_add_f32 v[126:127], v[128:129], v[126:127]
	global_store_dwordx4 v[212:213], v[120:123], off
	global_store_dwordx4 v[212:213], v[124:127], off offset:16
	s_nop 0
	v_sub_f32_e32 v121, v155, v214
	v_sub_f32_e32 v120, v154, v214
	v_sub_f32_e32 v123, v153, v214
	v_sub_f32_e32 v122, v152, v214
	v_pk_mul_f32 v[122:123], v[214:215], v[122:123] op_sel:[1,0]
	v_pk_mul_f32 v[120:121], v[214:215], v[120:121] op_sel:[1,0]
	v_pk_fma_f32 v[116:117], v[196:197], v[122:123], v[116:117]
	v_pk_fma_f32 v[118:119], v[194:195], v[120:121], v[118:119]
	v_sub_f32_e32 v121, v151, v214
	v_sub_f32_e32 v120, v150, v214
	v_sub_f32_e32 v123, v149, v214
	v_sub_f32_e32 v122, v148, v214
	v_pk_mul_f32 v[122:123], v[214:215], v[122:123] op_sel:[1,0]
	v_pk_mul_f32 v[120:121], v[214:215], v[120:121] op_sel:[1,0]
	v_pk_fma_f32 v[112:113], v[192:193], v[122:123], v[112:113]
	v_pk_fma_f32 v[114:115], v[190:191], v[120:121], v[114:115]
	v_pk_fma_f32 v[118:119], v[94:95], s[30:31], v[118:119] op_sel_hi:[1,0,1]
	v_pk_fma_f32 v[116:117], v[92:93], s[30:31], v[116:117] op_sel_hi:[1,0,1]
	v_pk_fma_f32 v[120:121], v[90:91], s[30:31], v[114:115] op_sel_hi:[1,0,1]
	v_pk_fma_f32 v[122:123], v[88:89], s[30:31], v[112:113] op_sel_hi:[1,0,1]
	v_lshlrev_b32_e32 v112, 16, v144
	v_and_b32_e32 v113, 0xffff0000, v144
	v_lshlrev_b32_e32 v114, 16, v145
	v_and_b32_e32 v115, 0xffff0000, v145
	v_pk_add_f32 v[112:113], v[116:117], v[112:113]
	v_pk_add_f32 v[114:115], v[118:119], v[114:115]
	v_lshlrev_b32_e32 v116, 16, v146
	v_and_b32_e32 v117, 0xffff0000, v146
	v_lshlrev_b32_e32 v118, 16, v147
	v_and_b32_e32 v119, 0xffff0000, v147
	v_pk_add_f32 v[116:117], v[122:123], v[116:117]
	v_pk_add_f32 v[118:119], v[120:121], v[118:119]
	global_store_dwordx4 v[212:213], v[112:115], off offset:512
	global_store_dwordx4 v[212:213], v[116:119], off offset:528
	s_nop 0
	v_or_b32_e32 v112, 32, v208
	v_ashrrev_i32_e32 v113, 31, v112
	v_lshl_add_u64 v[114:115], v[112:113], 3, s[12:13]
	global_load_dwordx2 v[162:163], v[114:115], off
	v_lshlrev_b64 v[114:115], 12, v[112:113]
	v_lshl_add_u64 v[114:115], s[6:7], 0, v[114:115]
	v_lshl_add_u64 v[164:165], v[114:115], 0, v[206:207]
	global_load_dwordx4 v[114:117], v[164:165], off
	global_load_dwordx4 v[118:121], v[164:165], off offset:16
	v_lshlrev_b64 v[112:113], 11, v[112:113]
	v_lshl_add_u64 v[112:113], s[10:11], 0, v[112:113]
	v_lshl_add_u64 v[112:113], v[112:113], 0, v[210:211]
	global_load_dwordx4 v[122:125], v[112:113], off
	global_load_dwordx4 v[126:129], v[164:165], off offset:512
	global_load_dwordx4 v[130:133], v[164:165], off offset:528
	global_load_dwordx4 v[134:137], v[112:113], off offset:256
	v_or_b32_e32 v112, 48, v208
	v_ashrrev_i32_e32 v113, 31, v112
	v_lshl_add_u64 v[138:139], v[112:113], 3, s[12:13]
	global_load_dwordx2 v[166:167], v[138:139], off
	v_lshlrev_b64 v[138:139], 12, v[112:113]
	v_lshl_add_u64 v[138:139], s[6:7], 0, v[138:139]
	v_lshlrev_b64 v[112:113], 11, v[112:113]
	v_lshl_add_u64 v[146:147], s[10:11], 0, v[112:113]
	v_lshl_add_u64 v[112:113], v[138:139], 0, v[206:207]
	global_load_dwordx4 v[138:141], v[112:113], off
	global_load_dwordx4 v[142:145], v[112:113], off offset:16
	v_lshl_add_u64 v[158:159], v[146:147], 0, v[210:211]
	global_load_dwordx4 v[146:149], v[158:159], off
	global_load_dwordx4 v[150:153], v[112:113], off offset:512
	global_load_dwordx4 v[154:157], v[112:113], off offset:528
	s_nop 0
	global_load_dwordx4 v[158:161], v[158:159], off offset:256
	s_waitcnt vmcnt(0) lgkmcnt(0)
	v_sub_f32_e32 v117, v117, v162
	v_sub_f32_e32 v116, v116, v162
	v_sub_f32_e32 v115, v115, v162
	v_sub_f32_e32 v114, v114, v162
	v_pk_mul_f32 v[114:115], v[162:163], v[114:115] op_sel:[1,0]
	v_pk_mul_f32 v[116:117], v[162:163], v[116:117] op_sel:[1,0]
	v_pk_fma_f32 v[108:109], v[204:205], v[114:115], v[108:109]
	v_pk_fma_f32 v[110:111], v[202:203], v[116:117], v[110:111]
	v_sub_f32_e32 v115, v121, v162
	v_sub_f32_e32 v114, v120, v162
	v_sub_f32_e32 v117, v119, v162
	v_sub_f32_e32 v116, v118, v162
	v_pk_mul_f32 v[116:117], v[162:163], v[116:117] op_sel:[1,0]
	v_pk_mul_f32 v[114:115], v[162:163], v[114:115] op_sel:[1,0]
	v_pk_fma_f32 v[104:105], v[200:201], v[116:117], v[104:105]
	v_pk_fma_f32 v[106:107], v[198:199], v[114:115], v[106:107]
	v_pk_fma_f32 v[110:111], v[102:103], s[30:31], v[110:111] op_sel_hi:[1,0,1]
	v_pk_fma_f32 v[108:109], v[100:101], s[30:31], v[108:109] op_sel_hi:[1,0,1]
	v_pk_fma_f32 v[114:115], v[98:99], s[30:31], v[106:107] op_sel_hi:[1,0,1]
	v_pk_fma_f32 v[116:117], v[96:97], s[30:31], v[104:105] op_sel_hi:[1,0,1]
	v_lshlrev_b32_e32 v104, 16, v122
	v_and_b32_e32 v105, 0xffff0000, v122
	v_lshlrev_b32_e32 v106, 16, v123
	v_and_b32_e32 v107, 0xffff0000, v123
	v_pk_add_f32 v[104:105], v[108:109], v[104:105]
	v_pk_add_f32 v[106:107], v[110:111], v[106:107]
	v_lshlrev_b32_e32 v108, 16, v124
	v_and_b32_e32 v109, 0xffff0000, v124
	v_lshlrev_b32_e32 v110, 16, v125
	v_and_b32_e32 v111, 0xffff0000, v125
	v_pk_add_f32 v[108:109], v[116:117], v[108:109]
	v_pk_add_f32 v[110:111], v[114:115], v[110:111]
	global_store_dwordx4 v[164:165], v[104:107], off
	global_store_dwordx4 v[164:165], v[108:111], off offset:16
	s_nop 0
	v_sub_f32_e32 v105, v129, v162
	v_sub_f32_e32 v104, v128, v162
	v_sub_f32_e32 v107, v127, v162
	v_sub_f32_e32 v106, v126, v162
	v_pk_mul_f32 v[106:107], v[162:163], v[106:107] op_sel:[1,0]
	v_pk_mul_f32 v[104:105], v[162:163], v[104:105] op_sel:[1,0]
	v_pk_fma_f32 v[84:85], v[196:197], v[106:107], v[84:85]
	v_pk_fma_f32 v[86:87], v[194:195], v[104:105], v[86:87]
	v_sub_f32_e32 v105, v133, v162
	v_sub_f32_e32 v104, v132, v162
	v_sub_f32_e32 v107, v131, v162
	v_sub_f32_e32 v106, v130, v162
	v_pk_mul_f32 v[106:107], v[162:163], v[106:107] op_sel:[1,0]
	v_pk_mul_f32 v[104:105], v[162:163], v[104:105] op_sel:[1,0]
	v_pk_fma_f32 v[80:81], v[192:193], v[106:107], v[80:81]
	v_pk_fma_f32 v[82:83], v[190:191], v[104:105], v[82:83]
	v_pk_fma_f32 v[86:87], v[94:95], s[30:31], v[86:87] op_sel_hi:[1,0,1]
	v_pk_fma_f32 v[84:85], v[92:93], s[30:31], v[84:85] op_sel_hi:[1,0,1]
	v_pk_fma_f32 v[104:105], v[90:91], s[30:31], v[82:83] op_sel_hi:[1,0,1]
	v_pk_fma_f32 v[106:107], v[88:89], s[30:31], v[80:81] op_sel_hi:[1,0,1]
	v_lshlrev_b32_e32 v80, 16, v134
	v_and_b32_e32 v81, 0xffff0000, v134
	v_lshlrev_b32_e32 v82, 16, v135
	v_and_b32_e32 v83, 0xffff0000, v135
	v_pk_add_f32 v[80:81], v[84:85], v[80:81]
	v_pk_add_f32 v[82:83], v[86:87], v[82:83]
	v_lshlrev_b32_e32 v84, 16, v136
	v_and_b32_e32 v85, 0xffff0000, v136
	v_lshlrev_b32_e32 v86, 16, v137
	v_and_b32_e32 v87, 0xffff0000, v137
	v_pk_add_f32 v[84:85], v[106:107], v[84:85]
	v_pk_add_f32 v[86:87], v[104:105], v[86:87]
	global_store_dwordx4 v[164:165], v[80:83], off offset:512
	global_store_dwordx4 v[164:165], v[84:87], off offset:528
	s_nop 0
	v_sub_f32_e32 v81, v141, v166
	v_sub_f32_e32 v80, v140, v166
	v_sub_f32_e32 v83, v139, v166
	v_sub_f32_e32 v82, v138, v166
	v_pk_mul_f32 v[82:83], v[166:167], v[82:83] op_sel:[1,0]
	v_pk_mul_f32 v[80:81], v[166:167], v[80:81] op_sel:[1,0]
	v_pk_fma_f32 v[76:77], v[204:205], v[82:83], v[76:77]
	v_pk_fma_f32 v[78:79], v[202:203], v[80:81], v[78:79]
	v_sub_f32_e32 v81, v145, v166
	v_sub_f32_e32 v80, v144, v166
	v_sub_f32_e32 v83, v143, v166
	v_sub_f32_e32 v82, v142, v166
	v_pk_mul_f32 v[82:83], v[166:167], v[82:83] op_sel:[1,0]
	v_pk_mul_f32 v[80:81], v[166:167], v[80:81] op_sel:[1,0]
	v_pk_fma_f32 v[72:73], v[200:201], v[82:83], v[72:73]
	v_pk_fma_f32 v[74:75], v[198:199], v[80:81], v[74:75]
	v_pk_fma_f32 v[78:79], v[102:103], s[30:31], v[78:79] op_sel_hi:[1,0,1]
	v_pk_fma_f32 v[76:77], v[100:101], s[30:31], v[76:77] op_sel_hi:[1,0,1]
	v_pk_fma_f32 v[80:81], v[98:99], s[30:31], v[74:75] op_sel_hi:[1,0,1]
	v_pk_fma_f32 v[82:83], v[96:97], s[30:31], v[72:73] op_sel_hi:[1,0,1]
	v_lshlrev_b32_e32 v72, 16, v146
	v_and_b32_e32 v73, 0xffff0000, v146
	v_lshlrev_b32_e32 v74, 16, v147
	v_and_b32_e32 v75, 0xffff0000, v147
	v_pk_add_f32 v[72:73], v[76:77], v[72:73]
	v_pk_add_f32 v[74:75], v[78:79], v[74:75]
	v_lshlrev_b32_e32 v76, 16, v148
	v_and_b32_e32 v77, 0xffff0000, v148
	v_lshlrev_b32_e32 v78, 16, v149
	v_and_b32_e32 v79, 0xffff0000, v149
	v_pk_add_f32 v[76:77], v[82:83], v[76:77]
	v_pk_add_f32 v[78:79], v[80:81], v[78:79]
	global_store_dwordx4 v[112:113], v[72:75], off
	global_store_dwordx4 v[112:113], v[76:79], off offset:16
	s_nop 0
	v_sub_f32_e32 v73, v153, v166
	v_sub_f32_e32 v72, v152, v166
	v_sub_f32_e32 v75, v151, v166
	v_sub_f32_e32 v74, v150, v166
	v_pk_mul_f32 v[74:75], v[166:167], v[74:75] op_sel:[1,0]
	v_pk_mul_f32 v[72:73], v[166:167], v[72:73] op_sel:[1,0]
	v_pk_fma_f32 v[68:69], v[196:197], v[74:75], v[68:69]
	v_pk_fma_f32 v[70:71], v[194:195], v[72:73], v[70:71]
	v_sub_f32_e32 v73, v157, v166
	v_sub_f32_e32 v72, v156, v166
	v_sub_f32_e32 v75, v155, v166
	v_sub_f32_e32 v74, v154, v166
	v_pk_mul_f32 v[74:75], v[166:167], v[74:75] op_sel:[1,0]
	v_pk_mul_f32 v[72:73], v[166:167], v[72:73] op_sel:[1,0]
	v_pk_fma_f32 v[64:65], v[192:193], v[74:75], v[64:65]
	v_pk_fma_f32 v[66:67], v[190:191], v[72:73], v[66:67]
	v_pk_fma_f32 v[70:71], v[94:95], s[30:31], v[70:71] op_sel_hi:[1,0,1]
	v_pk_fma_f32 v[68:69], v[92:93], s[30:31], v[68:69] op_sel_hi:[1,0,1]
	v_pk_fma_f32 v[72:73], v[90:91], s[30:31], v[66:67] op_sel_hi:[1,0,1]
	v_pk_fma_f32 v[74:75], v[88:89], s[30:31], v[64:65] op_sel_hi:[1,0,1]
	v_lshlrev_b32_e32 v64, 16, v158
	v_and_b32_e32 v65, 0xffff0000, v158
	v_lshlrev_b32_e32 v66, 16, v159
	v_and_b32_e32 v67, 0xffff0000, v159
	v_pk_add_f32 v[64:65], v[68:69], v[64:65]
	v_pk_add_f32 v[66:67], v[70:71], v[66:67]
	v_lshlrev_b32_e32 v68, 16, v160
	v_and_b32_e32 v69, 0xffff0000, v160
	v_lshlrev_b32_e32 v70, 16, v161
	v_and_b32_e32 v71, 0xffff0000, v161
	v_pk_add_f32 v[68:69], v[74:75], v[68:69]
	v_pk_add_f32 v[70:71], v[72:73], v[70:71]
	global_store_dwordx4 v[112:113], v[64:67], off offset:512
	global_store_dwordx4 v[112:113], v[68:71], off offset:528
	s_nop 0
	v_add_u32_e32 v64, 0x80, v208
	v_ashrrev_i32_e32 v65, 31, v64
	v_lshl_add_u64 v[66:67], v[64:65], 3, s[12:13]
	global_load_dwordx2 v[86:87], v[66:67], off
	v_lshlrev_b64 v[66:67], 12, v[64:65]
	v_lshl_add_u64 v[66:67], s[6:7], 0, v[66:67]
	v_lshl_add_u64 v[132:133], v[66:67], 0, v[206:207]
	global_load_dwordx4 v[66:69], v[132:133], off
	global_load_dwordx4 v[70:73], v[132:133], off offset:16
	v_lshlrev_b64 v[64:65], 11, v[64:65]
	v_lshl_add_u64 v[64:65], s[10:11], 0, v[64:65]
	v_lshl_add_u64 v[64:65], v[64:65], 0, v[210:211]
	global_load_dwordx4 v[74:77], v[64:65], off
	global_load_dwordx4 v[78:81], v[132:133], off offset:512
	global_load_dwordx4 v[82:85], v[132:133], off offset:528
	global_load_dwordx4 v[104:107], v[64:65], off offset:256
	v_add_u32_e32 v64, 0x90, v208
	v_ashrrev_i32_e32 v65, 31, v64
	v_lshl_add_u64 v[108:109], v[64:65], 3, s[12:13]
	global_load_dwordx2 v[134:135], v[108:109], off
	v_lshlrev_b64 v[108:109], 12, v[64:65]
	v_lshl_add_u64 v[108:109], s[6:7], 0, v[108:109]
	v_lshlrev_b64 v[64:65], 11, v[64:65]
	v_lshl_add_u64 v[116:117], s[10:11], 0, v[64:65]
	v_lshl_add_u64 v[64:65], v[108:109], 0, v[206:207]
	global_load_dwordx4 v[108:111], v[64:65], off
	global_load_dwordx4 v[112:115], v[64:65], off offset:16
	v_lshl_add_u64 v[128:129], v[116:117], 0, v[210:211]
	global_load_dwordx4 v[116:119], v[128:129], off
	global_load_dwordx4 v[120:123], v[64:65], off offset:512
	global_load_dwordx4 v[124:127], v[64:65], off offset:528
	s_nop 0
	global_load_dwordx4 v[128:131], v[128:129], off offset:256
	s_waitcnt vmcnt(0) lgkmcnt(0)
	v_sub_f32_e32 v69, v69, v86
	v_sub_f32_e32 v68, v68, v86
	v_sub_f32_e32 v67, v67, v86
	v_sub_f32_e32 v66, v66, v86
	v_pk_mul_f32 v[66:67], v[86:87], v[66:67] op_sel:[1,0]
	v_pk_mul_f32 v[68:69], v[86:87], v[68:69] op_sel:[1,0]
	v_pk_fma_f32 v[60:61], v[204:205], v[66:67], v[60:61]
	v_pk_fma_f32 v[62:63], v[202:203], v[68:69], v[62:63]
	v_sub_f32_e32 v67, v73, v86
	v_sub_f32_e32 v66, v72, v86
	v_sub_f32_e32 v69, v71, v86
	v_sub_f32_e32 v68, v70, v86
	v_pk_mul_f32 v[68:69], v[86:87], v[68:69] op_sel:[1,0]
	v_pk_mul_f32 v[66:67], v[86:87], v[66:67] op_sel:[1,0]
	v_pk_fma_f32 v[56:57], v[200:201], v[68:69], v[56:57]
	v_pk_fma_f32 v[58:59], v[198:199], v[66:67], v[58:59]
	v_pk_fma_f32 v[62:63], v[102:103], s[30:31], v[62:63] op_sel_hi:[1,0,1]
	v_pk_fma_f32 v[60:61], v[100:101], s[30:31], v[60:61] op_sel_hi:[1,0,1]
	v_pk_fma_f32 v[66:67], v[98:99], s[30:31], v[58:59] op_sel_hi:[1,0,1]
	v_pk_fma_f32 v[68:69], v[96:97], s[30:31], v[56:57] op_sel_hi:[1,0,1]
	v_lshlrev_b32_e32 v56, 16, v74
	v_and_b32_e32 v57, 0xffff0000, v74
	v_lshlrev_b32_e32 v58, 16, v75
	v_and_b32_e32 v59, 0xffff0000, v75
	v_pk_add_f32 v[56:57], v[60:61], v[56:57]
	v_pk_add_f32 v[58:59], v[62:63], v[58:59]
	v_lshlrev_b32_e32 v60, 16, v76
	v_and_b32_e32 v61, 0xffff0000, v76
	v_lshlrev_b32_e32 v62, 16, v77
	v_and_b32_e32 v63, 0xffff0000, v77
	v_pk_add_f32 v[60:61], v[68:69], v[60:61]
	v_pk_add_f32 v[62:63], v[66:67], v[62:63]
	global_store_dwordx4 v[132:133], v[56:59], off
	global_store_dwordx4 v[132:133], v[60:63], off offset:16
	s_nop 0
	v_sub_f32_e32 v57, v81, v86
	v_sub_f32_e32 v56, v80, v86
	v_sub_f32_e32 v59, v79, v86
	v_sub_f32_e32 v58, v78, v86
	v_pk_mul_f32 v[58:59], v[86:87], v[58:59] op_sel:[1,0]
	v_pk_mul_f32 v[56:57], v[86:87], v[56:57] op_sel:[1,0]
	v_pk_fma_f32 v[52:53], v[196:197], v[58:59], v[52:53]
	v_pk_fma_f32 v[54:55], v[194:195], v[56:57], v[54:55]
	v_sub_f32_e32 v57, v85, v86
	v_sub_f32_e32 v56, v84, v86
	v_sub_f32_e32 v59, v83, v86
	v_sub_f32_e32 v58, v82, v86
	v_pk_mul_f32 v[58:59], v[86:87], v[58:59] op_sel:[1,0]
	v_pk_mul_f32 v[56:57], v[86:87], v[56:57] op_sel:[1,0]
	v_pk_fma_f32 v[48:49], v[192:193], v[58:59], v[48:49]
	v_pk_fma_f32 v[50:51], v[190:191], v[56:57], v[50:51]
	v_pk_fma_f32 v[54:55], v[94:95], s[30:31], v[54:55] op_sel_hi:[1,0,1]
	v_pk_fma_f32 v[52:53], v[92:93], s[30:31], v[52:53] op_sel_hi:[1,0,1]
	v_pk_fma_f32 v[56:57], v[90:91], s[30:31], v[50:51] op_sel_hi:[1,0,1]
	v_pk_fma_f32 v[58:59], v[88:89], s[30:31], v[48:49] op_sel_hi:[1,0,1]
	v_lshlrev_b32_e32 v48, 16, v104
	v_and_b32_e32 v49, 0xffff0000, v104
	v_lshlrev_b32_e32 v50, 16, v105
	v_and_b32_e32 v51, 0xffff0000, v105
	v_pk_add_f32 v[48:49], v[52:53], v[48:49]
	v_pk_add_f32 v[50:51], v[54:55], v[50:51]
	v_lshlrev_b32_e32 v52, 16, v106
	v_and_b32_e32 v53, 0xffff0000, v106
	v_lshlrev_b32_e32 v54, 16, v107
	v_and_b32_e32 v55, 0xffff0000, v107
	v_pk_add_f32 v[52:53], v[58:59], v[52:53]
	v_pk_add_f32 v[54:55], v[56:57], v[54:55]
	global_store_dwordx4 v[132:133], v[48:51], off offset:512
	global_store_dwordx4 v[132:133], v[52:55], off offset:528
	s_nop 0
	v_sub_f32_e32 v49, v111, v134
	v_sub_f32_e32 v48, v110, v134
	v_sub_f32_e32 v51, v109, v134
	v_sub_f32_e32 v50, v108, v134
	v_pk_mul_f32 v[50:51], v[134:135], v[50:51] op_sel:[1,0]
	v_pk_mul_f32 v[48:49], v[134:135], v[48:49] op_sel:[1,0]
	v_pk_fma_f32 v[44:45], v[204:205], v[50:51], v[44:45]
	v_pk_fma_f32 v[46:47], v[202:203], v[48:49], v[46:47]
	v_sub_f32_e32 v49, v115, v134
	v_sub_f32_e32 v48, v114, v134
	v_sub_f32_e32 v51, v113, v134
	v_sub_f32_e32 v50, v112, v134
	v_pk_mul_f32 v[50:51], v[134:135], v[50:51] op_sel:[1,0]
	v_pk_mul_f32 v[48:49], v[134:135], v[48:49] op_sel:[1,0]
	v_pk_fma_f32 v[40:41], v[200:201], v[50:51], v[40:41]
	v_pk_fma_f32 v[42:43], v[198:199], v[48:49], v[42:43]
	v_pk_fma_f32 v[46:47], v[102:103], s[30:31], v[46:47] op_sel_hi:[1,0,1]
	v_pk_fma_f32 v[44:45], v[100:101], s[30:31], v[44:45] op_sel_hi:[1,0,1]
	v_pk_fma_f32 v[48:49], v[98:99], s[30:31], v[42:43] op_sel_hi:[1,0,1]
	v_pk_fma_f32 v[50:51], v[96:97], s[30:31], v[40:41] op_sel_hi:[1,0,1]
	v_lshlrev_b32_e32 v40, 16, v116
	v_and_b32_e32 v41, 0xffff0000, v116
	v_lshlrev_b32_e32 v42, 16, v117
	v_and_b32_e32 v43, 0xffff0000, v117
	v_pk_add_f32 v[40:41], v[44:45], v[40:41]
	v_pk_add_f32 v[42:43], v[46:47], v[42:43]
	v_lshlrev_b32_e32 v44, 16, v118
	v_and_b32_e32 v45, 0xffff0000, v118
	v_lshlrev_b32_e32 v46, 16, v119
	v_and_b32_e32 v47, 0xffff0000, v119
	v_pk_add_f32 v[44:45], v[50:51], v[44:45]
	v_pk_add_f32 v[46:47], v[48:49], v[46:47]
	global_store_dwordx4 v[64:65], v[40:43], off
	global_store_dwordx4 v[64:65], v[44:47], off offset:16
	s_nop 0
	v_sub_f32_e32 v41, v123, v134
	v_sub_f32_e32 v40, v122, v134
	v_sub_f32_e32 v43, v121, v134
	v_sub_f32_e32 v42, v120, v134
	v_pk_mul_f32 v[42:43], v[134:135], v[42:43] op_sel:[1,0]
	v_pk_mul_f32 v[40:41], v[134:135], v[40:41] op_sel:[1,0]
	v_pk_fma_f32 v[36:37], v[196:197], v[42:43], v[36:37]
	v_pk_fma_f32 v[38:39], v[194:195], v[40:41], v[38:39]
	v_sub_f32_e32 v41, v127, v134
	v_sub_f32_e32 v40, v126, v134
	v_sub_f32_e32 v43, v125, v134
	v_sub_f32_e32 v42, v124, v134
	v_pk_mul_f32 v[42:43], v[134:135], v[42:43] op_sel:[1,0]
	v_pk_mul_f32 v[40:41], v[134:135], v[40:41] op_sel:[1,0]
	v_pk_fma_f32 v[32:33], v[192:193], v[42:43], v[32:33]
	v_pk_fma_f32 v[34:35], v[190:191], v[40:41], v[34:35]
	v_pk_fma_f32 v[38:39], v[94:95], s[30:31], v[38:39] op_sel_hi:[1,0,1]
	v_pk_fma_f32 v[36:37], v[92:93], s[30:31], v[36:37] op_sel_hi:[1,0,1]
	v_pk_fma_f32 v[40:41], v[90:91], s[30:31], v[34:35] op_sel_hi:[1,0,1]
	v_pk_fma_f32 v[42:43], v[88:89], s[30:31], v[32:33] op_sel_hi:[1,0,1]
	v_lshlrev_b32_e32 v32, 16, v128
	v_and_b32_e32 v33, 0xffff0000, v128
	v_lshlrev_b32_e32 v34, 16, v129
	v_and_b32_e32 v35, 0xffff0000, v129
	v_pk_add_f32 v[32:33], v[36:37], v[32:33]
	v_pk_add_f32 v[34:35], v[38:39], v[34:35]
	v_lshlrev_b32_e32 v36, 16, v130
	v_and_b32_e32 v37, 0xffff0000, v130
	v_lshlrev_b32_e32 v38, 16, v131
	v_and_b32_e32 v39, 0xffff0000, v131
	v_pk_add_f32 v[36:37], v[42:43], v[36:37]
	v_pk_add_f32 v[38:39], v[40:41], v[38:39]
	global_store_dwordx4 v[64:65], v[32:35], off offset:512
	global_store_dwordx4 v[64:65], v[36:39], off offset:528
	s_nop 0
	v_add_u32_e32 v32, 0xa0, v208
	v_ashrrev_i32_e32 v33, 31, v32
	v_lshl_add_u64 v[34:35], v[32:33], 3, s[12:13]
	global_load_dwordx2 v[82:83], v[34:35], off
	v_lshlrev_b64 v[34:35], 12, v[32:33]
	v_lshl_add_u64 v[34:35], s[6:7], 0, v[34:35]
	v_lshl_add_u64 v[84:85], v[34:35], 0, v[206:207]
	global_load_dwordx4 v[34:37], v[84:85], off
	global_load_dwordx4 v[38:41], v[84:85], off offset:16
	v_lshlrev_b64 v[32:33], 11, v[32:33]
	v_lshl_add_u64 v[32:33], s[10:11], 0, v[32:33]
	v_lshl_add_u64 v[32:33], v[32:33], 0, v[210:211]
	global_load_dwordx4 v[42:45], v[32:33], off
	global_load_dwordx4 v[46:49], v[84:85], off offset:512
	global_load_dwordx4 v[50:53], v[84:85], off offset:528
	global_load_dwordx4 v[54:57], v[32:33], off offset:256
	v_add_u32_e32 v32, 0xb0, v208
	v_ashrrev_i32_e32 v33, 31, v32
	v_lshl_add_u64 v[58:59], v[32:33], 3, s[12:13]
	global_load_dwordx2 v[86:87], v[58:59], off
	v_lshlrev_b64 v[58:59], 12, v[32:33]
	v_lshl_add_u64 v[58:59], s[6:7], 0, v[58:59]
	v_lshlrev_b64 v[32:33], 11, v[32:33]
	v_lshl_add_u64 v[66:67], s[10:11], 0, v[32:33]
	v_lshl_add_u64 v[32:33], v[58:59], 0, v[206:207]
	global_load_dwordx4 v[58:61], v[32:33], off
	global_load_dwordx4 v[62:65], v[32:33], off offset:16
	v_lshl_add_u64 v[78:79], v[66:67], 0, v[210:211]
	global_load_dwordx4 v[66:69], v[78:79], off
	global_load_dwordx4 v[70:73], v[32:33], off offset:512
	global_load_dwordx4 v[74:77], v[32:33], off offset:528
	s_nop 0
	global_load_dwordx4 v[78:81], v[78:79], off offset:256
	s_waitcnt vmcnt(0) lgkmcnt(0)
	v_sub_f32_e32 v37, v37, v82
	v_sub_f32_e32 v36, v36, v82
	v_sub_f32_e32 v35, v35, v82
	v_sub_f32_e32 v34, v34, v82
	v_pk_mul_f32 v[34:35], v[82:83], v[34:35] op_sel:[1,0]
	v_pk_mul_f32 v[36:37], v[82:83], v[36:37] op_sel:[1,0]
	v_pk_fma_f32 v[28:29], v[204:205], v[34:35], v[28:29]
	v_pk_fma_f32 v[30:31], v[202:203], v[36:37], v[30:31]
	v_sub_f32_e32 v35, v41, v82
	v_sub_f32_e32 v34, v40, v82
	v_sub_f32_e32 v37, v39, v82
	v_sub_f32_e32 v36, v38, v82
	v_pk_mul_f32 v[36:37], v[82:83], v[36:37] op_sel:[1,0]
	v_pk_mul_f32 v[34:35], v[82:83], v[34:35] op_sel:[1,0]
	v_pk_fma_f32 v[24:25], v[200:201], v[36:37], v[24:25]
	v_pk_fma_f32 v[26:27], v[198:199], v[34:35], v[26:27]
	v_pk_fma_f32 v[30:31], v[102:103], s[30:31], v[30:31] op_sel_hi:[1,0,1]
	v_pk_fma_f32 v[28:29], v[100:101], s[30:31], v[28:29] op_sel_hi:[1,0,1]
	v_pk_fma_f32 v[34:35], v[98:99], s[30:31], v[26:27] op_sel_hi:[1,0,1]
	v_pk_fma_f32 v[36:37], v[96:97], s[30:31], v[24:25] op_sel_hi:[1,0,1]
	v_lshlrev_b32_e32 v24, 16, v42
	v_and_b32_e32 v25, 0xffff0000, v42
	v_lshlrev_b32_e32 v26, 16, v43
	v_and_b32_e32 v27, 0xffff0000, v43
	v_pk_add_f32 v[24:25], v[28:29], v[24:25]
	v_pk_add_f32 v[26:27], v[30:31], v[26:27]
	v_lshlrev_b32_e32 v28, 16, v44
	v_and_b32_e32 v29, 0xffff0000, v44
	v_lshlrev_b32_e32 v30, 16, v45
	v_and_b32_e32 v31, 0xffff0000, v45
	v_pk_add_f32 v[28:29], v[36:37], v[28:29]
	v_pk_add_f32 v[30:31], v[34:35], v[30:31]
	global_store_dwordx4 v[84:85], v[24:27], off
	global_store_dwordx4 v[84:85], v[28:31], off offset:16
	s_nop 0
	v_sub_f32_e32 v25, v49, v82
	v_sub_f32_e32 v24, v48, v82
	v_sub_f32_e32 v27, v47, v82
	v_sub_f32_e32 v26, v46, v82
	v_pk_mul_f32 v[26:27], v[82:83], v[26:27] op_sel:[1,0]
	v_pk_mul_f32 v[24:25], v[82:83], v[24:25] op_sel:[1,0]
	v_pk_fma_f32 v[20:21], v[196:197], v[26:27], v[20:21]
	v_pk_fma_f32 v[22:23], v[194:195], v[24:25], v[22:23]
	v_sub_f32_e32 v25, v53, v82
	v_sub_f32_e32 v24, v52, v82
	v_sub_f32_e32 v27, v51, v82
	v_sub_f32_e32 v26, v50, v82
	v_pk_mul_f32 v[26:27], v[82:83], v[26:27] op_sel:[1,0]
	v_pk_mul_f32 v[24:25], v[82:83], v[24:25] op_sel:[1,0]
	v_pk_fma_f32 v[16:17], v[192:193], v[26:27], v[16:17]
	v_pk_fma_f32 v[18:19], v[190:191], v[24:25], v[18:19]
	v_pk_fma_f32 v[22:23], v[94:95], s[30:31], v[22:23] op_sel_hi:[1,0,1]
	v_pk_fma_f32 v[20:21], v[92:93], s[30:31], v[20:21] op_sel_hi:[1,0,1]
	v_pk_fma_f32 v[24:25], v[90:91], s[30:31], v[18:19] op_sel_hi:[1,0,1]
	v_pk_fma_f32 v[26:27], v[88:89], s[30:31], v[16:17] op_sel_hi:[1,0,1]
	v_lshlrev_b32_e32 v16, 16, v54
	v_and_b32_e32 v17, 0xffff0000, v54
	v_lshlrev_b32_e32 v18, 16, v55
	v_and_b32_e32 v19, 0xffff0000, v55
	v_pk_add_f32 v[16:17], v[20:21], v[16:17]
	v_pk_add_f32 v[18:19], v[22:23], v[18:19]
	v_lshlrev_b32_e32 v20, 16, v56
	v_and_b32_e32 v21, 0xffff0000, v56
	v_lshlrev_b32_e32 v22, 16, v57
	v_and_b32_e32 v23, 0xffff0000, v57
	v_pk_add_f32 v[20:21], v[26:27], v[20:21]
	v_pk_add_f32 v[22:23], v[24:25], v[22:23]
	global_store_dwordx4 v[84:85], v[16:19], off offset:512
	global_store_dwordx4 v[84:85], v[20:23], off offset:528
	s_nop 0
	v_sub_f32_e32 v17, v61, v86
	v_sub_f32_e32 v16, v60, v86
	v_sub_f32_e32 v19, v59, v86
	v_sub_f32_e32 v18, v58, v86
	v_pk_mul_f32 v[18:19], v[86:87], v[18:19] op_sel:[1,0]
	v_pk_mul_f32 v[16:17], v[86:87], v[16:17] op_sel:[1,0]
	v_pk_fma_f32 v[12:13], v[204:205], v[18:19], v[12:13]
	v_pk_fma_f32 v[14:15], v[202:203], v[16:17], v[14:15]
	v_sub_f32_e32 v17, v65, v86
	v_sub_f32_e32 v16, v64, v86
	v_sub_f32_e32 v19, v63, v86
	v_sub_f32_e32 v18, v62, v86
	v_pk_mul_f32 v[18:19], v[86:87], v[18:19] op_sel:[1,0]
	v_pk_mul_f32 v[16:17], v[86:87], v[16:17] op_sel:[1,0]
	v_pk_fma_f32 v[8:9], v[200:201], v[18:19], v[8:9]
	v_pk_fma_f32 v[10:11], v[198:199], v[16:17], v[10:11]
	v_pk_fma_f32 v[14:15], v[102:103], s[30:31], v[14:15] op_sel_hi:[1,0,1]
	v_pk_fma_f32 v[12:13], v[100:101], s[30:31], v[12:13] op_sel_hi:[1,0,1]
	v_pk_fma_f32 v[16:17], v[98:99], s[30:31], v[10:11] op_sel_hi:[1,0,1]
	v_pk_fma_f32 v[18:19], v[96:97], s[30:31], v[8:9] op_sel_hi:[1,0,1]
	v_lshlrev_b32_e32 v8, 16, v66
	v_and_b32_e32 v9, 0xffff0000, v66
	v_lshlrev_b32_e32 v10, 16, v67
	v_and_b32_e32 v11, 0xffff0000, v67
	v_pk_add_f32 v[8:9], v[12:13], v[8:9]
	v_pk_add_f32 v[10:11], v[14:15], v[10:11]
	v_lshlrev_b32_e32 v12, 16, v68
	v_and_b32_e32 v13, 0xffff0000, v68
	v_lshlrev_b32_e32 v14, 16, v69
	v_and_b32_e32 v15, 0xffff0000, v69
	v_pk_add_f32 v[12:13], v[18:19], v[12:13]
	v_pk_add_f32 v[14:15], v[16:17], v[14:15]
	global_store_dwordx4 v[32:33], v[8:11], off
	global_store_dwordx4 v[32:33], v[12:15], off offset:16
	s_nop 0
	v_sub_f32_e32 v9, v73, v86
	v_sub_f32_e32 v8, v72, v86
	v_sub_f32_e32 v11, v71, v86
	v_sub_f32_e32 v10, v70, v86
	v_pk_mul_f32 v[10:11], v[86:87], v[10:11] op_sel:[1,0]
	v_pk_mul_f32 v[8:9], v[86:87], v[8:9] op_sel:[1,0]
	v_pk_fma_f32 v[4:5], v[196:197], v[10:11], v[4:5]
	v_pk_fma_f32 v[6:7], v[194:195], v[8:9], v[6:7]
	v_sub_f32_e32 v9, v77, v86
	v_sub_f32_e32 v8, v76, v86
	v_sub_f32_e32 v11, v75, v86
	v_sub_f32_e32 v10, v74, v86
	v_pk_mul_f32 v[10:11], v[86:87], v[10:11] op_sel:[1,0]
	v_pk_mul_f32 v[8:9], v[86:87], v[8:9] op_sel:[1,0]
	v_pk_fma_f32 v[0:1], v[192:193], v[10:11], v[0:1]
	v_pk_fma_f32 v[2:3], v[190:191], v[8:9], v[2:3]
	v_pk_fma_f32 v[6:7], v[94:95], s[30:31], v[6:7] op_sel_hi:[1,0,1]
	v_pk_fma_f32 v[4:5], v[92:93], s[30:31], v[4:5] op_sel_hi:[1,0,1]
	v_pk_fma_f32 v[8:9], v[90:91], s[30:31], v[2:3] op_sel_hi:[1,0,1]
	v_pk_fma_f32 v[10:11], v[88:89], s[30:31], v[0:1] op_sel_hi:[1,0,1]
	v_lshlrev_b32_e32 v0, 16, v78
	v_and_b32_e32 v1, 0xffff0000, v78
	v_lshlrev_b32_e32 v2, 16, v79
	v_and_b32_e32 v3, 0xffff0000, v79
	v_pk_add_f32 v[0:1], v[4:5], v[0:1]
	v_pk_add_f32 v[2:3], v[6:7], v[2:3]
	v_lshlrev_b32_e32 v4, 16, v80
	v_and_b32_e32 v5, 0xffff0000, v80
	v_lshlrev_b32_e32 v6, 16, v81
	v_and_b32_e32 v7, 0xffff0000, v81
	v_pk_add_f32 v[4:5], v[10:11], v[4:5]
	v_pk_add_f32 v[6:7], v[8:9], v[6:7]
	global_store_dwordx4 v[32:33], v[0:3], off offset:512
	global_store_dwordx4 v[32:33], v[4:7], off offset:528
	s_cbranch_vccnz .LBB0_1484
	s_andn2_b64 vcc, exec, s[8:9]
	s_cbranch_vccnz .LBB0_1483
	s_barrier
	s_branch .LBB0_1483

.LBB0_1552:
	v_add_co_u32_e32 v0, vcc, 0xffff8400, v138
	s_nop 1
	v_addc_co_u32_e32 v1, vcc, -1, v139, vcc
	v_add_co_u32_e32 v2, vcc, 0xffff8800, v138
	s_nop 1
	v_addc_co_u32_e32 v3, vcc, -1, v139, vcc
	s_waitcnt vmcnt(0)
	global_load_dwordx4 v[84:87], v[0:1], off
	global_load_dwordx4 v[48:51], v[2:3], off
	v_add_co_u32_e32 v0, vcc, 0xffff8c00, v138
	s_waitcnt vmcnt(0) lgkmcnt(0)
	v_add_f32_e32 v128, v84, v85
	v_addc_co_u32_e32 v1, vcc, -1, v139, vcc
	v_add_co_u32_e32 v2, vcc, 0xffff9000, v138
	v_add_f32_e32 v129, v86, v87
	s_nop 0
	v_addc_co_u32_e32 v3, vcc, -1, v139, vcc
	v_add_co_u32_e32 v4, vcc, 0xffff9400, v138
	global_load_dwordx4 v[20:23], v[0:1], off
	s_nop 0
	global_load_dwordx4 v[0:3], v[2:3], off
	v_addc_co_u32_e32 v5, vcc, -1, v139, vcc
	v_add_co_u32_e32 v6, vcc, 0xffff9800, v138
	v_add_f32_e32 v128, v128, v129
	s_nop 0
	v_addc_co_u32_e32 v7, vcc, -1, v139, vcc
	global_load_dwordx4 v[92:95], v[4:5], off
	global_load_dwordx4 v[56:59], v[6:7], off
	v_add_co_u32_e32 v4, vcc, 0xffff9c00, v138
	v_add_f32_e32 v129, v48, v49
	s_nop 0
	v_addc_co_u32_e32 v5, vcc, -1, v139, vcc
	v_add_co_u32_e32 v6, vcc, 0xffffa000, v138
	v_add_f32_e32 v130, v50, v51
	s_nop 0
	v_addc_co_u32_e32 v7, vcc, -1, v139, vcc
	v_add_co_u32_e32 v8, vcc, 0xffffa400, v138
	global_load_dwordx4 v[28:31], v[4:5], off
	s_nop 0
	global_load_dwordx4 v[4:7], v[6:7], off
	v_addc_co_u32_e32 v9, vcc, -1, v139, vcc
	v_add_co_u32_e32 v10, vcc, 0xffffa800, v138
	v_add_f32_e32 v128, 0, v128
	s_nop 0
	v_addc_co_u32_e32 v11, vcc, -1, v139, vcc
	global_load_dwordx4 v[100:103], v[8:9], off
	global_load_dwordx4 v[64:67], v[10:11], off
	v_add_co_u32_e32 v8, vcc, 0xffffac00, v138
	v_add_f32_e32 v129, v129, v130
	s_nop 0
	v_addc_co_u32_e32 v9, vcc, -1, v139, vcc
	v_add_co_u32_e32 v10, vcc, 0xffffb000, v138
	v_add_f32_e32 v128, v128, v129
	s_nop 0
	v_addc_co_u32_e32 v11, vcc, -1, v139, vcc
	v_add_co_u32_e32 v12, vcc, 0xffffb400, v138
	global_load_dwordx4 v[36:39], v[8:9], off
	s_nop 0
	global_load_dwordx4 v[8:11], v[10:11], off
	v_addc_co_u32_e32 v13, vcc, -1, v139, vcc
	v_add_co_u32_e32 v14, vcc, 0xffffb800, v138
	s_waitcnt vmcnt(0) lgkmcnt(0)
	v_add_f32_e32 v129, v20, v21
	v_addc_co_u32_e32 v15, vcc, -1, v139, vcc
	global_load_dwordx4 v[108:111], v[12:13], off
	global_load_dwordx4 v[76:79], v[14:15], off
	v_add_co_u32_e32 v12, vcc, 0xffffbc00, v138
	v_add_f32_e32 v130, v22, v23
	s_nop 0
	v_addc_co_u32_e32 v13, vcc, -1, v139, vcc
	v_add_co_u32_e32 v14, vcc, 0xffffc000, v138
	v_add_f32_e32 v129, v129, v130
	s_nop 0
	v_addc_co_u32_e32 v15, vcc, -1, v139, vcc
	v_add_co_u32_e32 v16, vcc, 0xffffc400, v138
	global_load_dwordx4 v[44:47], v[12:13], off
	s_nop 0
	global_load_dwordx4 v[12:15], v[14:15], off
	v_addc_co_u32_e32 v17, vcc, -1, v139, vcc
	v_add_co_u32_e32 v18, vcc, 0xffffc800, v138
	v_add_f32_e32 v128, v128, v129
	s_nop 0
	v_addc_co_u32_e32 v19, vcc, -1, v139, vcc
	global_load_dwordx4 v[112:115], v[16:17], off
	global_load_dwordx4 v[80:83], v[18:19], off
	v_add_co_u32_e32 v16, vcc, 0xffffcc00, v138
	v_add_f32_e32 v129, v0, v1
	s_nop 0
	v_addc_co_u32_e32 v17, vcc, -1, v139, vcc
	v_add_co_u32_e32 v18, vcc, 0xffffd000, v138
	v_add_f32_e32 v130, v2, v3
	s_nop 0
	v_addc_co_u32_e32 v19, vcc, -1, v139, vcc
	v_add_co_u32_e32 v24, vcc, 0xffffd400, v138
	global_load_dwordx4 v[52:55], v[16:17], off
	s_nop 0
	global_load_dwordx4 v[16:19], v[18:19], off
	v_addc_co_u32_e32 v25, vcc, -1, v139, vcc
	v_add_co_u32_e32 v26, vcc, 0xffffd800, v138
	v_add_f32_e32 v129, v129, v130
	s_nop 0
	v_addc_co_u32_e32 v27, vcc, -1, v139, vcc
	global_load_dwordx4 v[116:119], v[24:25], off
	global_load_dwordx4 v[88:91], v[26:27], off
	v_add_co_u32_e32 v24, vcc, 0xffffdc00, v138
	v_add_f32_e32 v128, v128, v129
	s_nop 0
	v_addc_co_u32_e32 v25, vcc, -1, v139, vcc
	v_add_co_u32_e32 v26, vcc, 0xffffe000, v138
	v_add_f32_e32 v129, v92, v93
	s_nop 0
	v_addc_co_u32_e32 v27, vcc, -1, v139, vcc
	v_add_co_u32_e32 v32, vcc, 0xffffe400, v138
	global_load_dwordx4 v[60:63], v[24:25], off
	s_nop 0
	global_load_dwordx4 v[24:27], v[26:27], off
	v_addc_co_u32_e32 v33, vcc, -1, v139, vcc
	v_add_co_u32_e32 v34, vcc, s46, v138
	v_add_f32_e32 v130, v94, v95
	s_nop 0
	v_addc_co_u32_e32 v35, vcc, -1, v139, vcc
	global_load_dwordx4 v[120:123], v[32:33], off
	global_load_dwordx4 v[96:99], v[34:35], off
	v_add_co_u32_e32 v32, vcc, 0xffffec00, v138
	v_add_f32_e32 v129, v129, v130
	s_nop 0
	v_addc_co_u32_e32 v33, vcc, -1, v139, vcc
	v_add_co_u32_e32 v34, vcc, 0xfffff000, v138
	v_add_f32_e32 v130, v56, v57
	s_nop 0
	v_addc_co_u32_e32 v35, vcc, -1, v139, vcc
	global_load_dwordx4 v[68:71], v[32:33], off
	s_nop 0
	global_load_dwordx4 v[32:35], v[34:35], off
	v_add_co_u32_e32 v40, vcc, 0xfffff400, v138
	v_add_f32_e32 v131, v58, v59
	s_nop 0
	v_addc_co_u32_e32 v41, vcc, -1, v139, vcc
	v_add_co_u32_e32 v42, vcc, 0xfffff800, v138
	v_add_f32_e32 v129, 0, v129
	s_nop 0
	v_addc_co_u32_e32 v43, vcc, -1, v139, vcc
	global_load_dwordx4 v[124:127], v[40:41], off
	global_load_dwordx4 v[104:107], v[42:43], off
	v_add_co_u32_e32 v40, vcc, s76, v138
	v_add_f32_e32 v130, v130, v131
	s_nop 0
	v_addc_co_u32_e32 v41, vcc, -1, v139, vcc
	global_load_dwordx4 v[72:75], v[40:41], off
	s_nop 0
	global_load_dwordx4 v[40:43], v[138:139], off
	v_add_f32_e32 v129, v129, v130
	v_add_f32_e32 v130, v28, v29
	v_add_f32_e32 v131, v30, v31
	v_add_f32_e32 v130, v130, v131
	v_add_f32_e32 v129, v129, v130
	v_add_f32_e32 v130, v4, v5
	v_add_f32_e32 v131, v6, v7
	v_add_f32_e32 v130, v130, v131
	v_add_f32_e32 v129, v129, v130
	v_add_f32_e32 v130, v100, v101
	v_add_f32_e32 v131, v102, v103
	v_add_f32_e32 v130, v130, v131
	v_add_f32_e32 v131, v64, v65
	v_add_f32_e32 v132, v66, v67
	v_add_f32_e32 v130, 0, v130
	v_add_f32_e32 v131, v131, v132
	v_add_f32_e32 v130, v130, v131
	v_add_f32_e32 v131, v36, v37
	v_add_f32_e32 v132, v38, v39
	v_add_f32_e32 v131, v131, v132
	v_add_f32_e32 v130, v130, v131
	v_add_f32_e32 v131, v8, v9
	v_add_f32_e32 v132, v10, v11
	v_add_f32_e32 v131, v131, v132
	v_add_f32_e32 v130, v130, v131
	s_waitcnt vmcnt(0) lgkmcnt(0)
	v_add_f32_e32 v131, v108, v109
	v_add_f32_e32 v132, v110, v111
	v_add_f32_e32 v131, v131, v132
	v_add_f32_e32 v132, v76, v77
	v_add_f32_e32 v133, v78, v79
	v_add_f32_e32 v131, 0, v131
	v_add_f32_e32 v132, v132, v133
	v_add_f32_e32 v131, v131, v132
	v_add_f32_e32 v132, v44, v45
	v_add_f32_e32 v133, v46, v47
	v_add_f32_e32 v132, v132, v133
	v_add_f32_e32 v131, v131, v132
	v_add_f32_e32 v132, v12, v13
	v_add_f32_e32 v133, v14, v15
	v_add_f32_e32 v132, v132, v133
	v_add_f32_e32 v131, v131, v132
	v_add_f32_e32 v132, v112, v113
	v_add_f32_e32 v133, v114, v115
	v_add_f32_e32 v132, v132, v133
	v_add_f32_e32 v133, v80, v81
	v_add_f32_e32 v140, v82, v83
	v_add_f32_e32 v132, 0, v132
	v_add_f32_e32 v133, v133, v140
	v_add_f32_e32 v132, v132, v133
	v_add_f32_e32 v133, v52, v53
	v_add_f32_e32 v140, v54, v55
	v_add_f32_e32 v133, v133, v140
	v_add_f32_e32 v132, v132, v133
	v_add_f32_e32 v133, v16, v17
	v_add_f32_e32 v140, v18, v19
	v_add_f32_e32 v133, v133, v140
	v_add_f32_e32 v132, v132, v133
	v_add_f32_e32 v133, v116, v117
	v_add_f32_e32 v140, v118, v119
	v_add_f32_e32 v133, v133, v140
	v_add_f32_e32 v140, v88, v89
	v_add_f32_e32 v141, v90, v91
	v_add_f32_e32 v133, 0, v133
	v_add_f32_e32 v140, v140, v141
	v_add_f32_e32 v133, v133, v140
	v_add_f32_e32 v140, v60, v61
	v_add_f32_e32 v141, v62, v63
	v_add_f32_e32 v140, v140, v141
	v_add_f32_e32 v133, v133, v140
	v_add_f32_e32 v140, v24, v25
	v_add_f32_e32 v141, v26, v27
	v_add_f32_e32 v140, v140, v141
	v_add_f32_e32 v133, v133, v140
	v_add_f32_e32 v140, v120, v121
	v_add_f32_e32 v141, v122, v123
	v_add_f32_e32 v140, v140, v141
	v_add_f32_e32 v141, v96, v97
	v_add_f32_e32 v142, v98, v99
	v_add_f32_e32 v140, 0, v140
	v_add_f32_e32 v141, v141, v142
	v_add_f32_e32 v140, v140, v141
	v_add_f32_e32 v141, v68, v69
	v_add_f32_e32 v142, v70, v71
	v_add_f32_e32 v141, v141, v142
	v_add_f32_e32 v140, v140, v141
	v_add_f32_e32 v141, v32, v33
	v_add_f32_e32 v142, v34, v35
	v_add_f32_e32 v141, v141, v142
	v_add_f32_e32 v140, v140, v141
	v_add_f32_e32 v141, v124, v125
	v_add_f32_e32 v142, v126, v127
	v_add_f32_e32 v141, v141, v142
	v_add_f32_e32 v143, v104, v105
	v_add_f32_e32 v144, v106, v107
	v_add_f32_e32 v141, 0, v141
	v_add_f32_e32 v143, v143, v144
	v_add_f32_e32 v141, v141, v143
	ds_swizzle_b32 v143, v129 offset:swizzle(SWAP,1)
	ds_swizzle_b32 v142, v128 offset:swizzle(SWAP,1)
	v_add_f32_e32 v144, v72, v73
	v_add_f32_e32 v145, v74, v75
	v_add_f32_e32 v144, v144, v145
	s_waitcnt lgkmcnt(1)
	v_add_f32_e32 v129, v129, v143
	ds_swizzle_b32 v143, v129 offset:swizzle(SWAP,2)
	s_waitcnt lgkmcnt(1)
	v_add_f32_e32 v128, v128, v142
	ds_swizzle_b32 v142, v128 offset:swizzle(SWAP,2)
	v_add_f32_e32 v141, v141, v144
	v_add_f32_e32 v144, v40, v41
	s_waitcnt lgkmcnt(1)
	v_add_f32_e32 v129, v129, v143
	ds_swizzle_b32 v143, v129 offset:swizzle(SWAP,4)
	s_waitcnt lgkmcnt(1)
	v_add_f32_e32 v128, v128, v142
	ds_swizzle_b32 v142, v128 offset:swizzle(SWAP,4)
	v_add_f32_e32 v145, v42, v43
	v_add_f32_e32 v144, v144, v145
	s_waitcnt lgkmcnt(1)
	v_add_f32_e32 v129, v129, v143
	ds_swizzle_b32 v143, v129 offset:swizzle(SWAP,8)
	s_waitcnt lgkmcnt(1)
	v_add_f32_e32 v128, v128, v142
	ds_swizzle_b32 v142, v128 offset:swizzle(SWAP,8)
	v_add_f32_e32 v141, v141, v144
	ds_swizzle_b32 v144, v130 offset:swizzle(SWAP,1)
	s_waitcnt lgkmcnt(2)
	v_add_f32_e32 v129, v129, v143
	ds_swizzle_b32 v143, v129 offset:swizzle(SWAP,16)
	s_waitcnt lgkmcnt(2)
	v_add_f32_e32 v128, v128, v142
	ds_swizzle_b32 v142, v128 offset:swizzle(SWAP,16)
	s_waitcnt lgkmcnt(2)
	v_add_f32_e32 v130, v130, v144
	ds_swizzle_b32 v144, v131 offset:swizzle(SWAP,1)
	s_waitcnt lgkmcnt(2)
	v_add_f32_e32 v129, v129, v143
	v_mov_b32_e32 v143, v129
	s_waitcnt lgkmcnt(1)
	v_add_f32_e32 v128, v128, v142
	v_permlane32_swap_b32_e32 v129, v143
	v_mov_b32_e32 v142, v128
	s_waitcnt lgkmcnt(0)
	v_add_f32_e32 v131, v131, v144
	v_add_f32_e32 v129, v129, v143
	ds_swizzle_b32 v143, v132 offset:swizzle(SWAP,1)
	v_permlane32_swap_b32_e32 v128, v142
	ds_swizzle_b32 v144, v131 offset:swizzle(SWAP,2)
	v_add_f32_e32 v128, v128, v142
	ds_swizzle_b32 v142, v130 offset:swizzle(SWAP,2)
	s_waitcnt lgkmcnt(2)
	v_add_f32_e32 v132, v132, v143
	ds_swizzle_b32 v143, v132 offset:swizzle(SWAP,2)
	s_waitcnt lgkmcnt(2)
	v_add_f32_e32 v131, v131, v144
	ds_swizzle_b32 v144, v131 offset:swizzle(SWAP,4)
	s_waitcnt lgkmcnt(2)
	v_add_f32_e32 v130, v130, v142
	ds_swizzle_b32 v142, v130 offset:swizzle(SWAP,4)
	s_waitcnt lgkmcnt(2)
	v_add_f32_e32 v132, v132, v143
	ds_swizzle_b32 v143, v132 offset:swizzle(SWAP,4)
	s_waitcnt lgkmcnt(2)
	v_add_f32_e32 v131, v131, v144
	ds_swizzle_b32 v144, v131 offset:swizzle(SWAP,8)
	s_waitcnt lgkmcnt(2)
	v_add_f32_e32 v130, v130, v142
	ds_swizzle_b32 v142, v130 offset:swizzle(SWAP,8)
	s_waitcnt lgkmcnt(2)
	v_add_f32_e32 v132, v132, v143
	ds_swizzle_b32 v143, v132 offset:swizzle(SWAP,8)
	s_waitcnt lgkmcnt(2)
	v_add_f32_e32 v131, v131, v144
	ds_swizzle_b32 v144, v131 offset:swizzle(SWAP,16)
	s_waitcnt lgkmcnt(2)
	v_add_f32_e32 v130, v130, v142
	ds_swizzle_b32 v142, v130 offset:swizzle(SWAP,16)
	s_waitcnt lgkmcnt(2)
	v_add_f32_e32 v132, v132, v143
	ds_swizzle_b32 v143, v132 offset:swizzle(SWAP,16)
	s_waitcnt lgkmcnt(2)
	v_add_f32_e32 v131, v131, v144
	ds_swizzle_b32 v144, v133 offset:swizzle(SWAP,1)
	s_waitcnt lgkmcnt(2)
	v_add_f32_e32 v130, v130, v142
	v_mov_b32_e32 v142, v130
	s_nop 1
	v_permlane32_swap_b32_e32 v130, v142
	v_add_f32_e32 v130, v130, v142
	v_mov_b32_e32 v142, v131
	s_nop 1
	v_permlane32_swap_b32_e32 v131, v142
	s_waitcnt lgkmcnt(1)
	v_add_f32_e32 v132, v132, v143
	s_waitcnt lgkmcnt(0)
	v_add_f32_e32 v133, v133, v144
	ds_swizzle_b32 v144, v140 offset:swizzle(SWAP,1)
	v_add_f32_e32 v131, v131, v142
	ds_swizzle_b32 v142, v133 offset:swizzle(SWAP,2)
	v_mov_b32_e32 v143, v132
	s_nop 1
	v_permlane32_swap_b32_e32 v132, v143
	v_add_f32_e32 v132, v132, v143
	ds_swizzle_b32 v143, v141 offset:swizzle(SWAP,1)
	s_waitcnt lgkmcnt(2)
	v_add_f32_e32 v140, v140, v144
	s_waitcnt lgkmcnt(1)
	v_add_f32_e32 v133, v133, v142
	ds_swizzle_b32 v144, v140 offset:swizzle(SWAP,2)
	ds_swizzle_b32 v142, v133 offset:swizzle(SWAP,4)
	s_waitcnt lgkmcnt(2)
	v_add_f32_e32 v141, v141, v143
	ds_swizzle_b32 v143, v141 offset:swizzle(SWAP,2)
	v_fmamk_f32 v87, v128, 0xba800000, v87
	s_waitcnt lgkmcnt(2)
	v_add_f32_e32 v140, v140, v144
	s_waitcnt lgkmcnt(1)
	v_add_f32_e32 v133, v133, v142
	ds_swizzle_b32 v144, v140 offset:swizzle(SWAP,4)
	ds_swizzle_b32 v142, v133 offset:swizzle(SWAP,8)
	s_waitcnt lgkmcnt(2)
	v_add_f32_e32 v141, v141, v143
	ds_swizzle_b32 v143, v141 offset:swizzle(SWAP,4)
	v_fmamk_f32 v85, v128, 0xba800000, v85
	s_waitcnt lgkmcnt(2)
	v_add_f32_e32 v140, v140, v144
	s_waitcnt lgkmcnt(1)
	v_add_f32_e32 v133, v133, v142
	ds_swizzle_b32 v144, v140 offset:swizzle(SWAP,8)
	ds_swizzle_b32 v142, v133 offset:swizzle(SWAP,16)
	s_waitcnt lgkmcnt(2)
	v_add_f32_e32 v141, v141, v143
	ds_swizzle_b32 v143, v141 offset:swizzle(SWAP,8)
	v_fmamk_f32 v86, v128, 0xba800000, v86
	s_waitcnt lgkmcnt(2)
	v_add_f32_e32 v140, v140, v144
	s_waitcnt lgkmcnt(1)
	v_add_f32_e32 v133, v133, v142
	ds_swizzle_b32 v144, v140 offset:swizzle(SWAP,16)
	v_mov_b32_e32 v142, v133
	s_nop 1
	v_permlane32_swap_b32_e32 v133, v142
	s_waitcnt lgkmcnt(1)
	v_add_f32_e32 v141, v141, v143
	v_add_f32_e32 v133, v133, v142
	ds_swizzle_b32 v142, v141 offset:swizzle(SWAP,16)
	s_waitcnt lgkmcnt(1)
	v_add_f32_e32 v140, v140, v144
	v_mov_b32_e32 v143, v140
	s_nop 1
	v_permlane32_swap_b32_e32 v140, v143
	v_add_f32_e32 v143, v140, v143
	s_waitcnt lgkmcnt(0)
	v_add_f32_e32 v140, v141, v142
	v_mov_b32_e32 v141, v140
	s_nop 1
	v_permlane32_swap_b32_e32 v140, v141
	v_add_f32_e32 v142, v140, v141
	v_fmac_f32_e32 v84, 0xba800000, v128
	v_mul_f32_e32 v140, v85, v85
	v_mul_f32_e32 v141, v87, v87
	v_fmac_f32_e32 v140, v84, v84
	v_fmac_f32_e32 v141, v86, v86
	v_fmamk_f32 v51, v128, 0xba800000, v51
	v_fmamk_f32 v49, v128, 0xba800000, v49
	v_add_f32_e32 v140, v140, v141
	v_fmamk_f32 v50, v128, 0xba800000, v50
	v_fmac_f32_e32 v48, 0xba800000, v128
	v_mul_f32_e32 v141, v49, v49
	v_mul_f32_e32 v144, v51, v51
	v_fmac_f32_e32 v141, v48, v48
	v_fmac_f32_e32 v144, v50, v50
	v_add_f32_e32 v141, v141, v144
	v_fmamk_f32 v23, v128, 0xba800000, v23
	v_fmamk_f32 v21, v128, 0xba800000, v21
	v_add_f32_e32 v140, v140, v141
	v_fmamk_f32 v22, v128, 0xba800000, v22
	v_fmac_f32_e32 v20, 0xba800000, v128
	v_mul_f32_e32 v141, v21, v21
	v_mul_f32_e32 v144, v23, v23
	v_fmac_f32_e32 v141, v20, v20
	v_fmac_f32_e32 v144, v22, v22
	v_add_f32_e32 v141, v141, v144
	v_fmamk_f32 v3, v128, 0xba800000, v3
	v_fmamk_f32 v1, v128, 0xba800000, v1
	v_add_f32_e32 v140, v141, v140
	v_fmamk_f32 v2, v128, 0xba800000, v2
	v_fmac_f32_e32 v0, 0xba800000, v128
	v_mul_f32_e32 v128, v1, v1
	v_mul_f32_e32 v141, v3, v3
	v_fmac_f32_e32 v128, v0, v0
	v_fmac_f32_e32 v141, v2, v2
	v_add_f32_e32 v128, v128, v141
	v_fmamk_f32 v95, v129, 0xba800000, v95
	v_fmamk_f32 v93, v129, 0xba800000, v93
	v_add_f32_e32 v128, v128, v140
	v_fmamk_f32 v94, v129, 0xba800000, v94
	v_fmac_f32_e32 v92, 0xba800000, v129
	v_mul_f32_e32 v140, v93, v93
	v_mul_f32_e32 v141, v95, v95
	v_fmac_f32_e32 v140, v92, v92
	v_fmac_f32_e32 v141, v94, v94
	v_fmamk_f32 v59, v129, 0xba800000, v59
	v_fmamk_f32 v57, v129, 0xba800000, v57
	v_add_f32_e32 v140, v140, v141
	v_fmamk_f32 v58, v129, 0xba800000, v58
	v_fmac_f32_e32 v56, 0xba800000, v129
	v_mul_f32_e32 v141, v57, v57
	v_mul_f32_e32 v144, v59, v59
	v_fmac_f32_e32 v141, v56, v56
	v_fmac_f32_e32 v144, v58, v58
	v_add_f32_e32 v141, v141, v144
	v_fmamk_f32 v31, v129, 0xba800000, v31
	v_fmamk_f32 v29, v129, 0xba800000, v29
	v_add_f32_e32 v140, v140, v141
	v_fmamk_f32 v30, v129, 0xba800000, v30
	v_fmac_f32_e32 v28, 0xba800000, v129
	v_mul_f32_e32 v141, v29, v29
	v_mul_f32_e32 v144, v31, v31
	v_fmac_f32_e32 v141, v28, v28
	v_fmac_f32_e32 v144, v30, v30
	v_add_f32_e32 v141, v141, v144
	v_fmamk_f32 v7, v129, 0xba800000, v7
	v_fmamk_f32 v5, v129, 0xba800000, v5
	v_add_f32_e32 v140, v141, v140
	v_fmamk_f32 v6, v129, 0xba800000, v6
	v_fmac_f32_e32 v4, 0xba800000, v129
	v_mul_f32_e32 v129, v5, v5
	v_mul_f32_e32 v141, v7, v7
	v_fmac_f32_e32 v129, v4, v4
	v_fmac_f32_e32 v141, v6, v6
	v_add_f32_e32 v129, v129, v141
	v_fmamk_f32 v103, v130, 0xba800000, v103
	v_fmamk_f32 v101, v130, 0xba800000, v101
	v_add_f32_e32 v129, v129, v140
	v_fmamk_f32 v102, v130, 0xba800000, v102
	v_fmac_f32_e32 v100, 0xba800000, v130
	v_mul_f32_e32 v140, v101, v101
	v_mul_f32_e32 v141, v103, v103
	v_fmac_f32_e32 v140, v100, v100
	v_fmac_f32_e32 v141, v102, v102
	v_fmamk_f32 v67, v130, 0xba800000, v67
	v_fmamk_f32 v65, v130, 0xba800000, v65
	v_add_f32_e32 v140, v140, v141
	v_fmamk_f32 v66, v130, 0xba800000, v66
	v_fmac_f32_e32 v64, 0xba800000, v130
	v_mul_f32_e32 v141, v65, v65
	v_mul_f32_e32 v144, v67, v67
	v_fmac_f32_e32 v141, v64, v64
	v_fmac_f32_e32 v144, v66, v66
	v_add_f32_e32 v141, v141, v144
	v_fmamk_f32 v39, v130, 0xba800000, v39
	v_fmamk_f32 v37, v130, 0xba800000, v37
	v_add_f32_e32 v140, v140, v141
	v_fmamk_f32 v38, v130, 0xba800000, v38
	v_fmac_f32_e32 v36, 0xba800000, v130
	v_mul_f32_e32 v141, v37, v37
	v_mul_f32_e32 v144, v39, v39
	v_fmac_f32_e32 v141, v36, v36
	v_fmac_f32_e32 v144, v38, v38
	v_add_f32_e32 v141, v141, v144
	v_fmamk_f32 v11, v130, 0xba800000, v11
	v_fmamk_f32 v9, v130, 0xba800000, v9
	v_add_f32_e32 v140, v141, v140
	v_fmamk_f32 v10, v130, 0xba800000, v10
	v_fmac_f32_e32 v8, 0xba800000, v130
	v_mul_f32_e32 v130, v9, v9
	v_mul_f32_e32 v141, v11, v11
	v_fmac_f32_e32 v130, v8, v8
	v_fmac_f32_e32 v141, v10, v10
	v_add_f32_e32 v130, v130, v141
	v_fmamk_f32 v111, v131, 0xba800000, v111
	v_fmamk_f32 v109, v131, 0xba800000, v109
	v_add_f32_e32 v130, v130, v140
	v_fmamk_f32 v110, v131, 0xba800000, v110
	v_fmac_f32_e32 v108, 0xba800000, v131
	v_mul_f32_e32 v140, v109, v109
	v_mul_f32_e32 v141, v111, v111
	v_fmac_f32_e32 v140, v108, v108
	v_fmac_f32_e32 v141, v110, v110
	v_fmamk_f32 v79, v131, 0xba800000, v79
	v_fmamk_f32 v77, v131, 0xba800000, v77
	v_add_f32_e32 v140, v140, v141
	v_fmamk_f32 v78, v131, 0xba800000, v78
	v_fmac_f32_e32 v76, 0xba800000, v131
	v_mul_f32_e32 v141, v77, v77
	v_mul_f32_e32 v144, v79, v79
	v_fmac_f32_e32 v141, v76, v76
	v_fmac_f32_e32 v144, v78, v78
	v_add_f32_e32 v141, v141, v144
	v_fmamk_f32 v47, v131, 0xba800000, v47
	v_fmamk_f32 v45, v131, 0xba800000, v45
	v_add_f32_e32 v140, v140, v141
	v_fmamk_f32 v46, v131, 0xba800000, v46
	v_fmac_f32_e32 v44, 0xba800000, v131
	v_mul_f32_e32 v141, v45, v45
	v_mul_f32_e32 v144, v47, v47
	v_fmac_f32_e32 v141, v44, v44
	v_fmac_f32_e32 v144, v46, v46
	v_add_f32_e32 v141, v141, v144
	v_fmamk_f32 v15, v131, 0xba800000, v15
	v_fmamk_f32 v13, v131, 0xba800000, v13
	v_add_f32_e32 v140, v141, v140
	v_fmamk_f32 v14, v131, 0xba800000, v14
	v_fmac_f32_e32 v12, 0xba800000, v131
	v_mul_f32_e32 v131, v13, v13
	v_mul_f32_e32 v141, v15, v15
	v_fmac_f32_e32 v131, v12, v12
	v_fmac_f32_e32 v141, v14, v14
	v_add_f32_e32 v131, v131, v141
	v_fmamk_f32 v115, v132, 0xba800000, v115
	v_fmamk_f32 v113, v132, 0xba800000, v113
	v_add_f32_e32 v131, v131, v140
	v_fmamk_f32 v114, v132, 0xba800000, v114
	v_fmac_f32_e32 v112, 0xba800000, v132
	v_mul_f32_e32 v140, v113, v113
	v_mul_f32_e32 v141, v115, v115
	v_fmac_f32_e32 v140, v112, v112
	v_fmac_f32_e32 v141, v114, v114
	v_fmamk_f32 v83, v132, 0xba800000, v83
	v_fmamk_f32 v81, v132, 0xba800000, v81
	v_add_f32_e32 v140, v140, v141
	v_fmamk_f32 v82, v132, 0xba800000, v82
	v_fmac_f32_e32 v80, 0xba800000, v132
	v_mul_f32_e32 v141, v81, v81
	v_mul_f32_e32 v144, v83, v83
	v_fmac_f32_e32 v141, v80, v80
	v_fmac_f32_e32 v144, v82, v82
	v_add_f32_e32 v141, v141, v144
	v_fmamk_f32 v55, v132, 0xba800000, v55
	v_fmamk_f32 v53, v132, 0xba800000, v53
	v_add_f32_e32 v140, v140, v141
	v_fmamk_f32 v54, v132, 0xba800000, v54
	v_fmac_f32_e32 v52, 0xba800000, v132
	v_mul_f32_e32 v141, v53, v53
	v_mul_f32_e32 v144, v55, v55
	v_fmac_f32_e32 v141, v52, v52
	v_fmac_f32_e32 v144, v54, v54
	v_add_f32_e32 v141, v141, v144
	v_fmamk_f32 v19, v132, 0xba800000, v19
	v_fmamk_f32 v17, v132, 0xba800000, v17
	v_add_f32_e32 v140, v141, v140
	v_fmamk_f32 v18, v132, 0xba800000, v18
	v_fmac_f32_e32 v16, 0xba800000, v132
	v_mul_f32_e32 v132, v17, v17
	v_mul_f32_e32 v141, v19, v19
	v_fmac_f32_e32 v132, v16, v16
	v_fmac_f32_e32 v141, v18, v18
	v_add_f32_e32 v132, v132, v141
	v_fmamk_f32 v141, v133, 0xba800000, v119
	v_fmamk_f32 v117, v133, 0xba800000, v117
	v_add_f32_e32 v132, v132, v140
	v_fmamk_f32 v140, v133, 0xba800000, v118
	v_fmac_f32_e32 v116, 0xba800000, v133
	v_mul_f32_e32 v118, v117, v117
	v_mul_f32_e32 v119, v141, v141
	v_fmac_f32_e32 v118, v116, v116
	v_fmac_f32_e32 v119, v140, v140
	v_fmamk_f32 v91, v133, 0xba800000, v91
	v_fmamk_f32 v89, v133, 0xba800000, v89
	v_add_f32_e32 v118, v118, v119
	v_fmamk_f32 v90, v133, 0xba800000, v90
	v_fmac_f32_e32 v88, 0xba800000, v133
	v_mul_f32_e32 v119, v89, v89
	v_mul_f32_e32 v144, v91, v91
	v_fmac_f32_e32 v119, v88, v88
	v_fmac_f32_e32 v144, v90, v90
	v_add_f32_e32 v119, v119, v144
	v_fmamk_f32 v63, v133, 0xba800000, v63
	v_fmamk_f32 v61, v133, 0xba800000, v61
	v_add_f32_e32 v118, v118, v119
	v_fmamk_f32 v62, v133, 0xba800000, v62
	v_fmac_f32_e32 v60, 0xba800000, v133
	v_mul_f32_e32 v119, v61, v61
	v_mul_f32_e32 v144, v63, v63
	v_fmac_f32_e32 v119, v60, v60
	v_fmac_f32_e32 v144, v62, v62
	v_add_f32_e32 v119, v119, v144
	v_fmamk_f32 v27, v133, 0xba800000, v27
	v_fmamk_f32 v25, v133, 0xba800000, v25
	v_add_f32_e32 v118, v119, v118
	v_fmamk_f32 v26, v133, 0xba800000, v26
	v_fmac_f32_e32 v24, 0xba800000, v133
	v_mul_f32_e32 v119, v25, v25
	v_mul_f32_e32 v133, v27, v27
	v_fmac_f32_e32 v119, v24, v24
	v_fmac_f32_e32 v133, v26, v26
	v_add_f32_e32 v119, v119, v133
	v_fmamk_f32 v153, v143, 0xba800000, v123
	v_fmamk_f32 v121, v143, 0xba800000, v121
	v_add_f32_e32 v118, v119, v118
	v_fmamk_f32 v152, v143, 0xba800000, v122
	v_fmac_f32_e32 v120, 0xba800000, v143
	v_mul_f32_e32 v119, v121, v121
	v_mul_f32_e32 v122, v153, v153
	v_fmac_f32_e32 v119, v120, v120
	v_fmac_f32_e32 v122, v152, v152
	v_fmamk_f32 v99, v143, 0xba800000, v99
	v_fmamk_f32 v97, v143, 0xba800000, v97
	v_add_f32_e32 v119, v119, v122
	v_fmamk_f32 v98, v143, 0xba800000, v98
	v_fmac_f32_e32 v96, 0xba800000, v143
	v_mul_f32_e32 v122, v97, v97
	v_mul_f32_e32 v123, v99, v99
	v_fmac_f32_e32 v122, v96, v96
	v_fmac_f32_e32 v123, v98, v98
	v_add_f32_e32 v122, v122, v123
	v_fmamk_f32 v71, v143, 0xba800000, v71
	v_fmamk_f32 v69, v143, 0xba800000, v69
	v_add_f32_e32 v119, v119, v122
	v_fmamk_f32 v70, v143, 0xba800000, v70
	v_fmac_f32_e32 v68, 0xba800000, v143
	v_mul_f32_e32 v122, v69, v69
	v_mul_f32_e32 v123, v71, v71
	v_fmac_f32_e32 v122, v68, v68
	v_fmac_f32_e32 v123, v70, v70
	v_add_f32_e32 v122, v122, v123
	v_fmamk_f32 v35, v143, 0xba800000, v35
	v_fmamk_f32 v33, v143, 0xba800000, v33
	v_add_f32_e32 v119, v122, v119
	v_fmamk_f32 v34, v143, 0xba800000, v34
	v_fmac_f32_e32 v32, 0xba800000, v143
	v_mul_f32_e32 v122, v33, v33
	v_mul_f32_e32 v123, v35, v35
	v_fmac_f32_e32 v122, v32, v32
	v_fmac_f32_e32 v123, v34, v34
	v_add_f32_e32 v122, v122, v123
	v_fmamk_f32 v155, v142, 0xba800000, v127
	v_fmamk_f32 v125, v142, 0xba800000, v125
	v_add_f32_e32 v119, v122, v119
	v_fmamk_f32 v154, v142, 0xba800000, v126
	v_fmac_f32_e32 v124, 0xba800000, v142
	v_mul_f32_e32 v122, v125, v125
	v_mul_f32_e32 v123, v155, v155
	v_fmac_f32_e32 v122, v124, v124
	v_fmac_f32_e32 v123, v154, v154
	v_fmamk_f32 v107, v142, 0xba800000, v107
	v_fmamk_f32 v105, v142, 0xba800000, v105
	v_add_f32_e32 v122, v122, v123
	v_fmamk_f32 v106, v142, 0xba800000, v106
	v_fmac_f32_e32 v104, 0xba800000, v142
	v_mul_f32_e32 v123, v105, v105
	v_mul_f32_e32 v126, v107, v107
	v_fmac_f32_e32 v123, v104, v104
	v_fmac_f32_e32 v126, v106, v106
	ds_swizzle_b32 v127, v128 offset:swizzle(SWAP,1)
	v_add_f32_e32 v123, v123, v126
	v_fmamk_f32 v75, v142, 0xba800000, v75
	v_fmamk_f32 v73, v142, 0xba800000, v73
	v_add_f32_e32 v122, v122, v123
	v_fmamk_f32 v74, v142, 0xba800000, v74
	v_fmac_f32_e32 v72, 0xba800000, v142
	v_mul_f32_e32 v123, v73, v73
	v_mul_f32_e32 v126, v75, v75
	v_fmac_f32_e32 v123, v72, v72
	v_fmac_f32_e32 v126, v74, v74
	v_add_f32_e32 v123, v123, v126
	v_add_f32_e32 v122, v123, v122
	s_waitcnt lgkmcnt(0)
	v_add_f32_e32 v123, v128, v127
	ds_swizzle_b32 v126, v123 offset:swizzle(SWAP,2)
	ds_swizzle_b32 v127, v129 offset:swizzle(SWAP,1)
	v_fmamk_f32 v43, v142, 0xba800000, v43
	v_fmamk_f32 v41, v142, 0xba800000, v41
	v_fmamk_f32 v42, v142, 0xba800000, v42
	s_waitcnt lgkmcnt(1)
	v_add_f32_e32 v123, v123, v126
	s_waitcnt lgkmcnt(0)
	v_add_f32_e32 v127, v129, v127
	ds_swizzle_b32 v126, v123 offset:swizzle(SWAP,4)
	ds_swizzle_b32 v129, v127 offset:swizzle(SWAP,2)
	v_fmac_f32_e32 v40, 0xba800000, v142
	v_mul_f32_e32 v128, v41, v41
	v_mul_f32_e32 v133, v43, v43
	s_waitcnt lgkmcnt(1)
	v_add_f32_e32 v123, v123, v126
	s_waitcnt lgkmcnt(0)
	v_add_f32_e32 v127, v127, v129
	ds_swizzle_b32 v126, v123 offset:swizzle(SWAP,8)
	ds_swizzle_b32 v129, v127 offset:swizzle(SWAP,4)
	v_fmac_f32_e32 v128, v40, v40
	v_fmac_f32_e32 v133, v42, v42
	v_add_f32_e32 v128, v128, v133
	s_waitcnt lgkmcnt(1)
	v_add_f32_e32 v123, v123, v126
	s_waitcnt lgkmcnt(0)
	v_add_f32_e32 v129, v127, v129
	ds_swizzle_b32 v126, v123 offset:swizzle(SWAP,16)
	ds_swizzle_b32 v133, v129 offset:swizzle(SWAP,8)
	v_add_f32_e32 v122, v128, v122
	ds_swizzle_b32 v128, v130 offset:swizzle(SWAP,1)
	s_andn2_b64 vcc, exec, s[16:17]
	s_waitcnt lgkmcnt(2)
	v_add_f32_e32 v126, v123, v126
	s_waitcnt lgkmcnt(1)
	v_add_f32_e32 v123, v129, v133
	ds_swizzle_b32 v129, v123 offset:swizzle(SWAP,16)
	s_waitcnt lgkmcnt(1)
	v_add_f32_e32 v128, v130, v128
	ds_swizzle_b32 v130, v128 offset:swizzle(SWAP,2)
	ds_swizzle_b32 v133, v131 offset:swizzle(SWAP,1)
	v_mov_b32_e32 v127, v126
	s_waitcnt lgkmcnt(2)
	v_add_f32_e32 v209, v123, v129
	v_mov_b32_e32 v211, v209
	s_waitcnt lgkmcnt(1)
	v_add_f32_e32 v123, v128, v130
	s_waitcnt lgkmcnt(0)
	v_add_f32_e32 v129, v131, v133
	ds_swizzle_b32 v128, v123 offset:swizzle(SWAP,4)
	ds_swizzle_b32 v130, v129 offset:swizzle(SWAP,2)
	ds_swizzle_b32 v131, v132 offset:swizzle(SWAP,1)
	v_permlane32_swap_b32_e32 v126, v127
	s_waitcnt lgkmcnt(2)
	v_add_f32_e32 v123, v123, v128
	s_waitcnt lgkmcnt(1)
	v_add_f32_e32 v129, v129, v130
	s_waitcnt lgkmcnt(0)
	v_add_f32_e32 v131, v132, v131
	ds_swizzle_b32 v128, v123 offset:swizzle(SWAP,8)
	ds_swizzle_b32 v130, v129 offset:swizzle(SWAP,4)
	ds_swizzle_b32 v132, v131 offset:swizzle(SWAP,2)
	v_permlane32_swap_b32_e32 v209, v211
	s_waitcnt lgkmcnt(2)
	v_add_f32_e32 v123, v123, v128
	s_waitcnt lgkmcnt(1)
	v_add_f32_e32 v129, v129, v130
	s_waitcnt lgkmcnt(0)
	v_add_f32_e32 v131, v131, v132
	ds_swizzle_b32 v128, v123 offset:swizzle(SWAP,16)
	ds_swizzle_b32 v130, v129 offset:swizzle(SWAP,8)
	ds_swizzle_b32 v132, v131 offset:swizzle(SWAP,4)
	s_waitcnt lgkmcnt(2)
	v_add_f32_e32 v213, v123, v128
	s_waitcnt lgkmcnt(1)
	v_add_f32_e32 v123, v129, v130
	s_waitcnt lgkmcnt(0)
	v_add_f32_e32 v129, v131, v132
	ds_swizzle_b32 v131, v118 offset:swizzle(SWAP,1)
	ds_swizzle_b32 v128, v123 offset:swizzle(SWAP,16)
	ds_swizzle_b32 v130, v129 offset:swizzle(SWAP,8)
	v_mov_b32_e32 v215, v213
	s_nop 1
	v_permlane32_swap_b32_e32 v213, v215
	s_waitcnt lgkmcnt(2)
	v_add_f32_e32 v118, v118, v131
	s_waitcnt lgkmcnt(1)
	v_add_f32_e32 v214, v123, v128
	s_waitcnt lgkmcnt(0)
	v_add_f32_e32 v123, v129, v130
	ds_swizzle_b32 v129, v118 offset:swizzle(SWAP,2)
	ds_swizzle_b32 v128, v123 offset:swizzle(SWAP,16)
	v_mov_b32_e32 v216, v214
	s_nop 1
	v_permlane32_swap_b32_e32 v214, v216
	s_waitcnt lgkmcnt(1)
	v_add_f32_e32 v118, v118, v129
	s_waitcnt lgkmcnt(0)
	v_add_f32_e32 v212, v123, v128
	ds_swizzle_b32 v123, v119 offset:swizzle(SWAP,1)
	ds_swizzle_b32 v128, v118 offset:swizzle(SWAP,4)
	ds_swizzle_b32 v129, v122 offset:swizzle(SWAP,1)
	v_mov_b32_e32 v217, v212
	s_nop 1
	v_permlane32_swap_b32_e32 v212, v217
	s_waitcnt lgkmcnt(2)
	v_add_f32_e32 v119, v119, v123
	s_waitcnt lgkmcnt(1)
	v_add_f32_e32 v118, v118, v128
	s_waitcnt lgkmcnt(0)
	v_add_f32_e32 v122, v122, v129
	ds_swizzle_b32 v123, v119 offset:swizzle(SWAP,2)
	ds_swizzle_b32 v128, v118 offset:swizzle(SWAP,8)
	ds_swizzle_b32 v129, v122 offset:swizzle(SWAP,2)
	s_waitcnt lgkmcnt(2)
	v_add_f32_e32 v119, v119, v123
	s_waitcnt lgkmcnt(1)
	v_add_f32_e32 v118, v118, v128
	s_waitcnt lgkmcnt(0)
	v_add_f32_e32 v122, v122, v129
	ds_swizzle_b32 v123, v119 offset:swizzle(SWAP,4)
	ds_swizzle_b32 v128, v118 offset:swizzle(SWAP,16)
	ds_swizzle_b32 v129, v122 offset:swizzle(SWAP,4)
	s_waitcnt lgkmcnt(2)
	v_add_f32_e32 v119, v119, v123
	s_waitcnt lgkmcnt(1)
	v_add_f32_e32 v210, v118, v128
	s_waitcnt lgkmcnt(0)
	v_add_f32_e32 v118, v122, v129
	ds_swizzle_b32 v123, v119 offset:swizzle(SWAP,8)
	ds_swizzle_b32 v122, v118 offset:swizzle(SWAP,8)
	v_mov_b32_e32 v218, v210
	s_nop 1
	v_permlane32_swap_b32_e32 v210, v218
	s_waitcnt lgkmcnt(1)
	v_add_f32_e32 v119, v119, v123
	s_waitcnt lgkmcnt(0)
	v_add_f32_e32 v118, v118, v122
	ds_swizzle_b32 v123, v119 offset:swizzle(SWAP,16)
	ds_swizzle_b32 v122, v118 offset:swizzle(SWAP,16)
	s_waitcnt lgkmcnt(1)
	v_add_f32_e32 v208, v119, v123
	s_waitcnt lgkmcnt(0)
	v_add_f32_e32 v190, v118, v122
	v_mov_b32_e32 v219, v208
	v_mov_b32_e32 v220, v190
	s_nop 0
	v_permlane32_swap_b32_e32 v208, v219
	v_permlane32_swap_b32_e32 v190, v220
	s_cbranch_vccnz .LBB0_1551
	s_movk_i32 s6, 0x8400
	s_mov_b32 s7, -1
	v_lshl_add_u64 v[192:193], v[138:139], 0, s[6:7]
	s_movk_i32 s6, 0x8800
	s_mov_b32 s7, -1
	v_lshl_add_u64 v[172:173], v[138:139], 0, s[6:7]
	s_movk_i32 s6, 0x8c00
	s_mov_b32 s7, -1
	v_lshl_add_u64 v[156:157], v[138:139], 0, s[6:7]
	s_movk_i32 s6, 0x9000
	s_mov_b32 s7, -1
	v_lshl_add_u64 v[118:119], v[138:139], 0, s[6:7]
	s_movk_i32 s6, 0x9400
	s_mov_b32 s7, -1
	v_lshl_add_u64 v[194:195], v[138:139], 0, s[6:7]
	s_movk_i32 s6, 0x9800
	s_mov_b32 s7, -1
	v_lshl_add_u64 v[174:175], v[138:139], 0, s[6:7]
	s_movk_i32 s6, 0x9c00
	s_mov_b32 s7, -1
	v_lshl_add_u64 v[158:159], v[138:139], 0, s[6:7]
	s_movk_i32 s6, 0xa000
	s_mov_b32 s7, -1
	v_lshl_add_u64 v[122:123], v[138:139], 0, s[6:7]
	s_movk_i32 s6, 0xa400
	s_mov_b32 s7, -1
	v_lshl_add_u64 v[198:199], v[138:139], 0, s[6:7]
	s_movk_i32 s6, 0xa800
	s_mov_b32 s7, -1
	v_lshl_add_u64 v[176:177], v[138:139], 0, s[6:7]
	s_movk_i32 s6, 0xac00
	s_mov_b32 s7, -1
	v_lshl_add_u64 v[160:161], v[138:139], 0, s[6:7]
	s_movk_i32 s6, 0xb000
	s_mov_b32 s7, -1
	v_lshl_add_u64 v[142:143], v[138:139], 0, s[6:7]
	s_movk_i32 s6, 0xb400
	s_mov_b32 s7, -1
	v_lshl_add_u64 v[200:201], v[138:139], 0, s[6:7]
	s_movk_i32 s6, 0xb800
	s_mov_b32 s7, -1
	v_lshl_add_u64 v[178:179], v[138:139], 0, s[6:7]
	s_movk_i32 s6, 0xbc00
	s_mov_b32 s7, -1
	v_lshl_add_u64 v[162:163], v[138:139], 0, s[6:7]
	s_movk_i32 s6, 0xc000
	s_mov_b32 s7, -1
	v_lshl_add_u64 v[144:145], v[138:139], 0, s[6:7]
	s_movk_i32 s6, 0xc400
	s_mov_b32 s7, -1
	v_lshl_add_u64 v[204:205], v[138:139], 0, s[6:7]
	s_movk_i32 s6, 0xc800
	s_mov_b32 s7, -1
	v_lshl_add_u64 v[182:183], v[138:139], 0, s[6:7]
	s_movk_i32 s6, 0xcc00
	s_mov_b32 s7, -1
	v_lshl_add_u64 v[166:167], v[138:139], 0, s[6:7]
	s_movk_i32 s6, 0xd000
	s_mov_b32 s7, -1
	v_lshl_add_u64 v[146:147], v[138:139], 0, s[6:7]
	s_movk_i32 s6, 0xd400
	s_mov_b32 s7, -1
	v_lshl_add_u64 v[206:207], v[138:139], 0, s[6:7]
	s_movk_i32 s6, 0xd800
	s_mov_b32 s7, -1
	v_lshl_add_u64 v[186:187], v[138:139], 0, s[6:7]
	s_movk_i32 s6, 0xdc00
	s_mov_b32 s7, -1
	v_lshl_add_u64 v[170:171], v[138:139], 0, s[6:7]
	s_movk_i32 s6, 0xe000
	s_mov_b32 s7, -1
	v_lshl_add_u64 v[150:151], v[138:139], 0, s[6:7]
	s_movk_i32 s6, 0xe400
	s_mov_b32 s7, -1
	v_lshl_add_u64 v[202:203], v[138:139], 0, s[6:7]
	s_movk_i32 s6, 0xe800
	s_mov_b32 s7, -1
	v_lshl_add_u64 v[184:185], v[138:139], 0, s[6:7]
	s_movk_i32 s6, 0xec00
	v_add_f32_e32 v126, v126, v127
	s_mov_b32 s7, -1
	v_fmamk_f32 v126, v126, 0x3a800000, v243
	v_lshl_add_u64 v[168:169], v[138:139], 0, s[6:7]
	s_movk_i32 s6, 0xf000
	v_cmp_gt_f32_e32 vcc, s84, v126
	v_mul_f32_e32 v127, 0x4f800000, v126
	s_mov_b32 s7, -1
	v_cndmask_b32_e32 v126, v126, v127, vcc
	v_lshl_add_u64 v[148:149], v[138:139], 0, s[6:7]
	s_movk_i32 s6, 0xf400
	v_sqrt_f32_e32 v127, v126
	s_mov_b32 s7, -1
	v_lshl_add_u64 v[196:197], v[138:139], 0, s[6:7]
	s_movk_i32 s6, 0xf800
	s_mov_b32 s7, -1
	v_lshl_add_u64 v[180:181], v[138:139], 0, s[6:7]
	s_movk_i32 s6, 0xfc00
	v_add_u32_e32 v128, -1, v127
	s_mov_b32 s7, -1
	v_fma_f32 v129, -v128, v127, v126
	v_lshl_add_u64 v[164:165], v[138:139], 0, s[6:7]
	v_cmp_ge_f32_e64 s[6:7], 0, v129
	v_add_u32_e32 v129, 1, v127
	v_add_f32_e32 v190, v190, v220
	v_cndmask_b32_e64 v128, v127, v128, s[6:7]
	v_fma_f32 v127, -v129, v127, v126
	v_cmp_lt_f32_e64 s[6:7], 0, v127
	v_fmamk_f32 v190, v190, 0x3a800000, v243
	v_mul_f32_e32 v220, 0x4f800000, v190
	v_cndmask_b32_e64 v127, v128, v129, s[6:7]
	v_mul_f32_e32 v128, 0x37800000, v127
	v_cndmask_b32_e32 v127, v127, v128, vcc
	v_cmp_class_f32_e32 vcc, v126, v248
	v_add_f32_e32 v208, v208, v219
	v_fmamk_f32 v208, v208, 0x3a800000, v243
	v_cndmask_b32_e32 v126, v127, v126, vcc
	v_div_scale_f32 v127, s[6:7], v126, v126, 1.0
	v_rcp_f32_e32 v128, v127
	v_mul_f32_e32 v219, 0x4f800000, v208
	v_add_f32_e32 v210, v210, v218
	v_fmamk_f32 v210, v210, 0x3a800000, v243
	v_fma_f32 v129, -v127, v128, 1.0
	v_fmac_f32_e32 v128, v129, v128
	v_div_scale_f32 v129, vcc, 1.0, v126, 1.0
	v_mul_f32_e32 v130, v129, v128
	v_fma_f32 v131, -v127, v130, v129
	v_fmac_f32_e32 v130, v131, v128
	v_fma_f32 v127, -v127, v130, v129
	v_div_fmas_f32 v127, v127, v128, v130
	v_cmp_gt_f32_e32 vcc, s84, v190
	v_mul_f32_e32 v218, 0x4f800000, v210
	v_add_f32_e32 v212, v212, v217
	v_cndmask_b32_e32 v190, v190, v220, vcc
	v_sqrt_f32_e32 v220, v190
	v_fmamk_f32 v212, v212, 0x3a800000, v243
	v_mul_f32_e32 v217, 0x4f800000, v212
	v_add_f32_e32 v214, v214, v216
	v_add_u32_e32 v221, -1, v220
	v_fma_f32 v222, -v221, v220, v190
	v_cmp_ge_f32_e64 s[6:7], 0, v222
	v_add_u32_e32 v222, 1, v220
	v_div_fixup_f32 v188, v127, v126, 1.0
	v_cndmask_b32_e64 v221, v220, v221, s[6:7]
	v_fma_f32 v220, -v222, v220, v190
	v_cmp_lt_f32_e64 s[6:7], 0, v220
	global_load_dwordx4 v[126:129], v[136:137], off
	global_load_dwordx4 v[130:133], v[134:135], off
	v_cndmask_b32_e64 v220, v221, v222, s[6:7]
	v_mul_f32_e32 v221, 0x37800000, v220
	v_cndmask_b32_e32 v220, v220, v221, vcc
	v_cmp_class_f32_e32 vcc, v190, v248
	v_fmamk_f32 v214, v214, 0x3a800000, v243
	v_mul_f32_e32 v216, 0x4f800000, v214
	v_cndmask_b32_e32 v190, v220, v190, vcc
	v_div_scale_f32 v220, s[6:7], v190, v190, 1.0
	v_rcp_f32_e32 v221, v220
	v_add_f32_e32 v213, v213, v215
	v_fmamk_f32 v213, v213, 0x3a800000, v243
	v_mul_f32_e32 v215, 0x4f800000, v213
	v_fma_f32 v222, -v220, v221, 1.0
	v_fmac_f32_e32 v221, v222, v221
	v_div_scale_f32 v222, vcc, 1.0, v190, 1.0
	v_mul_f32_e32 v223, v222, v221
	v_fma_f32 v224, -v220, v223, v222
	v_fmac_f32_e32 v223, v224, v221
	v_fma_f32 v220, -v220, v223, v222
	v_div_fmas_f32 v220, v220, v221, v223
	v_cmp_gt_f32_e32 vcc, s84, v208
	v_div_fixup_f32 v190, v220, v190, 1.0
	v_add_f32_e32 v209, v209, v211
	v_cndmask_b32_e32 v208, v208, v219, vcc
	v_sqrt_f32_e32 v219, v208
	v_fmamk_f32 v209, v209, 0x3a800000, v243
	v_mul_f32_e32 v211, 0x4f800000, v209
	v_pk_mul_f32 v[84:85], v[84:85], v[188:189] op_sel_hi:[1,0]
	v_add_u32_e32 v220, -1, v219
	v_fma_f32 v221, -v220, v219, v208
	v_cmp_ge_f32_e64 s[6:7], 0, v221
	v_add_u32_e32 v221, 1, v219
	v_pk_mul_f32 v[86:87], v[86:87], v[188:189] op_sel_hi:[1,0]
	v_cndmask_b32_e64 v220, v219, v220, s[6:7]
	v_fma_f32 v219, -v221, v219, v208
	v_cmp_lt_f32_e64 s[6:7], 0, v219
	v_pk_mul_f32 v[50:51], v[50:51], v[188:189] op_sel_hi:[1,0]
	v_pk_mul_f32 v[48:49], v[48:49], v[188:189] op_sel_hi:[1,0]
	v_cndmask_b32_e64 v219, v220, v221, s[6:7]
	v_mul_f32_e32 v220, 0x37800000, v219
	v_cndmask_b32_e32 v219, v219, v220, vcc
	v_cmp_class_f32_e32 vcc, v208, v248
	v_pk_mul_f32 v[22:23], v[22:23], v[188:189] op_sel_hi:[1,0]
	v_pk_mul_f32 v[20:21], v[20:21], v[188:189] op_sel_hi:[1,0]
	v_cndmask_b32_e32 v208, v219, v208, vcc
	v_div_scale_f32 v219, s[6:7], v208, v208, 1.0
	v_rcp_f32_e32 v220, v219
	v_pk_mul_f32 v[2:3], v[2:3], v[188:189] op_sel_hi:[1,0]
	v_pk_mul_f32 v[0:1], v[0:1], v[188:189] op_sel_hi:[1,0]
	v_fma_f32 v221, -v219, v220, 1.0
	v_fmac_f32_e32 v220, v221, v220
	v_div_scale_f32 v221, vcc, 1.0, v208, 1.0
	v_mul_f32_e32 v222, v221, v220
	v_fma_f32 v223, -v219, v222, v221
	v_fmac_f32_e32 v222, v223, v220
	v_fma_f32 v219, -v219, v222, v221
	v_div_fmas_f32 v219, v219, v220, v222
	v_cmp_gt_f32_e32 vcc, s84, v210
	v_div_fixup_f32 v208, v219, v208, 1.0
	s_waitcnt vmcnt(0) lgkmcnt(0)
	v_pk_fma_f32 v[86:87], v[86:87], v[132:133], v[128:129]
	v_cndmask_b32_e32 v210, v210, v218, vcc
	v_sqrt_f32_e32 v218, v210
	v_pk_fma_f32 v[84:85], v[84:85], v[130:131], v[126:127]
	global_store_dwordx4 v[192:193], v[84:87], off
	v_add_u32_e32 v219, -1, v218
	v_fma_f32 v220, -v219, v218, v210
	v_cmp_ge_f32_e64 s[6:7], 0, v220
	v_add_u32_e32 v220, 1, v218
	s_nop 0
	v_cndmask_b32_e64 v219, v218, v219, s[6:7]
	v_fma_f32 v218, -v220, v218, v210
	v_cmp_lt_f32_e64 s[6:7], 0, v218
	s_nop 1
	v_cndmask_b32_e64 v218, v219, v220, s[6:7]
	v_mul_f32_e32 v219, 0x37800000, v218
	v_cndmask_b32_e32 v218, v218, v219, vcc
	v_cmp_class_f32_e32 vcc, v210, v248
	s_nop 1
	v_cndmask_b32_e32 v210, v218, v210, vcc
	v_div_scale_f32 v218, s[6:7], v210, v210, 1.0
	v_rcp_f32_e32 v219, v218
	s_nop 0
	v_fma_f32 v220, -v218, v219, 1.0
	v_fmac_f32_e32 v219, v220, v219
	v_div_scale_f32 v220, vcc, 1.0, v210, 1.0
	v_mul_f32_e32 v221, v220, v219
	v_fma_f32 v222, -v218, v221, v220
	v_fmac_f32_e32 v221, v222, v219
	v_fma_f32 v218, -v218, v221, v220
	v_div_fmas_f32 v218, v218, v219, v221
	v_cmp_gt_f32_e32 vcc, s84, v212
	v_div_fixup_f32 v210, v218, v210, 1.0
	s_nop 0
	v_cndmask_b32_e32 v212, v212, v217, vcc
	v_sqrt_f32_e32 v217, v212
	s_nop 0
	v_add_u32_e32 v218, -1, v217
	v_fma_f32 v219, -v218, v217, v212
	v_cmp_ge_f32_e64 s[6:7], 0, v219
	v_add_u32_e32 v219, 1, v217
	s_nop 0
	v_cndmask_b32_e64 v218, v217, v218, s[6:7]
	v_fma_f32 v217, -v219, v217, v212
	v_cmp_lt_f32_e64 s[6:7], 0, v217
	s_nop 1
	v_cndmask_b32_e64 v217, v218, v219, s[6:7]
	v_mul_f32_e32 v218, 0x37800000, v217
	v_cndmask_b32_e32 v217, v217, v218, vcc
	v_cmp_class_f32_e32 vcc, v212, v248
	s_nop 1
	v_cndmask_b32_e32 v212, v217, v212, vcc
	v_div_scale_f32 v217, s[6:7], v212, v212, 1.0
	v_rcp_f32_e32 v218, v217
	s_nop 0
	v_fma_f32 v219, -v217, v218, 1.0
	v_fmac_f32_e32 v218, v219, v218
	v_div_scale_f32 v219, vcc, 1.0, v212, 1.0
	v_mul_f32_e32 v220, v219, v218
	v_fma_f32 v221, -v217, v220, v219
	v_fmac_f32_e32 v220, v221, v218
	v_fma_f32 v217, -v217, v220, v219
	v_div_fmas_f32 v217, v217, v218, v220
	v_cmp_gt_f32_e32 vcc, s84, v214
	v_div_fixup_f32 v212, v217, v212, 1.0
	s_nop 0
	v_cndmask_b32_e32 v214, v214, v216, vcc
	v_sqrt_f32_e32 v216, v214
	s_nop 0
	v_add_u32_e32 v217, -1, v216
	v_fma_f32 v218, -v217, v216, v214
	v_cmp_ge_f32_e64 s[6:7], 0, v218
	v_add_u32_e32 v218, 1, v216
	s_nop 0
	v_cndmask_b32_e64 v217, v216, v217, s[6:7]
	v_fma_f32 v216, -v218, v216, v214
	v_cmp_lt_f32_e64 s[6:7], 0, v216
	s_nop 1
	v_cndmask_b32_e64 v216, v217, v218, s[6:7]
	v_mul_f32_e32 v217, 0x37800000, v216
	v_cndmask_b32_e32 v216, v216, v217, vcc
	v_cmp_class_f32_e32 vcc, v214, v248
	s_nop 1
	v_cndmask_b32_e32 v214, v216, v214, vcc
	v_div_scale_f32 v216, s[6:7], v214, v214, 1.0
	v_rcp_f32_e32 v217, v216
	s_nop 0
	v_fma_f32 v218, -v216, v217, 1.0
	v_fmac_f32_e32 v217, v218, v217
	v_div_scale_f32 v218, vcc, 1.0, v214, 1.0
	v_mul_f32_e32 v219, v218, v217
	v_fma_f32 v220, -v216, v219, v218
	v_fmac_f32_e32 v219, v220, v217
	v_fma_f32 v216, -v216, v219, v218
	v_div_fmas_f32 v216, v216, v217, v219
	v_cmp_gt_f32_e32 vcc, s84, v213
	v_div_fixup_f32 v214, v216, v214, 1.0
	s_nop 0
	v_cndmask_b32_e32 v213, v213, v215, vcc
	v_sqrt_f32_e32 v215, v213
	s_nop 0
	v_add_u32_e32 v216, -1, v215
	v_fma_f32 v217, -v216, v215, v213
	v_cmp_ge_f32_e64 s[6:7], 0, v217
	v_add_u32_e32 v217, 1, v215
	s_nop 0
	v_cndmask_b32_e64 v216, v215, v216, s[6:7]
	v_fma_f32 v215, -v217, v215, v213
	v_cmp_lt_f32_e64 s[6:7], 0, v215
	s_nop 1
	v_cndmask_b32_e64 v215, v216, v217, s[6:7]
	v_mul_f32_e32 v216, 0x37800000, v215
	v_cndmask_b32_e32 v215, v215, v216, vcc
	v_cmp_class_f32_e32 vcc, v213, v248
	s_nop 1
	v_cndmask_b32_e32 v213, v215, v213, vcc
	v_div_scale_f32 v215, s[6:7], v213, v213, 1.0
	v_rcp_f32_e32 v216, v215
	s_nop 0
	v_fma_f32 v217, -v215, v216, 1.0
	v_fmac_f32_e32 v216, v217, v216
	v_div_scale_f32 v217, vcc, 1.0, v213, 1.0
	v_mul_f32_e32 v218, v217, v216
	v_fma_f32 v219, -v215, v218, v217
	v_fmac_f32_e32 v218, v219, v216
	v_fma_f32 v215, -v215, v218, v217
	v_div_fmas_f32 v215, v215, v216, v218
	v_cmp_gt_f32_e32 vcc, s84, v209
	v_div_fixup_f32 v216, v215, v213, 1.0
	s_nop 0
	v_cndmask_b32_e32 v209, v209, v211, vcc
	v_sqrt_f32_e32 v211, v209
	s_nop 0
	v_add_u32_e32 v213, -1, v211
	v_fma_f32 v215, -v213, v211, v209
	v_cmp_ge_f32_e64 s[6:7], 0, v215
	v_add_u32_e32 v215, 1, v211
	s_nop 0
	v_cndmask_b32_e64 v213, v211, v213, s[6:7]
	v_fma_f32 v211, -v215, v211, v209
	v_cmp_lt_f32_e64 s[6:7], 0, v211
	s_nop 1
	v_cndmask_b32_e64 v211, v213, v215, s[6:7]
	v_mul_f32_e32 v213, 0x37800000, v211
	v_cndmask_b32_e32 v211, v211, v213, vcc
	v_cmp_class_f32_e32 vcc, v209, v248
	s_nop 1
	v_cndmask_b32_e32 v209, v211, v209, vcc
	v_div_scale_f32 v211, s[6:7], v209, v209, 1.0
	v_rcp_f32_e32 v213, v211
	s_nop 0
	v_fma_f32 v215, -v211, v213, 1.0
	v_fmac_f32_e32 v213, v215, v213
	v_div_scale_f32 v215, vcc, 1.0, v209, 1.0
	v_mul_f32_e32 v217, v215, v213
	v_fma_f32 v218, -v211, v217, v215
	v_fmac_f32_e32 v217, v218, v213
	v_fma_f32 v211, -v211, v217, v215
	v_div_fmas_f32 v211, v211, v213, v217
	v_div_fixup_f32 v218, v211, v209, 1.0
	v_pk_mul_f32 v[84:85], v[92:93], v[218:219] op_sel_hi:[1,0]
	v_pk_mul_f32 v[86:87], v[94:95], v[218:219] op_sel_hi:[1,0]
	v_pk_fma_f32 v[84:85], v[84:85], v[130:131], v[126:127]
	v_pk_fma_f32 v[86:87], v[86:87], v[132:133], v[128:129]
	global_store_dwordx4 v[194:195], v[84:87], off
	s_nop 1
	v_pk_mul_f32 v[84:85], v[100:101], v[216:217] op_sel_hi:[1,0]
	v_pk_mul_f32 v[86:87], v[102:103], v[216:217] op_sel_hi:[1,0]
	v_pk_fma_f32 v[84:85], v[84:85], v[130:131], v[126:127]
	v_pk_fma_f32 v[86:87], v[86:87], v[132:133], v[128:129]
	global_store_dwordx4 v[198:199], v[84:87], off
	s_nop 1
	v_pk_mul_f32 v[84:85], v[108:109], v[214:215] op_sel_hi:[1,0]
	v_pk_mul_f32 v[86:87], v[110:111], v[214:215] op_sel_hi:[1,0]
	v_pk_fma_f32 v[84:85], v[84:85], v[130:131], v[126:127]
	v_pk_fma_f32 v[86:87], v[86:87], v[132:133], v[128:129]
	global_store_dwordx4 v[200:201], v[84:87], off
	s_nop 1
	v_pk_mul_f32 v[84:85], v[112:113], v[212:213] op_sel_hi:[1,0]
	v_pk_mul_f32 v[86:87], v[114:115], v[212:213] op_sel_hi:[1,0]
	v_pk_fma_f32 v[84:85], v[84:85], v[130:131], v[126:127]
	v_pk_fma_f32 v[86:87], v[86:87], v[132:133], v[128:129]
	global_store_dwordx4 v[204:205], v[84:87], off
	s_nop 1
	v_pk_mul_f32 v[84:85], v[116:117], v[210:211] op_sel_hi:[1,0]
	v_pk_mul_f32 v[86:87], v[140:141], v[210:211] op_sel_hi:[1,0]
	v_pk_fma_f32 v[84:85], v[84:85], v[130:131], v[126:127]
	v_pk_fma_f32 v[86:87], v[86:87], v[132:133], v[128:129]
	global_store_dwordx4 v[206:207], v[84:87], off
	s_nop 1
	v_pk_mul_f32 v[84:85], v[120:121], v[208:209] op_sel_hi:[1,0]
	v_pk_mul_f32 v[86:87], v[152:153], v[208:209] op_sel_hi:[1,0]
	v_pk_fma_f32 v[84:85], v[130:131], v[84:85], v[126:127]
	v_pk_fma_f32 v[86:87], v[132:133], v[86:87], v[128:129]
	global_store_dwordx4 v[202:203], v[84:87], off
	s_nop 1
	v_pk_mul_f32 v[84:85], v[124:125], v[190:191] op_sel_hi:[1,0]
	v_pk_mul_f32 v[86:87], v[154:155], v[190:191] op_sel_hi:[1,0]
	v_pk_fma_f32 v[84:85], v[130:131], v[84:85], v[126:127]
	v_pk_fma_f32 v[86:87], v[132:133], v[86:87], v[128:129]
	global_store_dwordx4 v[196:197], v[84:87], off
	global_load_dwordx4 v[84:87], v[134:135], off offset:1024
	s_nop 0
	global_load_dwordx4 v[92:95], v[136:137], off offset:1024
	s_waitcnt vmcnt(0) lgkmcnt(0)
	v_pk_fma_f32 v[48:49], v[48:49], v[84:85], v[92:93]
	v_pk_fma_f32 v[50:51], v[50:51], v[86:87], v[94:95]
	global_store_dwordx4 v[172:173], v[48:51], off
	s_nop 1
	v_pk_mul_f32 v[50:51], v[58:59], v[218:219] op_sel_hi:[1,0]
	v_pk_mul_f32 v[48:49], v[56:57], v[218:219] op_sel_hi:[1,0]
	v_pk_fma_f32 v[50:51], v[50:51], v[86:87], v[94:95]
	v_pk_fma_f32 v[48:49], v[48:49], v[84:85], v[92:93]
	global_store_dwordx4 v[174:175], v[48:51], off
	s_nop 1
	v_pk_mul_f32 v[50:51], v[66:67], v[216:217] op_sel_hi:[1,0]
	v_pk_mul_f32 v[48:49], v[64:65], v[216:217] op_sel_hi:[1,0]
	v_pk_fma_f32 v[50:51], v[50:51], v[86:87], v[94:95]
	v_pk_fma_f32 v[48:49], v[48:49], v[84:85], v[92:93]
	global_store_dwordx4 v[176:177], v[48:51], off
	s_nop 1
	v_pk_mul_f32 v[50:51], v[78:79], v[214:215] op_sel_hi:[1,0]
	v_pk_mul_f32 v[48:49], v[76:77], v[214:215] op_sel_hi:[1,0]
	v_pk_fma_f32 v[50:51], v[50:51], v[86:87], v[94:95]
	v_pk_fma_f32 v[48:49], v[48:49], v[84:85], v[92:93]
	global_store_dwordx4 v[178:179], v[48:51], off
	s_nop 1
	v_pk_mul_f32 v[50:51], v[82:83], v[212:213] op_sel_hi:[1,0]
	v_pk_mul_f32 v[48:49], v[80:81], v[212:213] op_sel_hi:[1,0]
	v_pk_fma_f32 v[50:51], v[50:51], v[86:87], v[94:95]
	v_pk_fma_f32 v[48:49], v[48:49], v[84:85], v[92:93]
	global_store_dwordx4 v[182:183], v[48:51], off
	s_nop 1
	v_pk_mul_f32 v[50:51], v[90:91], v[210:211] op_sel_hi:[1,0]
	v_pk_mul_f32 v[48:49], v[88:89], v[210:211] op_sel_hi:[1,0]
	v_pk_fma_f32 v[50:51], v[50:51], v[86:87], v[94:95]
	v_pk_fma_f32 v[48:49], v[48:49], v[84:85], v[92:93]
	global_store_dwordx4 v[186:187], v[48:51], off
	s_nop 1
	v_pk_mul_f32 v[50:51], v[98:99], v[208:209] op_sel_hi:[1,0]
	v_pk_mul_f32 v[48:49], v[96:97], v[208:209] op_sel_hi:[1,0]
	v_pk_fma_f32 v[50:51], v[50:51], v[86:87], v[94:95]
	v_pk_fma_f32 v[48:49], v[48:49], v[84:85], v[92:93]
	global_store_dwordx4 v[184:185], v[48:51], off
	s_nop 1
	v_pk_mul_f32 v[50:51], v[106:107], v[190:191] op_sel_hi:[1,0]
	v_pk_mul_f32 v[48:49], v[104:105], v[190:191] op_sel_hi:[1,0]
	v_pk_fma_f32 v[50:51], v[50:51], v[86:87], v[94:95]
	v_pk_fma_f32 v[48:49], v[48:49], v[84:85], v[92:93]
	global_store_dwordx4 v[180:181], v[48:51], off
	global_load_dwordx4 v[48:51], v[134:135], off offset:2048
	s_nop 0
	global_load_dwordx4 v[56:59], v[136:137], off offset:2048
	s_waitcnt vmcnt(0) lgkmcnt(0)
	v_pk_fma_f32 v[20:21], v[20:21], v[48:49], v[56:57]
	v_pk_fma_f32 v[22:23], v[22:23], v[50:51], v[58:59]
	global_store_dwordx4 v[156:157], v[20:23], off
	s_nop 1
	v_pk_mul_f32 v[22:23], v[30:31], v[218:219] op_sel_hi:[1,0]
	v_pk_mul_f32 v[20:21], v[28:29], v[218:219] op_sel_hi:[1,0]
	v_pk_fma_f32 v[22:23], v[22:23], v[50:51], v[58:59]
	v_pk_fma_f32 v[20:21], v[20:21], v[48:49], v[56:57]
	global_store_dwordx4 v[158:159], v[20:23], off
	s_nop 1
	v_pk_mul_f32 v[22:23], v[38:39], v[216:217] op_sel_hi:[1,0]
	v_pk_mul_f32 v[20:21], v[36:37], v[216:217] op_sel_hi:[1,0]
	v_pk_fma_f32 v[22:23], v[22:23], v[50:51], v[58:59]
	v_pk_fma_f32 v[20:21], v[20:21], v[48:49], v[56:57]
	global_store_dwordx4 v[160:161], v[20:23], off
	s_nop 1
	v_pk_mul_f32 v[22:23], v[46:47], v[214:215] op_sel_hi:[1,0]
	v_pk_mul_f32 v[20:21], v[44:45], v[214:215] op_sel_hi:[1,0]
	v_pk_fma_f32 v[22:23], v[22:23], v[50:51], v[58:59]
	v_pk_fma_f32 v[20:21], v[20:21], v[48:49], v[56:57]
	global_store_dwordx4 v[162:163], v[20:23], off
	s_nop 1
	v_pk_mul_f32 v[22:23], v[54:55], v[212:213] op_sel_hi:[1,0]
	v_pk_mul_f32 v[20:21], v[52:53], v[212:213] op_sel_hi:[1,0]
	v_pk_fma_f32 v[22:23], v[22:23], v[50:51], v[58:59]
	v_pk_fma_f32 v[20:21], v[20:21], v[48:49], v[56:57]
	global_store_dwordx4 v[166:167], v[20:23], off
	s_nop 1
	v_pk_mul_f32 v[22:23], v[62:63], v[210:211] op_sel_hi:[1,0]
	v_pk_mul_f32 v[20:21], v[60:61], v[210:211] op_sel_hi:[1,0]
	v_pk_fma_f32 v[22:23], v[22:23], v[50:51], v[58:59]
	v_pk_fma_f32 v[20:21], v[20:21], v[48:49], v[56:57]
	global_store_dwordx4 v[170:171], v[20:23], off
	s_nop 1
	v_pk_mul_f32 v[22:23], v[70:71], v[208:209] op_sel_hi:[1,0]
	v_pk_mul_f32 v[20:21], v[68:69], v[208:209] op_sel_hi:[1,0]
	v_pk_fma_f32 v[22:23], v[22:23], v[50:51], v[58:59]
	v_pk_fma_f32 v[20:21], v[20:21], v[48:49], v[56:57]
	global_store_dwordx4 v[168:169], v[20:23], off
	s_nop 1
	v_pk_mul_f32 v[22:23], v[74:75], v[190:191] op_sel_hi:[1,0]
	v_pk_mul_f32 v[20:21], v[72:73], v[190:191] op_sel_hi:[1,0]
	v_pk_fma_f32 v[22:23], v[22:23], v[50:51], v[58:59]
	v_pk_fma_f32 v[20:21], v[20:21], v[48:49], v[56:57]
	global_store_dwordx4 v[164:165], v[20:23], off
	global_load_dwordx4 v[20:23], v[134:135], off offset:3072
	s_nop 0
	global_load_dwordx4 v[28:31], v[136:137], off offset:3072
	s_waitcnt vmcnt(0) lgkmcnt(0)
	v_pk_fma_f32 v[0:1], v[0:1], v[20:21], v[28:29]
	v_pk_fma_f32 v[2:3], v[2:3], v[22:23], v[30:31]
	global_store_dwordx4 v[118:119], v[0:3], off
	s_nop 1
	v_pk_mul_f32 v[2:3], v[6:7], v[218:219] op_sel_hi:[1,0]
	v_pk_mul_f32 v[0:1], v[4:5], v[218:219] op_sel_hi:[1,0]
	v_pk_fma_f32 v[2:3], v[2:3], v[22:23], v[30:31]
	v_pk_fma_f32 v[0:1], v[0:1], v[20:21], v[28:29]
	global_store_dwordx4 v[122:123], v[0:3], off
	s_nop 1
	v_pk_mul_f32 v[2:3], v[10:11], v[216:217] op_sel_hi:[1,0]
	v_pk_mul_f32 v[0:1], v[8:9], v[216:217] op_sel_hi:[1,0]
	v_pk_fma_f32 v[2:3], v[2:3], v[22:23], v[30:31]
	v_pk_fma_f32 v[0:1], v[0:1], v[20:21], v[28:29]
	global_store_dwordx4 v[142:143], v[0:3], off
	s_nop 1
	v_pk_mul_f32 v[2:3], v[14:15], v[214:215] op_sel_hi:[1,0]
	v_pk_mul_f32 v[0:1], v[12:13], v[214:215] op_sel_hi:[1,0]
	v_pk_fma_f32 v[2:3], v[2:3], v[22:23], v[30:31]
	v_pk_fma_f32 v[0:1], v[0:1], v[20:21], v[28:29]
	global_store_dwordx4 v[144:145], v[0:3], off
	s_nop 1
	v_pk_mul_f32 v[2:3], v[18:19], v[212:213] op_sel_hi:[1,0]
	v_pk_mul_f32 v[0:1], v[16:17], v[212:213] op_sel_hi:[1,0]
	v_pk_fma_f32 v[2:3], v[2:3], v[22:23], v[30:31]
	v_pk_fma_f32 v[0:1], v[0:1], v[20:21], v[28:29]
	global_store_dwordx4 v[146:147], v[0:3], off
	s_nop 1
	v_pk_mul_f32 v[2:3], v[26:27], v[210:211] op_sel_hi:[1,0]
	v_pk_mul_f32 v[0:1], v[24:25], v[210:211] op_sel_hi:[1,0]
	v_pk_fma_f32 v[2:3], v[2:3], v[22:23], v[30:31]
	v_pk_fma_f32 v[0:1], v[0:1], v[20:21], v[28:29]
	global_store_dwordx4 v[150:151], v[0:3], off
	s_nop 1
	v_pk_mul_f32 v[2:3], v[34:35], v[208:209] op_sel_hi:[1,0]
	v_pk_mul_f32 v[0:1], v[32:33], v[208:209] op_sel_hi:[1,0]
	v_pk_fma_f32 v[2:3], v[2:3], v[22:23], v[30:31]
	v_pk_fma_f32 v[0:1], v[0:1], v[20:21], v[28:29]
	global_store_dwordx4 v[148:149], v[0:3], off
	s_nop 1
	v_pk_mul_f32 v[2:3], v[42:43], v[190:191] op_sel_hi:[1,0]
	v_pk_mul_f32 v[0:1], v[40:41], v[190:191] op_sel_hi:[1,0]
	v_pk_fma_f32 v[2:3], v[2:3], v[22:23], v[30:31]
	v_pk_fma_f32 v[0:1], v[0:1], v[20:21], v[28:29]
	global_store_dwordx4 v[138:139], v[0:3], off
	s_branch .LBB0_1551

.LBB0_1558:
	s_or_b64 exec, exec, s[6:7]
	global_load_dwordx4 v[126:129], v[134:135], off
	global_load_dwordx4 v[130:133], v[136:137], off
	v_pk_mul_f32 v[94:95], v[150:151], v[74:75] op_sel_hi:[1,0]
	v_pk_mul_f32 v[104:105], v[104:105], v[74:75] op_sel_hi:[1,0]
	v_lshl_add_u64 v[62:63], s[0:1], 0, v[138:139]
	s_mov_b32 s6, 0x3a00000
	v_pk_mul_f32 v[96:97], v[96:97], v[78:79] op_sel_hi:[1,0]
	v_pk_mul_f32 v[64:65], v[64:65], v[74:75] op_sel_hi:[1,0]
	v_pk_mul_f32 v[34:35], v[34:35], v[74:75] op_sel_hi:[1,0]
	v_pk_mul_f32 v[32:33], v[32:33], v[74:75] op_sel_hi:[1,0]
	v_pk_mul_f32 v[2:3], v[2:3], v[74:75] op_sel_hi:[1,0]
	v_pk_mul_f32 v[0:1], v[0:1], v[74:75] op_sel_hi:[1,0]
	s_add_i32 s10, s10, s12
	s_add_u32 s14, s14, s16
	s_addc_u32 s15, s15, s17
	v_lshl_add_u64 v[138:139], v[138:139], 0, s[18:19]
	v_lshl_add_u64 v[140:141], v[140:141], 0, s[20:21]
	s_cmpk_gt_i32 s10, 0x7fff
	s_waitcnt vmcnt(0) lgkmcnt(0)
	v_pk_fma_f32 v[94:95], v[94:95], v[128:129], v[132:133]
	v_pk_fma_f32 v[104:105], v[104:105], v[126:127], v[130:131]
	v_cvt_pk_bf16_f32 v151, v94, v95
	v_pk_mul_f32 v[94:95], v[98:99], v[78:79] op_sel_hi:[1,0]
	v_cvt_pk_bf16_f32 v150, v104, v105
	v_add_co_u32_e32 v104, vcc, s6, v62
	v_pk_fma_f32 v[94:95], v[94:95], v[128:129], v[132:133]
	v_pk_fma_f32 v[96:97], v[96:97], v[126:127], v[130:131]
	v_addc_co_u32_e32 v105, vcc, 0, v63, vcc
	v_cvt_pk_bf16_f32 v96, v96, v97
	v_cvt_pk_bf16_f32 v97, v94, v95
	global_store_dwordx2 v[104:105], v[96:97], off offset:2048
	v_pk_mul_f32 v[94:95], v[152:153], v[82:83] op_sel_hi:[1,0]
	v_pk_mul_f32 v[96:97], v[108:109], v[82:83] op_sel_hi:[1,0]
	s_mov_b32 s6, 0x3a01000
	v_pk_fma_f32 v[94:95], v[94:95], v[128:129], v[132:133]
	v_pk_fma_f32 v[96:97], v[96:97], v[126:127], v[130:131]
	v_add_co_u32_e32 v108, vcc, s6, v62
	v_cvt_pk_bf16_f32 v96, v96, v97
	v_cvt_pk_bf16_f32 v97, v94, v95
	v_addc_co_u32_e32 v109, vcc, 0, v63, vcc
	global_store_dwordx2 v[108:109], v[96:97], off
	v_pk_mul_f32 v[94:95], v[154:155], v[86:87] op_sel_hi:[1,0]
	v_pk_mul_f32 v[96:97], v[100:101], v[86:87] op_sel_hi:[1,0]
	v_pk_fma_f32 v[94:95], v[94:95], v[128:129], v[132:133]
	v_pk_fma_f32 v[96:97], v[96:97], v[126:127], v[130:131]
	s_mov_b32 s6, 0x3a02000
	v_cvt_pk_bf16_f32 v96, v96, v97
	v_cvt_pk_bf16_f32 v97, v94, v95
	global_store_dwordx2 v[108:109], v[96:97], off offset:2048
	v_pk_mul_f32 v[94:95], v[156:157], v[90:91] op_sel_hi:[1,0]
	v_pk_mul_f32 v[96:97], v[116:117], v[90:91] op_sel_hi:[1,0]
	v_pk_fma_f32 v[94:95], v[94:95], v[128:129], v[132:133]
	v_pk_fma_f32 v[96:97], v[96:97], v[126:127], v[130:131]
	v_add_co_u32_e32 v116, vcc, s6, v62
	v_cvt_pk_bf16_f32 v96, v96, v97
	v_cvt_pk_bf16_f32 v97, v94, v95
	v_addc_co_u32_e32 v117, vcc, 0, v63, vcc
	global_store_dwordx2 v[116:117], v[96:97], off
	v_pk_mul_f32 v[94:95], v[158:159], v[102:103] op_sel_hi:[1,0]
	v_pk_mul_f32 v[96:97], v[112:113], v[102:103] op_sel_hi:[1,0]
	v_pk_fma_f32 v[94:95], v[94:95], v[128:129], v[132:133]
	v_pk_fma_f32 v[96:97], v[96:97], v[126:127], v[130:131]
	s_mov_b32 s6, 0x3a03000
	v_cvt_pk_bf16_f32 v96, v96, v97
	v_cvt_pk_bf16_f32 v97, v94, v95
	global_store_dwordx2 v[116:117], v[96:97], off offset:2048
	v_pk_mul_f32 v[94:95], v[160:161], v[114:115] op_sel_hi:[1,0]
	v_pk_mul_f32 v[96:97], v[124:125], v[114:115] op_sel_hi:[1,0]
	v_pk_fma_f32 v[94:95], v[94:95], v[128:129], v[132:133]
	v_pk_fma_f32 v[96:97], v[96:97], v[126:127], v[130:131]
	v_add_co_u32_e32 v112, vcc, s6, v62
	v_cvt_pk_bf16_f32 v96, v96, v97
	v_cvt_pk_bf16_f32 v97, v94, v95
	v_addc_co_u32_e32 v113, vcc, 0, v63, vcc
	v_pk_mul_f32 v[62:63], v[162:163], v[118:119] op_sel_hi:[1,0]
	v_pk_mul_f32 v[94:95], v[120:121], v[118:119] op_sel_hi:[1,0]
	v_pk_fma_f32 v[62:63], v[62:63], v[128:129], v[132:133]
	v_pk_fma_f32 v[94:95], v[94:95], v[126:127], v[130:131]
	global_store_dwordx2 v[104:105], v[150:151], off
	v_cvt_pk_bf16_f32 v94, v94, v95
	v_cvt_pk_bf16_f32 v95, v62, v63
	global_store_dwordx2 v[112:113], v[96:97], off
	global_store_dwordx2 v[112:113], v[94:95], off offset:2048
	global_load_dwordx4 v[94:97], v[134:135], off offset:1024
	s_nop 0
	global_load_dwordx4 v[98:101], v[136:137], off offset:1024
	v_pk_mul_f32 v[62:63], v[66:67], v[74:75] op_sel_hi:[1,0]
	s_waitcnt vmcnt(0) lgkmcnt(0)
	v_pk_fma_f32 v[64:65], v[64:65], v[94:95], v[98:99]
	v_pk_fma_f32 v[62:63], v[62:63], v[96:97], v[100:101]
	v_cvt_pk_bf16_f32 v64, v64, v65
	v_cvt_pk_bf16_f32 v65, v62, v63
	global_store_dwordx2 v[104:105], v[64:65], off offset:512
	v_pk_mul_f32 v[62:63], v[106:107], v[78:79] op_sel_hi:[1,0]
	v_pk_mul_f32 v[64:65], v[68:69], v[78:79] op_sel_hi:[1,0]
	v_pk_fma_f32 v[62:63], v[62:63], v[96:97], v[100:101]
	v_pk_fma_f32 v[64:65], v[64:65], v[94:95], v[98:99]
	s_nop 0
	v_cvt_pk_bf16_f32 v64, v64, v65
	v_cvt_pk_bf16_f32 v65, v62, v63
	global_store_dwordx2 v[104:105], v[64:65], off offset:2560
	v_pk_mul_f32 v[62:63], v[110:111], v[82:83] op_sel_hi:[1,0]
	v_pk_mul_f32 v[64:65], v[72:73], v[82:83] op_sel_hi:[1,0]
	v_pk_fma_f32 v[62:63], v[62:63], v[96:97], v[100:101]
	v_pk_fma_f32 v[64:65], v[64:65], v[94:95], v[98:99]
	s_nop 0
	v_cvt_pk_bf16_f32 v64, v64, v65
	v_cvt_pk_bf16_f32 v65, v62, v63
	global_store_dwordx2 v[108:109], v[64:65], off offset:512
	v_pk_mul_f32 v[62:63], v[142:143], v[86:87] op_sel_hi:[1,0]
	v_pk_mul_f32 v[64:65], v[76:77], v[86:87] op_sel_hi:[1,0]
	v_pk_fma_f32 v[62:63], v[62:63], v[96:97], v[100:101]
	v_pk_fma_f32 v[64:65], v[64:65], v[94:95], v[98:99]
	s_nop 0
	v_cvt_pk_bf16_f32 v64, v64, v65
	v_cvt_pk_bf16_f32 v65, v62, v63
	global_store_dwordx2 v[108:109], v[64:65], off offset:2560
	v_pk_mul_f32 v[62:63], v[144:145], v[90:91] op_sel_hi:[1,0]
	v_pk_mul_f32 v[64:65], v[80:81], v[90:91] op_sel_hi:[1,0]
	v_pk_fma_f32 v[62:63], v[62:63], v[96:97], v[100:101]
	v_pk_fma_f32 v[64:65], v[64:65], v[94:95], v[98:99]
	s_nop 0
	v_cvt_pk_bf16_f32 v64, v64, v65
	v_cvt_pk_bf16_f32 v65, v62, v63
	global_store_dwordx2 v[116:117], v[64:65], off offset:512
	v_pk_mul_f32 v[62:63], v[146:147], v[102:103] op_sel_hi:[1,0]
	v_pk_mul_f32 v[64:65], v[84:85], v[102:103] op_sel_hi:[1,0]
	v_pk_fma_f32 v[62:63], v[62:63], v[96:97], v[100:101]
	v_pk_fma_f32 v[64:65], v[64:65], v[94:95], v[98:99]
	s_nop 0
	v_cvt_pk_bf16_f32 v64, v64, v65
	v_cvt_pk_bf16_f32 v65, v62, v63
	global_store_dwordx2 v[116:117], v[64:65], off offset:2560
	v_pk_mul_f32 v[62:63], v[148:149], v[114:115] op_sel_hi:[1,0]
	v_pk_mul_f32 v[64:65], v[88:89], v[114:115] op_sel_hi:[1,0]
	v_pk_fma_f32 v[62:63], v[62:63], v[96:97], v[100:101]
	v_pk_fma_f32 v[64:65], v[64:65], v[94:95], v[98:99]
	s_nop 0
	v_cvt_pk_bf16_f32 v64, v64, v65
	v_cvt_pk_bf16_f32 v65, v62, v63
	global_store_dwordx2 v[112:113], v[64:65], off offset:512
	v_pk_mul_f32 v[62:63], v[122:123], v[118:119] op_sel_hi:[1,0]
	v_pk_mul_f32 v[64:65], v[92:93], v[118:119] op_sel_hi:[1,0]
	v_pk_fma_f32 v[62:63], v[62:63], v[96:97], v[100:101]
	v_pk_fma_f32 v[64:65], v[64:65], v[94:95], v[98:99]
	s_nop 0
	v_cvt_pk_bf16_f32 v64, v64, v65
	v_cvt_pk_bf16_f32 v65, v62, v63
	global_store_dwordx2 v[112:113], v[64:65], off offset:2560
	global_load_dwordx4 v[62:65], v[134:135], off offset:2048
	s_nop 0
	global_load_dwordx4 v[66:69], v[136:137], off offset:2048
	s_waitcnt vmcnt(0) lgkmcnt(0)
	v_pk_fma_f32 v[34:35], v[34:35], v[64:65], v[68:69]
	v_pk_fma_f32 v[32:33], v[32:33], v[62:63], v[66:67]
	s_nop 0
	v_cvt_pk_bf16_f32 v32, v32, v33
	v_cvt_pk_bf16_f32 v33, v34, v35
	global_store_dwordx2 v[104:105], v[32:33], off offset:1024
	v_pk_mul_f32 v[32:33], v[38:39], v[78:79] op_sel_hi:[1,0]
	v_pk_mul_f32 v[34:35], v[36:37], v[78:79] op_sel_hi:[1,0]
	v_pk_fma_f32 v[32:33], v[32:33], v[64:65], v[68:69]
	v_pk_fma_f32 v[34:35], v[34:35], v[62:63], v[66:67]
	s_nop 0
	v_cvt_pk_bf16_f32 v34, v34, v35
	v_cvt_pk_bf16_f32 v35, v32, v33
	global_store_dwordx2 v[104:105], v[34:35], off offset:3072
	v_pk_mul_f32 v[32:33], v[42:43], v[82:83] op_sel_hi:[1,0]
	v_pk_mul_f32 v[34:35], v[40:41], v[82:83] op_sel_hi:[1,0]
	v_pk_fma_f32 v[32:33], v[32:33], v[64:65], v[68:69]
	v_pk_fma_f32 v[34:35], v[34:35], v[62:63], v[66:67]
	s_nop 0
	v_cvt_pk_bf16_f32 v34, v34, v35
	v_cvt_pk_bf16_f32 v35, v32, v33
	global_store_dwordx2 v[108:109], v[34:35], off offset:1024
	v_pk_mul_f32 v[32:33], v[46:47], v[86:87] op_sel_hi:[1,0]
	v_pk_mul_f32 v[34:35], v[44:45], v[86:87] op_sel_hi:[1,0]
	v_pk_fma_f32 v[32:33], v[32:33], v[64:65], v[68:69]
	v_pk_fma_f32 v[34:35], v[34:35], v[62:63], v[66:67]
	s_nop 0
	v_cvt_pk_bf16_f32 v34, v34, v35
	v_cvt_pk_bf16_f32 v35, v32, v33
	global_store_dwordx2 v[108:109], v[34:35], off offset:3072
	v_pk_mul_f32 v[32:33], v[50:51], v[90:91] op_sel_hi:[1,0]
	v_pk_mul_f32 v[34:35], v[48:49], v[90:91] op_sel_hi:[1,0]
	v_pk_fma_f32 v[32:33], v[32:33], v[64:65], v[68:69]
	v_pk_fma_f32 v[34:35], v[34:35], v[62:63], v[66:67]
	s_nop 0
	v_cvt_pk_bf16_f32 v34, v34, v35
	v_cvt_pk_bf16_f32 v35, v32, v33
	global_store_dwordx2 v[116:117], v[34:35], off offset:1024
	v_pk_mul_f32 v[32:33], v[54:55], v[102:103] op_sel_hi:[1,0]
	v_pk_mul_f32 v[34:35], v[52:53], v[102:103] op_sel_hi:[1,0]
	v_pk_fma_f32 v[32:33], v[32:33], v[64:65], v[68:69]
	v_pk_fma_f32 v[34:35], v[34:35], v[62:63], v[66:67]
	s_nop 0
	v_cvt_pk_bf16_f32 v34, v34, v35
	v_cvt_pk_bf16_f32 v35, v32, v33
	global_store_dwordx2 v[116:117], v[34:35], off offset:3072
	v_pk_mul_f32 v[32:33], v[58:59], v[114:115] op_sel_hi:[1,0]
	v_pk_mul_f32 v[34:35], v[56:57], v[114:115] op_sel_hi:[1,0]
	v_pk_fma_f32 v[32:33], v[32:33], v[64:65], v[68:69]
	v_pk_fma_f32 v[34:35], v[34:35], v[62:63], v[66:67]
	s_nop 0
	v_cvt_pk_bf16_f32 v34, v34, v35
	v_cvt_pk_bf16_f32 v35, v32, v33
	global_store_dwordx2 v[112:113], v[34:35], off offset:1024
	v_pk_mul_f32 v[32:33], v[70:71], v[118:119] op_sel_hi:[1,0]
	v_pk_mul_f32 v[34:35], v[60:61], v[118:119] op_sel_hi:[1,0]
	v_pk_fma_f32 v[32:33], v[32:33], v[64:65], v[68:69]
	v_pk_fma_f32 v[34:35], v[34:35], v[62:63], v[66:67]
	s_nop 0
	v_cvt_pk_bf16_f32 v34, v34, v35
	v_cvt_pk_bf16_f32 v35, v32, v33
	global_store_dwordx2 v[112:113], v[34:35], off offset:3072
	global_load_dwordx4 v[32:35], v[134:135], off offset:3072
	s_nop 0
	global_load_dwordx4 v[36:39], v[136:137], off offset:3072
	s_waitcnt vmcnt(0) lgkmcnt(0)
	v_pk_fma_f32 v[2:3], v[2:3], v[34:35], v[38:39]
	v_pk_fma_f32 v[0:1], v[0:1], v[32:33], v[36:37]
	s_nop 0
	v_cvt_pk_bf16_f32 v0, v0, v1
	v_cvt_pk_bf16_f32 v1, v2, v3
	global_store_dwordx2 v[104:105], v[0:1], off offset:1536
	v_pk_mul_f32 v[0:1], v[6:7], v[78:79] op_sel_hi:[1,0]
	v_pk_mul_f32 v[2:3], v[4:5], v[78:79] op_sel_hi:[1,0]
	v_pk_fma_f32 v[0:1], v[0:1], v[34:35], v[38:39]
	v_pk_fma_f32 v[2:3], v[2:3], v[32:33], v[36:37]
	s_nop 0
	v_cvt_pk_bf16_f32 v2, v2, v3
	v_cvt_pk_bf16_f32 v3, v0, v1
	global_store_dwordx2 v[104:105], v[2:3], off offset:3584
	v_pk_mul_f32 v[0:1], v[10:11], v[82:83] op_sel_hi:[1,0]
	v_pk_mul_f32 v[2:3], v[8:9], v[82:83] op_sel_hi:[1,0]
	v_pk_fma_f32 v[0:1], v[0:1], v[34:35], v[38:39]
	v_pk_fma_f32 v[2:3], v[2:3], v[32:33], v[36:37]
	s_nop 0
	v_cvt_pk_bf16_f32 v2, v2, v3
	v_cvt_pk_bf16_f32 v3, v0, v1
	global_store_dwordx2 v[108:109], v[2:3], off offset:1536
	v_pk_mul_f32 v[0:1], v[14:15], v[86:87] op_sel_hi:[1,0]
	v_pk_mul_f32 v[2:3], v[12:13], v[86:87] op_sel_hi:[1,0]
	v_pk_fma_f32 v[0:1], v[0:1], v[34:35], v[38:39]
	v_pk_fma_f32 v[2:3], v[2:3], v[32:33], v[36:37]
	s_nop 0
	v_cvt_pk_bf16_f32 v2, v2, v3
	v_cvt_pk_bf16_f32 v3, v0, v1
	global_store_dwordx2 v[108:109], v[2:3], off offset:3584
	v_pk_mul_f32 v[0:1], v[18:19], v[90:91] op_sel_hi:[1,0]
	v_pk_mul_f32 v[2:3], v[16:17], v[90:91] op_sel_hi:[1,0]
	v_pk_fma_f32 v[0:1], v[0:1], v[34:35], v[38:39]
	v_pk_fma_f32 v[2:3], v[2:3], v[32:33], v[36:37]
	s_nop 0
	v_cvt_pk_bf16_f32 v2, v2, v3
	v_cvt_pk_bf16_f32 v3, v0, v1
	global_store_dwordx2 v[116:117], v[2:3], off offset:1536
	v_pk_mul_f32 v[0:1], v[22:23], v[102:103] op_sel_hi:[1,0]
	v_pk_mul_f32 v[2:3], v[20:21], v[102:103] op_sel_hi:[1,0]
	v_pk_fma_f32 v[0:1], v[0:1], v[34:35], v[38:39]
	v_pk_fma_f32 v[2:3], v[2:3], v[32:33], v[36:37]
	s_nop 0
	v_cvt_pk_bf16_f32 v2, v2, v3
	v_cvt_pk_bf16_f32 v3, v0, v1
	global_store_dwordx2 v[116:117], v[2:3], off offset:3584
	v_pk_mul_f32 v[0:1], v[26:27], v[114:115] op_sel_hi:[1,0]
	v_pk_mul_f32 v[2:3], v[24:25], v[114:115] op_sel_hi:[1,0]
	v_pk_fma_f32 v[0:1], v[0:1], v[34:35], v[38:39]
	v_pk_fma_f32 v[2:3], v[2:3], v[32:33], v[36:37]
	s_nop 0
	v_cvt_pk_bf16_f32 v2, v2, v3
	v_cvt_pk_bf16_f32 v3, v0, v1
	global_store_dwordx2 v[112:113], v[2:3], off offset:1536
	v_pk_mul_f32 v[0:1], v[30:31], v[118:119] op_sel_hi:[1,0]
	v_pk_mul_f32 v[2:3], v[28:29], v[118:119] op_sel_hi:[1,0]
	v_pk_fma_f32 v[0:1], v[0:1], v[34:35], v[38:39]
	v_pk_fma_f32 v[2:3], v[2:3], v[32:33], v[36:37]
	s_nop 0
	v_cvt_pk_bf16_f32 v2, v2, v3
	v_cvt_pk_bf16_f32 v3, v0, v1
	global_store_dwordx2 v[112:113], v[2:3], off offset:3584
	s_cbranch_scc1 .LBB0_1575
.LBB0_1559:
	v_add_co_u32_e32 v0, vcc, 0xffff8400, v140
	s_add_u32 s13, s0, s14
	s_nop 0
	v_addc_co_u32_e32 v1, vcc, -1, v141, vcc
	v_add_co_u32_e32 v2, vcc, 0xffff8800, v140
	s_addc_u32 s11, s1, s15
	s_nop 0
	v_addc_co_u32_e32 v3, vcc, -1, v141, vcc
	global_load_dwordx4 v[104:107], v[0:1], off
	s_waitcnt vmcnt(0)
	global_load_dwordx4 v[64:67], v[2:3], off
	v_add_co_u32_e32 v0, vcc, 0xffff8c00, v140
	s_waitcnt lgkmcnt(0)
	v_add_f32_e32 v128, v104, v105
	v_addc_co_u32_e32 v1, vcc, -1, v141, vcc
	v_add_co_u32_e32 v2, vcc, 0xffff9000, v140
	v_add_f32_e32 v129, v106, v107
	s_nop 0
	v_addc_co_u32_e32 v3, vcc, -1, v141, vcc
	v_add_co_u32_e32 v4, vcc, 0xffff9400, v140
	global_load_dwordx4 v[32:35], v[0:1], off
	s_nop 0
	global_load_dwordx4 v[0:3], v[2:3], off
	v_addc_co_u32_e32 v5, vcc, -1, v141, vcc
	v_add_co_u32_e32 v6, vcc, 0xffff9800, v140
	v_add_f32_e32 v128, v128, v129
	s_nop 0
	v_addc_co_u32_e32 v7, vcc, -1, v141, vcc
	global_load_dwordx4 v[96:99], v[4:5], off
	global_load_dwordx4 v[68:71], v[6:7], off
	v_add_co_u32_e32 v4, vcc, 0xffff9c00, v140
	s_waitcnt vmcnt(0)
	v_add_f32_e32 v129, v64, v65
	v_addc_co_u32_e32 v5, vcc, -1, v141, vcc
	v_add_co_u32_e32 v6, vcc, 0xffffa000, v140
	v_add_f32_e32 v130, v66, v67
	s_nop 0
	v_addc_co_u32_e32 v7, vcc, -1, v141, vcc
	v_add_co_u32_e32 v8, vcc, 0xffffa400, v140
	global_load_dwordx4 v[36:39], v[4:5], off
	s_nop 0
	global_load_dwordx4 v[4:7], v[6:7], off
	v_addc_co_u32_e32 v9, vcc, -1, v141, vcc
	v_add_co_u32_e32 v10, vcc, 0xffffa800, v140
	v_add_f32_e32 v128, 0, v128
	s_nop 0
	v_addc_co_u32_e32 v11, vcc, -1, v141, vcc
	global_load_dwordx4 v[108:111], v[8:9], off
	global_load_dwordx4 v[72:75], v[10:11], off
	v_add_co_u32_e32 v8, vcc, 0xffffac00, v140
	v_add_f32_e32 v129, v129, v130
	s_nop 0
	v_addc_co_u32_e32 v9, vcc, -1, v141, vcc
	v_add_co_u32_e32 v10, vcc, 0xffffb000, v140
	v_add_f32_e32 v128, v128, v129
	s_nop 0
	v_addc_co_u32_e32 v11, vcc, -1, v141, vcc
	v_add_co_u32_e32 v12, vcc, 0xffffb400, v140
	global_load_dwordx4 v[40:43], v[8:9], off
	s_nop 0
	global_load_dwordx4 v[8:11], v[10:11], off
	v_addc_co_u32_e32 v13, vcc, -1, v141, vcc
	v_add_co_u32_e32 v14, vcc, 0xffffb800, v140
	s_waitcnt lgkmcnt(0)
	v_add_f32_e32 v129, v32, v33
	v_addc_co_u32_e32 v15, vcc, -1, v141, vcc
	global_load_dwordx4 v[100:103], v[12:13], off
	global_load_dwordx4 v[76:79], v[14:15], off
	v_add_co_u32_e32 v12, vcc, 0xffffbc00, v140
	v_add_f32_e32 v130, v34, v35
	s_nop 0
	v_addc_co_u32_e32 v13, vcc, -1, v141, vcc
	v_add_co_u32_e32 v14, vcc, 0xffffc000, v140
	v_add_f32_e32 v129, v129, v130
	s_nop 0
	v_addc_co_u32_e32 v15, vcc, -1, v141, vcc
	v_add_co_u32_e32 v16, vcc, 0xffffc400, v140
	global_load_dwordx4 v[44:47], v[12:13], off
	s_nop 0
	global_load_dwordx4 v[12:15], v[14:15], off
	v_addc_co_u32_e32 v17, vcc, -1, v141, vcc
	v_add_co_u32_e32 v18, vcc, 0xffffc800, v140
	v_add_f32_e32 v128, v128, v129
	s_nop 0
	v_addc_co_u32_e32 v19, vcc, -1, v141, vcc
	global_load_dwordx4 v[116:119], v[16:17], off
	global_load_dwordx4 v[80:83], v[18:19], off
	v_add_co_u32_e32 v16, vcc, 0xffffcc00, v140
	v_add_f32_e32 v129, v0, v1
	s_nop 0
	v_addc_co_u32_e32 v17, vcc, -1, v141, vcc
	v_add_co_u32_e32 v18, vcc, 0xffffd000, v140
	v_add_f32_e32 v130, v2, v3
	s_nop 0
	v_addc_co_u32_e32 v19, vcc, -1, v141, vcc
	v_add_co_u32_e32 v20, vcc, 0xffffd400, v140
	global_load_dwordx4 v[48:51], v[16:17], off
	s_nop 0
	global_load_dwordx4 v[16:19], v[18:19], off
	v_addc_co_u32_e32 v21, vcc, -1, v141, vcc
	v_add_co_u32_e32 v22, vcc, 0xffffd800, v140
	v_add_f32_e32 v129, v129, v130
	s_nop 0
	v_addc_co_u32_e32 v23, vcc, -1, v141, vcc
	global_load_dwordx4 v[112:115], v[20:21], off
	global_load_dwordx4 v[84:87], v[22:23], off
	v_add_co_u32_e32 v20, vcc, 0xffffdc00, v140
	v_add_f32_e32 v128, v128, v129
	s_nop 0
	v_addc_co_u32_e32 v21, vcc, -1, v141, vcc
	v_add_co_u32_e32 v22, vcc, 0xffffe000, v140
	v_add_f32_e32 v129, v96, v97
	s_nop 0
	v_addc_co_u32_e32 v23, vcc, -1, v141, vcc
	v_add_co_u32_e32 v24, vcc, 0xffffe400, v140
	global_load_dwordx4 v[52:55], v[20:21], off
	s_nop 0
	global_load_dwordx4 v[20:23], v[22:23], off
	v_addc_co_u32_e32 v25, vcc, -1, v141, vcc
	v_add_co_u32_e32 v26, vcc, s46, v140
	v_add_f32_e32 v130, v98, v99
	s_nop 0
	v_addc_co_u32_e32 v27, vcc, -1, v141, vcc
	global_load_dwordx4 v[124:127], v[24:25], off
	global_load_dwordx4 v[88:91], v[26:27], off
	v_add_co_u32_e32 v24, vcc, 0xffffec00, v140
	v_add_f32_e32 v129, v129, v130
	s_nop 0
	v_addc_co_u32_e32 v25, vcc, -1, v141, vcc
	v_add_co_u32_e32 v26, vcc, 0xfffff000, v140
	v_add_f32_e32 v130, v68, v69
	s_nop 0
	v_addc_co_u32_e32 v27, vcc, -1, v141, vcc
	global_load_dwordx4 v[56:59], v[24:25], off
	s_nop 0
	global_load_dwordx4 v[24:27], v[26:27], off
	v_add_co_u32_e32 v28, vcc, 0xfffff400, v140
	v_add_f32_e32 v131, v70, v71
	s_nop 0
	v_addc_co_u32_e32 v29, vcc, -1, v141, vcc
	v_add_co_u32_e32 v30, vcc, 0xfffff800, v140
	v_add_f32_e32 v129, 0, v129
	s_nop 0
	v_addc_co_u32_e32 v31, vcc, -1, v141, vcc
	global_load_dwordx4 v[120:123], v[28:29], off
	global_load_dwordx4 v[92:95], v[30:31], off
	v_add_co_u32_e32 v28, vcc, s76, v140
	v_add_f32_e32 v130, v130, v131
	s_nop 0
	v_addc_co_u32_e32 v29, vcc, -1, v141, vcc
	global_load_dwordx4 v[60:63], v[28:29], off
	s_nop 0
	global_load_dwordx4 v[28:31], v[140:141], off
	v_add_f32_e32 v129, v129, v130
	s_waitcnt vmcnt(0)
	v_add_f32_e32 v130, v36, v37
	v_add_f32_e32 v131, v38, v39
	v_add_f32_e32 v130, v130, v131
	v_add_f32_e32 v129, v129, v130
	v_add_f32_e32 v130, v4, v5
	v_add_f32_e32 v131, v6, v7
	v_add_f32_e32 v130, v130, v131
	v_add_f32_e32 v129, v129, v130
	v_add_f32_e32 v130, v108, v109
	v_add_f32_e32 v131, v110, v111
	v_add_f32_e32 v130, v130, v131
	v_add_f32_e32 v131, v72, v73
	v_add_f32_e32 v132, v74, v75
	v_add_f32_e32 v130, 0, v130
	v_add_f32_e32 v131, v131, v132
	v_add_f32_e32 v130, v130, v131
	v_add_f32_e32 v131, v40, v41
	v_add_f32_e32 v132, v42, v43
	v_add_f32_e32 v131, v131, v132
	v_add_f32_e32 v130, v130, v131
	v_add_f32_e32 v131, v8, v9
	v_add_f32_e32 v132, v10, v11
	v_add_f32_e32 v131, v131, v132
	v_add_f32_e32 v130, v130, v131
	s_waitcnt lgkmcnt(0)
	v_add_f32_e32 v131, v100, v101
	v_add_f32_e32 v132, v102, v103
	v_add_f32_e32 v131, v131, v132
	v_add_f32_e32 v132, v76, v77
	v_add_f32_e32 v133, v78, v79
	v_add_f32_e32 v131, 0, v131
	v_add_f32_e32 v132, v132, v133
	v_add_f32_e32 v131, v131, v132
	v_add_f32_e32 v132, v44, v45
	v_add_f32_e32 v133, v46, v47
	v_add_f32_e32 v132, v132, v133
	v_add_f32_e32 v131, v131, v132
	v_add_f32_e32 v132, v12, v13
	v_add_f32_e32 v133, v14, v15
	v_add_f32_e32 v132, v132, v133
	v_add_f32_e32 v131, v131, v132
	v_add_f32_e32 v132, v116, v117
	v_add_f32_e32 v133, v118, v119
	v_add_f32_e32 v132, v132, v133
	v_add_f32_e32 v133, v80, v81
	v_add_f32_e32 v142, v82, v83
	v_add_f32_e32 v132, 0, v132
	v_add_f32_e32 v133, v133, v142
	v_add_f32_e32 v132, v132, v133
	v_add_f32_e32 v133, v48, v49
	v_add_f32_e32 v142, v50, v51
	v_add_f32_e32 v133, v133, v142
	v_add_f32_e32 v132, v132, v133
	v_add_f32_e32 v133, v16, v17
	v_add_f32_e32 v142, v18, v19
	v_add_f32_e32 v133, v133, v142
	v_add_f32_e32 v132, v132, v133
	v_add_f32_e32 v133, v112, v113
	v_add_f32_e32 v142, v114, v115
	v_add_f32_e32 v133, v133, v142
	v_add_f32_e32 v142, v84, v85
	v_add_f32_e32 v143, v86, v87
	v_add_f32_e32 v133, 0, v133
	v_add_f32_e32 v142, v142, v143
	v_add_f32_e32 v133, v133, v142
	v_add_f32_e32 v142, v52, v53
	v_add_f32_e32 v143, v54, v55
	v_add_f32_e32 v142, v142, v143
	v_add_f32_e32 v133, v133, v142
	v_add_f32_e32 v142, v20, v21
	v_add_f32_e32 v143, v22, v23
	v_add_f32_e32 v142, v142, v143
	v_add_f32_e32 v142, v133, v142
	v_add_f32_e32 v133, v124, v125
	v_add_f32_e32 v143, v126, v127
	v_add_f32_e32 v133, v133, v143
	v_add_f32_e32 v143, v88, v89
	v_add_f32_e32 v144, v90, v91
	v_add_f32_e32 v133, 0, v133
	v_add_f32_e32 v143, v143, v144
	v_add_f32_e32 v133, v133, v143
	v_add_f32_e32 v143, v56, v57
	v_add_f32_e32 v144, v58, v59
	v_add_f32_e32 v143, v143, v144
	v_add_f32_e32 v133, v133, v143
	v_add_f32_e32 v143, v24, v25
	v_add_f32_e32 v144, v26, v27
	v_add_f32_e32 v143, v143, v144
	v_add_f32_e32 v143, v133, v143
	v_add_f32_e32 v133, v120, v121
	v_add_f32_e32 v144, v122, v123
	v_add_f32_e32 v133, v133, v144
	ds_swizzle_b32 v144, v128 offset:swizzle(SWAP,1)
	v_add_f32_e32 v145, v92, v93
	v_add_f32_e32 v146, v94, v95
	v_add_f32_e32 v133, 0, v133
	v_add_f32_e32 v145, v145, v146
	s_waitcnt lgkmcnt(0)
	v_add_f32_e32 v128, v128, v144
	v_add_f32_e32 v133, v133, v145
	ds_swizzle_b32 v145, v129 offset:swizzle(SWAP,1)
	ds_swizzle_b32 v144, v128 offset:swizzle(SWAP,2)
	v_add_f32_e32 v146, v60, v61
	v_add_f32_e32 v147, v62, v63
	v_add_f32_e32 v146, v146, v147
	s_waitcnt lgkmcnt(1)
	v_add_f32_e32 v129, v129, v145
	s_waitcnt lgkmcnt(0)
	v_add_f32_e32 v128, v128, v144
	ds_swizzle_b32 v145, v129 offset:swizzle(SWAP,2)
	ds_swizzle_b32 v144, v128 offset:swizzle(SWAP,4)
	v_add_f32_e32 v133, v133, v146
	v_add_f32_e32 v146, v28, v29
	v_add_f32_e32 v147, v30, v31
	s_waitcnt lgkmcnt(1)
	v_add_f32_e32 v129, v129, v145
	s_waitcnt lgkmcnt(0)
	v_add_f32_e32 v128, v128, v144
	ds_swizzle_b32 v145, v129 offset:swizzle(SWAP,4)
	ds_swizzle_b32 v144, v128 offset:swizzle(SWAP,8)
	v_add_f32_e32 v146, v146, v147
	v_add_f32_e32 v146, v133, v146
	s_waitcnt lgkmcnt(1)
	v_add_f32_e32 v129, v129, v145
	s_waitcnt lgkmcnt(0)
	v_add_f32_e32 v128, v128, v144
	ds_swizzle_b32 v145, v129 offset:swizzle(SWAP,8)
	ds_swizzle_b32 v144, v128 offset:swizzle(SWAP,16)
	s_waitcnt lgkmcnt(1)
	v_add_f32_e32 v129, v129, v145
	s_waitcnt lgkmcnt(0)
	v_add_f32_e32 v128, v128, v144
	ds_swizzle_b32 v144, v129 offset:swizzle(SWAP,16)
	ds_swizzle_b32 v145, v130 offset:swizzle(SWAP,1)
	v_mov_b32_e32 v133, v128
	s_nop 1
	v_permlane32_swap_b32_e32 v128, v133
	v_add_f32_e32 v165, v128, v133
	s_waitcnt lgkmcnt(1)
	v_add_f32_e32 v128, v129, v144
	ds_swizzle_b32 v144, v131 offset:swizzle(SWAP,1)
	s_waitcnt lgkmcnt(1)
	v_add_f32_e32 v129, v130, v145
	ds_swizzle_b32 v130, v129 offset:swizzle(SWAP,2)
	v_mov_b32_e32 v133, v128
	s_nop 1
	v_permlane32_swap_b32_e32 v128, v133
	s_waitcnt lgkmcnt(1)
	v_add_f32_e32 v131, v131, v144
	ds_swizzle_b32 v144, v131 offset:swizzle(SWAP,2)
	v_add_f32_e32 v164, v128, v133
	ds_swizzle_b32 v128, v132 offset:swizzle(SWAP,1)
	s_waitcnt lgkmcnt(2)
	v_add_f32_e32 v129, v129, v130
	ds_swizzle_b32 v130, v129 offset:swizzle(SWAP,4)
	s_waitcnt lgkmcnt(2)
	v_add_f32_e32 v131, v131, v144
	ds_swizzle_b32 v133, v131 offset:swizzle(SWAP,4)
	s_waitcnt lgkmcnt(2)
	v_add_f32_e32 v128, v132, v128
	ds_swizzle_b32 v132, v128 offset:swizzle(SWAP,2)
	s_waitcnt lgkmcnt(2)
	v_add_f32_e32 v129, v129, v130
	ds_swizzle_b32 v130, v129 offset:swizzle(SWAP,8)
	s_waitcnt lgkmcnt(2)
	v_add_f32_e32 v131, v131, v133
	ds_swizzle_b32 v133, v131 offset:swizzle(SWAP,8)
	s_waitcnt lgkmcnt(2)
	v_add_f32_e32 v128, v128, v132
	ds_swizzle_b32 v132, v128 offset:swizzle(SWAP,4)
	s_waitcnt lgkmcnt(2)
	v_add_f32_e32 v129, v129, v130
	ds_swizzle_b32 v130, v129 offset:swizzle(SWAP,16)
	s_waitcnt lgkmcnt(2)
	v_add_f32_e32 v131, v131, v133
	ds_swizzle_b32 v144, v131 offset:swizzle(SWAP,16)
	s_waitcnt lgkmcnt(2)
	v_add_f32_e32 v128, v128, v132
	ds_swizzle_b32 v132, v128 offset:swizzle(SWAP,8)
	s_waitcnt lgkmcnt(2)
	v_add_f32_e32 v129, v129, v130
	v_mov_b32_e32 v130, v129
	s_nop 1
	v_permlane32_swap_b32_e32 v129, v130
	v_add_f32_e32 v133, v129, v130
	s_waitcnt lgkmcnt(1)
	v_add_f32_e32 v129, v131, v144
	ds_swizzle_b32 v144, v142 offset:swizzle(SWAP,1)
	s_waitcnt lgkmcnt(1)
	v_add_f32_e32 v128, v128, v132
	ds_swizzle_b32 v131, v128 offset:swizzle(SWAP,16)
	v_mov_b32_e32 v130, v129
	s_nop 1
	v_permlane32_swap_b32_e32 v129, v130
	v_add_f32_e32 v132, v129, v130
	s_waitcnt lgkmcnt(1)
	v_add_f32_e32 v129, v142, v144
	ds_swizzle_b32 v142, v143 offset:swizzle(SWAP,1)
	s_waitcnt lgkmcnt(1)
	v_add_f32_e32 v128, v128, v131
	ds_swizzle_b32 v130, v129 offset:swizzle(SWAP,2)
	v_mov_b32_e32 v131, v128
	s_nop 1
	v_permlane32_swap_b32_e32 v128, v131
	s_waitcnt lgkmcnt(1)
	v_add_f32_e32 v142, v143, v142
	v_add_f32_e32 v131, v128, v131
	ds_swizzle_b32 v128, v146 offset:swizzle(SWAP,1)
	ds_swizzle_b32 v143, v142 offset:swizzle(SWAP,2)
	s_waitcnt lgkmcnt(2)
	v_add_f32_e32 v129, v129, v130
	ds_swizzle_b32 v130, v129 offset:swizzle(SWAP,4)
	v_fmamk_f32 v151, v165, 0xba800000, v107
	s_waitcnt lgkmcnt(2)
	v_add_f32_e32 v128, v146, v128
	s_waitcnt lgkmcnt(1)
	v_add_f32_e32 v142, v142, v143
	ds_swizzle_b32 v144, v128 offset:swizzle(SWAP,2)
	ds_swizzle_b32 v143, v142 offset:swizzle(SWAP,4)
	s_waitcnt lgkmcnt(2)
	v_add_f32_e32 v129, v129, v130
	ds_swizzle_b32 v130, v129 offset:swizzle(SWAP,8)
	v_fmamk_f32 v105, v165, 0xba800000, v105
	s_waitcnt lgkmcnt(2)
	v_add_f32_e32 v128, v128, v144
	s_waitcnt lgkmcnt(1)
	v_add_f32_e32 v142, v142, v143
	ds_swizzle_b32 v144, v128 offset:swizzle(SWAP,4)
	ds_swizzle_b32 v143, v142 offset:swizzle(SWAP,8)
	s_waitcnt lgkmcnt(2)
	v_add_f32_e32 v129, v129, v130
	ds_swizzle_b32 v130, v129 offset:swizzle(SWAP,16)
	v_fmamk_f32 v150, v165, 0xba800000, v106
	s_waitcnt lgkmcnt(2)
	v_add_f32_e32 v128, v128, v144
	s_waitcnt lgkmcnt(1)
	v_add_f32_e32 v142, v142, v143
	ds_swizzle_b32 v144, v128 offset:swizzle(SWAP,8)
	ds_swizzle_b32 v143, v142 offset:swizzle(SWAP,16)
	s_waitcnt lgkmcnt(2)
	v_add_f32_e32 v129, v129, v130
	v_mov_b32_e32 v130, v129
	s_nop 1
	v_permlane32_swap_b32_e32 v129, v130
	s_waitcnt lgkmcnt(1)
	v_add_f32_e32 v128, v128, v144
	v_add_f32_e32 v130, v129, v130
	s_waitcnt lgkmcnt(0)
	v_add_f32_e32 v129, v142, v143
	ds_swizzle_b32 v142, v128 offset:swizzle(SWAP,16)
	v_fmac_f32_e32 v104, 0xba800000, v165
	v_mul_f32_e32 v106, v105, v105
	v_mul_f32_e32 v107, v151, v151
	v_fmac_f32_e32 v106, v104, v104
	s_waitcnt lgkmcnt(0)
	v_add_f32_e32 v128, v128, v142
	v_mov_b32_e32 v142, v128
	s_nop 1
	v_permlane32_swap_b32_e32 v128, v142
	v_fmac_f32_e32 v107, v150, v150
	v_fmamk_f32 v67, v165, 0xba800000, v67
	v_fmamk_f32 v65, v165, 0xba800000, v65
	v_add_f32_e32 v128, v128, v142
	v_add_f32_e32 v106, v106, v107
	v_fmamk_f32 v66, v165, 0xba800000, v66
	v_fmac_f32_e32 v64, 0xba800000, v165
	v_mul_f32_e32 v107, v65, v65
	v_mul_f32_e32 v142, v67, v67
	v_fmac_f32_e32 v107, v64, v64
	v_fmac_f32_e32 v142, v66, v66
	v_add_f32_e32 v107, v107, v142
	v_fmamk_f32 v35, v165, 0xba800000, v35
	v_fmamk_f32 v33, v165, 0xba800000, v33
	v_add_f32_e32 v106, v106, v107
	v_fmamk_f32 v34, v165, 0xba800000, v34
	v_fmac_f32_e32 v32, 0xba800000, v165
	v_mul_f32_e32 v107, v33, v33
	v_mul_f32_e32 v142, v35, v35
	v_fmac_f32_e32 v107, v32, v32
	v_fmac_f32_e32 v142, v34, v34
	v_add_f32_e32 v107, v107, v142
	v_fmamk_f32 v3, v165, 0xba800000, v3
	v_fmamk_f32 v1, v165, 0xba800000, v1
	v_add_f32_e32 v106, v107, v106
	v_fmamk_f32 v2, v165, 0xba800000, v2
	v_fmac_f32_e32 v0, 0xba800000, v165
	v_mul_f32_e32 v107, v1, v1
	v_mul_f32_e32 v142, v3, v3
	v_fmac_f32_e32 v107, v0, v0
	v_fmac_f32_e32 v142, v2, v2
	v_add_f32_e32 v107, v107, v142
	v_fmamk_f32 v99, v164, 0xba800000, v99
	v_fmamk_f32 v97, v164, 0xba800000, v97
	v_add_f32_e32 v166, v107, v106
	v_fmamk_f32 v98, v164, 0xba800000, v98
	v_fmac_f32_e32 v96, 0xba800000, v164
	v_mul_f32_e32 v106, v97, v97
	v_mul_f32_e32 v107, v99, v99
	v_fmac_f32_e32 v106, v96, v96
	v_fmac_f32_e32 v107, v98, v98
	v_add_f32_e32 v142, v106, v107
	v_fmamk_f32 v107, v164, 0xba800000, v71
	v_fmamk_f32 v69, v164, 0xba800000, v69
	v_fmamk_f32 v106, v164, 0xba800000, v70
	v_fmac_f32_e32 v68, 0xba800000, v164
	v_mul_f32_e32 v70, v69, v69
	v_mul_f32_e32 v71, v107, v107
	v_fmac_f32_e32 v70, v68, v68
	v_fmac_f32_e32 v71, v106, v106
	v_add_f32_e32 v70, v70, v71
	v_fmamk_f32 v39, v164, 0xba800000, v39
	v_fmamk_f32 v37, v164, 0xba800000, v37
	v_add_f32_e32 v70, v142, v70
	v_fmamk_f32 v38, v164, 0xba800000, v38
	v_fmac_f32_e32 v36, 0xba800000, v164
	v_mul_f32_e32 v71, v37, v37
	v_mul_f32_e32 v142, v39, v39
	v_fmac_f32_e32 v71, v36, v36
	v_fmac_f32_e32 v142, v38, v38
	v_add_f32_e32 v71, v71, v142
	v_fmamk_f32 v7, v164, 0xba800000, v7
	v_fmamk_f32 v5, v164, 0xba800000, v5
	v_add_f32_e32 v70, v71, v70
	v_fmamk_f32 v6, v164, 0xba800000, v6
	v_fmac_f32_e32 v4, 0xba800000, v164
	v_mul_f32_e32 v71, v5, v5
	v_mul_f32_e32 v142, v7, v7
	v_fmac_f32_e32 v71, v4, v4
	v_fmac_f32_e32 v142, v6, v6
	v_add_f32_e32 v71, v71, v142
	v_fmamk_f32 v153, v133, 0xba800000, v111
	v_fmamk_f32 v109, v133, 0xba800000, v109
	v_add_f32_e32 v167, v71, v70
	v_fmamk_f32 v152, v133, 0xba800000, v110
	v_fmac_f32_e32 v108, 0xba800000, v133
	v_mul_f32_e32 v70, v109, v109
	v_mul_f32_e32 v71, v153, v153
	v_fmac_f32_e32 v70, v108, v108
	v_fmac_f32_e32 v71, v152, v152
	v_fmamk_f32 v111, v133, 0xba800000, v75
	v_fmamk_f32 v73, v133, 0xba800000, v73
	v_add_f32_e32 v70, v70, v71
	v_fmamk_f32 v110, v133, 0xba800000, v74
	v_fmac_f32_e32 v72, 0xba800000, v133
	v_mul_f32_e32 v71, v73, v73
	v_mul_f32_e32 v74, v111, v111
	v_fmac_f32_e32 v71, v72, v72
	v_fmac_f32_e32 v74, v110, v110
	v_add_f32_e32 v71, v71, v74
	v_fmamk_f32 v43, v133, 0xba800000, v43
	v_fmamk_f32 v41, v133, 0xba800000, v41
	v_add_f32_e32 v70, v70, v71
	v_fmamk_f32 v42, v133, 0xba800000, v42
	v_fmac_f32_e32 v40, 0xba800000, v133
	v_mul_f32_e32 v71, v41, v41
	v_mul_f32_e32 v74, v43, v43
	v_fmac_f32_e32 v71, v40, v40
	v_fmac_f32_e32 v74, v42, v42
	v_add_f32_e32 v71, v71, v74
	v_fmamk_f32 v11, v133, 0xba800000, v11
	v_fmamk_f32 v9, v133, 0xba800000, v9
	v_add_f32_e32 v70, v71, v70
	v_fmamk_f32 v10, v133, 0xba800000, v10
	v_fmac_f32_e32 v8, 0xba800000, v133
	v_mul_f32_e32 v71, v9, v9
	v_mul_f32_e32 v74, v11, v11
	v_fmac_f32_e32 v71, v8, v8
	v_fmac_f32_e32 v74, v10, v10
	v_mov_b32_e32 v143, v129
	v_add_f32_e32 v71, v71, v74
	v_fmamk_f32 v155, v132, 0xba800000, v103
	v_fmamk_f32 v101, v132, 0xba800000, v101
	v_permlane32_swap_b32_e32 v129, v143
	v_add_f32_e32 v74, v71, v70
	v_fmamk_f32 v154, v132, 0xba800000, v102
	v_fmac_f32_e32 v100, 0xba800000, v132
	v_mul_f32_e32 v70, v101, v101
	v_mul_f32_e32 v71, v155, v155
	v_add_f32_e32 v129, v129, v143
	v_fmac_f32_e32 v70, v100, v100
	v_fmac_f32_e32 v71, v154, v154
	v_fmamk_f32 v143, v132, 0xba800000, v79
	v_fmamk_f32 v77, v132, 0xba800000, v77
	v_add_f32_e32 v70, v70, v71
	v_fmamk_f32 v142, v132, 0xba800000, v78
	v_fmac_f32_e32 v76, 0xba800000, v132
	v_mul_f32_e32 v71, v77, v77
	v_mul_f32_e32 v75, v143, v143
	v_fmac_f32_e32 v71, v76, v76
	v_fmac_f32_e32 v75, v142, v142
	v_add_f32_e32 v71, v71, v75
	v_fmamk_f32 v47, v132, 0xba800000, v47
	v_fmamk_f32 v45, v132, 0xba800000, v45
	v_add_f32_e32 v70, v70, v71
	v_fmamk_f32 v46, v132, 0xba800000, v46
	v_fmac_f32_e32 v44, 0xba800000, v132
	v_mul_f32_e32 v71, v45, v45
	v_mul_f32_e32 v75, v47, v47
	v_fmac_f32_e32 v71, v44, v44
	v_fmac_f32_e32 v75, v46, v46
	v_add_f32_e32 v71, v71, v75
	v_fmamk_f32 v15, v132, 0xba800000, v15
	v_fmamk_f32 v13, v132, 0xba800000, v13
	v_add_f32_e32 v70, v71, v70
	v_fmamk_f32 v14, v132, 0xba800000, v14
	v_fmac_f32_e32 v12, 0xba800000, v132
	v_mul_f32_e32 v71, v13, v13
	v_mul_f32_e32 v75, v15, v15
	v_fmac_f32_e32 v71, v12, v12
	v_fmac_f32_e32 v75, v14, v14
	v_add_f32_e32 v71, v71, v75
	v_fmamk_f32 v157, v131, 0xba800000, v119
	v_fmamk_f32 v117, v131, 0xba800000, v117
	v_add_f32_e32 v75, v71, v70
	v_fmamk_f32 v156, v131, 0xba800000, v118
	v_fmac_f32_e32 v116, 0xba800000, v131
	v_mul_f32_e32 v70, v117, v117
	v_mul_f32_e32 v71, v157, v157
	v_fmac_f32_e32 v70, v116, v116
	v_fmac_f32_e32 v71, v156, v156
	v_fmamk_f32 v145, v131, 0xba800000, v83
	v_fmamk_f32 v81, v131, 0xba800000, v81
	v_add_f32_e32 v70, v70, v71
	v_fmamk_f32 v144, v131, 0xba800000, v82
	v_fmac_f32_e32 v80, 0xba800000, v131
	v_mul_f32_e32 v71, v81, v81
	v_mul_f32_e32 v78, v145, v145
	v_fmac_f32_e32 v71, v80, v80
	v_fmac_f32_e32 v78, v144, v144
	v_add_f32_e32 v71, v71, v78
	v_fmamk_f32 v51, v131, 0xba800000, v51
	v_fmamk_f32 v49, v131, 0xba800000, v49
	v_add_f32_e32 v70, v70, v71
	v_fmamk_f32 v50, v131, 0xba800000, v50
	v_fmac_f32_e32 v48, 0xba800000, v131
	v_mul_f32_e32 v71, v49, v49
	v_mul_f32_e32 v78, v51, v51
	v_fmac_f32_e32 v71, v48, v48
	v_fmac_f32_e32 v78, v50, v50
	v_add_f32_e32 v71, v71, v78
	v_fmamk_f32 v19, v131, 0xba800000, v19
	v_fmamk_f32 v17, v131, 0xba800000, v17
	v_add_f32_e32 v70, v71, v70
	v_fmamk_f32 v18, v131, 0xba800000, v18
	v_fmac_f32_e32 v16, 0xba800000, v131
	v_mul_f32_e32 v71, v17, v17
	v_mul_f32_e32 v78, v19, v19
	v_fmac_f32_e32 v71, v16, v16
	v_fmac_f32_e32 v78, v18, v18
	v_add_f32_e32 v71, v71, v78
	v_fmamk_f32 v159, v130, 0xba800000, v115
	v_fmamk_f32 v113, v130, 0xba800000, v113
	v_add_f32_e32 v79, v71, v70
	v_fmamk_f32 v158, v130, 0xba800000, v114
	v_fmac_f32_e32 v112, 0xba800000, v130
	v_mul_f32_e32 v70, v113, v113
	v_mul_f32_e32 v71, v159, v159
	v_fmac_f32_e32 v70, v112, v112
	v_fmac_f32_e32 v71, v158, v158
	v_fmamk_f32 v147, v130, 0xba800000, v87
	v_fmamk_f32 v85, v130, 0xba800000, v85
	v_add_f32_e32 v70, v70, v71
	v_fmamk_f32 v146, v130, 0xba800000, v86
	v_fmac_f32_e32 v84, 0xba800000, v130
	v_mul_f32_e32 v71, v85, v85
	v_mul_f32_e32 v78, v147, v147
	v_fmac_f32_e32 v71, v84, v84
	v_fmac_f32_e32 v78, v146, v146
	v_add_f32_e32 v71, v71, v78
	v_fmamk_f32 v55, v130, 0xba800000, v55
	v_fmamk_f32 v53, v130, 0xba800000, v53
	v_add_f32_e32 v70, v70, v71
	v_fmamk_f32 v54, v130, 0xba800000, v54
	v_fmac_f32_e32 v52, 0xba800000, v130
	v_mul_f32_e32 v71, v53, v53
	v_mul_f32_e32 v78, v55, v55
	v_fmac_f32_e32 v71, v52, v52
	v_fmac_f32_e32 v78, v54, v54
	v_add_f32_e32 v71, v71, v78
	v_fmamk_f32 v23, v130, 0xba800000, v23
	v_fmamk_f32 v21, v130, 0xba800000, v21
	v_add_f32_e32 v70, v71, v70
	v_fmamk_f32 v22, v130, 0xba800000, v22
	v_fmac_f32_e32 v20, 0xba800000, v130
	v_mul_f32_e32 v71, v21, v21
	v_mul_f32_e32 v78, v23, v23
	v_fmac_f32_e32 v71, v20, v20
	v_fmac_f32_e32 v78, v22, v22
	v_add_f32_e32 v71, v71, v78
	v_fmamk_f32 v161, v129, 0xba800000, v127
	v_fmamk_f32 v125, v129, 0xba800000, v125
	v_add_f32_e32 v83, v71, v70
	v_fmamk_f32 v160, v129, 0xba800000, v126
	v_fmac_f32_e32 v124, 0xba800000, v129
	v_mul_f32_e32 v70, v125, v125
	v_mul_f32_e32 v71, v161, v161
	v_fmac_f32_e32 v70, v124, v124
	v_fmac_f32_e32 v71, v160, v160
	v_fmamk_f32 v149, v129, 0xba800000, v91
	v_fmamk_f32 v89, v129, 0xba800000, v89
	v_add_f32_e32 v70, v70, v71
	v_fmamk_f32 v148, v129, 0xba800000, v90
	v_fmac_f32_e32 v88, 0xba800000, v129
	v_mul_f32_e32 v71, v89, v89
	v_mul_f32_e32 v78, v149, v149
	v_fmac_f32_e32 v71, v88, v88
	v_fmac_f32_e32 v78, v148, v148
	v_add_f32_e32 v71, v71, v78
	v_fmamk_f32 v59, v129, 0xba800000, v59
	v_fmamk_f32 v57, v129, 0xba800000, v57
	v_add_f32_e32 v70, v70, v71
	v_fmamk_f32 v58, v129, 0xba800000, v58
	v_fmac_f32_e32 v56, 0xba800000, v129
	v_mul_f32_e32 v71, v57, v57
	v_mul_f32_e32 v78, v59, v59
	v_fmac_f32_e32 v71, v56, v56
	v_fmac_f32_e32 v78, v58, v58
	v_add_f32_e32 v71, v71, v78
	v_fmamk_f32 v27, v129, 0xba800000, v27
	v_fmamk_f32 v25, v129, 0xba800000, v25
	v_add_f32_e32 v70, v71, v70
	v_fmamk_f32 v26, v129, 0xba800000, v26
	v_fmac_f32_e32 v24, 0xba800000, v129
	v_mul_f32_e32 v71, v25, v25
	v_mul_f32_e32 v78, v27, v27
	v_fmac_f32_e32 v71, v24, v24
	v_fmac_f32_e32 v78, v26, v26
	v_add_f32_e32 v71, v71, v78
	v_fmamk_f32 v163, v128, 0xba800000, v123
	v_fmamk_f32 v121, v128, 0xba800000, v121
	v_add_f32_e32 v87, v71, v70
	v_fmamk_f32 v162, v128, 0xba800000, v122
	v_fmac_f32_e32 v120, 0xba800000, v128
	v_mul_f32_e32 v70, v121, v121
	v_mul_f32_e32 v71, v163, v163
	v_fmac_f32_e32 v70, v120, v120
	v_fmac_f32_e32 v71, v162, v162
	v_fmamk_f32 v123, v128, 0xba800000, v95
	v_fmamk_f32 v93, v128, 0xba800000, v93
	v_add_f32_e32 v70, v70, v71
	v_fmamk_f32 v122, v128, 0xba800000, v94
	v_fmac_f32_e32 v92, 0xba800000, v128
	v_mul_f32_e32 v71, v93, v93
	v_mul_f32_e32 v78, v123, v123
	v_fmac_f32_e32 v71, v92, v92
	v_fmac_f32_e32 v78, v122, v122
	v_add_f32_e32 v71, v71, v78
	v_add_f32_e32 v78, v70, v71
	v_fmamk_f32 v70, v128, 0xba800000, v62
	ds_swizzle_b32 v62, v166 offset:swizzle(SWAP,1)
	v_fmamk_f32 v71, v128, 0xba800000, v63
	v_fmamk_f32 v61, v128, 0xba800000, v61
	v_fmac_f32_e32 v60, 0xba800000, v128
	v_mul_f32_e32 v63, v61, v61
	s_waitcnt lgkmcnt(0)
	v_add_f32_e32 v62, v166, v62
	ds_swizzle_b32 v86, v62 offset:swizzle(SWAP,2)
	v_mul_f32_e32 v82, v71, v71
	v_fmac_f32_e32 v63, v60, v60
	v_fmac_f32_e32 v82, v70, v70
	v_add_f32_e32 v63, v63, v82
	s_waitcnt lgkmcnt(0)
	v_add_f32_e32 v62, v62, v86
	v_add_f32_e32 v63, v63, v78
	ds_swizzle_b32 v78, v62 offset:swizzle(SWAP,4)
	ds_swizzle_b32 v82, v167 offset:swizzle(SWAP,1)
	v_fmamk_f32 v31, v128, 0xba800000, v31
	v_fmamk_f32 v29, v128, 0xba800000, v29
	v_fmamk_f32 v30, v128, 0xba800000, v30
	s_waitcnt lgkmcnt(1)
	v_add_f32_e32 v62, v62, v78
	s_waitcnt lgkmcnt(0)
	v_add_f32_e32 v82, v167, v82
	ds_swizzle_b32 v78, v62 offset:swizzle(SWAP,8)
	ds_swizzle_b32 v90, v82 offset:swizzle(SWAP,2)
	v_fmac_f32_e32 v28, 0xba800000, v128
	v_mul_f32_e32 v86, v29, v29
	v_mul_f32_e32 v91, v31, v31
	s_waitcnt lgkmcnt(1)
	v_add_f32_e32 v62, v62, v78
	s_waitcnt lgkmcnt(0)
	v_add_f32_e32 v82, v82, v90
	ds_swizzle_b32 v78, v62 offset:swizzle(SWAP,16)
	ds_swizzle_b32 v90, v82 offset:swizzle(SWAP,4)
	v_fmac_f32_e32 v86, v28, v28
	v_fmac_f32_e32 v91, v30, v30
	v_add_f32_e32 v86, v86, v91
	s_waitcnt lgkmcnt(1)
	v_add_f32_e32 v62, v62, v78
	s_waitcnt lgkmcnt(0)
	v_add_f32_e32 v78, v82, v90
	ds_swizzle_b32 v90, v74 offset:swizzle(SWAP,1)
	ds_swizzle_b32 v82, v78 offset:swizzle(SWAP,8)
	v_add_f32_e32 v63, v86, v63
	v_mov_b32_e32 v86, v62
	s_nop 1
	v_permlane32_swap_b32_e32 v62, v86
	s_waitcnt lgkmcnt(1)
	v_add_f32_e32 v74, v74, v90
	s_waitcnt lgkmcnt(0)
	v_add_f32_e32 v78, v78, v82
	ds_swizzle_b32 v90, v74 offset:swizzle(SWAP,2)
	v_add_f32_e32 v62, v62, v86
	ds_swizzle_b32 v86, v75 offset:swizzle(SWAP,1)
	ds_swizzle_b32 v82, v78 offset:swizzle(SWAP,16)
	ds_swizzle_b32 v91, v83 offset:swizzle(SWAP,1)
	s_waitcnt lgkmcnt(3)
	v_add_f32_e32 v74, v74, v90
	ds_swizzle_b32 v90, v79 offset:swizzle(SWAP,1)
	s_waitcnt lgkmcnt(3)
	v_add_f32_e32 v75, v75, v86
	s_waitcnt lgkmcnt(2)
	v_add_f32_e32 v78, v78, v82
	ds_swizzle_b32 v82, v74 offset:swizzle(SWAP,4)
	ds_swizzle_b32 v86, v75 offset:swizzle(SWAP,2)
	s_waitcnt lgkmcnt(2)
	v_add_f32_e32 v79, v79, v90
	ds_swizzle_b32 v90, v79 offset:swizzle(SWAP,2)
	ds_swizzle_b32 v103, v87 offset:swizzle(SWAP,1)
	s_waitcnt lgkmcnt(3)
	v_add_f32_e32 v74, v74, v82
	s_waitcnt lgkmcnt(2)
	v_add_f32_e32 v75, v75, v86
	ds_swizzle_b32 v82, v74 offset:swizzle(SWAP,8)
	ds_swizzle_b32 v86, v75 offset:swizzle(SWAP,4)
	s_waitcnt lgkmcnt(3)
	v_add_f32_e32 v79, v79, v90
	ds_swizzle_b32 v90, v79 offset:swizzle(SWAP,4)
	v_fmamk_f32 v62, v62, 0x3a800000, v243
	s_waitcnt lgkmcnt(2)
	v_add_f32_e32 v74, v74, v82
	s_waitcnt lgkmcnt(1)
	v_add_f32_e32 v75, v75, v86
	ds_swizzle_b32 v82, v74 offset:swizzle(SWAP,16)
	ds_swizzle_b32 v86, v75 offset:swizzle(SWAP,8)
	s_waitcnt lgkmcnt(2)
	v_add_f32_e32 v79, v79, v90
	ds_swizzle_b32 v90, v79 offset:swizzle(SWAP,8)
	v_cmp_gt_f32_e32 vcc, s84, v62
	s_waitcnt lgkmcnt(2)
	v_add_f32_e32 v82, v74, v82
	s_waitcnt lgkmcnt(1)
	v_add_f32_e32 v74, v75, v86
	ds_swizzle_b32 v75, v74 offset:swizzle(SWAP,16)
	v_mov_b32_e32 v102, v78
	v_mov_b32_e32 v95, v82
	s_nop 0
	v_permlane32_swap_b32_e32 v78, v102
	s_waitcnt lgkmcnt(0)
	v_add_f32_e32 v86, v74, v75
	v_add_f32_e32 v74, v79, v90
	v_add_f32_e32 v79, v83, v91
	ds_swizzle_b32 v75, v74 offset:swizzle(SWAP,16)
	ds_swizzle_b32 v83, v79 offset:swizzle(SWAP,2)
	v_mov_b32_e32 v94, v86
	v_permlane32_swap_b32_e32 v82, v95
	s_waitcnt lgkmcnt(1)
	v_add_f32_e32 v90, v74, v75
	s_waitcnt lgkmcnt(0)
	v_add_f32_e32 v74, v79, v83
	v_add_f32_e32 v79, v87, v103
	ds_swizzle_b32 v87, v63 offset:swizzle(SWAP,1)
	ds_swizzle_b32 v75, v74 offset:swizzle(SWAP,4)
	ds_swizzle_b32 v83, v79 offset:swizzle(SWAP,2)
	v_mov_b32_e32 v91, v90
	v_permlane32_swap_b32_e32 v86, v94
	s_waitcnt lgkmcnt(2)
	v_add_f32_e32 v63, v63, v87
	s_waitcnt lgkmcnt(1)
	v_add_f32_e32 v74, v74, v75
	s_waitcnt lgkmcnt(0)
	v_add_f32_e32 v79, v79, v83
	ds_swizzle_b32 v87, v63 offset:swizzle(SWAP,2)
	ds_swizzle_b32 v75, v74 offset:swizzle(SWAP,8)
	ds_swizzle_b32 v83, v79 offset:swizzle(SWAP,4)
	v_permlane32_swap_b32_e32 v90, v91
	s_waitcnt lgkmcnt(2)
	v_add_f32_e32 v63, v63, v87
	s_waitcnt lgkmcnt(1)
	v_add_f32_e32 v74, v74, v75
	s_waitcnt lgkmcnt(0)
	v_add_f32_e32 v79, v79, v83
	ds_swizzle_b32 v114, v63 offset:swizzle(SWAP,4)
	ds_swizzle_b32 v75, v74 offset:swizzle(SWAP,16)
	ds_swizzle_b32 v103, v79 offset:swizzle(SWAP,8)
	s_waitcnt lgkmcnt(2)
	v_add_f32_e32 v63, v63, v114
	s_waitcnt lgkmcnt(1)
	v_add_f32_e32 v83, v74, v75
	s_waitcnt lgkmcnt(0)
	v_add_f32_e32 v74, v79, v103
	ds_swizzle_b32 v103, v63 offset:swizzle(SWAP,8)
	ds_swizzle_b32 v75, v74 offset:swizzle(SWAP,16)
	v_mov_b32_e32 v87, v83
	s_nop 1
	v_permlane32_swap_b32_e32 v83, v87
	s_waitcnt lgkmcnt(1)
	v_add_f32_e32 v63, v63, v103
	v_mul_f32_e32 v103, 0x4f800000, v62
	s_waitcnt lgkmcnt(0)
	v_add_f32_e32 v75, v74, v75
	ds_swizzle_b32 v74, v63 offset:swizzle(SWAP,16)
	v_cndmask_b32_e32 v103, v62, v103, vcc
	v_sqrt_f32_e32 v114, v103
	v_mov_b32_e32 v79, v75
	s_nop 1
	v_permlane32_swap_b32_e32 v75, v79
	s_waitcnt lgkmcnt(0)
	v_add_f32_e32 v62, v63, v74
	v_add_u32_e32 v63, -1, v114
	v_fma_f32 v74, -v63, v114, v103
	v_cmp_ge_f32_e64 s[6:7], 0, v74
	v_add_u32_e32 v74, 1, v114
	s_nop 0
	v_cndmask_b32_e64 v63, v114, v63, s[6:7]
	v_fma_f32 v114, -v74, v114, v103
	v_cmp_lt_f32_e64 s[6:7], 0, v114
	s_nop 1
	v_cndmask_b32_e64 v63, v63, v74, s[6:7]
	v_mul_f32_e32 v74, 0x37800000, v63
	v_cndmask_b32_e32 v63, v63, v74, vcc
	v_cmp_class_f32_e32 vcc, v103, v248
	s_nop 1
	v_cndmask_b32_e32 v74, v63, v103, vcc
	v_div_scale_f32 v103, s[6:7], v74, v74, 1.0
	v_rcp_f32_e32 v114, v103
	v_mov_b32_e32 v63, v62
	s_nop 1
	v_permlane32_swap_b32_e32 v62, v63
	v_fma_f32 v115, -v103, v114, 1.0
	v_fmac_f32_e32 v114, v115, v114
	v_div_scale_f32 v115, vcc, 1.0, v74, 1.0
	v_mul_f32_e32 v118, v115, v114
	v_fma_f32 v119, -v103, v118, v115
	v_fmac_f32_e32 v118, v119, v114
	v_fma_f32 v103, -v103, v118, v115
	v_div_fmas_f32 v103, v103, v114, v118
	v_div_fixup_f32 v74, v103, v74, 1.0
	s_and_saveexec_b64 s[6:7], s[4:5]
	s_cbranch_execz .LBB0_1561
	v_mov_b32_e32 v103, s13
	v_add_co_u32_e32 v118, vcc, 0x1fa00000, v103
	v_mov_b32_e32 v103, s11
	v_mul_f32_e32 v114, 0x3a800000, v165
	v_addc_co_u32_e32 v119, vcc, 0, v103, vcc
	v_mov_b32_e32 v115, v74
	global_store_dwordx2 v[118:119], v[114:115], off

.LBB0_1578:
	s_mul_hi_i32 s2, s13, 0x10624dd3
	s_lshr_b32 s3, s2, 31
	s_ashr_i32 s2, s2, 3
	s_add_i32 s2, s2, s3
	s_lshl_b32 s6, s2, 6
	s_mulk_i32 s2, 0xf060
	s_add_i32 s2, s10, s2
	s_ashr_i32 s3, s2, 31
	v_or_b32_e32 v27, s6, v24
	v_lshl_add_u64 v[0:1], s[2:3], 2, v[20:21]
	v_mad_i64_i32 v[2:3], s[14:15], v27, s29, v[0:1]
	global_load_dwordx4 v[28:31], v[2:3], off
	v_or_b32_e32 v2, 8, v27
	v_mad_i64_i32 v[2:3], s[14:15], v2, s29, v[0:1]
	global_load_dwordx4 v[36:39], v[2:3], off
	v_or_b32_e32 v2, 16, v27
	v_mad_i64_i32 v[2:3], s[14:15], v2, s29, v[0:1]
	global_load_dwordx4 v[40:43], v[2:3], off
	v_or_b32_e32 v2, 24, v27
	v_mad_i64_i32 v[2:3], s[14:15], v2, s29, v[0:1]
	global_load_dwordx4 v[16:19], v[2:3], off
	v_or_b32_e32 v2, 32, v27
	v_mad_i64_i32 v[2:3], s[14:15], v2, s29, v[0:1]
	global_load_dwordx4 v[12:15], v[2:3], off
	v_or_b32_e32 v2, 40, v27
	v_mad_i64_i32 v[2:3], s[14:15], v2, s29, v[0:1]
	global_load_dwordx4 v[8:11], v[2:3], off
	v_or_b32_e32 v2, 48, v27
	v_mad_i64_i32 v[2:3], s[14:15], v2, s29, v[0:1]
	global_load_dwordx4 v[4:7], v[2:3], off
	v_or_b32_e32 v2, 56, v27
	v_mad_i64_i32 v[0:1], s[14:15], v2, s29, v[0:1]
	global_load_dwordx4 v[0:3], v[0:1], off
	v_add_u32_e32 v27, 0x420, v26
	s_ashr_i32 s7, s6, 31
	s_add_i32 s13, s13, s16
	s_add_i32 s10, s10, s11
	s_cmpk_lt_i32 s13, 0x7d0
	s_waitcnt vmcnt(0) lgkmcnt(0)
	ds_write2_b32 v26, v28, v29 offset1:1
	ds_write2_b32 v26, v30, v31 offset0:2 offset1:3
	ds_write2_b32 v27, v36, v37 offset1:1
	v_add_u32_e32 v27, 0x428, v26
	ds_write2_b32 v27, v38, v39 offset1:1
	v_add_u32_e32 v27, 0x840, v26
	ds_write2_b32 v27, v40, v41 offset1:1
	v_add_u32_e32 v27, 0x848, v26
	ds_write2_b32 v27, v42, v43 offset1:1
	v_add_u32_e32 v27, 0xc60, v26
	ds_write2_b32 v27, v16, v17 offset1:1
	v_add_u32_e32 v16, 0xc68, v26
	ds_write2_b32 v16, v18, v19 offset1:1
	v_add_u32_e32 v16, 0x1080, v26
	ds_write2_b32 v16, v12, v13 offset1:1
	v_add_u32_e32 v12, 0x1088, v26
	ds_write2_b32 v12, v14, v15 offset1:1
	v_add_u32_e32 v12, 0x14a0, v26
	ds_write2_b32 v12, v8, v9 offset1:1
	v_add_u32_e32 v8, 0x14a8, v26
	ds_write2_b32 v8, v10, v11 offset1:1
	v_add_u32_e32 v8, 0x18c0, v26
	ds_write2_b32 v8, v4, v5 offset1:1
	v_add_u32_e32 v4, 0x18c8, v26
	ds_write2_b32 v4, v6, v7 offset1:1
	v_add_u32_e32 v4, 0x1ce0, v26
	ds_write2_b32 v4, v0, v1 offset1:1
	v_add_u32_e32 v0, 0x1ce8, v26
	ds_write2_b32 v0, v2, v3 offset1:1
	ds_read_b32 v0, v25
	ds_read_b32 v1, v25 offset:132
	v_lshl_add_u64 v[4:5], s[6:7], 1, v[22:23]
	s_waitcnt lgkmcnt(0)
	v_cvt_pk_bf16_f32 v0, v0, v1
	ds_read_b32 v1, v25 offset:264
	ds_read_b32 v2, v25 offset:396
	s_waitcnt lgkmcnt(0)
	v_cvt_pk_bf16_f32 v1, v1, v2
	ds_read_b32 v2, v25 offset:528
	ds_read_b32 v3, v25 offset:660
	s_waitcnt lgkmcnt(0)
	v_cvt_pk_bf16_f32 v2, v2, v3
	ds_read_b32 v3, v25 offset:792
	ds_read_b32 v6, v25 offset:924
	s_waitcnt lgkmcnt(0)
	v_cvt_pk_bf16_f32 v3, v3, v6
	v_add_u32_e32 v6, s2, v24
	v_ashrrev_i32_e32 v7, 31, v6
	v_lshlrev_b64 v[8:9], 11, v[6:7]
	v_lshl_add_u64 v[8:9], v[4:5], 0, v[8:9]
	global_store_dwordx4 v[8:9], v[0:3], off
	ds_read_b32 v0, v25 offset:32
	ds_read_b32 v1, v25 offset:164
	v_add_u32_e32 v8, 8, v6
	v_ashrrev_i32_e32 v9, 31, v8
	v_lshlrev_b64 v[8:9], 11, v[8:9]
	v_lshl_add_u64 v[8:9], v[4:5], 0, v[8:9]
	s_waitcnt lgkmcnt(0)
	v_cvt_pk_bf16_f32 v0, v0, v1
	ds_read_b32 v1, v25 offset:296
	ds_read_b32 v2, v25 offset:428
	s_waitcnt lgkmcnt(0)
	v_cvt_pk_bf16_f32 v1, v1, v2
	ds_read_b32 v2, v25 offset:560
	ds_read_b32 v3, v25 offset:692
	s_waitcnt lgkmcnt(0)
	v_cvt_pk_bf16_f32 v2, v2, v3
	ds_read_b32 v3, v25 offset:824
	ds_read_b32 v7, v25 offset:956
	s_waitcnt lgkmcnt(0)
	v_cvt_pk_bf16_f32 v3, v3, v7
	global_store_dwordx4 v[8:9], v[0:3], off
	ds_read_b32 v0, v25 offset:64
	ds_read_b32 v1, v25 offset:196
	v_add_u32_e32 v8, 16, v6
	v_ashrrev_i32_e32 v9, 31, v8
	v_lshlrev_b64 v[8:9], 11, v[8:9]
	v_lshl_add_u64 v[8:9], v[4:5], 0, v[8:9]
	s_waitcnt lgkmcnt(0)
	v_cvt_pk_bf16_f32 v0, v0, v1
	ds_read_b32 v1, v25 offset:328
	ds_read_b32 v2, v25 offset:460
	v_add_u32_e32 v6, 24, v6
	s_waitcnt lgkmcnt(0)
	v_cvt_pk_bf16_f32 v1, v1, v2
	ds_read_b32 v2, v25 offset:592
	ds_read_b32 v3, v25 offset:724
	s_waitcnt lgkmcnt(0)
	v_cvt_pk_bf16_f32 v2, v2, v3
	ds_read_b32 v3, v25 offset:856
	ds_read_b32 v7, v25 offset:988
	s_waitcnt lgkmcnt(0)
	v_cvt_pk_bf16_f32 v3, v3, v7
	global_store_dwordx4 v[8:9], v[0:3], off
	ds_read_b32 v0, v25 offset:96
	ds_read_b32 v1, v25 offset:228
	s_waitcnt lgkmcnt(0)
	v_cvt_pk_bf16_f32 v0, v0, v1
	ds_read_b32 v1, v25 offset:360
	ds_read_b32 v2, v25 offset:492
	s_waitcnt lgkmcnt(0)
	v_cvt_pk_bf16_f32 v1, v1, v2
	ds_read_b32 v2, v25 offset:624
	ds_read_b32 v3, v25 offset:756
	s_waitcnt lgkmcnt(0)
	v_cvt_pk_bf16_f32 v2, v2, v3
	ds_read_b32 v3, v25 offset:888
	ds_read_b32 v7, v25 offset:1020
	s_waitcnt lgkmcnt(0)
	v_cvt_pk_bf16_f32 v3, v3, v7
	v_ashrrev_i32_e32 v7, 31, v6
	v_lshlrev_b64 v[6:7], 11, v[6:7]
	v_lshl_add_u64 v[4:5], v[4:5], 0, v[6:7]
	global_store_dwordx4 v[4:5], v[0:3], off
	s_cbranch_scc1 .LBB0_1578

.LBB0_1581:
	s_ashr_i32 s4, s15, 31
	s_lshr_b32 s4, s4, 25
	s_add_i32 s4, s15, s4
	s_ashr_i32 s4, s4, 7
	s_lshl_b32 s10, s4, 6
	s_lshl_b32 s4, s4, 12
	s_sub_i32 s4, s13, s4
	s_ashr_i32 s5, s4, 31
	v_or_b32_e32 v27, s10, v24
	v_lshl_add_u64 v[0:1], s[4:5], 2, v[20:21]
	v_mad_i64_i32 v[2:3], s[18:19], v27, s29, v[0:1]
	global_load_dwordx4 v[28:31], v[2:3], off
	v_or_b32_e32 v2, 8, v27
	v_mad_i64_i32 v[2:3], s[18:19], v2, s29, v[0:1]
	global_load_dwordx4 v[36:39], v[2:3], off
	v_or_b32_e32 v2, 16, v27
	v_mad_i64_i32 v[2:3], s[18:19], v2, s29, v[0:1]
	global_load_dwordx4 v[40:43], v[2:3], off
	v_or_b32_e32 v2, 24, v27
	v_mad_i64_i32 v[2:3], s[18:19], v2, s29, v[0:1]
	global_load_dwordx4 v[16:19], v[2:3], off
	v_or_b32_e32 v2, 32, v27
	v_mad_i64_i32 v[2:3], s[18:19], v2, s29, v[0:1]
	global_load_dwordx4 v[12:15], v[2:3], off
	v_or_b32_e32 v2, 40, v27
	v_mad_i64_i32 v[2:3], s[18:19], v2, s29, v[0:1]
	global_load_dwordx4 v[8:11], v[2:3], off
	v_or_b32_e32 v2, 48, v27
	v_mad_i64_i32 v[2:3], s[18:19], v2, s29, v[0:1]
	global_load_dwordx4 v[4:7], v[2:3], off
	v_or_b32_e32 v2, 56, v27
	v_mad_i64_i32 v[0:1], s[18:19], v2, s29, v[0:1]
	global_load_dwordx4 v[0:3], v[0:1], off
	v_add_u32_e32 v27, 0x420, v26
	s_ashr_i32 s11, s10, 31
	s_add_i32 s15, s15, s16
	s_add_i32 s13, s13, s14
	s_cmpk_lt_i32 s15, 0x800
	s_waitcnt vmcnt(0) lgkmcnt(0)
	ds_write2_b32 v26, v28, v29 offset1:1
	ds_write2_b32 v26, v30, v31 offset0:2 offset1:3
	ds_write2_b32 v27, v36, v37 offset1:1
	v_add_u32_e32 v27, 0x428, v26
	ds_write2_b32 v27, v38, v39 offset1:1
	v_add_u32_e32 v27, 0x840, v26
	ds_write2_b32 v27, v40, v41 offset1:1
	v_add_u32_e32 v27, 0x848, v26
	ds_write2_b32 v27, v42, v43 offset1:1
	v_add_u32_e32 v27, 0xc60, v26
	ds_write2_b32 v27, v16, v17 offset1:1
	v_add_u32_e32 v16, 0xc68, v26
	ds_write2_b32 v16, v18, v19 offset1:1
	v_add_u32_e32 v16, 0x1080, v26
	ds_write2_b32 v16, v12, v13 offset1:1
	v_add_u32_e32 v12, 0x1088, v26
	ds_write2_b32 v12, v14, v15 offset1:1
	v_add_u32_e32 v12, 0x14a0, v26
	ds_write2_b32 v12, v8, v9 offset1:1
	v_add_u32_e32 v8, 0x14a8, v26
	ds_write2_b32 v8, v10, v11 offset1:1
	v_add_u32_e32 v8, 0x18c0, v26
	ds_write2_b32 v8, v4, v5 offset1:1
	v_add_u32_e32 v4, 0x18c8, v26
	ds_write2_b32 v4, v6, v7 offset1:1
	v_add_u32_e32 v4, 0x1ce0, v26
	ds_write2_b32 v4, v0, v1 offset1:1
	v_add_u32_e32 v0, 0x1ce8, v26
	ds_write2_b32 v0, v2, v3 offset1:1
	ds_read_b32 v0, v25
	ds_read_b32 v1, v25 offset:132
	v_lshl_add_u64 v[4:5], s[10:11], 1, v[22:23]
	s_waitcnt lgkmcnt(0)
	v_cvt_pk_bf16_f32 v0, v0, v1
	ds_read_b32 v1, v25 offset:264
	ds_read_b32 v2, v25 offset:396
	s_waitcnt lgkmcnt(0)
	v_cvt_pk_bf16_f32 v1, v1, v2
	ds_read_b32 v2, v25 offset:528
	ds_read_b32 v3, v25 offset:660
	s_waitcnt lgkmcnt(0)
	v_cvt_pk_bf16_f32 v2, v2, v3
	ds_read_b32 v3, v25 offset:792
	ds_read_b32 v6, v25 offset:924
	s_waitcnt lgkmcnt(0)
	v_cvt_pk_bf16_f32 v3, v3, v6
	v_add_u32_e32 v6, s4, v24
	v_ashrrev_i32_e32 v7, 31, v6
	v_lshlrev_b64 v[8:9], 11, v[6:7]
	v_lshl_add_u64 v[8:9], v[4:5], 0, v[8:9]
	global_store_dwordx4 v[8:9], v[0:3], off
	ds_read_b32 v0, v25 offset:32
	ds_read_b32 v1, v25 offset:164
	v_add_u32_e32 v8, 8, v6
	v_ashrrev_i32_e32 v9, 31, v8
	v_lshlrev_b64 v[8:9], 11, v[8:9]
	v_lshl_add_u64 v[8:9], v[4:5], 0, v[8:9]
	s_waitcnt lgkmcnt(0)
	v_cvt_pk_bf16_f32 v0, v0, v1
	ds_read_b32 v1, v25 offset:296
	ds_read_b32 v2, v25 offset:428
	s_waitcnt lgkmcnt(0)
	v_cvt_pk_bf16_f32 v1, v1, v2
	ds_read_b32 v2, v25 offset:560
	ds_read_b32 v3, v25 offset:692
	s_waitcnt lgkmcnt(0)
	v_cvt_pk_bf16_f32 v2, v2, v3
	ds_read_b32 v3, v25 offset:824
	ds_read_b32 v7, v25 offset:956
	s_waitcnt lgkmcnt(0)
	v_cvt_pk_bf16_f32 v3, v3, v7
	global_store_dwordx4 v[8:9], v[0:3], off
	ds_read_b32 v0, v25 offset:64
	ds_read_b32 v1, v25 offset:196
	v_add_u32_e32 v8, 16, v6
	v_ashrrev_i32_e32 v9, 31, v8
	v_lshlrev_b64 v[8:9], 11, v[8:9]
	v_lshl_add_u64 v[8:9], v[4:5], 0, v[8:9]
	s_waitcnt lgkmcnt(0)
	v_cvt_pk_bf16_f32 v0, v0, v1
	ds_read_b32 v1, v25 offset:328
	ds_read_b32 v2, v25 offset:460
	v_add_u32_e32 v6, 24, v6
	s_waitcnt lgkmcnt(0)
	v_cvt_pk_bf16_f32 v1, v1, v2
	ds_read_b32 v2, v25 offset:592
	ds_read_b32 v3, v25 offset:724
	s_waitcnt lgkmcnt(0)
	v_cvt_pk_bf16_f32 v2, v2, v3
	ds_read_b32 v3, v25 offset:856
	ds_read_b32 v7, v25 offset:988
	s_waitcnt lgkmcnt(0)
	v_cvt_pk_bf16_f32 v3, v3, v7
	global_store_dwordx4 v[8:9], v[0:3], off
	ds_read_b32 v0, v25 offset:96
	ds_read_b32 v1, v25 offset:228
	s_waitcnt lgkmcnt(0)
	v_cvt_pk_bf16_f32 v0, v0, v1
	ds_read_b32 v1, v25 offset:360
	ds_read_b32 v2, v25 offset:492
	s_waitcnt lgkmcnt(0)
	v_cvt_pk_bf16_f32 v1, v1, v2
	ds_read_b32 v2, v25 offset:624
	ds_read_b32 v3, v25 offset:756
	s_waitcnt lgkmcnt(0)
	v_cvt_pk_bf16_f32 v2, v2, v3
	ds_read_b32 v3, v25 offset:888
	ds_read_b32 v7, v25 offset:1020
	s_waitcnt lgkmcnt(0)
	v_cvt_pk_bf16_f32 v3, v3, v7
	v_ashrrev_i32_e32 v7, 31, v6
	v_lshlrev_b64 v[6:7], 11, v[6:7]
	v_lshl_add_u64 v[4:5], v[4:5], 0, v[6:7]
	global_store_dwordx4 v[4:5], v[0:3], off
	s_cbranch_scc1 .LBB0_1581

.LBB0_1584:
	s_ashr_i32 s4, s13, 31
	s_lshr_b32 s4, s4, 25
	s_add_i32 s4, s13, s4
	s_ashr_i32 s4, s4, 7
	s_lshl_b32 s6, s4, 6
	s_lshl_b32 s4, s4, 12
	s_sub_i32 s4, s10, s4
	v_or_b32_e32 v0, s6, v33
	s_ashr_i32 s5, s4, 31
	v_ashrrev_i32_e32 v1, 31, v0
	v_lshl_add_u64 v[2:3], s[4:5], 2, v[28:29]
	v_lshlrev_b64 v[4:5], 14, v[0:1]
	v_lshl_add_u64 v[4:5], v[2:3], 0, v[4:5]
	global_load_dwordx4 v[38:41], v[4:5], off
	v_or_b32_e32 v4, 8, v0
	v_ashrrev_i32_e32 v5, 31, v4
	v_lshlrev_b64 v[4:5], 14, v[4:5]
	v_lshl_add_u64 v[4:5], v[2:3], 0, v[4:5]
	global_load_dwordx4 v[24:27], v[4:5], off
	v_or_b32_e32 v4, 16, v0
	v_ashrrev_i32_e32 v5, 31, v4
	v_lshlrev_b64 v[4:5], 14, v[4:5]
	v_lshl_add_u64 v[4:5], v[2:3], 0, v[4:5]
	global_load_dwordx4 v[20:23], v[4:5], off
	v_or_b32_e32 v4, 24, v0
	v_ashrrev_i32_e32 v5, 31, v4
	v_lshlrev_b64 v[4:5], 14, v[4:5]
	v_lshl_add_u64 v[4:5], v[2:3], 0, v[4:5]
	global_load_dwordx4 v[16:19], v[4:5], off
	v_or_b32_e32 v4, 32, v0
	v_ashrrev_i32_e32 v5, 31, v4
	v_lshlrev_b64 v[4:5], 14, v[4:5]
	v_lshl_add_u64 v[4:5], v[2:3], 0, v[4:5]
	global_load_dwordx4 v[12:15], v[4:5], off
	v_or_b32_e32 v4, 40, v0
	v_ashrrev_i32_e32 v5, 31, v4
	v_lshlrev_b64 v[4:5], 14, v[4:5]
	v_lshl_add_u64 v[4:5], v[2:3], 0, v[4:5]
	global_load_dwordx4 v[8:11], v[4:5], off
	v_or_b32_e32 v4, 48, v0
	v_ashrrev_i32_e32 v5, 31, v4
	v_lshlrev_b64 v[4:5], 14, v[4:5]
	v_or_b32_e32 v0, 56, v0
	v_lshl_add_u64 v[4:5], v[2:3], 0, v[4:5]
	v_ashrrev_i32_e32 v1, 31, v0
	global_load_dwordx4 v[4:7], v[4:5], off
	v_lshlrev_b64 v[0:1], 14, v[0:1]
	v_lshl_add_u64 v[0:1], v[2:3], 0, v[0:1]
	global_load_dwordx4 v[0:3], v[0:1], off
	s_ashr_i32 s7, s6, 31
	s_add_i32 s13, s13, s16
	s_add_i32 s10, s10, s11
	s_cmpk_lt_i32 s13, 0x800
	s_waitcnt vmcnt(0) lgkmcnt(0)
	ds_write2_b32 v37, v38, v39 offset1:1
	ds_write2_b32 v37, v40, v41 offset0:2 offset1:3
	v_add_u32_e32 v38, 0x420, v37
	ds_write2_b32 v38, v24, v25 offset1:1
	v_add_u32_e32 v24, 0x428, v37
	ds_write2_b32 v24, v26, v27 offset1:1
	v_add_u32_e32 v24, 0x840, v37
	ds_write2_b32 v24, v20, v21 offset1:1
	v_add_u32_e32 v20, 0x848, v37
	ds_write2_b32 v20, v22, v23 offset1:1
	v_add_u32_e32 v20, 0xc60, v37
	ds_write2_b32 v20, v16, v17 offset1:1
	v_add_u32_e32 v16, 0xc68, v37
	ds_write2_b32 v16, v18, v19 offset1:1
	v_add_u32_e32 v16, 0x1080, v37
	ds_write2_b32 v16, v12, v13 offset1:1
	v_add_u32_e32 v12, 0x1088, v37
	ds_write2_b32 v12, v14, v15 offset1:1
	v_add_u32_e32 v12, 0x14a0, v37
	ds_write2_b32 v12, v8, v9 offset1:1
	v_add_u32_e32 v8, 0x14a8, v37
	ds_write2_b32 v8, v10, v11 offset1:1
	v_add_u32_e32 v8, 0x18c0, v37
	ds_write2_b32 v8, v4, v5 offset1:1
	v_add_u32_e32 v4, 0x18c8, v37
	ds_write2_b32 v4, v6, v7 offset1:1
	v_add_u32_e32 v4, 0x1ce0, v37
	ds_write2_b32 v4, v0, v1 offset1:1
	v_add_u32_e32 v0, 0x1ce8, v37
	ds_write2_b32 v0, v2, v3 offset1:1
	ds_read_b32 v0, v36
	ds_read_b32 v1, v36 offset:132
	v_lshl_add_u64 v[4:5], s[6:7], 1, v[30:31]
	s_waitcnt lgkmcnt(0)
	v_cvt_pk_bf16_f32 v0, v0, v1
	ds_read_b32 v1, v36 offset:264
	ds_read_b32 v2, v36 offset:396
	s_waitcnt lgkmcnt(0)
	v_cvt_pk_bf16_f32 v1, v1, v2
	ds_read_b32 v2, v36 offset:528
	ds_read_b32 v3, v36 offset:660
	s_waitcnt lgkmcnt(0)
	v_cvt_pk_bf16_f32 v2, v2, v3
	ds_read_b32 v3, v36 offset:792
	ds_read_b32 v6, v36 offset:924
	s_waitcnt lgkmcnt(0)
	v_cvt_pk_bf16_f32 v3, v3, v6
	v_add_u32_e32 v6, s4, v33
	v_ashrrev_i32_e32 v7, 31, v6
	v_lshlrev_b64 v[8:9], 11, v[6:7]
	v_lshl_add_u64 v[8:9], v[4:5], 0, v[8:9]
	global_store_dwordx4 v[8:9], v[0:3], off
	ds_read_b32 v0, v36 offset:32
	ds_read_b32 v1, v36 offset:164
	v_add_u32_e32 v8, 8, v6
	v_ashrrev_i32_e32 v9, 31, v8
	v_lshlrev_b64 v[8:9], 11, v[8:9]
	v_lshl_add_u64 v[8:9], v[4:5], 0, v[8:9]
	s_waitcnt lgkmcnt(0)
	v_cvt_pk_bf16_f32 v0, v0, v1
	ds_read_b32 v1, v36 offset:296
	ds_read_b32 v2, v36 offset:428
	s_waitcnt lgkmcnt(0)
	v_cvt_pk_bf16_f32 v1, v1, v2
	ds_read_b32 v2, v36 offset:560
	ds_read_b32 v3, v36 offset:692
	s_waitcnt lgkmcnt(0)
	v_cvt_pk_bf16_f32 v2, v2, v3
	ds_read_b32 v3, v36 offset:824
	ds_read_b32 v7, v36 offset:956
	s_waitcnt lgkmcnt(0)
	v_cvt_pk_bf16_f32 v3, v3, v7
	global_store_dwordx4 v[8:9], v[0:3], off
	ds_read_b32 v0, v36 offset:64
	ds_read_b32 v1, v36 offset:196
	v_add_u32_e32 v8, 16, v6
	v_ashrrev_i32_e32 v9, 31, v8
	v_lshlrev_b64 v[8:9], 11, v[8:9]
	v_lshl_add_u64 v[8:9], v[4:5], 0, v[8:9]
	s_waitcnt lgkmcnt(0)
	v_cvt_pk_bf16_f32 v0, v0, v1
	ds_read_b32 v1, v36 offset:328
	ds_read_b32 v2, v36 offset:460
	v_add_u32_e32 v6, 24, v6
	s_waitcnt lgkmcnt(0)
	v_cvt_pk_bf16_f32 v1, v1, v2
	ds_read_b32 v2, v36 offset:592
	ds_read_b32 v3, v36 offset:724
	s_waitcnt lgkmcnt(0)
	v_cvt_pk_bf16_f32 v2, v2, v3
	ds_read_b32 v3, v36 offset:856
	ds_read_b32 v7, v36 offset:988
	s_waitcnt lgkmcnt(0)
	v_cvt_pk_bf16_f32 v3, v3, v7
	global_store_dwordx4 v[8:9], v[0:3], off
	ds_read_b32 v0, v36 offset:96
	ds_read_b32 v1, v36 offset:228
	s_waitcnt lgkmcnt(0)
	v_cvt_pk_bf16_f32 v0, v0, v1
	ds_read_b32 v1, v36 offset:360
	ds_read_b32 v2, v36 offset:492
	s_waitcnt lgkmcnt(0)
	v_cvt_pk_bf16_f32 v1, v1, v2
	ds_read_b32 v2, v36 offset:624
	ds_read_b32 v3, v36 offset:756
	s_waitcnt lgkmcnt(0)
	v_cvt_pk_bf16_f32 v2, v2, v3
	ds_read_b32 v3, v36 offset:888
	ds_read_b32 v7, v36 offset:1020
	s_waitcnt lgkmcnt(0)
	v_cvt_pk_bf16_f32 v3, v3, v7
	v_ashrrev_i32_e32 v7, 31, v6
	v_lshlrev_b64 v[6:7], 11, v[6:7]
	v_lshl_add_u64 v[4:5], v[4:5], 0, v[6:7]
	global_store_dwordx4 v[4:5], v[0:3], off
	s_cbranch_scc1 .LBB0_1584

.LBB0_1589:
	s_ashr_i32 s2, s10, 31
	s_lshr_b32 s2, s2, 27
	s_add_i32 s2, s10, s2
	s_ashr_i32 s2, s2, 5
	s_lshl_b32 s4, s2, 6
	s_lshl_b32 s2, s2, 10
	s_sub_i32 s2, s6, s2
	v_or_b32_e32 v0, s4, v35
	s_ashr_i32 s3, s2, 31
	v_ashrrev_i32_e32 v1, 31, v0
	v_lshl_add_u64 v[2:3], s[2:3], 2, v[30:31]
	v_lshlrev_b64 v[4:5], 12, v[0:1]
	v_lshl_add_u64 v[4:5], v[2:3], 0, v[4:5]
	global_load_dwordx4 v[42:45], v[4:5], off
	v_or_b32_e32 v4, 8, v0
	v_ashrrev_i32_e32 v5, 31, v4
	v_lshlrev_b64 v[4:5], 12, v[4:5]
	v_lshl_add_u64 v[4:5], v[2:3], 0, v[4:5]
	global_load_dwordx4 v[24:27], v[4:5], off
	v_or_b32_e32 v4, 16, v0
	v_ashrrev_i32_e32 v5, 31, v4
	v_lshlrev_b64 v[4:5], 12, v[4:5]
	v_lshl_add_u64 v[4:5], v[2:3], 0, v[4:5]
	global_load_dwordx4 v[20:23], v[4:5], off
	v_or_b32_e32 v4, 24, v0
	v_ashrrev_i32_e32 v5, 31, v4
	v_lshlrev_b64 v[4:5], 12, v[4:5]
	v_lshl_add_u64 v[4:5], v[2:3], 0, v[4:5]
	global_load_dwordx4 v[16:19], v[4:5], off
	v_or_b32_e32 v4, 32, v0
	v_ashrrev_i32_e32 v5, 31, v4
	v_lshlrev_b64 v[4:5], 12, v[4:5]
	v_lshl_add_u64 v[4:5], v[2:3], 0, v[4:5]
	global_load_dwordx4 v[12:15], v[4:5], off
	v_or_b32_e32 v4, 40, v0
	v_ashrrev_i32_e32 v5, 31, v4
	v_lshlrev_b64 v[4:5], 12, v[4:5]
	v_lshl_add_u64 v[4:5], v[2:3], 0, v[4:5]
	global_load_dwordx4 v[8:11], v[4:5], off
	v_or_b32_e32 v4, 48, v0
	v_ashrrev_i32_e32 v5, 31, v4
	v_lshlrev_b64 v[4:5], 12, v[4:5]
	v_or_b32_e32 v0, 56, v0
	v_lshl_add_u64 v[4:5], v[2:3], 0, v[4:5]
	v_ashrrev_i32_e32 v1, 31, v0
	global_load_dwordx4 v[4:7], v[4:5], off
	v_lshlrev_b64 v[0:1], 12, v[0:1]
	v_lshl_add_u64 v[0:1], v[2:3], 0, v[0:1]
	global_load_dwordx4 v[0:3], v[0:1], off
	v_add_u32_e32 v41, 0x420, v40
	s_ashr_i32 s5, s4, 31
	s_add_i32 s10, s10, s16
	s_add_i32 s6, s6, s7
	s_cmpk_lt_i32 s10, 0x800
	s_waitcnt vmcnt(0) lgkmcnt(0)
	ds_write2_b32 v40, v42, v43 offset1:1
	ds_write2_b32 v40, v44, v45 offset0:2 offset1:3
	ds_write2_b32 v41, v24, v25 offset1:1
	v_add_u32_e32 v24, 0x428, v40
	ds_write2_b32 v24, v26, v27 offset1:1
	v_add_u32_e32 v24, 0x840, v40
	ds_write2_b32 v24, v20, v21 offset1:1
	v_add_u32_e32 v20, 0x848, v40
	ds_write2_b32 v20, v22, v23 offset1:1
	v_add_u32_e32 v20, 0xc60, v40
	ds_write2_b32 v20, v16, v17 offset1:1
	v_add_u32_e32 v16, 0xc68, v40
	ds_write2_b32 v16, v18, v19 offset1:1
	v_add_u32_e32 v16, 0x1080, v40
	ds_write2_b32 v16, v12, v13 offset1:1
	v_add_u32_e32 v12, 0x1088, v40
	ds_write2_b32 v12, v14, v15 offset1:1
	v_add_u32_e32 v12, 0x14a0, v40
	ds_write2_b32 v12, v8, v9 offset1:1
	v_add_u32_e32 v8, 0x14a8, v40
	ds_write2_b32 v8, v10, v11 offset1:1
	v_add_u32_e32 v8, 0x18c0, v40
	ds_write2_b32 v8, v4, v5 offset1:1
	v_add_u32_e32 v4, 0x18c8, v40
	ds_write2_b32 v4, v6, v7 offset1:1
	v_add_u32_e32 v4, 0x1ce0, v40
	ds_write2_b32 v4, v0, v1 offset1:1
	v_add_u32_e32 v0, 0x1ce8, v40
	ds_write2_b32 v0, v2, v3 offset1:1
	ds_read_b32 v0, v29
	ds_read_b32 v1, v29 offset:132
	v_lshl_add_u64 v[4:5], s[4:5], 1, v[32:33]
	s_waitcnt lgkmcnt(0)
	v_cvt_pk_bf16_f32 v0, v0, v1
	ds_read_b32 v1, v29 offset:264
	ds_read_b32 v2, v29 offset:396
	s_waitcnt lgkmcnt(0)
	v_cvt_pk_bf16_f32 v1, v1, v2
	ds_read_b32 v2, v29 offset:528
	ds_read_b32 v3, v29 offset:660
	s_waitcnt lgkmcnt(0)
	v_cvt_pk_bf16_f32 v2, v2, v3
	ds_read_b32 v3, v29 offset:792
	ds_read_b32 v6, v29 offset:924
	s_waitcnt lgkmcnt(0)
	v_cvt_pk_bf16_f32 v3, v3, v6
	v_add_u32_e32 v6, s2, v35
	v_ashrrev_i32_e32 v7, 31, v6
	v_lshlrev_b64 v[8:9], 13, v[6:7]
	v_lshl_add_u64 v[8:9], v[4:5], 0, v[8:9]
	global_store_dwordx4 v[8:9], v[0:3], off
	ds_read_b32 v0, v29 offset:32
	ds_read_b32 v1, v29 offset:164
	v_add_u32_e32 v8, 8, v6
	v_ashrrev_i32_e32 v9, 31, v8
	v_lshlrev_b64 v[8:9], 13, v[8:9]
	v_lshl_add_u64 v[8:9], v[4:5], 0, v[8:9]
	s_waitcnt lgkmcnt(0)
	v_cvt_pk_bf16_f32 v0, v0, v1
	ds_read_b32 v1, v29 offset:296
	ds_read_b32 v2, v29 offset:428
	s_waitcnt lgkmcnt(0)
	v_cvt_pk_bf16_f32 v1, v1, v2
	ds_read_b32 v2, v29 offset:560
	ds_read_b32 v3, v29 offset:692
	s_waitcnt lgkmcnt(0)
	v_cvt_pk_bf16_f32 v2, v2, v3
	ds_read_b32 v3, v29 offset:824
	ds_read_b32 v7, v29 offset:956
	s_waitcnt lgkmcnt(0)
	v_cvt_pk_bf16_f32 v3, v3, v7
	global_store_dwordx4 v[8:9], v[0:3], off
	ds_read_b32 v0, v29 offset:64
	ds_read_b32 v1, v29 offset:196
	v_add_u32_e32 v8, 16, v6
	v_ashrrev_i32_e32 v9, 31, v8
	v_lshlrev_b64 v[8:9], 13, v[8:9]
	v_lshl_add_u64 v[8:9], v[4:5], 0, v[8:9]
	s_waitcnt lgkmcnt(0)
	v_cvt_pk_bf16_f32 v0, v0, v1
	ds_read_b32 v1, v29 offset:328
	ds_read_b32 v2, v29 offset:460
	v_add_u32_e32 v6, 24, v6
	s_waitcnt lgkmcnt(0)
	v_cvt_pk_bf16_f32 v1, v1, v2
	ds_read_b32 v2, v29 offset:592
	ds_read_b32 v3, v29 offset:724
	s_waitcnt lgkmcnt(0)
	v_cvt_pk_bf16_f32 v2, v2, v3
	ds_read_b32 v3, v29 offset:856
	ds_read_b32 v7, v29 offset:988
	s_waitcnt lgkmcnt(0)
	v_cvt_pk_bf16_f32 v3, v3, v7
	global_store_dwordx4 v[8:9], v[0:3], off
	ds_read_b32 v0, v29 offset:96
	ds_read_b32 v1, v29 offset:228
	s_waitcnt lgkmcnt(0)
	v_cvt_pk_bf16_f32 v0, v0, v1
	ds_read_b32 v1, v29 offset:360
	ds_read_b32 v2, v29 offset:492
	s_waitcnt lgkmcnt(0)
	v_cvt_pk_bf16_f32 v1, v1, v2
	ds_read_b32 v2, v29 offset:624
	ds_read_b32 v3, v29 offset:756
	s_waitcnt lgkmcnt(0)
	v_cvt_pk_bf16_f32 v2, v2, v3
	ds_read_b32 v3, v29 offset:888
	ds_read_b32 v7, v29 offset:1020
	s_waitcnt lgkmcnt(0)
	v_cvt_pk_bf16_f32 v3, v3, v7
	v_ashrrev_i32_e32 v7, 31, v6
	v_lshlrev_b64 v[6:7], 13, v[6:7]
	v_lshl_add_u64 v[4:5], v[4:5], 0, v[6:7]
	global_store_dwordx4 v[4:5], v[0:3], off
	s_cbranch_scc1 .LBB0_1589
	v_mov_b32_e32 v40, v35
	v_mov_b32_e32 v0, v28
	v_mov_b32_e32 v2, v34

.LBB0_1595:
	s_ashr_i32 s6, s14, 31
	s_lshr_b32 s6, s6, 27
	s_add_i32 s6, s14, s6
	s_ashr_i32 s6, s6, 5
	s_lshl_b32 s10, s6, 6
	s_lshl_b32 s6, s6, 10
	s_sub_i32 s6, s12, s6
	v_or_b32_e32 v34, s10, v40
	s_ashr_i32 s7, s6, 31
	v_ashrrev_i32_e32 v35, 31, v34
	v_or_b32_e32 v4, 8, v34
	v_lshl_add_u64 v[20:21], s[6:7], 2, v[16:17]
	v_lshlrev_b64 v[0:1], 12, v[34:35]
	v_ashrrev_i32_e32 v5, 31, v4
	v_or_b32_e32 v8, 16, v34
	v_lshl_add_u64 v[0:1], v[20:21], 0, v[0:1]
	v_lshlrev_b64 v[4:5], 12, v[4:5]
	v_ashrrev_i32_e32 v9, 31, v8
	v_or_b32_e32 v22, 24, v34
	global_load_dwordx4 v[0:3], v[0:1], off
	v_lshl_add_u64 v[4:5], v[20:21], 0, v[4:5]
	v_lshlrev_b64 v[8:9], 12, v[8:9]
	v_ashrrev_i32_e32 v23, 31, v22
	v_or_b32_e32 v26, 32, v34
	global_load_dwordx4 v[4:7], v[4:5], off
	v_lshl_add_u64 v[8:9], v[20:21], 0, v[8:9]
	v_lshlrev_b64 v[22:23], 12, v[22:23]
	v_ashrrev_i32_e32 v27, 31, v26
	global_load_dwordx4 v[8:11], v[8:9], off
	v_lshl_add_u64 v[22:23], v[20:21], 0, v[22:23]
	v_lshlrev_b64 v[26:27], 12, v[26:27]
	v_or_b32_e32 v30, 40, v34
	global_load_dwordx4 v[22:25], v[22:23], off
	v_lshl_add_u64 v[26:27], v[20:21], 0, v[26:27]
	v_ashrrev_i32_e32 v31, 31, v30
	global_load_dwordx4 v[26:29], v[26:27], off
	v_lshlrev_b64 v[30:31], 12, v[30:31]
	v_or_b32_e32 v42, 48, v34
	v_lshl_add_u64 v[30:31], v[20:21], 0, v[30:31]
	v_ashrrev_i32_e32 v43, 31, v42
	global_load_dwordx4 v[30:33], v[30:31], off
	v_lshlrev_b64 v[42:43], 12, v[42:43]
	v_or_b32_e32 v34, 56, v34
	v_lshl_add_u64 v[42:43], v[20:21], 0, v[42:43]
	v_ashrrev_i32_e32 v35, 31, v34
	global_load_dwordx4 v[42:45], v[42:43], off
	v_lshlrev_b64 v[34:35], 12, v[34:35]
	v_lshl_add_u64 v[20:21], v[20:21], 0, v[34:35]
	global_load_dwordx4 v[58:61], v[20:21], off
	v_add_u32_e32 v20, v53, v46
	s_ashr_i32 s11, s10, 31
	s_add_i32 s14, s14, s16
	s_add_i32 s12, s12, s13
	s_cmpk_lt_i32 s14, 0x80
	s_waitcnt vmcnt(0) lgkmcnt(0)
	ds_write2_b32 v20, v0, v1 offset1:1
	ds_write2_b32 v20, v2, v3 offset0:2 offset1:3
	v_add_u32_e32 v0, v53, v48
	ds_write2_b32 v0, v4, v5 offset1:1
	ds_write2_b32 v0, v6, v7 offset0:2 offset1:3
	v_add_u32_e32 v0, v53, v50
	ds_write2_b32 v0, v8, v9 offset1:1
	ds_write2_b32 v0, v10, v11 offset0:2 offset1:3
	v_add_u32_e32 v0, v53, v52
	ds_write2_b32 v0, v22, v23 offset1:1
	ds_write2_b32 v0, v24, v25 offset0:2 offset1:3
	v_add_u32_e32 v0, 0x1080, v20
	v_lshl_add_u64 v[4:5], s[10:11], 1, v[18:19]
	ds_write2_b32 v0, v26, v27 offset1:1
	v_add_u32_e32 v0, 0x1088, v20
	ds_write2_b32 v0, v28, v29 offset1:1
	v_add_u32_e32 v0, 0x14a0, v20
	ds_write2_b32 v0, v30, v31 offset1:1
	v_add_u32_e32 v0, 0x14a8, v20
	ds_write2_b32 v0, v32, v33 offset1:1
	v_add_u32_e32 v0, 0x18c0, v20
	ds_write2_b32 v0, v42, v43 offset1:1
	v_add_u32_e32 v0, 0x18c8, v20
	ds_write2_b32 v0, v44, v45 offset1:1
	v_add_u32_e32 v0, 0x1ce0, v20
	ds_write2_b32 v0, v58, v59 offset1:1
	v_add_u32_e32 v0, 0x1ce8, v20
	ds_write2_b32 v0, v60, v61 offset1:1
	ds_read2_b32 v[0:1], v54 offset1:33
	ds_read2_b32 v[2:3], v54 offset0:66 offset1:99
	ds_read2_b32 v[6:7], v54 offset0:198 offset1:231
	s_waitcnt lgkmcnt(2)
	v_cvt_pk_bf16_f32 v0, v0, v1
	s_waitcnt lgkmcnt(1)
	v_cvt_pk_bf16_f32 v1, v2, v3
	ds_read2_b32 v[2:3], v54 offset0:132 offset1:165
	s_waitcnt lgkmcnt(0)
	v_cvt_pk_bf16_f32 v2, v2, v3
	v_cvt_pk_bf16_f32 v3, v6, v7
	v_add_u32_e32 v6, s6, v40
	v_ashrrev_i32_e32 v7, 31, v6
	v_lshlrev_b64 v[6:7], 9, v[6:7]
	v_lshl_add_u64 v[6:7], v[4:5], 0, v[6:7]
	global_store_dwordx4 v[6:7], v[0:3], off
	ds_read2_b32 v[0:1], v55 offset1:33
	ds_read2_b32 v[2:3], v55 offset0:66 offset1:99
	ds_read2_b32 v[6:7], v55 offset0:198 offset1:231
	s_waitcnt lgkmcnt(0)
	v_cvt_pk_bf16_f32 v0, v0, v1
	v_cvt_pk_bf16_f32 v1, v2, v3
	ds_read2_b32 v[2:3], v55 offset0:132 offset1:165
	s_waitcnt lgkmcnt(0)
	v_cvt_pk_bf16_f32 v2, v2, v3
	v_cvt_pk_bf16_f32 v3, v6, v7
	v_add_u32_e32 v6, s6, v47
	v_ashrrev_i32_e32 v7, 31, v6
	v_lshlrev_b64 v[6:7], 9, v[6:7]
	v_lshl_add_u64 v[6:7], v[4:5], 0, v[6:7]
	global_store_dwordx4 v[6:7], v[0:3], off
	ds_read2_b32 v[0:1], v56 offset1:33
	ds_read2_b32 v[2:3], v56 offset0:66 offset1:99
	ds_read2_b32 v[6:7], v56 offset0:198 offset1:231
	s_waitcnt lgkmcnt(0)
	v_cvt_pk_bf16_f32 v0, v0, v1
	v_cvt_pk_bf16_f32 v1, v2, v3
	ds_read2_b32 v[2:3], v56 offset0:132 offset1:165
	s_waitcnt lgkmcnt(0)
	v_cvt_pk_bf16_f32 v2, v2, v3
	v_cvt_pk_bf16_f32 v3, v6, v7
	v_add_u32_e32 v6, s6, v49
	v_ashrrev_i32_e32 v7, 31, v6
	v_lshlrev_b64 v[6:7], 9, v[6:7]
	v_lshl_add_u64 v[6:7], v[4:5], 0, v[6:7]
	global_store_dwordx4 v[6:7], v[0:3], off
	ds_read2_b32 v[0:1], v57 offset1:33
	ds_read2_b32 v[2:3], v57 offset0:66 offset1:99
	ds_read2_b32 v[6:7], v57 offset0:198 offset1:231
	s_waitcnt lgkmcnt(0)
	v_cvt_pk_bf16_f32 v0, v0, v1
	v_cvt_pk_bf16_f32 v1, v2, v3
	ds_read2_b32 v[2:3], v57 offset0:132 offset1:165
	s_waitcnt lgkmcnt(0)
	v_cvt_pk_bf16_f32 v2, v2, v3
	v_cvt_pk_bf16_f32 v3, v6, v7
	v_add_u32_e32 v6, s6, v51
	v_ashrrev_i32_e32 v7, 31, v6
	v_lshlrev_b64 v[6:7], 9, v[6:7]
	v_lshl_add_u64 v[4:5], v[4:5], 0, v[6:7]
	global_store_dwordx4 v[4:5], v[0:3], off
	s_cbranch_scc1 .LBB0_1595
	s_branch .LBB0_1592

.LBB0_1598:
	s_ashr_i32 s6, s14, 31
	s_lshr_b32 s6, s6, 27
	s_add_i32 s6, s14, s6
	s_ashr_i32 s6, s6, 5
	s_lshl_b32 s10, s6, 6
	s_lshl_b32 s6, s6, 10
	s_sub_i32 s6, s12, s6
	v_or_b32_e32 v42, s10, v40
	s_ashr_i32 s7, s6, 31
	v_ashrrev_i32_e32 v43, 31, v42
	v_or_b32_e32 v4, 8, v42
	v_lshl_add_u64 v[18:19], s[6:7], 2, v[14:15]
	v_lshlrev_b64 v[0:1], 12, v[42:43]
	v_ashrrev_i32_e32 v5, 31, v4
	v_or_b32_e32 v8, 16, v42
	v_lshl_add_u64 v[0:1], v[18:19], 0, v[0:1]
	v_lshlrev_b64 v[4:5], 12, v[4:5]
	v_ashrrev_i32_e32 v9, 31, v8
	v_or_b32_e32 v20, 24, v42
	global_load_dwordx4 v[0:3], v[0:1], off
	v_lshl_add_u64 v[4:5], v[18:19], 0, v[4:5]
	v_lshlrev_b64 v[8:9], 12, v[8:9]
	v_ashrrev_i32_e32 v21, 31, v20
	v_or_b32_e32 v24, 32, v42
	global_load_dwordx4 v[4:7], v[4:5], off
	v_lshl_add_u64 v[8:9], v[18:19], 0, v[8:9]
	v_lshlrev_b64 v[20:21], 12, v[20:21]
	v_ashrrev_i32_e32 v25, 31, v24
	global_load_dwordx4 v[8:11], v[8:9], off
	v_lshl_add_u64 v[20:21], v[18:19], 0, v[20:21]
	v_lshlrev_b64 v[24:25], 12, v[24:25]
	v_or_b32_e32 v28, 40, v42
	global_load_dwordx4 v[20:23], v[20:21], off
	v_lshl_add_u64 v[24:25], v[18:19], 0, v[24:25]
	v_ashrrev_i32_e32 v29, 31, v28
	global_load_dwordx4 v[24:27], v[24:25], off
	v_lshlrev_b64 v[28:29], 12, v[28:29]
	v_or_b32_e32 v32, 48, v42
	v_lshl_add_u64 v[28:29], v[18:19], 0, v[28:29]
	v_ashrrev_i32_e32 v33, 31, v32
	global_load_dwordx4 v[28:31], v[28:29], off
	v_lshlrev_b64 v[32:33], 12, v[32:33]
	v_or_b32_e32 v42, 56, v42
	v_lshl_add_u64 v[32:33], v[18:19], 0, v[32:33]
	v_ashrrev_i32_e32 v43, 31, v42
	global_load_dwordx4 v[32:35], v[32:33], off
	v_lshlrev_b64 v[42:43], 12, v[42:43]
	v_lshl_add_u64 v[18:19], v[18:19], 0, v[42:43]
	global_load_dwordx4 v[42:45], v[18:19], off
	v_add_u32_e32 v18, v53, v46
	s_ashr_i32 s11, s10, 31
	s_add_i32 s14, s14, s16
	s_add_i32 s12, s12, s13
	s_cmpk_lt_i32 s14, 0x200
	s_waitcnt vmcnt(0) lgkmcnt(0)
	ds_write2_b32 v18, v0, v1 offset1:1
	ds_write2_b32 v18, v2, v3 offset0:2 offset1:3
	v_add_u32_e32 v0, v53, v48
	ds_write2_b32 v0, v4, v5 offset1:1
	ds_write2_b32 v0, v6, v7 offset0:2 offset1:3
	v_add_u32_e32 v0, v53, v50
	ds_write2_b32 v0, v8, v9 offset1:1
	ds_write2_b32 v0, v10, v11 offset0:2 offset1:3
	v_add_u32_e32 v0, v53, v52
	ds_write2_b32 v0, v20, v21 offset1:1
	ds_write2_b32 v0, v22, v23 offset0:2 offset1:3
	v_add_u32_e32 v0, 0x1080, v18
	v_lshl_add_u64 v[4:5], s[10:11], 1, v[16:17]
	ds_write2_b32 v0, v24, v25 offset1:1
	v_add_u32_e32 v0, 0x1088, v18
	ds_write2_b32 v0, v26, v27 offset1:1
	v_add_u32_e32 v0, 0x14a0, v18
	ds_write2_b32 v0, v28, v29 offset1:1
	v_add_u32_e32 v0, 0x14a8, v18
	ds_write2_b32 v0, v30, v31 offset1:1
	v_add_u32_e32 v0, 0x18c0, v18
	ds_write2_b32 v0, v32, v33 offset1:1
	v_add_u32_e32 v0, 0x18c8, v18
	ds_write2_b32 v0, v34, v35 offset1:1
	v_add_u32_e32 v0, 0x1ce0, v18
	ds_write2_b32 v0, v42, v43 offset1:1
	v_add_u32_e32 v0, 0x1ce8, v18
	ds_write2_b32 v0, v44, v45 offset1:1
	ds_read2_b32 v[0:1], v54 offset1:33
	ds_read2_b32 v[2:3], v54 offset0:66 offset1:99
	ds_read2_b32 v[6:7], v54 offset0:198 offset1:231
	s_waitcnt lgkmcnt(2)
	v_cvt_pk_bf16_f32 v0, v0, v1
	s_waitcnt lgkmcnt(1)
	v_cvt_pk_bf16_f32 v1, v2, v3
	ds_read2_b32 v[2:3], v54 offset0:132 offset1:165
	s_waitcnt lgkmcnt(0)
	v_cvt_pk_bf16_f32 v2, v2, v3
	v_cvt_pk_bf16_f32 v3, v6, v7
	v_add_u32_e32 v6, s6, v40
	v_ashrrev_i32_e32 v7, 31, v6
	v_lshlrev_b64 v[6:7], 11, v[6:7]
	v_lshl_add_u64 v[6:7], v[4:5], 0, v[6:7]
	global_store_dwordx4 v[6:7], v[0:3], off
	ds_read2_b32 v[0:1], v55 offset1:33
	ds_read2_b32 v[2:3], v55 offset0:66 offset1:99
	ds_read2_b32 v[6:7], v55 offset0:198 offset1:231
	s_waitcnt lgkmcnt(0)
	v_cvt_pk_bf16_f32 v0, v0, v1
	v_cvt_pk_bf16_f32 v1, v2, v3
	ds_read2_b32 v[2:3], v55 offset0:132 offset1:165
	s_waitcnt lgkmcnt(0)
	v_cvt_pk_bf16_f32 v2, v2, v3
	v_cvt_pk_bf16_f32 v3, v6, v7
	v_add_u32_e32 v6, s6, v47
	v_ashrrev_i32_e32 v7, 31, v6
	v_lshlrev_b64 v[6:7], 11, v[6:7]
	v_lshl_add_u64 v[6:7], v[4:5], 0, v[6:7]
	global_store_dwordx4 v[6:7], v[0:3], off
	ds_read2_b32 v[0:1], v56 offset1:33
	ds_read2_b32 v[2:3], v56 offset0:66 offset1:99
	ds_read2_b32 v[6:7], v56 offset0:198 offset1:231
	s_waitcnt lgkmcnt(0)
	v_cvt_pk_bf16_f32 v0, v0, v1
	v_cvt_pk_bf16_f32 v1, v2, v3
	ds_read2_b32 v[2:3], v56 offset0:132 offset1:165
	s_waitcnt lgkmcnt(0)
	v_cvt_pk_bf16_f32 v2, v2, v3
	v_cvt_pk_bf16_f32 v3, v6, v7
	v_add_u32_e32 v6, s6, v49
	v_ashrrev_i32_e32 v7, 31, v6
	v_lshlrev_b64 v[6:7], 11, v[6:7]
	v_lshl_add_u64 v[6:7], v[4:5], 0, v[6:7]
	global_store_dwordx4 v[6:7], v[0:3], off
	ds_read2_b32 v[0:1], v57 offset1:33
	ds_read2_b32 v[2:3], v57 offset0:66 offset1:99
	ds_read2_b32 v[6:7], v57 offset0:198 offset1:231
	s_waitcnt lgkmcnt(0)
	v_cvt_pk_bf16_f32 v0, v0, v1
	v_cvt_pk_bf16_f32 v1, v2, v3
	ds_read2_b32 v[2:3], v57 offset0:132 offset1:165
	s_waitcnt lgkmcnt(0)
	v_cvt_pk_bf16_f32 v2, v2, v3
	v_cvt_pk_bf16_f32 v3, v6, v7
	v_add_u32_e32 v6, s6, v51
	v_ashrrev_i32_e32 v7, 31, v6
	v_lshlrev_b64 v[6:7], 11, v[6:7]
	v_lshl_add_u64 v[4:5], v[4:5], 0, v[6:7]
	global_store_dwordx4 v[4:5], v[0:3], off
	s_cbranch_scc1 .LBB0_1598

.LBB0_1601:
	s_ashr_i32 s4, s12, 31
	s_lshr_b32 s4, s4, 27
	s_add_i32 s4, s12, s4
	s_ashr_i32 s4, s4, 5
	s_lshl_b32 s6, s4, 6
	s_lshl_b32 s4, s4, 10
	s_sub_i32 s4, s10, s4
	v_or_b32_e32 v42, s6, v40
	s_ashr_i32 s5, s4, 31
	v_ashrrev_i32_e32 v43, 31, v42
	v_or_b32_e32 v4, 8, v42
	v_lshl_add_u64 v[18:19], s[4:5], 2, v[14:15]
	v_lshlrev_b64 v[0:1], 12, v[42:43]
	v_ashrrev_i32_e32 v5, 31, v4
	v_or_b32_e32 v8, 16, v42
	v_lshl_add_u64 v[0:1], v[18:19], 0, v[0:1]
	v_lshlrev_b64 v[4:5], 12, v[4:5]
	v_ashrrev_i32_e32 v9, 31, v8
	v_or_b32_e32 v20, 24, v42
	global_load_dwordx4 v[0:3], v[0:1], off
	v_lshl_add_u64 v[4:5], v[18:19], 0, v[4:5]
	v_lshlrev_b64 v[8:9], 12, v[8:9]
	v_ashrrev_i32_e32 v21, 31, v20
	v_or_b32_e32 v24, 32, v42
	global_load_dwordx4 v[4:7], v[4:5], off
	v_lshl_add_u64 v[8:9], v[18:19], 0, v[8:9]
	v_lshlrev_b64 v[20:21], 12, v[20:21]
	v_ashrrev_i32_e32 v25, 31, v24
	global_load_dwordx4 v[8:11], v[8:9], off
	v_lshl_add_u64 v[20:21], v[18:19], 0, v[20:21]
	v_lshlrev_b64 v[24:25], 12, v[24:25]
	v_or_b32_e32 v28, 40, v42
	global_load_dwordx4 v[20:23], v[20:21], off
	v_lshl_add_u64 v[24:25], v[18:19], 0, v[24:25]
	v_ashrrev_i32_e32 v29, 31, v28
	global_load_dwordx4 v[24:27], v[24:25], off
	v_lshlrev_b64 v[28:29], 12, v[28:29]
	v_or_b32_e32 v32, 48, v42
	v_lshl_add_u64 v[28:29], v[18:19], 0, v[28:29]
	v_ashrrev_i32_e32 v33, 31, v32
	global_load_dwordx4 v[28:31], v[28:29], off
	v_lshlrev_b64 v[32:33], 12, v[32:33]
	v_or_b32_e32 v42, 56, v42
	v_lshl_add_u64 v[32:33], v[18:19], 0, v[32:33]
	v_ashrrev_i32_e32 v43, 31, v42
	global_load_dwordx4 v[32:35], v[32:33], off
	v_lshlrev_b64 v[42:43], 12, v[42:43]
	v_lshl_add_u64 v[18:19], v[18:19], 0, v[42:43]
	global_load_dwordx4 v[42:45], v[18:19], off
	v_add_u32_e32 v18, v53, v46
	s_ashr_i32 s7, s6, 31
	s_add_i32 s12, s12, s16
	s_add_i32 s10, s10, s11
	s_cmpk_lt_i32 s12, 0x200
	s_waitcnt vmcnt(0) lgkmcnt(0)
	ds_write2_b32 v18, v0, v1 offset1:1
	ds_write2_b32 v18, v2, v3 offset0:2 offset1:3
	v_add_u32_e32 v0, v53, v48
	ds_write2_b32 v0, v4, v5 offset1:1
	ds_write2_b32 v0, v6, v7 offset0:2 offset1:3
	v_add_u32_e32 v0, v53, v50
	ds_write2_b32 v0, v8, v9 offset1:1
	ds_write2_b32 v0, v10, v11 offset0:2 offset1:3
	v_add_u32_e32 v0, v53, v52
	ds_write2_b32 v0, v20, v21 offset1:1
	ds_write2_b32 v0, v22, v23 offset0:2 offset1:3
	v_add_u32_e32 v0, 0x1080, v18
	v_lshl_add_u64 v[4:5], s[6:7], 1, v[16:17]
	ds_write2_b32 v0, v24, v25 offset1:1
	v_add_u32_e32 v0, 0x1088, v18
	ds_write2_b32 v0, v26, v27 offset1:1
	v_add_u32_e32 v0, 0x14a0, v18
	ds_write2_b32 v0, v28, v29 offset1:1
	v_add_u32_e32 v0, 0x14a8, v18
	ds_write2_b32 v0, v30, v31 offset1:1
	v_add_u32_e32 v0, 0x18c0, v18
	ds_write2_b32 v0, v32, v33 offset1:1
	v_add_u32_e32 v0, 0x18c8, v18
	ds_write2_b32 v0, v34, v35 offset1:1
	v_add_u32_e32 v0, 0x1ce0, v18
	ds_write2_b32 v0, v42, v43 offset1:1
	v_add_u32_e32 v0, 0x1ce8, v18
	ds_write2_b32 v0, v44, v45 offset1:1
	ds_read2_b32 v[0:1], v54 offset1:33
	ds_read2_b32 v[2:3], v54 offset0:66 offset1:99
	ds_read2_b32 v[6:7], v54 offset0:198 offset1:231
	s_waitcnt lgkmcnt(2)
	v_cvt_pk_bf16_f32 v0, v0, v1
	s_waitcnt lgkmcnt(1)
	v_cvt_pk_bf16_f32 v1, v2, v3
	ds_read2_b32 v[2:3], v54 offset0:132 offset1:165
	s_waitcnt lgkmcnt(0)
	v_cvt_pk_bf16_f32 v2, v2, v3
	v_cvt_pk_bf16_f32 v3, v6, v7
	v_add_u32_e32 v6, s4, v40
	v_ashrrev_i32_e32 v7, 31, v6
	v_lshlrev_b64 v[6:7], 11, v[6:7]
	v_lshl_add_u64 v[6:7], v[4:5], 0, v[6:7]
	global_store_dwordx4 v[6:7], v[0:3], off
	ds_read2_b32 v[0:1], v55 offset1:33
	ds_read2_b32 v[2:3], v55 offset0:66 offset1:99
	ds_read2_b32 v[6:7], v55 offset0:198 offset1:231
	s_waitcnt lgkmcnt(0)
	v_cvt_pk_bf16_f32 v0, v0, v1
	v_cvt_pk_bf16_f32 v1, v2, v3
	ds_read2_b32 v[2:3], v55 offset0:132 offset1:165
	s_waitcnt lgkmcnt(0)
	v_cvt_pk_bf16_f32 v2, v2, v3
	v_cvt_pk_bf16_f32 v3, v6, v7
	v_add_u32_e32 v6, s4, v47
	v_ashrrev_i32_e32 v7, 31, v6
	v_lshlrev_b64 v[6:7], 11, v[6:7]
	v_lshl_add_u64 v[6:7], v[4:5], 0, v[6:7]
	global_store_dwordx4 v[6:7], v[0:3], off
	ds_read2_b32 v[0:1], v56 offset1:33
	ds_read2_b32 v[2:3], v56 offset0:66 offset1:99
	ds_read2_b32 v[6:7], v56 offset0:198 offset1:231
	s_waitcnt lgkmcnt(0)
	v_cvt_pk_bf16_f32 v0, v0, v1
	v_cvt_pk_bf16_f32 v1, v2, v3
	ds_read2_b32 v[2:3], v56 offset0:132 offset1:165
	s_waitcnt lgkmcnt(0)
	v_cvt_pk_bf16_f32 v2, v2, v3
	v_cvt_pk_bf16_f32 v3, v6, v7
	v_add_u32_e32 v6, s4, v49
	v_ashrrev_i32_e32 v7, 31, v6
	v_lshlrev_b64 v[6:7], 11, v[6:7]
	v_lshl_add_u64 v[6:7], v[4:5], 0, v[6:7]
	global_store_dwordx4 v[6:7], v[0:3], off
	ds_read2_b32 v[0:1], v57 offset1:33
	ds_read2_b32 v[2:3], v57 offset0:66 offset1:99
	ds_read2_b32 v[6:7], v57 offset0:198 offset1:231
	s_waitcnt lgkmcnt(0)
	v_cvt_pk_bf16_f32 v0, v0, v1
	v_cvt_pk_bf16_f32 v1, v2, v3
	ds_read2_b32 v[2:3], v57 offset0:132 offset1:165
	s_waitcnt lgkmcnt(0)
	v_cvt_pk_bf16_f32 v2, v2, v3
	v_cvt_pk_bf16_f32 v3, v6, v7
	v_add_u32_e32 v6, s4, v51
	v_ashrrev_i32_e32 v7, 31, v6
	v_lshlrev_b64 v[6:7], 11, v[6:7]
	v_lshl_add_u64 v[4:5], v[4:5], 0, v[6:7]
	global_store_dwordx4 v[4:5], v[0:3], off
	s_cbranch_scc1 .LBB0_1601

.LBB0_1604:
	s_ashr_i32 s2, s10, 31
	s_lshr_b32 s2, s2, 27
	s_add_i32 s2, s10, s2
	s_ashr_i32 s2, s2, 5
	s_lshl_b32 s4, s2, 6
	s_lshl_b32 s2, s2, 10
	s_sub_i32 s2, s6, s2
	v_or_b32_e32 v42, s4, v40
	s_ashr_i32 s3, s2, 31
	v_ashrrev_i32_e32 v43, 31, v42
	v_or_b32_e32 v4, 8, v42
	v_lshl_add_u64 v[18:19], s[2:3], 2, v[14:15]
	v_lshlrev_b64 v[0:1], 12, v[42:43]
	v_ashrrev_i32_e32 v5, 31, v4
	v_or_b32_e32 v8, 16, v42
	v_lshl_add_u64 v[0:1], v[18:19], 0, v[0:1]
	v_lshlrev_b64 v[4:5], 12, v[4:5]
	v_ashrrev_i32_e32 v9, 31, v8
	v_or_b32_e32 v20, 24, v42
	global_load_dwordx4 v[0:3], v[0:1], off
	v_lshl_add_u64 v[4:5], v[18:19], 0, v[4:5]
	v_lshlrev_b64 v[8:9], 12, v[8:9]
	v_ashrrev_i32_e32 v21, 31, v20
	v_or_b32_e32 v24, 32, v42
	global_load_dwordx4 v[4:7], v[4:5], off
	v_lshl_add_u64 v[8:9], v[18:19], 0, v[8:9]
	v_lshlrev_b64 v[20:21], 12, v[20:21]
	v_ashrrev_i32_e32 v25, 31, v24
	global_load_dwordx4 v[8:11], v[8:9], off
	v_lshl_add_u64 v[20:21], v[18:19], 0, v[20:21]
	v_lshlrev_b64 v[24:25], 12, v[24:25]
	v_or_b32_e32 v28, 40, v42
	global_load_dwordx4 v[20:23], v[20:21], off
	v_lshl_add_u64 v[24:25], v[18:19], 0, v[24:25]
	v_ashrrev_i32_e32 v29, 31, v28
	global_load_dwordx4 v[24:27], v[24:25], off
	v_lshlrev_b64 v[28:29], 12, v[28:29]
	v_or_b32_e32 v32, 48, v42
	v_lshl_add_u64 v[28:29], v[18:19], 0, v[28:29]
	v_ashrrev_i32_e32 v33, 31, v32
	global_load_dwordx4 v[28:31], v[28:29], off
	v_lshlrev_b64 v[32:33], 12, v[32:33]
	v_or_b32_e32 v42, 56, v42
	v_lshl_add_u64 v[32:33], v[18:19], 0, v[32:33]
	v_ashrrev_i32_e32 v43, 31, v42
	global_load_dwordx4 v[32:35], v[32:33], off
	v_lshlrev_b64 v[42:43], 12, v[42:43]
	v_lshl_add_u64 v[18:19], v[18:19], 0, v[42:43]
	global_load_dwordx4 v[42:45], v[18:19], off
	v_add_u32_e32 v18, v53, v46
	s_ashr_i32 s5, s4, 31
	s_add_i32 s10, s10, s16
	s_add_i32 s6, s6, s7
	s_cmpk_lt_i32 s10, 0x80
	s_waitcnt vmcnt(0) lgkmcnt(0)
	ds_write2_b32 v18, v0, v1 offset1:1
	ds_write2_b32 v18, v2, v3 offset0:2 offset1:3
	v_add_u32_e32 v0, v53, v48
	ds_write2_b32 v0, v4, v5 offset1:1
	ds_write2_b32 v0, v6, v7 offset0:2 offset1:3
	v_add_u32_e32 v0, v53, v50
	ds_write2_b32 v0, v8, v9 offset1:1
	ds_write2_b32 v0, v10, v11 offset0:2 offset1:3
	v_add_u32_e32 v0, v53, v52
	ds_write2_b32 v0, v20, v21 offset1:1
	ds_write2_b32 v0, v22, v23 offset0:2 offset1:3
	v_add_u32_e32 v0, 0x1080, v18
	v_lshl_add_u64 v[4:5], s[4:5], 1, v[16:17]
	ds_write2_b32 v0, v24, v25 offset1:1
	v_add_u32_e32 v0, 0x1088, v18
	ds_write2_b32 v0, v26, v27 offset1:1
	v_add_u32_e32 v0, 0x14a0, v18
	ds_write2_b32 v0, v28, v29 offset1:1
	v_add_u32_e32 v0, 0x14a8, v18
	ds_write2_b32 v0, v30, v31 offset1:1
	v_add_u32_e32 v0, 0x18c0, v18
	ds_write2_b32 v0, v32, v33 offset1:1
	v_add_u32_e32 v0, 0x18c8, v18
	ds_write2_b32 v0, v34, v35 offset1:1
	v_add_u32_e32 v0, 0x1ce0, v18
	ds_write2_b32 v0, v42, v43 offset1:1
	v_add_u32_e32 v0, 0x1ce8, v18
	ds_write2_b32 v0, v44, v45 offset1:1
	ds_read2_b32 v[0:1], v54 offset1:33
	ds_read2_b32 v[2:3], v54 offset0:66 offset1:99
	ds_read2_b32 v[6:7], v54 offset0:198 offset1:231
	s_waitcnt lgkmcnt(2)
	v_cvt_pk_bf16_f32 v0, v0, v1
	s_waitcnt lgkmcnt(1)
	v_cvt_pk_bf16_f32 v1, v2, v3
	ds_read2_b32 v[2:3], v54 offset0:132 offset1:165
	s_waitcnt lgkmcnt(0)
	v_cvt_pk_bf16_f32 v2, v2, v3
	v_cvt_pk_bf16_f32 v3, v6, v7
	v_add_u32_e32 v6, s2, v40
	v_ashrrev_i32_e32 v7, 31, v6
	v_lshlrev_b64 v[6:7], 9, v[6:7]
	v_lshl_add_u64 v[6:7], v[4:5], 0, v[6:7]
	global_store_dwordx4 v[6:7], v[0:3], off
	ds_read2_b32 v[0:1], v55 offset1:33
	ds_read2_b32 v[2:3], v55 offset0:66 offset1:99
	ds_read2_b32 v[6:7], v55 offset0:198 offset1:231
	s_waitcnt lgkmcnt(0)
	v_cvt_pk_bf16_f32 v0, v0, v1
	v_cvt_pk_bf16_f32 v1, v2, v3
	ds_read2_b32 v[2:3], v55 offset0:132 offset1:165
	s_waitcnt lgkmcnt(0)
	v_cvt_pk_bf16_f32 v2, v2, v3
	v_cvt_pk_bf16_f32 v3, v6, v7
	v_add_u32_e32 v6, s2, v47
	v_ashrrev_i32_e32 v7, 31, v6
	v_lshlrev_b64 v[6:7], 9, v[6:7]
	v_lshl_add_u64 v[6:7], v[4:5], 0, v[6:7]
	global_store_dwordx4 v[6:7], v[0:3], off
	ds_read2_b32 v[0:1], v56 offset1:33
	ds_read2_b32 v[2:3], v56 offset0:66 offset1:99
	ds_read2_b32 v[6:7], v56 offset0:198 offset1:231
	s_waitcnt lgkmcnt(0)
	v_cvt_pk_bf16_f32 v0, v0, v1
	v_cvt_pk_bf16_f32 v1, v2, v3
	ds_read2_b32 v[2:3], v56 offset0:132 offset1:165
	s_waitcnt lgkmcnt(0)
	v_cvt_pk_bf16_f32 v2, v2, v3
	v_cvt_pk_bf16_f32 v3, v6, v7
	v_add_u32_e32 v6, s2, v49
	v_ashrrev_i32_e32 v7, 31, v6
	v_lshlrev_b64 v[6:7], 9, v[6:7]
	v_lshl_add_u64 v[6:7], v[4:5], 0, v[6:7]
	global_store_dwordx4 v[6:7], v[0:3], off
	ds_read2_b32 v[0:1], v57 offset1:33
	ds_read2_b32 v[2:3], v57 offset0:66 offset1:99
	ds_read2_b32 v[6:7], v57 offset0:198 offset1:231
	s_waitcnt lgkmcnt(0)
	v_cvt_pk_bf16_f32 v0, v0, v1
	v_cvt_pk_bf16_f32 v1, v2, v3
	ds_read2_b32 v[2:3], v57 offset0:132 offset1:165
	s_waitcnt lgkmcnt(0)
	v_cvt_pk_bf16_f32 v2, v2, v3
	v_cvt_pk_bf16_f32 v3, v6, v7
	v_add_u32_e32 v6, s2, v51
	v_ashrrev_i32_e32 v7, 31, v6
	v_lshlrev_b64 v[6:7], 9, v[6:7]
	v_lshl_add_u64 v[4:5], v[4:5], 0, v[6:7]
	global_store_dwordx4 v[4:5], v[0:3], off
	s_cbranch_scc1 .LBB0_1604

.LBB0_1607:
	ds_write2_b32 v63, v8, v9 offset1:1
	ds_write2_b32 v63, v10, v11 offset0:2 offset1:3
	ds_read2_b32 v[0:1], v54 offset1:33
	ds_read2_b32 v[2:3], v54 offset0:66 offset1:99
	ds_read2_b32 v[6:7], v54 offset0:198 offset1:231
	v_lshl_add_u64 v[4:5], s[12:13], 1, v[44:45]
	s_add_i32 s19, s19, s16
	s_waitcnt lgkmcnt(2)
	v_cvt_pk_bf16_f32 v0, v0, v1
	s_waitcnt lgkmcnt(1)
	v_cvt_pk_bf16_f32 v1, v2, v3
	ds_read2_b32 v[2:3], v54 offset0:132 offset1:165
	s_add_i32 s17, s17, s18
	s_cmp_lt_i32 s19, 48
	s_waitcnt lgkmcnt(0)
	v_cvt_pk_bf16_f32 v2, v2, v3
	v_cvt_pk_bf16_f32 v3, v6, v7
	v_add_u32_e32 v6, s10, v40
	v_ashrrev_i32_e32 v7, 31, v6
	v_lshlrev_b64 v[6:7], 9, v[6:7]
	v_lshl_add_u64 v[6:7], v[4:5], 0, v[6:7]
	global_store_dwordx4 v[6:7], v[0:3], off
	ds_read2_b32 v[0:1], v55 offset1:33
	ds_read2_b32 v[2:3], v55 offset0:66 offset1:99
	ds_read2_b32 v[6:7], v55 offset0:198 offset1:231
	s_waitcnt lgkmcnt(0)
	v_cvt_pk_bf16_f32 v0, v0, v1
	v_cvt_pk_bf16_f32 v1, v2, v3
	ds_read2_b32 v[2:3], v55 offset0:132 offset1:165
	s_waitcnt lgkmcnt(0)
	v_cvt_pk_bf16_f32 v2, v2, v3
	v_cvt_pk_bf16_f32 v3, v6, v7
	v_add_u32_e32 v6, s10, v47
	v_ashrrev_i32_e32 v7, 31, v6
	v_lshlrev_b64 v[6:7], 9, v[6:7]
	v_lshl_add_u64 v[6:7], v[4:5], 0, v[6:7]
	global_store_dwordx4 v[6:7], v[0:3], off
	ds_read2_b32 v[0:1], v56 offset1:33
	ds_read2_b32 v[2:3], v56 offset0:66 offset1:99
	ds_read2_b32 v[6:7], v56 offset0:198 offset1:231
	s_waitcnt lgkmcnt(0)
	v_cvt_pk_bf16_f32 v0, v0, v1
	v_cvt_pk_bf16_f32 v1, v2, v3
	ds_read2_b32 v[2:3], v56 offset0:132 offset1:165
	s_waitcnt lgkmcnt(0)
	v_cvt_pk_bf16_f32 v2, v2, v3
	v_cvt_pk_bf16_f32 v3, v6, v7
	v_add_u32_e32 v6, s10, v49
	v_ashrrev_i32_e32 v7, 31, v6
	v_lshlrev_b64 v[6:7], 9, v[6:7]
	v_lshl_add_u64 v[6:7], v[4:5], 0, v[6:7]
	global_store_dwordx4 v[6:7], v[0:3], off
	ds_read2_b32 v[0:1], v57 offset1:33
	ds_read2_b32 v[2:3], v57 offset0:66 offset1:99
	ds_read2_b32 v[6:7], v57 offset0:198 offset1:231
	s_waitcnt lgkmcnt(0)
	v_cvt_pk_bf16_f32 v0, v0, v1
	v_cvt_pk_bf16_f32 v1, v2, v3
	ds_read2_b32 v[2:3], v57 offset0:132 offset1:165
	s_waitcnt lgkmcnt(0)
	v_cvt_pk_bf16_f32 v2, v2, v3
	v_cvt_pk_bf16_f32 v3, v6, v7
	v_add_u32_e32 v6, s10, v51
	v_ashrrev_i32_e32 v7, 31, v6
	v_lshlrev_b64 v[6:7], 9, v[6:7]
	v_lshl_add_u64 v[4:5], v[4:5], 0, v[6:7]
	global_store_dwordx4 v[4:5], v[0:3], off
	s_cbranch_scc0 .LBB0_1624
.LBB0_1608:
	s_mul_hi_i32 s2, s19, 0x2aaaaaab
	s_lshr_b32 s3, s2, 31
	s_ashr_i32 s2, s2, 1
	s_add_i32 s2, s2, s3
	s_lshl_b32 s12, s2, 6
	s_mulk_i32 s2, 0xfe80
	s_add_i32 s10, s17, s2
	v_or_b32_e32 v32, s12, v40
	s_ashr_i32 s11, s10, 31
	v_lshl_add_u64 v[0:1], s[10:11], 2, v[42:43]
	v_or_b32_e32 v4, 8, v32
	v_mad_i64_i32 v[2:3], s[2:3], v32, s31, v[0:1]
	v_mad_i64_i32 v[4:5], s[2:3], v4, s31, v[0:1]
	global_load_dwordx4 v[24:27], v[2:3], off
	global_load_dwordx4 v[28:31], v[4:5], off
	v_or_b32_e32 v2, 16, v32
	v_or_b32_e32 v4, 24, v32
	v_mad_i64_i32 v[2:3], s[2:3], v2, s31, v[0:1]
	v_mad_i64_i32 v[4:5], s[2:3], v4, s31, v[0:1]
	global_load_dwordx4 v[16:19], v[2:3], off
	global_load_dwordx4 v[20:23], v[4:5], off
	v_or_b32_e32 v2, 32, v32
	v_or_b32_e32 v4, 40, v32
	v_mad_i64_i32 v[2:3], s[2:3], v2, s31, v[0:1]
	v_mad_i64_i32 v[4:5], s[2:3], v4, s31, v[0:1]
	global_load_dwordx4 v[8:11], v[2:3], off
	global_load_dwordx4 v[12:15], v[4:5], off
	v_or_b32_e32 v2, 48, v32
	v_or_b32_e32 v4, 56, v32
	v_mad_i64_i32 v[2:3], s[2:3], v2, s31, v[0:1]
	v_mad_i64_i32 v[0:1], s[2:3], v4, s31, v[0:1]
	global_load_dwordx4 v[4:7], v[2:3], off
	s_nop 0
	global_load_dwordx4 v[0:3], v[0:1], off
	v_cndmask_b32_e64 v33, 0, 1, s[6:7]
	v_cmp_ne_u32_e64 s[2:3], 1, v33
	s_andn2_b64 vcc, exec, s[6:7]
	s_cbranch_vccnz .LBB0_1619
	v_ashrrev_i32_e32 v33, 31, v32
	v_lshl_add_u64 v[32:33], v[32:33], 2, s[4:5]
	global_load_dword v32, v[32:33], off offset:1024
	v_add_u32_e32 v66, v53, v46
	s_waitcnt vmcnt(0) lgkmcnt(0)
	v_pk_mul_f32 v[34:35], v[26:27], v[32:33] op_sel_hi:[1,0]
	v_pk_mul_f32 v[32:33], v[24:25], v[32:33] op_sel_hi:[1,0]
	ds_write2_b32 v66, v32, v33 offset1:1
	ds_write2_b32 v66, v34, v35 offset0:2 offset1:3
	v_or_b32_e32 v32, s12, v47
	v_ashrrev_i32_e32 v33, 31, v32
	v_lshl_add_u64 v[32:33], v[32:33], 2, s[4:5]
	global_load_dword v32, v[32:33], off offset:1024
	s_waitcnt vmcnt(0) lgkmcnt(0)
	v_pk_mul_f32 v[34:35], v[30:31], v[32:33] op_sel_hi:[1,0]
	v_pk_mul_f32 v[32:33], v[28:29], v[32:33] op_sel_hi:[1,0]
	s_cbranch_execnz .LBB0_1611

.LBB0_1611:
	s_waitcnt vmcnt(0) lgkmcnt(0)
	v_add_u32_e32 v24, v53, v48
	s_and_b64 vcc, exec, s[2:3]
	ds_write2_b32 v24, v32, v33 offset1:1
	ds_write2_b32 v24, v34, v35 offset0:2 offset1:3
	s_cbranch_vccnz .LBB0_1620
	v_or_b32_e32 v24, s12, v49
	v_ashrrev_i32_e32 v25, 31, v24
	v_lshl_add_u64 v[24:25], v[24:25], 2, s[4:5]
	global_load_dword v24, v[24:25], off offset:1024
	v_add_u32_e32 v28, v53, v50
	s_waitcnt vmcnt(0) lgkmcnt(0)
	v_pk_mul_f32 v[26:27], v[18:19], v[24:25] op_sel_hi:[1,0]
	v_pk_mul_f32 v[24:25], v[16:17], v[24:25] op_sel_hi:[1,0]
	ds_write2_b32 v28, v24, v25 offset1:1
	ds_write2_b32 v28, v26, v27 offset0:2 offset1:3
	v_or_b32_e32 v24, s12, v51
	v_ashrrev_i32_e32 v25, 31, v24
	v_lshl_add_u64 v[24:25], v[24:25], 2, s[4:5]
	global_load_dword v24, v[24:25], off offset:1024
	s_waitcnt vmcnt(0) lgkmcnt(0)
	v_pk_mul_f32 v[26:27], v[22:23], v[24:25] op_sel_hi:[1,0]
	v_pk_mul_f32 v[24:25], v[20:21], v[24:25] op_sel_hi:[1,0]
	s_cbranch_execnz .LBB0_1614

.LBB0_1614:
	v_add_u32_e32 v16, v53, v52
	s_and_b64 vcc, exec, s[2:3]
	ds_write2_b32 v16, v24, v25 offset1:1
	ds_write2_b32 v16, v26, v27 offset0:2 offset1:3
	s_cbranch_vccnz .LBB0_1621
	s_ashr_i32 s13, s12, 31
	v_lshl_add_u64 v[16:17], s[12:13], 0, v[40:41]
	v_lshl_add_u64 v[16:17], v[16:17], 2, s[4:5]
	global_load_dword v18, v[16:17], off offset:1152
	s_waitcnt vmcnt(0) lgkmcnt(0)
	v_pk_mul_f32 v[20:21], v[10:11], v[18:19] op_sel_hi:[1,0]
	v_pk_mul_f32 v[18:19], v[8:9], v[18:19] op_sel_hi:[1,0]
	ds_write2_b32 v64, v18, v19 offset1:1
	ds_write2_b32 v64, v20, v21 offset0:2 offset1:3
	global_load_dword v16, v[16:17], off offset:1184
	s_waitcnt vmcnt(0) lgkmcnt(0)
	v_pk_mul_f32 v[18:19], v[14:15], v[16:17] op_sel_hi:[1,0]
	v_pk_mul_f32 v[16:17], v[12:13], v[16:17] op_sel_hi:[1,0]
	s_cbranch_execnz .LBB0_1617

.LBB0_1617:
	s_and_b64 vcc, exec, s[2:3]
	ds_write2_b32 v62, v16, v17 offset1:1
	ds_write2_b32 v62, v18, v19 offset0:2 offset1:3
	s_cbranch_vccnz .LBB0_1622
	s_ashr_i32 s13, s12, 31
	v_lshl_add_u64 v[8:9], s[12:13], 0, v[40:41]
	v_lshl_add_u64 v[8:9], v[8:9], 2, s[4:5]
	global_load_dword v10, v[8:9], off offset:1216
	s_waitcnt vmcnt(0) lgkmcnt(0)
	v_pk_mul_f32 v[12:13], v[6:7], v[10:11] op_sel_hi:[1,0]
	v_pk_mul_f32 v[10:11], v[4:5], v[10:11] op_sel_hi:[1,0]
	ds_write2_b32 v65, v10, v11 offset1:1
	ds_write2_b32 v65, v12, v13 offset0:2 offset1:3
	global_load_dword v8, v[8:9], off offset:1248
	s_waitcnt vmcnt(0) lgkmcnt(0)
	v_pk_mul_f32 v[10:11], v[2:3], v[8:9] op_sel_hi:[1,0]
	v_pk_mul_f32 v[8:9], v[0:1], v[8:9] op_sel_hi:[1,0]
	s_cbranch_execnz .LBB0_1607
	s_branch .LBB0_1623

.LBB0_1626:
	ds_write2_b32 v43, v8, v9 offset1:1
	ds_write2_b32 v43, v10, v11 offset0:2 offset1:3
	ds_read2_b32 v[0:1], v54 offset1:33
	ds_read2_b32 v[2:3], v54 offset0:66 offset1:99
	ds_read2_b32 v[6:7], v54 offset0:198 offset1:231
	s_sub_i32 s2, 0, s19
	s_add_i32 s2, s2, s17
	s_waitcnt lgkmcnt(2)
	v_cvt_pk_bf16_f32 v0, v0, v1
	s_waitcnt lgkmcnt(1)
	v_cvt_pk_bf16_f32 v1, v2, v3
	ds_read2_b32 v[2:3], v54 offset0:132 offset1:165
	v_lshl_add_u64 v[4:5], s[12:13], 1, v[36:37]
	s_add_i32 s26, s26, s16
	s_add_i32 s17, s17, s18
	s_cmp_lt_i32 s26, 32
	s_waitcnt lgkmcnt(0)
	v_cvt_pk_bf16_f32 v2, v2, v3
	v_cvt_pk_bf16_f32 v3, v6, v7
	v_add_u32_e32 v6, s2, v40
	v_ashrrev_i32_e32 v7, 31, v6
	v_lshlrev_b64 v[6:7], 9, v[6:7]
	v_lshl_add_u64 v[6:7], v[4:5], 0, v[6:7]
	global_store_dwordx4 v[6:7], v[0:3], off
	ds_read2_b32 v[0:1], v55 offset1:33
	ds_read2_b32 v[2:3], v55 offset0:66 offset1:99
	ds_read2_b32 v[6:7], v55 offset0:198 offset1:231
	s_waitcnt lgkmcnt(0)
	v_cvt_pk_bf16_f32 v0, v0, v1
	v_cvt_pk_bf16_f32 v1, v2, v3
	ds_read2_b32 v[2:3], v55 offset0:132 offset1:165
	s_waitcnt lgkmcnt(0)
	v_cvt_pk_bf16_f32 v2, v2, v3
	v_cvt_pk_bf16_f32 v3, v6, v7
	v_add_u32_e32 v6, s2, v47
	v_ashrrev_i32_e32 v7, 31, v6
	v_lshlrev_b64 v[6:7], 9, v[6:7]
	v_lshl_add_u64 v[6:7], v[4:5], 0, v[6:7]
	global_store_dwordx4 v[6:7], v[0:3], off
	ds_read2_b32 v[0:1], v56 offset1:33
	ds_read2_b32 v[2:3], v56 offset0:66 offset1:99
	ds_read2_b32 v[6:7], v56 offset0:198 offset1:231
	s_waitcnt lgkmcnt(0)
	v_cvt_pk_bf16_f32 v0, v0, v1
	v_cvt_pk_bf16_f32 v1, v2, v3
	ds_read2_b32 v[2:3], v56 offset0:132 offset1:165
	s_waitcnt lgkmcnt(0)
	v_cvt_pk_bf16_f32 v2, v2, v3
	v_cvt_pk_bf16_f32 v3, v6, v7
	v_add_u32_e32 v6, s2, v49
	v_ashrrev_i32_e32 v7, 31, v6
	v_lshlrev_b64 v[6:7], 9, v[6:7]
	v_lshl_add_u64 v[6:7], v[4:5], 0, v[6:7]
	global_store_dwordx4 v[6:7], v[0:3], off
	ds_read2_b32 v[0:1], v57 offset1:33
	ds_read2_b32 v[2:3], v57 offset0:66 offset1:99
	ds_read2_b32 v[6:7], v57 offset0:198 offset1:231
	s_waitcnt lgkmcnt(0)
	v_cvt_pk_bf16_f32 v0, v0, v1
	v_cvt_pk_bf16_f32 v1, v2, v3
	ds_read2_b32 v[2:3], v57 offset0:132 offset1:165
	s_waitcnt lgkmcnt(0)
	v_cvt_pk_bf16_f32 v2, v2, v3
	v_cvt_pk_bf16_f32 v3, v6, v7
	v_add_u32_e32 v6, s2, v51
	v_ashrrev_i32_e32 v7, 31, v6
	v_lshlrev_b64 v[6:7], 9, v[6:7]
	v_lshl_add_u64 v[4:5], v[4:5], 0, v[6:7]
	global_store_dwordx4 v[4:5], v[0:3], off
	s_cbranch_scc0 .LBB0_1643
.LBB0_1627:
	s_ashr_i32 s2, s26, 31
	s_lshr_b32 s2, s2, 28
	s_add_i32 s2, s26, s2
	s_ashr_i32 s2, s2, 4
	s_lshl_b32 s12, s2, 6
	s_lshl_b32 s19, s2, 9
	v_or_b32_e32 v32, s12, v40
	s_sub_i32 s2, s17, s19
	v_or_b32_e32 v4, 8, v32
	s_ashr_i32 s3, s2, 31
	v_ashrrev_i32_e32 v33, 31, v32
	v_ashrrev_i32_e32 v5, 31, v4
	v_lshl_add_u64 v[0:1], s[2:3], 2, v[38:39]
	v_lshlrev_b64 v[2:3], 11, v[32:33]
	v_lshlrev_b64 v[4:5], 11, v[4:5]
	v_lshl_add_u64 v[2:3], v[0:1], 0, v[2:3]
	v_lshl_add_u64 v[4:5], v[0:1], 0, v[4:5]
	global_load_dwordx4 v[24:27], v[2:3], off
	global_load_dwordx4 v[28:31], v[4:5], off
	v_or_b32_e32 v2, 16, v32
	v_or_b32_e32 v4, 24, v32
	v_ashrrev_i32_e32 v3, 31, v2
	v_ashrrev_i32_e32 v5, 31, v4
	v_lshlrev_b64 v[2:3], 11, v[2:3]
	v_lshlrev_b64 v[4:5], 11, v[4:5]
	v_lshl_add_u64 v[2:3], v[0:1], 0, v[2:3]
	v_lshl_add_u64 v[4:5], v[0:1], 0, v[4:5]
	global_load_dwordx4 v[16:19], v[2:3], off
	global_load_dwordx4 v[20:23], v[4:5], off
	v_or_b32_e32 v2, 32, v32
	v_or_b32_e32 v4, 40, v32
	v_ashrrev_i32_e32 v3, 31, v2
	v_ashrrev_i32_e32 v5, 31, v4
	v_lshlrev_b64 v[2:3], 11, v[2:3]
	v_lshlrev_b64 v[4:5], 11, v[4:5]
	v_lshl_add_u64 v[2:3], v[0:1], 0, v[2:3]
	v_lshl_add_u64 v[4:5], v[0:1], 0, v[4:5]
	global_load_dwordx4 v[8:11], v[2:3], off
	global_load_dwordx4 v[12:15], v[4:5], off
	v_or_b32_e32 v2, 48, v32
	v_or_b32_e32 v4, 56, v32
	v_ashrrev_i32_e32 v3, 31, v2
	v_ashrrev_i32_e32 v5, 31, v4
	v_lshlrev_b64 v[2:3], 11, v[2:3]
	v_lshlrev_b64 v[4:5], 11, v[4:5]
	v_lshl_add_u64 v[2:3], v[0:1], 0, v[2:3]
	v_lshl_add_u64 v[0:1], v[0:1], 0, v[4:5]
	global_load_dwordx4 v[4:7], v[2:3], off
	s_nop 0
	global_load_dwordx4 v[0:3], v[0:1], off
	v_cndmask_b32_e64 v34, 0, 1, s[10:11]
	v_cmp_ne_u32_e64 s[2:3], 1, v34
	s_andn2_b64 vcc, exec, s[10:11]
	v_add_u32_e32 v58, v53, v46
	s_cbranch_vccnz .LBB0_1638
	v_lshl_add_u64 v[32:33], v[32:33], 2, s[6:7]
	global_load_dword v32, v[32:33], off offset:512
	s_waitcnt vmcnt(0) lgkmcnt(0)
	v_pk_mul_f32 v[34:35], v[26:27], v[32:33] op_sel_hi:[1,0]
	v_pk_mul_f32 v[32:33], v[24:25], v[32:33] op_sel_hi:[1,0]
	ds_write2_b32 v58, v32, v33 offset1:1
	ds_write2_b32 v58, v34, v35 offset0:2 offset1:3
	v_or_b32_e32 v32, s12, v47
	v_ashrrev_i32_e32 v33, 31, v32
	v_lshl_add_u64 v[32:33], v[32:33], 2, s[6:7]
	global_load_dword v32, v[32:33], off offset:512
	s_waitcnt vmcnt(0) lgkmcnt(0)
	v_pk_mul_f32 v[34:35], v[30:31], v[32:33] op_sel_hi:[1,0]
	v_pk_mul_f32 v[32:33], v[28:29], v[32:33] op_sel_hi:[1,0]
	s_cbranch_execnz .LBB0_1630

.LBB0_1630:
	s_waitcnt vmcnt(0) lgkmcnt(0)
	v_add_u32_e32 v24, v53, v48
	s_and_b64 vcc, exec, s[2:3]
	v_add_u32_e32 v28, v53, v50
	ds_write2_b32 v24, v32, v33 offset1:1
	ds_write2_b32 v24, v34, v35 offset0:2 offset1:3
	s_cbranch_vccnz .LBB0_1639
	v_or_b32_e32 v24, s12, v49
	v_ashrrev_i32_e32 v25, 31, v24
	v_lshl_add_u64 v[24:25], v[24:25], 2, s[6:7]
	global_load_dword v24, v[24:25], off offset:512
	s_waitcnt vmcnt(0) lgkmcnt(0)
	v_pk_mul_f32 v[26:27], v[18:19], v[24:25] op_sel_hi:[1,0]
	v_pk_mul_f32 v[24:25], v[16:17], v[24:25] op_sel_hi:[1,0]
	ds_write2_b32 v28, v24, v25 offset1:1
	ds_write2_b32 v28, v26, v27 offset0:2 offset1:3
	v_or_b32_e32 v24, s12, v51
	v_ashrrev_i32_e32 v25, 31, v24
	v_lshl_add_u64 v[24:25], v[24:25], 2, s[6:7]
	global_load_dword v24, v[24:25], off offset:512
	s_waitcnt vmcnt(0) lgkmcnt(0)
	v_pk_mul_f32 v[26:27], v[22:23], v[24:25] op_sel_hi:[1,0]
	v_pk_mul_f32 v[24:25], v[20:21], v[24:25] op_sel_hi:[1,0]
	s_cbranch_execnz .LBB0_1633

.LBB0_1633:
	v_add_u32_e32 v16, v53, v52
	s_and_b64 vcc, exec, s[2:3]
	ds_write2_b32 v16, v24, v25 offset1:1
	ds_write2_b32 v16, v26, v27 offset0:2 offset1:3
	s_cbranch_vccnz .LBB0_1640
	s_ashr_i32 s13, s12, 31
	v_lshl_add_u64 v[16:17], s[12:13], 0, v[40:41]
	v_lshl_add_u64 v[16:17], v[16:17], 2, s[6:7]
	global_load_dword v18, v[16:17], off offset:640
	s_waitcnt vmcnt(0) lgkmcnt(0)
	v_pk_mul_f32 v[20:21], v[10:11], v[18:19] op_sel_hi:[1,0]
	v_pk_mul_f32 v[18:19], v[8:9], v[18:19] op_sel_hi:[1,0]
	ds_write2_b32 v44, v18, v19 offset1:1
	ds_write2_b32 v44, v20, v21 offset0:2 offset1:3
	global_load_dword v16, v[16:17], off offset:672
	s_waitcnt vmcnt(0) lgkmcnt(0)
	v_pk_mul_f32 v[18:19], v[14:15], v[16:17] op_sel_hi:[1,0]
	v_pk_mul_f32 v[16:17], v[12:13], v[16:17] op_sel_hi:[1,0]
	s_cbranch_execnz .LBB0_1636

.LBB0_1636:
	s_and_b64 vcc, exec, s[2:3]
	ds_write2_b32 v42, v16, v17 offset1:1
	ds_write2_b32 v42, v18, v19 offset0:2 offset1:3
	s_cbranch_vccnz .LBB0_1641
	s_ashr_i32 s13, s12, 31
	v_lshl_add_u64 v[8:9], s[12:13], 0, v[40:41]
	v_lshl_add_u64 v[8:9], v[8:9], 2, s[6:7]
	global_load_dword v10, v[8:9], off offset:704
	s_waitcnt vmcnt(0) lgkmcnt(0)
	v_pk_mul_f32 v[12:13], v[6:7], v[10:11] op_sel_hi:[1,0]
	v_pk_mul_f32 v[10:11], v[4:5], v[10:11] op_sel_hi:[1,0]
	ds_write2_b32 v45, v10, v11 offset1:1
	ds_write2_b32 v45, v12, v13 offset0:2 offset1:3
	global_load_dword v8, v[8:9], off offset:736
	s_waitcnt vmcnt(0) lgkmcnt(0)
	v_pk_mul_f32 v[10:11], v[2:3], v[8:9] op_sel_hi:[1,0]
	v_pk_mul_f32 v[8:9], v[0:1], v[8:9] op_sel_hi:[1,0]
	s_cbranch_execnz .LBB0_1626
	s_branch .LBB0_1642

.LBB0_1646:
	v_add_u32_e32 v7, -2, v7
	v_ashrrev_i32_e32 v9, 31, v3
	v_mov_b32_e32 v8, v3
	v_ashrrev_i32_e32 v11, 31, v2
	v_mov_b32_e32 v10, v2
	v_cmp_eq_u32_e32 vcc, 0, v7
	v_add_u32_e32 v3, s16, v3
	v_add_u32_e32 v2, s3, v2
	v_lshl_add_u64 v[10:11], v[10:11], 2, s[10:11]
	v_lshl_add_u64 v[8:9], v[8:9], 2, s[10:11]
	s_or_b64 s[14:15], vcc, s[14:15]
	global_store_dword v[10:11], v233, off
	global_store_dword v[8:9], v233, off
	s_andn2_b64 exec, exec, s[14:15]
	s_cbranch_execnz .LBB0_1646
	s_or_b64 exec, exec, s[14:15]
	v_mad_u64_u32 v[2:3], s[14:15], v5, s2, v[0:1]
	v_cmp_ne_u32_e32 vcc, v4, v5
	s_orn2_b64 s[14:15], vcc, exec

.LBB0_1650:
	v_add_u32_e32 v2, s2, v2
	s_mov_b32 s3, 0xbfff
	v_cmp_lt_i32_e32 vcc, s3, v2
	global_store_dword v[4:5], v233, off
	s_or_b64 s[12:13], vcc, s[12:13]
	v_lshl_add_u64 v[4:5], v[4:5], 0, s[10:11]
	s_andn2_b64 exec, exec, s[12:13]
	s_cbranch_execnz .LBB0_1650

.LBB0_1658:
	v_add_u32_e32 v2, s2, v2
	s_movk_i32 s3, 0x3fff
	v_cmp_lt_i32_e32 vcc, s3, v2
	global_store_dword v[4:5], v233, off
	s_or_b64 s[12:13], vcc, s[12:13]
	v_lshl_add_u64 v[4:5], v[4:5], 0, s[10:11]
	s_andn2_b64 exec, exec, s[12:13]
	s_cbranch_execnz .LBB0_1658

.LBB0_1662:
	v_add_u32_e32 v1, s3, v4
	v_add_u32_e32 v9, s14, v5
	v_ashrrev_i32_e32 v12, 6, v4
	v_ashrrev_i32_e32 v10, 6, v5
	v_add_u32_e32 v8, -4, v8
	v_ashrrev_i32_e32 v14, 6, v9
	v_ashrrev_i32_e32 v16, 6, v1
	v_ashrrev_i32_e32 v13, 31, v12
	v_ashrrev_i32_e32 v11, 31, v10
	v_cmp_eq_u32_e32 vcc, 0, v8
	v_ashrrev_i32_e32 v17, 31, v16
	v_ashrrev_i32_e32 v15, 31, v14
	v_lshlrev_b64 v[12:13], 9, v[12:13]
	v_add_u32_e32 v5, s16, v5
	v_add_u32_e32 v4, s15, v4
	v_lshlrev_b64 v[10:11], 9, v[10:11]
	s_or_b64 s[12:13], vcc, s[12:13]
	v_lshlrev_b64 v[14:15], 9, v[14:15]
	v_lshlrev_b64 v[16:17], 9, v[16:17]
	v_lshl_add_u64 v[12:13], v[2:3], 0, v[12:13]
	v_lshl_add_u64 v[10:11], v[2:3], 0, v[10:11]
	v_lshl_add_u64 v[16:17], v[2:3], 0, v[16:17]
	v_lshl_add_u64 v[14:15], v[2:3], 0, v[14:15]
	global_store_dword v[12:13], v233, off offset:256
	global_store_dword v[10:11], v233, off offset:256
	global_store_dword v[16:17], v233, off offset:256
	global_store_dword v[14:15], v233, off offset:256
	s_andn2_b64 exec, exec, s[12:13]
	s_cbranch_execnz .LBB0_1662
	s_or_b64 exec, exec, s[12:13]
	v_mad_u64_u32 v[2:3], s[12:13], v7, s2, v[0:1]
	v_cmp_ne_u32_e32 vcc, v6, v7
	s_orn2_b64 s[12:13], vcc, exec

.LBB0_1666:
	v_ashrrev_i32_e32 v6, 6, v2
	v_add_u32_e32 v2, s2, v2
	v_ashrrev_i32_e32 v7, 31, v6
	s_movk_i32 s3, 0x7fff
	v_cmp_lt_i32_e32 vcc, s3, v2
	v_lshlrev_b64 v[6:7], 9, v[6:7]
	s_or_b64 s[4:5], vcc, s[4:5]
	v_lshl_add_u64 v[6:7], v[4:5], 0, v[6:7]
	global_store_dword v[6:7], v233, off offset:256
	s_andn2_b64 exec, exec, s[4:5]
	s_cbranch_execnz .LBB0_1666

.LBB0_1669:
	v_ashrrev_i32_e32 v5, 31, v4
	v_lshl_add_u64 v[10:11], v[4:5], 4, s[6:7]
	global_load_dwordx4 v[6:9], v[10:11], off
	s_nop 0
	global_load_dwordx4 v[10:13], v[10:11], off offset:16
	v_add_u32_e32 v0, s2, v0
	v_cmp_lt_i32_e32 vcc, s28, v0
	v_add_u32_e32 v4, s3, v4
	s_or_b64 s[10:11], vcc, s[10:11]
	s_waitcnt vmcnt(0) lgkmcnt(0)
	v_cvt_pk_bf16_f32 v6, v6, v7
	v_cvt_pk_bf16_f32 v7, v8, v9
	v_cvt_pk_bf16_f32 v8, v10, v11
	v_cvt_pk_bf16_f32 v9, v12, v13
	global_store_dwordx4 v[2:3], v[6:9], off
	v_lshl_add_u64 v[2:3], v[2:3], 0, s[0:1]
	s_andn2_b64 exec, exec, s[10:11]
	s_cbranch_execnz .LBB0_1669

.LBB0_1679:
	v_mov_b64_e32 v[12:13], s[34:35]
	global_load_dword v1, v[12:13], off offset:1024 sc1
	s_waitcnt lgkmcnt(0)
	global_load_dword v0, v[12:13], off offset:1280 sc1
	global_load_dword v2, v[12:13], off offset:1536 sc1
	s_or_b64 s[14:15], s[14:15], exec
	s_or_b64 s[12:13], s[12:13], exec
	s_waitcnt vmcnt(0) lgkmcnt(0)
	v_add_u32_e32 v3, v0, v1
	v_add_u32_e32 v4, v3, v2
	global_load_dword v3, v[12:13], off offset:1792 sc1
	s_waitcnt vmcnt(0) lgkmcnt(0)
	v_add_u32_e32 v5, v4, v3
	global_load_dword v4, v[12:13], off offset:2048 sc1
	s_waitcnt vmcnt(0) lgkmcnt(0)
	v_add_u32_e32 v6, v5, v4
	global_load_dword v5, v[12:13], off offset:2304 sc1
	s_waitcnt vmcnt(0) lgkmcnt(0)
	v_add_u32_e32 v7, v6, v5
	global_load_dword v6, v[12:13], off offset:2560 sc1
	s_waitcnt vmcnt(0) lgkmcnt(0)
	v_add_u32_e32 v8, v7, v6
	global_load_dword v7, v[12:13], off offset:2816 sc1
	s_waitcnt vmcnt(0) lgkmcnt(0)
	v_add_u32_e32 v9, v8, v7
	global_load_dword v8, v[12:13], off offset:3072 sc1
	s_waitcnt vmcnt(0) lgkmcnt(0)
	v_add_u32_e32 v10, v9, v8
	global_load_dword v9, v[12:13], off offset:3328 sc1
	s_waitcnt vmcnt(0) lgkmcnt(0)
	v_add_u32_e32 v11, v10, v9
	global_load_dword v10, v[12:13], off offset:3584 sc1
	s_waitcnt vmcnt(0) lgkmcnt(0)
	v_add_u32_e32 v14, v11, v10
	global_load_dword v11, v[12:13], off offset:3840 sc1
	v_mov_b64_e32 v[12:13], s[0:1]
	global_load_dword v12, v[12:13], off sc1
	s_waitcnt vmcnt(0) lgkmcnt(0)
	v_add_u32_e32 v14, v14, v11
	v_add_u32_e32 v16, v14, v12
	v_mov_b64_e32 v[14:15], s[2:3]
	global_load_dword v13, v[14:15], off sc1
	v_mov_b64_e32 v[14:15], s[4:5]
	global_load_dword v14, v[14:15], off sc1
	s_waitcnt vmcnt(0) lgkmcnt(0)
	v_add_u32_e32 v16, v16, v13
	v_add_u32_e32 v18, v16, v14
	v_mov_b64_e32 v[16:17], s[6:7]
	global_load_dword v15, v[16:17], off sc1
	s_waitcnt vmcnt(0) lgkmcnt(0)
	v_add_u32_e32 v16, v18, v15
	v_cmp_ne_u32_e32 vcc, s74, v16
	s_and_saveexec_b64 s[16:17], vcc
	s_cbranch_execz .LBB0_1678
	s_and_b32 s20, s26, 0xff
	s_mov_b64 s[18:19], -1
	s_cmp_eq_u32 s20, 0
	s_mov_b64 s[22:23], -1
	s_mov_b64 s[20:21], -1
	s_sleep 1
	s_cbranch_scc1 .LBB0_1682
	s_and_saveexec_b64 s[24:25], s[22:23]
	s_cbranch_execz .LBB0_1677
	s_branch .LBB0_1685
.LBB0_1682:
	v_mov_b64_e32 v[16:17], s[34:35]
	global_load_dword v16, v[16:17], off offset:512 sc1
	s_mov_b64 s[22:23], 0
	s_waitcnt vmcnt(0) lgkmcnt(0)
	v_cmp_eq_u32_e32 vcc, 0, v16
	s_and_saveexec_b64 s[24:25], vcc
	s_cmp_lt_u32 s26, 0x100001
	s_cselect_b64 s[22:23], -1, 0
	s_xor_b64 s[20:21], exec, -1
	s_and_b64 s[22:23], s[22:23], exec
	s_or_b64 exec, exec, s[24:25]
	s_and_saveexec_b64 s[24:25], s[22:23]
	s_cbranch_execz .LBB0_1677

.LBB0_1689:
	s_lshl_b32 s0, s36, 8
	s_add_u32 s21, s34, s0
	s_addc_u32 s20, s35, 0
	v_mov_b32_e32 v1, s21
	v_add_co_u32_e32 v4, vcc, 0x1000, v1
	v_mov_b32_e32 v1, s20
	s_nop 0
	v_addc_co_u32_e32 v5, vcc, 0, v1, vcc
	v_mov_b32_e32 v1, 1
	flat_atomic_add v3, v[4:5], v1 offset:1024 sc0
	v_cvt_f32_u32_e32 v1, v2
	v_sub_u32_e32 v4, 0, v2
	v_rcp_iflag_f32_e32 v1, v1
	s_nop 0
	v_mul_f32_e32 v1, 0x4f7ffffe, v1
	v_cvt_u32_f32_e32 v1, v1
	v_mul_lo_u32 v4, v4, v1
	v_mul_hi_u32 v4, v1, v4
	v_add_u32_e32 v1, v1, v4
	s_waitcnt vmcnt(0) lgkmcnt(0)
	v_mul_hi_u32 v1, v3, v1
	v_mul_lo_u32 v4, v1, v2
	v_sub_u32_e32 v4, v3, v4
	v_cmp_ge_u32_e32 vcc, v4, v2
	v_add_u32_e32 v5, 1, v1
	s_nop 0
	v_cndmask_b32_e32 v1, v1, v5, vcc
	v_sub_u32_e32 v5, v4, v2
	v_cndmask_b32_e32 v4, v4, v5, vcc
	v_cmp_ge_u32_e32 vcc, v4, v2
	v_add_u32_e32 v4, 1, v1
	s_nop 0
	v_cndmask_b32_e32 v1, v1, v4, vcc
	v_add_u32_e32 v4, 1, v3
	v_mad_u64_u32 v[2:3], s[0:1], v2, v1, v[2:3]
	v_cmp_ne_u32_e32 vcc, v4, v2
	s_and_saveexec_b64 s[0:1], vcc
	s_xor_b64 s[0:1], exec, s[0:1]
	s_cbranch_execz .LBB0_1702
	v_mov_b32_e32 v0, s21
	v_add_co_u32_e32 v2, vcc, 0x2000, v0
	v_mov_b32_e32 v0, s20
	s_nop 0
	v_addc_co_u32_e32 v3, vcc, 0, v0, vcc
	global_load_dword v0, v[2:3], off offset:1024 sc1
	s_add_u32 s4, s21, 0x2400
	s_addc_u32 s5, s20, 0
	s_waitcnt vmcnt(0) lgkmcnt(0)
	v_cmp_eq_u32_e32 vcc, v0, v1
	s_and_saveexec_b64 s[2:3], vcc
	s_cbranch_execz .LBB0_1701
	s_mov_b32 s22, 1
	s_mov_b64 s[6:7], 0
	s_branch .LBB0_1693

.LBB0_1693:
	s_and_b32 s14, s22, 0xff
	s_mov_b64 s[12:13], -1
	s_cmp_lg_u32 s14, 0
	s_mov_b64 s[14:15], -1
	s_sleep 1
	s_cbranch_scc1 .LBB0_1697
	v_mov_b64_e32 v[2:3], s[34:35]
	global_load_dword v0, v[2:3], off offset:512 sc1
	s_mov_b64 s[14:15], 0
	s_mov_b64 s[16:17], -1
	s_waitcnt vmcnt(0) lgkmcnt(0)
	v_cmp_eq_u32_e32 vcc, 0, v0
	s_and_saveexec_b64 s[18:19], vcc
	s_cmp_lt_u32 s22, 0x100001
	s_cselect_b64 s[14:15], -1, 0
	s_xor_b64 s[16:17], exec, -1
	s_and_b64 s[14:15], s[14:15], exec
	s_or_b64 exec, exec, s[18:19]
.LBB0_1697:
	s_andn2_b64 s[10:11], s[10:11], exec
	s_and_b64 s[16:17], s[16:17], exec
	s_or_b64 s[10:11], s[10:11], s[16:17]
	s_and_saveexec_b64 s[16:17], s[14:15]
	s_cbranch_execz .LBB0_1692
	v_mov_b64_e32 v[2:3], s[4:5]
	global_load_dword v0, v[2:3], off sc1
	s_add_i32 s22, s22, 1
	s_or_b64 s[10:11], s[10:11], exec
	s_waitcnt vmcnt(0) lgkmcnt(0)
	v_cmp_ne_u32_e32 vcc, v0, v1
	s_orn2_b64 s[12:13], vcc, exec
	s_branch .LBB0_1692

.LBB0_1703:
	v_mov_b32_e32 v1, s34
	v_add_co_u32_e32 v2, vcc, 0x3000, v1
	v_mov_b32_e32 v1, s35
	buffer_wbl2 sc1
	s_waitcnt vmcnt(0)
	v_addc_co_u32_e32 v3, vcc, 0, v1, vcc
	v_mov_b32_e32 v1, 1
	flat_atomic_add v1, v[2:3], v1 offset:1024 sc0
	v_cvt_f32_u32_e32 v2, v0
	v_sub_u32_e32 v3, 0, v0
	s_mov_b64 s[4:5], -1
	v_rcp_iflag_f32_e32 v2, v2
	s_nop 0
	v_mul_f32_e32 v2, 0x4f7ffffe, v2
	v_cvt_u32_f32_e32 v2, v2
	v_mul_lo_u32 v3, v3, v2
	v_mul_hi_u32 v3, v2, v3
	v_add_u32_e32 v2, v2, v3
	s_waitcnt vmcnt(0) lgkmcnt(0)
	v_mul_hi_u32 v2, v1, v2
	v_mul_lo_u32 v3, v2, v0
	v_sub_u32_e32 v3, v1, v3
	v_cmp_ge_u32_e32 vcc, v3, v0
	v_add_u32_e32 v4, 1, v2
	s_nop 0
	v_cndmask_b32_e32 v2, v2, v4, vcc
	v_sub_u32_e32 v4, v3, v0
	v_cndmask_b32_e32 v3, v3, v4, vcc
	v_cmp_ge_u32_e32 vcc, v3, v0
	v_add_u32_e32 v3, 1, v2
	s_nop 0
	v_cndmask_b32_e32 v2, v2, v3, vcc
	v_add_u32_e32 v3, 1, v1
	v_mad_u64_u32 v[0:1], s[0:1], v0, v2, v[0:1]
	s_add_u32 s0, s34, 0x3500
	s_addc_u32 s1, s35, 0
	v_cmp_ne_u32_e32 vcc, v3, v0
	v_mov_b64_e32 v[0:1], s[0:1]
	s_and_saveexec_b64 s[2:3], vcc
	s_cbranch_execz .LBB0_1715
	v_mov_b64_e32 v[0:1], s[0:1]
	global_load_dword v0, v[0:1], off sc1
	s_mov_b64 s[8:9], 0
	s_waitcnt vmcnt(0) lgkmcnt(0)
	v_cmp_eq_u32_e32 vcc, v0, v2
	s_and_saveexec_b64 s[6:7], vcc
	s_cbranch_execz .LBB0_1714
	s_add_u32 s4, s34, 0x200
	s_addc_u32 s5, s35, 0
	s_mov_b32 s22, 1
	s_branch .LBB0_1707

.LBB0_1709:
	v_mov_b64_e32 v[0:1], s[4:5]
	global_load_dword v0, v[0:1], off sc1
	s_mov_b64 s[16:17], 0
	s_mov_b64 s[14:15], -1
	s_waitcnt vmcnt(0) lgkmcnt(0)
	v_cmp_eq_u32_e32 vcc, 0, v0
	s_and_saveexec_b64 s[18:19], vcc
	s_cmp_lt_u32 s22, 0x100001
	s_cselect_b64 s[16:17], -1, 0
	s_xor_b64 s[14:15], exec, -1
	s_and_b64 s[16:17], s[16:17], exec
	s_or_b64 exec, exec, s[18:19]
	s_and_saveexec_b64 s[18:19], s[16:17]
	s_cbranch_execz .LBB0_1706
.LBB0_1712:
	v_mov_b64_e32 v[0:1], s[0:1]
	global_load_dword v0, v[0:1], off sc1
	s_add_i32 s22, s22, 1
	s_or_b64 s[14:15], s[14:15], exec
	s_waitcnt vmcnt(0) lgkmcnt(0)
	v_cmp_ne_u32_e32 vcc, v0, v2
	s_orn2_b64 s[12:13], vcc, exec
	s_branch .LBB0_1706
